# hand-written RWKV-7 scan item (branch-free addressing, unrolled 16-step scan, counted lgkmcnt) + cvt_pk_bf16 conversions
# speedup vs baseline: 1.0340x; 1.0340x over previous
_Z6k_mega1P:
	v_writelane_b32 v246, s0, 10
	v_writelane_b32 v246, s1, 11
	s_mov_b32 s73, s2
	s_load_dwordx16 s[80:95], s[0:1], 0x140
	s_load_dword s2, s[0:1], 0x1b8
	s_load_dwordx2 s[96:97], s[0:1], 0x1b0
	s_add_u32 s10, s0, 0x1b0
	v_and_b32_e32 v226, 0x3ff, v0
	s_addc_u32 s11, s1, 0
	v_cmp_eq_u32_e64 s[74:75], 0, v226
	s_waitcnt lgkmcnt(0)
	v_writelane_b32 v241, s2, 0
	s_and_saveexec_b64 s[4:5], s[74:75]
	s_cbranch_execz .LBB0_2
	v_mov_b32_e32 v2, 0
	v_mov_b32_e32 v3, v2
	v_mov_b32_e32 v4, v2
	v_mov_b32_e32 v5, v2
	v_mov_b32_e32 v1, 0x12000
	ds_write_b128 v1, v[2:5]

.LBB0_18:
	s_or_b64 exec, exec, s[6:7]
	s_waitcnt vmcnt(0)
	v_cvt_pk_bf16_f32 v3, v7, v7
	global_store_short_d16_hi v[4:5], v3, off
	v_add_u32_e32 v3, 0x100, v2
	s_mov_b64 s[6:7], 0x200
	v_cmp_le_i32_e32 vcc, s20, v2
	v_lshl_add_u64 v[4:5], v[4:5], 0, s[6:7]
	s_or_b64 s[4:5], vcc, s[4:5]
	v_mov_b32_e32 v2, v3
	s_andn2_b64 exec, exec, s[4:5]
	s_cbranch_execz .LBB0_32

.LBB0_56:
	ds_read2_b32 v[18:19], v13 offset1:4
	ds_read2_b32 v[20:21], v13 offset0:8 offset1:12
	v_add_u32_e32 v22, s41, v6
	v_ashrrev_i32_e32 v23, 31, v22
	v_lshlrev_b64 v[22:23], 11, v[22:23]
	s_waitcnt lgkmcnt(1)
	v_and_b32_sdwa v16, v18, v39 dst_sel:DWORD dst_unused:UNUSED_PAD src0_sel:WORD_1 src1_sel:DWORD
	v_and_b32_sdwa v3, v19, v39 dst_sel:DWORD dst_unused:UNUSED_PAD src0_sel:WORD_1 src1_sel:DWORD
	v_add3_u32 v16, v18, v16, s25
	v_add_u32_e32 v18, s41, v7
	v_add3_u32 v3, v19, v3, s25
	v_ashrrev_i32_e32 v19, 31, v18
	v_lshlrev_b64 v[18:19], 11, v[18:19]
	v_lshl_add_u64 v[22:23], v[4:5], 0, v[22:23]
	v_lshl_add_u64 v[18:19], v[4:5], 0, v[18:19]
	global_store_short_d16_hi v[22:23], v16, off
	global_store_short_d16_hi v[18:19], v3, off
	s_waitcnt lgkmcnt(0)
	v_and_b32_sdwa v16, v20, v39 dst_sel:DWORD dst_unused:UNUSED_PAD src0_sel:WORD_1 src1_sel:DWORD
	v_and_b32_sdwa v3, v21, v39 dst_sel:DWORD dst_unused:UNUSED_PAD src0_sel:WORD_1 src1_sel:DWORD
	v_add3_u32 v16, v20, v16, s25
	v_add_u32_e32 v20, s21, v6
	v_add3_u32 v3, v21, v3, s25
	v_add_u32_e32 v18, s42, v7
	v_ashrrev_i32_e32 v21, 31, v20
	v_ashrrev_i32_e32 v19, 31, v18
	v_lshlrev_b64 v[20:21], 11, v[20:21]
	v_lshlrev_b64 v[18:19], 11, v[18:19]
	v_lshl_add_u64 v[20:21], v[4:5], 0, v[20:21]
	v_lshl_add_u64 v[18:19], v[4:5], 0, v[18:19]
	global_store_short_d16_hi v[20:21], v16, off
	global_store_short_d16_hi v[18:19], v3, off
	ds_read2_b32 v[18:19], v13 offset0:16 offset1:20
	v_add_u32_e32 v20, s43, v6
	v_ashrrev_i32_e32 v21, 31, v20
	v_lshlrev_b64 v[20:21], 11, v[20:21]
	v_lshl_add_u64 v[20:21], v[4:5], 0, v[20:21]
	s_waitcnt lgkmcnt(0)
	v_and_b32_sdwa v16, v18, v39 dst_sel:DWORD dst_unused:UNUSED_PAD src0_sel:WORD_1 src1_sel:DWORD
	v_and_b32_sdwa v3, v19, v39 dst_sel:DWORD dst_unused:UNUSED_PAD src0_sel:WORD_1 src1_sel:DWORD
	v_add3_u32 v16, v18, v16, s25
	v_add_u32_e32 v18, s44, v7
	v_add3_u32 v3, v19, v3, s25
	v_ashrrev_i32_e32 v19, 31, v18
	v_lshlrev_b64 v[18:19], 11, v[18:19]
	v_lshl_add_u64 v[18:19], v[4:5], 0, v[18:19]
	global_store_short_d16_hi v[20:21], v16, off
	global_store_short_d16_hi v[18:19], v3, off
	ds_read2_b32 v[18:19], v13 offset0:24 offset1:28
	v_add_u32_e32 v20, s45, v6
	v_ashrrev_i32_e32 v21, 31, v20
	v_lshlrev_b64 v[20:21], 11, v[20:21]
	v_add_u32_e32 v12, -4, v12
	s_waitcnt lgkmcnt(0)
	v_cvt_pk_bf16_f32 v16, v18, v18
	v_add_u32_e32 v18, s46, v7
	v_cvt_pk_bf16_f32 v3, v19, v19
	v_ashrrev_i32_e32 v19, 31, v18
	v_lshlrev_b64 v[18:19], 11, v[18:19]
	v_lshl_add_u64 v[20:21], v[4:5], 0, v[20:21]
	s_add_i32 s47, s47, 8
	v_cmp_eq_u32_e32 vcc, 0, v12
	v_lshl_add_u64 v[18:19], v[4:5], 0, v[18:19]
	global_store_short_d16_hi v[20:21], v16, off
	global_store_short_d16_hi v[18:19], v3, off
	v_add_u32_e32 v7, 32, v7
	v_add_u32_e32 v6, 32, v6
	v_add_u32_e32 v13, 0x80, v13
	s_or_b64 s[18:19], vcc, s[18:19]
	v_mov_b32_e32 v16, s47
	s_andn2_b64 exec, exec, s[18:19]
	s_cbranch_execnz .LBB0_56
	s_or_b64 exec, exec, s[18:19]

.LBB0_60:
	ds_read2_b32 v[12:13], v10 offset1:4
	v_add_u32_e32 v18, s41, v6
	v_ashrrev_i32_e32 v19, 31, v18
	v_add_u32_e32 v3, -1, v3
	v_lshlrev_b64 v[18:19], 11, v[18:19]
	s_waitcnt lgkmcnt(0)
	v_cvt_pk_bf16_f32 v16, v12, v12
	v_add_u32_e32 v12, s41, v7
	v_cvt_pk_bf16_f32 v11, v13, v13
	v_ashrrev_i32_e32 v13, 31, v12
	v_cmp_eq_u32_e32 vcc, 0, v3
	v_lshlrev_b64 v[12:13], 11, v[12:13]
	v_lshl_add_u64 v[18:19], v[4:5], 0, v[18:19]
	v_add_u32_e32 v7, 8, v7
	v_add_u32_e32 v6, 8, v6
	v_add_u32_e32 v10, 32, v10
	s_or_b64 s[18:19], vcc, s[18:19]
	v_lshl_add_u64 v[12:13], v[4:5], 0, v[12:13]
	global_store_short_d16_hi v[18:19], v16, off
	global_store_short_d16_hi v[12:13], v11, off
	s_andn2_b64 exec, exec, s[18:19]
	s_cbranch_execnz .LBB0_60

.LBB0_64:
	ds_read_b32 v3, v2
	v_add_u32_e32 v6, 4, v6
	v_cmp_lt_i32_e32 vcc, 59, v6
	s_mov_b64 s[8:9], 0x2000
	v_add_u32_e32 v2, 16, v2
	s_waitcnt lgkmcnt(0)
	v_cvt_pk_bf16_f32 v3, v3, v3
	s_or_b64 s[4:5], vcc, s[4:5]
	global_store_short_d16_hi v[4:5], v3, off
	v_lshl_add_u64 v[4:5], v[4:5], 0, s[8:9]
	s_andn2_b64 exec, exec, s[4:5]
	s_cbranch_execnz .LBB0_64

.LBB0_147:
	s_or_b64 exec, exec, s[14:15]
	s_and_b64 s[0:1], exec, vcc
	s_or_b64 s[12:13], s[0:1], s[12:13]
	v_add_u32_e32 v50, 0x1000, v49
	v_lshrrev_b32_e32 v49, 12, v49
	s_movk_i32 s0, 0xfff
	v_add_u32_e32 v49, 1, v49
	v_cmp_lt_i32_e32 vcc, s0, v50
	s_movk_i32 s0, 0x6000
	v_lshl_add_u64 v[36:37], v[36:37], 0, s[6:7]
	v_cndmask_b32_e32 v49, 0, v49, vcc
	v_mad_u64_u32 v[50:51], s[0:1], v49, s0, v[40:41]
	s_mov_b64 s[0:1], 0x1000
	s_nop 0
	v_lshl_add_u64 v[52:53], v[50:51], 0, s[0:1]
	v_lshl_add_u64 v[58:59], v[50:51], 0, v[32:33]
	v_lshl_add_u64 v[54:55], v[52:53], 0, v[32:33]
	v_lshl_add_u64 v[60:61], v[52:53], 0, v[42:43]
	v_lshl_add_u64 v[62:63], v[52:53], 0, v[44:45]
	v_lshl_add_u64 v[64:65], v[52:53], 0, v[46:47]
	global_load_dwordx4 v[50:53], v[58:59], off
	s_nop 0
	global_load_dwordx4 v[54:57], v[54:55], off
	s_waitcnt vmcnt(0)
	v_pk_add_f32 v[56:57], v[56:57], 1.0 op_sel_hi:[1,0]
	v_pk_add_f32 v[54:55], v[54:55], 1.0 op_sel_hi:[1,0]
	v_pk_fma_f32 v[52:53], v[18:19], v[56:57], v[52:53]
	v_pk_fma_f32 v[50:51], v[16:17], v[54:55], v[50:51]
	v_cvt_pk_bf16_f32 v67, v52, v53
	v_cvt_pk_bf16_f32 v66, v50, v51
	global_load_dwordx4 v[50:53], v[58:59], off offset:1024
	global_load_dwordx4 v[54:57], v[60:61], off
	s_waitcnt vmcnt(0)
	v_pk_add_f32 v[56:57], v[56:57], 1.0 op_sel_hi:[1,0]
	v_pk_add_f32 v[54:55], v[54:55], 1.0 op_sel_hi:[1,0]
	v_pk_fma_f32 v[52:53], v[30:31], v[56:57], v[52:53]
	v_pk_fma_f32 v[50:51], v[28:29], v[54:55], v[50:51]
	v_cvt_pk_bf16_f32 v61, v52, v53
	v_cvt_pk_bf16_f32 v60, v50, v51
	global_load_dwordx4 v[50:53], v[58:59], off offset:2048
	global_load_dwordx4 v[54:57], v[62:63], off
	s_waitcnt vmcnt(0)
	v_pk_add_f32 v[56:57], v[56:57], 1.0 op_sel_hi:[1,0]
	v_pk_add_f32 v[54:55], v[54:55], 1.0 op_sel_hi:[1,0]
	v_pk_fma_f32 v[52:53], v[26:27], v[56:57], v[52:53]
	v_pk_fma_f32 v[50:51], v[24:25], v[54:55], v[50:51]
	v_cvt_pk_bf16_f32 v63, v52, v53
	v_cvt_pk_bf16_f32 v62, v50, v51
	global_load_dwordx4 v[50:53], v[58:59], off offset:3072
	global_load_dwordx4 v[54:57], v[64:65], off
	s_nop 0
	global_store_dwordx4 v[38:39], v[16:19], off
	global_store_dwordx4 v[38:39], v[28:31], off offset:1024
	global_store_dwordx4 v[38:39], v[24:27], off offset:2048
	global_store_dwordx4 v[38:39], v[20:23], off offset:3072
	global_store_dwordx2 v[34:35], v[66:67], off offset:-1024
	global_store_dwordx2 v[34:35], v[60:61], off offset:-512
	global_store_dwordx2 v[34:35], v[62:63], off
	v_lshl_add_u64 v[38:39], v[38:39], 0, s[10:11]
	v_mov_b32_e32 v49, v48
	v_mov_b64_e32 v[28:29], v[4:5]
	v_mov_b64_e32 v[30:31], v[6:7]
	v_mov_b64_e32 v[24:25], v[8:9]
	v_mov_b64_e32 v[26:27], v[10:11]
	s_waitcnt vmcnt(7)
	v_pk_add_f32 v[16:17], v[56:57], 1.0 op_sel_hi:[1,0]
	v_pk_add_f32 v[18:19], v[54:55], 1.0 op_sel_hi:[1,0]
	v_pk_fma_f32 v[16:17], v[22:23], v[16:17], v[52:53]
	v_pk_fma_f32 v[18:19], v[20:21], v[18:19], v[50:51]
	v_cvt_pk_bf16_f32 v17, v16, v17
	v_cvt_pk_bf16_f32 v16, v18, v19
	global_store_dwordx2 v[34:35], v[16:17], off offset:512
	v_lshl_add_u64 v[34:35], v[34:35], 0, s[8:9]
	v_mov_b64_e32 v[16:17], v[0:1]
	v_mov_b64_e32 v[18:19], v[2:3]
	v_mov_b64_e32 v[20:21], v[12:13]
	v_mov_b64_e32 v[22:23], v[14:15]
	s_andn2_b64 exec, exec, s[12:13]
	s_cbranch_execz .LBB0_150

.LBB0_206:
	s_mul_i32 s8, s6, 0x6000
	s_waitcnt vmcnt(6)
	s_add_i32 s10, s27, s8
	s_mul_i32 s98, s7, 0x6000
	v_lshl_add_u64 v[200:201], v[140:141], 0, s[0:1]
	v_lshl_add_u64 v[202:203], v[138:139], 0, s[0:1]
	s_add_i32 s99, s10, s28
	s_waitcnt lgkmcnt(0)
	s_barrier
	v_add_u32_e32 v182, s98, v142
	v_add_u32_e32 v183, s98, v144
	ds_read_b128 v[166:169], v183
	ds_read_b128 v[150:153], v182
	ds_read_b128 v[170:173], v183 offset:1024
	ds_read_b128 v[174:177], v183 offset:2048
	ds_read_b128 v[178:181], v183 offset:3072
	ds_read_b128 v[154:157], v182 offset:1024
	ds_read_b128 v[158:161], v182 offset:2048
	ds_read_b128 v[162:165], v182 offset:3072
	ds_read_b128 v[184:187], v182 offset:4096
	ds_read_b128 v[188:191], v182 offset:5120
	ds_read_b128 v[192:195], v182 offset:6144
	ds_read_b128 v[196:199], v182 offset:7168
	v_lshl_add_u64 v[204:205], v[200:201], 0, s[20:21]
	s_mov_b32 m0, s10
	s_waitcnt lgkmcnt(10)
	v_mfma_f32_16x16x32_bf16 v[84:87], v[150:153], v[166:169], v[84:87]
	global_load_lds_dwordx4 v[204:205], off
	s_waitcnt lgkmcnt(9)
	v_mfma_f32_16x16x32_bf16 v[76:79], v[150:153], v[170:173], v[76:79]
	v_lshl_add_u64 v[204:205], v[200:201], 0, s[22:23]
	s_add_i32 m0, s10, 0x400
	s_waitcnt lgkmcnt(8)
	v_mfma_f32_16x16x32_bf16 v[68:71], v[150:153], v[174:177], v[68:71]
	global_load_lds_dwordx4 v[204:205], off
	s_waitcnt lgkmcnt(7)
	v_mfma_f32_16x16x32_bf16 v[60:63], v[150:153], v[178:181], v[60:63]
	s_mov_b64 s[100:101], 0x10080
	v_lshl_add_u64 v[204:205], v[200:201], 0, s[100:101]
	s_add_i32 m0, s10, 0x800
	s_waitcnt lgkmcnt(6)
	v_mfma_f32_16x16x32_bf16 v[52:55], v[154:157], v[166:169], v[52:55]
	global_load_lds_dwordx4 v[204:205], off
	v_mfma_f32_16x16x32_bf16 v[44:47], v[154:157], v[170:173], v[44:47]
	v_mfma_f32_16x16x32_bf16 v[36:39], v[154:157], v[174:177], v[36:39]
	s_mov_b64 s[100:101], 0x18080
	v_lshl_add_u64 v[204:205], v[200:201], 0, s[100:101]
	s_add_i32 m0, s10, 0xc00
	v_mfma_f32_16x16x32_bf16 v[32:35], v[154:157], v[178:181], v[32:35]
	global_load_lds_dwordx4 v[204:205], off
	s_waitcnt lgkmcnt(5)
	v_mfma_f32_16x16x32_bf16 v[28:31], v[158:161], v[166:169], v[28:31]
	v_lshl_add_u64 v[204:205], v[202:203], 0, s[20:21]
	s_add_i32 m0, s99, 0x4000
	v_mfma_f32_16x16x32_bf16 v[24:27], v[158:161], v[170:173], v[24:27]
	global_load_lds_dwordx4 v[204:205], off
	v_mfma_f32_16x16x32_bf16 v[20:23], v[158:161], v[174:177], v[20:23]
	v_lshl_add_u64 v[204:205], v[202:203], 0, s[22:23]
	s_add_i32 m0, s99, 0x4400
	v_mfma_f32_16x16x32_bf16 v[16:19], v[158:161], v[178:181], v[16:19]
	global_load_lds_dwordx4 v[204:205], off
	s_waitcnt lgkmcnt(4)
	v_mfma_f32_16x16x32_bf16 v[12:15], v[162:165], v[166:169], v[12:15]
	v_mfma_f32_16x16x32_bf16 v[8:11], v[162:165], v[170:173], v[8:11]
	v_mfma_f32_16x16x32_bf16 v[4:7], v[162:165], v[174:177], v[4:7]
	v_mfma_f32_16x16x32_bf16 v[0:3], v[162:165], v[178:181], v[0:3]
	s_waitcnt lgkmcnt(3)
	v_mfma_f32_16x16x32_bf16 v[124:127], v[184:187], v[166:169], v[124:127]
	v_mfma_f32_16x16x32_bf16 v[120:123], v[184:187], v[170:173], v[120:123]
	v_mfma_f32_16x16x32_bf16 v[116:119], v[184:187], v[174:177], v[116:119]
	v_mfma_f32_16x16x32_bf16 v[112:115], v[184:187], v[178:181], v[112:115]
	s_waitcnt lgkmcnt(2)
	v_mfma_f32_16x16x32_bf16 v[108:111], v[188:191], v[166:169], v[108:111]
	v_mfma_f32_16x16x32_bf16 v[104:107], v[188:191], v[170:173], v[104:107]
	v_mfma_f32_16x16x32_bf16 v[100:103], v[188:191], v[174:177], v[100:103]
	v_mfma_f32_16x16x32_bf16 v[96:99], v[188:191], v[178:181], v[96:99]
	s_waitcnt lgkmcnt(1)
	v_mfma_f32_16x16x32_bf16 v[92:95], v[192:195], v[166:169], v[92:95]
	v_mfma_f32_16x16x32_bf16 v[88:91], v[192:195], v[170:173], v[88:91]
	v_mfma_f32_16x16x32_bf16 v[80:83], v[192:195], v[174:177], v[80:83]
	v_mfma_f32_16x16x32_bf16 v[72:75], v[192:195], v[178:181], v[72:75]
	s_waitcnt lgkmcnt(0)
	v_mfma_f32_16x16x32_bf16 v[64:67], v[196:199], v[166:169], v[64:67]
	v_mfma_f32_16x16x32_bf16 v[56:59], v[196:199], v[170:173], v[56:59]
	v_mfma_f32_16x16x32_bf16 v[48:51], v[196:199], v[174:177], v[48:51]
	v_mfma_f32_16x16x32_bf16 v[40:43], v[196:199], v[178:181], v[40:43]
	s_add_i32 s8, s7, 1
	s_cmp_lg_u32 s7, 2
	s_cselect_b32 s7, s8, 0
	s_add_i32 s8, s6, 1
	s_cmp_lg_u32 s6, 2
	s_cselect_b32 s6, s8, 0
	s_add_u32 s0, s0, 64
	s_addc_u32 s1, s1, 0
	s_cmpk_eq_i32 s0, 0x780
	s_cbranch_scc0 .LBB0_206
	s_waitcnt vmcnt(6)
	s_waitcnt lgkmcnt(0)
	s_barrier
	ds_read_b128 v[138:141], v142
	ds_read_b128 v[150:153], v142 offset:1024
	ds_read_b128 v[154:157], v142 offset:2048
	ds_read_b128 v[158:161], v142 offset:3072
	ds_read_b128 v[162:165], v144
	ds_read_b128 v[166:169], v144 offset:1024
	ds_read_b128 v[170:173], v144 offset:2048
	ds_read_b128 v[174:177], v144 offset:3072
	s_waitcnt lgkmcnt(0)
	s_nop 0
	v_mfma_f32_16x16x32_bf16 v[84:87], v[138:141], v[162:165], v[84:87]
	v_mfma_f32_16x16x32_bf16 v[76:79], v[138:141], v[166:169], v[76:79]
	v_mfma_f32_16x16x32_bf16 v[68:71], v[138:141], v[170:173], v[68:71]
	v_mfma_f32_16x16x32_bf16 v[60:63], v[138:141], v[174:177], v[60:63]
	v_mfma_f32_16x16x32_bf16 v[52:55], v[150:153], v[162:165], v[52:55]
	v_mfma_f32_16x16x32_bf16 v[44:47], v[150:153], v[166:169], v[44:47]
	v_mfma_f32_16x16x32_bf16 v[36:39], v[150:153], v[170:173], v[36:39]
	v_mfma_f32_16x16x32_bf16 v[32:35], v[150:153], v[174:177], v[32:35]
	v_mfma_f32_16x16x32_bf16 v[28:31], v[154:157], v[162:165], v[28:31]
	v_mfma_f32_16x16x32_bf16 v[24:27], v[154:157], v[166:169], v[24:27]
	v_mfma_f32_16x16x32_bf16 v[20:23], v[154:157], v[170:173], v[20:23]
	v_mfma_f32_16x16x32_bf16 v[16:19], v[154:157], v[174:177], v[16:19]
	v_mfma_f32_16x16x32_bf16 v[12:15], v[158:161], v[162:165], v[12:15]
	v_mfma_f32_16x16x32_bf16 v[8:11], v[158:161], v[166:169], v[8:11]
	v_mfma_f32_16x16x32_bf16 v[4:7], v[158:161], v[170:173], v[4:7]
	v_mfma_f32_16x16x32_bf16 v[0:3], v[158:161], v[174:177], v[0:3]
	ds_read_b128 v[138:141], v142 offset:4096
	ds_read_b128 v[150:153], v142 offset:5120
	ds_read_b128 v[154:157], v142 offset:6144
	ds_read_b128 v[158:161], v142 offset:7168
	s_waitcnt lgkmcnt(0)
	s_nop 0
	v_mfma_f32_16x16x32_bf16 v[178:181], v[138:141], v[162:165], v[124:127]
	v_mfma_f32_16x16x32_bf16 v[182:185], v[138:141], v[166:169], v[120:123]
	v_mfma_f32_16x16x32_bf16 v[186:189], v[138:141], v[170:173], v[116:119]
	v_mfma_f32_16x16x32_bf16 v[138:141], v[138:141], v[174:177], v[112:115]
	v_mfma_f32_16x16x32_bf16 v[190:193], v[150:153], v[162:165], v[108:111]
	v_mfma_f32_16x16x32_bf16 v[194:197], v[150:153], v[166:169], v[104:107]
	v_mfma_f32_16x16x32_bf16 v[198:201], v[150:153], v[170:173], v[100:103]
	v_mfma_f32_16x16x32_bf16 v[150:153], v[150:153], v[174:177], v[96:99]
	v_mfma_f32_16x16x32_bf16 v[202:205], v[154:157], v[162:165], v[92:95]
	v_mfma_f32_16x16x32_bf16 v[206:209], v[154:157], v[166:169], v[88:91]
	v_mfma_f32_16x16x32_bf16 v[210:213], v[154:157], v[170:173], v[80:83]
	v_mfma_f32_16x16x32_bf16 v[154:157], v[154:157], v[174:177], v[72:75]
	v_mfma_f32_16x16x32_bf16 v[162:165], v[158:161], v[162:165], v[64:67]
	v_mfma_f32_16x16x32_bf16 v[166:169], v[158:161], v[166:169], v[56:59]
	v_mfma_f32_16x16x32_bf16 v[170:173], v[158:161], v[170:173], v[48:51]
	v_mfma_f32_16x16x32_bf16 v[158:161], v[158:161], v[174:177], v[40:43]
	s_waitcnt vmcnt(0)
	s_waitcnt lgkmcnt(0)
	s_barrier
	ds_read_b128 v[40:43], v148
	ds_read_b128 v[48:51], v148 offset:1024
	ds_read_b128 v[56:59], v148 offset:2048
	ds_read_b128 v[174:177], v148 offset:3072
	ds_read_b128 v[214:217], v149
	ds_read_b128 v[218:221], v149 offset:1024
	ds_read_b128 v[222:225], v149 offset:2048
	ds_read_b128 v[228:231], v149 offset:3072
	s_waitcnt lgkmcnt(0)
	s_nop 0
	v_mfma_f32_16x16x32_bf16 v[116:119], v[40:43], v[218:221], v[76:79]
	v_mfma_f32_16x16x32_bf16 v[120:123], v[40:43], v[222:225], v[68:71]
	v_mfma_f32_16x16x32_bf16 v[64:67], v[174:177], v[214:217], v[12:15]
	v_mfma_f32_16x16x32_bf16 v[68:71], v[174:177], v[218:221], v[8:11]
	v_mfma_f32_16x16x32_bf16 v[72:75], v[174:177], v[222:225], v[4:7]
	v_mfma_f32_16x16x32_bf16 v[76:79], v[174:177], v[228:231], v[0:3]
	ds_read_b128 v[0:3], v148 offset:4096
	ds_read_b128 v[4:7], v148 offset:5120
	ds_read_b128 v[8:11], v148 offset:6144
	ds_read_b128 v[12:15], v148 offset:7168
	s_waitcnt lgkmcnt(0)
	v_mfma_f32_16x16x32_bf16 v[112:115], v[40:43], v[214:217], v[84:87]
	v_mfma_f32_16x16x32_bf16 v[124:127], v[40:43], v[228:231], v[60:63]
	v_mfma_f32_16x16x32_bf16 v[96:99], v[48:51], v[214:217], v[52:55]
	v_mfma_f32_16x16x32_bf16 v[100:103], v[48:51], v[218:221], v[44:47]
	v_mfma_f32_16x16x32_bf16 v[104:107], v[48:51], v[222:225], v[36:39]
	v_mfma_f32_16x16x32_bf16 v[108:111], v[48:51], v[228:231], v[32:35]
	v_mfma_f32_16x16x32_bf16 v[80:83], v[56:59], v[214:217], v[28:31]
	v_mfma_f32_16x16x32_bf16 v[84:87], v[56:59], v[218:221], v[24:27]
	v_mfma_f32_16x16x32_bf16 v[88:91], v[56:59], v[222:225], v[20:23]
	v_mfma_f32_16x16x32_bf16 v[92:95], v[56:59], v[228:231], v[16:19]
	v_mfma_f32_16x16x32_bf16 v[48:51], v[0:3], v[214:217], v[178:181]
	v_mfma_f32_16x16x32_bf16 v[52:55], v[0:3], v[218:221], v[182:185]
	v_mfma_f32_16x16x32_bf16 v[56:59], v[0:3], v[222:225], v[186:189]
	v_mfma_f32_16x16x32_bf16 v[60:63], v[0:3], v[228:231], v[138:141]
	v_mfma_f32_16x16x32_bf16 v[32:35], v[4:7], v[214:217], v[190:193]
	v_mfma_f32_16x16x32_bf16 v[36:39], v[4:7], v[218:221], v[194:197]
	v_mfma_f32_16x16x32_bf16 v[40:43], v[4:7], v[222:225], v[198:201]
	v_mfma_f32_16x16x32_bf16 v[44:47], v[4:7], v[228:231], v[150:153]
	v_mfma_f32_16x16x32_bf16 v[16:19], v[8:11], v[214:217], v[202:205]
	v_mfma_f32_16x16x32_bf16 v[20:23], v[8:11], v[218:221], v[206:209]
	v_mfma_f32_16x16x32_bf16 v[24:27], v[8:11], v[222:225], v[210:213]
	v_mfma_f32_16x16x32_bf16 v[28:31], v[8:11], v[228:231], v[154:157]
	v_mfma_f32_16x16x32_bf16 v[0:3], v[12:15], v[214:217], v[162:165]
	v_mfma_f32_16x16x32_bf16 v[4:7], v[12:15], v[218:221], v[166:169]
	v_mfma_f32_16x16x32_bf16 v[8:11], v[12:15], v[222:225], v[170:173]
	v_mfma_f32_16x16x32_bf16 v[12:15], v[12:15], v[228:231], v[158:161]
	v_add_u32_e32 v150, s4, v129
	v_or_b32_e32 v151, v150, v147
	v_or_b32_e32 v138, s5, v143
	v_mov_b32_e32 v153, v151
	v_mov_b64_e32 v[140:141], s[94:95]
	s_waitcnt lgkmcnt(0)
	s_barrier
	v_ashrrev_i32_e32 v139, 31, v138
	v_or_b32_e32 v152, v138, v128
	v_mad_i64_i32 v[140:141], s[0:1], v153, s43, v[140:141]
	v_lshl_add_u64 v[140:141], v[138:139], 1, v[140:141]
	v_lshl_add_u64 v[140:141], v[140:141], 0, v[130:131]
	v_cmp_gt_i32_e32 vcc, s44, v152
	s_and_saveexec_b64 s[0:1], vcc
	s_cbranch_execz .LBB0_209
	v_cvt_pk_bf16_f32 v153, v112, v112
	global_store_short_d16_hi v[140:141], v153, off
.LBB0_209:
	s_or_b64 exec, exec, s[0:1]
	v_or_b32_e32 v153, 16, v152
	v_cmp_gt_i32_e64 s[0:1], s44, v153
	s_and_saveexec_b64 s[4:5], s[0:1]
	s_cbranch_execz .LBB0_211
	v_cvt_pk_bf16_f32 v153, v116, v116
	global_store_short_d16_hi v[140:141], v153, off offset:32
.LBB0_211:
	s_or_b64 exec, exec, s[4:5]
	v_or_b32_e32 v153, 32, v152
	v_cmp_gt_i32_e64 s[4:5], s44, v153
	s_and_saveexec_b64 s[6:7], s[4:5]
	s_cbranch_execz .LBB0_213
	v_cvt_pk_bf16_f32 v153, v120, v120
	global_store_short_d16_hi v[140:141], v153, off offset:64
.LBB0_213:
	s_or_b64 exec, exec, s[6:7]
	v_or_b32_e32 v152, 48, v152
	v_cmp_gt_i32_e64 s[6:7], s44, v152
	s_and_saveexec_b64 s[8:9], s[6:7]
	s_cbranch_execz .LBB0_215
	v_cvt_pk_bf16_f32 v152, v124, v124
	global_store_short_d16_hi v[140:141], v152, off offset:96

.LBB0_219:
	v_cvt_pk_bf16_f32 v153, v125, v125
	global_store_short_d16_hi v[140:141], v153, off offset:96

.LBB0_224:
	v_cvt_pk_bf16_f32 v154, v126, v126
	global_store_short_d16_hi v[140:141], v154, off offset:96

.LBB0_229:
	v_cvt_pk_bf16_f32 v155, v127, v127
	global_store_short_d16_hi v[140:141], v155, off offset:96

.LBB0_234:
	v_cvt_pk_bf16_f32 v156, v108, v108
	global_store_short_d16_hi v[140:141], v156, off offset:96

.LBB0_239:
	v_cvt_pk_bf16_f32 v157, v109, v109
	global_store_short_d16_hi v[140:141], v157, off offset:96

.LBB0_244:
	v_cvt_pk_bf16_f32 v158, v110, v110
	global_store_short_d16_hi v[140:141], v158, off offset:96

.LBB0_249:
	v_cvt_pk_bf16_f32 v159, v111, v111
	global_store_short_d16_hi v[140:141], v159, off offset:96

.LBB0_254:
	v_cvt_pk_bf16_f32 v160, v92, v92
	global_store_short_d16_hi v[140:141], v160, off offset:96

.LBB0_259:
	v_cvt_pk_bf16_f32 v161, v93, v93
	global_store_short_d16_hi v[140:141], v161, off offset:96

.LBB0_264:
	v_cvt_pk_bf16_f32 v162, v94, v94
	global_store_short_d16_hi v[140:141], v162, off offset:96

.LBB0_269:
	v_cvt_pk_bf16_f32 v163, v95, v95
	global_store_short_d16_hi v[140:141], v163, off offset:96

.LBB0_274:
	v_cvt_pk_bf16_f32 v164, v76, v76
	global_store_short_d16_hi v[140:141], v164, off offset:96

.LBB0_279:
	v_cvt_pk_bf16_f32 v165, v77, v77
	global_store_short_d16_hi v[140:141], v165, off offset:96

.LBB0_284:
	v_cvt_pk_bf16_f32 v166, v78, v78
	global_store_short_d16_hi v[140:141], v166, off offset:96

.LBB0_289:
	v_cvt_pk_bf16_f32 v167, v79, v79
	global_store_short_d16_hi v[140:141], v167, off offset:96

.LBB0_296:
	v_cvt_pk_bf16_f32 v68, v60, v60
	global_store_short_d16_hi v[64:65], v68, off offset:96

.LBB0_301:
	v_cvt_pk_bf16_f32 v69, v61, v61
	global_store_short_d16_hi v[64:65], v69, off offset:96

.LBB0_306:
	v_cvt_pk_bf16_f32 v70, v62, v62
	global_store_short_d16_hi v[64:65], v70, off offset:96

.LBB0_311:
	v_cvt_pk_bf16_f32 v71, v63, v63
	global_store_short_d16_hi v[64:65], v71, off offset:96

.LBB0_316:
	v_cvt_pk_bf16_f32 v72, v44, v44
	global_store_short_d16_hi v[64:65], v72, off offset:96

.LBB0_321:
	v_cvt_pk_bf16_f32 v73, v45, v45
	global_store_short_d16_hi v[64:65], v73, off offset:96

.LBB0_326:
	v_cvt_pk_bf16_f32 v74, v46, v46
	global_store_short_d16_hi v[64:65], v74, off offset:96

.LBB0_331:
	v_cvt_pk_bf16_f32 v75, v47, v47
	global_store_short_d16_hi v[64:65], v75, off offset:96

.LBB0_336:
	v_cvt_pk_bf16_f32 v76, v28, v28
	global_store_short_d16_hi v[64:65], v76, off offset:96

.LBB0_341:
	v_cvt_pk_bf16_f32 v77, v29, v29
	global_store_short_d16_hi v[64:65], v77, off offset:96

.LBB0_346:
	v_cvt_pk_bf16_f32 v78, v30, v30
	global_store_short_d16_hi v[64:65], v78, off offset:96

.LBB0_351:
	v_cvt_pk_bf16_f32 v79, v31, v31
	global_store_short_d16_hi v[64:65], v79, off offset:96

.LBB0_356:
	v_cvt_pk_bf16_f32 v80, v12, v12
	global_store_short_d16_hi v[64:65], v80, off offset:96

.LBB0_361:
	v_cvt_pk_bf16_f32 v81, v13, v13
	global_store_short_d16_hi v[64:65], v81, off offset:96

.LBB0_366:
	v_cvt_pk_bf16_f32 v82, v14, v14
	global_store_short_d16_hi v[64:65], v82, off offset:96

.LBB0_371:
	v_cvt_pk_bf16_f32 v83, v15, v15
	global_store_short_d16_hi v[64:65], v83, off offset:96

.LBB0_374:
	v_cvt_pk_bf16_f32 v153, v113, v113
	global_store_short_d16_hi v[140:141], v153, off
	s_or_b64 exec, exec, s[8:9]
	s_and_saveexec_b64 s[8:9], s[0:1]
	s_cbranch_execz .LBB0_217
.LBB0_375:
	v_cvt_pk_bf16_f32 v153, v117, v117
	global_store_short_d16_hi v[140:141], v153, off offset:32
	s_or_b64 exec, exec, s[8:9]
	s_and_saveexec_b64 s[8:9], s[4:5]
	s_cbranch_execz .LBB0_218
.LBB0_376:
	v_cvt_pk_bf16_f32 v153, v121, v121
	global_store_short_d16_hi v[140:141], v153, off offset:64
	s_or_b64 exec, exec, s[8:9]
	s_and_saveexec_b64 s[8:9], s[6:7]
	s_cbranch_execnz .LBB0_219
	s_branch .LBB0_220
.LBB0_377:
	v_cvt_pk_bf16_f32 v154, v114, v114
	global_store_short_d16_hi v[140:141], v154, off
	s_or_b64 exec, exec, s[8:9]
	s_and_saveexec_b64 s[8:9], s[0:1]
	s_cbranch_execz .LBB0_222
.LBB0_378:
	v_cvt_pk_bf16_f32 v154, v118, v118
	global_store_short_d16_hi v[140:141], v154, off offset:32
	s_or_b64 exec, exec, s[8:9]
	s_and_saveexec_b64 s[8:9], s[4:5]
	s_cbranch_execz .LBB0_223
.LBB0_379:
	v_cvt_pk_bf16_f32 v154, v122, v122
	global_store_short_d16_hi v[140:141], v154, off offset:64
	s_or_b64 exec, exec, s[8:9]
	s_and_saveexec_b64 s[8:9], s[6:7]
	s_cbranch_execnz .LBB0_224
	s_branch .LBB0_225
.LBB0_380:
	v_cvt_pk_bf16_f32 v155, v115, v115
	global_store_short_d16_hi v[140:141], v155, off
	s_or_b64 exec, exec, s[8:9]
	s_and_saveexec_b64 s[8:9], s[0:1]
	s_cbranch_execz .LBB0_227
.LBB0_381:
	v_cvt_pk_bf16_f32 v155, v119, v119
	global_store_short_d16_hi v[140:141], v155, off offset:32
	s_or_b64 exec, exec, s[8:9]
	s_and_saveexec_b64 s[8:9], s[4:5]
	s_cbranch_execz .LBB0_228
.LBB0_382:
	v_cvt_pk_bf16_f32 v155, v123, v123
	global_store_short_d16_hi v[140:141], v155, off offset:64
	s_or_b64 exec, exec, s[8:9]
	s_and_saveexec_b64 s[8:9], s[6:7]
	s_cbranch_execnz .LBB0_229
	s_branch .LBB0_230
.LBB0_383:
	v_cvt_pk_bf16_f32 v156, v96, v96
	global_store_short_d16_hi v[140:141], v156, off
	s_or_b64 exec, exec, s[8:9]
	s_and_saveexec_b64 s[8:9], s[0:1]
	s_cbranch_execz .LBB0_232
.LBB0_384:
	v_cvt_pk_bf16_f32 v156, v100, v100
	global_store_short_d16_hi v[140:141], v156, off offset:32
	s_or_b64 exec, exec, s[8:9]
	s_and_saveexec_b64 s[8:9], s[4:5]
	s_cbranch_execz .LBB0_233
.LBB0_385:
	v_cvt_pk_bf16_f32 v156, v104, v104
	global_store_short_d16_hi v[140:141], v156, off offset:64
	s_or_b64 exec, exec, s[8:9]
	s_and_saveexec_b64 s[8:9], s[6:7]
	s_cbranch_execnz .LBB0_234
	s_branch .LBB0_235
.LBB0_386:
	v_cvt_pk_bf16_f32 v157, v97, v97
	global_store_short_d16_hi v[140:141], v157, off
	s_or_b64 exec, exec, s[8:9]
	s_and_saveexec_b64 s[8:9], s[0:1]
	s_cbranch_execz .LBB0_237
.LBB0_387:
	v_cvt_pk_bf16_f32 v157, v101, v101
	global_store_short_d16_hi v[140:141], v157, off offset:32
	s_or_b64 exec, exec, s[8:9]
	s_and_saveexec_b64 s[8:9], s[4:5]
	s_cbranch_execz .LBB0_238
.LBB0_388:
	v_cvt_pk_bf16_f32 v157, v105, v105
	global_store_short_d16_hi v[140:141], v157, off offset:64
	s_or_b64 exec, exec, s[8:9]
	s_and_saveexec_b64 s[8:9], s[6:7]
	s_cbranch_execnz .LBB0_239
	s_branch .LBB0_240
.LBB0_389:
	v_cvt_pk_bf16_f32 v158, v98, v98
	global_store_short_d16_hi v[140:141], v158, off
	s_or_b64 exec, exec, s[8:9]
	s_and_saveexec_b64 s[8:9], s[0:1]
	s_cbranch_execz .LBB0_242
.LBB0_390:
	v_cvt_pk_bf16_f32 v158, v102, v102
	global_store_short_d16_hi v[140:141], v158, off offset:32
	s_or_b64 exec, exec, s[8:9]
	s_and_saveexec_b64 s[8:9], s[4:5]
	s_cbranch_execz .LBB0_243
.LBB0_391:
	v_cvt_pk_bf16_f32 v158, v106, v106
	global_store_short_d16_hi v[140:141], v158, off offset:64
	s_or_b64 exec, exec, s[8:9]
	s_and_saveexec_b64 s[8:9], s[6:7]
	s_cbranch_execnz .LBB0_244
	s_branch .LBB0_245
.LBB0_392:
	v_cvt_pk_bf16_f32 v159, v99, v99
	global_store_short_d16_hi v[140:141], v159, off
	s_or_b64 exec, exec, s[8:9]
	s_and_saveexec_b64 s[8:9], s[0:1]
	s_cbranch_execz .LBB0_247
.LBB0_393:
	v_cvt_pk_bf16_f32 v159, v103, v103
	global_store_short_d16_hi v[140:141], v159, off offset:32
	s_or_b64 exec, exec, s[8:9]
	s_and_saveexec_b64 s[8:9], s[4:5]
	s_cbranch_execz .LBB0_248
.LBB0_394:
	v_cvt_pk_bf16_f32 v159, v107, v107
	global_store_short_d16_hi v[140:141], v159, off offset:64
	s_or_b64 exec, exec, s[8:9]
	s_and_saveexec_b64 s[8:9], s[6:7]
	s_cbranch_execnz .LBB0_249
	s_branch .LBB0_250
.LBB0_395:
	v_cvt_pk_bf16_f32 v160, v80, v80
	global_store_short_d16_hi v[140:141], v160, off
	s_or_b64 exec, exec, s[8:9]
	s_and_saveexec_b64 s[8:9], s[0:1]
	s_cbranch_execz .LBB0_252
.LBB0_396:
	v_cvt_pk_bf16_f32 v160, v84, v84
	global_store_short_d16_hi v[140:141], v160, off offset:32
	s_or_b64 exec, exec, s[8:9]
	s_and_saveexec_b64 s[8:9], s[4:5]
	s_cbranch_execz .LBB0_253
.LBB0_397:
	v_cvt_pk_bf16_f32 v160, v88, v88
	global_store_short_d16_hi v[140:141], v160, off offset:64
	s_or_b64 exec, exec, s[8:9]
	s_and_saveexec_b64 s[8:9], s[6:7]
	s_cbranch_execnz .LBB0_254
	s_branch .LBB0_255
.LBB0_398:
	v_cvt_pk_bf16_f32 v161, v81, v81
	global_store_short_d16_hi v[140:141], v161, off
	s_or_b64 exec, exec, s[8:9]
	s_and_saveexec_b64 s[8:9], s[0:1]
	s_cbranch_execz .LBB0_257
.LBB0_399:
	v_cvt_pk_bf16_f32 v161, v85, v85
	global_store_short_d16_hi v[140:141], v161, off offset:32
	s_or_b64 exec, exec, s[8:9]
	s_and_saveexec_b64 s[8:9], s[4:5]
	s_cbranch_execz .LBB0_258
.LBB0_400:
	v_cvt_pk_bf16_f32 v161, v89, v89
	global_store_short_d16_hi v[140:141], v161, off offset:64
	s_or_b64 exec, exec, s[8:9]
	s_and_saveexec_b64 s[8:9], s[6:7]
	s_cbranch_execnz .LBB0_259
	s_branch .LBB0_260
.LBB0_401:
	v_cvt_pk_bf16_f32 v162, v82, v82
	global_store_short_d16_hi v[140:141], v162, off
	s_or_b64 exec, exec, s[8:9]
	s_and_saveexec_b64 s[8:9], s[0:1]
	s_cbranch_execz .LBB0_262
.LBB0_402:
	v_cvt_pk_bf16_f32 v162, v86, v86
	global_store_short_d16_hi v[140:141], v162, off offset:32
	s_or_b64 exec, exec, s[8:9]
	s_and_saveexec_b64 s[8:9], s[4:5]
	s_cbranch_execz .LBB0_263
.LBB0_403:
	v_cvt_pk_bf16_f32 v162, v90, v90
	global_store_short_d16_hi v[140:141], v162, off offset:64
	s_or_b64 exec, exec, s[8:9]
	s_and_saveexec_b64 s[8:9], s[6:7]
	s_cbranch_execnz .LBB0_264
	s_branch .LBB0_265
.LBB0_404:
	v_cvt_pk_bf16_f32 v163, v83, v83
	global_store_short_d16_hi v[140:141], v163, off
	s_or_b64 exec, exec, s[8:9]
	s_and_saveexec_b64 s[8:9], s[0:1]
	s_cbranch_execz .LBB0_267
.LBB0_405:
	v_cvt_pk_bf16_f32 v163, v87, v87
	global_store_short_d16_hi v[140:141], v163, off offset:32
	s_or_b64 exec, exec, s[8:9]
	s_and_saveexec_b64 s[8:9], s[4:5]
	s_cbranch_execz .LBB0_268
.LBB0_406:
	v_cvt_pk_bf16_f32 v163, v91, v91
	global_store_short_d16_hi v[140:141], v163, off offset:64
	s_or_b64 exec, exec, s[8:9]
	s_and_saveexec_b64 s[8:9], s[6:7]
	s_cbranch_execnz .LBB0_269
	s_branch .LBB0_270
.LBB0_407:
	v_cvt_pk_bf16_f32 v164, v64, v64
	global_store_short_d16_hi v[140:141], v164, off
	s_or_b64 exec, exec, s[8:9]
	s_and_saveexec_b64 s[8:9], s[0:1]
	s_cbranch_execz .LBB0_272
.LBB0_408:
	v_cvt_pk_bf16_f32 v164, v68, v68
	global_store_short_d16_hi v[140:141], v164, off offset:32
	s_or_b64 exec, exec, s[8:9]
	s_and_saveexec_b64 s[8:9], s[4:5]
	s_cbranch_execz .LBB0_273
.LBB0_409:
	v_cvt_pk_bf16_f32 v164, v72, v72
	global_store_short_d16_hi v[140:141], v164, off offset:64
	s_or_b64 exec, exec, s[8:9]
	s_and_saveexec_b64 s[8:9], s[6:7]
	s_cbranch_execnz .LBB0_274
	s_branch .LBB0_275
.LBB0_410:
	v_cvt_pk_bf16_f32 v165, v65, v65
	global_store_short_d16_hi v[140:141], v165, off
	s_or_b64 exec, exec, s[8:9]
	s_and_saveexec_b64 s[8:9], s[0:1]
	s_cbranch_execz .LBB0_277
.LBB0_411:
	v_cvt_pk_bf16_f32 v165, v69, v69
	global_store_short_d16_hi v[140:141], v165, off offset:32
	s_or_b64 exec, exec, s[8:9]
	s_and_saveexec_b64 s[8:9], s[4:5]
	s_cbranch_execz .LBB0_278
.LBB0_412:
	v_cvt_pk_bf16_f32 v165, v73, v73
	global_store_short_d16_hi v[140:141], v165, off offset:64
	s_or_b64 exec, exec, s[8:9]
	s_and_saveexec_b64 s[8:9], s[6:7]
	s_cbranch_execnz .LBB0_279
	s_branch .LBB0_280
.LBB0_413:
	v_cvt_pk_bf16_f32 v166, v66, v66
	global_store_short_d16_hi v[140:141], v166, off
	s_or_b64 exec, exec, s[8:9]
	s_and_saveexec_b64 s[8:9], s[0:1]
	s_cbranch_execz .LBB0_282
.LBB0_414:
	v_cvt_pk_bf16_f32 v166, v70, v70
	global_store_short_d16_hi v[140:141], v166, off offset:32
	s_or_b64 exec, exec, s[8:9]
	s_and_saveexec_b64 s[8:9], s[4:5]
	s_cbranch_execz .LBB0_283
.LBB0_415:
	v_cvt_pk_bf16_f32 v166, v74, v74
	global_store_short_d16_hi v[140:141], v166, off offset:64
	s_or_b64 exec, exec, s[8:9]
	s_and_saveexec_b64 s[8:9], s[6:7]
	s_cbranch_execnz .LBB0_284
	s_branch .LBB0_285
.LBB0_416:
	v_cvt_pk_bf16_f32 v167, v67, v67
	global_store_short_d16_hi v[140:141], v167, off
	s_or_b64 exec, exec, s[8:9]
	s_and_saveexec_b64 s[8:9], s[0:1]
	s_cbranch_execz .LBB0_287
.LBB0_417:
	v_cvt_pk_bf16_f32 v167, v71, v71
	global_store_short_d16_hi v[140:141], v167, off offset:32
	s_or_b64 exec, exec, s[8:9]
	s_and_saveexec_b64 s[8:9], s[4:5]
	s_cbranch_execz .LBB0_288
.LBB0_418:
	v_cvt_pk_bf16_f32 v167, v75, v75
	global_store_short_d16_hi v[140:141], v167, off offset:64
	s_or_b64 exec, exec, s[8:9]
	s_and_saveexec_b64 s[8:9], s[6:7]
	s_cbranch_execnz .LBB0_289
	s_branch .LBB0_290
.LBB0_419:
	v_cvt_pk_bf16_f32 v68, v48, v48
	global_store_short_d16_hi v[64:65], v68, off
	s_or_b64 exec, exec, s[8:9]
	s_and_saveexec_b64 s[8:9], s[0:1]
	s_cbranch_execz .LBB0_294
.LBB0_420:
	v_cvt_pk_bf16_f32 v68, v52, v52
	global_store_short_d16_hi v[64:65], v68, off offset:32
	s_or_b64 exec, exec, s[8:9]
	s_and_saveexec_b64 s[8:9], s[4:5]
	s_cbranch_execz .LBB0_295
.LBB0_421:
	v_cvt_pk_bf16_f32 v68, v56, v56
	global_store_short_d16_hi v[64:65], v68, off offset:64
	s_or_b64 exec, exec, s[8:9]
	s_and_saveexec_b64 s[8:9], s[6:7]
	s_cbranch_execnz .LBB0_296
	s_branch .LBB0_297
.LBB0_422:
	v_cvt_pk_bf16_f32 v69, v49, v49
	global_store_short_d16_hi v[64:65], v69, off
	s_or_b64 exec, exec, s[8:9]
	s_and_saveexec_b64 s[8:9], s[0:1]
	s_cbranch_execz .LBB0_299
.LBB0_423:
	v_cvt_pk_bf16_f32 v69, v53, v53
	global_store_short_d16_hi v[64:65], v69, off offset:32
	s_or_b64 exec, exec, s[8:9]
	s_and_saveexec_b64 s[8:9], s[4:5]
	s_cbranch_execz .LBB0_300
.LBB0_424:
	v_cvt_pk_bf16_f32 v69, v57, v57
	global_store_short_d16_hi v[64:65], v69, off offset:64
	s_or_b64 exec, exec, s[8:9]
	s_and_saveexec_b64 s[8:9], s[6:7]
	s_cbranch_execnz .LBB0_301
	s_branch .LBB0_302
.LBB0_425:
	v_cvt_pk_bf16_f32 v70, v50, v50
	global_store_short_d16_hi v[64:65], v70, off
	s_or_b64 exec, exec, s[8:9]
	s_and_saveexec_b64 s[8:9], s[0:1]
	s_cbranch_execz .LBB0_304
.LBB0_426:
	v_cvt_pk_bf16_f32 v70, v54, v54
	global_store_short_d16_hi v[64:65], v70, off offset:32
	s_or_b64 exec, exec, s[8:9]
	s_and_saveexec_b64 s[8:9], s[4:5]
	s_cbranch_execz .LBB0_305
.LBB0_427:
	v_cvt_pk_bf16_f32 v70, v58, v58
	global_store_short_d16_hi v[64:65], v70, off offset:64
	s_or_b64 exec, exec, s[8:9]
	s_and_saveexec_b64 s[8:9], s[6:7]
	s_cbranch_execnz .LBB0_306
	s_branch .LBB0_307
.LBB0_428:
	v_cvt_pk_bf16_f32 v71, v51, v51
	global_store_short_d16_hi v[64:65], v71, off
	s_or_b64 exec, exec, s[8:9]
	s_and_saveexec_b64 s[8:9], s[0:1]
	s_cbranch_execz .LBB0_309
.LBB0_429:
	v_cvt_pk_bf16_f32 v71, v55, v55
	global_store_short_d16_hi v[64:65], v71, off offset:32
	s_or_b64 exec, exec, s[8:9]
	s_and_saveexec_b64 s[8:9], s[4:5]
	s_cbranch_execz .LBB0_310
.LBB0_430:
	v_cvt_pk_bf16_f32 v71, v59, v59
	global_store_short_d16_hi v[64:65], v71, off offset:64
	s_or_b64 exec, exec, s[8:9]
	s_and_saveexec_b64 s[8:9], s[6:7]
	s_cbranch_execnz .LBB0_311
	s_branch .LBB0_312
.LBB0_431:
	v_cvt_pk_bf16_f32 v72, v32, v32
	global_store_short_d16_hi v[64:65], v72, off
	s_or_b64 exec, exec, s[8:9]
	s_and_saveexec_b64 s[8:9], s[0:1]
	s_cbranch_execz .LBB0_314
.LBB0_432:
	v_cvt_pk_bf16_f32 v72, v36, v36
	global_store_short_d16_hi v[64:65], v72, off offset:32
	s_or_b64 exec, exec, s[8:9]
	s_and_saveexec_b64 s[8:9], s[4:5]
	s_cbranch_execz .LBB0_315
.LBB0_433:
	v_cvt_pk_bf16_f32 v72, v40, v40
	global_store_short_d16_hi v[64:65], v72, off offset:64
	s_or_b64 exec, exec, s[8:9]
	s_and_saveexec_b64 s[8:9], s[6:7]
	s_cbranch_execnz .LBB0_316
	s_branch .LBB0_317
.LBB0_434:
	v_cvt_pk_bf16_f32 v73, v33, v33
	global_store_short_d16_hi v[64:65], v73, off
	s_or_b64 exec, exec, s[8:9]
	s_and_saveexec_b64 s[8:9], s[0:1]
	s_cbranch_execz .LBB0_319
.LBB0_435:
	v_cvt_pk_bf16_f32 v73, v37, v37
	global_store_short_d16_hi v[64:65], v73, off offset:32
	s_or_b64 exec, exec, s[8:9]
	s_and_saveexec_b64 s[8:9], s[4:5]
	s_cbranch_execz .LBB0_320
.LBB0_436:
	v_cvt_pk_bf16_f32 v73, v41, v41
	global_store_short_d16_hi v[64:65], v73, off offset:64
	s_or_b64 exec, exec, s[8:9]
	s_and_saveexec_b64 s[8:9], s[6:7]
	s_cbranch_execnz .LBB0_321
	s_branch .LBB0_322
.LBB0_437:
	v_cvt_pk_bf16_f32 v74, v34, v34
	global_store_short_d16_hi v[64:65], v74, off
	s_or_b64 exec, exec, s[8:9]
	s_and_saveexec_b64 s[8:9], s[0:1]
	s_cbranch_execz .LBB0_324
.LBB0_438:
	v_cvt_pk_bf16_f32 v74, v38, v38
	global_store_short_d16_hi v[64:65], v74, off offset:32
	s_or_b64 exec, exec, s[8:9]
	s_and_saveexec_b64 s[8:9], s[4:5]
	s_cbranch_execz .LBB0_325
.LBB0_439:
	v_cvt_pk_bf16_f32 v74, v42, v42
	global_store_short_d16_hi v[64:65], v74, off offset:64
	s_or_b64 exec, exec, s[8:9]
	s_and_saveexec_b64 s[8:9], s[6:7]
	s_cbranch_execnz .LBB0_326
	s_branch .LBB0_327
.LBB0_440:
	v_cvt_pk_bf16_f32 v75, v35, v35
	global_store_short_d16_hi v[64:65], v75, off
	s_or_b64 exec, exec, s[8:9]
	s_and_saveexec_b64 s[8:9], s[0:1]
	s_cbranch_execz .LBB0_329
.LBB0_441:
	v_cvt_pk_bf16_f32 v75, v39, v39
	global_store_short_d16_hi v[64:65], v75, off offset:32
	s_or_b64 exec, exec, s[8:9]
	s_and_saveexec_b64 s[8:9], s[4:5]
	s_cbranch_execz .LBB0_330
.LBB0_442:
	v_cvt_pk_bf16_f32 v75, v43, v43
	global_store_short_d16_hi v[64:65], v75, off offset:64
	s_or_b64 exec, exec, s[8:9]
	s_and_saveexec_b64 s[8:9], s[6:7]
	s_cbranch_execnz .LBB0_331
	s_branch .LBB0_332
.LBB0_443:
	v_cvt_pk_bf16_f32 v76, v16, v16
	global_store_short_d16_hi v[64:65], v76, off
	s_or_b64 exec, exec, s[8:9]
	s_and_saveexec_b64 s[8:9], s[0:1]
	s_cbranch_execz .LBB0_334
.LBB0_444:
	v_cvt_pk_bf16_f32 v76, v20, v20
	global_store_short_d16_hi v[64:65], v76, off offset:32
	s_or_b64 exec, exec, s[8:9]
	s_and_saveexec_b64 s[8:9], s[4:5]
	s_cbranch_execz .LBB0_335
.LBB0_445:
	v_cvt_pk_bf16_f32 v76, v24, v24
	global_store_short_d16_hi v[64:65], v76, off offset:64
	s_or_b64 exec, exec, s[8:9]
	s_and_saveexec_b64 s[8:9], s[6:7]
	s_cbranch_execnz .LBB0_336
	s_branch .LBB0_337
.LBB0_446:
	v_cvt_pk_bf16_f32 v77, v17, v17
	global_store_short_d16_hi v[64:65], v77, off
	s_or_b64 exec, exec, s[8:9]
	s_and_saveexec_b64 s[8:9], s[0:1]
	s_cbranch_execz .LBB0_339
.LBB0_447:
	v_cvt_pk_bf16_f32 v77, v21, v21
	global_store_short_d16_hi v[64:65], v77, off offset:32
	s_or_b64 exec, exec, s[8:9]
	s_and_saveexec_b64 s[8:9], s[4:5]
	s_cbranch_execz .LBB0_340
.LBB0_448:
	v_cvt_pk_bf16_f32 v77, v25, v25
	global_store_short_d16_hi v[64:65], v77, off offset:64
	s_or_b64 exec, exec, s[8:9]
	s_and_saveexec_b64 s[8:9], s[6:7]
	s_cbranch_execnz .LBB0_341
	s_branch .LBB0_342
.LBB0_449:
	v_cvt_pk_bf16_f32 v78, v18, v18
	global_store_short_d16_hi v[64:65], v78, off
	s_or_b64 exec, exec, s[8:9]
	s_and_saveexec_b64 s[8:9], s[0:1]
	s_cbranch_execz .LBB0_344
.LBB0_450:
	v_cvt_pk_bf16_f32 v78, v22, v22
	global_store_short_d16_hi v[64:65], v78, off offset:32
	s_or_b64 exec, exec, s[8:9]
	s_and_saveexec_b64 s[8:9], s[4:5]
	s_cbranch_execz .LBB0_345
.LBB0_451:
	v_cvt_pk_bf16_f32 v78, v26, v26
	global_store_short_d16_hi v[64:65], v78, off offset:64
	s_or_b64 exec, exec, s[8:9]
	s_and_saveexec_b64 s[8:9], s[6:7]
	s_cbranch_execnz .LBB0_346
	s_branch .LBB0_347
.LBB0_452:
	v_cvt_pk_bf16_f32 v79, v19, v19
	global_store_short_d16_hi v[64:65], v79, off
	s_or_b64 exec, exec, s[8:9]
	s_and_saveexec_b64 s[8:9], s[0:1]
	s_cbranch_execz .LBB0_349
.LBB0_453:
	v_cvt_pk_bf16_f32 v79, v23, v23
	global_store_short_d16_hi v[64:65], v79, off offset:32
	s_or_b64 exec, exec, s[8:9]
	s_and_saveexec_b64 s[8:9], s[4:5]
	s_cbranch_execz .LBB0_350
.LBB0_454:
	v_cvt_pk_bf16_f32 v79, v27, v27
	global_store_short_d16_hi v[64:65], v79, off offset:64
	s_or_b64 exec, exec, s[8:9]
	s_and_saveexec_b64 s[8:9], s[6:7]
	s_cbranch_execnz .LBB0_351
	s_branch .LBB0_352
.LBB0_455:
	v_cvt_pk_bf16_f32 v80, v0, v0
	global_store_short_d16_hi v[64:65], v80, off
	s_or_b64 exec, exec, s[8:9]
	s_and_saveexec_b64 s[8:9], s[0:1]
	s_cbranch_execz .LBB0_354
.LBB0_456:
	v_cvt_pk_bf16_f32 v80, v4, v4
	global_store_short_d16_hi v[64:65], v80, off offset:32
	s_or_b64 exec, exec, s[8:9]
	s_and_saveexec_b64 s[8:9], s[4:5]
	s_cbranch_execz .LBB0_355
.LBB0_457:
	v_cvt_pk_bf16_f32 v80, v8, v8
	global_store_short_d16_hi v[64:65], v80, off offset:64
	s_or_b64 exec, exec, s[8:9]
	s_and_saveexec_b64 s[8:9], s[6:7]
	s_cbranch_execnz .LBB0_356
	s_branch .LBB0_357
.LBB0_458:
	v_cvt_pk_bf16_f32 v81, v1, v1
	global_store_short_d16_hi v[64:65], v81, off
	s_or_b64 exec, exec, s[8:9]
	s_and_saveexec_b64 s[8:9], s[0:1]
	s_cbranch_execz .LBB0_359
.LBB0_459:
	v_cvt_pk_bf16_f32 v81, v5, v5
	global_store_short_d16_hi v[64:65], v81, off offset:32
	s_or_b64 exec, exec, s[8:9]
	s_and_saveexec_b64 s[8:9], s[4:5]
	s_cbranch_execz .LBB0_360
.LBB0_460:
	v_cvt_pk_bf16_f32 v81, v9, v9
	global_store_short_d16_hi v[64:65], v81, off offset:64
	s_or_b64 exec, exec, s[8:9]
	s_and_saveexec_b64 s[8:9], s[6:7]
	s_cbranch_execnz .LBB0_361
	s_branch .LBB0_362
.LBB0_461:
	v_cvt_pk_bf16_f32 v82, v2, v2
	global_store_short_d16_hi v[64:65], v82, off
	s_or_b64 exec, exec, s[8:9]
	s_and_saveexec_b64 s[8:9], s[0:1]
	s_cbranch_execz .LBB0_364
.LBB0_462:
	v_cvt_pk_bf16_f32 v82, v6, v6
	global_store_short_d16_hi v[64:65], v82, off offset:32
	s_or_b64 exec, exec, s[8:9]
	s_and_saveexec_b64 s[8:9], s[4:5]
	s_cbranch_execz .LBB0_365
.LBB0_463:
	v_cvt_pk_bf16_f32 v82, v10, v10
	global_store_short_d16_hi v[64:65], v82, off offset:64
	s_or_b64 exec, exec, s[8:9]
	s_and_saveexec_b64 s[8:9], s[6:7]
	s_cbranch_execnz .LBB0_366
	s_branch .LBB0_367
.LBB0_464:
	v_cvt_pk_bf16_f32 v83, v3, v3
	global_store_short_d16_hi v[64:65], v83, off
	s_or_b64 exec, exec, s[8:9]
	s_and_saveexec_b64 s[8:9], s[0:1]
	s_cbranch_execz .LBB0_369
.LBB0_465:
	v_cvt_pk_bf16_f32 v83, v7, v7
	global_store_short_d16_hi v[64:65], v83, off offset:32
	s_or_b64 exec, exec, s[8:9]
	s_and_saveexec_b64 s[0:1], s[4:5]
	s_cbranch_execz .LBB0_370
.LBB0_466:
	v_cvt_pk_bf16_f32 v83, v11, v11
	global_store_short_d16_hi v[64:65], v83, off offset:64
	s_or_b64 exec, exec, s[0:1]
	s_and_saveexec_b64 s[0:1], s[6:7]
	s_cbranch_execnz .LBB0_371
	s_branch .LBB0_372

.LBB0_522:
	s_or_b64 exec, exec, s[6:7]
	v_cvt_pk_bf16_f32 v12, v12, v12
	v_lshrrev_b32_e32 v12, 16, v12
	v_cvt_pk_bf16_f32 v13, v13, v13
	v_and_or_b32 v14, v13, s2, v12
	v_cvt_pk_bf16_f32 v8, v8, v8
	v_lshrrev_b32_e32 v8, 16, v8
	v_cvt_pk_bf16_f32 v9, v9, v9
	v_and_or_b32 v13, v9, s2, v8
	v_cvt_pk_bf16_f32 v8, v28, v28
	v_lshrrev_b32_e32 v8, 16, v8
	v_cvt_pk_bf16_f32 v9, v29, v29
	v_and_or_b32 v12, v9, s2, v8
	v_cvt_pk_bf16_f32 v8, v10, v10
	v_add_u32_e32 v32, s10, v32
	s_movk_i32 s6, 0x4fff
	v_lshrrev_b32_e32 v8, 16, v8
	v_cvt_pk_bf16_f32 v9, v11, v11
	v_cmp_lt_i32_e32 vcc, s6, v32
	v_and_or_b32 v15, v9, s2, v8
	v_lshl_add_u64 v[8:9], v[26:27], 0, v[20:21]
	v_lshl_add_u64 v[24:25], v[24:25], 0, s[12:13]
	s_or_b64 s[16:17], vcc, s[16:17]
	v_lshl_add_u64 v[26:27], v[26:27], 0, s[14:15]
	global_store_dwordx4 v[8:9], v[12:15], off
	s_andn2_b64 exec, exec, s[16:17]
	s_cbranch_execz .LBB0_578

.LBB0_632:
	s_or_b64 exec, exec, s[34:35]
	v_readlane_b32 s56, v241, 17
	v_and_b32_sdwa v6, v5, v89 dst_sel:DWORD dst_unused:UNUSED_PAD src0_sel:WORD_1 src1_sel:DWORD
	v_and_b32_sdwa v7, v4, v89 dst_sel:DWORD dst_unused:UNUSED_PAD src0_sel:WORD_1 src1_sel:DWORD
	v_readlane_b32 s58, v241, 19
	v_readlane_b32 s59, v241, 20
	v_add3_u32 v4, v4, v7, s52
	v_add3_u32 v5, v5, v6, s52
	v_mov_b64_e32 v[2:3], s[58:59]
	v_cvt_pk_bf16_f32 v1, v1, v1
	v_cvt_pk_bf16_f32 v0, v0, v0
	v_mad_i64_i32 v[2:3], s[30:31], v58, s51, v[2:3]
	v_and_b32_e32 v1, 0xffff0000, v1
	v_and_b32_e32 v0, 0xffff0000, v0
	s_add_i32 s2, s2, s3
	s_add_i32 s37, s37, s38
	v_lshl_add_u64 v[2:3], v[78:79], 1, v[2:3]
	v_or_b32_sdwa v1, v1, v5 dst_sel:DWORD dst_unused:UNUSED_PAD src0_sel:DWORD src1_sel:WORD_1
	v_or_b32_sdwa v0, v0, v4 dst_sel:DWORD dst_unused:UNUSED_PAD src0_sel:DWORD src1_sel:WORD_1
	s_cmpk_lt_i32 s2, 0xc8
	v_readlane_b32 s57, v241, 18
	v_readlane_b32 s60, v241, 21
	v_readlane_b32 s61, v241, 22
	v_readlane_b32 s62, v241, 23
	v_readlane_b32 s63, v241, 24
	global_store_dwordx2 v[2:3], v[0:1], off offset:96
	s_cbranch_scc0 .LBB0_689

.LBB0_640:
	s_or_b64 exec, exec, s[34:35]
	v_mad_i64_i32 v[68:69], s[34:35], v70, s51, v[76:77]
	v_and_b32_sdwa v70, v55, v89 dst_sel:DWORD dst_unused:UNUSED_PAD src0_sel:WORD_1 src1_sel:DWORD
	v_and_b32_sdwa v91, v54, v89 dst_sel:DWORD dst_unused:UNUSED_PAD src0_sel:WORD_1 src1_sel:DWORD
	v_add3_u32 v54, v54, v91, s52
	v_add3_u32 v55, v55, v70, s52
	v_cvt_pk_bf16_f32 v67, v67, v67
	v_cvt_pk_bf16_f32 v66, v66, v66
	v_and_b32_e32 v67, 0xffff0000, v67
	v_and_b32_e32 v66, 0xffff0000, v66
	v_lshl_add_u64 v[68:69], v[78:79], 1, v[68:69]
	v_or_b32_sdwa v55, v67, v55 dst_sel:DWORD dst_unused:UNUSED_PAD src0_sel:DWORD src1_sel:WORD_1
	v_or_b32_sdwa v54, v66, v54 dst_sel:DWORD dst_unused:UNUSED_PAD src0_sel:DWORD src1_sel:WORD_1
	global_store_dwordx2 v[68:69], v[54:55], off
	v_or_b32_e32 v66, 16, v90
	v_mov_b32_e32 v54, v62
	v_mov_b32_e32 v55, v64
	v_mov_b32_e32 v64, v63
	v_mov_b32_e32 v67, v66
	v_pk_add_f32 v[54:55], v[54:55], v[52:53]
	v_pk_add_f32 v[62:63], v[64:65], v[56:57]
	s_and_saveexec_b64 s[34:35], s[30:31]
	s_cbranch_execz .LBB0_642
	v_mul_f32_e32 v54, 0xbfb8aa3b, v54
	v_mul_f32_e32 v55, 0xbfb8aa3b, v55
	v_exp_f32_e32 v54, v54
	v_exp_f32_e32 v55, v55
	v_mul_f32_e32 v62, 0xbfb8aa3b, v62
	v_mul_f32_e32 v63, 0xbfb8aa3b, v63
	v_exp_f32_e32 v62, v62
	v_pk_add_f32 v[54:55], v[54:55], 1.0 op_sel_hi:[1,0]
	v_exp_f32_e32 v63, v63
	v_rcp_f32_e32 v65, v55
	v_pk_add_f32 v[62:63], v[62:63], 1.0 op_sel_hi:[1,0]
	v_mul_f32_e32 v55, 1.0, v65
	v_rcp_f32_e32 v65, v54
	s_nop 0
	v_mul_f32_e32 v54, 1.0, v65
	v_rcp_f32_e32 v65, v63
	s_nop 0
	v_mul_f32_e32 v63, 1.0, v65
	v_rcp_f32_e32 v65, v62
	s_nop 0
	v_mul_f32_e32 v62, 1.0, v65
.LBB0_642:
	s_or_b64 exec, exec, s[34:35]
	v_mad_i64_i32 v[64:65], s[34:35], v67, s51, v[76:77]
	v_and_b32_sdwa v67, v55, v89 dst_sel:DWORD dst_unused:UNUSED_PAD src0_sel:WORD_1 src1_sel:DWORD
	v_and_b32_sdwa v68, v54, v89 dst_sel:DWORD dst_unused:UNUSED_PAD src0_sel:WORD_1 src1_sel:DWORD
	v_add3_u32 v54, v54, v68, s52
	v_add3_u32 v55, v55, v67, s52
	v_cvt_pk_bf16_f32 v63, v63, v63
	v_cvt_pk_bf16_f32 v62, v62, v62
	v_and_b32_e32 v63, 0xffff0000, v63
	v_and_b32_e32 v62, 0xffff0000, v62
	v_lshl_add_u64 v[64:65], v[78:79], 1, v[64:65]
	v_or_b32_sdwa v55, v63, v55 dst_sel:DWORD dst_unused:UNUSED_PAD src0_sel:DWORD src1_sel:WORD_1
	v_or_b32_sdwa v54, v62, v54 dst_sel:DWORD dst_unused:UNUSED_PAD src0_sel:DWORD src1_sel:WORD_1
	global_store_dwordx2 v[64:65], v[54:55], off
	v_or_b32_e32 v62, 32, v90
	v_mov_b32_e32 v54, v58
	v_mov_b32_e32 v55, v60
	v_mov_b32_e32 v60, v59
	v_mov_b32_e32 v63, v62
	v_pk_add_f32 v[54:55], v[54:55], v[52:53]
	v_pk_add_f32 v[58:59], v[60:61], v[56:57]
	s_and_saveexec_b64 s[34:35], s[30:31]
	s_cbranch_execz .LBB0_644
	v_mul_f32_e32 v54, 0xbfb8aa3b, v54
	v_mul_f32_e32 v55, 0xbfb8aa3b, v55
	v_exp_f32_e32 v54, v54
	v_exp_f32_e32 v55, v55
	v_mul_f32_e32 v58, 0xbfb8aa3b, v58
	v_mul_f32_e32 v59, 0xbfb8aa3b, v59
	v_exp_f32_e32 v58, v58
	v_pk_add_f32 v[54:55], v[54:55], 1.0 op_sel_hi:[1,0]
	v_exp_f32_e32 v59, v59
	v_rcp_f32_e32 v61, v55
	v_pk_add_f32 v[58:59], v[58:59], 1.0 op_sel_hi:[1,0]
	v_mul_f32_e32 v55, 1.0, v61
	v_rcp_f32_e32 v61, v54
	s_nop 0
	v_mul_f32_e32 v54, 1.0, v61
	v_rcp_f32_e32 v61, v59
	s_nop 0
	v_mul_f32_e32 v59, 1.0, v61
	v_rcp_f32_e32 v61, v58
	s_nop 0
	v_mul_f32_e32 v58, 1.0, v61
.LBB0_644:
	s_or_b64 exec, exec, s[34:35]
	v_readlane_b32 s56, v241, 17
	v_readlane_b32 s58, v241, 19
	v_readlane_b32 s59, v241, 20
	v_and_b32_sdwa v64, v54, v89 dst_sel:DWORD dst_unused:UNUSED_PAD src0_sel:WORD_1 src1_sel:DWORD
	v_add3_u32 v54, v54, v64, s52
	v_mov_b64_e32 v[60:61], s[58:59]
	v_mad_i64_i32 v[60:61], s[34:35], v63, s51, v[60:61]
	v_and_b32_sdwa v63, v55, v89 dst_sel:DWORD dst_unused:UNUSED_PAD src0_sel:WORD_1 src1_sel:DWORD
	v_add3_u32 v55, v55, v63, s52
	v_cvt_pk_bf16_f32 v59, v59, v59
	v_cvt_pk_bf16_f32 v58, v58, v58
	v_and_b32_e32 v59, 0xffff0000, v59
	v_and_b32_e32 v58, 0xffff0000, v58
	v_lshl_add_u64 v[60:61], v[78:79], 1, v[60:61]
	v_or_b32_sdwa v55, v59, v55 dst_sel:DWORD dst_unused:UNUSED_PAD src0_sel:DWORD src1_sel:WORD_1
	v_or_b32_sdwa v54, v58, v54 dst_sel:DWORD dst_unused:UNUSED_PAD src0_sel:DWORD src1_sel:WORD_1
	global_store_dwordx2 v[60:61], v[54:55], off
	v_or_b32_e32 v58, 48, v90
	v_mov_b32_e32 v60, v48
	v_mov_b32_e32 v61, v50
	v_mov_b32_e32 v50, v49
	v_mov_b32_e32 v54, v58
	v_pk_add_f32 v[52:53], v[60:61], v[52:53]
	v_pk_add_f32 v[48:49], v[50:51], v[56:57]
	v_readlane_b32 s57, v241, 18
	v_readlane_b32 s60, v241, 21
	v_readlane_b32 s61, v241, 22
	v_readlane_b32 s62, v241, 23
	v_readlane_b32 s63, v241, 24
	s_and_saveexec_b64 s[34:35], s[30:31]
	s_cbranch_execz .LBB0_646
	v_mul_f32_e32 v50, 0xbfb8aa3b, v52
	v_mul_f32_e32 v51, 0xbfb8aa3b, v53
	v_exp_f32_e32 v50, v50
	v_exp_f32_e32 v51, v51
	v_mul_f32_e32 v48, 0xbfb8aa3b, v48
	v_mul_f32_e32 v49, 0xbfb8aa3b, v49
	v_exp_f32_e32 v48, v48
	v_pk_add_f32 v[50:51], v[50:51], 1.0 op_sel_hi:[1,0]
	v_exp_f32_e32 v49, v49
	v_rcp_f32_e32 v53, v51
	v_pk_add_f32 v[48:49], v[48:49], 1.0 op_sel_hi:[1,0]
	v_mul_f32_e32 v53, 1.0, v53
	v_rcp_f32_e32 v52, v50
	s_nop 0
	v_mul_f32_e32 v52, 1.0, v52
	v_rcp_f32_e32 v51, v49
	s_nop 0
	v_mul_f32_e32 v49, 1.0, v51
	v_rcp_f32_e32 v51, v48
	s_nop 0
	v_mul_f32_e32 v48, 1.0, v51
.LBB0_646:
	s_or_b64 exec, exec, s[34:35]
	v_readlane_b32 s56, v241, 17
	v_readlane_b32 s58, v241, 19
	v_readlane_b32 s59, v241, 20
	v_and_b32_sdwa v55, v52, v89 dst_sel:DWORD dst_unused:UNUSED_PAD src0_sel:WORD_1 src1_sel:DWORD
	v_add3_u32 v52, v52, v55, s52
	v_mov_b64_e32 v[50:51], s[58:59]
	v_mad_i64_i32 v[50:51], s[30:31], v54, s51, v[50:51]
	v_and_b32_sdwa v54, v53, v89 dst_sel:DWORD dst_unused:UNUSED_PAD src0_sel:WORD_1 src1_sel:DWORD
	v_add3_u32 v53, v53, v54, s52
	v_cvt_pk_bf16_f32 v49, v49, v49
	v_cvt_pk_bf16_f32 v48, v48, v48
	v_and_b32_e32 v49, 0xffff0000, v49
	v_and_b32_e32 v48, 0xffff0000, v48
	v_lshl_add_u64 v[50:51], v[78:79], 1, v[50:51]
	v_or_b32_sdwa v49, v49, v53 dst_sel:DWORD dst_unused:UNUSED_PAD src0_sel:DWORD src1_sel:WORD_1
	v_or_b32_sdwa v48, v48, v52 dst_sel:DWORD dst_unused:UNUSED_PAD src0_sel:DWORD src1_sel:WORD_1
	global_store_dwordx2 v[50:51], v[48:49], off
	v_or_b32_e32 v48, 16, v78
	v_cmp_lt_i32_e32 vcc, s50, v48
	v_readlane_b32 s57, v241, 18
	v_readlane_b32 s60, v241, 21
	v_readlane_b32 s61, v241, 22
	v_readlane_b32 s62, v241, 23
	v_readlane_b32 s63, v241, 24
	s_and_saveexec_b64 s[34:35], vcc
	s_xor_b64 s[34:35], exec, s[34:35]
	s_cbranch_execz .LBB0_651
	s_cmpk_gt_u32 s53, 0x3ff
	s_cbranch_scc1 .LBB0_650
	v_readlane_b32 s56, v241, 57
	v_mov_b32_e32 v70, v78
	v_readlane_b32 s68, v240, 5
	v_readlane_b32 s69, v240, 6
	v_readlane_b32 s57, v241, 58
	v_readlane_b32 s58, v241, 59
	v_lshl_add_u64 v[48:49], v[70:71], 2, s[68:69]
	global_load_dwordx4 v[50:53], v[48:49], off offset:-1984
	v_readlane_b32 s59, v241, 60
	v_readlane_b32 s60, v241, 61
	v_readlane_b32 s61, v241, 62
	v_readlane_b32 s62, v241, 63
	v_readlane_b32 s63, v240, 0
	v_readlane_b32 s64, v240, 1
	v_readlane_b32 s65, v240, 2
	v_readlane_b32 s66, v240, 3
	v_readlane_b32 s67, v240, 4
	v_readlane_b32 s70, v240, 7
	v_readlane_b32 s71, v240, 8
	s_mov_b64 s[30:31], -1
	s_waitcnt vmcnt(0)
	v_mov_b32_e32 v49, v52
	v_mov_b32_e32 v48, v50
	v_mov_b32_e32 v52, v51
	s_branch .LBB0_651

.LBB0_655:
	s_or_b64 exec, exec, s[34:35]
	v_readlane_b32 s56, v241, 17
	v_readlane_b32 s58, v241, 19
	v_readlane_b32 s59, v241, 20
	v_and_b32_sdwa v57, v50, v89 dst_sel:DWORD dst_unused:UNUSED_PAD src0_sel:WORD_1 src1_sel:DWORD
	v_add3_u32 v50, v50, v57, s52
	v_mov_b64_e32 v[46:47], s[58:59]
	v_mad_i64_i32 v[46:47], s[34:35], v56, s51, v[46:47]
	v_and_b32_sdwa v56, v51, v89 dst_sel:DWORD dst_unused:UNUSED_PAD src0_sel:WORD_1 src1_sel:DWORD
	v_add3_u32 v51, v51, v56, s52
	v_cvt_pk_bf16_f32 v45, v45, v45
	v_cvt_pk_bf16_f32 v44, v44, v44
	v_and_b32_e32 v45, 0xffff0000, v45
	v_and_b32_e32 v44, 0xffff0000, v44
	v_lshl_add_u64 v[46:47], v[78:79], 1, v[46:47]
	v_or_b32_sdwa v45, v45, v51 dst_sel:DWORD dst_unused:UNUSED_PAD src0_sel:DWORD src1_sel:WORD_1
	v_or_b32_sdwa v44, v44, v50 dst_sel:DWORD dst_unused:UNUSED_PAD src0_sel:DWORD src1_sel:WORD_1
	global_store_dwordx2 v[46:47], v[44:45], off offset:32
	v_mov_b32_e32 v44, v40
	v_mov_b32_e32 v45, v42
	v_mov_b32_e32 v42, v41
	v_mov_b32_e32 v46, v66
	v_pk_add_f32 v[44:45], v[44:45], v[48:49]
	v_pk_add_f32 v[40:41], v[42:43], v[52:53]
	v_readlane_b32 s57, v241, 18
	v_readlane_b32 s60, v241, 21
	v_readlane_b32 s61, v241, 22
	v_readlane_b32 s62, v241, 23
	v_readlane_b32 s63, v241, 24
	s_and_saveexec_b64 s[34:35], s[30:31]
	s_cbranch_execz .LBB0_657
	v_mul_f32_e32 v42, 0xbfb8aa3b, v44
	v_mul_f32_e32 v43, 0xbfb8aa3b, v45
	v_exp_f32_e32 v42, v42
	v_exp_f32_e32 v43, v43
	v_mul_f32_e32 v40, 0xbfb8aa3b, v40
	v_mul_f32_e32 v41, 0xbfb8aa3b, v41
	v_exp_f32_e32 v40, v40
	v_pk_add_f32 v[42:43], v[42:43], 1.0 op_sel_hi:[1,0]
	v_exp_f32_e32 v41, v41
	v_rcp_f32_e32 v45, v43
	v_pk_add_f32 v[40:41], v[40:41], 1.0 op_sel_hi:[1,0]
	v_mul_f32_e32 v45, 1.0, v45
	v_rcp_f32_e32 v44, v42
	s_nop 0
	v_mul_f32_e32 v44, 1.0, v44
	v_rcp_f32_e32 v43, v41
	s_nop 0
	v_mul_f32_e32 v41, 1.0, v43
	v_rcp_f32_e32 v43, v40
	s_nop 0
	v_mul_f32_e32 v40, 1.0, v43
.LBB0_657:
	s_or_b64 exec, exec, s[34:35]
	v_readlane_b32 s56, v241, 17
	v_readlane_b32 s58, v241, 19
	v_readlane_b32 s59, v241, 20
	v_and_b32_sdwa v47, v44, v89 dst_sel:DWORD dst_unused:UNUSED_PAD src0_sel:WORD_1 src1_sel:DWORD
	v_add3_u32 v44, v44, v47, s52
	v_mov_b64_e32 v[42:43], s[58:59]
	v_mad_i64_i32 v[42:43], s[34:35], v46, s51, v[42:43]
	v_and_b32_sdwa v46, v45, v89 dst_sel:DWORD dst_unused:UNUSED_PAD src0_sel:WORD_1 src1_sel:DWORD
	v_add3_u32 v45, v45, v46, s52
	v_cvt_pk_bf16_f32 v41, v41, v41
	v_cvt_pk_bf16_f32 v40, v40, v40
	v_and_b32_e32 v41, 0xffff0000, v41
	v_and_b32_e32 v40, 0xffff0000, v40
	v_lshl_add_u64 v[42:43], v[78:79], 1, v[42:43]
	v_or_b32_sdwa v41, v41, v45 dst_sel:DWORD dst_unused:UNUSED_PAD src0_sel:DWORD src1_sel:WORD_1
	v_or_b32_sdwa v40, v40, v44 dst_sel:DWORD dst_unused:UNUSED_PAD src0_sel:DWORD src1_sel:WORD_1
	global_store_dwordx2 v[42:43], v[40:41], off offset:32
	v_mov_b32_e32 v40, v36
	v_mov_b32_e32 v41, v38
	v_mov_b32_e32 v38, v37
	v_mov_b32_e32 v42, v62
	v_pk_add_f32 v[40:41], v[40:41], v[48:49]
	v_pk_add_f32 v[36:37], v[38:39], v[52:53]
	v_readlane_b32 s57, v241, 18
	v_readlane_b32 s60, v241, 21
	v_readlane_b32 s61, v241, 22
	v_readlane_b32 s62, v241, 23
	v_readlane_b32 s63, v241, 24
	s_and_saveexec_b64 s[34:35], s[30:31]
	s_cbranch_execz .LBB0_659
	v_mul_f32_e32 v38, 0xbfb8aa3b, v40
	v_mul_f32_e32 v39, 0xbfb8aa3b, v41
	v_exp_f32_e32 v38, v38
	v_exp_f32_e32 v39, v39
	v_mul_f32_e32 v36, 0xbfb8aa3b, v36
	v_mul_f32_e32 v37, 0xbfb8aa3b, v37
	v_exp_f32_e32 v36, v36
	v_pk_add_f32 v[38:39], v[38:39], 1.0 op_sel_hi:[1,0]
	v_exp_f32_e32 v37, v37
	v_rcp_f32_e32 v41, v39
	v_pk_add_f32 v[36:37], v[36:37], 1.0 op_sel_hi:[1,0]
	v_mul_f32_e32 v41, 1.0, v41
	v_rcp_f32_e32 v40, v38
	s_nop 0
	v_mul_f32_e32 v40, 1.0, v40
	v_rcp_f32_e32 v39, v37
	s_nop 0
	v_mul_f32_e32 v37, 1.0, v39
	v_rcp_f32_e32 v39, v36
	s_nop 0
	v_mul_f32_e32 v36, 1.0, v39
.LBB0_659:
	s_or_b64 exec, exec, s[34:35]
	v_readlane_b32 s56, v241, 17
	v_readlane_b32 s58, v241, 19
	v_readlane_b32 s59, v241, 20
	v_and_b32_sdwa v43, v40, v89 dst_sel:DWORD dst_unused:UNUSED_PAD src0_sel:WORD_1 src1_sel:DWORD
	v_add3_u32 v40, v40, v43, s52
	v_mov_b64_e32 v[38:39], s[58:59]
	v_mad_i64_i32 v[38:39], s[34:35], v42, s51, v[38:39]
	v_and_b32_sdwa v42, v41, v89 dst_sel:DWORD dst_unused:UNUSED_PAD src0_sel:WORD_1 src1_sel:DWORD
	v_add3_u32 v41, v41, v42, s52
	v_cvt_pk_bf16_f32 v37, v37, v37
	v_cvt_pk_bf16_f32 v36, v36, v36
	v_and_b32_e32 v37, 0xffff0000, v37
	v_and_b32_e32 v36, 0xffff0000, v36
	v_lshl_add_u64 v[38:39], v[78:79], 1, v[38:39]
	v_or_b32_sdwa v37, v37, v41 dst_sel:DWORD dst_unused:UNUSED_PAD src0_sel:DWORD src1_sel:WORD_1
	v_or_b32_sdwa v36, v36, v40 dst_sel:DWORD dst_unused:UNUSED_PAD src0_sel:DWORD src1_sel:WORD_1
	global_store_dwordx2 v[38:39], v[36:37], off offset:32
	v_mov_b32_e32 v36, v32
	v_mov_b32_e32 v37, v34
	v_mov_b32_e32 v34, v33
	v_mov_b32_e32 v38, v58
	v_pk_add_f32 v[36:37], v[36:37], v[48:49]
	v_pk_add_f32 v[32:33], v[34:35], v[52:53]
	v_readlane_b32 s57, v241, 18
	v_readlane_b32 s60, v241, 21
	v_readlane_b32 s61, v241, 22
	v_readlane_b32 s62, v241, 23
	v_readlane_b32 s63, v241, 24
	s_and_saveexec_b64 s[34:35], s[30:31]
	s_cbranch_execz .LBB0_661
	v_mul_f32_e32 v34, 0xbfb8aa3b, v36
	v_mul_f32_e32 v35, 0xbfb8aa3b, v37
	v_exp_f32_e32 v34, v34
	v_exp_f32_e32 v35, v35
	v_mul_f32_e32 v32, 0xbfb8aa3b, v32
	v_mul_f32_e32 v33, 0xbfb8aa3b, v33
	v_exp_f32_e32 v32, v32
	v_pk_add_f32 v[34:35], v[34:35], 1.0 op_sel_hi:[1,0]
	v_exp_f32_e32 v33, v33
	v_rcp_f32_e32 v37, v35
	v_pk_add_f32 v[32:33], v[32:33], 1.0 op_sel_hi:[1,0]
	v_mul_f32_e32 v37, 1.0, v37
	v_rcp_f32_e32 v36, v34
	s_nop 0
	v_mul_f32_e32 v36, 1.0, v36
	v_rcp_f32_e32 v35, v33
	s_nop 0
	v_mul_f32_e32 v33, 1.0, v35
	v_rcp_f32_e32 v35, v32
	s_nop 0
	v_mul_f32_e32 v32, 1.0, v35
.LBB0_661:
	s_or_b64 exec, exec, s[34:35]
	v_readlane_b32 s56, v241, 17
	v_readlane_b32 s58, v241, 19
	v_readlane_b32 s59, v241, 20
	v_and_b32_sdwa v39, v36, v89 dst_sel:DWORD dst_unused:UNUSED_PAD src0_sel:WORD_1 src1_sel:DWORD
	v_add3_u32 v36, v36, v39, s52
	v_mov_b64_e32 v[34:35], s[58:59]
	v_mad_i64_i32 v[34:35], s[30:31], v38, s51, v[34:35]
	v_and_b32_sdwa v38, v37, v89 dst_sel:DWORD dst_unused:UNUSED_PAD src0_sel:WORD_1 src1_sel:DWORD
	v_add3_u32 v37, v37, v38, s52
	v_and_b32_sdwa v39, v32, v89 dst_sel:DWORD dst_unused:UNUSED_PAD src0_sel:WORD_1 src1_sel:DWORD
	v_cvt_pk_bf16_f32 v33, v33, v33
	v_add3_u32 v32, v32, v39, s52
	v_and_b32_e32 v33, 0xffff0000, v33
	v_and_b32_e32 v32, 0xffff0000, v32
	v_lshl_add_u64 v[34:35], v[78:79], 1, v[34:35]
	v_or_b32_sdwa v33, v33, v37 dst_sel:DWORD dst_unused:UNUSED_PAD src0_sel:DWORD src1_sel:WORD_1
	v_or_b32_sdwa v32, v32, v36 dst_sel:DWORD dst_unused:UNUSED_PAD src0_sel:DWORD src1_sel:WORD_1
	global_store_dwordx2 v[34:35], v[32:33], off offset:32
	v_or_b32_e32 v32, 32, v78
	v_cmp_lt_i32_e32 vcc, s50, v32
	v_readlane_b32 s57, v241, 18
	v_readlane_b32 s60, v241, 21
	v_readlane_b32 s61, v241, 22
	v_readlane_b32 s62, v241, 23
	v_readlane_b32 s63, v241, 24
	s_and_saveexec_b64 s[34:35], vcc
	s_xor_b64 s[34:35], exec, s[34:35]
	s_cbranch_execz .LBB0_664
	s_cmpk_gt_u32 s53, 0x3ff
	s_cbranch_scc1 .LBB0_687
	v_readlane_b32 s56, v241, 57
	v_mov_b32_e32 v70, v78
	v_readlane_b32 s68, v240, 5
	v_readlane_b32 s69, v240, 6
	v_readlane_b32 s57, v241, 58
	v_readlane_b32 s58, v241, 59
	v_lshl_add_u64 v[32:33], v[70:71], 2, s[68:69]
	global_load_dwordx4 v[34:37], v[32:33], off offset:-1920
	v_readlane_b32 s59, v241, 60
	v_readlane_b32 s60, v241, 61
	v_readlane_b32 s61, v241, 62
	v_readlane_b32 s62, v241, 63
	v_readlane_b32 s63, v240, 0
	v_readlane_b32 s64, v240, 1
	v_readlane_b32 s65, v240, 2
	v_readlane_b32 s66, v240, 3
	v_readlane_b32 s67, v240, 4
	v_readlane_b32 s70, v240, 7
	v_readlane_b32 s71, v240, 8
	s_mov_b64 s[30:31], -1
	s_waitcnt vmcnt(0)
	v_mov_b32_e32 v33, v36
	v_mov_b32_e32 v32, v34
	v_mov_b32_e32 v36, v35

.LBB0_668:
	s_or_b64 exec, exec, s[34:35]
	v_readlane_b32 s56, v241, 17
	v_readlane_b32 s58, v241, 19
	v_readlane_b32 s59, v241, 20
	v_and_b32_sdwa v39, v34, v89 dst_sel:DWORD dst_unused:UNUSED_PAD src0_sel:WORD_1 src1_sel:DWORD
	v_add3_u32 v34, v34, v39, s52
	v_mov_b64_e32 v[30:31], s[58:59]
	v_mad_i64_i32 v[30:31], s[34:35], v38, s51, v[30:31]
	v_and_b32_sdwa v38, v35, v89 dst_sel:DWORD dst_unused:UNUSED_PAD src0_sel:WORD_1 src1_sel:DWORD
	v_add3_u32 v35, v35, v38, s52
	v_cvt_pk_bf16_f32 v29, v29, v29
	v_cvt_pk_bf16_f32 v28, v28, v28
	v_and_b32_e32 v29, 0xffff0000, v29
	v_and_b32_e32 v28, 0xffff0000, v28
	v_lshl_add_u64 v[30:31], v[78:79], 1, v[30:31]
	v_or_b32_sdwa v29, v29, v35 dst_sel:DWORD dst_unused:UNUSED_PAD src0_sel:DWORD src1_sel:WORD_1
	v_or_b32_sdwa v28, v28, v34 dst_sel:DWORD dst_unused:UNUSED_PAD src0_sel:DWORD src1_sel:WORD_1
	global_store_dwordx2 v[30:31], v[28:29], off offset:64
	v_mov_b32_e32 v28, v24
	v_mov_b32_e32 v29, v26
	v_mov_b32_e32 v26, v25
	v_mov_b32_e32 v30, v66
	v_pk_add_f32 v[28:29], v[28:29], v[32:33]
	v_pk_add_f32 v[24:25], v[26:27], v[36:37]
	v_readlane_b32 s57, v241, 18
	v_readlane_b32 s60, v241, 21
	v_readlane_b32 s61, v241, 22
	v_readlane_b32 s62, v241, 23
	v_readlane_b32 s63, v241, 24
	s_and_saveexec_b64 s[34:35], s[30:31]
	s_cbranch_execz .LBB0_670
	v_mul_f32_e32 v26, 0xbfb8aa3b, v28
	v_mul_f32_e32 v27, 0xbfb8aa3b, v29
	v_exp_f32_e32 v26, v26
	v_exp_f32_e32 v27, v27
	v_mul_f32_e32 v24, 0xbfb8aa3b, v24
	v_mul_f32_e32 v25, 0xbfb8aa3b, v25
	v_exp_f32_e32 v24, v24
	v_pk_add_f32 v[26:27], v[26:27], 1.0 op_sel_hi:[1,0]
	v_exp_f32_e32 v25, v25
	v_rcp_f32_e32 v29, v27
	v_pk_add_f32 v[24:25], v[24:25], 1.0 op_sel_hi:[1,0]
	v_mul_f32_e32 v29, 1.0, v29
	v_rcp_f32_e32 v28, v26
	s_nop 0
	v_mul_f32_e32 v28, 1.0, v28
	v_rcp_f32_e32 v27, v25
	s_nop 0
	v_mul_f32_e32 v25, 1.0, v27
	v_rcp_f32_e32 v27, v24
	s_nop 0
	v_mul_f32_e32 v24, 1.0, v27
.LBB0_670:
	s_or_b64 exec, exec, s[34:35]
	v_readlane_b32 s56, v241, 17
	v_readlane_b32 s58, v241, 19
	v_readlane_b32 s59, v241, 20
	v_and_b32_sdwa v31, v28, v89 dst_sel:DWORD dst_unused:UNUSED_PAD src0_sel:WORD_1 src1_sel:DWORD
	v_add3_u32 v28, v28, v31, s52
	v_mov_b64_e32 v[26:27], s[58:59]
	v_mad_i64_i32 v[26:27], s[34:35], v30, s51, v[26:27]
	v_and_b32_sdwa v30, v29, v89 dst_sel:DWORD dst_unused:UNUSED_PAD src0_sel:WORD_1 src1_sel:DWORD
	v_add3_u32 v29, v29, v30, s52
	v_cvt_pk_bf16_f32 v25, v25, v25
	v_cvt_pk_bf16_f32 v24, v24, v24
	v_and_b32_e32 v25, 0xffff0000, v25
	v_and_b32_e32 v24, 0xffff0000, v24
	v_lshl_add_u64 v[26:27], v[78:79], 1, v[26:27]
	v_or_b32_sdwa v25, v25, v29 dst_sel:DWORD dst_unused:UNUSED_PAD src0_sel:DWORD src1_sel:WORD_1
	v_or_b32_sdwa v24, v24, v28 dst_sel:DWORD dst_unused:UNUSED_PAD src0_sel:DWORD src1_sel:WORD_1
	global_store_dwordx2 v[26:27], v[24:25], off offset:64
	v_mov_b32_e32 v24, v20
	v_mov_b32_e32 v25, v22
	v_mov_b32_e32 v22, v21
	v_mov_b32_e32 v26, v62
	v_pk_add_f32 v[24:25], v[24:25], v[32:33]
	v_pk_add_f32 v[20:21], v[22:23], v[36:37]
	v_readlane_b32 s57, v241, 18
	v_readlane_b32 s60, v241, 21
	v_readlane_b32 s61, v241, 22
	v_readlane_b32 s62, v241, 23
	v_readlane_b32 s63, v241, 24
	s_and_saveexec_b64 s[34:35], s[30:31]
	s_cbranch_execz .LBB0_672
	v_mul_f32_e32 v22, 0xbfb8aa3b, v24
	v_mul_f32_e32 v23, 0xbfb8aa3b, v25
	v_exp_f32_e32 v22, v22
	v_exp_f32_e32 v23, v23
	v_mul_f32_e32 v20, 0xbfb8aa3b, v20
	v_mul_f32_e32 v21, 0xbfb8aa3b, v21
	v_exp_f32_e32 v20, v20
	v_pk_add_f32 v[22:23], v[22:23], 1.0 op_sel_hi:[1,0]
	v_exp_f32_e32 v21, v21
	v_rcp_f32_e32 v25, v23
	v_pk_add_f32 v[20:21], v[20:21], 1.0 op_sel_hi:[1,0]
	v_mul_f32_e32 v25, 1.0, v25
	v_rcp_f32_e32 v24, v22
	s_nop 0
	v_mul_f32_e32 v24, 1.0, v24
	v_rcp_f32_e32 v23, v21
	s_nop 0
	v_mul_f32_e32 v21, 1.0, v23
	v_rcp_f32_e32 v23, v20
	s_nop 0
	v_mul_f32_e32 v20, 1.0, v23
.LBB0_672:
	s_or_b64 exec, exec, s[34:35]
	v_readlane_b32 s56, v241, 17
	v_readlane_b32 s58, v241, 19
	v_readlane_b32 s59, v241, 20
	v_and_b32_sdwa v27, v24, v89 dst_sel:DWORD dst_unused:UNUSED_PAD src0_sel:WORD_1 src1_sel:DWORD
	v_add3_u32 v24, v24, v27, s52
	v_mov_b64_e32 v[22:23], s[58:59]
	v_mad_i64_i32 v[22:23], s[34:35], v26, s51, v[22:23]
	v_and_b32_sdwa v26, v25, v89 dst_sel:DWORD dst_unused:UNUSED_PAD src0_sel:WORD_1 src1_sel:DWORD
	v_add3_u32 v25, v25, v26, s52
	v_cvt_pk_bf16_f32 v21, v21, v21
	v_cvt_pk_bf16_f32 v20, v20, v20
	v_and_b32_e32 v21, 0xffff0000, v21
	v_and_b32_e32 v20, 0xffff0000, v20
	v_lshl_add_u64 v[22:23], v[78:79], 1, v[22:23]
	v_or_b32_sdwa v21, v21, v25 dst_sel:DWORD dst_unused:UNUSED_PAD src0_sel:DWORD src1_sel:WORD_1
	v_or_b32_sdwa v20, v20, v24 dst_sel:DWORD dst_unused:UNUSED_PAD src0_sel:DWORD src1_sel:WORD_1
	global_store_dwordx2 v[22:23], v[20:21], off offset:64
	v_mov_b32_e32 v20, v16
	v_mov_b32_e32 v21, v18
	v_mov_b32_e32 v18, v17
	v_mov_b32_e32 v22, v58
	v_pk_add_f32 v[20:21], v[20:21], v[32:33]
	v_pk_add_f32 v[16:17], v[18:19], v[36:37]
	v_readlane_b32 s57, v241, 18
	v_readlane_b32 s60, v241, 21
	v_readlane_b32 s61, v241, 22
	v_readlane_b32 s62, v241, 23
	v_readlane_b32 s63, v241, 24
	s_and_saveexec_b64 s[34:35], s[30:31]
	s_cbranch_execz .LBB0_674
	v_mul_f32_e32 v18, 0xbfb8aa3b, v20
	v_mul_f32_e32 v19, 0xbfb8aa3b, v21
	v_exp_f32_e32 v18, v18
	v_exp_f32_e32 v19, v19
	v_mul_f32_e32 v16, 0xbfb8aa3b, v16
	v_mul_f32_e32 v17, 0xbfb8aa3b, v17
	v_exp_f32_e32 v16, v16
	v_pk_add_f32 v[18:19], v[18:19], 1.0 op_sel_hi:[1,0]
	v_exp_f32_e32 v17, v17
	v_rcp_f32_e32 v21, v19
	v_pk_add_f32 v[16:17], v[16:17], 1.0 op_sel_hi:[1,0]
	v_mul_f32_e32 v21, 1.0, v21
	v_rcp_f32_e32 v20, v18
	s_nop 0
	v_mul_f32_e32 v20, 1.0, v20
	v_rcp_f32_e32 v19, v17
	s_nop 0
	v_mul_f32_e32 v17, 1.0, v19
	v_rcp_f32_e32 v19, v16
	s_nop 0
	v_mul_f32_e32 v16, 1.0, v19

.LBB0_681:
	s_or_b64 exec, exec, s[34:35]
	v_readlane_b32 s56, v241, 17
	v_and_b32_sdwa v22, v19, v89 dst_sel:DWORD dst_unused:UNUSED_PAD src0_sel:WORD_1 src1_sel:DWORD
	v_and_b32_sdwa v23, v18, v89 dst_sel:DWORD dst_unused:UNUSED_PAD src0_sel:WORD_1 src1_sel:DWORD
	v_readlane_b32 s58, v241, 19
	v_readlane_b32 s59, v241, 20
	v_add3_u32 v18, v18, v23, s52
	v_add3_u32 v19, v19, v22, s52
	v_mov_b64_e32 v[14:15], s[58:59]
	v_cvt_pk_bf16_f32 v13, v13, v13
	v_cvt_pk_bf16_f32 v12, v12, v12
	v_mad_i64_i32 v[14:15], s[34:35], v90, s51, v[14:15]
	v_and_b32_e32 v13, 0xffff0000, v13
	v_and_b32_e32 v12, 0xffff0000, v12
	v_lshl_add_u64 v[14:15], v[78:79], 1, v[14:15]
	v_or_b32_sdwa v13, v13, v19 dst_sel:DWORD dst_unused:UNUSED_PAD src0_sel:DWORD src1_sel:WORD_1
	v_or_b32_sdwa v12, v12, v18 dst_sel:DWORD dst_unused:UNUSED_PAD src0_sel:DWORD src1_sel:WORD_1
	global_store_dwordx2 v[14:15], v[12:13], off offset:96
	v_mov_b32_e32 v12, v8
	v_mov_b32_e32 v13, v10
	v_mov_b32_e32 v10, v9
	v_pk_add_f32 v[12:13], v[12:13], v[16:17]
	v_pk_add_f32 v[8:9], v[10:11], v[20:21]
	v_readlane_b32 s57, v241, 18
	v_readlane_b32 s60, v241, 21
	v_readlane_b32 s61, v241, 22
	v_readlane_b32 s62, v241, 23
	v_readlane_b32 s63, v241, 24
	s_and_saveexec_b64 s[34:35], s[30:31]
	s_cbranch_execz .LBB0_683
	v_mul_f32_e32 v10, 0xbfb8aa3b, v12
	v_mul_f32_e32 v11, 0xbfb8aa3b, v13
	v_exp_f32_e32 v10, v10
	v_exp_f32_e32 v11, v11
	v_mul_f32_e32 v8, 0xbfb8aa3b, v8
	v_mul_f32_e32 v9, 0xbfb8aa3b, v9
	v_exp_f32_e32 v8, v8
	v_pk_add_f32 v[10:11], v[10:11], 1.0 op_sel_hi:[1,0]
	v_exp_f32_e32 v9, v9
	v_rcp_f32_e32 v13, v11
	v_pk_add_f32 v[8:9], v[8:9], 1.0 op_sel_hi:[1,0]
	v_mul_f32_e32 v13, 1.0, v13
	v_rcp_f32_e32 v12, v10
	s_nop 0
	v_mul_f32_e32 v12, 1.0, v12
	v_rcp_f32_e32 v11, v9
	s_nop 0
	v_mul_f32_e32 v9, 1.0, v11
	v_rcp_f32_e32 v11, v8
	s_nop 0
	v_mul_f32_e32 v8, 1.0, v11
.LBB0_683:
	s_or_b64 exec, exec, s[34:35]
	v_readlane_b32 s56, v241, 17
	v_and_b32_sdwa v14, v13, v89 dst_sel:DWORD dst_unused:UNUSED_PAD src0_sel:WORD_1 src1_sel:DWORD
	v_and_b32_sdwa v15, v12, v89 dst_sel:DWORD dst_unused:UNUSED_PAD src0_sel:WORD_1 src1_sel:DWORD
	v_readlane_b32 s58, v241, 19
	v_readlane_b32 s59, v241, 20
	v_add3_u32 v12, v12, v15, s52
	v_add3_u32 v13, v13, v14, s52
	v_mov_b64_e32 v[10:11], s[58:59]
	v_cvt_pk_bf16_f32 v9, v9, v9
	v_cvt_pk_bf16_f32 v8, v8, v8
	v_mad_i64_i32 v[10:11], s[34:35], v66, s51, v[10:11]
	v_and_b32_e32 v9, 0xffff0000, v9
	v_and_b32_e32 v8, 0xffff0000, v8
	v_lshl_add_u64 v[10:11], v[78:79], 1, v[10:11]
	v_or_b32_sdwa v9, v9, v13 dst_sel:DWORD dst_unused:UNUSED_PAD src0_sel:DWORD src1_sel:WORD_1
	v_or_b32_sdwa v8, v8, v12 dst_sel:DWORD dst_unused:UNUSED_PAD src0_sel:DWORD src1_sel:WORD_1
	global_store_dwordx2 v[10:11], v[8:9], off offset:96
	v_mov_b32_e32 v8, v4
	v_mov_b32_e32 v9, v6
	v_mov_b32_e32 v6, v5
	v_pk_add_f32 v[8:9], v[8:9], v[16:17]
	v_pk_add_f32 v[4:5], v[6:7], v[20:21]
	v_readlane_b32 s57, v241, 18
	v_readlane_b32 s60, v241, 21
	v_readlane_b32 s61, v241, 22
	v_readlane_b32 s62, v241, 23
	v_readlane_b32 s63, v241, 24
	s_and_saveexec_b64 s[34:35], s[30:31]
	s_cbranch_execz .LBB0_685
	v_mul_f32_e32 v6, 0xbfb8aa3b, v8
	v_mul_f32_e32 v7, 0xbfb8aa3b, v9
	v_exp_f32_e32 v6, v6
	v_exp_f32_e32 v7, v7
	v_mul_f32_e32 v4, 0xbfb8aa3b, v4
	v_mul_f32_e32 v5, 0xbfb8aa3b, v5
	v_exp_f32_e32 v4, v4
	v_pk_add_f32 v[6:7], v[6:7], 1.0 op_sel_hi:[1,0]
	v_exp_f32_e32 v5, v5
	v_rcp_f32_e32 v9, v7
	v_pk_add_f32 v[4:5], v[4:5], 1.0 op_sel_hi:[1,0]
	v_mul_f32_e32 v9, 1.0, v9
	v_rcp_f32_e32 v8, v6
	s_nop 0
	v_mul_f32_e32 v8, 1.0, v8
	v_rcp_f32_e32 v7, v5
	s_nop 0
	v_mul_f32_e32 v5, 1.0, v7
	v_rcp_f32_e32 v7, v4
	s_nop 0
	v_mul_f32_e32 v4, 1.0, v7
.LBB0_685:
	s_or_b64 exec, exec, s[34:35]
	v_readlane_b32 s56, v241, 17
	v_and_b32_sdwa v10, v9, v89 dst_sel:DWORD dst_unused:UNUSED_PAD src0_sel:WORD_1 src1_sel:DWORD
	v_and_b32_sdwa v11, v8, v89 dst_sel:DWORD dst_unused:UNUSED_PAD src0_sel:WORD_1 src1_sel:DWORD
	v_readlane_b32 s58, v241, 19
	v_readlane_b32 s59, v241, 20
	v_add3_u32 v8, v8, v11, s52
	v_add3_u32 v9, v9, v10, s52
	v_mov_b64_e32 v[6:7], s[58:59]
	v_cvt_pk_bf16_f32 v5, v5, v5
	v_cvt_pk_bf16_f32 v4, v4, v4
	v_mad_i64_i32 v[6:7], s[34:35], v62, s51, v[6:7]
	v_and_b32_e32 v5, 0xffff0000, v5
	v_and_b32_e32 v4, 0xffff0000, v4
	v_lshl_add_u64 v[6:7], v[78:79], 1, v[6:7]
	v_or_b32_sdwa v5, v5, v9 dst_sel:DWORD dst_unused:UNUSED_PAD src0_sel:DWORD src1_sel:WORD_1
	v_or_b32_sdwa v4, v4, v8 dst_sel:DWORD dst_unused:UNUSED_PAD src0_sel:DWORD src1_sel:WORD_1
	global_store_dwordx2 v[6:7], v[4:5], off offset:96
	v_mov_b32_e32 v4, v0
	v_mov_b32_e32 v5, v2
	v_mov_b32_e32 v2, v1
	v_pk_add_f32 v[4:5], v[4:5], v[16:17]
	v_pk_add_f32 v[0:1], v[2:3], v[20:21]
	v_readlane_b32 s57, v241, 18
	v_readlane_b32 s60, v241, 21
	v_readlane_b32 s61, v241, 22
	v_readlane_b32 s62, v241, 23
	v_readlane_b32 s63, v241, 24
	s_and_saveexec_b64 s[34:35], s[30:31]
	s_cbranch_execz .LBB0_632
	v_mul_f32_e32 v2, 0xbfb8aa3b, v4
	v_mul_f32_e32 v3, 0xbfb8aa3b, v5
	v_exp_f32_e32 v2, v2
	v_exp_f32_e32 v3, v3
	v_mul_f32_e32 v0, 0xbfb8aa3b, v0
	v_mul_f32_e32 v1, 0xbfb8aa3b, v1
	v_exp_f32_e32 v0, v0
	v_pk_add_f32 v[2:3], v[2:3], 1.0 op_sel_hi:[1,0]
	v_exp_f32_e32 v1, v1
	v_rcp_f32_e32 v5, v3
	v_pk_add_f32 v[0:1], v[0:1], 1.0 op_sel_hi:[1,0]
	v_mul_f32_e32 v5, 1.0, v5
	v_rcp_f32_e32 v4, v2
	s_nop 0
	v_mul_f32_e32 v4, 1.0, v4
	v_rcp_f32_e32 v3, v1
	s_nop 0
	v_mul_f32_e32 v1, 1.0, v3
	v_rcp_f32_e32 v3, v0
	s_nop 0
	v_mul_f32_e32 v0, 1.0, v3
	s_branch .LBB0_632

.LBB0_799:
	s_waitcnt vmcnt(0)
	ds_read2_b32 v[14:15], v13 offset1:4
	ds_read2_b32 v[16:17], v13 offset0:8 offset1:12
	v_add_u32_e32 v12, -2, v12
	s_add_i32 s15, s15, 4
	v_cmp_eq_u32_e32 vcc, 0, v12
	s_waitcnt lgkmcnt(1)
	v_and_b32_sdwa v3, v15, v116 dst_sel:DWORD dst_unused:UNUSED_PAD src0_sel:WORD_1 src1_sel:DWORD
	v_cvt_pk_bf16_f32 v20, v14, v14
	v_add_u32_e32 v14, s13, v10
	v_add3_u32 v3, v15, v3, s33
	v_add_u32_e32 v18, s13, v11
	v_mad_i64_i32 v[14:15], s[18:19], v14, s58, v[8:9]
	v_mad_i64_i32 v[18:19], s[18:19], v18, s58, v[8:9]
	global_store_short_d16_hi v[14:15], v20, off
	global_store_short_d16_hi v[18:19], v3, off
	s_waitcnt lgkmcnt(0)
	v_cvt_pk_bf16_f32 v18, v16, v16
	v_add_u32_e32 v14, s11, v10
	v_cvt_pk_bf16_f32 v3, v17, v17
	v_add_u32_e32 v16, s14, v11
	v_mad_i64_i32 v[14:15], s[18:19], v14, s58, v[8:9]
	v_mad_i64_i32 v[16:17], s[18:19], v16, s58, v[8:9]
	global_store_short_d16_hi v[14:15], v18, off
	global_store_short_d16_hi v[16:17], v3, off
	v_add_u32_e32 v11, 16, v11
	v_add_u32_e32 v10, 16, v10
	v_add_u32_e32 v13, 64, v13
	s_or_b64 s[8:9], vcc, s[8:9]
	v_mov_b32_e32 v3, s15
	s_andn2_b64 exec, exec, s[8:9]
	s_cbranch_execnz .LBB0_799
	s_or_b64 exec, exec, s[8:9]
	v_lshlrev_b32_e32 v12, 2, v3
.LBB0_801:
	s_or_b64 exec, exec, s[6:7]
	v_and_b32_e32 v3, 2, v7
	v_cmp_eq_u32_e32 vcc, 0, v3
	s_and_saveexec_b64 s[6:7], vcc
	s_cbranch_execz .LBB0_803
	v_lshl_or_b32 v3, v1, 8, v4
	v_add_u32_e32 v4, v2, v12
	v_lshl_add_u32 v3, v4, 2, v3
	ds_read2_b32 v[12:13], v3 offset1:4
	v_add_u32_e32 v10, s13, v10
	v_add_u32_e32 v3, s13, v11
	v_mad_i64_i32 v[10:11], s[8:9], v10, s58, v[8:9]
	s_waitcnt lgkmcnt(0)
	v_cvt_pk_bf16_f32 v7, v12, v12
	v_cvt_pk_bf16_f32 v4, v13, v13
	v_mad_i64_i32 v[8:9], s[8:9], v3, s58, v[8:9]
	global_store_short_d16_hi v[10:11], v7, off
	global_store_short_d16_hi v[8:9], v4, off

.LBB0_806:
	ds_read_b32 v2, v1
	v_add_u32_e32 v3, 4, v3
	v_cmp_lt_i32_e32 vcc, 59, v3
	s_mov_b64 s[6:7], 0x5800
	v_add_u32_e32 v1, 16, v1
	s_waitcnt lgkmcnt(0)
	v_cvt_pk_bf16_f32 v2, v2, v2
	s_or_b64 s[4:5], vcc, s[4:5]
	global_store_short_d16_hi v[4:5], v2, off
	v_lshl_add_u64 v[4:5], v[4:5], 0, s[6:7]
	s_andn2_b64 exec, exec, s[4:5]
	s_cbranch_execnz .LBB0_806

.LBB0_825:
	s_waitcnt vmcnt(0)
	ds_read2_b32 v[14:15], v12 offset1:4
	ds_read2_b32 v[16:17], v12 offset0:8 offset1:12
	v_add_u32_e32 v18, s13, v6
	v_ashrrev_i32_e32 v19, 31, v18
	v_lshlrev_b64 v[18:19], 11, v[18:19]
	s_waitcnt lgkmcnt(1)
	v_and_b32_sdwa v13, v14, v116 dst_sel:DWORD dst_unused:UNUSED_PAD src0_sel:WORD_1 src1_sel:DWORD
	v_and_b32_sdwa v3, v15, v116 dst_sel:DWORD dst_unused:UNUSED_PAD src0_sel:WORD_1 src1_sel:DWORD
	v_add3_u32 v13, v14, v13, s33
	v_add_u32_e32 v14, s13, v7
	v_add3_u32 v3, v15, v3, s33
	v_ashrrev_i32_e32 v15, 31, v14
	v_lshlrev_b64 v[14:15], 11, v[14:15]
	v_lshl_add_u64 v[18:19], v[4:5], 0, v[18:19]
	v_lshl_add_u64 v[14:15], v[4:5], 0, v[14:15]
	global_store_short_d16_hi v[18:19], v13, off
	global_store_short_d16_hi v[14:15], v3, off
	s_waitcnt lgkmcnt(0)
	v_and_b32_sdwa v13, v16, v116 dst_sel:DWORD dst_unused:UNUSED_PAD src0_sel:WORD_1 src1_sel:DWORD
	v_and_b32_sdwa v3, v17, v116 dst_sel:DWORD dst_unused:UNUSED_PAD src0_sel:WORD_1 src1_sel:DWORD
	v_add3_u32 v13, v16, v13, s33
	v_add_u32_e32 v16, s10, v6
	v_add3_u32 v3, v17, v3, s33
	v_add_u32_e32 v14, s11, v7
	v_ashrrev_i32_e32 v17, 31, v16
	v_ashrrev_i32_e32 v15, 31, v14
	v_lshlrev_b64 v[16:17], 11, v[16:17]
	v_lshlrev_b64 v[14:15], 11, v[14:15]
	v_lshl_add_u64 v[16:17], v[4:5], 0, v[16:17]
	v_lshl_add_u64 v[14:15], v[4:5], 0, v[14:15]
	global_store_short_d16_hi v[16:17], v13, off
	global_store_short_d16_hi v[14:15], v3, off
	ds_read2_b32 v[14:15], v12 offset0:16 offset1:20
	v_add_u32_e32 v16, s14, v6
	v_ashrrev_i32_e32 v17, 31, v16
	v_lshlrev_b64 v[16:17], 11, v[16:17]
	v_lshl_add_u64 v[16:17], v[4:5], 0, v[16:17]
	s_waitcnt lgkmcnt(0)
	v_and_b32_sdwa v13, v14, v116 dst_sel:DWORD dst_unused:UNUSED_PAD src0_sel:WORD_1 src1_sel:DWORD
	v_and_b32_sdwa v3, v15, v116 dst_sel:DWORD dst_unused:UNUSED_PAD src0_sel:WORD_1 src1_sel:DWORD
	v_add3_u32 v13, v14, v13, s33
	v_add_u32_e32 v14, s15, v7
	v_add3_u32 v3, v15, v3, s33
	v_ashrrev_i32_e32 v15, 31, v14
	v_lshlrev_b64 v[14:15], 11, v[14:15]
	v_lshl_add_u64 v[14:15], v[4:5], 0, v[14:15]
	global_store_short_d16_hi v[16:17], v13, off
	global_store_short_d16_hi v[14:15], v3, off
	ds_read2_b32 v[14:15], v12 offset0:24 offset1:28
	v_add_u32_e32 v16, s17, v6
	v_ashrrev_i32_e32 v17, 31, v16
	v_lshlrev_b64 v[16:17], 11, v[16:17]
	v_add_u32_e32 v11, -4, v11
	s_waitcnt lgkmcnt(0)
	v_cvt_pk_bf16_f32 v13, v14, v14
	v_add_u32_e32 v14, s18, v7
	v_cvt_pk_bf16_f32 v3, v15, v15
	v_ashrrev_i32_e32 v15, 31, v14
	v_lshlrev_b64 v[14:15], 11, v[14:15]
	v_lshl_add_u64 v[16:17], v[4:5], 0, v[16:17]
	s_add_i32 s19, s19, 8
	v_cmp_eq_u32_e32 vcc, 0, v11
	v_lshl_add_u64 v[14:15], v[4:5], 0, v[14:15]
	global_store_short_d16_hi v[16:17], v13, off
	global_store_short_d16_hi v[14:15], v3, off
	v_add_u32_e32 v7, 32, v7
	v_add_u32_e32 v6, 32, v6
	v_add_u32_e32 v12, 0x80, v12
	s_or_b64 s[8:9], vcc, s[8:9]
	v_mov_b32_e32 v13, s19
	s_andn2_b64 exec, exec, s[8:9]
	s_cbranch_execnz .LBB0_825
	s_or_b64 exec, exec, s[8:9]

.LBB0_829:
	ds_read2_b32 v[10:11], v9 offset1:4
	v_add_u32_e32 v3, -1, v3
	v_cmp_eq_u32_e32 vcc, 0, v3
	v_add_u32_e32 v9, 32, v9
	s_or_b64 s[8:9], vcc, s[8:9]
	s_waitcnt lgkmcnt(0)
	s_waitcnt vmcnt(0)
	v_cvt_pk_bf16_f32 v14, v11, v11
	v_add_u32_e32 v12, s13, v6
	v_cvt_pk_bf16_f32 v15, v10, v10
	v_add_u32_e32 v10, s13, v7
	v_ashrrev_i32_e32 v13, 31, v12
	v_ashrrev_i32_e32 v11, 31, v10
	v_lshlrev_b64 v[12:13], 11, v[12:13]
	v_lshlrev_b64 v[10:11], 11, v[10:11]
	v_lshl_add_u64 v[12:13], v[4:5], 0, v[12:13]
	v_add_u32_e32 v7, 8, v7
	v_add_u32_e32 v6, 8, v6
	v_lshl_add_u64 v[10:11], v[4:5], 0, v[10:11]
	global_store_short_d16_hi v[12:13], v15, off
	global_store_short_d16_hi v[10:11], v14, off
	s_andn2_b64 exec, exec, s[8:9]
	s_cbranch_execnz .LBB0_829

.LBB0_833:
	ds_read_b32 v2, v1
	v_add_u32_e32 v6, s12, v3
	v_add_u32_e32 v6, 0xfffffc04, v6
	v_add_u32_e32 v3, 4, v3
	v_ashrrev_i32_e32 v7, 31, v6
	v_cmp_lt_i32_e32 vcc, 59, v3
	v_lshlrev_b64 v[6:7], 11, v[6:7]
	s_waitcnt lgkmcnt(0)
	v_add_u32_e32 v1, 16, v1
	s_or_b64 s[4:5], vcc, s[4:5]
	v_lshl_add_u64 v[6:7], v[4:5], 0, v[6:7]
	v_cvt_pk_bf16_f32 v2, v2, v2
	global_store_short_d16_hi v[6:7], v2, off
	s_andn2_b64 exec, exec, s[4:5]
	s_cbranch_execnz .LBB0_833

.LBB0_845:
	ds_read2_b32 v[14:15], v13 offset1:4
	ds_read2_b32 v[16:17], v13 offset0:8 offset1:12
	v_add_u32_e32 v12, -4, v12
	s_add_i32 s20, s20, 8
	v_cmp_eq_u32_e32 vcc, 0, v12
	s_waitcnt lgkmcnt(1)
	v_and_b32_sdwa v3, v15, v116 dst_sel:DWORD dst_unused:UNUSED_PAD src0_sel:WORD_1 src1_sel:DWORD
	v_cvt_pk_bf16_f32 v20, v14, v14
	v_add_u32_e32 v14, s6, v9
	v_add_u32_e32 v18, s6, v8
	v_add3_u32 v3, v15, v3, s33
	v_ashrrev_i32_e32 v19, 31, v18
	v_ashrrev_i32_e32 v15, 31, v14
	v_lshlrev_b64 v[14:15], 11, v[14:15]
	v_lshlrev_b64 v[18:19], 11, v[18:19]
	v_lshl_add_u64 v[18:19], v[6:7], 0, v[18:19]
	v_lshl_add_u64 v[14:15], v[6:7], 0, v[14:15]
	global_store_short_d16_hi v[18:19], v20, off
	global_store_short_d16_hi v[14:15], v3, off
	s_waitcnt lgkmcnt(0)
	v_and_b32_sdwa v3, v17, v116 dst_sel:DWORD dst_unused:UNUSED_PAD src0_sel:WORD_1 src1_sel:DWORD
	v_cvt_pk_bf16_f32 v18, v16, v16
	v_add_u32_e32 v16, s7, v8
	v_add3_u32 v3, v17, v3, s33
	v_add_u32_e32 v14, s14, v9
	v_ashrrev_i32_e32 v17, 31, v16
	v_ashrrev_i32_e32 v15, 31, v14
	v_lshlrev_b64 v[16:17], 11, v[16:17]
	v_lshlrev_b64 v[14:15], 11, v[14:15]
	v_lshl_add_u64 v[16:17], v[6:7], 0, v[16:17]
	v_lshl_add_u64 v[14:15], v[6:7], 0, v[14:15]
	global_store_short_d16_hi v[16:17], v18, off
	global_store_short_d16_hi v[14:15], v3, off
	ds_read2_b32 v[14:15], v13 offset0:16 offset1:20
	s_or_b64 s[12:13], vcc, s[12:13]
	s_waitcnt lgkmcnt(0)
	v_cvt_pk_bf16_f32 v18, v14, v14
	v_add_u32_e32 v16, s15, v8
	v_and_b32_sdwa v3, v15, v116 dst_sel:DWORD dst_unused:UNUSED_PAD src0_sel:WORD_1 src1_sel:DWORD
	v_add_u32_e32 v14, s17, v9
	v_ashrrev_i32_e32 v17, 31, v16
	v_add3_u32 v3, v15, v3, s33
	v_ashrrev_i32_e32 v15, 31, v14
	v_lshlrev_b64 v[16:17], 11, v[16:17]
	v_lshlrev_b64 v[14:15], 11, v[14:15]
	v_lshl_add_u64 v[16:17], v[6:7], 0, v[16:17]
	v_lshl_add_u64 v[14:15], v[6:7], 0, v[14:15]
	global_store_short_d16_hi v[16:17], v18, off
	global_store_short_d16_hi v[14:15], v3, off
	ds_read2_b32 v[14:15], v13 offset0:24 offset1:28
	v_add_u32_e32 v13, 0x80, v13
	s_waitcnt lgkmcnt(0)
	v_cvt_pk_bf16_f32 v18, v14, v14
	v_add_u32_e32 v14, s19, v9
	v_add_u32_e32 v16, s18, v8
	v_cvt_pk_bf16_f32 v3, v15, v15
	v_ashrrev_i32_e32 v17, 31, v16
	v_ashrrev_i32_e32 v15, 31, v14
	v_lshlrev_b64 v[14:15], 11, v[14:15]
	v_lshlrev_b64 v[16:17], 11, v[16:17]
	v_lshl_add_u64 v[16:17], v[6:7], 0, v[16:17]
	v_lshl_add_u64 v[14:15], v[6:7], 0, v[14:15]
	global_store_short_d16_hi v[16:17], v18, off
	global_store_short_d16_hi v[14:15], v3, off
	v_add_u32_e32 v9, 32, v9
	v_add_u32_e32 v8, 32, v8
	v_mov_b32_e32 v14, s20
	s_andn2_b64 exec, exec, s[12:13]
	s_cbranch_execnz .LBB0_845
	s_or_b64 exec, exec, s[12:13]

.LBB0_849:
	ds_read2_b32 v[12:13], v10 offset1:4
	v_add_u32_e32 v3, -1, v3
	v_cmp_eq_u32_e32 vcc, 0, v3
	v_add_u32_e32 v10, 32, v10
	s_or_b64 s[12:13], vcc, s[12:13]
	s_waitcnt lgkmcnt(0)
	v_cvt_pk_bf16_f32 v16, v12, v12
	v_add_u32_e32 v14, s6, v8
	v_add_u32_e32 v12, s6, v9
	v_ashrrev_i32_e32 v15, 31, v14
	v_cvt_pk_bf16_f32 v11, v13, v13
	v_ashrrev_i32_e32 v13, 31, v12
	v_lshlrev_b64 v[14:15], 11, v[14:15]
	v_lshlrev_b64 v[12:13], 11, v[12:13]
	v_lshl_add_u64 v[14:15], v[6:7], 0, v[14:15]
	v_add_u32_e32 v9, 8, v9
	v_add_u32_e32 v8, 8, v8
	v_lshl_add_u64 v[12:13], v[6:7], 0, v[12:13]
	global_store_short_d16_hi v[14:15], v16, off
	global_store_short_d16_hi v[12:13], v11, off
	s_andn2_b64 exec, exec, s[12:13]
	s_cbranch_execnz .LBB0_849

.LBB0_853:
	ds_read_b32 v2, v1
	v_add_u32_e32 v6, 4, v6
	v_cmp_lt_i32_e32 vcc, 59, v6
	s_mov_b64 s[6:7], 0x2000
	v_add_u32_e32 v1, 16, v1
	s_waitcnt lgkmcnt(0)
	v_cvt_pk_bf16_f32 v2, v2, v2
	s_or_b64 s[4:5], vcc, s[4:5]
	global_store_short_d16_hi v[4:5], v2, off
	v_lshl_add_u64 v[4:5], v[4:5], 0, s[6:7]
	s_andn2_b64 exec, exec, s[4:5]
	s_cbranch_execnz .LBB0_853

.LBB0_861:
	s_waitcnt vmcnt(0)
	v_ashrrev_i32_e32 v64, 2, v1
	s_lshl_b32 s19, s6, 6
	v_and_b32_e32 v47, -16, v64
	v_and_b32_e32 v45, 15, v1
	v_add_u32_e32 v37, s19, v47
	v_or_b32_e32 v35, v37, v45
	v_add_u32_e32 v4, s17, v35
	v_mov_b64_e32 v[2:3], s[94:95]
	s_lshl_b32 s8, s10, 6
	v_bfe_u32 v36, v1, 4, 2
	v_mad_i64_i32 v[2:3], s[4:5], v4, s70, v[2:3]
	s_ashr_i32 s9, s8, 31
	v_lshl_add_u64 v[16:17], s[8:9], 1, v[2:3]
	v_lshlrev_b32_e32 v24, 4, v36
	v_mov_b32_e32 v25, v0
	v_lshl_add_u64 v[20:21], v[16:17], 0, v[24:25]
	global_load_dwordx4 v[2:5], v[20:21], off
	v_cndmask_b32_e64 v6, 0, 1, s[12:13]
	s_mov_b64 s[14:15], -1
	v_cmp_gt_u32_e64 s[4:5], 2, v36
	v_cmp_ne_u32_e64 s[6:7], 1, v6
	s_andn2_b64 vcc, exec, s[12:13]
	s_waitcnt vmcnt(0)
	v_and_b32_e32 v31, 0xffff0000, v2
	v_lshlrev_b32_e32 v30, 16, v2
	v_and_b32_e32 v29, 0xffff0000, v3
	v_lshlrev_b32_e32 v28, 16, v3
	v_and_b32_e32 v27, 0xffff0000, v4
	v_lshlrev_b32_e32 v26, 16, v4
	v_lshlrev_b32_e32 v22, 16, v5
	v_and_b32_e32 v2, 0xffff0000, v5
	s_cbranch_vccnz .LBB0_863
	s_mov_b32 s12, 0x3e000000
	v_pk_mul_f32 v[4:5], v[30:31], s[12:13] op_sel_hi:[1,0]
	s_mov_b64 s[14:15], 0
	v_and_b32_sdwa v6, v4, v116 dst_sel:DWORD dst_unused:UNUSED_PAD src0_sel:WORD_1 src1_sel:DWORD
	v_add3_u32 v7, v4, v6, s33
	v_cvt_pk_bf16_f32 v3, v5, v5
	v_pk_mul_f32 v[4:5], v[28:29], s[12:13] op_sel_hi:[1,0]
	s_nop 0
	v_and_b32_sdwa v6, v5, v116 dst_sel:DWORD dst_unused:UNUSED_PAD src0_sel:WORD_1 src1_sel:DWORD
	v_cvt_pk_bf16_f32 v8, v4, v4
	v_add3_u32 v9, v5, v6, s33
	v_pk_mul_f32 v[4:5], v[26:27], s[12:13] op_sel_hi:[1,0]
	s_nop 0
	v_cvt_pk_bf16_f32 v6, v4, v5
	v_perm_b32 v4, v3, v7, s3
	v_mul_f32_e32 v3, 0x3e000000, v22
	v_bfe_u32 v7, v3, 16, 1
	v_add3_u32 v3, v3, v7, s33
	v_perm_b32 v5, v9, v8, s3
	v_alignbit_b32 v7, 0, v3, 16
.LBB0_863:
	v_lshlrev_b32_e32 v3, 3, v36
	v_xor_b32_e32 v3, 16, v3
	v_and_b32_e32 v25, 16, v1
	s_andn2_b64 vcc, exec, s[14:15]
	v_lshlrev_b32_e32 v18, 1, v3
	s_cbranch_vccnz .LBB0_865
	v_ashrrev_i32_e32 v3, 1, v37
	s_movk_i32 s11, 0xffe0
	v_and_or_b32 v4, v3, s11, v25
	v_readlane_b32 s36, v241, 1
	v_mov_b32_e32 v19, v0
	v_ashrrev_i32_e32 v5, 31, v4
	v_readlane_b32 s48, v241, 13
	v_readlane_b32 s49, v241, 14
	v_lshl_add_u64 v[12:13], v[16:17], 0, v[18:19]
	v_mov_b32_e32 v55, v31
	v_lshl_add_u64 v[8:9], v[4:5], 2, s[48:49]
	global_load_dwordx4 v[4:7], v[8:9], off offset:32
	global_load_dwordx4 v[38:41], v[8:9], off offset:16
	global_load_dwordx4 v[48:51], v[8:9], off
	s_nop 0
	global_load_dwordx4 v[8:11], v[8:9], off offset:48
	s_mov_b32 s12, 0x3e000000
	global_load_dwordx4 v[12:15], v[12:13], off
	v_readlane_b32 s37, v241, 2
	v_readlane_b32 s38, v241, 3
	v_readlane_b32 s39, v241, 4
	v_readlane_b32 s40, v241, 5
	v_readlane_b32 s41, v241, 6
	v_readlane_b32 s42, v241, 7
	v_readlane_b32 s43, v241, 8
	v_readlane_b32 s44, v241, 9
	v_readlane_b32 s45, v241, 10
	v_readlane_b32 s46, v241, 11
	v_readlane_b32 s47, v241, 12
	v_readlane_b32 s50, v241, 15
	v_readlane_b32 s51, v241, 16
	s_waitcnt vmcnt(4)
	v_mov_b32_e32 v52, v5
	s_waitcnt vmcnt(3)
	v_mov_b32_e32 v42, v39
	s_waitcnt vmcnt(2)
	v_mov_b32_e32 v32, v49
	v_mov_b32_e32 v49, v51
	v_mov_b32_e32 v33, v50
	s_waitcnt vmcnt(0)
	v_lshlrev_b32_e32 v3, 16, v12
	v_cndmask_b32_e64 v54, v3, -v3, s[4:5]
	v_and_b32_e32 v3, 0xffff0000, v12
	v_cndmask_b32_e64 v3, v3, -v3, s[4:5]
	v_mov_b32_e32 v31, v3
	v_pk_mul_f32 v[30:31], v[48:49], v[30:31]
	v_mov_b32_e32 v39, v41
	v_pk_fma_f32 v[30:31], v[32:33], v[54:55], v[30:31]
	v_mov_b32_e32 v43, v40
	v_pk_mul_f32 v[30:31], v[30:31], s[12:13] op_sel_hi:[1,0]
	v_mov_b32_e32 v53, v6
	v_lshlrev_b32_e32 v5, 16, v13
	v_cndmask_b32_e64 v12, v5, -v5, s[4:5]
	v_and_b32_e32 v5, 0xffff0000, v13
	v_cndmask_b32_e64 v5, v5, -v5, s[4:5]
	v_mov_b32_e32 v13, v29
	v_mov_b32_e32 v29, v5
	v_pk_mul_f32 v[28:29], v[38:39], v[28:29]
	v_pk_fma_f32 v[12:13], v[12:13], v[42:43], v[28:29]
	v_pk_mul_f32 v[12:13], v[12:13], s[12:13] op_sel_hi:[1,0]
	s_nop 0
	v_cvt_pk_bf16_f32 v28, v13, v13
	v_lshlrev_b32_e32 v5, 16, v14
	v_cvt_pk_bf16_f32 v23, v12, v12
	v_cndmask_b32_e64 v12, v5, -v5, s[4:5]
	v_and_b32_e32 v5, 0xffff0000, v14
	v_cndmask_b32_e64 v6, v5, -v5, s[4:5]
	v_mov_b32_e32 v13, v27
	v_mov_b32_e32 v5, v7
	v_mov_b32_e32 v27, v6
	v_pk_mul_f32 v[4:5], v[4:5], v[26:27]
	s_nop 0
	v_pk_fma_f32 v[4:5], v[12:13], v[52:53], v[4:5]
	s_nop 0
	v_pk_mul_f32 v[4:5], v[4:5], s[12:13] op_sel_hi:[1,0]
	s_nop 0
	v_cvt_pk_bf16_f32 v6, v4, v5
	v_cvt_pk_bf16_f32 v4, v30, v31
	v_lshlrev_b32_e32 v3, 16, v15
	v_perm_b32 v5, v28, v23, s3
	v_cndmask_b32_e64 v23, v3, -v3, s[4:5]
	v_pk_mul_f32 v[8:9], v[8:9], v[22:23]
	s_nop 0
	v_add_f32_e32 v3, v8, v9
	v_mul_f32_e32 v3, 0x3e000000, v3
	v_bfe_u32 v7, v3, 16, 1
	v_add3_u32 v3, v3, v7, s33
	v_alignbit_b32 v7, 0, v3, 16
	v_and_b32_e32 v3, 0xffff0000, v15
	v_cndmask_b32_e64 v3, v3, -v3, s[4:5]
	v_pk_mul_f32 v[2:3], v[10:11], v[2:3]
	s_nop 0
	v_add_f32_e32 v2, v2, v3
.LBB0_865:
	global_load_dwordx4 v[8:11], v[20:21], off offset:64
	s_mov_b64 s[12:13], -1
	s_and_b64 vcc, exec, s[6:7]
	s_waitcnt vmcnt(0)
	v_and_b32_e32 v29, 0xffff0000, v8
	v_lshlrev_b32_e32 v28, 16, v8
	v_and_b32_e32 v31, 0xffff0000, v9
	v_lshlrev_b32_e32 v30, 16, v9
	v_and_b32_e32 v33, 0xffff0000, v10
	v_lshlrev_b32_e32 v32, 16, v10
	v_lshlrev_b32_e32 v34, 16, v11
	v_and_b32_e32 v26, 0xffff0000, v11
	s_cbranch_vccnz .LBB0_867
	s_mov_b32 s6, 0x3e000000
	v_pk_mul_f32 v[8:9], v[28:29], s[6:7] op_sel_hi:[1,0]
	s_mov_b64 s[12:13], 0
	v_and_b32_sdwa v10, v8, v116 dst_sel:DWORD dst_unused:UNUSED_PAD src0_sel:WORD_1 src1_sel:DWORD
	v_add3_u32 v11, v8, v10, s33
	v_cvt_pk_bf16_f32 v3, v9, v9
	v_pk_mul_f32 v[8:9], v[30:31], s[6:7] op_sel_hi:[1,0]
	s_nop 0
	v_and_b32_sdwa v10, v9, v116 dst_sel:DWORD dst_unused:UNUSED_PAD src0_sel:WORD_1 src1_sel:DWORD
	v_cvt_pk_bf16_f32 v12, v8, v8
	v_add3_u32 v13, v9, v10, s33
	v_pk_mul_f32 v[8:9], v[32:33], s[6:7] op_sel_hi:[1,0]
	s_nop 0
	v_cvt_pk_bf16_f32 v10, v8, v9
	v_perm_b32 v8, v3, v11, s3
	v_mul_f32_e32 v3, 0x3e000000, v34
	v_bfe_u32 v11, v3, 16, 1
	v_add3_u32 v3, v3, v11, s33
	v_perm_b32 v9, v13, v12, s3
	v_alignbit_b32 v11, 0, v3, 16
.LBB0_867:
	s_mov_b32 s27, s23
	s_mov_b32 s21, 4
	s_andn2_b64 vcc, exec, s[12:13]
	s_mov_b32 s20, 4
	s_cbranch_vccnz .LBB0_869
	v_mov_b32_e32 v19, v0
	v_lshl_add_u64 v[8:9], v[16:17], 0, v[18:19]
	v_lshlrev_b32_e32 v3, 5, v35
	s_movk_i32 s6, 0x7e0
	global_load_dwordx4 v[38:41], v[8:9], off offset:64
	v_and_or_b32 v3, v3, s6, v25
	v_readlane_b32 s36, v241, 1
	v_lshlrev_b32_e32 v3, 2, v3
	v_readlane_b32 s48, v241, 13
	v_readlane_b32 s49, v241, 14
	s_nop 4
	global_load_dwordx4 v[16:19], v3, s[48:49]
	global_load_dwordx4 v[12:15], v3, s[48:49] offset:16
	global_load_dwordx4 v[8:11], v3, s[48:49] offset:32
	global_load_dwordx4 v[20:23], v3, s[48:49] offset:48
	v_mov_b32_e32 v43, v29
	v_mov_b32_e32 v49, v31
	v_mov_b32_e32 v51, v33
	s_mov_b32 s20, 5
	s_mov_b32 s21, 9
	v_readlane_b32 s37, v241, 2
	v_readlane_b32 s38, v241, 3
	v_readlane_b32 s39, v241, 4
	v_readlane_b32 s40, v241, 5
	v_readlane_b32 s41, v241, 6
	v_readlane_b32 s42, v241, 7
	v_readlane_b32 s43, v241, 8
	v_readlane_b32 s44, v241, 9
	v_readlane_b32 s45, v241, 10
	v_readlane_b32 s46, v241, 11
	v_readlane_b32 s47, v241, 12
	v_readlane_b32 s50, v241, 15
	v_readlane_b32 s51, v241, 16
	s_waitcnt vmcnt(4)
	v_lshlrev_b32_e32 v3, 16, v38
	v_and_b32_e32 v25, 0xffff0000, v38
	v_and_b32_e32 v29, 0xffff0000, v39
	v_lshlrev_b32_e32 v31, 16, v40
	v_and_b32_e32 v33, 0xffff0000, v40
	v_lshlrev_b32_e32 v35, 16, v41
	s_waitcnt vmcnt(1)
	v_mov_b32_e32 v53, v10
	v_cndmask_b32_e64 v42, v3, -v3, s[4:5]
	v_cndmask_b32_e64 v3, v25, -v25, s[4:5]
	v_cndmask_b32_e64 v10, v29, -v29, s[4:5]
	v_lshlrev_b32_e32 v27, 16, v39
	v_mov_b32_e32 v38, v17
	v_mov_b32_e32 v40, v13
	v_mov_b32_e32 v52, v9
	v_mov_b32_e32 v17, v19
	v_mov_b32_e32 v13, v15
	v_cndmask_b32_e64 v50, v31, -v31, s[4:5]
	v_cndmask_b32_e64 v33, v33, -v33, s[4:5]
	v_mov_b32_e32 v9, v11
	v_cndmask_b32_e64 v35, v35, -v35, s[4:5]
	v_mov_b32_e32 v29, v3
	v_mov_b32_e32 v31, v10
	v_and_b32_e32 v44, 0xffff0000, v41
	v_mov_b32_e32 v39, v18
	v_mov_b32_e32 v41, v14
	v_cndmask_b32_e64 v48, v27, -v27, s[4:5]
	s_waitcnt vmcnt(0)
	v_pk_mul_f32 v[10:11], v[20:21], v[34:35]
	v_pk_mul_f32 v[16:17], v[16:17], v[28:29]
	v_pk_mul_f32 v[12:13], v[12:13], v[30:31]
	v_pk_mul_f32 v[8:9], v[8:9], v[32:33]
	v_cndmask_b32_e64 v27, v44, -v44, s[4:5]
	v_add_f32_e32 v3, v10, v11
	v_pk_fma_f32 v[10:11], v[38:39], v[42:43], v[16:17]
	v_pk_fma_f32 v[12:13], v[48:49], v[40:41], v[12:13]
	v_pk_fma_f32 v[8:9], v[50:51], v[52:53], v[8:9]
	s_mov_b32 s4, 0x3e000000
	v_pk_mul_f32 v[14:15], v[22:23], v[26:27]
	v_mul_f32_e32 v3, 0x3e000000, v3
	v_pk_mul_f32 v[10:11], v[10:11], s[4:5] op_sel_hi:[1,0]
	v_pk_mul_f32 v[12:13], v[12:13], s[4:5] op_sel_hi:[1,0]
	v_pk_mul_f32 v[8:9], v[8:9], s[4:5] op_sel_hi:[1,0]
	v_add_f32_e32 v26, v14, v15
	v_bfe_u32 v14, v3, 16, 1
	v_and_b32_sdwa v17, v13, v116 dst_sel:DWORD dst_unused:UNUSED_PAD src0_sel:WORD_1 src1_sel:DWORD
	v_add3_u32 v3, v3, v14, s33
	v_cvt_pk_bf16_f32 v14, v10, v10
	v_cvt_pk_bf16_f32 v15, v11, v11
	v_cvt_pk_bf16_f32 v12, v12, v12
	v_add3_u32 v13, v13, v17, s33
	v_alignbit_b32 v11, 0, v3, 16
	v_cvt_pk_bf16_f32 v10, v8, v9
	v_perm_b32 v9, v13, v12, s3
	v_perm_b32 v8, v15, v14, s3

.LBB0_884:
	v_cvt_pk_bf16_f32 v31, v30, v36
	v_cvt_pk_bf16_f32 v30, v38, v29
	v_cvt_pk_bf16_f32 v29, v60, v35
	v_cvt_pk_bf16_f32 v28, v62, v33
	ds_write_b128 v76, v[28:31]
	s_andn2_b64 vcc, exec, s[14:15]
	s_mov_b64 s[14:15], -1
	s_cbranch_vccnz .LBB0_886
	global_load_dwordx4 v[36:39], v[56:57], off offset:32
	global_load_dwordx4 v[28:31], v[56:57], off offset:48
	s_mov_b64 s[14:15], 0

.LBB0_889:
	s_waitcnt vmcnt(0)
	v_cvt_pk_bf16_f32 v31, v30, v31
	v_cvt_pk_bf16_f32 v30, v28, v29
	v_cvt_pk_bf16_f32 v29, v38, v39
	v_cvt_pk_bf16_f32 v28, v36, v37
	ds_write_b128 v76, v[28:31] offset:16
	s_waitcnt lgkmcnt(0)
	s_barrier
	ds_read_b128 v[28:31], v77
	ds_read_b128 v[32:35], v77 offset:64
	s_waitcnt lgkmcnt(1)
	v_mfma_f32_16x16x32_bf16 v[28:31], v[4:7], v[28:31], 0
	s_and_b64 s[6:7], s[0:1], s[12:13]
	s_andn2_b64 vcc, exec, s[6:7]
	s_waitcnt lgkmcnt(0)
	v_mfma_f32_16x16x32_bf16 v[28:31], v[8:11], v[32:35], v[28:31]
	ds_read_b128 v[32:35], v77 offset:2304
	ds_read_b128 v[36:39], v77 offset:2368
	s_waitcnt lgkmcnt(1)
	v_mfma_f32_16x16x32_bf16 v[32:35], v[4:7], v[32:35], 0
	s_waitcnt lgkmcnt(0)
	v_mfma_f32_16x16x32_bf16 v[32:35], v[8:11], v[36:39], v[32:35]
	ds_read_b128 v[36:39], v77 offset:4608
	ds_read_b128 v[40:43], v77 offset:4672
	s_waitcnt lgkmcnt(1)
	v_mfma_f32_16x16x32_bf16 v[36:39], v[4:7], v[36:39], 0
	s_waitcnt lgkmcnt(0)
	v_mfma_f32_16x16x32_bf16 v[36:39], v[8:11], v[40:43], v[36:39]
	ds_read_b128 v[40:43], v77 offset:6912
	ds_read_b128 v[56:59], v77 offset:6976
	s_waitcnt lgkmcnt(1)
	v_mfma_f32_16x16x32_bf16 v[40:43], v[4:7], v[40:43], 0
	s_waitcnt lgkmcnt(0)
	v_mfma_f32_16x16x32_bf16 v[40:43], v[8:11], v[56:59], v[40:43]
	s_cbranch_vccnz .LBB0_870
	v_add_u32_e32 v56, s26, v45
	v_sub_u32_e32 v57, v69, v56
	v_sub_u32_e32 v58, 0, v57
	v_max_i32_e32 v58, v57, v58
	s_movk_i32 s6, 0x80
	v_cmp_lt_u32_e32 vcc, s6, v58
	v_add_u32_e32 v58, 1, v57
	v_not_b32_e32 v59, v57
	v_max_i32_e32 v58, v58, v59
	v_cndmask_b32_e32 v28, v28, v118, vcc
	v_cmp_gt_u32_e32 vcc, s74, v58
	v_add_u32_e32 v58, 2, v57
	v_sub_u32_e32 v59, -2, v57
	v_max_i32_e32 v58, v58, v59
	v_cndmask_b32_e32 v29, v118, v29, vcc
	v_cmp_gt_u32_e32 vcc, s74, v58
	v_add_u32_e32 v58, 3, v57
	v_sub_u32_e32 v57, -3, v57
	v_max_i32_e32 v57, v58, v57
	v_cndmask_b32_e32 v30, v118, v30, vcc
	v_cmp_gt_u32_e32 vcc, s74, v57
	v_sub_u32_e32 v57, v70, v56
	v_sub_u32_e32 v58, 0, v57
	v_max_i32_e32 v58, v57, v58
	v_cndmask_b32_e32 v31, v118, v31, vcc
	v_cmp_gt_u32_e32 vcc, s74, v58
	v_add_u32_e32 v58, 1, v57
	v_not_b32_e32 v59, v57
	v_max_i32_e32 v58, v58, v59
	v_cndmask_b32_e32 v32, v118, v32, vcc
	v_cmp_gt_u32_e32 vcc, s74, v58
	v_add_u32_e32 v58, 2, v57
	v_sub_u32_e32 v59, -2, v57
	v_max_i32_e32 v58, v58, v59
	v_cndmask_b32_e32 v33, v118, v33, vcc
	v_cmp_gt_u32_e32 vcc, s74, v58
	v_add_u32_e32 v58, 3, v57
	v_sub_u32_e32 v57, -3, v57
	v_max_i32_e32 v57, v58, v57
	v_cndmask_b32_e32 v34, v118, v34, vcc
	v_cmp_gt_u32_e32 vcc, s74, v57
	v_sub_u32_e32 v57, v71, v56
	v_sub_u32_e32 v58, 0, v57
	v_max_i32_e32 v58, v57, v58
	v_cndmask_b32_e32 v35, v118, v35, vcc
	v_cmp_gt_u32_e32 vcc, s74, v58
	v_add_u32_e32 v58, 1, v57
	v_not_b32_e32 v59, v57
	v_max_i32_e32 v58, v58, v59
	v_cndmask_b32_e32 v36, v118, v36, vcc
	v_cmp_gt_u32_e32 vcc, s74, v58
	v_add_u32_e32 v58, 2, v57
	v_sub_u32_e32 v59, -2, v57
	v_max_i32_e32 v58, v58, v59
	v_cndmask_b32_e32 v37, v118, v37, vcc
	v_cmp_gt_u32_e32 vcc, s74, v58
	v_add_u32_e32 v58, 3, v57
	v_sub_u32_e32 v57, -3, v57
	v_max_i32_e32 v57, v58, v57
	v_sub_u32_e32 v56, v72, v56
	v_cndmask_b32_e32 v38, v118, v38, vcc
	v_cmp_gt_u32_e32 vcc, s74, v57
	v_sub_u32_e32 v57, 0, v56
	v_max_i32_e32 v57, v56, v57
	v_cndmask_b32_e32 v39, v118, v39, vcc
	v_cmp_gt_u32_e32 vcc, s74, v57
	v_add_u32_e32 v57, 1, v56
	v_not_b32_e32 v58, v56
	v_max_i32_e32 v57, v57, v58
	v_cndmask_b32_e32 v40, v118, v40, vcc
	v_cmp_gt_u32_e32 vcc, s74, v57
	v_add_u32_e32 v57, 2, v56
	v_sub_u32_e32 v58, -2, v56
	v_max_i32_e32 v57, v57, v58
	v_cndmask_b32_e32 v41, v118, v41, vcc
	v_cmp_gt_u32_e32 vcc, s74, v57
	v_add_u32_e32 v57, 3, v56
	v_sub_u32_e32 v56, -3, v56
	v_max_i32_e32 v56, v57, v56
	v_cndmask_b32_e32 v42, v118, v42, vcc
	v_cmp_gt_u32_e32 vcc, s74, v56
	s_nop 1
	v_cndmask_b32_e32 v43, v118, v43, vcc
	s_branch .LBB0_870

.LBB0_985:
	s_andn2_saveexec_b64 s[0:1], s[0:1]
	s_cbranch_execz .LBB0_1003
	v_add_u32_e32 v74, v129, v129
	v_add_u32_e32 v1, 0xb400, v74
	v_add_u32_e32 v142, 0xc000, v74
	ds_read2_b64 v[66:69], v1 offset0:96 offset1:192
	v_add_u32_e32 v89, 0xbc00, v74
	ds_read2_b64 v[74:77], v142 offset0:96 offset1:192
	ds_read2_b64 v[70:73], v89 offset0:32 offset1:128
	s_waitcnt vmcnt(16)
	v_lshlrev_b32_e32 v144, 16, v26
	v_lshlrev_b32_e32 v80, 16, v18
	v_lshlrev_b32_e32 v146, 16, v30
	v_mov_b32_e32 v81, v144
	v_lshlrev_b32_e32 v84, 16, v14
	s_waitcnt lgkmcnt(1)
	v_pk_fma_f32 v[80:81], v[66:67], v[80:81], v[76:77] op_sel_hi:[0,1,0]
	v_mov_b32_e32 v85, v146
	v_lshlrev_b32_e32 v145, 16, v34
	v_pk_fma_f32 v[80:81], v[68:69], v[84:85], v[80:81] op_sel_hi:[0,1,1]
	v_lshlrev_b32_e32 v147, 16, v38
	s_waitcnt lgkmcnt(0)
	v_pk_fma_f32 v[80:81], v[70:71], v[144:145], v[80:81] op_sel_hi:[0,1,1]
	v_lshlrev_b32_e32 v83, 16, v42
	v_mov_b32_e32 v82, v145
	v_pk_fma_f32 v[80:81], v[72:73], v[146:147], v[80:81] op_sel_hi:[0,1,1]
	v_pk_fma_f32 v[80:81], v[74:75], v[82:83], v[80:81] op_sel_hi:[0,1,1]
	v_mul_f32_e32 v107, 0xbfb8aa3b, v80
	v_pk_fma_f32 v[84:85], v[66:67], v[84:85], v[76:77] op_sel_hi:[0,1,0]
	v_exp_f32_e32 v154, v107
	v_mul_f32_e32 v107, 0xbfb8aa3b, v81
	v_pk_fma_f32 v[84:85], v[68:69], v[144:145], v[84:85] op_sel_hi:[0,1,1]
	v_exp_f32_e32 v155, v107
	v_pk_fma_f32 v[84:85], v[70:71], v[146:147], v[84:85] op_sel_hi:[0,1,1]
	v_lshlrev_b32_e32 v79, 16, v46
	v_mov_b32_e32 v78, v147
	v_pk_fma_f32 v[84:85], v[72:73], v[82:83], v[84:85] op_sel_hi:[0,1,1]
	v_pk_fma_f32 v[84:85], v[74:75], v[78:79], v[84:85] op_sel_hi:[0,1,1]
	v_mul_f32_e32 v107, 0xbfb8aa3b, v84
	v_pk_add_f32 v[154:155], v[154:155], 1.0 op_sel_hi:[1,0]
	v_exp_f32_e32 v144, v107
	v_mul_f32_e32 v107, 0xbfb8aa3b, v85
	v_exp_f32_e32 v145, v107
	v_rcp_f32_e32 v143, v155
	v_pk_add_f32 v[146:147], v[144:145], 1.0 op_sel_hi:[1,0]
	v_and_b32_e32 v150, 0xffff0000, v26
	v_and_b32_e32 v148, 0xffff0000, v18
	v_mul_f32_e32 v143, v81, v143
	v_rcp_f32_e32 v107, v154
	v_and_b32_e32 v152, 0xffff0000, v30
	v_and_b32_e32 v106, 0xffff0000, v14
	v_mul_f32_e32 v144, v80, v107
	v_rcp_f32_e32 v81, v147
	s_nop 0
	v_mul_f32_e32 v145, v85, v81
	v_rcp_f32_e32 v81, v146
	v_mov_b32_e32 v149, v150
	v_pk_fma_f32 v[148:149], v[66:67], v[148:149], v[76:77] op_sel:[1,0,1]
	v_mul_f32_e32 v146, v84, v81
	v_and_b32_e32 v84, 0xffff0000, v34
	v_mov_b32_e32 v107, v152
	v_mov_b32_e32 v151, v84
	v_and_b32_e32 v80, 0xffff0000, v38
	v_pk_fma_f32 v[148:149], v[68:69], v[106:107], v[148:149] op_sel:[1,0,0]
	v_mov_b32_e32 v153, v80
	v_pk_fma_f32 v[148:149], v[70:71], v[150:151], v[148:149] op_sel:[1,0,0]
	v_pk_fma_f32 v[106:107], v[66:67], v[106:107], v[76:77] op_sel:[1,0,1]
	v_and_b32_e32 v85, 0xffff0000, v42
	v_pk_fma_f32 v[148:149], v[72:73], v[152:153], v[148:149] op_sel:[1,0,0]
	v_pk_fma_f32 v[106:107], v[68:69], v[150:151], v[106:107] op_sel:[1,0,0]
	v_pk_fma_f32 v[148:149], v[74:75], v[84:85], v[148:149] op_sel:[1,0,0]
	v_pk_fma_f32 v[106:107], v[70:71], v[152:153], v[106:107] op_sel:[1,0,0]
	v_and_b32_e32 v81, 0xffff0000, v46
	v_mul_f32_e32 v147, 0xbfb8aa3b, v148
	v_pk_fma_f32 v[106:107], v[72:73], v[84:85], v[106:107] op_sel:[1,0,0]
	v_exp_f32_e32 v154, v147
	v_mul_f32_e32 v147, 0xbfb8aa3b, v149
	v_pk_fma_f32 v[150:151], v[74:75], v[80:81], v[106:107] op_sel:[1,0,0]
	v_exp_f32_e32 v155, v147
	v_mul_f32_e32 v106, 0xbfb8aa3b, v150
	v_mul_f32_e32 v107, 0xbfb8aa3b, v151
	v_exp_f32_e32 v106, v106
	v_exp_f32_e32 v107, v107
	v_pk_add_f32 v[154:155], v[154:155], 1.0 op_sel_hi:[1,0]
	v_pk_add_f32 v[152:153], v[106:107], 1.0 op_sel_hi:[1,0]
	v_rcp_f32_e32 v107, v155
	s_nop 0
	v_mul_f32_e32 v106, v149, v107
	v_rcp_f32_e32 v147, v154
	s_nop 0
	v_mul_f32_e32 v107, v148, v147
	v_rcp_f32_e32 v148, v153
	s_nop 0
	v_mul_f32_e32 v147, v151, v148
	v_rcp_f32_e32 v149, v152
	s_nop 0
	v_mul_f32_e32 v148, v150, v149
	v_lshlrev_b32_e32 v150, 16, v50
	v_lshlrev_b32_e32 v151, 16, v58
	v_pk_fma_f32 v[154:155], v[66:67], v[82:83], v[76:77] op_sel_hi:[0,1,0]
	v_lshlrev_b32_e32 v152, 16, v54
	v_lshlrev_b32_e32 v153, 16, v62
	v_pk_fma_f32 v[154:155], v[68:69], v[78:79], v[154:155] op_sel_hi:[0,1,1]
	v_pk_mov_b32 v[82:83], v[82:83], v[150:151] op_sel:[1,0]
	v_pk_mov_b32 v[156:157], v[78:79], v[152:153] op_sel:[1,0]
	v_pk_fma_f32 v[154:155], v[70:71], v[82:83], v[154:155] op_sel_hi:[0,1,1]
	v_pk_fma_f32 v[78:79], v[66:67], v[78:79], v[76:77] op_sel_hi:[0,1,0]
	v_pk_fma_f32 v[154:155], v[72:73], v[156:157], v[154:155] op_sel_hi:[0,1,1]
	v_pk_fma_f32 v[78:79], v[68:69], v[82:83], v[78:79] op_sel_hi:[0,1,1]
	v_pk_fma_f32 v[154:155], v[74:75], v[150:151], v[154:155] op_sel_hi:[0,1,1]
	v_pk_fma_f32 v[78:79], v[70:71], v[156:157], v[78:79] op_sel_hi:[0,1,1]
	v_mul_f32_e32 v149, 0xbfb8aa3b, v154
	v_pk_fma_f32 v[78:79], v[72:73], v[150:151], v[78:79] op_sel_hi:[0,1,1]
	v_exp_f32_e32 v158, v149
	v_mul_f32_e32 v149, 0xbfb8aa3b, v155
	v_pk_fma_f32 v[150:151], v[74:75], v[152:153], v[78:79] op_sel_hi:[0,1,1]
	v_exp_f32_e32 v159, v149
	v_mul_f32_e32 v78, 0xbfb8aa3b, v150
	v_mul_f32_e32 v79, 0xbfb8aa3b, v151
	v_exp_f32_e32 v78, v78
	v_exp_f32_e32 v79, v79
	v_pk_add_f32 v[158:159], v[158:159], 1.0 op_sel_hi:[1,0]
	v_pk_add_f32 v[152:153], v[78:79], 1.0 op_sel_hi:[1,0]
	v_rcp_f32_e32 v79, v159
	s_nop 0
	v_mul_f32_e32 v78, v155, v79
	v_rcp_f32_e32 v82, v158
	s_nop 0
	v_mul_f32_e32 v79, v154, v82
	v_rcp_f32_e32 v83, v153
	s_nop 0
	v_mul_f32_e32 v82, v151, v83
	v_rcp_f32_e32 v149, v152
	s_nop 0
	v_mul_f32_e32 v83, v150, v149
	v_and_b32_e32 v151, 0xffff0000, v58
	v_and_b32_e32 v150, 0xffff0000, v50
	v_pk_fma_f32 v[154:155], v[66:67], v[84:85], v[76:77] op_sel:[1,0,1]
	v_and_b32_e32 v153, 0xffff0000, v62
	v_and_b32_e32 v152, 0xffff0000, v54
	v_pk_fma_f32 v[154:155], v[68:69], v[80:81], v[154:155] op_sel:[1,0,0]
	v_pk_mov_b32 v[84:85], v[84:85], v[150:151] op_sel:[1,0]
	v_pk_mov_b32 v[156:157], v[80:81], v[152:153] op_sel:[1,0]
	v_pk_fma_f32 v[154:155], v[70:71], v[84:85], v[154:155] op_sel:[1,0,0]
	v_pk_fma_f32 v[66:67], v[66:67], v[80:81], v[76:77] op_sel:[1,0,1]
	v_pk_fma_f32 v[154:155], v[72:73], v[156:157], v[154:155] op_sel:[1,0,0]
	v_pk_fma_f32 v[66:67], v[68:69], v[84:85], v[66:67] op_sel:[1,0,0]
	v_pk_fma_f32 v[154:155], v[74:75], v[150:151], v[154:155] op_sel:[1,0,0]
	v_pk_fma_f32 v[66:67], v[70:71], v[156:157], v[66:67] op_sel:[1,0,0]
	v_mul_f32_e32 v149, 0xbfb8aa3b, v154
	v_pk_fma_f32 v[66:67], v[72:73], v[150:151], v[66:67] op_sel:[1,0,0]
	v_exp_f32_e32 v158, v149
	v_mul_f32_e32 v149, 0xbfb8aa3b, v155
	v_pk_fma_f32 v[70:71], v[74:75], v[152:153], v[66:67] op_sel:[1,0,0]
	v_exp_f32_e32 v159, v149
	v_mul_f32_e32 v66, 0xbfb8aa3b, v70
	v_mul_f32_e32 v67, 0xbfb8aa3b, v71
	v_exp_f32_e32 v66, v66
	v_exp_f32_e32 v67, v67
	v_pk_add_f32 v[158:159], v[158:159], 1.0 op_sel_hi:[1,0]
	v_pk_add_f32 v[72:73], v[66:67], 1.0 op_sel_hi:[1,0]
	v_rcp_f32_e32 v67, v159
	s_nop 0
	v_mul_f32_e32 v66, v155, v67
	v_rcp_f32_e32 v68, v158
	s_nop 0
	v_mul_f32_e32 v67, v154, v68
	v_rcp_f32_e32 v69, v73
	s_nop 0
	v_mul_f32_e32 v68, v71, v69
	v_rcp_f32_e32 v71, v72
	s_nop 0
	v_mul_f32_e32 v69, v70, v71
	s_and_saveexec_b64 s[58:59], s[8:9]
	s_cbranch_execz .LBB0_988
	v_cvt_pk_bf16_f32 v70, v144, v107
	v_cvt_pk_bf16_f32 v71, v146, v148
	ds_write2_b32 v140, v70, v71 offset1:36
	v_cvt_pk_bf16_f32 v70, v143, v106
	v_cvt_pk_bf16_f32 v71, v145, v147
	ds_write2_b32 v140, v70, v71 offset0:72 offset1:108
	v_cvt_pk_bf16_f32 v70, v79, v67
	v_cvt_pk_bf16_f32 v71, v83, v69
	ds_write2_b32 v140, v70, v71 offset0:144 offset1:180
	v_cvt_pk_bf16_f32 v70, v78, v66
	v_cvt_pk_bf16_f32 v71, v82, v68
	ds_write2_b32 v140, v70, v71 offset0:216 offset1:252
.LBB0_988:
	s_or_b64 exec, exec, s[58:59]
	s_and_saveexec_b64 s[58:59], s[10:11]
	s_cbranch_execz .LBB0_990
	v_and_b32_sdwa v71, v144, v116 dst_sel:DWORD dst_unused:UNUSED_PAD src0_sel:WORD_1 src1_sel:DWORD
	v_add3_u32 v72, v144, v71, s33
	v_and_b32_sdwa v70, v143, v116 dst_sel:DWORD dst_unused:UNUSED_PAD src0_sel:WORD_1 src1_sel:DWORD
	v_cvt_pk_bf16_f32 v71, v145, v145
	v_cvt_pk_bf16_f32 v73, v146, v146
	v_add3_u32 v70, v143, v70, s33
	v_and_b32_e32 v71, 0xffff0000, v71
	v_and_b32_e32 v73, 0xffff0000, v73
	v_or_b32_sdwa v71, v71, v70 dst_sel:DWORD dst_unused:UNUSED_PAD src0_sel:DWORD src1_sel:WORD_1
	v_or_b32_sdwa v70, v73, v72 dst_sel:DWORD dst_unused:UNUSED_PAD src0_sel:DWORD src1_sel:WORD_1
	v_and_b32_sdwa v73, v79, v116 dst_sel:DWORD dst_unused:UNUSED_PAD src0_sel:WORD_1 src1_sel:DWORD
	v_add3_u32 v74, v79, v73, s33
	v_and_b32_sdwa v72, v78, v116 dst_sel:DWORD dst_unused:UNUSED_PAD src0_sel:WORD_1 src1_sel:DWORD
	v_cvt_pk_bf16_f32 v73, v82, v82
	v_cvt_pk_bf16_f32 v75, v83, v83
	v_add3_u32 v72, v78, v72, s33
	v_and_b32_e32 v73, 0xffff0000, v73
	v_and_b32_e32 v75, 0xffff0000, v75
	v_or_b32_sdwa v73, v73, v72 dst_sel:DWORD dst_unused:UNUSED_PAD src0_sel:DWORD src1_sel:WORD_1
	v_or_b32_sdwa v72, v75, v74 dst_sel:DWORD dst_unused:UNUSED_PAD src0_sel:DWORD src1_sel:WORD_1
	ds_write_b128 v130, v[70:73]
	v_and_b32_sdwa v71, v107, v116 dst_sel:DWORD dst_unused:UNUSED_PAD src0_sel:WORD_1 src1_sel:DWORD
	v_add3_u32 v72, v107, v71, s33
	v_and_b32_sdwa v70, v106, v116 dst_sel:DWORD dst_unused:UNUSED_PAD src0_sel:WORD_1 src1_sel:DWORD
	v_cvt_pk_bf16_f32 v71, v147, v147
	v_cvt_pk_bf16_f32 v73, v148, v148
	v_add3_u32 v70, v106, v70, s33
	v_and_b32_e32 v71, 0xffff0000, v71
	v_and_b32_e32 v73, 0xffff0000, v73
	v_or_b32_sdwa v71, v71, v70 dst_sel:DWORD dst_unused:UNUSED_PAD src0_sel:DWORD src1_sel:WORD_1
	v_or_b32_sdwa v70, v73, v72 dst_sel:DWORD dst_unused:UNUSED_PAD src0_sel:DWORD src1_sel:WORD_1
	v_and_b32_sdwa v72, v66, v116 dst_sel:DWORD dst_unused:UNUSED_PAD src0_sel:WORD_1 src1_sel:DWORD
	v_and_b32_sdwa v73, v67, v116 dst_sel:DWORD dst_unused:UNUSED_PAD src0_sel:WORD_1 src1_sel:DWORD
	v_add3_u32 v67, v67, v73, s33
	v_add3_u32 v66, v66, v72, s33
	v_and_b32_sdwa v72, v68, v116 dst_sel:DWORD dst_unused:UNUSED_PAD src0_sel:WORD_1 src1_sel:DWORD
	v_and_b32_sdwa v73, v69, v116 dst_sel:DWORD dst_unused:UNUSED_PAD src0_sel:WORD_1 src1_sel:DWORD
	v_add3_u32 v68, v68, v72, s33
	v_add3_u32 v69, v69, v73, s33
	v_and_b32_e32 v68, 0xffff0000, v68
	v_and_b32_e32 v69, 0xffff0000, v69
	v_or_b32_sdwa v73, v68, v66 dst_sel:DWORD dst_unused:UNUSED_PAD src0_sel:DWORD src1_sel:WORD_1
	v_or_b32_sdwa v72, v69, v67 dst_sel:DWORD dst_unused:UNUSED_PAD src0_sel:DWORD src1_sel:WORD_1
	ds_write_b128 v130, v[70:73] offset:144
.LBB0_990:
	s_or_b64 exec, exec, s[58:59]
	ds_read2_b64 v[74:77], v1 offset0:97 offset1:193
	ds_read2_b64 v[66:69], v89 offset0:33 offset1:129
	ds_read2_b64 v[70:73], v142 offset0:97 offset1:193
	v_lshlrev_b32_e32 v106, 16, v27
	v_lshlrev_b32_e32 v80, 16, v19
	v_lshlrev_b32_e32 v144, 16, v31
	v_mov_b32_e32 v81, v106
	v_lshlrev_b32_e32 v84, 16, v15
	s_waitcnt lgkmcnt(0)
	v_pk_fma_f32 v[80:81], v[74:75], v[80:81], v[72:73] op_sel_hi:[0,1,0]
	v_mov_b32_e32 v85, v144
	v_lshlrev_b32_e32 v107, 16, v35
	v_pk_fma_f32 v[80:81], v[76:77], v[84:85], v[80:81] op_sel_hi:[0,1,1]
	v_lshlrev_b32_e32 v145, 16, v39
	v_pk_fma_f32 v[80:81], v[66:67], v[106:107], v[80:81] op_sel_hi:[0,1,1]
	v_pk_fma_f32 v[84:85], v[74:75], v[84:85], v[72:73] op_sel_hi:[0,1,0]
	v_lshlrev_b32_e32 v83, 16, v43
	v_mov_b32_e32 v82, v107
	v_pk_fma_f32 v[80:81], v[68:69], v[144:145], v[80:81] op_sel_hi:[0,1,1]
	v_pk_fma_f32 v[84:85], v[76:77], v[106:107], v[84:85] op_sel_hi:[0,1,1]
	v_pk_fma_f32 v[80:81], v[70:71], v[82:83], v[80:81] op_sel_hi:[0,1,1]
	v_pk_fma_f32 v[84:85], v[66:67], v[144:145], v[84:85] op_sel_hi:[0,1,1]
	v_lshlrev_b32_e32 v79, 16, v47
	v_mov_b32_e32 v78, v145
	v_mul_f32_e32 v143, 0xbfb8aa3b, v80
	v_pk_fma_f32 v[84:85], v[68:69], v[82:83], v[84:85] op_sel_hi:[0,1,1]
	v_exp_f32_e32 v154, v143
	v_mul_f32_e32 v143, 0xbfb8aa3b, v81
	v_pk_fma_f32 v[84:85], v[70:71], v[78:79], v[84:85] op_sel_hi:[0,1,1]
	v_exp_f32_e32 v155, v143
	v_mul_f32_e32 v106, 0xbfb8aa3b, v84
	v_mul_f32_e32 v107, 0xbfb8aa3b, v85
	v_exp_f32_e32 v106, v106
	v_exp_f32_e32 v107, v107
	v_pk_add_f32 v[154:155], v[154:155], 1.0 op_sel_hi:[1,0]
	v_and_b32_e32 v150, 0xffff0000, v27
	v_and_b32_e32 v146, 0xffff0000, v19
	v_pk_add_f32 v[144:145], v[106:107], 1.0 op_sel_hi:[1,0]
	v_rcp_f32_e32 v107, v155
	v_and_b32_e32 v152, 0xffff0000, v31
	v_and_b32_e32 v148, 0xffff0000, v15
	v_mul_f32_e32 v106, v81, v107
	v_rcp_f32_e32 v107, v154
	s_nop 0
	v_mul_f32_e32 v107, v80, v107
	v_rcp_f32_e32 v81, v145
	s_nop 0
	v_mul_f32_e32 v143, v85, v81
	v_rcp_f32_e32 v81, v144
	v_mov_b32_e32 v149, v152
	v_mul_f32_e32 v144, v84, v81
	v_mov_b32_e32 v147, v150
	v_and_b32_e32 v84, 0xffff0000, v35
	v_pk_fma_f32 v[146:147], v[74:75], v[146:147], v[72:73] op_sel:[1,0,1]
	v_mov_b32_e32 v151, v84
	v_and_b32_e32 v80, 0xffff0000, v39
	v_pk_fma_f32 v[146:147], v[76:77], v[148:149], v[146:147] op_sel:[1,0,0]
	v_mov_b32_e32 v153, v80
	v_pk_fma_f32 v[146:147], v[66:67], v[150:151], v[146:147] op_sel:[1,0,0]
	v_and_b32_e32 v85, 0xffff0000, v43
	v_pk_fma_f32 v[146:147], v[68:69], v[152:153], v[146:147] op_sel:[1,0,0]
	v_pk_fma_f32 v[148:149], v[74:75], v[148:149], v[72:73] op_sel:[1,0,1]
	v_pk_fma_f32 v[146:147], v[70:71], v[84:85], v[146:147] op_sel:[1,0,0]
	v_pk_fma_f32 v[148:149], v[76:77], v[150:151], v[148:149] op_sel:[1,0,0]
	v_mul_f32_e32 v145, 0xbfb8aa3b, v146
	v_exp_f32_e32 v154, v145
	v_mul_f32_e32 v145, 0xbfb8aa3b, v147
	v_exp_f32_e32 v155, v145
	v_pk_fma_f32 v[148:149], v[66:67], v[152:153], v[148:149] op_sel:[1,0,0]
	v_and_b32_e32 v81, 0xffff0000, v47
	v_pk_fma_f32 v[148:149], v[68:69], v[84:85], v[148:149] op_sel:[1,0,0]
	v_pk_add_f32 v[154:155], v[154:155], 1.0 op_sel_hi:[1,0]
	v_pk_fma_f32 v[148:149], v[70:71], v[80:81], v[148:149] op_sel:[1,0,0]
	s_nop 0
	v_mul_f32_e32 v145, 0xbfb8aa3b, v148
	v_exp_f32_e32 v150, v145
	v_mul_f32_e32 v145, 0xbfb8aa3b, v149
	v_exp_f32_e32 v151, v145
	v_rcp_f32_e32 v152, v155
	v_pk_add_f32 v[150:151], v[150:151], 1.0 op_sel_hi:[1,0]
	v_mul_f32_e32 v145, v147, v152
	v_rcp_f32_e32 v152, v154
	s_nop 0
	v_mul_f32_e32 v146, v146, v152
	v_rcp_f32_e32 v152, v151
	s_nop 0
	v_mul_f32_e32 v147, v149, v152
	v_rcp_f32_e32 v151, v150
	s_nop 0
	v_mul_f32_e32 v148, v148, v151
	v_lshlrev_b32_e32 v150, 16, v51
	v_lshlrev_b32_e32 v151, 16, v59
	v_pk_fma_f32 v[154:155], v[74:75], v[82:83], v[72:73] op_sel_hi:[0,1,0]
	v_lshlrev_b32_e32 v152, 16, v55
	v_lshlrev_b32_e32 v153, 16, v63
	v_pk_fma_f32 v[154:155], v[76:77], v[78:79], v[154:155] op_sel_hi:[0,1,1]
	v_pk_mov_b32 v[82:83], v[82:83], v[150:151] op_sel:[1,0]
	v_pk_mov_b32 v[156:157], v[78:79], v[152:153] op_sel:[1,0]
	v_pk_fma_f32 v[154:155], v[66:67], v[82:83], v[154:155] op_sel_hi:[0,1,1]
	v_pk_fma_f32 v[78:79], v[74:75], v[78:79], v[72:73] op_sel_hi:[0,1,0]
	v_pk_fma_f32 v[154:155], v[68:69], v[156:157], v[154:155] op_sel_hi:[0,1,1]
	v_pk_fma_f32 v[78:79], v[76:77], v[82:83], v[78:79] op_sel_hi:[0,1,1]
	v_pk_fma_f32 v[154:155], v[70:71], v[150:151], v[154:155] op_sel_hi:[0,1,1]
	v_pk_fma_f32 v[78:79], v[66:67], v[156:157], v[78:79] op_sel_hi:[0,1,1]
	v_mul_f32_e32 v149, 0xbfb8aa3b, v154
	v_pk_fma_f32 v[78:79], v[68:69], v[150:151], v[78:79] op_sel_hi:[0,1,1]
	v_exp_f32_e32 v158, v149
	v_mul_f32_e32 v149, 0xbfb8aa3b, v155
	v_pk_fma_f32 v[150:151], v[70:71], v[152:153], v[78:79] op_sel_hi:[0,1,1]
	v_exp_f32_e32 v159, v149
	v_mul_f32_e32 v78, 0xbfb8aa3b, v150
	v_mul_f32_e32 v79, 0xbfb8aa3b, v151
	v_exp_f32_e32 v78, v78
	v_exp_f32_e32 v79, v79
	v_pk_add_f32 v[158:159], v[158:159], 1.0 op_sel_hi:[1,0]
	v_pk_add_f32 v[152:153], v[78:79], 1.0 op_sel_hi:[1,0]
	v_rcp_f32_e32 v79, v159
	s_nop 0
	v_mul_f32_e32 v78, v155, v79
	v_rcp_f32_e32 v82, v158
	s_nop 0
	v_mul_f32_e32 v79, v154, v82
	v_rcp_f32_e32 v83, v153
	s_nop 0
	v_mul_f32_e32 v82, v151, v83
	v_rcp_f32_e32 v149, v152
	s_nop 0
	v_mul_f32_e32 v83, v150, v149
	v_and_b32_e32 v151, 0xffff0000, v59
	v_and_b32_e32 v150, 0xffff0000, v51
	v_pk_fma_f32 v[154:155], v[74:75], v[84:85], v[72:73] op_sel:[1,0,1]
	v_and_b32_e32 v153, 0xffff0000, v63
	v_and_b32_e32 v152, 0xffff0000, v55
	v_pk_fma_f32 v[154:155], v[76:77], v[80:81], v[154:155] op_sel:[1,0,0]
	v_pk_mov_b32 v[84:85], v[84:85], v[150:151] op_sel:[1,0]
	v_pk_mov_b32 v[156:157], v[80:81], v[152:153] op_sel:[1,0]
	v_pk_fma_f32 v[154:155], v[66:67], v[84:85], v[154:155] op_sel:[1,0,0]
	v_pk_fma_f32 v[72:73], v[74:75], v[80:81], v[72:73] op_sel:[1,0,1]
	v_pk_fma_f32 v[154:155], v[68:69], v[156:157], v[154:155] op_sel:[1,0,0]
	v_pk_fma_f32 v[72:73], v[76:77], v[84:85], v[72:73] op_sel:[1,0,0]
	v_pk_fma_f32 v[154:155], v[70:71], v[150:151], v[154:155] op_sel:[1,0,0]
	v_pk_fma_f32 v[66:67], v[66:67], v[156:157], v[72:73] op_sel:[1,0,0]
	v_mul_f32_e32 v149, 0xbfb8aa3b, v154
	v_pk_fma_f32 v[66:67], v[68:69], v[150:151], v[66:67] op_sel:[1,0,0]
	v_exp_f32_e32 v158, v149
	v_mul_f32_e32 v149, 0xbfb8aa3b, v155
	v_pk_fma_f32 v[70:71], v[70:71], v[152:153], v[66:67] op_sel:[1,0,0]
	v_exp_f32_e32 v159, v149
	v_mul_f32_e32 v66, 0xbfb8aa3b, v70
	v_mul_f32_e32 v67, 0xbfb8aa3b, v71
	v_exp_f32_e32 v66, v66
	v_exp_f32_e32 v67, v67
	v_pk_add_f32 v[158:159], v[158:159], 1.0 op_sel_hi:[1,0]
	v_pk_add_f32 v[72:73], v[66:67], 1.0 op_sel_hi:[1,0]
	v_rcp_f32_e32 v67, v159
	s_nop 0
	v_mul_f32_e32 v66, v155, v67
	v_rcp_f32_e32 v68, v158
	s_nop 0
	v_mul_f32_e32 v67, v154, v68
	v_rcp_f32_e32 v69, v73
	s_nop 0
	v_mul_f32_e32 v68, v71, v69
	v_rcp_f32_e32 v71, v72
	s_nop 0
	v_mul_f32_e32 v69, v70, v71
	s_and_saveexec_b64 s[58:59], s[8:9]
	s_cbranch_execz .LBB0_992
	v_cvt_pk_bf16_f32 v70, v107, v146
	v_cvt_pk_bf16_f32 v71, v144, v148
	ds_write2_b32 v140, v70, v71 offset0:1 offset1:37
	v_cvt_pk_bf16_f32 v70, v106, v145
	v_cvt_pk_bf16_f32 v71, v143, v147
	ds_write2_b32 v140, v70, v71 offset0:73 offset1:109
	v_cvt_pk_bf16_f32 v70, v79, v67
	v_cvt_pk_bf16_f32 v71, v83, v69
	ds_write2_b32 v140, v70, v71 offset0:145 offset1:181
	v_cvt_pk_bf16_f32 v70, v78, v66
	v_cvt_pk_bf16_f32 v71, v82, v68
	ds_write2_b32 v140, v70, v71 offset0:217 offset1:253
.LBB0_992:
	s_or_b64 exec, exec, s[58:59]
	s_and_saveexec_b64 s[58:59], s[10:11]
	s_cbranch_execz .LBB0_994
	v_and_b32_sdwa v71, v107, v116 dst_sel:DWORD dst_unused:UNUSED_PAD src0_sel:WORD_1 src1_sel:DWORD
	v_add3_u32 v72, v107, v71, s33
	v_and_b32_sdwa v70, v106, v116 dst_sel:DWORD dst_unused:UNUSED_PAD src0_sel:WORD_1 src1_sel:DWORD
	v_cvt_pk_bf16_f32 v71, v143, v143
	v_cvt_pk_bf16_f32 v73, v144, v144
	v_add3_u32 v70, v106, v70, s33
	v_and_b32_e32 v71, 0xffff0000, v71
	v_and_b32_e32 v73, 0xffff0000, v73
	v_or_b32_sdwa v71, v71, v70 dst_sel:DWORD dst_unused:UNUSED_PAD src0_sel:DWORD src1_sel:WORD_1
	v_or_b32_sdwa v70, v73, v72 dst_sel:DWORD dst_unused:UNUSED_PAD src0_sel:DWORD src1_sel:WORD_1
	v_and_b32_sdwa v73, v79, v116 dst_sel:DWORD dst_unused:UNUSED_PAD src0_sel:WORD_1 src1_sel:DWORD
	v_add3_u32 v74, v79, v73, s33
	v_and_b32_sdwa v72, v78, v116 dst_sel:DWORD dst_unused:UNUSED_PAD src0_sel:WORD_1 src1_sel:DWORD
	v_cvt_pk_bf16_f32 v73, v82, v82
	v_cvt_pk_bf16_f32 v75, v83, v83
	v_add3_u32 v72, v78, v72, s33
	v_and_b32_e32 v73, 0xffff0000, v73
	v_and_b32_e32 v75, 0xffff0000, v75
	v_or_b32_sdwa v73, v73, v72 dst_sel:DWORD dst_unused:UNUSED_PAD src0_sel:DWORD src1_sel:WORD_1
	v_or_b32_sdwa v72, v75, v74 dst_sel:DWORD dst_unused:UNUSED_PAD src0_sel:DWORD src1_sel:WORD_1
	ds_write_b128 v131, v[70:73]
	v_and_b32_sdwa v71, v146, v116 dst_sel:DWORD dst_unused:UNUSED_PAD src0_sel:WORD_1 src1_sel:DWORD
	v_add3_u32 v72, v146, v71, s33
	v_and_b32_sdwa v70, v145, v116 dst_sel:DWORD dst_unused:UNUSED_PAD src0_sel:WORD_1 src1_sel:DWORD
	v_cvt_pk_bf16_f32 v71, v147, v147
	v_cvt_pk_bf16_f32 v73, v148, v148
	v_add3_u32 v70, v145, v70, s33
	v_and_b32_e32 v71, 0xffff0000, v71
	v_and_b32_e32 v73, 0xffff0000, v73
	v_or_b32_sdwa v71, v71, v70 dst_sel:DWORD dst_unused:UNUSED_PAD src0_sel:DWORD src1_sel:WORD_1
	v_or_b32_sdwa v70, v73, v72 dst_sel:DWORD dst_unused:UNUSED_PAD src0_sel:DWORD src1_sel:WORD_1
	v_and_b32_sdwa v72, v66, v116 dst_sel:DWORD dst_unused:UNUSED_PAD src0_sel:WORD_1 src1_sel:DWORD
	v_and_b32_sdwa v73, v67, v116 dst_sel:DWORD dst_unused:UNUSED_PAD src0_sel:WORD_1 src1_sel:DWORD
	v_add3_u32 v67, v67, v73, s33
	v_add3_u32 v66, v66, v72, s33
	v_and_b32_sdwa v72, v68, v116 dst_sel:DWORD dst_unused:UNUSED_PAD src0_sel:WORD_1 src1_sel:DWORD
	v_and_b32_sdwa v73, v69, v116 dst_sel:DWORD dst_unused:UNUSED_PAD src0_sel:WORD_1 src1_sel:DWORD
	v_add3_u32 v68, v68, v72, s33
	v_add3_u32 v69, v69, v73, s33
	v_and_b32_e32 v68, 0xffff0000, v68
	v_and_b32_e32 v69, 0xffff0000, v69
	v_or_b32_sdwa v73, v68, v66 dst_sel:DWORD dst_unused:UNUSED_PAD src0_sel:DWORD src1_sel:WORD_1
	v_or_b32_sdwa v72, v69, v67 dst_sel:DWORD dst_unused:UNUSED_PAD src0_sel:DWORD src1_sel:WORD_1
	ds_write_b128 v131, v[70:73] offset:144
.LBB0_994:
	s_or_b64 exec, exec, s[58:59]
	ds_read2_b64 v[74:77], v1 offset0:98 offset1:194
	ds_read2_b64 v[66:69], v89 offset0:34 offset1:130
	ds_read2_b64 v[70:73], v142 offset0:98 offset1:194
	v_lshlrev_b32_e32 v106, 16, v28
	v_lshlrev_b32_e32 v80, 16, v20
	v_lshlrev_b32_e32 v144, 16, v32
	v_mov_b32_e32 v81, v106
	v_lshlrev_b32_e32 v84, 16, v16
	s_waitcnt lgkmcnt(0)
	v_pk_fma_f32 v[80:81], v[74:75], v[80:81], v[72:73] op_sel_hi:[0,1,0]
	v_mov_b32_e32 v85, v144
	v_lshlrev_b32_e32 v107, 16, v36
	v_pk_fma_f32 v[80:81], v[76:77], v[84:85], v[80:81] op_sel_hi:[0,1,1]
	v_lshlrev_b32_e32 v145, 16, v40
	v_pk_fma_f32 v[80:81], v[66:67], v[106:107], v[80:81] op_sel_hi:[0,1,1]
	v_pk_fma_f32 v[84:85], v[74:75], v[84:85], v[72:73] op_sel_hi:[0,1,0]
	v_lshlrev_b32_e32 v83, 16, v44
	v_mov_b32_e32 v82, v107
	v_pk_fma_f32 v[80:81], v[68:69], v[144:145], v[80:81] op_sel_hi:[0,1,1]
	v_pk_fma_f32 v[84:85], v[76:77], v[106:107], v[84:85] op_sel_hi:[0,1,1]
	v_pk_fma_f32 v[80:81], v[70:71], v[82:83], v[80:81] op_sel_hi:[0,1,1]
	v_pk_fma_f32 v[84:85], v[66:67], v[144:145], v[84:85] op_sel_hi:[0,1,1]
	v_lshlrev_b32_e32 v79, 16, v48
	v_mov_b32_e32 v78, v145
	v_mul_f32_e32 v143, 0xbfb8aa3b, v80
	v_pk_fma_f32 v[84:85], v[68:69], v[82:83], v[84:85] op_sel_hi:[0,1,1]
	v_exp_f32_e32 v154, v143
	v_mul_f32_e32 v143, 0xbfb8aa3b, v81
	v_pk_fma_f32 v[84:85], v[70:71], v[78:79], v[84:85] op_sel_hi:[0,1,1]
	v_exp_f32_e32 v155, v143
	v_mul_f32_e32 v106, 0xbfb8aa3b, v84
	v_mul_f32_e32 v107, 0xbfb8aa3b, v85
	v_exp_f32_e32 v106, v106
	v_exp_f32_e32 v107, v107
	v_pk_add_f32 v[154:155], v[154:155], 1.0 op_sel_hi:[1,0]
	v_and_b32_e32 v150, 0xffff0000, v28
	v_and_b32_e32 v146, 0xffff0000, v20
	v_pk_add_f32 v[144:145], v[106:107], 1.0 op_sel_hi:[1,0]
	v_rcp_f32_e32 v107, v155
	v_and_b32_e32 v152, 0xffff0000, v32
	v_and_b32_e32 v148, 0xffff0000, v16
	v_mul_f32_e32 v106, v81, v107
	v_rcp_f32_e32 v107, v154
	s_nop 0
	v_mul_f32_e32 v107, v80, v107
	v_rcp_f32_e32 v81, v145
	s_nop 0
	v_mul_f32_e32 v143, v85, v81
	v_rcp_f32_e32 v81, v144
	v_mov_b32_e32 v149, v152
	v_mul_f32_e32 v144, v84, v81
	v_mov_b32_e32 v147, v150
	v_and_b32_e32 v84, 0xffff0000, v36
	v_pk_fma_f32 v[146:147], v[74:75], v[146:147], v[72:73] op_sel:[1,0,1]
	v_mov_b32_e32 v151, v84
	v_and_b32_e32 v80, 0xffff0000, v40
	v_pk_fma_f32 v[146:147], v[76:77], v[148:149], v[146:147] op_sel:[1,0,0]
	v_mov_b32_e32 v153, v80
	v_pk_fma_f32 v[146:147], v[66:67], v[150:151], v[146:147] op_sel:[1,0,0]
	v_and_b32_e32 v85, 0xffff0000, v44
	v_pk_fma_f32 v[146:147], v[68:69], v[152:153], v[146:147] op_sel:[1,0,0]
	v_pk_fma_f32 v[148:149], v[74:75], v[148:149], v[72:73] op_sel:[1,0,1]
	v_pk_fma_f32 v[146:147], v[70:71], v[84:85], v[146:147] op_sel:[1,0,0]
	v_pk_fma_f32 v[148:149], v[76:77], v[150:151], v[148:149] op_sel:[1,0,0]
	v_mul_f32_e32 v145, 0xbfb8aa3b, v146
	v_exp_f32_e32 v154, v145
	v_mul_f32_e32 v145, 0xbfb8aa3b, v147
	v_exp_f32_e32 v155, v145
	v_pk_fma_f32 v[148:149], v[66:67], v[152:153], v[148:149] op_sel:[1,0,0]
	v_and_b32_e32 v81, 0xffff0000, v48
	v_pk_fma_f32 v[148:149], v[68:69], v[84:85], v[148:149] op_sel:[1,0,0]
	v_pk_add_f32 v[154:155], v[154:155], 1.0 op_sel_hi:[1,0]
	v_pk_fma_f32 v[148:149], v[70:71], v[80:81], v[148:149] op_sel:[1,0,0]
	s_nop 0
	v_mul_f32_e32 v145, 0xbfb8aa3b, v148
	v_exp_f32_e32 v150, v145
	v_mul_f32_e32 v145, 0xbfb8aa3b, v149
	v_exp_f32_e32 v151, v145
	v_rcp_f32_e32 v152, v155
	v_pk_add_f32 v[150:151], v[150:151], 1.0 op_sel_hi:[1,0]
	v_mul_f32_e32 v145, v147, v152
	v_rcp_f32_e32 v152, v154
	s_nop 0
	v_mul_f32_e32 v146, v146, v152
	v_rcp_f32_e32 v152, v151
	s_nop 0
	v_mul_f32_e32 v147, v149, v152
	v_rcp_f32_e32 v151, v150
	s_nop 0
	v_mul_f32_e32 v148, v148, v151
	v_lshlrev_b32_e32 v150, 16, v52
	v_lshlrev_b32_e32 v151, 16, v60
	v_pk_fma_f32 v[154:155], v[74:75], v[82:83], v[72:73] op_sel_hi:[0,1,0]
	v_lshlrev_b32_e32 v152, 16, v56
	v_lshlrev_b32_e32 v153, 16, v64
	v_pk_fma_f32 v[154:155], v[76:77], v[78:79], v[154:155] op_sel_hi:[0,1,1]
	v_pk_mov_b32 v[82:83], v[82:83], v[150:151] op_sel:[1,0]
	v_pk_mov_b32 v[156:157], v[78:79], v[152:153] op_sel:[1,0]
	v_pk_fma_f32 v[154:155], v[66:67], v[82:83], v[154:155] op_sel_hi:[0,1,1]
	v_pk_fma_f32 v[78:79], v[74:75], v[78:79], v[72:73] op_sel_hi:[0,1,0]
	v_pk_fma_f32 v[154:155], v[68:69], v[156:157], v[154:155] op_sel_hi:[0,1,1]
	v_pk_fma_f32 v[78:79], v[76:77], v[82:83], v[78:79] op_sel_hi:[0,1,1]
	v_pk_fma_f32 v[154:155], v[70:71], v[150:151], v[154:155] op_sel_hi:[0,1,1]
	v_pk_fma_f32 v[78:79], v[66:67], v[156:157], v[78:79] op_sel_hi:[0,1,1]
	v_mul_f32_e32 v149, 0xbfb8aa3b, v154
	v_pk_fma_f32 v[78:79], v[68:69], v[150:151], v[78:79] op_sel_hi:[0,1,1]
	v_exp_f32_e32 v158, v149
	v_mul_f32_e32 v149, 0xbfb8aa3b, v155
	v_pk_fma_f32 v[150:151], v[70:71], v[152:153], v[78:79] op_sel_hi:[0,1,1]
	v_exp_f32_e32 v159, v149
	v_mul_f32_e32 v78, 0xbfb8aa3b, v150
	v_mul_f32_e32 v79, 0xbfb8aa3b, v151
	v_exp_f32_e32 v78, v78
	v_exp_f32_e32 v79, v79
	v_pk_add_f32 v[158:159], v[158:159], 1.0 op_sel_hi:[1,0]
	v_pk_add_f32 v[152:153], v[78:79], 1.0 op_sel_hi:[1,0]
	v_rcp_f32_e32 v79, v159
	s_nop 0
	v_mul_f32_e32 v78, v155, v79
	v_rcp_f32_e32 v82, v158
	s_nop 0
	v_mul_f32_e32 v79, v154, v82
	v_rcp_f32_e32 v83, v153
	s_nop 0
	v_mul_f32_e32 v82, v151, v83
	v_rcp_f32_e32 v149, v152
	s_nop 0
	v_mul_f32_e32 v83, v150, v149
	v_and_b32_e32 v151, 0xffff0000, v60
	v_and_b32_e32 v150, 0xffff0000, v52
	v_pk_fma_f32 v[154:155], v[74:75], v[84:85], v[72:73] op_sel:[1,0,1]
	v_and_b32_e32 v153, 0xffff0000, v64
	v_and_b32_e32 v152, 0xffff0000, v56
	v_pk_fma_f32 v[154:155], v[76:77], v[80:81], v[154:155] op_sel:[1,0,0]
	v_pk_mov_b32 v[84:85], v[84:85], v[150:151] op_sel:[1,0]
	v_pk_mov_b32 v[156:157], v[80:81], v[152:153] op_sel:[1,0]
	v_pk_fma_f32 v[154:155], v[66:67], v[84:85], v[154:155] op_sel:[1,0,0]
	v_pk_fma_f32 v[72:73], v[74:75], v[80:81], v[72:73] op_sel:[1,0,1]
	v_pk_fma_f32 v[154:155], v[68:69], v[156:157], v[154:155] op_sel:[1,0,0]
	v_pk_fma_f32 v[72:73], v[76:77], v[84:85], v[72:73] op_sel:[1,0,0]
	v_pk_fma_f32 v[154:155], v[70:71], v[150:151], v[154:155] op_sel:[1,0,0]
	v_pk_fma_f32 v[66:67], v[66:67], v[156:157], v[72:73] op_sel:[1,0,0]
	v_mul_f32_e32 v149, 0xbfb8aa3b, v154
	v_pk_fma_f32 v[66:67], v[68:69], v[150:151], v[66:67] op_sel:[1,0,0]
	v_exp_f32_e32 v158, v149
	v_mul_f32_e32 v149, 0xbfb8aa3b, v155
	v_pk_fma_f32 v[70:71], v[70:71], v[152:153], v[66:67] op_sel:[1,0,0]
	v_exp_f32_e32 v159, v149
	v_mul_f32_e32 v66, 0xbfb8aa3b, v70
	v_mul_f32_e32 v67, 0xbfb8aa3b, v71
	v_exp_f32_e32 v66, v66
	v_exp_f32_e32 v67, v67
	v_pk_add_f32 v[158:159], v[158:159], 1.0 op_sel_hi:[1,0]
	v_pk_add_f32 v[72:73], v[66:67], 1.0 op_sel_hi:[1,0]
	v_rcp_f32_e32 v67, v159
	s_nop 0
	v_mul_f32_e32 v66, v155, v67
	v_rcp_f32_e32 v68, v158
	s_nop 0
	v_mul_f32_e32 v67, v154, v68
	v_rcp_f32_e32 v69, v73
	s_nop 0
	v_mul_f32_e32 v68, v71, v69
	v_rcp_f32_e32 v71, v72
	s_nop 0
	v_mul_f32_e32 v69, v70, v71
	s_and_saveexec_b64 s[58:59], s[8:9]
	s_cbranch_execz .LBB0_996
	v_cvt_pk_bf16_f32 v70, v107, v146
	v_cvt_pk_bf16_f32 v71, v144, v148
	ds_write2_b32 v140, v70, v71 offset0:2 offset1:38
	v_cvt_pk_bf16_f32 v70, v106, v145
	v_cvt_pk_bf16_f32 v71, v143, v147
	ds_write2_b32 v140, v70, v71 offset0:74 offset1:110
	v_cvt_pk_bf16_f32 v70, v79, v67
	v_cvt_pk_bf16_f32 v71, v83, v69
	ds_write2_b32 v140, v70, v71 offset0:146 offset1:182
	v_cvt_pk_bf16_f32 v70, v78, v66
	v_cvt_pk_bf16_f32 v71, v82, v68
	ds_write2_b32 v140, v70, v71 offset0:218 offset1:254
.LBB0_996:
	s_or_b64 exec, exec, s[58:59]
	s_and_saveexec_b64 s[58:59], s[10:11]
	s_cbranch_execz .LBB0_998
	v_and_b32_sdwa v71, v107, v116 dst_sel:DWORD dst_unused:UNUSED_PAD src0_sel:WORD_1 src1_sel:DWORD
	v_add3_u32 v72, v107, v71, s33
	v_and_b32_sdwa v70, v106, v116 dst_sel:DWORD dst_unused:UNUSED_PAD src0_sel:WORD_1 src1_sel:DWORD
	v_cvt_pk_bf16_f32 v71, v143, v143
	v_cvt_pk_bf16_f32 v73, v144, v144
	v_add3_u32 v70, v106, v70, s33
	v_and_b32_e32 v71, 0xffff0000, v71
	v_and_b32_e32 v73, 0xffff0000, v73
	v_or_b32_sdwa v71, v71, v70 dst_sel:DWORD dst_unused:UNUSED_PAD src0_sel:DWORD src1_sel:WORD_1
	v_or_b32_sdwa v70, v73, v72 dst_sel:DWORD dst_unused:UNUSED_PAD src0_sel:DWORD src1_sel:WORD_1
	v_and_b32_sdwa v73, v79, v116 dst_sel:DWORD dst_unused:UNUSED_PAD src0_sel:WORD_1 src1_sel:DWORD
	v_add3_u32 v74, v79, v73, s33
	v_and_b32_sdwa v72, v78, v116 dst_sel:DWORD dst_unused:UNUSED_PAD src0_sel:WORD_1 src1_sel:DWORD
	v_cvt_pk_bf16_f32 v73, v82, v82
	v_cvt_pk_bf16_f32 v75, v83, v83
	v_add3_u32 v72, v78, v72, s33
	v_and_b32_e32 v73, 0xffff0000, v73
	v_and_b32_e32 v75, 0xffff0000, v75
	v_or_b32_sdwa v73, v73, v72 dst_sel:DWORD dst_unused:UNUSED_PAD src0_sel:DWORD src1_sel:WORD_1
	v_or_b32_sdwa v72, v75, v74 dst_sel:DWORD dst_unused:UNUSED_PAD src0_sel:DWORD src1_sel:WORD_1
	ds_write_b128 v132, v[70:73]
	v_and_b32_sdwa v71, v146, v116 dst_sel:DWORD dst_unused:UNUSED_PAD src0_sel:WORD_1 src1_sel:DWORD
	v_add3_u32 v72, v146, v71, s33
	v_and_b32_sdwa v70, v145, v116 dst_sel:DWORD dst_unused:UNUSED_PAD src0_sel:WORD_1 src1_sel:DWORD
	v_cvt_pk_bf16_f32 v71, v147, v147
	v_cvt_pk_bf16_f32 v73, v148, v148
	v_add3_u32 v70, v145, v70, s33
	v_and_b32_e32 v71, 0xffff0000, v71
	v_and_b32_e32 v73, 0xffff0000, v73
	v_or_b32_sdwa v71, v71, v70 dst_sel:DWORD dst_unused:UNUSED_PAD src0_sel:DWORD src1_sel:WORD_1
	v_or_b32_sdwa v70, v73, v72 dst_sel:DWORD dst_unused:UNUSED_PAD src0_sel:DWORD src1_sel:WORD_1
	v_and_b32_sdwa v72, v66, v116 dst_sel:DWORD dst_unused:UNUSED_PAD src0_sel:WORD_1 src1_sel:DWORD
	v_and_b32_sdwa v73, v67, v116 dst_sel:DWORD dst_unused:UNUSED_PAD src0_sel:WORD_1 src1_sel:DWORD
	v_add3_u32 v67, v67, v73, s33
	v_add3_u32 v66, v66, v72, s33
	v_and_b32_sdwa v72, v68, v116 dst_sel:DWORD dst_unused:UNUSED_PAD src0_sel:WORD_1 src1_sel:DWORD
	v_and_b32_sdwa v73, v69, v116 dst_sel:DWORD dst_unused:UNUSED_PAD src0_sel:WORD_1 src1_sel:DWORD
	v_add3_u32 v68, v68, v72, s33
	v_add3_u32 v69, v69, v73, s33
	v_and_b32_e32 v68, 0xffff0000, v68
	v_and_b32_e32 v69, 0xffff0000, v69
	v_or_b32_sdwa v73, v68, v66 dst_sel:DWORD dst_unused:UNUSED_PAD src0_sel:DWORD src1_sel:WORD_1
	v_or_b32_sdwa v72, v69, v67 dst_sel:DWORD dst_unused:UNUSED_PAD src0_sel:DWORD src1_sel:WORD_1
	ds_write_b128 v132, v[70:73] offset:144
.LBB0_998:
	s_or_b64 exec, exec, s[58:59]
	ds_read2_b64 v[74:77], v1 offset0:99 offset1:195
	ds_read2_b64 v[66:69], v89 offset0:35 offset1:131
	ds_read2_b64 v[70:73], v142 offset0:99 offset1:195
	v_lshlrev_b32_e32 v106, 16, v29
	v_lshlrev_b32_e32 v80, 16, v21
	v_lshlrev_b32_e32 v150, 16, v33
	v_mov_b32_e32 v81, v106
	v_lshlrev_b32_e32 v84, 16, v17
	s_waitcnt lgkmcnt(0)
	v_pk_fma_f32 v[80:81], v[74:75], v[80:81], v[72:73] op_sel_hi:[0,1,0]
	v_mov_b32_e32 v85, v150
	v_lshlrev_b32_e32 v107, 16, v37
	v_pk_fma_f32 v[80:81], v[76:77], v[84:85], v[80:81] op_sel_hi:[0,1,1]
	v_lshlrev_b32_e32 v151, 16, v41
	v_pk_fma_f32 v[80:81], v[66:67], v[106:107], v[80:81] op_sel_hi:[0,1,1]
	v_lshlrev_b32_e32 v83, 16, v45
	v_mov_b32_e32 v82, v107
	v_pk_fma_f32 v[80:81], v[68:69], v[150:151], v[80:81] op_sel_hi:[0,1,1]
	v_pk_fma_f32 v[80:81], v[70:71], v[82:83], v[80:81] op_sel_hi:[0,1,1]
	v_mul_f32_e32 v1, 0xbfb8aa3b, v80
	v_pk_fma_f32 v[84:85], v[74:75], v[84:85], v[72:73] op_sel_hi:[0,1,0]
	v_exp_f32_e32 v142, v1
	v_mul_f32_e32 v1, 0xbfb8aa3b, v81
	v_pk_fma_f32 v[84:85], v[76:77], v[106:107], v[84:85] op_sel_hi:[0,1,1]
	v_exp_f32_e32 v143, v1
	v_pk_fma_f32 v[84:85], v[66:67], v[150:151], v[84:85] op_sel_hi:[0,1,1]
	v_lshlrev_b32_e32 v79, 16, v49
	v_mov_b32_e32 v78, v151
	v_pk_fma_f32 v[84:85], v[68:69], v[82:83], v[84:85] op_sel_hi:[0,1,1]
	v_pk_fma_f32 v[84:85], v[70:71], v[78:79], v[84:85] op_sel_hi:[0,1,1]
	v_mul_f32_e32 v1, 0xbfb8aa3b, v84
	v_pk_add_f32 v[142:143], v[142:143], 1.0 op_sel_hi:[1,0]
	v_exp_f32_e32 v106, v1
	v_mul_f32_e32 v1, 0xbfb8aa3b, v85
	v_exp_f32_e32 v107, v1
	v_rcp_f32_e32 v89, v143
	v_pk_add_f32 v[150:151], v[106:107], 1.0 op_sel_hi:[1,0]
	v_and_b32_e32 v148, 0xffff0000, v29
	v_and_b32_e32 v144, 0xffff0000, v21
	v_mul_f32_e32 v1, v81, v89
	v_rcp_f32_e32 v89, v142
	v_and_b32_e32 v152, 0xffff0000, v33
	v_mov_b32_e32 v145, v148
	v_and_b32_e32 v146, 0xffff0000, v17
	v_mul_f32_e32 v89, v80, v89
	v_rcp_f32_e32 v81, v151
	v_mov_b32_e32 v147, v152
	v_mul_f32_e32 v106, v85, v81
	v_rcp_f32_e32 v81, v150
	s_nop 0
	v_mul_f32_e32 v107, v84, v81
	v_and_b32_e32 v84, 0xffff0000, v37
	v_pk_fma_f32 v[142:143], v[74:75], v[144:145], v[72:73] op_sel:[1,0,1]
	v_mov_b32_e32 v149, v84
	v_and_b32_e32 v80, 0xffff0000, v41
	v_pk_fma_f32 v[142:143], v[76:77], v[146:147], v[142:143] op_sel:[1,0,0]
	v_mov_b32_e32 v153, v80
	v_pk_fma_f32 v[142:143], v[66:67], v[148:149], v[142:143] op_sel:[1,0,0]
	v_and_b32_e32 v85, 0xffff0000, v45
	v_pk_fma_f32 v[142:143], v[68:69], v[152:153], v[142:143] op_sel:[1,0,0]
	v_and_b32_e32 v81, 0xffff0000, v49
	v_pk_fma_f32 v[144:145], v[70:71], v[84:85], v[142:143] op_sel:[1,0,0]
	s_nop 0
	v_mul_f32_e32 v142, 0xbfb8aa3b, v144
	v_mul_f32_e32 v143, 0xbfb8aa3b, v145
	v_exp_f32_e32 v142, v142
	v_exp_f32_e32 v143, v143
	s_nop 0
	v_pk_add_f32 v[150:151], v[142:143], 1.0 op_sel_hi:[1,0]
	v_pk_fma_f32 v[142:143], v[74:75], v[146:147], v[72:73] op_sel:[1,0,1]
	s_nop 0
	v_pk_fma_f32 v[142:143], v[76:77], v[148:149], v[142:143] op_sel:[1,0,0]
	s_nop 0
	v_pk_fma_f32 v[142:143], v[66:67], v[152:153], v[142:143] op_sel:[1,0,0]
	s_nop 0
	v_pk_fma_f32 v[142:143], v[68:69], v[84:85], v[142:143] op_sel:[1,0,0]
	s_nop 0
	v_pk_fma_f32 v[146:147], v[70:71], v[80:81], v[142:143] op_sel:[1,0,0]
	s_nop 0
	v_mul_f32_e32 v142, 0xbfb8aa3b, v146
	v_mul_f32_e32 v143, 0xbfb8aa3b, v147
	v_exp_f32_e32 v142, v142
	v_exp_f32_e32 v143, v143
	s_nop 0
	v_pk_add_f32 v[148:149], v[142:143], 1.0 op_sel_hi:[1,0]
	v_rcp_f32_e32 v143, v151
	s_nop 0
	v_mul_f32_e32 v142, v145, v143
	v_rcp_f32_e32 v145, v150
	s_nop 0
	v_mul_f32_e32 v143, v144, v145
	v_rcp_f32_e32 v145, v149
	s_nop 0
	v_mul_f32_e32 v144, v147, v145
	v_rcp_f32_e32 v147, v148
	s_nop 0
	v_mul_f32_e32 v145, v146, v147
	v_lshlrev_b32_e32 v146, 16, v53
	v_lshlrev_b32_e32 v147, 16, v61
	v_lshlrev_b32_e32 v148, 16, v57
	v_lshlrev_b32_e32 v149, 16, v65
	v_pk_fma_f32 v[150:151], v[74:75], v[82:83], v[72:73] op_sel_hi:[0,1,0]
	v_pk_fma_f32 v[150:151], v[76:77], v[78:79], v[150:151] op_sel_hi:[0,1,1]
	v_pk_mov_b32 v[82:83], v[82:83], v[146:147] op_sel:[1,0]
	v_pk_mov_b32 v[152:153], v[78:79], v[148:149] op_sel:[1,0]
	v_pk_fma_f32 v[78:79], v[74:75], v[78:79], v[72:73] op_sel_hi:[0,1,0]
	v_pk_fma_f32 v[150:151], v[66:67], v[82:83], v[150:151] op_sel_hi:[0,1,1]
	v_pk_fma_f32 v[78:79], v[76:77], v[82:83], v[78:79] op_sel_hi:[0,1,1]
	v_pk_fma_f32 v[150:151], v[68:69], v[152:153], v[150:151] op_sel_hi:[0,1,1]
	v_pk_fma_f32 v[78:79], v[66:67], v[152:153], v[78:79] op_sel_hi:[0,1,1]
	v_pk_fma_f32 v[150:151], v[70:71], v[146:147], v[150:151] op_sel_hi:[0,1,1]
	v_pk_fma_f32 v[78:79], v[68:69], v[146:147], v[78:79] op_sel_hi:[0,1,1]
	v_mul_f32_e32 v154, 0xbfb8aa3b, v150
	v_mul_f32_e32 v155, 0xbfb8aa3b, v151
	v_pk_fma_f32 v[146:147], v[70:71], v[148:149], v[78:79] op_sel_hi:[0,1,1]
	v_exp_f32_e32 v154, v154
	v_exp_f32_e32 v155, v155
	v_mul_f32_e32 v78, 0xbfb8aa3b, v146
	v_mul_f32_e32 v79, 0xbfb8aa3b, v147
	v_exp_f32_e32 v78, v78
	v_exp_f32_e32 v79, v79
	v_pk_add_f32 v[154:155], v[154:155], 1.0 op_sel_hi:[1,0]
	v_pk_add_f32 v[148:149], v[78:79], 1.0 op_sel_hi:[1,0]
	v_rcp_f32_e32 v79, v155
	s_nop 0
	v_mul_f32_e32 v78, v151, v79
	v_rcp_f32_e32 v82, v154
	s_nop 0
	v_mul_f32_e32 v79, v150, v82
	v_rcp_f32_e32 v83, v149
	s_nop 0
	v_mul_f32_e32 v82, v147, v83
	v_rcp_f32_e32 v147, v148
	s_nop 0
	v_mul_f32_e32 v83, v146, v147
	v_and_b32_e32 v147, 0xffff0000, v61
	v_and_b32_e32 v146, 0xffff0000, v53
	v_pk_fma_f32 v[150:151], v[74:75], v[84:85], v[72:73] op_sel:[1,0,1]
	v_and_b32_e32 v149, 0xffff0000, v65
	v_and_b32_e32 v148, 0xffff0000, v57
	v_pk_fma_f32 v[150:151], v[76:77], v[80:81], v[150:151] op_sel:[1,0,0]
	v_pk_mov_b32 v[84:85], v[84:85], v[146:147] op_sel:[1,0]
	v_pk_fma_f32 v[72:73], v[74:75], v[80:81], v[72:73] op_sel:[1,0,1]
	v_pk_fma_f32 v[150:151], v[66:67], v[84:85], v[150:151] op_sel:[1,0,0]
	v_pk_mov_b32 v[152:153], v[80:81], v[148:149] op_sel:[1,0]
	v_pk_fma_f32 v[72:73], v[76:77], v[84:85], v[72:73] op_sel:[1,0,0]
	v_pk_fma_f32 v[150:151], v[68:69], v[152:153], v[150:151] op_sel:[1,0,0]
	v_pk_fma_f32 v[66:67], v[66:67], v[152:153], v[72:73] op_sel:[1,0,0]
	v_pk_fma_f32 v[150:151], v[70:71], v[146:147], v[150:151] op_sel:[1,0,0]
	v_pk_fma_f32 v[66:67], v[68:69], v[146:147], v[66:67] op_sel:[1,0,0]
	v_mul_f32_e32 v154, 0xbfb8aa3b, v150
	v_mul_f32_e32 v155, 0xbfb8aa3b, v151
	v_pk_fma_f32 v[70:71], v[70:71], v[148:149], v[66:67] op_sel:[1,0,0]
	v_exp_f32_e32 v154, v154
	v_exp_f32_e32 v155, v155
	v_mul_f32_e32 v66, 0xbfb8aa3b, v70
	v_mul_f32_e32 v67, 0xbfb8aa3b, v71
	v_exp_f32_e32 v66, v66
	v_exp_f32_e32 v67, v67
	v_pk_add_f32 v[154:155], v[154:155], 1.0 op_sel_hi:[1,0]
	v_pk_add_f32 v[72:73], v[66:67], 1.0 op_sel_hi:[1,0]
	v_rcp_f32_e32 v67, v155
	s_nop 0
	v_mul_f32_e32 v66, v151, v67
	v_rcp_f32_e32 v68, v154
	s_nop 0
	v_mul_f32_e32 v67, v150, v68
	v_rcp_f32_e32 v69, v73
	s_nop 0
	v_mul_f32_e32 v68, v71, v69
	v_rcp_f32_e32 v71, v72
	s_nop 0
	v_mul_f32_e32 v69, v70, v71
	s_and_saveexec_b64 s[58:59], s[8:9]
	s_cbranch_execz .LBB0_1000
	v_cvt_pk_bf16_f32 v70, v89, v143
	v_cvt_pk_bf16_f32 v71, v107, v145
	ds_write2_b32 v140, v70, v71 offset0:3 offset1:39
	v_cvt_pk_bf16_f32 v70, v1, v142
	v_cvt_pk_bf16_f32 v71, v106, v144
	ds_write2_b32 v140, v70, v71 offset0:75 offset1:111
	v_cvt_pk_bf16_f32 v70, v79, v67
	v_cvt_pk_bf16_f32 v71, v83, v69
	ds_write2_b32 v140, v70, v71 offset0:147 offset1:183
	v_cvt_pk_bf16_f32 v70, v78, v66
	v_cvt_pk_bf16_f32 v71, v82, v68
	ds_write2_b32 v140, v70, v71 offset0:219 offset1:255
.LBB0_1000:
	s_or_b64 exec, exec, s[58:59]
	s_and_saveexec_b64 s[58:59], s[10:11]
	s_cbranch_execz .LBB0_1002
	v_and_b32_sdwa v70, v1, v116 dst_sel:DWORD dst_unused:UNUSED_PAD src0_sel:WORD_1 src1_sel:DWORD
	v_and_b32_sdwa v71, v89, v116 dst_sel:DWORD dst_unused:UNUSED_PAD src0_sel:WORD_1 src1_sel:DWORD
	v_add3_u32 v72, v89, v71, s33
	v_add3_u32 v1, v1, v70, s33
	v_and_b32_sdwa v71, v107, v116 dst_sel:DWORD dst_unused:UNUSED_PAD src0_sel:WORD_1 src1_sel:DWORD
	v_cvt_pk_bf16_f32 v70, v106, v106
	v_add3_u32 v71, v107, v71, s33
	v_and_b32_e32 v70, 0xffff0000, v70
	v_and_b32_e32 v73, 0xffff0000, v71
	v_or_b32_sdwa v71, v70, v1 dst_sel:DWORD dst_unused:UNUSED_PAD src0_sel:DWORD src1_sel:WORD_1
	v_or_b32_sdwa v70, v73, v72 dst_sel:DWORD dst_unused:UNUSED_PAD src0_sel:DWORD src1_sel:WORD_1
	v_and_b32_sdwa v1, v78, v116 dst_sel:DWORD dst_unused:UNUSED_PAD src0_sel:WORD_1 src1_sel:DWORD
	v_and_b32_sdwa v72, v79, v116 dst_sel:DWORD dst_unused:UNUSED_PAD src0_sel:WORD_1 src1_sel:DWORD
	v_cvt_pk_bf16_f32 v73, v82, v82
	v_cvt_pk_bf16_f32 v74, v83, v83
	v_add3_u32 v72, v79, v72, s33
	v_add3_u32 v1, v78, v1, s33
	v_and_b32_e32 v73, 0xffff0000, v73
	v_and_b32_e32 v74, 0xffff0000, v74
	v_or_b32_sdwa v73, v73, v1 dst_sel:DWORD dst_unused:UNUSED_PAD src0_sel:DWORD src1_sel:WORD_1
	v_or_b32_sdwa v72, v74, v72 dst_sel:DWORD dst_unused:UNUSED_PAD src0_sel:DWORD src1_sel:WORD_1
	ds_write_b128 v133, v[70:73]
	v_and_b32_sdwa v1, v142, v116 dst_sel:DWORD dst_unused:UNUSED_PAD src0_sel:WORD_1 src1_sel:DWORD
	v_and_b32_sdwa v70, v143, v116 dst_sel:DWORD dst_unused:UNUSED_PAD src0_sel:WORD_1 src1_sel:DWORD
	v_cvt_pk_bf16_f32 v71, v144, v144
	v_cvt_pk_bf16_f32 v72, v145, v145
	v_add3_u32 v70, v143, v70, s33
	v_add3_u32 v1, v142, v1, s33
	v_and_b32_e32 v71, 0xffff0000, v71
	v_and_b32_e32 v72, 0xffff0000, v72
	v_or_b32_sdwa v71, v71, v1 dst_sel:DWORD dst_unused:UNUSED_PAD src0_sel:DWORD src1_sel:WORD_1
	v_or_b32_sdwa v70, v72, v70 dst_sel:DWORD dst_unused:UNUSED_PAD src0_sel:DWORD src1_sel:WORD_1
	v_and_b32_sdwa v1, v66, v116 dst_sel:DWORD dst_unused:UNUSED_PAD src0_sel:WORD_1 src1_sel:DWORD
	v_and_b32_sdwa v72, v67, v116 dst_sel:DWORD dst_unused:UNUSED_PAD src0_sel:WORD_1 src1_sel:DWORD
	v_add3_u32 v67, v67, v72, s33
	v_add3_u32 v1, v66, v1, s33
	v_and_b32_sdwa v72, v69, v116 dst_sel:DWORD dst_unused:UNUSED_PAD src0_sel:WORD_1 src1_sel:DWORD
	v_cvt_pk_bf16_f32 v66, v68, v68
	v_add3_u32 v68, v69, v72, s33
	v_and_b32_e32 v66, 0xffff0000, v66
	v_and_b32_e32 v68, 0xffff0000, v68
	v_or_b32_sdwa v73, v66, v1 dst_sel:DWORD dst_unused:UNUSED_PAD src0_sel:DWORD src1_sel:WORD_1
	v_or_b32_sdwa v72, v68, v67 dst_sel:DWORD dst_unused:UNUSED_PAD src0_sel:DWORD src1_sel:WORD_1
	ds_write_b128 v133, v[70:73] offset:144

.Lssd0_pf_done:
	ds_read_b128 v[70:73], v1
	ds_read_b128 v[66:69], v1 offset:64
	ds_read_b128 v[74:77], v141 offset:9216
	ds_read_b128 v[78:81], v141 offset:9280
	s_waitcnt lgkmcnt(1)
	v_mfma_f32_16x16x32_bf16 v[74:77], v[70:73], v[74:77], 0
	v_add_u32_e32 v89, 0xb400, v92
	s_add_i32 s97, s78, 64
	s_cmp_ge_u32 s97, s75
	s_waitcnt lgkmcnt(0)
	v_mfma_f32_16x16x32_bf16 v[142:145], v[66:69], v[78:81], v[74:77]
	ds_read_b128 v[78:81], v141 offset:11584
	s_nop 1
	ds_read_b128 v[74:77], v141 offset:11520
	s_waitcnt lgkmcnt(0)
	v_mfma_f32_16x16x32_bf16 v[74:77], v[70:73], v[74:77], 0
	v_mfma_f32_16x16x32_bf16 v[146:149], v[66:69], v[78:81], v[74:77]
	ds_read_b128 v[78:81], v141 offset:13888
	s_nop 5
	ds_read_b128 v[74:77], v141 offset:13824
	s_waitcnt lgkmcnt(0)
	v_mfma_f32_16x16x32_bf16 v[74:77], v[70:73], v[74:77], 0
	v_mfma_f32_16x16x32_bf16 v[82:85], v[66:69], v[78:81], v[74:77]
	ds_read_b128 v[78:81], v141 offset:16192
	s_nop 5
	ds_read_b128 v[74:77], v141 offset:16128
	s_waitcnt lgkmcnt(0)
	v_mfma_f32_16x16x32_bf16 v[74:77], v[70:73], v[74:77], 0
	v_mfma_f32_16x16x32_bf16 v[78:81], v[66:69], v[78:81], v[74:77]
	s_nop 6
	ds_read_b128 v[74:77], v139 offset:46080
	ds_read2_b32 v[106:107], v89 offset1:16
	ds_read2_b32 v[150:151], v89 offset0:64 offset1:80
	s_waitcnt lgkmcnt(1)
	v_sub_f32_e32 v152, v74, v106
	v_mul_f32_e32 v152, 0x3fb8aa3b, v152
	v_exp_f32_e32 v152, v152
	s_waitcnt lgkmcnt(0)
	v_mul_f32_e32 v152, v150, v152
	v_cndmask_b32_e64 v152, v152, 0, s[24:25]
	v_mul_f32_e32 v142, v142, v152
	v_cvt_pk_bf16_f32 v142, v142, v142
	ds_write_b16_d16_hi v93, v142
	v_sub_f32_e32 v142, v75, v106
	v_mul_f32_e32 v142, 0x3fb8aa3b, v142
	v_exp_f32_e32 v142, v142
	s_nop 0
	v_mul_f32_e32 v142, v150, v142
	v_cndmask_b32_e64 v142, v142, 0, s[26:27]
	v_mul_f32_e32 v142, v143, v142
	v_bfe_u32 v143, v142, 16, 1
	v_add3_u32 v142, v142, v143, s33
	ds_write_b16_d16_hi v93, v142 offset:144
	v_sub_f32_e32 v142, v76, v106
	v_mul_f32_e32 v142, 0x3fb8aa3b, v142
	v_exp_f32_e32 v142, v142
	v_sub_f32_e32 v106, v77, v106
	v_mul_f32_e32 v106, 0x3fb8aa3b, v106
	v_exp_f32_e32 v106, v106
	v_mul_f32_e32 v142, v150, v142
	v_cndmask_b32_e64 v142, v142, 0, s[28:29]
	v_mul_f32_e32 v142, v144, v142
	v_mul_f32_e32 v106, v150, v106
	v_bfe_u32 v143, v142, 16, 1
	v_cndmask_b32_e64 v106, v106, 0, s[30:31]
	v_add3_u32 v142, v142, v143, s33
	v_mul_f32_e32 v106, v145, v106
	ds_write_b16_d16_hi v93, v142 offset:288
	v_bfe_u32 v142, v106, 16, 1
	v_add3_u32 v106, v106, v142, s33
	ds_write_b16_d16_hi v93, v106 offset:432
	v_sub_f32_e32 v106, v74, v107
	v_mul_f32_e32 v106, 0x3fb8aa3b, v106
	v_exp_f32_e32 v106, v106
	s_nop 0
	v_mul_f32_e32 v106, v151, v106
	v_cndmask_b32_e64 v106, v106, 0, s[34:35]
	v_mul_f32_e32 v106, v146, v106
	v_bfe_u32 v142, v106, 16, 1
	v_add3_u32 v106, v106, v142, s33
	ds_write_b16_d16_hi v93, v106 offset:32
	v_sub_f32_e32 v106, v75, v107
	v_mul_f32_e32 v106, 0x3fb8aa3b, v106
	v_exp_f32_e32 v106, v106
	s_nop 0
	v_mul_f32_e32 v106, v151, v106
	v_cndmask_b32_e64 v106, v106, 0, s[36:37]
	v_mul_f32_e32 v106, v147, v106
	v_bfe_u32 v142, v106, 16, 1
	v_add3_u32 v106, v106, v142, s33
	ds_write_b16_d16_hi v93, v106 offset:176
	v_sub_f32_e32 v106, v76, v107
	v_mul_f32_e32 v106, 0x3fb8aa3b, v106
	v_exp_f32_e32 v106, v106
	s_nop 0
	v_mul_f32_e32 v106, v151, v106
	v_cndmask_b32_e64 v106, v106, 0, s[38:39]
	v_mul_f32_e32 v106, v148, v106
	v_bfe_u32 v142, v106, 16, 1
	v_add3_u32 v106, v106, v142, s33
	ds_write_b16_d16_hi v93, v106 offset:320
	v_sub_f32_e32 v106, v77, v107
	v_mul_f32_e32 v106, 0x3fb8aa3b, v106
	v_exp_f32_e32 v106, v106
	s_nop 0
	v_mul_f32_e32 v106, v151, v106
	v_cndmask_b32_e64 v106, v106, 0, s[40:41]
	v_mul_f32_e32 v106, v149, v106
	v_bfe_u32 v107, v106, 16, 1
	v_add3_u32 v106, v106, v107, s33
	ds_write_b16_d16_hi v93, v106 offset:464
	ds_read2_b32 v[106:107], v89 offset0:32 offset1:48
	ds_read2_b32 v[142:143], v89 offset0:96 offset1:112
	s_waitcnt lgkmcnt(1)
	v_sub_f32_e32 v89, v74, v106
	v_mul_f32_e32 v89, 0x3fb8aa3b, v89
	v_exp_f32_e32 v89, v89
	s_waitcnt lgkmcnt(0)
	v_mul_f32_e32 v89, v142, v89
	v_cndmask_b32_e64 v89, v89, 0, s[42:43]
	v_mul_f32_e32 v82, v82, v89
	v_bfe_u32 v89, v82, 16, 1
	v_add3_u32 v82, v82, v89, s33
	ds_write_b16_d16_hi v93, v82 offset:64
	v_sub_f32_e32 v82, v75, v106
	v_mul_f32_e32 v82, 0x3fb8aa3b, v82
	v_exp_f32_e32 v82, v82
	s_nop 0
	v_mul_f32_e32 v82, v142, v82
	v_cndmask_b32_e64 v82, v82, 0, s[44:45]
	v_mul_f32_e32 v82, v83, v82
	v_bfe_u32 v83, v82, 16, 1
	v_add3_u32 v82, v82, v83, s33
	ds_write_b16_d16_hi v93, v82 offset:208
	v_sub_f32_e32 v82, v76, v106
	v_mul_f32_e32 v82, 0x3fb8aa3b, v82
	v_exp_f32_e32 v82, v82
	s_nop 0
	v_mul_f32_e32 v82, v142, v82
	v_cndmask_b32_e64 v82, v82, 0, s[46:47]
	v_mul_f32_e32 v82, v84, v82
	v_bfe_u32 v83, v82, 16, 1
	v_add3_u32 v82, v82, v83, s33
	ds_write_b16_d16_hi v93, v82 offset:352
	v_sub_f32_e32 v82, v77, v106
	v_mul_f32_e32 v82, 0x3fb8aa3b, v82
	v_exp_f32_e32 v82, v82
	s_nop 0
	v_mul_f32_e32 v82, v142, v82
	v_cndmask_b32_e64 v82, v82, 0, s[48:49]
	v_mul_f32_e32 v82, v85, v82
	v_bfe_u32 v83, v82, 16, 1
	v_add3_u32 v82, v82, v83, s33
	ds_write_b16_d16_hi v93, v82 offset:496
	v_sub_f32_e32 v82, v74, v107
	v_mul_f32_e32 v82, 0x3fb8aa3b, v82
	v_exp_f32_e32 v82, v82
	s_nop 0
	v_mul_f32_e32 v82, v143, v82
	v_cndmask_b32_e64 v82, v82, 0, s[50:51]
	v_mul_f32_e32 v78, v78, v82
	v_bfe_u32 v82, v78, 16, 1
	v_add3_u32 v78, v78, v82, s33
	ds_write_b16_d16_hi v93, v78 offset:96
	v_sub_f32_e32 v78, v75, v107
	v_mul_f32_e32 v78, 0x3fb8aa3b, v78
	v_exp_f32_e32 v78, v78
	s_nop 0
	v_mul_f32_e32 v78, v143, v78
	v_cndmask_b32_e64 v78, v78, 0, s[52:53]
	v_mul_f32_e32 v78, v79, v78
	v_bfe_u32 v79, v78, 16, 1
	v_add3_u32 v78, v78, v79, s33
	ds_write_b16_d16_hi v93, v78 offset:240
	v_sub_f32_e32 v78, v76, v107
	v_mul_f32_e32 v78, 0x3fb8aa3b, v78
	v_exp_f32_e32 v78, v78
	s_nop 0
	v_mul_f32_e32 v78, v143, v78
	v_cndmask_b32_e64 v78, v78, 0, s[54:55]
	v_mul_f32_e32 v78, v80, v78
	v_bfe_u32 v79, v78, 16, 1
	v_add3_u32 v78, v78, v79, s33
	ds_write_b16_d16_hi v93, v78 offset:384
	v_sub_f32_e32 v78, v77, v107
	v_mul_f32_e32 v78, 0x3fb8aa3b, v78
	v_exp_f32_e32 v78, v78
	s_nop 0
	v_mul_f32_e32 v78, v143, v78
	v_cndmask_b32_e64 v78, v78, 0, s[56:57]
	v_mul_f32_e32 v78, v81, v78
	v_bfe_u32 v79, v78, 16, 1
	v_add3_u32 v78, v78, v79, s33
	ds_write_b16_d16_hi v93, v78 offset:528
	ds_read_b128 v[78:81], v1
	ds_read_b128 v[82:85], v1 offset:64
	ds_read_b128 v[142:145], v141 offset:36864
	ds_read_b128 v[146:149], v141 offset:36928
	ds_read_b128 v[150:153], v141 offset:41536
	s_waitcnt lgkmcnt(2)
	v_mfma_f32_16x16x32_bf16 v[142:145], v[70:73], v[142:145], 0
	v_mul_f32_e32 v1, 0x3fb8aa3b, v74
	v_exp_f32_e32 v106, v1
	v_mul_f32_e32 v1, 0x3fb8aa3b, v75
	v_exp_f32_e32 v107, v1
	v_mul_f32_e32 v1, 0x3fb8aa3b, v76
	v_exp_f32_e32 v154, v1
	v_mul_f32_e32 v1, 0x3fb8aa3b, v77
	s_waitcnt lgkmcnt(1)
	v_mfma_f32_16x16x32_bf16 v[142:145], v[66:69], v[146:149], v[142:145]
	v_exp_f32_e32 v155, v1
	ds_read_b128 v[74:77], v141 offset:18432
	ds_read_b128 v[146:149], v141 offset:39232
	v_add_u32_e32 v1, s78, v137
	s_nop 3
	v_pk_mul_f32 v[142:143], v[106:107], v[142:143]
	v_pk_mul_f32 v[144:145], v[154:155], v[144:145]
	s_waitcnt lgkmcnt(1)
	s_nop 0
	v_mfma_f32_16x16x32_bf16 v[74:77], v[78:81], v[74:77], v[142:145]
	s_nop 2
	ds_read_b128 v[142:145], v141 offset:18496
	s_waitcnt lgkmcnt(0)
	v_mfma_f32_16x16x32_bf16 v[74:77], v[82:85], v[142:145], v[74:77]
	ds_read_b128 v[142:145], v141 offset:39168
	s_waitcnt lgkmcnt(0)
	v_mfma_f32_16x16x32_bf16 v[142:145], v[70:73], v[142:145], 0
	v_mfma_f32_16x16x32_bf16 v[142:145], v[66:69], v[146:149], v[142:145]
	ds_read_b128 v[146:149], v141 offset:20736
	s_nop 6
	v_pk_mul_f32 v[142:143], v[106:107], v[142:143]
	v_pk_mul_f32 v[144:145], v[154:155], v[144:145]
	s_waitcnt lgkmcnt(0)
	s_nop 0
	v_mfma_f32_16x16x32_bf16 v[142:145], v[78:81], v[146:149], v[142:145]
	ds_read_b128 v[146:149], v141 offset:20800
	s_waitcnt lgkmcnt(0)
	v_mfma_f32_16x16x32_bf16 v[142:145], v[82:85], v[146:149], v[142:145]
	ds_read_b128 v[146:149], v141 offset:41472
	s_waitcnt lgkmcnt(0)
	v_mfma_f32_16x16x32_bf16 v[146:149], v[70:73], v[146:149], 0
	v_mfma_f32_16x16x32_bf16 v[146:149], v[66:69], v[150:153], v[146:149]
	ds_read_b128 v[150:153], v141 offset:23040
	s_nop 6
	v_pk_mul_f32 v[146:147], v[106:107], v[146:147]
	v_pk_mul_f32 v[148:149], v[154:155], v[148:149]
	s_waitcnt lgkmcnt(0)
	s_nop 0
	v_mfma_f32_16x16x32_bf16 v[146:149], v[78:81], v[150:153], v[146:149]
	ds_read_b128 v[150:153], v141 offset:23104
	s_waitcnt lgkmcnt(0)
	v_mfma_f32_16x16x32_bf16 v[146:149], v[82:85], v[150:153], v[146:149]
	ds_read_b128 v[150:153], v141 offset:43776
	s_waitcnt lgkmcnt(0)
	v_mfma_f32_16x16x32_bf16 v[70:73], v[70:73], v[150:153], 0
	ds_read_b128 v[150:153], v141 offset:43840
	s_waitcnt lgkmcnt(0)
	v_mfma_f32_16x16x32_bf16 v[66:69], v[66:69], v[150:153], v[70:73]
	s_nop 4
	ds_read_b128 v[70:73], v141 offset:25344
	s_nop 1
	v_pk_mul_f32 v[66:67], v[106:107], v[66:67]
	v_pk_mul_f32 v[68:69], v[154:155], v[68:69]
	s_waitcnt lgkmcnt(0)
	s_nop 0
	v_mfma_f32_16x16x32_bf16 v[66:69], v[78:81], v[70:73], v[66:69]
	ds_read_b128 v[70:73], v141 offset:25408
	s_waitcnt lgkmcnt(0)
	v_mfma_f32_16x16x32_bf16 v[66:69], v[82:85], v[70:73], v[66:69]
	v_add_u32_e32 v70, s76, v138
	v_cndmask_b32_e64 v70, v70, v1, s[6:7]
	v_add_u32_e32 v70, s96, v70
	v_mad_i64_i32 v[70:71], s[0:1], v70, s72, v[102:103]
	v_cvt_pk_bf16_f32 v72, v74, v74
	global_store_short_d16_hi v[70:71], v72, off offset:1024
	v_cvt_pk_bf16_f32 v72, v142, v142
	global_store_short_d16_hi v[70:71], v72, off offset:1056
	v_cvt_pk_bf16_f32 v72, v146, v146
	global_store_short_d16_hi v[70:71], v72, off offset:1088
	v_cvt_pk_bf16_f32 v66, v66, v66
	global_store_short_d16_hi v[70:71], v66, off offset:1120
	v_add_u32_e32 v66, 1, v1
	v_xad_u32 v70, v1, -2, s75
	v_cndmask_b32_e64 v66, v70, v66, s[6:7]
	v_add_u32_e32 v66, s96, v66
	v_mad_i64_i32 v[70:71], s[0:1], v66, s72, v[102:103]
	v_cvt_pk_bf16_f32 v66, v75, v75
	global_store_short_d16_hi v[70:71], v66, off offset:1024
	v_cvt_pk_bf16_f32 v66, v143, v143
	global_store_short_d16_hi v[70:71], v66, off offset:1056
	v_cvt_pk_bf16_f32 v66, v147, v147
	global_store_short_d16_hi v[70:71], v66, off offset:1088
	v_cvt_pk_bf16_f32 v66, v67, v67
	global_store_short_d16_hi v[70:71], v66, off offset:1120
	v_add_u32_e32 v66, 2, v1
	v_xad_u32 v67, v1, -3, s75
	v_cndmask_b32_e64 v66, v67, v66, s[6:7]
	v_add_u32_e32 v66, s96, v66
	v_mad_i64_i32 v[66:67], s[0:1], v66, s72, v[102:103]
	v_cvt_pk_bf16_f32 v70, v76, v76
	global_store_short_d16_hi v[66:67], v70, off offset:1024
	v_cvt_pk_bf16_f32 v70, v144, v144
	global_store_short_d16_hi v[66:67], v70, off offset:1056
	v_cvt_pk_bf16_f32 v70, v148, v148
	global_store_short_d16_hi v[66:67], v70, off offset:1088
	v_cvt_pk_bf16_f32 v68, v68, v68
	global_store_short_d16_hi v[66:67], v68, off offset:1120
	v_add_u32_e32 v66, 3, v1
	v_xad_u32 v1, v1, -4, s75
	v_cndmask_b32_e64 v1, v1, v66, s[6:7]
	v_add_u32_e32 v1, s96, v1
	v_mad_i64_i32 v[66:67], s[0:1], v1, s72, v[102:103]
	v_cvt_pk_bf16_f32 v1, v77, v77
	global_store_short_d16_hi v[66:67], v1, off offset:1024
	v_cvt_pk_bf16_f32 v1, v145, v145
	global_store_short_d16_hi v[66:67], v1, off offset:1056
	v_cvt_pk_bf16_f32 v1, v149, v149
	global_store_short_d16_hi v[66:67], v1, off offset:1088
	s_cselect_b64 s[0:1], -1, 0
	v_cvt_pk_bf16_f32 v1, v69, v69
	s_and_b64 vcc, exec, s[0:1]
	global_store_short_d16_hi v[66:67], v1, off offset:1120
.LBB0_1033:
	ds_read_b32 v1, v0 offset:46332
	ds_read_b128 v[66:69], v115 offset:18432
	ds_read_b128 v[70:73], v127 offset:46592
	ds_read_b128 v[74:77], v127 offset:46608
	s_sub_i32 s76, s76, 64
	s_and_b64 vcc, exec, s[0:1]
	s_waitcnt lgkmcnt(2)
	v_and_b32_e32 v79, 0xffff0000, v66
	v_lshlrev_b32_e32 v78, 16, v66
	s_waitcnt lgkmcnt(1)
	v_pk_mul_f32 v[70:71], v[70:71], v[78:79]
	v_and_b32_e32 v79, 0xffff0000, v67
	v_lshlrev_b32_e32 v78, 16, v67
	v_pk_mul_f32 v[66:67], v[72:73], v[78:79]
	v_and_b32_e32 v73, 0xffff0000, v68
	v_lshlrev_b32_e32 v72, 16, v68
	s_waitcnt lgkmcnt(0)
	v_pk_mul_f32 v[72:73], v[74:75], v[72:73]
	v_and_b32_e32 v75, 0xffff0000, v69
	v_lshlrev_b32_e32 v74, 16, v69
	v_pk_mul_f32 v[68:69], v[76:77], v[74:75]
	v_bfe_u32 v79, v72, 16, 1
	v_cvt_pk_bf16_f32 v82, v66, v66
	v_cvt_pk_bf16_f32 v83, v67, v67
	v_cvt_pk_bf16_f32 v84, v68, v68
	v_cvt_pk_bf16_f32 v85, v69, v69
	v_cvt_pk_bf16_f32 v81, v70, v70
	v_cvt_pk_bf16_f32 v80, v71, v71
	v_add3_u32 v79, v72, v79, s33
	v_cvt_pk_bf16_f32 v89, v73, v73
	ds_read_b128 v[66:69], v115 offset:18496
	ds_read_b128 v[70:73], v127 offset:46720
	v_mul_f32_e32 v1, 0x3fb8aa3b, v1
	s_waitcnt lgkmcnt(1)
	v_and_b32_e32 v75, 0xffff0000, v66
	v_lshlrev_b32_e32 v74, 16, v66
	s_waitcnt lgkmcnt(0)
	v_pk_mul_f32 v[74:75], v[70:71], v[74:75]
	v_and_b32_e32 v71, 0xffff0000, v67
	v_lshlrev_b32_e32 v70, 16, v67
	v_pk_mul_f32 v[66:67], v[72:73], v[70:71]
	ds_read_b128 v[70:73], v127 offset:46736
	v_and_b32_e32 v77, 0xffff0000, v68
	v_lshlrev_b32_e32 v76, 16, v68
	s_waitcnt lgkmcnt(0)
	v_pk_mul_f32 v[70:71], v[70:71], v[76:77]
	v_and_b32_e32 v77, 0xffff0000, v69
	v_lshlrev_b32_e32 v76, 16, v69
	v_pk_mul_f32 v[68:69], v[72:73], v[76:77]
	v_cvt_pk_bf16_f32 v143, v66, v66
	v_cvt_pk_bf16_f32 v144, v67, v67
	v_cvt_pk_bf16_f32 v145, v68, v68
	v_cvt_pk_bf16_f32 v146, v69, v69
	v_cvt_pk_bf16_f32 v106, v70, v70
	v_cvt_pk_bf16_f32 v147, v71, v71
	v_exp_f32_e32 v78, v1
	ds_read_b128 v[66:69], v141 offset:27648
	v_perm_b32 v73, v85, v84, s3
	v_perm_b32 v71, v83, v82, s3
	v_perm_b32 v72, v89, v79, s3
	v_perm_b32 v70, v80, v81, s3
	v_cvt_pk_bf16_f32 v142, v74, v74
	v_cvt_pk_bf16_f32 v107, v75, v75
	v_pk_mul_f32 v[4:5], v[4:5], v[78:79] op_sel_hi:[1,0]
	v_pk_mul_f32 v[2:3], v[2:3], v[78:79] op_sel_hi:[1,0]
	ds_read_b128 v[74:77], v141 offset:27712
	v_pk_mul_f32 v[8:9], v[8:9], v[78:79] op_sel_hi:[1,0]
	s_waitcnt lgkmcnt(1)
	v_mfma_f32_16x16x32_bf16 v[2:5], v[70:73], v[66:69], v[2:5]
	v_perm_b32 v69, v146, v145, s3
	v_perm_b32 v67, v144, v143, s3
	v_perm_b32 v68, v147, v106, s3
	v_perm_b32 v66, v107, v142, s3
	v_pk_mul_f32 v[6:7], v[6:7], v[78:79] op_sel_hi:[1,0]
	v_pk_mul_f32 v[12:13], v[12:13], v[78:79] op_sel_hi:[1,0]
	s_waitcnt lgkmcnt(0)
	v_mfma_f32_16x16x32_bf16 v[2:5], v[66:69], v[74:77], v[2:5]
	ds_read_b128 v[74:77], v141 offset:29952
	v_pk_mul_f32 v[10:11], v[10:11], v[78:79] op_sel_hi:[1,0]
	v_pk_mul_f32 v[24:25], v[24:25], v[78:79] op_sel_hi:[1,0]
	s_waitcnt lgkmcnt(0)
	v_mfma_f32_16x16x32_bf16 v[6:9], v[70:73], v[74:77], v[6:9]
	ds_read_b128 v[74:77], v141 offset:30016
	s_nop 1
	v_bfe_u32 v1, v2, 16, 1
	v_pk_mul_f32 v[22:23], v[22:23], v[78:79] op_sel_hi:[1,0]
	s_waitcnt lgkmcnt(0)
	v_mfma_f32_16x16x32_bf16 v[6:9], v[66:69], v[74:77], v[6:9]
	ds_read_b128 v[74:77], v141 offset:32256
	v_add3_u32 v1, v2, v1, s33
	s_waitcnt lgkmcnt(0)
	v_mfma_f32_16x16x32_bf16 v[10:13], v[70:73], v[74:77], v[10:13]
	ds_read_b128 v[74:77], v141 offset:32320
	s_waitcnt lgkmcnt(0)
	v_mfma_f32_16x16x32_bf16 v[10:13], v[66:69], v[74:77], v[10:13]
	ds_read_b128 v[74:77], v141 offset:34560
	s_waitcnt lgkmcnt(0)
	v_mfma_f32_16x16x32_bf16 v[22:25], v[70:73], v[74:77], v[22:25]
	ds_read_b128 v[70:73], v141 offset:34624
	s_waitcnt lgkmcnt(0)
	s_barrier
	ds_write_b16_d16_hi v93, v1 offset:36864
	v_bfe_u32 v1, v3, 16, 1
	v_add3_u32 v1, v3, v1, s33
	ds_write_b16_d16_hi v93, v1 offset:37008
	v_bfe_u32 v1, v4, 16, 1
	v_add3_u32 v1, v4, v1, s33
	ds_write_b16_d16_hi v93, v1 offset:37152
	v_bfe_u32 v1, v5, 16, 1
	v_add3_u32 v1, v5, v1, s33
	ds_write_b16_d16_hi v93, v1 offset:37296
	v_bfe_u32 v1, v6, 16, 1
	v_add3_u32 v1, v6, v1, s33
	ds_write_b16_d16_hi v93, v1 offset:36896
	v_bfe_u32 v1, v7, 16, 1
	v_add3_u32 v1, v7, v1, s33
	ds_write_b16_d16_hi v93, v1 offset:37040
	v_bfe_u32 v1, v8, 16, 1
	v_add3_u32 v1, v8, v1, s33
	ds_write_b16_d16_hi v93, v1 offset:37184
	v_bfe_u32 v1, v9, 16, 1
	v_add3_u32 v1, v9, v1, s33
	ds_write_b16_d16_hi v93, v1 offset:37328
	v_bfe_u32 v1, v10, 16, 1
	v_add3_u32 v1, v10, v1, s33
	ds_write_b16_d16_hi v93, v1 offset:36928
	v_bfe_u32 v1, v11, 16, 1
	v_add3_u32 v1, v11, v1, s33
	v_mfma_f32_16x16x32_bf16 v[22:25], v[66:69], v[70:73], v[22:25]
	ds_write_b16_d16_hi v93, v1 offset:37072
	v_bfe_u32 v1, v12, 16, 1
	v_add3_u32 v1, v12, v1, s33
	ds_write_b16_d16_hi v93, v1 offset:37216
	v_bfe_u32 v1, v13, 16, 1
	v_add3_u32 v1, v13, v1, s33
	ds_write_b16_d16_hi v93, v1 offset:37360
	s_nop 0
	v_bfe_u32 v1, v22, 16, 1
	v_add3_u32 v1, v22, v1, s33
	ds_write_b16_d16_hi v93, v1 offset:36960
	v_bfe_u32 v1, v23, 16, 1
	v_add3_u32 v1, v23, v1, s33
	ds_write_b16_d16_hi v93, v1 offset:37104
	v_bfe_u32 v1, v24, 16, 1
	v_add3_u32 v1, v24, v1, s33
	ds_write_b16_d16_hi v93, v1 offset:37248
	v_bfe_u32 v1, v25, 16, 1
	v_add3_u32 v1, v25, v1, s33
	ds_write_b16_d16_hi v93, v1 offset:37392
	s_cbranch_vccnz .LBB0_1035
	s_mov_b32 s78, s97
	s_and_saveexec_b64 s[0:1], s[4:5]
	s_xor_b64 s[0:1], exec, s[0:1]
	s_cbranch_execnz .Lssd0_w3back
	s_branch .LBB0_985

.LBB0_1046:
	s_lshl_b64 s[0:1], s[8:9], 1
	v_readlane_b32 s4, v241, 17
	v_readlane_b32 s5, v241, 18
	v_rcp_f32_e32 v7, v55
	s_add_i32 s19, s19, s17
	v_readlane_b32 s8, v241, 21
	v_readlane_b32 s9, v241, 22
	v_mul_f32_e32 v8, 1.0, v7
	s_add_u32 s0, s8, s0
	v_or_b32_e32 v1, v68, v47
	s_addc_u32 s1, s9, s1
	v_lshlrev_b32_e32 v4, 1, v45
	v_mov_b32_e32 v5, v0
	v_mul_f32_e32 v9, v8, v12
	v_add_u32_e32 v1, s19, v1
	v_lshl_add_u64 v[4:5], s[0:1], 0, v[4:5]
	s_movk_i32 s4, 0x300
	v_mad_i64_i32 v[6:7], s[0:1], v1, s4, v[4:5]
	v_cvt_pk_bf16_f32 v9, v9, v9
	global_store_short_d16_hi v[6:7], v9, off
	v_mul_f32_e32 v9, v8, v16
	v_cvt_pk_bf16_f32 v9, v9, v9
	global_store_short_d16_hi v[6:7], v9, off offset:32
	v_mul_f32_e32 v9, v8, v20
	v_cvt_pk_bf16_f32 v9, v9, v9
	global_store_short_d16_hi v[6:7], v9, off offset:64
	v_rcp_f32_e32 v10, v54
	v_mul_f32_e32 v8, v8, v24
	v_cvt_pk_bf16_f32 v8, v8, v8
	global_store_short_d16_hi v[6:7], v8, off offset:96
	v_mul_f32_e32 v8, 1.0, v10
	v_mul_f32_e32 v9, v8, v13
	v_add_u32_e32 v6, 1, v1
	v_mad_i64_i32 v[6:7], s[0:1], v6, s4, v[4:5]
	v_cvt_pk_bf16_f32 v9, v9, v9
	global_store_short_d16_hi v[6:7], v9, off
	v_mul_f32_e32 v9, v8, v17
	v_cvt_pk_bf16_f32 v9, v9, v9
	global_store_short_d16_hi v[6:7], v9, off offset:32
	v_mul_f32_e32 v9, v8, v21
	v_cvt_pk_bf16_f32 v9, v9, v9
	global_store_short_d16_hi v[6:7], v9, off offset:64
	v_rcp_f32_e32 v10, v3
	v_mul_f32_e32 v8, v8, v25
	v_cvt_pk_bf16_f32 v8, v8, v8
	global_store_short_d16_hi v[6:7], v8, off offset:96
	v_mul_f32_e32 v3, 1.0, v10
	v_mul_f32_e32 v8, v3, v14
	v_add_u32_e32 v6, 2, v1
	v_mad_i64_i32 v[6:7], s[0:1], v6, s4, v[4:5]
	v_cvt_pk_bf16_f32 v8, v8, v8
	global_store_short_d16_hi v[6:7], v8, off
	v_mul_f32_e32 v8, v3, v18
	v_cvt_pk_bf16_f32 v8, v8, v8
	global_store_short_d16_hi v[6:7], v8, off offset:32
	v_mul_f32_e32 v8, v3, v22
	v_cvt_pk_bf16_f32 v8, v8, v8
	global_store_short_d16_hi v[6:7], v8, off offset:64
	v_rcp_f32_e32 v9, v2
	v_mul_f32_e32 v3, v3, v26
	v_cvt_pk_bf16_f32 v3, v3, v3
	global_store_short_d16_hi v[6:7], v3, off offset:96
	v_mul_f32_e32 v6, 1.0, v9
	v_add_u32_e32 v1, 3, v1
	v_mad_i64_i32 v[2:3], s[0:1], v1, s4, v[4:5]
	v_mul_f32_e32 v1, v6, v15
	v_cvt_pk_bf16_f32 v1, v1, v1
	global_store_short_d16_hi v[2:3], v1, off
	v_mul_f32_e32 v1, v6, v19
	v_cvt_pk_bf16_f32 v1, v1, v1
	global_store_short_d16_hi v[2:3], v1, off offset:32
	v_mul_f32_e32 v1, v6, v23
	v_cvt_pk_bf16_f32 v1, v1, v1
	global_store_short_d16_hi v[2:3], v1, off offset:64
	v_mul_f32_e32 v1, v6, v27
	v_cvt_pk_bf16_f32 v1, v1, v1
	v_readlane_b32 s6, v241, 19
	v_readlane_b32 s7, v241, 20
	v_readlane_b32 s10, v241, 23
	v_readlane_b32 s11, v241, 24
	global_store_short_d16_hi v[2:3], v1, off offset:96
	s_barrier
	s_mov_b32 s23, s27
	s_cbranch_execz .LBB0_893
	s_branch .LBB0_1038

.LBB0_1143:
	s_cmp_le_u32 s50, s68
	s_cbranch_scc1 .LBB0_1145
	s_not_b32 s30, s50
	s_lshl_b32 s30, s30, 6
	s_and_b32 s30, s30, 0x400
	v_add_u32_e32 v1, s30, v99
	ds_read_b32 v1, v1 offset:21504
	v_add_u32_e32 v50, s50, v93
	v_xad_u32 v51, v50, -1, s42
	v_cndmask_b32_e64 v50, v51, v50, s[16:17]
	v_add_u32_e32 v50, s41, v50
	s_waitcnt lgkmcnt(0)
	v_cvt_pk_bf16_f32 v1, v1, v1
	v_mad_i64_i32 v[50:51], s[30:31], s47, v50, 0
	v_lshl_add_u64 v[50:51], v[50:51], 1, v[100:101]
	global_store_short_d16_hi v[50:51], v1, off

.LBB0_1179:
	s_cmp_lt_u32 s50, s68
	s_cbranch_scc1 .LBB0_1181
	ds_read_b32 v1, v99 offset:21504
	v_add_u32_e32 v50, s50, v87
	v_xad_u32 v51, v50, -1, s42
	v_cndmask_b32_e64 v50, v51, v50, s[16:17]
	v_add_u32_e32 v50, s41, v50
	s_waitcnt lgkmcnt(0)
	v_cvt_pk_bf16_f32 v1, v1, v1
	v_mad_i64_i32 v[50:51], s[30:31], s47, v50, 0
	v_lshl_add_u64 v[50:51], v[50:51], 1, v[100:101]
	global_store_short_d16_hi v[50:51], v1, off

.LBB0_1228:
	s_waitcnt lgkmcnt(0)
	s_barrier
	ds_read_b32 v2, v99 offset:22528
	v_add_u32_e32 v1, s48, v93
	s_cmp_eq_u32 s69, 0
	v_xad_u32 v3, v1, -1, s42
	s_cselect_b64 vcc, -1, 0
	v_cndmask_b32_e32 v1, v3, v1, vcc
	s_waitcnt lgkmcnt(0)
	v_add_u32_e32 v1, s41, v1
	v_cvt_pk_bf16_f32 v4, v2, v2
	v_mad_i64_i32 v[2:3], s[4:5], s47, v1, 0
	v_lshl_add_u64 v[2:3], v[2:3], 1, s[26:27]
	v_lshl_add_u64 v[2:3], v[94:95], 1, v[2:3]
	s_cmp_lg_u32 s79, 3
	global_store_short_d16_hi v[2:3], v4, off
	s_cbranch_scc0 .LBB0_1232
	s_mov_b64 s[6:7], 0
	s_and_b64 vcc, exec, s[0:1]
	s_mov_b64 s[4:5], 0
	s_cbranch_vccnz .LBB0_1233
	s_and_b64 vcc, exec, s[6:7]
	s_cbranch_vccnz .LBB0_1234

.Lrw0_entry:
	s_waitcnt vmcnt(0) lgkmcnt(0)
	s_cmp_lt_u32 s12, 0x180
	s_cbranch_scc0 .Lrw0_dctx
	s_lshr_b32 s18, s12, 7
	s_bfe_u32 s16, s12, 0x50002
	s_and_b32 s17, s12, 3
	s_branch .Lrw0_ddone
.Lrw0_dctx:
	s_sub_u32 s30, s12, 0x1b0
	s_lshr_b32 s16, s30, 2
	s_add_u32 s16, s16, 32
	s_and_b32 s17, s30, 3
	s_mov_b32 s18, 3
.Lrw0_ddone:
	s_bfe_u32 s19, s16, 0x20001
	s_and_b32 s20, s16, 1
	s_cmp_lt_u32 s16, 32
	s_cbranch_scc0 .Lrw0_gctx
	s_lshr_b32 s21, s16, 3
	s_lshl_b32 s22, s21, 12
	s_add_u32 s22, s22, 0x1000
	s_movk_i32 s23, 0x1000
	s_branch .Lrw0_gdone
.Lrw0_gctx:
	s_sub_u32 s21, s16, 32
	s_lshr_b32 s21, s21, 3
	s_lshl_b32 s22, s21, 8
	s_movk_i32 s23, 0x100
.Lrw0_gdone:
	s_sub_u32 s29, s23, 1
	s_lshr_b32 s30, s23, 1
	s_cmp_eq_u32 s18, 0
	s_cselect_b32 s25, s30, s23
	s_sub_u32 s31, s18, 1
	s_cmp_lt_u32 s31, 2
	s_cselect_b32 s24, s30, 0
	s_cmp_eq_u32 s18, 2
	s_cselect_b32 s40, 0, 1.0
	s_mov_b32 s41, s40
	s_lshl_b32 s42, s21, 1
	s_add_u32 s42, s42, 0
	s_lshl_b32 s42, s42, 1
	s_add_u32 s42, s42, s20
	s_lshl_b32 s42, s42, 2
	s_add_u32 s42, s42, s19
	v_readlane_b32 s14, v246, 10
	v_readlane_b32 s15, v246, 11
	s_nop 4
	s_load_dwordx2 s[4:5], s[14:15], 0x178
	s_load_dwordx2 s[6:7], s[14:15], 0x188
	s_load_dwordx2 s[8:9], s[14:15], 0x198
	s_load_dwordx2 s[10:11], s[14:15], 0x98
	s_load_dwordx2 s[12:13], s[14:15], 0xc8
	s_load_dwordx2 s[26:27], s[14:15], 0xd0
	v_and_b32_e32 v87, 15, v226
	v_lshrrev_b32_e32 v127, 4, v226
	v_lshlrev_b32_e32 v95, 4, v87
	v_lshlrev_b32_e32 v108, 2, v127
	v_lshlrev_b32_e32 v110, 4, v226
	v_lshlrev_b32_e32 v115, 2, v226
	v_mul_u32_u24_e32 v1, 0x180, v127
	v_lshl_add_u32 v1, v87, 3, v1
	v_lshlrev_b32_e32 v2, 8, v127
	v_add_u32_e32 v3, v2, v95
	v_lshl_add_u32 v2, v87, 3, v2
	v_lshrrev_b32_e32 v89, 2, v87
	v_and_b32_e32 v90, 3, v87
	v_lshlrev_b32_e32 v91, 6, v127
	v_lshl_add_u32 v91, v90, 4, v91
	v_add_u32_e32 v91, 0x5000, v91
	v_add_u32_e32 v92, 0x9000, v110
	v_cmp_eq_u32_e32 vcc, s17, v89
	s_nop 1
	v_cndmask_b32_e32 v4, v92, v91, vcc
	s_mov_b32 s30, 0xaaaaaab
	s_lshl_b32 s31, s19, 7
	v_mul_hi_u32 v87, v226, s30
	v_mul_u32_u24_e32 v89, 24, v87
	v_sub_u32_e32 v89, v226, v89
	v_add_u32_e32 v15, -1, v87
	v_lshrrev_b32_e32 v90, 3, v89
	v_and_b32_e32 v89, 7, v89
	v_lshlrev_b32_e32 v90, 9, v90
	v_lshl_add_u32 v91, v89, 4, v90
	v_add_u32_e32 v91, s31, v91
	v_add_u32_e32 v91, 0xd20, v91
	s_add_u32 s34, s22, s29
	s_cmp_eq_u32 s20, 0
	s_cselect_b32 s34, s22, s34
	s_waitcnt lgkmcnt(0)
	s_mul_i32 s98, s34, 0x1520
	s_mul_hi_u32 s99, s34, 0x1520
	s_add_u32 s100, s4, s98
	s_addc_u32 s101, s5, s99
	s_mul_i32 s98, s34, 0xa00
	s_mul_hi_u32 s99, s34, 0xa00
	s_add_u32 s98, s6, s98
	s_addc_u32 s99, s7, s99
	v_mov_b32_e32 v92, 0
	v_mov_b32_e32 v6, s100
	v_mov_b32_e32 v7, s101
	v_add_co_u32_e32 v6, vcc, v6, v91
	s_nop 1
	v_addc_co_u32_e32 v7, vcc, 0, v7, vcc
	s_movk_i32 s36, 0x1520
	s_mul_i32 s37, s36, -1
	s_cmp_eq_u32 s20, 0
	s_cselect_b32 s34, s36, s37
	s_movk_i32 s36, 0xa00
	s_mul_i32 s37, s36, -1
	s_cselect_b32 s35, s36, s37
	v_mov_b32_e32 v12, s34
	v_add_u32_e32 v92, 0x100, v226
	v_mul_hi_u32 v87, v92, s30
	v_mul_u32_u24_e32 v89, 24, v87
	v_sub_u32_e32 v89, v92, v89
	v_add_u32_e32 v16, -1, v87
	v_lshrrev_b32_e32 v90, 3, v89
	v_and_b32_e32 v89, 7, v89
	v_lshlrev_b32_e32 v90, 9, v90
	v_lshl_add_u32 v91, v89, 4, v90
	v_add_u32_e32 v91, s31, v91
	v_add_u32_e32 v91, 0xd20, v91
	s_lshl_b32 s36, s20, 9
	s_add_u32 s36, s36, s31
	v_add_u32_e32 v92, 0xffffff50, v226
	v_lshrrev_b32_e32 v21, 4, v92
	v_and_b32_e32 v87, 15, v92
	v_lshrrev_b32_e32 v89, 3, v87
	v_and_b32_e32 v87, 7, v87
	v_lshlrev_b32_e32 v89, 10, v89
	v_lshl_add_u32 v90, v87, 4, v89
	v_add_u32_e32 v90, s36, v90
	v_cmp_gt_u32_e32 vcc, 0xb0, v226
	s_nop 1
	v_cndmask_b32_e32 v16, v21, v16, vcc
	v_cndmask_b32_e32 v91, v90, v91, vcc
	v_mov_b32_e32 v87, s35
	v_mov_b32_e32 v89, s34
	v_cndmask_b32_e32 v13, v87, v89, vcc
	v_mov_b32_e32 v87, s98
	v_mov_b32_e32 v89, s100
	v_cndmask_b32_e32 v8, v87, v89, vcc
	v_mov_b32_e32 v87, s99
	v_mov_b32_e32 v89, s101
	v_cndmask_b32_e32 v9, v87, v89, vcc
	v_add_co_u32_e32 v8, vcc, v8, v91
	s_nop 1
	v_addc_co_u32_e32 v9, vcc, 0, v9, vcc
	v_add_u32_e32 v92, 0x50, v226
	v_lshrrev_b32_e32 v17, 4, v92
	v_and_b32_e32 v87, 15, v92
	v_lshrrev_b32_e32 v89, 3, v87
	v_and_b32_e32 v87, 7, v87
	v_lshlrev_b32_e32 v89, 10, v89
	v_lshl_add_u32 v91, v87, 4, v89
	v_add_u32_e32 v91, s36, v91
	v_mov_b32_e32 v10, s98
	v_mov_b32_e32 v11, s99
	v_add_co_u32_e32 v10, vcc, v10, v91
	s_nop 1
	v_addc_co_u32_e32 v11, vcc, 0, v11, vcc
	v_mov_b32_e32 v14, s35
	s_add_u32 s30, s22, s29
	s_cmp_eq_u32 s20, 0
	s_cselect_b32 s30, s22, s30
	s_lshl_b32 s36, s19, 7
	s_lshl_b32 s37, s17, 5
	s_add_u32 s36, s36, s37
	s_cmp_eq_u32 s18, 2
	s_cbranch_scc1 .Lrw0_o_u2
	s_lshl_b32 s37, s20, 9
	s_add_u32 s36, s36, s37
	s_mul_i32 s98, s30, 0xa00
	s_mul_hi_u32 s99, s30, 0xa00
	s_add_u32 s98, s98, s36
	s_addc_u32 s99, s99, 0
	s_add_u32 s98, s8, s98
	s_addc_u32 s99, s9, s99
	s_movk_i32 s36, 0xa00
	s_mul_i32 s37, s36, -1
	s_cmp_eq_u32 s20, 0
	s_cselect_b32 s35, s36, s37
	s_branch .Lrw0_o_done
.Lrw0_o_u2:
	s_add_u32 s36, s36, 0x1320
	s_mul_i32 s98, s30, 0x1520
	s_mul_hi_u32 s99, s30, 0x1520
	s_add_u32 s98, s98, s36
	s_addc_u32 s99, s99, 0
	s_add_u32 s98, s4, s98
	s_addc_u32 s99, s5, s99
	s_movk_i32 s36, 0x1520
	s_mul_i32 s37, s36, -1
	s_cmp_eq_u32 s20, 0
	s_cselect_b32 s35, s36, s37
.Lrw0_o_done:
	v_and_b32_e32 v87, 15, v226
	v_lshlrev_b32_e32 v87, 1, v87
	v_mov_b32_e32 v18, s98
	v_mov_b32_e32 v19, s99
	v_add_co_u32_e32 v18, vcc, v18, v87
	s_nop 1
	v_addc_co_u32_e32 v19, vcc, 0, v19, vcc
	v_mov_b32_e32 v20, s35
	s_lshl_b32 s36, s19, 8
	s_add_u32 s98, s10, s36
	s_addc_u32 s99, s11, 0
	s_add_u32 s98, s98, 0x0
	s_addc_u32 s99, s99, 0
	global_load_dwordx4 v[26:29], v95, s[98:99]
	global_load_dwordx4 v[30:33], v95, s[98:99] offset:1024
	global_load_dwordx4 v[34:37], v95, s[98:99] offset:2048
	s_add_u32 s98, s12, s36
	s_addc_u32 s99, s13, 0
	s_add_u32 s100, s26, s36
	s_addc_u32 s101, s27, 0
	global_load_dwordx4 v[38:41], v95, s[98:99] offset:0
	global_load_dwordx4 v[42:45], v95, s[100:101] offset:0
	v_lshl_add_u32 v87, s17, 4, v127
	v_lshl_add_u32 v89, v87, 8, v95
	v_mov_b32_e32 v22, 0
	v_mov_b32_e32 v23, 0
	v_mov_b32_e32 v24, 0
	v_mov_b32_e32 v25, 0
	s_cmp_eq_u32 s18, 0
	s_cbranch_scc0 .Lrw0_s_not0
	s_load_dwordx2 s[36:37], s[14:15], 0x28
	s_waitcnt lgkmcnt(0)
	s_lshl_b32 s98, s42, 14
	s_add_u32 s36, s36, s98
	s_addc_u32 s37, s37, 0
	global_load_dwordx4 v[22:25], v89, s[36:37]
	s_branch .Lrw0_s_done
.Lrw0_s_not0:
	s_cmp_eq_u32 s18, 2
	s_cbranch_scc0 .Lrw0_s_done
	v_lshrrev_b32_e32 v90, 2, v95
	v_add_u32_e32 v91, 0, v90
	v_cmp_eq_u32_e32 vcc, v91, v87
	s_nop 1
	v_cndmask_b32_e64 v22, 0, 1.0, vcc
	v_add_u32_e32 v91, 1, v90
	v_cmp_eq_u32_e32 vcc, v91, v87
	s_nop 1
	v_cndmask_b32_e64 v23, 0, 1.0, vcc
	v_add_u32_e32 v91, 2, v90
	v_cmp_eq_u32_e32 vcc, v91, v87
	s_nop 1
	v_cndmask_b32_e64 v24, 0, 1.0, vcc
	v_add_u32_e32 v91, 3, v90
	v_cmp_eq_u32_e32 vcc, v91, v87
	s_nop 1
	v_cndmask_b32_e64 v25, 0, 1.0, vcc
.Lrw0_s_done:
	s_mov_b32 s28, s24
	s_mov_b32 s30, s24
	v_add_u32_e32 v87, s30, v15
	v_med3_i32 v87, v87, 0, s29
	v_mad_i64_i32 v[104:105], vcc, v87, v12, v[6:7]
	global_load_dwordx4 v[46:49], v[104:105], off
	v_add_u32_e32 v87, s30, v16
	v_med3_i32 v87, v87, 0, s29
	v_mad_i64_i32 v[104:105], vcc, v87, v13, v[8:9]
	global_load_dwordx4 v[50:53], v[104:105], off
	v_add_u32_e32 v87, s30, v17
	v_med3_i32 v87, v87, 0, s29
	v_mad_i64_i32 v[104:105], vcc, v87, v14, v[10:11]
	global_load_dwordx4 v[54:57], v[104:105], off
	s_add_u32 s30, s24, 16
	v_add_u32_e32 v87, s30, v15
	v_med3_i32 v87, v87, 0, s29
	v_mad_i64_i32 v[104:105], vcc, v87, v12, v[6:7]
	global_load_dwordx4 v[58:61], v[104:105], off
	v_add_u32_e32 v87, s30, v16
	v_med3_i32 v87, v87, 0, s29
	v_mad_i64_i32 v[104:105], vcc, v87, v13, v[8:9]
	global_load_dwordx4 v[62:65], v[104:105], off
	v_add_u32_e32 v87, s30, v17
	v_med3_i32 v87, v87, 0, s29
	v_mad_i64_i32 v[104:105], vcc, v87, v14, v[10:11]
	global_load_dwordx4 v[66:69], v[104:105], off
	s_mov_b32 s35, 0
.Lrw0_loop:
	s_waitcnt vmcnt(0)
	ds_write_b128 v110, v[46:49] offset:23552
	ds_write_b128 v110, v[50:53] offset:27648
	ds_write_b128 v110, v[54:57] offset:31744
	s_waitcnt lgkmcnt(0)
	s_barrier
	s_add_u32 s30, s28, 32
	v_add_u32_e32 v87, s30, v15
	v_med3_i32 v87, v87, 0, s29
	v_mad_i64_i32 v[104:105], vcc, v87, v12, v[6:7]
	global_load_dwordx4 v[46:49], v[104:105], off
	v_add_u32_e32 v87, s30, v16
	v_med3_i32 v87, v87, 0, s29
	v_mad_i64_i32 v[104:105], vcc, v87, v13, v[8:9]
	global_load_dwordx4 v[50:53], v[104:105], off
	v_add_u32_e32 v87, s30, v17
	v_med3_i32 v87, v87, 0, s29
	v_mad_i64_i32 v[104:105], vcc, v87, v14, v[10:11]
	global_load_dwordx4 v[54:57], v[104:105], off
	s_cmp_eq_u32 s35, 0
	s_cbranch_scc1 .Lrw0_noout
	ds_read_b32 v89, v115 offset:22528
	s_sub_u32 s98, s28, 16
	v_add_u32_e32 v87, s98, v127
	v_mad_i64_i32 v[104:105], vcc, v87, v20, v[18:19]
	s_waitcnt lgkmcnt(0)
	v_cvt_pk_bf16_f32 v89, v89, v89
	global_store_short v[104:105], v89, off
.Lrw0_noout:
	ds_read_b64 v[70:71], v1 offset:23936
	ds_read_b64 v[72:73], v1 offset:23552
	ds_read_b64 v[74:75], v1 offset:24320
	ds_read_b64 v[76:77], v1 offset:24064
	ds_read_b64 v[78:79], v1 offset:23680
	ds_read_b64 v[80:81], v1 offset:24448
	ds_read_b64 v[82:83], v1 offset:24192
	ds_read_b64 v[84:85], v1 offset:23808
	ds_read_b64 v[96:97], v1 offset:24576
	ds_read_b64 v[128:129], v2 offset:30464
	ds_read_b64 v[130:131], v2 offset:30592
	v_add_u32_e32 v87, s28, v127
	v_cmp_ne_u32_e32 vcc, 0, v87
	s_nop 1
	v_cndmask_b32_e64 v98, 0, 0.5, vcc
	v_cmp_ne_u32_e32 vcc, s29, v87
	s_nop 1
	v_cndmask_b32_e64 v100, 0, 0.5, vcc
	s_waitcnt lgkmcnt(8)
	v_lshlrev_b32_e32 v132, 16, v70
	v_and_b32_e32 v133, 0xffff0000, v70
	v_lshlrev_b32_e32 v134, 16, v71
	v_and_b32_e32 v135, 0xffff0000, v71
	v_lshlrev_b32_e32 v136, 16, v72
	v_and_b32_e32 v137, 0xffff0000, v72
	v_lshlrev_b32_e32 v138, 16, v73
	v_and_b32_e32 v139, 0xffff0000, v73
	v_lshlrev_b32_e32 v140, 16, v74
	v_and_b32_e32 v141, 0xffff0000, v74
	v_lshlrev_b32_e32 v142, 16, v75
	v_and_b32_e32 v143, 0xffff0000, v75
	v_pk_mul_f32 v[136:137], v[136:137], v[98:99] op_sel_hi:[1,0]
	v_pk_fma_f32 v[136:137], v[140:141], v[100:101], v[136:137] op_sel_hi:[1,0,1]
	v_pk_add_f32 v[136:137], v[136:137], v[132:133] neg_lo:[0,1] neg_hi:[0,1]
	v_pk_fma_f32 v[144:145], v[26:27], v[136:137], v[132:133]
	v_pk_mul_f32 v[138:139], v[138:139], v[98:99] op_sel_hi:[1,0]
	v_pk_fma_f32 v[138:139], v[142:143], v[100:101], v[138:139] op_sel_hi:[1,0,1]
	v_pk_add_f32 v[138:139], v[138:139], v[134:135] neg_lo:[0,1] neg_hi:[0,1]
	v_pk_fma_f32 v[146:147], v[28:29], v[138:139], v[134:135]
	s_waitcnt lgkmcnt(5)
	v_lshlrev_b32_e32 v132, 16, v76
	v_and_b32_e32 v133, 0xffff0000, v76
	v_lshlrev_b32_e32 v134, 16, v77
	v_and_b32_e32 v135, 0xffff0000, v77
	v_lshlrev_b32_e32 v136, 16, v78
	v_and_b32_e32 v137, 0xffff0000, v78
	v_lshlrev_b32_e32 v138, 16, v79
	v_and_b32_e32 v139, 0xffff0000, v79
	v_lshlrev_b32_e32 v140, 16, v80
	v_and_b32_e32 v141, 0xffff0000, v80
	v_lshlrev_b32_e32 v142, 16, v81
	v_and_b32_e32 v143, 0xffff0000, v81
	v_pk_mul_f32 v[136:137], v[136:137], v[98:99] op_sel_hi:[1,0]
	v_pk_fma_f32 v[136:137], v[140:141], v[100:101], v[136:137] op_sel_hi:[1,0,1]
	v_pk_add_f32 v[136:137], v[136:137], v[132:133] neg_lo:[0,1] neg_hi:[0,1]
	v_pk_fma_f32 v[102:103], v[30:31], v[136:137], v[132:133]
	v_pk_mul_f32 v[138:139], v[138:139], v[98:99] op_sel_hi:[1,0]
	v_pk_fma_f32 v[138:139], v[142:143], v[100:101], v[138:139] op_sel_hi:[1,0,1]
	v_pk_add_f32 v[138:139], v[138:139], v[134:135] neg_lo:[0,1] neg_hi:[0,1]
	v_pk_fma_f32 v[104:105], v[32:33], v[138:139], v[134:135]
	s_waitcnt lgkmcnt(2)
	v_lshlrev_b32_e32 v132, 16, v82
	v_and_b32_e32 v133, 0xffff0000, v82
	v_lshlrev_b32_e32 v134, 16, v83
	v_and_b32_e32 v135, 0xffff0000, v83
	v_lshlrev_b32_e32 v136, 16, v84
	v_and_b32_e32 v137, 0xffff0000, v84
	v_lshlrev_b32_e32 v138, 16, v85
	v_and_b32_e32 v139, 0xffff0000, v85
	v_lshlrev_b32_e32 v140, 16, v96
	v_and_b32_e32 v141, 0xffff0000, v96
	v_lshlrev_b32_e32 v142, 16, v97
	v_and_b32_e32 v143, 0xffff0000, v97
	v_pk_mul_f32 v[136:137], v[136:137], v[98:99] op_sel_hi:[1,0]
	v_pk_fma_f32 v[136:137], v[140:141], v[100:101], v[136:137] op_sel_hi:[1,0,1]
	v_pk_add_f32 v[136:137], v[136:137], v[132:133] neg_lo:[0,1] neg_hi:[0,1]
	v_pk_fma_f32 v[148:149], v[34:35], v[136:137], v[132:133]
	v_pk_mul_f32 v[138:139], v[138:139], v[98:99] op_sel_hi:[1,0]
	v_pk_fma_f32 v[138:139], v[142:143], v[100:101], v[138:139] op_sel_hi:[1,0,1]
	v_pk_add_f32 v[138:139], v[138:139], v[134:135] neg_lo:[0,1] neg_hi:[0,1]
	v_pk_fma_f32 v[150:151], v[36:37], v[138:139], v[134:135]
	s_waitcnt lgkmcnt(0)
	v_lshlrev_b32_e32 v132, 16, v128
	v_and_b32_e32 v133, 0xffff0000, v128
	v_lshlrev_b32_e32 v134, 16, v129
	v_and_b32_e32 v135, 0xffff0000, v129
	v_lshlrev_b32_e32 v136, 16, v130
	v_and_b32_e32 v137, 0xffff0000, v130
	v_lshlrev_b32_e32 v138, 16, v131
	v_and_b32_e32 v139, 0xffff0000, v131
	s_mov_b32 s98, 0xbf60028b
	v_mul_f32_e32 v132, s98, v132
	v_mul_f32_e32 v133, s98, v133
	v_mul_f32_e32 v134, s98, v134
	v_mul_f32_e32 v135, s98, v135
	v_exp_f32_e32 v132, v132
	v_exp_f32_e32 v133, v133
	v_exp_f32_e32 v134, v134
	v_exp_f32_e32 v135, v135
	v_pk_mul_f32 v[140:141], v[102:103], v[38:39]
	v_pk_mul_f32 v[142:143], v[104:105], v[40:41]
	v_pk_mul_f32 v[106:107], v[140:141], v[140:141]
	v_pk_fma_f32 v[106:107], v[142:143], v[142:143], v[106:107]
	v_add_f32_e32 v106, v106, v107
	s_nop 1
	v_add_f32_dpp v106, v106, v106 row_ror:8 row_mask:0xf bank_mask:0xf bound_ctrl:1
	s_nop 1
	v_add_f32_dpp v106, v106, v106 row_ror:4 row_mask:0xf bank_mask:0xf bound_ctrl:1
	s_nop 1
	v_add_f32_dpp v106, v106, v106 row_ror:2 row_mask:0xf bank_mask:0xf bound_ctrl:1
	s_nop 1
	v_add_f32_dpp v106, v106, v106 row_ror:1 row_mask:0xf bank_mask:0xf bound_ctrl:1
	v_add_f32_e32 v106, 0x2b8cbccc, v106
	v_rsq_f32_e32 v106, v106
	v_pk_mul_f32 v[148:149], v[148:149], s[40:41] op_sel_hi:[1,0]
	v_pk_mul_f32 v[150:151], v[150:151], s[40:41] op_sel_hi:[1,0]
	v_pk_mul_f32 v[140:141], v[140:141], v[106:107] op_sel_hi:[1,0]
	v_pk_mul_f32 v[142:143], v[142:143], v[106:107] op_sel_hi:[1,0]
	v_pk_add_f32 v[70:71], v[136:137], -1.0 op_sel_hi:[1,0]
	v_pk_add_f32 v[72:73], v[138:139], -1.0 op_sel_hi:[1,0]
	v_pk_fma_f32 v[70:71], v[42:43], v[70:71], 1.0 op_sel_hi:[1,1,0]
	v_pk_fma_f32 v[72:73], v[44:45], v[72:73], 1.0 op_sel_hi:[1,1,0]
	v_pk_mul_f32 v[70:71], v[102:103], v[70:71]
	v_pk_mul_f32 v[72:73], v[104:105], v[72:73]
	v_pk_mul_f32 v[74:75], v[140:141], v[136:137]
	v_pk_mul_f32 v[76:77], v[142:143], v[138:139]
	ds_write_b128 v3, v[140:143] offset:0
	ds_write_b128 v3, v[132:135] offset:4096
	ds_write_b128 v3, v[74:77] offset:8192
	ds_write_b128 v3, v[70:73] offset:12288
	ds_write_b128 v3, v[144:147] offset:16384
	ds_write_b128 v4, v[148:151]
	s_waitcnt lgkmcnt(0)
	s_barrier
	ds_read_b128 v[70:73], v95 offset:0
	ds_read_b128 v[82:85], v95 offset:12288
	ds_read_b32 v100, v108 offset:20480
	ds_read_b128 v[74:77], v95 offset:4096
	ds_read_b128 v[78:81], v95 offset:8192
	ds_read_b128 v[96:99], v95 offset:16384
	s_waitcnt lgkmcnt(5)
	v_pk_mul_f32 v[102:103], v[22:23], v[70:71]
	s_waitcnt lgkmcnt(3)
	v_pk_mul_f32 v[104:105], v[82:83], v[100:101] op_sel_hi:[1,0]
	v_pk_fma_f32 v[102:103], v[24:25], v[72:73], v[102:103]
	v_pk_mul_f32 v[106:107], v[84:85], v[100:101] op_sel_hi:[1,0]
	v_add_f32_e32 v112, v102, v103
	s_waitcnt lgkmcnt(2)
	v_pk_fma_f32 v[104:105], v[22:23], v[74:75], v[104:105]
	v_pk_fma_f32 v[106:107], v[24:25], v[76:77], v[106:107]
	v_add_f32_dpp v112, v112, v112 row_ror:8 row_mask:0xf bank_mask:0xf bound_ctrl:1
	ds_read_b128 v[128:131], v95 offset:256
	s_nop 0
	v_add_f32_dpp v112, v112, v112 row_ror:4 row_mask:0xf bank_mask:0xf bound_ctrl:1
	ds_read_b128 v[140:143], v95 offset:12544
	s_nop 0
	v_add_f32_dpp v112, v112, v112 row_ror:2 row_mask:0xf bank_mask:0xf bound_ctrl:1
	ds_read_b32 v148, v108 offset:20544
	s_nop 0
	v_add_f32_dpp v112, v112, v112 row_ror:1 row_mask:0xf bank_mask:0xf bound_ctrl:1
	ds_read_b128 v[132:135], v95 offset:4352
	ds_read_b128 v[136:139], v95 offset:8448
	ds_read_b128 v[144:147], v95 offset:16640
	s_waitcnt lgkmcnt(7)
	v_pk_fma_f32 v[22:23], v[112:113], v[78:79], v[104:105] op_sel_hi:[0,1,1] neg_lo:[1,0,0] neg_hi:[1,0,0]
	v_pk_fma_f32 v[24:25], v[112:113], v[80:81], v[106:107] op_sel_hi:[0,1,1] neg_lo:[1,0,0] neg_hi:[1,0,0]
	s_waitcnt lgkmcnt(5)
	v_pk_mul_f32 v[102:103], v[22:23], v[128:129]
	s_waitcnt lgkmcnt(3)
	v_pk_mul_f32 v[104:105], v[140:141], v[148:149] op_sel_hi:[1,0]
	v_pk_fma_f32 v[102:103], v[24:25], v[130:131], v[102:103]
	v_pk_mul_f32 v[106:107], v[142:143], v[148:149] op_sel_hi:[1,0]
	v_pk_mul_f32 v[150:151], v[96:97], v[22:23]
	v_add_f32_e32 v112, v102, v103
	v_pk_fma_f32 v[150:151], v[98:99], v[24:25], v[150:151]
	s_waitcnt lgkmcnt(2)
	v_pk_fma_f32 v[104:105], v[22:23], v[132:133], v[104:105]
	v_add_f32_e32 v114, v150, v151
	v_pk_fma_f32 v[106:107], v[24:25], v[134:135], v[106:107]
	v_add_f32_dpp v112, v112, v112 row_ror:8 row_mask:0xf bank_mask:0xf bound_ctrl:1
	v_add_f32_dpp v114, v114, v114 row_ror:8 row_mask:0xf bank_mask:0xf bound_ctrl:1
	ds_read_b128 v[70:73], v95 offset:512
	v_add_f32_dpp v112, v112, v112 row_ror:4 row_mask:0xf bank_mask:0xf bound_ctrl:1
	v_add_f32_dpp v114, v114, v114 row_ror:4 row_mask:0xf bank_mask:0xf bound_ctrl:1
	ds_read_b128 v[82:85], v95 offset:12800
	v_add_f32_dpp v112, v112, v112 row_ror:2 row_mask:0xf bank_mask:0xf bound_ctrl:1
	v_add_f32_dpp v114, v114, v114 row_ror:2 row_mask:0xf bank_mask:0xf bound_ctrl:1
	ds_read_b32 v100, v108 offset:20608
	v_add_f32_dpp v112, v112, v112 row_ror:1 row_mask:0xf bank_mask:0xf bound_ctrl:1
	v_add_f32_dpp v114, v114, v114 row_ror:1 row_mask:0xf bank_mask:0xf bound_ctrl:1
	ds_read_b128 v[74:77], v95 offset:4608
	ds_read_b128 v[78:81], v95 offset:8704
	ds_read_b128 v[96:99], v95 offset:16896
	s_waitcnt lgkmcnt(7)
	v_pk_fma_f32 v[22:23], v[112:113], v[136:137], v[104:105] op_sel_hi:[0,1,1] neg_lo:[1,0,0] neg_hi:[1,0,0]
	v_pk_fma_f32 v[24:25], v[112:113], v[138:139], v[106:107] op_sel_hi:[0,1,1] neg_lo:[1,0,0] neg_hi:[1,0,0]
	ds_write_b32 v108, v114 offset:21504
	s_waitcnt lgkmcnt(6)
	v_pk_mul_f32 v[102:103], v[22:23], v[70:71]
	s_waitcnt lgkmcnt(4)
	v_pk_mul_f32 v[104:105], v[82:83], v[100:101] op_sel_hi:[1,0]
	v_pk_fma_f32 v[102:103], v[24:25], v[72:73], v[102:103]
	v_pk_mul_f32 v[106:107], v[84:85], v[100:101] op_sel_hi:[1,0]
	v_pk_mul_f32 v[150:151], v[144:145], v[22:23]
	v_add_f32_e32 v112, v102, v103
	v_pk_fma_f32 v[150:151], v[146:147], v[24:25], v[150:151]
	s_waitcnt lgkmcnt(3)
	v_pk_fma_f32 v[104:105], v[22:23], v[74:75], v[104:105]
	v_add_f32_e32 v114, v150, v151
	v_pk_fma_f32 v[106:107], v[24:25], v[76:77], v[106:107]
	v_add_f32_dpp v112, v112, v112 row_ror:8 row_mask:0xf bank_mask:0xf bound_ctrl:1
	v_add_f32_dpp v114, v114, v114 row_ror:8 row_mask:0xf bank_mask:0xf bound_ctrl:1
	ds_read_b128 v[128:131], v95 offset:768
	v_add_f32_dpp v112, v112, v112 row_ror:4 row_mask:0xf bank_mask:0xf bound_ctrl:1
	v_add_f32_dpp v114, v114, v114 row_ror:4 row_mask:0xf bank_mask:0xf bound_ctrl:1
	ds_read_b128 v[140:143], v95 offset:13056
	v_add_f32_dpp v112, v112, v112 row_ror:2 row_mask:0xf bank_mask:0xf bound_ctrl:1
	v_add_f32_dpp v114, v114, v114 row_ror:2 row_mask:0xf bank_mask:0xf bound_ctrl:1
	ds_read_b32 v148, v108 offset:20672
	v_add_f32_dpp v112, v112, v112 row_ror:1 row_mask:0xf bank_mask:0xf bound_ctrl:1
	v_add_f32_dpp v114, v114, v114 row_ror:1 row_mask:0xf bank_mask:0xf bound_ctrl:1
	ds_read_b128 v[132:135], v95 offset:4864
	ds_read_b128 v[136:139], v95 offset:8960
	ds_read_b128 v[144:147], v95 offset:17152
	s_waitcnt lgkmcnt(8)
	v_pk_fma_f32 v[22:23], v[112:113], v[78:79], v[104:105] op_sel_hi:[0,1,1] neg_lo:[1,0,0] neg_hi:[1,0,0]
	v_pk_fma_f32 v[24:25], v[112:113], v[80:81], v[106:107] op_sel_hi:[0,1,1] neg_lo:[1,0,0] neg_hi:[1,0,0]
	ds_write_b32 v108, v114 offset:21568
	s_waitcnt lgkmcnt(6)
	v_pk_mul_f32 v[102:103], v[22:23], v[128:129]
	s_waitcnt lgkmcnt(4)
	v_pk_mul_f32 v[104:105], v[140:141], v[148:149] op_sel_hi:[1,0]
	v_pk_fma_f32 v[102:103], v[24:25], v[130:131], v[102:103]
	v_pk_mul_f32 v[106:107], v[142:143], v[148:149] op_sel_hi:[1,0]
	v_pk_mul_f32 v[150:151], v[96:97], v[22:23]
	v_add_f32_e32 v112, v102, v103
	v_pk_fma_f32 v[150:151], v[98:99], v[24:25], v[150:151]
	s_waitcnt lgkmcnt(3)
	v_pk_fma_f32 v[104:105], v[22:23], v[132:133], v[104:105]
	v_add_f32_e32 v114, v150, v151
	v_pk_fma_f32 v[106:107], v[24:25], v[134:135], v[106:107]
	v_add_f32_dpp v112, v112, v112 row_ror:8 row_mask:0xf bank_mask:0xf bound_ctrl:1
	v_add_f32_dpp v114, v114, v114 row_ror:8 row_mask:0xf bank_mask:0xf bound_ctrl:1
	ds_read_b128 v[70:73], v95 offset:1024
	v_add_f32_dpp v112, v112, v112 row_ror:4 row_mask:0xf bank_mask:0xf bound_ctrl:1
	v_add_f32_dpp v114, v114, v114 row_ror:4 row_mask:0xf bank_mask:0xf bound_ctrl:1
	ds_read_b128 v[82:85], v95 offset:13312
	v_add_f32_dpp v112, v112, v112 row_ror:2 row_mask:0xf bank_mask:0xf bound_ctrl:1
	v_add_f32_dpp v114, v114, v114 row_ror:2 row_mask:0xf bank_mask:0xf bound_ctrl:1
	ds_read_b32 v100, v108 offset:20736
	v_add_f32_dpp v112, v112, v112 row_ror:1 row_mask:0xf bank_mask:0xf bound_ctrl:1
	v_add_f32_dpp v114, v114, v114 row_ror:1 row_mask:0xf bank_mask:0xf bound_ctrl:1
	ds_read_b128 v[74:77], v95 offset:5120
	ds_read_b128 v[78:81], v95 offset:9216
	ds_read_b128 v[96:99], v95 offset:17408
	s_waitcnt lgkmcnt(8)
	v_pk_fma_f32 v[22:23], v[112:113], v[136:137], v[104:105] op_sel_hi:[0,1,1] neg_lo:[1,0,0] neg_hi:[1,0,0]
	v_pk_fma_f32 v[24:25], v[112:113], v[138:139], v[106:107] op_sel_hi:[0,1,1] neg_lo:[1,0,0] neg_hi:[1,0,0]
	ds_write_b32 v108, v114 offset:21632
	s_waitcnt lgkmcnt(6)
	v_pk_mul_f32 v[102:103], v[22:23], v[70:71]
	s_waitcnt lgkmcnt(4)
	v_pk_mul_f32 v[104:105], v[82:83], v[100:101] op_sel_hi:[1,0]
	v_pk_fma_f32 v[102:103], v[24:25], v[72:73], v[102:103]
	v_pk_mul_f32 v[106:107], v[84:85], v[100:101] op_sel_hi:[1,0]
	v_pk_mul_f32 v[150:151], v[144:145], v[22:23]
	v_add_f32_e32 v112, v102, v103
	v_pk_fma_f32 v[150:151], v[146:147], v[24:25], v[150:151]
	s_waitcnt lgkmcnt(3)
	v_pk_fma_f32 v[104:105], v[22:23], v[74:75], v[104:105]
	v_add_f32_e32 v114, v150, v151
	v_pk_fma_f32 v[106:107], v[24:25], v[76:77], v[106:107]
	v_add_f32_dpp v112, v112, v112 row_ror:8 row_mask:0xf bank_mask:0xf bound_ctrl:1
	v_add_f32_dpp v114, v114, v114 row_ror:8 row_mask:0xf bank_mask:0xf bound_ctrl:1
	ds_read_b128 v[128:131], v95 offset:1280
	v_add_f32_dpp v112, v112, v112 row_ror:4 row_mask:0xf bank_mask:0xf bound_ctrl:1
	v_add_f32_dpp v114, v114, v114 row_ror:4 row_mask:0xf bank_mask:0xf bound_ctrl:1
	ds_read_b128 v[140:143], v95 offset:13568
	v_add_f32_dpp v112, v112, v112 row_ror:2 row_mask:0xf bank_mask:0xf bound_ctrl:1
	v_add_f32_dpp v114, v114, v114 row_ror:2 row_mask:0xf bank_mask:0xf bound_ctrl:1
	ds_read_b32 v148, v108 offset:20800
	v_add_f32_dpp v112, v112, v112 row_ror:1 row_mask:0xf bank_mask:0xf bound_ctrl:1
	v_add_f32_dpp v114, v114, v114 row_ror:1 row_mask:0xf bank_mask:0xf bound_ctrl:1
	ds_read_b128 v[132:135], v95 offset:5376
	ds_read_b128 v[136:139], v95 offset:9472
	ds_read_b128 v[144:147], v95 offset:17664
	s_waitcnt lgkmcnt(8)
	v_pk_fma_f32 v[22:23], v[112:113], v[78:79], v[104:105] op_sel_hi:[0,1,1] neg_lo:[1,0,0] neg_hi:[1,0,0]
	v_pk_fma_f32 v[24:25], v[112:113], v[80:81], v[106:107] op_sel_hi:[0,1,1] neg_lo:[1,0,0] neg_hi:[1,0,0]
	ds_write_b32 v108, v114 offset:21696
	s_waitcnt lgkmcnt(6)
	v_pk_mul_f32 v[102:103], v[22:23], v[128:129]
	s_waitcnt lgkmcnt(4)
	v_pk_mul_f32 v[104:105], v[140:141], v[148:149] op_sel_hi:[1,0]
	v_pk_fma_f32 v[102:103], v[24:25], v[130:131], v[102:103]
	v_pk_mul_f32 v[106:107], v[142:143], v[148:149] op_sel_hi:[1,0]
	v_pk_mul_f32 v[150:151], v[96:97], v[22:23]
	v_add_f32_e32 v112, v102, v103
	v_pk_fma_f32 v[150:151], v[98:99], v[24:25], v[150:151]
	s_waitcnt lgkmcnt(3)
	v_pk_fma_f32 v[104:105], v[22:23], v[132:133], v[104:105]
	v_add_f32_e32 v114, v150, v151
	v_pk_fma_f32 v[106:107], v[24:25], v[134:135], v[106:107]
	v_add_f32_dpp v112, v112, v112 row_ror:8 row_mask:0xf bank_mask:0xf bound_ctrl:1
	v_add_f32_dpp v114, v114, v114 row_ror:8 row_mask:0xf bank_mask:0xf bound_ctrl:1
	ds_read_b128 v[70:73], v95 offset:1536
	v_add_f32_dpp v112, v112, v112 row_ror:4 row_mask:0xf bank_mask:0xf bound_ctrl:1
	v_add_f32_dpp v114, v114, v114 row_ror:4 row_mask:0xf bank_mask:0xf bound_ctrl:1
	ds_read_b128 v[82:85], v95 offset:13824
	v_add_f32_dpp v112, v112, v112 row_ror:2 row_mask:0xf bank_mask:0xf bound_ctrl:1
	v_add_f32_dpp v114, v114, v114 row_ror:2 row_mask:0xf bank_mask:0xf bound_ctrl:1
	ds_read_b32 v100, v108 offset:20864
	v_add_f32_dpp v112, v112, v112 row_ror:1 row_mask:0xf bank_mask:0xf bound_ctrl:1
	v_add_f32_dpp v114, v114, v114 row_ror:1 row_mask:0xf bank_mask:0xf bound_ctrl:1
	ds_read_b128 v[74:77], v95 offset:5632
	ds_read_b128 v[78:81], v95 offset:9728
	ds_read_b128 v[96:99], v95 offset:17920
	s_waitcnt lgkmcnt(8)
	v_pk_fma_f32 v[22:23], v[112:113], v[136:137], v[104:105] op_sel_hi:[0,1,1] neg_lo:[1,0,0] neg_hi:[1,0,0]
	v_pk_fma_f32 v[24:25], v[112:113], v[138:139], v[106:107] op_sel_hi:[0,1,1] neg_lo:[1,0,0] neg_hi:[1,0,0]
	ds_write_b32 v108, v114 offset:21760
	s_waitcnt lgkmcnt(6)
	v_pk_mul_f32 v[102:103], v[22:23], v[70:71]
	s_waitcnt lgkmcnt(4)
	v_pk_mul_f32 v[104:105], v[82:83], v[100:101] op_sel_hi:[1,0]
	v_pk_fma_f32 v[102:103], v[24:25], v[72:73], v[102:103]
	v_pk_mul_f32 v[106:107], v[84:85], v[100:101] op_sel_hi:[1,0]
	v_pk_mul_f32 v[150:151], v[144:145], v[22:23]
	v_add_f32_e32 v112, v102, v103
	v_pk_fma_f32 v[150:151], v[146:147], v[24:25], v[150:151]
	s_waitcnt lgkmcnt(3)
	v_pk_fma_f32 v[104:105], v[22:23], v[74:75], v[104:105]
	v_add_f32_e32 v114, v150, v151
	v_pk_fma_f32 v[106:107], v[24:25], v[76:77], v[106:107]
	v_add_f32_dpp v112, v112, v112 row_ror:8 row_mask:0xf bank_mask:0xf bound_ctrl:1
	v_add_f32_dpp v114, v114, v114 row_ror:8 row_mask:0xf bank_mask:0xf bound_ctrl:1
	ds_read_b128 v[128:131], v95 offset:1792
	v_add_f32_dpp v112, v112, v112 row_ror:4 row_mask:0xf bank_mask:0xf bound_ctrl:1
	v_add_f32_dpp v114, v114, v114 row_ror:4 row_mask:0xf bank_mask:0xf bound_ctrl:1
	ds_read_b128 v[140:143], v95 offset:14080
	v_add_f32_dpp v112, v112, v112 row_ror:2 row_mask:0xf bank_mask:0xf bound_ctrl:1
	v_add_f32_dpp v114, v114, v114 row_ror:2 row_mask:0xf bank_mask:0xf bound_ctrl:1
	ds_read_b32 v148, v108 offset:20928
	v_add_f32_dpp v112, v112, v112 row_ror:1 row_mask:0xf bank_mask:0xf bound_ctrl:1
	v_add_f32_dpp v114, v114, v114 row_ror:1 row_mask:0xf bank_mask:0xf bound_ctrl:1
	ds_read_b128 v[132:135], v95 offset:5888
	ds_read_b128 v[136:139], v95 offset:9984
	ds_read_b128 v[144:147], v95 offset:18176
	s_waitcnt lgkmcnt(8)
	v_pk_fma_f32 v[22:23], v[112:113], v[78:79], v[104:105] op_sel_hi:[0,1,1] neg_lo:[1,0,0] neg_hi:[1,0,0]
	v_pk_fma_f32 v[24:25], v[112:113], v[80:81], v[106:107] op_sel_hi:[0,1,1] neg_lo:[1,0,0] neg_hi:[1,0,0]
	ds_write_b32 v108, v114 offset:21824
	s_waitcnt lgkmcnt(6)
	v_pk_mul_f32 v[102:103], v[22:23], v[128:129]
	s_waitcnt lgkmcnt(4)
	v_pk_mul_f32 v[104:105], v[140:141], v[148:149] op_sel_hi:[1,0]
	v_pk_fma_f32 v[102:103], v[24:25], v[130:131], v[102:103]
	v_pk_mul_f32 v[106:107], v[142:143], v[148:149] op_sel_hi:[1,0]
	v_pk_mul_f32 v[150:151], v[96:97], v[22:23]
	v_add_f32_e32 v112, v102, v103
	v_pk_fma_f32 v[150:151], v[98:99], v[24:25], v[150:151]
	s_waitcnt lgkmcnt(3)
	v_pk_fma_f32 v[104:105], v[22:23], v[132:133], v[104:105]
	v_add_f32_e32 v114, v150, v151
	v_pk_fma_f32 v[106:107], v[24:25], v[134:135], v[106:107]
	v_add_f32_dpp v112, v112, v112 row_ror:8 row_mask:0xf bank_mask:0xf bound_ctrl:1
	v_add_f32_dpp v114, v114, v114 row_ror:8 row_mask:0xf bank_mask:0xf bound_ctrl:1
	ds_read_b128 v[70:73], v95 offset:2048
	v_add_f32_dpp v112, v112, v112 row_ror:4 row_mask:0xf bank_mask:0xf bound_ctrl:1
	v_add_f32_dpp v114, v114, v114 row_ror:4 row_mask:0xf bank_mask:0xf bound_ctrl:1
	ds_read_b128 v[82:85], v95 offset:14336
	v_add_f32_dpp v112, v112, v112 row_ror:2 row_mask:0xf bank_mask:0xf bound_ctrl:1
	v_add_f32_dpp v114, v114, v114 row_ror:2 row_mask:0xf bank_mask:0xf bound_ctrl:1
	ds_read_b32 v100, v108 offset:20992
	v_add_f32_dpp v112, v112, v112 row_ror:1 row_mask:0xf bank_mask:0xf bound_ctrl:1
	v_add_f32_dpp v114, v114, v114 row_ror:1 row_mask:0xf bank_mask:0xf bound_ctrl:1
	ds_read_b128 v[74:77], v95 offset:6144
	ds_read_b128 v[78:81], v95 offset:10240
	ds_read_b128 v[96:99], v95 offset:18432
	s_waitcnt lgkmcnt(8)
	v_pk_fma_f32 v[22:23], v[112:113], v[136:137], v[104:105] op_sel_hi:[0,1,1] neg_lo:[1,0,0] neg_hi:[1,0,0]
	v_pk_fma_f32 v[24:25], v[112:113], v[138:139], v[106:107] op_sel_hi:[0,1,1] neg_lo:[1,0,0] neg_hi:[1,0,0]
	ds_write_b32 v108, v114 offset:21888
	s_waitcnt lgkmcnt(6)
	v_pk_mul_f32 v[102:103], v[22:23], v[70:71]
	s_waitcnt lgkmcnt(4)
	v_pk_mul_f32 v[104:105], v[82:83], v[100:101] op_sel_hi:[1,0]
	v_pk_fma_f32 v[102:103], v[24:25], v[72:73], v[102:103]
	v_pk_mul_f32 v[106:107], v[84:85], v[100:101] op_sel_hi:[1,0]
	v_pk_mul_f32 v[150:151], v[144:145], v[22:23]
	v_add_f32_e32 v112, v102, v103
	v_pk_fma_f32 v[150:151], v[146:147], v[24:25], v[150:151]
	s_waitcnt lgkmcnt(3)
	v_pk_fma_f32 v[104:105], v[22:23], v[74:75], v[104:105]
	v_add_f32_e32 v114, v150, v151
	v_pk_fma_f32 v[106:107], v[24:25], v[76:77], v[106:107]
	v_add_f32_dpp v112, v112, v112 row_ror:8 row_mask:0xf bank_mask:0xf bound_ctrl:1
	v_add_f32_dpp v114, v114, v114 row_ror:8 row_mask:0xf bank_mask:0xf bound_ctrl:1
	ds_read_b128 v[128:131], v95 offset:2304
	v_add_f32_dpp v112, v112, v112 row_ror:4 row_mask:0xf bank_mask:0xf bound_ctrl:1
	v_add_f32_dpp v114, v114, v114 row_ror:4 row_mask:0xf bank_mask:0xf bound_ctrl:1
	ds_read_b128 v[140:143], v95 offset:14592
	v_add_f32_dpp v112, v112, v112 row_ror:2 row_mask:0xf bank_mask:0xf bound_ctrl:1
	v_add_f32_dpp v114, v114, v114 row_ror:2 row_mask:0xf bank_mask:0xf bound_ctrl:1
	ds_read_b32 v148, v108 offset:21056
	v_add_f32_dpp v112, v112, v112 row_ror:1 row_mask:0xf bank_mask:0xf bound_ctrl:1
	v_add_f32_dpp v114, v114, v114 row_ror:1 row_mask:0xf bank_mask:0xf bound_ctrl:1
	ds_read_b128 v[132:135], v95 offset:6400
	ds_read_b128 v[136:139], v95 offset:10496
	ds_read_b128 v[144:147], v95 offset:18688
	s_waitcnt lgkmcnt(8)
	v_pk_fma_f32 v[22:23], v[112:113], v[78:79], v[104:105] op_sel_hi:[0,1,1] neg_lo:[1,0,0] neg_hi:[1,0,0]
	v_pk_fma_f32 v[24:25], v[112:113], v[80:81], v[106:107] op_sel_hi:[0,1,1] neg_lo:[1,0,0] neg_hi:[1,0,0]
	ds_write_b32 v108, v114 offset:21952
	s_waitcnt lgkmcnt(6)
	v_pk_mul_f32 v[102:103], v[22:23], v[128:129]
	s_waitcnt lgkmcnt(4)
	v_pk_mul_f32 v[104:105], v[140:141], v[148:149] op_sel_hi:[1,0]
	v_pk_fma_f32 v[102:103], v[24:25], v[130:131], v[102:103]
	v_pk_mul_f32 v[106:107], v[142:143], v[148:149] op_sel_hi:[1,0]
	v_pk_mul_f32 v[150:151], v[96:97], v[22:23]
	v_add_f32_e32 v112, v102, v103
	v_pk_fma_f32 v[150:151], v[98:99], v[24:25], v[150:151]
	s_waitcnt lgkmcnt(3)
	v_pk_fma_f32 v[104:105], v[22:23], v[132:133], v[104:105]
	v_add_f32_e32 v114, v150, v151
	v_pk_fma_f32 v[106:107], v[24:25], v[134:135], v[106:107]
	v_add_f32_dpp v112, v112, v112 row_ror:8 row_mask:0xf bank_mask:0xf bound_ctrl:1
	v_add_f32_dpp v114, v114, v114 row_ror:8 row_mask:0xf bank_mask:0xf bound_ctrl:1
	ds_read_b128 v[70:73], v95 offset:2560
	v_add_f32_dpp v112, v112, v112 row_ror:4 row_mask:0xf bank_mask:0xf bound_ctrl:1
	v_add_f32_dpp v114, v114, v114 row_ror:4 row_mask:0xf bank_mask:0xf bound_ctrl:1
	ds_read_b128 v[82:85], v95 offset:14848
	v_add_f32_dpp v112, v112, v112 row_ror:2 row_mask:0xf bank_mask:0xf bound_ctrl:1
	v_add_f32_dpp v114, v114, v114 row_ror:2 row_mask:0xf bank_mask:0xf bound_ctrl:1
	ds_read_b32 v100, v108 offset:21120
	v_add_f32_dpp v112, v112, v112 row_ror:1 row_mask:0xf bank_mask:0xf bound_ctrl:1
	v_add_f32_dpp v114, v114, v114 row_ror:1 row_mask:0xf bank_mask:0xf bound_ctrl:1
	ds_read_b128 v[74:77], v95 offset:6656
	ds_read_b128 v[78:81], v95 offset:10752
	ds_read_b128 v[96:99], v95 offset:18944
	s_waitcnt lgkmcnt(8)
	v_pk_fma_f32 v[22:23], v[112:113], v[136:137], v[104:105] op_sel_hi:[0,1,1] neg_lo:[1,0,0] neg_hi:[1,0,0]
	v_pk_fma_f32 v[24:25], v[112:113], v[138:139], v[106:107] op_sel_hi:[0,1,1] neg_lo:[1,0,0] neg_hi:[1,0,0]
	ds_write_b32 v108, v114 offset:22016
	s_waitcnt lgkmcnt(6)
	v_pk_mul_f32 v[102:103], v[22:23], v[70:71]
	s_waitcnt lgkmcnt(4)
	v_pk_mul_f32 v[104:105], v[82:83], v[100:101] op_sel_hi:[1,0]
	v_pk_fma_f32 v[102:103], v[24:25], v[72:73], v[102:103]
	v_pk_mul_f32 v[106:107], v[84:85], v[100:101] op_sel_hi:[1,0]
	v_pk_mul_f32 v[150:151], v[144:145], v[22:23]
	v_add_f32_e32 v112, v102, v103
	v_pk_fma_f32 v[150:151], v[146:147], v[24:25], v[150:151]
	s_waitcnt lgkmcnt(3)
	v_pk_fma_f32 v[104:105], v[22:23], v[74:75], v[104:105]
	v_add_f32_e32 v114, v150, v151
	v_pk_fma_f32 v[106:107], v[24:25], v[76:77], v[106:107]
	v_add_f32_dpp v112, v112, v112 row_ror:8 row_mask:0xf bank_mask:0xf bound_ctrl:1
	v_add_f32_dpp v114, v114, v114 row_ror:8 row_mask:0xf bank_mask:0xf bound_ctrl:1
	ds_read_b128 v[128:131], v95 offset:2816
	v_add_f32_dpp v112, v112, v112 row_ror:4 row_mask:0xf bank_mask:0xf bound_ctrl:1
	v_add_f32_dpp v114, v114, v114 row_ror:4 row_mask:0xf bank_mask:0xf bound_ctrl:1
	ds_read_b128 v[140:143], v95 offset:15104
	v_add_f32_dpp v112, v112, v112 row_ror:2 row_mask:0xf bank_mask:0xf bound_ctrl:1
	v_add_f32_dpp v114, v114, v114 row_ror:2 row_mask:0xf bank_mask:0xf bound_ctrl:1
	ds_read_b32 v148, v108 offset:21184
	v_add_f32_dpp v112, v112, v112 row_ror:1 row_mask:0xf bank_mask:0xf bound_ctrl:1
	v_add_f32_dpp v114, v114, v114 row_ror:1 row_mask:0xf bank_mask:0xf bound_ctrl:1
	ds_read_b128 v[132:135], v95 offset:6912
	ds_read_b128 v[136:139], v95 offset:11008
	ds_read_b128 v[144:147], v95 offset:19200
	s_waitcnt lgkmcnt(8)
	v_pk_fma_f32 v[22:23], v[112:113], v[78:79], v[104:105] op_sel_hi:[0,1,1] neg_lo:[1,0,0] neg_hi:[1,0,0]
	v_pk_fma_f32 v[24:25], v[112:113], v[80:81], v[106:107] op_sel_hi:[0,1,1] neg_lo:[1,0,0] neg_hi:[1,0,0]
	ds_write_b32 v108, v114 offset:22080
	s_waitcnt lgkmcnt(6)
	v_pk_mul_f32 v[102:103], v[22:23], v[128:129]
	s_waitcnt lgkmcnt(4)
	v_pk_mul_f32 v[104:105], v[140:141], v[148:149] op_sel_hi:[1,0]
	v_pk_fma_f32 v[102:103], v[24:25], v[130:131], v[102:103]
	v_pk_mul_f32 v[106:107], v[142:143], v[148:149] op_sel_hi:[1,0]
	v_pk_mul_f32 v[150:151], v[96:97], v[22:23]
	v_add_f32_e32 v112, v102, v103
	v_pk_fma_f32 v[150:151], v[98:99], v[24:25], v[150:151]
	s_waitcnt lgkmcnt(3)
	v_pk_fma_f32 v[104:105], v[22:23], v[132:133], v[104:105]
	v_add_f32_e32 v114, v150, v151
	v_pk_fma_f32 v[106:107], v[24:25], v[134:135], v[106:107]
	v_add_f32_dpp v112, v112, v112 row_ror:8 row_mask:0xf bank_mask:0xf bound_ctrl:1
	v_add_f32_dpp v114, v114, v114 row_ror:8 row_mask:0xf bank_mask:0xf bound_ctrl:1
	ds_read_b128 v[70:73], v95 offset:3072
	v_add_f32_dpp v112, v112, v112 row_ror:4 row_mask:0xf bank_mask:0xf bound_ctrl:1
	v_add_f32_dpp v114, v114, v114 row_ror:4 row_mask:0xf bank_mask:0xf bound_ctrl:1
	ds_read_b128 v[82:85], v95 offset:15360
	v_add_f32_dpp v112, v112, v112 row_ror:2 row_mask:0xf bank_mask:0xf bound_ctrl:1
	v_add_f32_dpp v114, v114, v114 row_ror:2 row_mask:0xf bank_mask:0xf bound_ctrl:1
	ds_read_b32 v100, v108 offset:21248
	v_add_f32_dpp v112, v112, v112 row_ror:1 row_mask:0xf bank_mask:0xf bound_ctrl:1
	v_add_f32_dpp v114, v114, v114 row_ror:1 row_mask:0xf bank_mask:0xf bound_ctrl:1
	ds_read_b128 v[74:77], v95 offset:7168
	ds_read_b128 v[78:81], v95 offset:11264
	ds_read_b128 v[96:99], v95 offset:19456
	s_waitcnt lgkmcnt(8)
	v_pk_fma_f32 v[22:23], v[112:113], v[136:137], v[104:105] op_sel_hi:[0,1,1] neg_lo:[1,0,0] neg_hi:[1,0,0]
	v_pk_fma_f32 v[24:25], v[112:113], v[138:139], v[106:107] op_sel_hi:[0,1,1] neg_lo:[1,0,0] neg_hi:[1,0,0]
	ds_write_b32 v108, v114 offset:22144
	s_waitcnt lgkmcnt(6)
	v_pk_mul_f32 v[102:103], v[22:23], v[70:71]
	s_waitcnt lgkmcnt(4)
	v_pk_mul_f32 v[104:105], v[82:83], v[100:101] op_sel_hi:[1,0]
	v_pk_fma_f32 v[102:103], v[24:25], v[72:73], v[102:103]
	v_pk_mul_f32 v[106:107], v[84:85], v[100:101] op_sel_hi:[1,0]
	v_pk_mul_f32 v[150:151], v[144:145], v[22:23]
	v_add_f32_e32 v112, v102, v103
	v_pk_fma_f32 v[150:151], v[146:147], v[24:25], v[150:151]
	s_waitcnt lgkmcnt(3)
	v_pk_fma_f32 v[104:105], v[22:23], v[74:75], v[104:105]
	v_add_f32_e32 v114, v150, v151
	v_pk_fma_f32 v[106:107], v[24:25], v[76:77], v[106:107]
	v_add_f32_dpp v112, v112, v112 row_ror:8 row_mask:0xf bank_mask:0xf bound_ctrl:1
	v_add_f32_dpp v114, v114, v114 row_ror:8 row_mask:0xf bank_mask:0xf bound_ctrl:1
	ds_read_b128 v[128:131], v95 offset:3328
	v_add_f32_dpp v112, v112, v112 row_ror:4 row_mask:0xf bank_mask:0xf bound_ctrl:1
	v_add_f32_dpp v114, v114, v114 row_ror:4 row_mask:0xf bank_mask:0xf bound_ctrl:1
	ds_read_b128 v[140:143], v95 offset:15616
	v_add_f32_dpp v112, v112, v112 row_ror:2 row_mask:0xf bank_mask:0xf bound_ctrl:1
	v_add_f32_dpp v114, v114, v114 row_ror:2 row_mask:0xf bank_mask:0xf bound_ctrl:1
	ds_read_b32 v148, v108 offset:21312
	v_add_f32_dpp v112, v112, v112 row_ror:1 row_mask:0xf bank_mask:0xf bound_ctrl:1
	v_add_f32_dpp v114, v114, v114 row_ror:1 row_mask:0xf bank_mask:0xf bound_ctrl:1
	ds_read_b128 v[132:135], v95 offset:7424
	ds_read_b128 v[136:139], v95 offset:11520
	ds_read_b128 v[144:147], v95 offset:19712
	s_waitcnt lgkmcnt(8)
	v_pk_fma_f32 v[22:23], v[112:113], v[78:79], v[104:105] op_sel_hi:[0,1,1] neg_lo:[1,0,0] neg_hi:[1,0,0]
	v_pk_fma_f32 v[24:25], v[112:113], v[80:81], v[106:107] op_sel_hi:[0,1,1] neg_lo:[1,0,0] neg_hi:[1,0,0]
	ds_write_b32 v108, v114 offset:22208
	s_waitcnt lgkmcnt(6)
	v_pk_mul_f32 v[102:103], v[22:23], v[128:129]
	s_waitcnt lgkmcnt(4)
	v_pk_mul_f32 v[104:105], v[140:141], v[148:149] op_sel_hi:[1,0]
	v_pk_fma_f32 v[102:103], v[24:25], v[130:131], v[102:103]
	v_pk_mul_f32 v[106:107], v[142:143], v[148:149] op_sel_hi:[1,0]
	v_pk_mul_f32 v[150:151], v[96:97], v[22:23]
	v_add_f32_e32 v112, v102, v103
	v_pk_fma_f32 v[150:151], v[98:99], v[24:25], v[150:151]
	s_waitcnt lgkmcnt(3)
	v_pk_fma_f32 v[104:105], v[22:23], v[132:133], v[104:105]
	v_add_f32_e32 v114, v150, v151
	v_pk_fma_f32 v[106:107], v[24:25], v[134:135], v[106:107]
	v_add_f32_dpp v112, v112, v112 row_ror:8 row_mask:0xf bank_mask:0xf bound_ctrl:1
	v_add_f32_dpp v114, v114, v114 row_ror:8 row_mask:0xf bank_mask:0xf bound_ctrl:1
	ds_read_b128 v[70:73], v95 offset:3584
	v_add_f32_dpp v112, v112, v112 row_ror:4 row_mask:0xf bank_mask:0xf bound_ctrl:1
	v_add_f32_dpp v114, v114, v114 row_ror:4 row_mask:0xf bank_mask:0xf bound_ctrl:1
	ds_read_b128 v[82:85], v95 offset:15872
	v_add_f32_dpp v112, v112, v112 row_ror:2 row_mask:0xf bank_mask:0xf bound_ctrl:1
	v_add_f32_dpp v114, v114, v114 row_ror:2 row_mask:0xf bank_mask:0xf bound_ctrl:1
	ds_read_b32 v100, v108 offset:21376
	v_add_f32_dpp v112, v112, v112 row_ror:1 row_mask:0xf bank_mask:0xf bound_ctrl:1
	v_add_f32_dpp v114, v114, v114 row_ror:1 row_mask:0xf bank_mask:0xf bound_ctrl:1
	ds_read_b128 v[74:77], v95 offset:7680
	ds_read_b128 v[78:81], v95 offset:11776
	ds_read_b128 v[96:99], v95 offset:19968
	s_waitcnt lgkmcnt(8)
	v_pk_fma_f32 v[22:23], v[112:113], v[136:137], v[104:105] op_sel_hi:[0,1,1] neg_lo:[1,0,0] neg_hi:[1,0,0]
	v_pk_fma_f32 v[24:25], v[112:113], v[138:139], v[106:107] op_sel_hi:[0,1,1] neg_lo:[1,0,0] neg_hi:[1,0,0]
	ds_write_b32 v108, v114 offset:22272
	s_waitcnt lgkmcnt(6)
	v_pk_mul_f32 v[102:103], v[22:23], v[70:71]
	s_waitcnt lgkmcnt(4)
	v_pk_mul_f32 v[104:105], v[82:83], v[100:101] op_sel_hi:[1,0]
	v_pk_fma_f32 v[102:103], v[24:25], v[72:73], v[102:103]
	v_pk_mul_f32 v[106:107], v[84:85], v[100:101] op_sel_hi:[1,0]
	v_pk_mul_f32 v[150:151], v[144:145], v[22:23]
	v_add_f32_e32 v112, v102, v103
	v_pk_fma_f32 v[150:151], v[146:147], v[24:25], v[150:151]
	s_waitcnt lgkmcnt(3)
	v_pk_fma_f32 v[104:105], v[22:23], v[74:75], v[104:105]
	v_add_f32_e32 v114, v150, v151
	v_pk_fma_f32 v[106:107], v[24:25], v[76:77], v[106:107]
	v_add_f32_dpp v112, v112, v112 row_ror:8 row_mask:0xf bank_mask:0xf bound_ctrl:1
	v_add_f32_dpp v114, v114, v114 row_ror:8 row_mask:0xf bank_mask:0xf bound_ctrl:1
	ds_read_b128 v[128:131], v95 offset:3840
	v_add_f32_dpp v112, v112, v112 row_ror:4 row_mask:0xf bank_mask:0xf bound_ctrl:1
	v_add_f32_dpp v114, v114, v114 row_ror:4 row_mask:0xf bank_mask:0xf bound_ctrl:1
	ds_read_b128 v[140:143], v95 offset:16128
	v_add_f32_dpp v112, v112, v112 row_ror:2 row_mask:0xf bank_mask:0xf bound_ctrl:1
	v_add_f32_dpp v114, v114, v114 row_ror:2 row_mask:0xf bank_mask:0xf bound_ctrl:1
	ds_read_b32 v148, v108 offset:21440
	v_add_f32_dpp v112, v112, v112 row_ror:1 row_mask:0xf bank_mask:0xf bound_ctrl:1
	v_add_f32_dpp v114, v114, v114 row_ror:1 row_mask:0xf bank_mask:0xf bound_ctrl:1
	ds_read_b128 v[132:135], v95 offset:7936
	ds_read_b128 v[136:139], v95 offset:12032
	ds_read_b128 v[144:147], v95 offset:20224
	s_waitcnt lgkmcnt(8)
	v_pk_fma_f32 v[22:23], v[112:113], v[78:79], v[104:105] op_sel_hi:[0,1,1] neg_lo:[1,0,0] neg_hi:[1,0,0]
	v_pk_fma_f32 v[24:25], v[112:113], v[80:81], v[106:107] op_sel_hi:[0,1,1] neg_lo:[1,0,0] neg_hi:[1,0,0]
	ds_write_b32 v108, v114 offset:22336
	s_waitcnt lgkmcnt(6)
	v_pk_mul_f32 v[102:103], v[22:23], v[128:129]
	s_waitcnt lgkmcnt(4)
	v_pk_mul_f32 v[104:105], v[140:141], v[148:149] op_sel_hi:[1,0]
	v_pk_fma_f32 v[102:103], v[24:25], v[130:131], v[102:103]
	v_pk_mul_f32 v[106:107], v[142:143], v[148:149] op_sel_hi:[1,0]
	v_pk_mul_f32 v[150:151], v[96:97], v[22:23]
	v_add_f32_e32 v112, v102, v103
	v_pk_fma_f32 v[150:151], v[98:99], v[24:25], v[150:151]
	s_waitcnt lgkmcnt(3)
	v_pk_fma_f32 v[104:105], v[22:23], v[132:133], v[104:105]
	v_add_f32_e32 v114, v150, v151
	v_pk_fma_f32 v[106:107], v[24:25], v[134:135], v[106:107]
	v_add_f32_dpp v112, v112, v112 row_ror:8 row_mask:0xf bank_mask:0xf bound_ctrl:1
	v_add_f32_dpp v114, v114, v114 row_ror:8 row_mask:0xf bank_mask:0xf bound_ctrl:1
	s_nop 0
	v_add_f32_dpp v112, v112, v112 row_ror:4 row_mask:0xf bank_mask:0xf bound_ctrl:1
	v_add_f32_dpp v114, v114, v114 row_ror:4 row_mask:0xf bank_mask:0xf bound_ctrl:1
	s_nop 0
	v_add_f32_dpp v112, v112, v112 row_ror:2 row_mask:0xf bank_mask:0xf bound_ctrl:1
	v_add_f32_dpp v114, v114, v114 row_ror:2 row_mask:0xf bank_mask:0xf bound_ctrl:1
	s_nop 0
	v_add_f32_dpp v112, v112, v112 row_ror:1 row_mask:0xf bank_mask:0xf bound_ctrl:1
	v_add_f32_dpp v114, v114, v114 row_ror:1 row_mask:0xf bank_mask:0xf bound_ctrl:1
	s_nop 0
	s_waitcnt lgkmcnt(2)
	v_pk_fma_f32 v[22:23], v[112:113], v[136:137], v[104:105] op_sel_hi:[0,1,1] neg_lo:[1,0,0] neg_hi:[1,0,0]
	v_pk_fma_f32 v[24:25], v[112:113], v[138:139], v[106:107] op_sel_hi:[0,1,1] neg_lo:[1,0,0] neg_hi:[1,0,0]
	ds_write_b32 v108, v114 offset:22400
	s_waitcnt lgkmcnt(2)
	v_pk_mul_f32 v[150:151], v[144:145], v[22:23]
	v_pk_fma_f32 v[150:151], v[146:147], v[24:25], v[150:151]
	v_add_f32_e32 v114, v150, v151
	s_nop 1
	v_add_f32_dpp v114, v114, v114 row_ror:8 row_mask:0xf bank_mask:0xf bound_ctrl:1
	s_nop 0
	s_nop 0
	v_add_f32_dpp v114, v114, v114 row_ror:4 row_mask:0xf bank_mask:0xf bound_ctrl:1
	s_nop 0
	s_nop 0
	v_add_f32_dpp v114, v114, v114 row_ror:2 row_mask:0xf bank_mask:0xf bound_ctrl:1
	s_nop 0
	s_nop 0
	v_add_f32_dpp v114, v114, v114 row_ror:1 row_mask:0xf bank_mask:0xf bound_ctrl:1
	s_nop 0
	ds_write_b32 v108, v114 offset:22464
	s_add_u32 s28, s28, 16
	s_mov_b32 s35, 1
	s_waitcnt vmcnt(0)
	ds_write_b128 v110, v[58:61] offset:23552
	ds_write_b128 v110, v[62:65] offset:27648
	ds_write_b128 v110, v[66:69] offset:31744
	s_waitcnt lgkmcnt(0)
	s_barrier
	s_add_u32 s30, s28, 32
	v_add_u32_e32 v87, s30, v15
	v_med3_i32 v87, v87, 0, s29
	v_mad_i64_i32 v[104:105], vcc, v87, v12, v[6:7]
	global_load_dwordx4 v[58:61], v[104:105], off
	v_add_u32_e32 v87, s30, v16
	v_med3_i32 v87, v87, 0, s29
	v_mad_i64_i32 v[104:105], vcc, v87, v13, v[8:9]
	global_load_dwordx4 v[62:65], v[104:105], off
	v_add_u32_e32 v87, s30, v17
	v_med3_i32 v87, v87, 0, s29
	v_mad_i64_i32 v[104:105], vcc, v87, v14, v[10:11]
	global_load_dwordx4 v[66:69], v[104:105], off
	ds_read_b32 v89, v115 offset:21504
	s_sub_u32 s98, s28, 16
	v_add_u32_e32 v87, s98, v127
	v_mad_i64_i32 v[104:105], vcc, v87, v20, v[18:19]
	s_waitcnt lgkmcnt(0)
	v_cvt_pk_bf16_f32 v89, v89, v89
	global_store_short v[104:105], v89, off
	ds_read_b64 v[70:71], v1 offset:23936
	ds_read_b64 v[72:73], v1 offset:23552
	ds_read_b64 v[74:75], v1 offset:24320
	ds_read_b64 v[76:77], v1 offset:24064
	ds_read_b64 v[78:79], v1 offset:23680
	ds_read_b64 v[80:81], v1 offset:24448
	ds_read_b64 v[82:83], v1 offset:24192
	ds_read_b64 v[84:85], v1 offset:23808
	ds_read_b64 v[96:97], v1 offset:24576
	ds_read_b64 v[128:129], v2 offset:30464
	ds_read_b64 v[130:131], v2 offset:30592
	v_add_u32_e32 v87, s28, v127
	v_cmp_ne_u32_e32 vcc, 0, v87
	s_nop 1
	v_cndmask_b32_e64 v98, 0, 0.5, vcc
	v_cmp_ne_u32_e32 vcc, s29, v87
	s_nop 1
	v_cndmask_b32_e64 v100, 0, 0.5, vcc
	s_waitcnt lgkmcnt(8)
	v_lshlrev_b32_e32 v132, 16, v70
	v_and_b32_e32 v133, 0xffff0000, v70
	v_lshlrev_b32_e32 v134, 16, v71
	v_and_b32_e32 v135, 0xffff0000, v71
	v_lshlrev_b32_e32 v136, 16, v72
	v_and_b32_e32 v137, 0xffff0000, v72
	v_lshlrev_b32_e32 v138, 16, v73
	v_and_b32_e32 v139, 0xffff0000, v73
	v_lshlrev_b32_e32 v140, 16, v74
	v_and_b32_e32 v141, 0xffff0000, v74
	v_lshlrev_b32_e32 v142, 16, v75
	v_and_b32_e32 v143, 0xffff0000, v75
	v_pk_mul_f32 v[136:137], v[136:137], v[98:99] op_sel_hi:[1,0]
	v_pk_fma_f32 v[136:137], v[140:141], v[100:101], v[136:137] op_sel_hi:[1,0,1]
	v_pk_add_f32 v[136:137], v[136:137], v[132:133] neg_lo:[0,1] neg_hi:[0,1]
	v_pk_fma_f32 v[144:145], v[26:27], v[136:137], v[132:133]
	v_pk_mul_f32 v[138:139], v[138:139], v[98:99] op_sel_hi:[1,0]
	v_pk_fma_f32 v[138:139], v[142:143], v[100:101], v[138:139] op_sel_hi:[1,0,1]
	v_pk_add_f32 v[138:139], v[138:139], v[134:135] neg_lo:[0,1] neg_hi:[0,1]
	v_pk_fma_f32 v[146:147], v[28:29], v[138:139], v[134:135]
	s_waitcnt lgkmcnt(5)
	v_lshlrev_b32_e32 v132, 16, v76
	v_and_b32_e32 v133, 0xffff0000, v76
	v_lshlrev_b32_e32 v134, 16, v77
	v_and_b32_e32 v135, 0xffff0000, v77
	v_lshlrev_b32_e32 v136, 16, v78
	v_and_b32_e32 v137, 0xffff0000, v78
	v_lshlrev_b32_e32 v138, 16, v79
	v_and_b32_e32 v139, 0xffff0000, v79
	v_lshlrev_b32_e32 v140, 16, v80
	v_and_b32_e32 v141, 0xffff0000, v80
	v_lshlrev_b32_e32 v142, 16, v81
	v_and_b32_e32 v143, 0xffff0000, v81
	v_pk_mul_f32 v[136:137], v[136:137], v[98:99] op_sel_hi:[1,0]
	v_pk_fma_f32 v[136:137], v[140:141], v[100:101], v[136:137] op_sel_hi:[1,0,1]
	v_pk_add_f32 v[136:137], v[136:137], v[132:133] neg_lo:[0,1] neg_hi:[0,1]
	v_pk_fma_f32 v[102:103], v[30:31], v[136:137], v[132:133]
	v_pk_mul_f32 v[138:139], v[138:139], v[98:99] op_sel_hi:[1,0]
	v_pk_fma_f32 v[138:139], v[142:143], v[100:101], v[138:139] op_sel_hi:[1,0,1]
	v_pk_add_f32 v[138:139], v[138:139], v[134:135] neg_lo:[0,1] neg_hi:[0,1]
	v_pk_fma_f32 v[104:105], v[32:33], v[138:139], v[134:135]
	s_waitcnt lgkmcnt(2)
	v_lshlrev_b32_e32 v132, 16, v82
	v_and_b32_e32 v133, 0xffff0000, v82
	v_lshlrev_b32_e32 v134, 16, v83
	v_and_b32_e32 v135, 0xffff0000, v83
	v_lshlrev_b32_e32 v136, 16, v84
	v_and_b32_e32 v137, 0xffff0000, v84
	v_lshlrev_b32_e32 v138, 16, v85
	v_and_b32_e32 v139, 0xffff0000, v85
	v_lshlrev_b32_e32 v140, 16, v96
	v_and_b32_e32 v141, 0xffff0000, v96
	v_lshlrev_b32_e32 v142, 16, v97
	v_and_b32_e32 v143, 0xffff0000, v97
	v_pk_mul_f32 v[136:137], v[136:137], v[98:99] op_sel_hi:[1,0]
	v_pk_fma_f32 v[136:137], v[140:141], v[100:101], v[136:137] op_sel_hi:[1,0,1]
	v_pk_add_f32 v[136:137], v[136:137], v[132:133] neg_lo:[0,1] neg_hi:[0,1]
	v_pk_fma_f32 v[148:149], v[34:35], v[136:137], v[132:133]
	v_pk_mul_f32 v[138:139], v[138:139], v[98:99] op_sel_hi:[1,0]
	v_pk_fma_f32 v[138:139], v[142:143], v[100:101], v[138:139] op_sel_hi:[1,0,1]
	v_pk_add_f32 v[138:139], v[138:139], v[134:135] neg_lo:[0,1] neg_hi:[0,1]
	v_pk_fma_f32 v[150:151], v[36:37], v[138:139], v[134:135]
	s_waitcnt lgkmcnt(0)
	v_lshlrev_b32_e32 v132, 16, v128
	v_and_b32_e32 v133, 0xffff0000, v128
	v_lshlrev_b32_e32 v134, 16, v129
	v_and_b32_e32 v135, 0xffff0000, v129
	v_lshlrev_b32_e32 v136, 16, v130
	v_and_b32_e32 v137, 0xffff0000, v130
	v_lshlrev_b32_e32 v138, 16, v131
	v_and_b32_e32 v139, 0xffff0000, v131
	s_mov_b32 s98, 0xbf60028b
	v_mul_f32_e32 v132, s98, v132
	v_mul_f32_e32 v133, s98, v133
	v_mul_f32_e32 v134, s98, v134
	v_mul_f32_e32 v135, s98, v135
	v_exp_f32_e32 v132, v132
	v_exp_f32_e32 v133, v133
	v_exp_f32_e32 v134, v134
	v_exp_f32_e32 v135, v135
	v_pk_mul_f32 v[140:141], v[102:103], v[38:39]
	v_pk_mul_f32 v[142:143], v[104:105], v[40:41]
	v_pk_mul_f32 v[106:107], v[140:141], v[140:141]
	v_pk_fma_f32 v[106:107], v[142:143], v[142:143], v[106:107]
	v_add_f32_e32 v106, v106, v107
	s_nop 1
	v_add_f32_dpp v106, v106, v106 row_ror:8 row_mask:0xf bank_mask:0xf bound_ctrl:1
	s_nop 1
	v_add_f32_dpp v106, v106, v106 row_ror:4 row_mask:0xf bank_mask:0xf bound_ctrl:1
	s_nop 1
	v_add_f32_dpp v106, v106, v106 row_ror:2 row_mask:0xf bank_mask:0xf bound_ctrl:1
	s_nop 1
	v_add_f32_dpp v106, v106, v106 row_ror:1 row_mask:0xf bank_mask:0xf bound_ctrl:1
	v_add_f32_e32 v106, 0x2b8cbccc, v106
	v_rsq_f32_e32 v106, v106
	v_pk_mul_f32 v[148:149], v[148:149], s[40:41] op_sel_hi:[1,0]
	v_pk_mul_f32 v[150:151], v[150:151], s[40:41] op_sel_hi:[1,0]
	v_pk_mul_f32 v[140:141], v[140:141], v[106:107] op_sel_hi:[1,0]
	v_pk_mul_f32 v[142:143], v[142:143], v[106:107] op_sel_hi:[1,0]
	v_pk_add_f32 v[70:71], v[136:137], -1.0 op_sel_hi:[1,0]
	v_pk_add_f32 v[72:73], v[138:139], -1.0 op_sel_hi:[1,0]
	v_pk_fma_f32 v[70:71], v[42:43], v[70:71], 1.0 op_sel_hi:[1,1,0]
	v_pk_fma_f32 v[72:73], v[44:45], v[72:73], 1.0 op_sel_hi:[1,1,0]
	v_pk_mul_f32 v[70:71], v[102:103], v[70:71]
	v_pk_mul_f32 v[72:73], v[104:105], v[72:73]
	v_pk_mul_f32 v[74:75], v[140:141], v[136:137]
	v_pk_mul_f32 v[76:77], v[142:143], v[138:139]
	ds_write_b128 v3, v[140:143] offset:0
	ds_write_b128 v3, v[132:135] offset:4096
	ds_write_b128 v3, v[74:77] offset:8192
	ds_write_b128 v3, v[70:73] offset:12288
	ds_write_b128 v3, v[144:147] offset:16384
	ds_write_b128 v4, v[148:151]
	s_waitcnt lgkmcnt(0)
	s_barrier
	ds_read_b128 v[70:73], v95 offset:0
	ds_read_b128 v[82:85], v95 offset:12288
	ds_read_b32 v100, v108 offset:20480
	ds_read_b128 v[74:77], v95 offset:4096
	ds_read_b128 v[78:81], v95 offset:8192
	ds_read_b128 v[96:99], v95 offset:16384
	s_waitcnt lgkmcnt(5)
	v_pk_mul_f32 v[102:103], v[22:23], v[70:71]
	s_waitcnt lgkmcnt(3)
	v_pk_mul_f32 v[104:105], v[82:83], v[100:101] op_sel_hi:[1,0]
	v_pk_fma_f32 v[102:103], v[24:25], v[72:73], v[102:103]
	v_pk_mul_f32 v[106:107], v[84:85], v[100:101] op_sel_hi:[1,0]
	v_add_f32_e32 v112, v102, v103
	s_waitcnt lgkmcnt(2)
	v_pk_fma_f32 v[104:105], v[22:23], v[74:75], v[104:105]
	v_pk_fma_f32 v[106:107], v[24:25], v[76:77], v[106:107]
	v_add_f32_dpp v112, v112, v112 row_ror:8 row_mask:0xf bank_mask:0xf bound_ctrl:1
	ds_read_b128 v[128:131], v95 offset:256
	s_nop 0
	v_add_f32_dpp v112, v112, v112 row_ror:4 row_mask:0xf bank_mask:0xf bound_ctrl:1
	ds_read_b128 v[140:143], v95 offset:12544
	s_nop 0
	v_add_f32_dpp v112, v112, v112 row_ror:2 row_mask:0xf bank_mask:0xf bound_ctrl:1
	ds_read_b32 v148, v108 offset:20544
	s_nop 0
	v_add_f32_dpp v112, v112, v112 row_ror:1 row_mask:0xf bank_mask:0xf bound_ctrl:1
	ds_read_b128 v[132:135], v95 offset:4352
	ds_read_b128 v[136:139], v95 offset:8448
	ds_read_b128 v[144:147], v95 offset:16640
	s_waitcnt lgkmcnt(7)
	v_pk_fma_f32 v[22:23], v[112:113], v[78:79], v[104:105] op_sel_hi:[0,1,1] neg_lo:[1,0,0] neg_hi:[1,0,0]
	v_pk_fma_f32 v[24:25], v[112:113], v[80:81], v[106:107] op_sel_hi:[0,1,1] neg_lo:[1,0,0] neg_hi:[1,0,0]
	s_waitcnt lgkmcnt(5)
	v_pk_mul_f32 v[102:103], v[22:23], v[128:129]
	s_waitcnt lgkmcnt(3)
	v_pk_mul_f32 v[104:105], v[140:141], v[148:149] op_sel_hi:[1,0]
	v_pk_fma_f32 v[102:103], v[24:25], v[130:131], v[102:103]
	v_pk_mul_f32 v[106:107], v[142:143], v[148:149] op_sel_hi:[1,0]
	v_pk_mul_f32 v[150:151], v[96:97], v[22:23]
	v_add_f32_e32 v112, v102, v103
	v_pk_fma_f32 v[150:151], v[98:99], v[24:25], v[150:151]
	s_waitcnt lgkmcnt(2)
	v_pk_fma_f32 v[104:105], v[22:23], v[132:133], v[104:105]
	v_add_f32_e32 v114, v150, v151
	v_pk_fma_f32 v[106:107], v[24:25], v[134:135], v[106:107]
	v_add_f32_dpp v112, v112, v112 row_ror:8 row_mask:0xf bank_mask:0xf bound_ctrl:1
	v_add_f32_dpp v114, v114, v114 row_ror:8 row_mask:0xf bank_mask:0xf bound_ctrl:1
	ds_read_b128 v[70:73], v95 offset:512
	v_add_f32_dpp v112, v112, v112 row_ror:4 row_mask:0xf bank_mask:0xf bound_ctrl:1
	v_add_f32_dpp v114, v114, v114 row_ror:4 row_mask:0xf bank_mask:0xf bound_ctrl:1
	ds_read_b128 v[82:85], v95 offset:12800
	v_add_f32_dpp v112, v112, v112 row_ror:2 row_mask:0xf bank_mask:0xf bound_ctrl:1
	v_add_f32_dpp v114, v114, v114 row_ror:2 row_mask:0xf bank_mask:0xf bound_ctrl:1
	ds_read_b32 v100, v108 offset:20608
	v_add_f32_dpp v112, v112, v112 row_ror:1 row_mask:0xf bank_mask:0xf bound_ctrl:1
	v_add_f32_dpp v114, v114, v114 row_ror:1 row_mask:0xf bank_mask:0xf bound_ctrl:1
	ds_read_b128 v[74:77], v95 offset:4608
	ds_read_b128 v[78:81], v95 offset:8704
	ds_read_b128 v[96:99], v95 offset:16896
	s_waitcnt lgkmcnt(7)
	v_pk_fma_f32 v[22:23], v[112:113], v[136:137], v[104:105] op_sel_hi:[0,1,1] neg_lo:[1,0,0] neg_hi:[1,0,0]
	v_pk_fma_f32 v[24:25], v[112:113], v[138:139], v[106:107] op_sel_hi:[0,1,1] neg_lo:[1,0,0] neg_hi:[1,0,0]
	ds_write_b32 v108, v114 offset:22528
	s_waitcnt lgkmcnt(6)
	v_pk_mul_f32 v[102:103], v[22:23], v[70:71]
	s_waitcnt lgkmcnt(4)
	v_pk_mul_f32 v[104:105], v[82:83], v[100:101] op_sel_hi:[1,0]
	v_pk_fma_f32 v[102:103], v[24:25], v[72:73], v[102:103]
	v_pk_mul_f32 v[106:107], v[84:85], v[100:101] op_sel_hi:[1,0]
	v_pk_mul_f32 v[150:151], v[144:145], v[22:23]
	v_add_f32_e32 v112, v102, v103
	v_pk_fma_f32 v[150:151], v[146:147], v[24:25], v[150:151]
	s_waitcnt lgkmcnt(3)
	v_pk_fma_f32 v[104:105], v[22:23], v[74:75], v[104:105]
	v_add_f32_e32 v114, v150, v151
	v_pk_fma_f32 v[106:107], v[24:25], v[76:77], v[106:107]
	v_add_f32_dpp v112, v112, v112 row_ror:8 row_mask:0xf bank_mask:0xf bound_ctrl:1
	v_add_f32_dpp v114, v114, v114 row_ror:8 row_mask:0xf bank_mask:0xf bound_ctrl:1
	ds_read_b128 v[128:131], v95 offset:768
	v_add_f32_dpp v112, v112, v112 row_ror:4 row_mask:0xf bank_mask:0xf bound_ctrl:1
	v_add_f32_dpp v114, v114, v114 row_ror:4 row_mask:0xf bank_mask:0xf bound_ctrl:1
	ds_read_b128 v[140:143], v95 offset:13056
	v_add_f32_dpp v112, v112, v112 row_ror:2 row_mask:0xf bank_mask:0xf bound_ctrl:1
	v_add_f32_dpp v114, v114, v114 row_ror:2 row_mask:0xf bank_mask:0xf bound_ctrl:1
	ds_read_b32 v148, v108 offset:20672
	v_add_f32_dpp v112, v112, v112 row_ror:1 row_mask:0xf bank_mask:0xf bound_ctrl:1
	v_add_f32_dpp v114, v114, v114 row_ror:1 row_mask:0xf bank_mask:0xf bound_ctrl:1
	ds_read_b128 v[132:135], v95 offset:4864
	ds_read_b128 v[136:139], v95 offset:8960
	ds_read_b128 v[144:147], v95 offset:17152
	s_waitcnt lgkmcnt(8)
	v_pk_fma_f32 v[22:23], v[112:113], v[78:79], v[104:105] op_sel_hi:[0,1,1] neg_lo:[1,0,0] neg_hi:[1,0,0]
	v_pk_fma_f32 v[24:25], v[112:113], v[80:81], v[106:107] op_sel_hi:[0,1,1] neg_lo:[1,0,0] neg_hi:[1,0,0]
	ds_write_b32 v108, v114 offset:22592
	s_waitcnt lgkmcnt(6)
	v_pk_mul_f32 v[102:103], v[22:23], v[128:129]
	s_waitcnt lgkmcnt(4)
	v_pk_mul_f32 v[104:105], v[140:141], v[148:149] op_sel_hi:[1,0]
	v_pk_fma_f32 v[102:103], v[24:25], v[130:131], v[102:103]
	v_pk_mul_f32 v[106:107], v[142:143], v[148:149] op_sel_hi:[1,0]
	v_pk_mul_f32 v[150:151], v[96:97], v[22:23]
	v_add_f32_e32 v112, v102, v103
	v_pk_fma_f32 v[150:151], v[98:99], v[24:25], v[150:151]
	s_waitcnt lgkmcnt(3)
	v_pk_fma_f32 v[104:105], v[22:23], v[132:133], v[104:105]
	v_add_f32_e32 v114, v150, v151
	v_pk_fma_f32 v[106:107], v[24:25], v[134:135], v[106:107]
	v_add_f32_dpp v112, v112, v112 row_ror:8 row_mask:0xf bank_mask:0xf bound_ctrl:1
	v_add_f32_dpp v114, v114, v114 row_ror:8 row_mask:0xf bank_mask:0xf bound_ctrl:1
	ds_read_b128 v[70:73], v95 offset:1024
	v_add_f32_dpp v112, v112, v112 row_ror:4 row_mask:0xf bank_mask:0xf bound_ctrl:1
	v_add_f32_dpp v114, v114, v114 row_ror:4 row_mask:0xf bank_mask:0xf bound_ctrl:1
	ds_read_b128 v[82:85], v95 offset:13312
	v_add_f32_dpp v112, v112, v112 row_ror:2 row_mask:0xf bank_mask:0xf bound_ctrl:1
	v_add_f32_dpp v114, v114, v114 row_ror:2 row_mask:0xf bank_mask:0xf bound_ctrl:1
	ds_read_b32 v100, v108 offset:20736
	v_add_f32_dpp v112, v112, v112 row_ror:1 row_mask:0xf bank_mask:0xf bound_ctrl:1
	v_add_f32_dpp v114, v114, v114 row_ror:1 row_mask:0xf bank_mask:0xf bound_ctrl:1
	ds_read_b128 v[74:77], v95 offset:5120
	ds_read_b128 v[78:81], v95 offset:9216
	ds_read_b128 v[96:99], v95 offset:17408
	s_waitcnt lgkmcnt(8)
	v_pk_fma_f32 v[22:23], v[112:113], v[136:137], v[104:105] op_sel_hi:[0,1,1] neg_lo:[1,0,0] neg_hi:[1,0,0]
	v_pk_fma_f32 v[24:25], v[112:113], v[138:139], v[106:107] op_sel_hi:[0,1,1] neg_lo:[1,0,0] neg_hi:[1,0,0]
	ds_write_b32 v108, v114 offset:22656
	s_waitcnt lgkmcnt(6)
	v_pk_mul_f32 v[102:103], v[22:23], v[70:71]
	s_waitcnt lgkmcnt(4)
	v_pk_mul_f32 v[104:105], v[82:83], v[100:101] op_sel_hi:[1,0]
	v_pk_fma_f32 v[102:103], v[24:25], v[72:73], v[102:103]
	v_pk_mul_f32 v[106:107], v[84:85], v[100:101] op_sel_hi:[1,0]
	v_pk_mul_f32 v[150:151], v[144:145], v[22:23]
	v_add_f32_e32 v112, v102, v103
	v_pk_fma_f32 v[150:151], v[146:147], v[24:25], v[150:151]
	s_waitcnt lgkmcnt(3)
	v_pk_fma_f32 v[104:105], v[22:23], v[74:75], v[104:105]
	v_add_f32_e32 v114, v150, v151
	v_pk_fma_f32 v[106:107], v[24:25], v[76:77], v[106:107]
	v_add_f32_dpp v112, v112, v112 row_ror:8 row_mask:0xf bank_mask:0xf bound_ctrl:1
	v_add_f32_dpp v114, v114, v114 row_ror:8 row_mask:0xf bank_mask:0xf bound_ctrl:1
	ds_read_b128 v[128:131], v95 offset:1280
	v_add_f32_dpp v112, v112, v112 row_ror:4 row_mask:0xf bank_mask:0xf bound_ctrl:1
	v_add_f32_dpp v114, v114, v114 row_ror:4 row_mask:0xf bank_mask:0xf bound_ctrl:1
	ds_read_b128 v[140:143], v95 offset:13568
	v_add_f32_dpp v112, v112, v112 row_ror:2 row_mask:0xf bank_mask:0xf bound_ctrl:1
	v_add_f32_dpp v114, v114, v114 row_ror:2 row_mask:0xf bank_mask:0xf bound_ctrl:1
	ds_read_b32 v148, v108 offset:20800
	v_add_f32_dpp v112, v112, v112 row_ror:1 row_mask:0xf bank_mask:0xf bound_ctrl:1
	v_add_f32_dpp v114, v114, v114 row_ror:1 row_mask:0xf bank_mask:0xf bound_ctrl:1
	ds_read_b128 v[132:135], v95 offset:5376
	ds_read_b128 v[136:139], v95 offset:9472
	ds_read_b128 v[144:147], v95 offset:17664
	s_waitcnt lgkmcnt(8)
	v_pk_fma_f32 v[22:23], v[112:113], v[78:79], v[104:105] op_sel_hi:[0,1,1] neg_lo:[1,0,0] neg_hi:[1,0,0]
	v_pk_fma_f32 v[24:25], v[112:113], v[80:81], v[106:107] op_sel_hi:[0,1,1] neg_lo:[1,0,0] neg_hi:[1,0,0]
	ds_write_b32 v108, v114 offset:22720
	s_waitcnt lgkmcnt(6)
	v_pk_mul_f32 v[102:103], v[22:23], v[128:129]
	s_waitcnt lgkmcnt(4)
	v_pk_mul_f32 v[104:105], v[140:141], v[148:149] op_sel_hi:[1,0]
	v_pk_fma_f32 v[102:103], v[24:25], v[130:131], v[102:103]
	v_pk_mul_f32 v[106:107], v[142:143], v[148:149] op_sel_hi:[1,0]
	v_pk_mul_f32 v[150:151], v[96:97], v[22:23]
	v_add_f32_e32 v112, v102, v103
	v_pk_fma_f32 v[150:151], v[98:99], v[24:25], v[150:151]
	s_waitcnt lgkmcnt(3)
	v_pk_fma_f32 v[104:105], v[22:23], v[132:133], v[104:105]
	v_add_f32_e32 v114, v150, v151
	v_pk_fma_f32 v[106:107], v[24:25], v[134:135], v[106:107]
	v_add_f32_dpp v112, v112, v112 row_ror:8 row_mask:0xf bank_mask:0xf bound_ctrl:1
	v_add_f32_dpp v114, v114, v114 row_ror:8 row_mask:0xf bank_mask:0xf bound_ctrl:1
	ds_read_b128 v[70:73], v95 offset:1536
	v_add_f32_dpp v112, v112, v112 row_ror:4 row_mask:0xf bank_mask:0xf bound_ctrl:1
	v_add_f32_dpp v114, v114, v114 row_ror:4 row_mask:0xf bank_mask:0xf bound_ctrl:1
	ds_read_b128 v[82:85], v95 offset:13824
	v_add_f32_dpp v112, v112, v112 row_ror:2 row_mask:0xf bank_mask:0xf bound_ctrl:1
	v_add_f32_dpp v114, v114, v114 row_ror:2 row_mask:0xf bank_mask:0xf bound_ctrl:1
	ds_read_b32 v100, v108 offset:20864
	v_add_f32_dpp v112, v112, v112 row_ror:1 row_mask:0xf bank_mask:0xf bound_ctrl:1
	v_add_f32_dpp v114, v114, v114 row_ror:1 row_mask:0xf bank_mask:0xf bound_ctrl:1
	ds_read_b128 v[74:77], v95 offset:5632
	ds_read_b128 v[78:81], v95 offset:9728
	ds_read_b128 v[96:99], v95 offset:17920
	s_waitcnt lgkmcnt(8)
	v_pk_fma_f32 v[22:23], v[112:113], v[136:137], v[104:105] op_sel_hi:[0,1,1] neg_lo:[1,0,0] neg_hi:[1,0,0]
	v_pk_fma_f32 v[24:25], v[112:113], v[138:139], v[106:107] op_sel_hi:[0,1,1] neg_lo:[1,0,0] neg_hi:[1,0,0]
	ds_write_b32 v108, v114 offset:22784
	s_waitcnt lgkmcnt(6)
	v_pk_mul_f32 v[102:103], v[22:23], v[70:71]
	s_waitcnt lgkmcnt(4)
	v_pk_mul_f32 v[104:105], v[82:83], v[100:101] op_sel_hi:[1,0]
	v_pk_fma_f32 v[102:103], v[24:25], v[72:73], v[102:103]
	v_pk_mul_f32 v[106:107], v[84:85], v[100:101] op_sel_hi:[1,0]
	v_pk_mul_f32 v[150:151], v[144:145], v[22:23]
	v_add_f32_e32 v112, v102, v103
	v_pk_fma_f32 v[150:151], v[146:147], v[24:25], v[150:151]
	s_waitcnt lgkmcnt(3)
	v_pk_fma_f32 v[104:105], v[22:23], v[74:75], v[104:105]
	v_add_f32_e32 v114, v150, v151
	v_pk_fma_f32 v[106:107], v[24:25], v[76:77], v[106:107]
	v_add_f32_dpp v112, v112, v112 row_ror:8 row_mask:0xf bank_mask:0xf bound_ctrl:1
	v_add_f32_dpp v114, v114, v114 row_ror:8 row_mask:0xf bank_mask:0xf bound_ctrl:1
	ds_read_b128 v[128:131], v95 offset:1792
	v_add_f32_dpp v112, v112, v112 row_ror:4 row_mask:0xf bank_mask:0xf bound_ctrl:1
	v_add_f32_dpp v114, v114, v114 row_ror:4 row_mask:0xf bank_mask:0xf bound_ctrl:1
	ds_read_b128 v[140:143], v95 offset:14080
	v_add_f32_dpp v112, v112, v112 row_ror:2 row_mask:0xf bank_mask:0xf bound_ctrl:1
	v_add_f32_dpp v114, v114, v114 row_ror:2 row_mask:0xf bank_mask:0xf bound_ctrl:1
	ds_read_b32 v148, v108 offset:20928
	v_add_f32_dpp v112, v112, v112 row_ror:1 row_mask:0xf bank_mask:0xf bound_ctrl:1
	v_add_f32_dpp v114, v114, v114 row_ror:1 row_mask:0xf bank_mask:0xf bound_ctrl:1
	ds_read_b128 v[132:135], v95 offset:5888
	ds_read_b128 v[136:139], v95 offset:9984
	ds_read_b128 v[144:147], v95 offset:18176
	s_waitcnt lgkmcnt(8)
	v_pk_fma_f32 v[22:23], v[112:113], v[78:79], v[104:105] op_sel_hi:[0,1,1] neg_lo:[1,0,0] neg_hi:[1,0,0]
	v_pk_fma_f32 v[24:25], v[112:113], v[80:81], v[106:107] op_sel_hi:[0,1,1] neg_lo:[1,0,0] neg_hi:[1,0,0]
	ds_write_b32 v108, v114 offset:22848
	s_waitcnt lgkmcnt(6)
	v_pk_mul_f32 v[102:103], v[22:23], v[128:129]
	s_waitcnt lgkmcnt(4)
	v_pk_mul_f32 v[104:105], v[140:141], v[148:149] op_sel_hi:[1,0]
	v_pk_fma_f32 v[102:103], v[24:25], v[130:131], v[102:103]
	v_pk_mul_f32 v[106:107], v[142:143], v[148:149] op_sel_hi:[1,0]
	v_pk_mul_f32 v[150:151], v[96:97], v[22:23]
	v_add_f32_e32 v112, v102, v103
	v_pk_fma_f32 v[150:151], v[98:99], v[24:25], v[150:151]
	s_waitcnt lgkmcnt(3)
	v_pk_fma_f32 v[104:105], v[22:23], v[132:133], v[104:105]
	v_add_f32_e32 v114, v150, v151
	v_pk_fma_f32 v[106:107], v[24:25], v[134:135], v[106:107]
	v_add_f32_dpp v112, v112, v112 row_ror:8 row_mask:0xf bank_mask:0xf bound_ctrl:1
	v_add_f32_dpp v114, v114, v114 row_ror:8 row_mask:0xf bank_mask:0xf bound_ctrl:1
	ds_read_b128 v[70:73], v95 offset:2048
	v_add_f32_dpp v112, v112, v112 row_ror:4 row_mask:0xf bank_mask:0xf bound_ctrl:1
	v_add_f32_dpp v114, v114, v114 row_ror:4 row_mask:0xf bank_mask:0xf bound_ctrl:1
	ds_read_b128 v[82:85], v95 offset:14336
	v_add_f32_dpp v112, v112, v112 row_ror:2 row_mask:0xf bank_mask:0xf bound_ctrl:1
	v_add_f32_dpp v114, v114, v114 row_ror:2 row_mask:0xf bank_mask:0xf bound_ctrl:1
	ds_read_b32 v100, v108 offset:20992
	v_add_f32_dpp v112, v112, v112 row_ror:1 row_mask:0xf bank_mask:0xf bound_ctrl:1
	v_add_f32_dpp v114, v114, v114 row_ror:1 row_mask:0xf bank_mask:0xf bound_ctrl:1
	ds_read_b128 v[74:77], v95 offset:6144
	ds_read_b128 v[78:81], v95 offset:10240
	ds_read_b128 v[96:99], v95 offset:18432
	s_waitcnt lgkmcnt(8)
	v_pk_fma_f32 v[22:23], v[112:113], v[136:137], v[104:105] op_sel_hi:[0,1,1] neg_lo:[1,0,0] neg_hi:[1,0,0]
	v_pk_fma_f32 v[24:25], v[112:113], v[138:139], v[106:107] op_sel_hi:[0,1,1] neg_lo:[1,0,0] neg_hi:[1,0,0]
	ds_write_b32 v108, v114 offset:22912
	s_waitcnt lgkmcnt(6)
	v_pk_mul_f32 v[102:103], v[22:23], v[70:71]
	s_waitcnt lgkmcnt(4)
	v_pk_mul_f32 v[104:105], v[82:83], v[100:101] op_sel_hi:[1,0]
	v_pk_fma_f32 v[102:103], v[24:25], v[72:73], v[102:103]
	v_pk_mul_f32 v[106:107], v[84:85], v[100:101] op_sel_hi:[1,0]
	v_pk_mul_f32 v[150:151], v[144:145], v[22:23]
	v_add_f32_e32 v112, v102, v103
	v_pk_fma_f32 v[150:151], v[146:147], v[24:25], v[150:151]
	s_waitcnt lgkmcnt(3)
	v_pk_fma_f32 v[104:105], v[22:23], v[74:75], v[104:105]
	v_add_f32_e32 v114, v150, v151
	v_pk_fma_f32 v[106:107], v[24:25], v[76:77], v[106:107]
	v_add_f32_dpp v112, v112, v112 row_ror:8 row_mask:0xf bank_mask:0xf bound_ctrl:1
	v_add_f32_dpp v114, v114, v114 row_ror:8 row_mask:0xf bank_mask:0xf bound_ctrl:1
	ds_read_b128 v[128:131], v95 offset:2304
	v_add_f32_dpp v112, v112, v112 row_ror:4 row_mask:0xf bank_mask:0xf bound_ctrl:1
	v_add_f32_dpp v114, v114, v114 row_ror:4 row_mask:0xf bank_mask:0xf bound_ctrl:1
	ds_read_b128 v[140:143], v95 offset:14592
	v_add_f32_dpp v112, v112, v112 row_ror:2 row_mask:0xf bank_mask:0xf bound_ctrl:1
	v_add_f32_dpp v114, v114, v114 row_ror:2 row_mask:0xf bank_mask:0xf bound_ctrl:1
	ds_read_b32 v148, v108 offset:21056
	v_add_f32_dpp v112, v112, v112 row_ror:1 row_mask:0xf bank_mask:0xf bound_ctrl:1
	v_add_f32_dpp v114, v114, v114 row_ror:1 row_mask:0xf bank_mask:0xf bound_ctrl:1
	ds_read_b128 v[132:135], v95 offset:6400
	ds_read_b128 v[136:139], v95 offset:10496
	ds_read_b128 v[144:147], v95 offset:18688
	s_waitcnt lgkmcnt(8)
	v_pk_fma_f32 v[22:23], v[112:113], v[78:79], v[104:105] op_sel_hi:[0,1,1] neg_lo:[1,0,0] neg_hi:[1,0,0]
	v_pk_fma_f32 v[24:25], v[112:113], v[80:81], v[106:107] op_sel_hi:[0,1,1] neg_lo:[1,0,0] neg_hi:[1,0,0]
	ds_write_b32 v108, v114 offset:22976
	s_waitcnt lgkmcnt(6)
	v_pk_mul_f32 v[102:103], v[22:23], v[128:129]
	s_waitcnt lgkmcnt(4)
	v_pk_mul_f32 v[104:105], v[140:141], v[148:149] op_sel_hi:[1,0]
	v_pk_fma_f32 v[102:103], v[24:25], v[130:131], v[102:103]
	v_pk_mul_f32 v[106:107], v[142:143], v[148:149] op_sel_hi:[1,0]
	v_pk_mul_f32 v[150:151], v[96:97], v[22:23]
	v_add_f32_e32 v112, v102, v103
	v_pk_fma_f32 v[150:151], v[98:99], v[24:25], v[150:151]
	s_waitcnt lgkmcnt(3)
	v_pk_fma_f32 v[104:105], v[22:23], v[132:133], v[104:105]
	v_add_f32_e32 v114, v150, v151
	v_pk_fma_f32 v[106:107], v[24:25], v[134:135], v[106:107]
	v_add_f32_dpp v112, v112, v112 row_ror:8 row_mask:0xf bank_mask:0xf bound_ctrl:1
	v_add_f32_dpp v114, v114, v114 row_ror:8 row_mask:0xf bank_mask:0xf bound_ctrl:1
	ds_read_b128 v[70:73], v95 offset:2560
	v_add_f32_dpp v112, v112, v112 row_ror:4 row_mask:0xf bank_mask:0xf bound_ctrl:1
	v_add_f32_dpp v114, v114, v114 row_ror:4 row_mask:0xf bank_mask:0xf bound_ctrl:1
	ds_read_b128 v[82:85], v95 offset:14848
	v_add_f32_dpp v112, v112, v112 row_ror:2 row_mask:0xf bank_mask:0xf bound_ctrl:1
	v_add_f32_dpp v114, v114, v114 row_ror:2 row_mask:0xf bank_mask:0xf bound_ctrl:1
	ds_read_b32 v100, v108 offset:21120
	v_add_f32_dpp v112, v112, v112 row_ror:1 row_mask:0xf bank_mask:0xf bound_ctrl:1
	v_add_f32_dpp v114, v114, v114 row_ror:1 row_mask:0xf bank_mask:0xf bound_ctrl:1
	ds_read_b128 v[74:77], v95 offset:6656
	ds_read_b128 v[78:81], v95 offset:10752
	ds_read_b128 v[96:99], v95 offset:18944
	s_waitcnt lgkmcnt(8)
	v_pk_fma_f32 v[22:23], v[112:113], v[136:137], v[104:105] op_sel_hi:[0,1,1] neg_lo:[1,0,0] neg_hi:[1,0,0]
	v_pk_fma_f32 v[24:25], v[112:113], v[138:139], v[106:107] op_sel_hi:[0,1,1] neg_lo:[1,0,0] neg_hi:[1,0,0]
	ds_write_b32 v108, v114 offset:23040
	s_waitcnt lgkmcnt(6)
	v_pk_mul_f32 v[102:103], v[22:23], v[70:71]
	s_waitcnt lgkmcnt(4)
	v_pk_mul_f32 v[104:105], v[82:83], v[100:101] op_sel_hi:[1,0]
	v_pk_fma_f32 v[102:103], v[24:25], v[72:73], v[102:103]
	v_pk_mul_f32 v[106:107], v[84:85], v[100:101] op_sel_hi:[1,0]
	v_pk_mul_f32 v[150:151], v[144:145], v[22:23]
	v_add_f32_e32 v112, v102, v103
	v_pk_fma_f32 v[150:151], v[146:147], v[24:25], v[150:151]
	s_waitcnt lgkmcnt(3)
	v_pk_fma_f32 v[104:105], v[22:23], v[74:75], v[104:105]
	v_add_f32_e32 v114, v150, v151
	v_pk_fma_f32 v[106:107], v[24:25], v[76:77], v[106:107]
	v_add_f32_dpp v112, v112, v112 row_ror:8 row_mask:0xf bank_mask:0xf bound_ctrl:1
	v_add_f32_dpp v114, v114, v114 row_ror:8 row_mask:0xf bank_mask:0xf bound_ctrl:1
	ds_read_b128 v[128:131], v95 offset:2816
	v_add_f32_dpp v112, v112, v112 row_ror:4 row_mask:0xf bank_mask:0xf bound_ctrl:1
	v_add_f32_dpp v114, v114, v114 row_ror:4 row_mask:0xf bank_mask:0xf bound_ctrl:1
	ds_read_b128 v[140:143], v95 offset:15104
	v_add_f32_dpp v112, v112, v112 row_ror:2 row_mask:0xf bank_mask:0xf bound_ctrl:1
	v_add_f32_dpp v114, v114, v114 row_ror:2 row_mask:0xf bank_mask:0xf bound_ctrl:1
	ds_read_b32 v148, v108 offset:21184
	v_add_f32_dpp v112, v112, v112 row_ror:1 row_mask:0xf bank_mask:0xf bound_ctrl:1
	v_add_f32_dpp v114, v114, v114 row_ror:1 row_mask:0xf bank_mask:0xf bound_ctrl:1
	ds_read_b128 v[132:135], v95 offset:6912
	ds_read_b128 v[136:139], v95 offset:11008
	ds_read_b128 v[144:147], v95 offset:19200
	s_waitcnt lgkmcnt(8)
	v_pk_fma_f32 v[22:23], v[112:113], v[78:79], v[104:105] op_sel_hi:[0,1,1] neg_lo:[1,0,0] neg_hi:[1,0,0]
	v_pk_fma_f32 v[24:25], v[112:113], v[80:81], v[106:107] op_sel_hi:[0,1,1] neg_lo:[1,0,0] neg_hi:[1,0,0]
	ds_write_b32 v108, v114 offset:23104
	s_waitcnt lgkmcnt(6)
	v_pk_mul_f32 v[102:103], v[22:23], v[128:129]
	s_waitcnt lgkmcnt(4)
	v_pk_mul_f32 v[104:105], v[140:141], v[148:149] op_sel_hi:[1,0]
	v_pk_fma_f32 v[102:103], v[24:25], v[130:131], v[102:103]
	v_pk_mul_f32 v[106:107], v[142:143], v[148:149] op_sel_hi:[1,0]
	v_pk_mul_f32 v[150:151], v[96:97], v[22:23]
	v_add_f32_e32 v112, v102, v103
	v_pk_fma_f32 v[150:151], v[98:99], v[24:25], v[150:151]
	s_waitcnt lgkmcnt(3)
	v_pk_fma_f32 v[104:105], v[22:23], v[132:133], v[104:105]
	v_add_f32_e32 v114, v150, v151
	v_pk_fma_f32 v[106:107], v[24:25], v[134:135], v[106:107]
	v_add_f32_dpp v112, v112, v112 row_ror:8 row_mask:0xf bank_mask:0xf bound_ctrl:1
	v_add_f32_dpp v114, v114, v114 row_ror:8 row_mask:0xf bank_mask:0xf bound_ctrl:1
	ds_read_b128 v[70:73], v95 offset:3072
	v_add_f32_dpp v112, v112, v112 row_ror:4 row_mask:0xf bank_mask:0xf bound_ctrl:1
	v_add_f32_dpp v114, v114, v114 row_ror:4 row_mask:0xf bank_mask:0xf bound_ctrl:1
	ds_read_b128 v[82:85], v95 offset:15360
	v_add_f32_dpp v112, v112, v112 row_ror:2 row_mask:0xf bank_mask:0xf bound_ctrl:1
	v_add_f32_dpp v114, v114, v114 row_ror:2 row_mask:0xf bank_mask:0xf bound_ctrl:1
	ds_read_b32 v100, v108 offset:21248
	v_add_f32_dpp v112, v112, v112 row_ror:1 row_mask:0xf bank_mask:0xf bound_ctrl:1
	v_add_f32_dpp v114, v114, v114 row_ror:1 row_mask:0xf bank_mask:0xf bound_ctrl:1
	ds_read_b128 v[74:77], v95 offset:7168
	ds_read_b128 v[78:81], v95 offset:11264
	ds_read_b128 v[96:99], v95 offset:19456
	s_waitcnt lgkmcnt(8)
	v_pk_fma_f32 v[22:23], v[112:113], v[136:137], v[104:105] op_sel_hi:[0,1,1] neg_lo:[1,0,0] neg_hi:[1,0,0]
	v_pk_fma_f32 v[24:25], v[112:113], v[138:139], v[106:107] op_sel_hi:[0,1,1] neg_lo:[1,0,0] neg_hi:[1,0,0]
	ds_write_b32 v108, v114 offset:23168
	s_waitcnt lgkmcnt(6)
	v_pk_mul_f32 v[102:103], v[22:23], v[70:71]
	s_waitcnt lgkmcnt(4)
	v_pk_mul_f32 v[104:105], v[82:83], v[100:101] op_sel_hi:[1,0]
	v_pk_fma_f32 v[102:103], v[24:25], v[72:73], v[102:103]
	v_pk_mul_f32 v[106:107], v[84:85], v[100:101] op_sel_hi:[1,0]
	v_pk_mul_f32 v[150:151], v[144:145], v[22:23]
	v_add_f32_e32 v112, v102, v103
	v_pk_fma_f32 v[150:151], v[146:147], v[24:25], v[150:151]
	s_waitcnt lgkmcnt(3)
	v_pk_fma_f32 v[104:105], v[22:23], v[74:75], v[104:105]
	v_add_f32_e32 v114, v150, v151
	v_pk_fma_f32 v[106:107], v[24:25], v[76:77], v[106:107]
	v_add_f32_dpp v112, v112, v112 row_ror:8 row_mask:0xf bank_mask:0xf bound_ctrl:1
	v_add_f32_dpp v114, v114, v114 row_ror:8 row_mask:0xf bank_mask:0xf bound_ctrl:1
	ds_read_b128 v[128:131], v95 offset:3328
	v_add_f32_dpp v112, v112, v112 row_ror:4 row_mask:0xf bank_mask:0xf bound_ctrl:1
	v_add_f32_dpp v114, v114, v114 row_ror:4 row_mask:0xf bank_mask:0xf bound_ctrl:1
	ds_read_b128 v[140:143], v95 offset:15616
	v_add_f32_dpp v112, v112, v112 row_ror:2 row_mask:0xf bank_mask:0xf bound_ctrl:1
	v_add_f32_dpp v114, v114, v114 row_ror:2 row_mask:0xf bank_mask:0xf bound_ctrl:1
	ds_read_b32 v148, v108 offset:21312
	v_add_f32_dpp v112, v112, v112 row_ror:1 row_mask:0xf bank_mask:0xf bound_ctrl:1
	v_add_f32_dpp v114, v114, v114 row_ror:1 row_mask:0xf bank_mask:0xf bound_ctrl:1
	ds_read_b128 v[132:135], v95 offset:7424
	ds_read_b128 v[136:139], v95 offset:11520
	ds_read_b128 v[144:147], v95 offset:19712
	s_waitcnt lgkmcnt(8)
	v_pk_fma_f32 v[22:23], v[112:113], v[78:79], v[104:105] op_sel_hi:[0,1,1] neg_lo:[1,0,0] neg_hi:[1,0,0]
	v_pk_fma_f32 v[24:25], v[112:113], v[80:81], v[106:107] op_sel_hi:[0,1,1] neg_lo:[1,0,0] neg_hi:[1,0,0]
	ds_write_b32 v108, v114 offset:23232
	s_waitcnt lgkmcnt(6)
	v_pk_mul_f32 v[102:103], v[22:23], v[128:129]
	s_waitcnt lgkmcnt(4)
	v_pk_mul_f32 v[104:105], v[140:141], v[148:149] op_sel_hi:[1,0]
	v_pk_fma_f32 v[102:103], v[24:25], v[130:131], v[102:103]
	v_pk_mul_f32 v[106:107], v[142:143], v[148:149] op_sel_hi:[1,0]
	v_pk_mul_f32 v[150:151], v[96:97], v[22:23]
	v_add_f32_e32 v112, v102, v103
	v_pk_fma_f32 v[150:151], v[98:99], v[24:25], v[150:151]
	s_waitcnt lgkmcnt(3)
	v_pk_fma_f32 v[104:105], v[22:23], v[132:133], v[104:105]
	v_add_f32_e32 v114, v150, v151
	v_pk_fma_f32 v[106:107], v[24:25], v[134:135], v[106:107]
	v_add_f32_dpp v112, v112, v112 row_ror:8 row_mask:0xf bank_mask:0xf bound_ctrl:1
	v_add_f32_dpp v114, v114, v114 row_ror:8 row_mask:0xf bank_mask:0xf bound_ctrl:1
	ds_read_b128 v[70:73], v95 offset:3584
	v_add_f32_dpp v112, v112, v112 row_ror:4 row_mask:0xf bank_mask:0xf bound_ctrl:1
	v_add_f32_dpp v114, v114, v114 row_ror:4 row_mask:0xf bank_mask:0xf bound_ctrl:1
	ds_read_b128 v[82:85], v95 offset:15872
	v_add_f32_dpp v112, v112, v112 row_ror:2 row_mask:0xf bank_mask:0xf bound_ctrl:1
	v_add_f32_dpp v114, v114, v114 row_ror:2 row_mask:0xf bank_mask:0xf bound_ctrl:1
	ds_read_b32 v100, v108 offset:21376
	v_add_f32_dpp v112, v112, v112 row_ror:1 row_mask:0xf bank_mask:0xf bound_ctrl:1
	v_add_f32_dpp v114, v114, v114 row_ror:1 row_mask:0xf bank_mask:0xf bound_ctrl:1
	ds_read_b128 v[74:77], v95 offset:7680
	ds_read_b128 v[78:81], v95 offset:11776
	ds_read_b128 v[96:99], v95 offset:19968
	s_waitcnt lgkmcnt(8)
	v_pk_fma_f32 v[22:23], v[112:113], v[136:137], v[104:105] op_sel_hi:[0,1,1] neg_lo:[1,0,0] neg_hi:[1,0,0]
	v_pk_fma_f32 v[24:25], v[112:113], v[138:139], v[106:107] op_sel_hi:[0,1,1] neg_lo:[1,0,0] neg_hi:[1,0,0]
	ds_write_b32 v108, v114 offset:23296
	s_waitcnt lgkmcnt(6)
	v_pk_mul_f32 v[102:103], v[22:23], v[70:71]
	s_waitcnt lgkmcnt(4)
	v_pk_mul_f32 v[104:105], v[82:83], v[100:101] op_sel_hi:[1,0]
	v_pk_fma_f32 v[102:103], v[24:25], v[72:73], v[102:103]
	v_pk_mul_f32 v[106:107], v[84:85], v[100:101] op_sel_hi:[1,0]
	v_pk_mul_f32 v[150:151], v[144:145], v[22:23]
	v_add_f32_e32 v112, v102, v103
	v_pk_fma_f32 v[150:151], v[146:147], v[24:25], v[150:151]
	s_waitcnt lgkmcnt(3)
	v_pk_fma_f32 v[104:105], v[22:23], v[74:75], v[104:105]
	v_add_f32_e32 v114, v150, v151
	v_pk_fma_f32 v[106:107], v[24:25], v[76:77], v[106:107]
	v_add_f32_dpp v112, v112, v112 row_ror:8 row_mask:0xf bank_mask:0xf bound_ctrl:1
	v_add_f32_dpp v114, v114, v114 row_ror:8 row_mask:0xf bank_mask:0xf bound_ctrl:1
	ds_read_b128 v[128:131], v95 offset:3840
	v_add_f32_dpp v112, v112, v112 row_ror:4 row_mask:0xf bank_mask:0xf bound_ctrl:1
	v_add_f32_dpp v114, v114, v114 row_ror:4 row_mask:0xf bank_mask:0xf bound_ctrl:1
	ds_read_b128 v[140:143], v95 offset:16128
	v_add_f32_dpp v112, v112, v112 row_ror:2 row_mask:0xf bank_mask:0xf bound_ctrl:1
	v_add_f32_dpp v114, v114, v114 row_ror:2 row_mask:0xf bank_mask:0xf bound_ctrl:1
	ds_read_b32 v148, v108 offset:21440
	v_add_f32_dpp v112, v112, v112 row_ror:1 row_mask:0xf bank_mask:0xf bound_ctrl:1
	v_add_f32_dpp v114, v114, v114 row_ror:1 row_mask:0xf bank_mask:0xf bound_ctrl:1
	ds_read_b128 v[132:135], v95 offset:7936
	ds_read_b128 v[136:139], v95 offset:12032
	ds_read_b128 v[144:147], v95 offset:20224
	s_waitcnt lgkmcnt(8)
	v_pk_fma_f32 v[22:23], v[112:113], v[78:79], v[104:105] op_sel_hi:[0,1,1] neg_lo:[1,0,0] neg_hi:[1,0,0]
	v_pk_fma_f32 v[24:25], v[112:113], v[80:81], v[106:107] op_sel_hi:[0,1,1] neg_lo:[1,0,0] neg_hi:[1,0,0]
	ds_write_b32 v108, v114 offset:23360
	s_waitcnt lgkmcnt(6)
	v_pk_mul_f32 v[102:103], v[22:23], v[128:129]
	s_waitcnt lgkmcnt(4)
	v_pk_mul_f32 v[104:105], v[140:141], v[148:149] op_sel_hi:[1,0]
	v_pk_fma_f32 v[102:103], v[24:25], v[130:131], v[102:103]
	v_pk_mul_f32 v[106:107], v[142:143], v[148:149] op_sel_hi:[1,0]
	v_pk_mul_f32 v[150:151], v[96:97], v[22:23]
	v_add_f32_e32 v112, v102, v103
	v_pk_fma_f32 v[150:151], v[98:99], v[24:25], v[150:151]
	s_waitcnt lgkmcnt(3)
	v_pk_fma_f32 v[104:105], v[22:23], v[132:133], v[104:105]
	v_add_f32_e32 v114, v150, v151
	v_pk_fma_f32 v[106:107], v[24:25], v[134:135], v[106:107]
	v_add_f32_dpp v112, v112, v112 row_ror:8 row_mask:0xf bank_mask:0xf bound_ctrl:1
	v_add_f32_dpp v114, v114, v114 row_ror:8 row_mask:0xf bank_mask:0xf bound_ctrl:1
	s_nop 0
	v_add_f32_dpp v112, v112, v112 row_ror:4 row_mask:0xf bank_mask:0xf bound_ctrl:1
	v_add_f32_dpp v114, v114, v114 row_ror:4 row_mask:0xf bank_mask:0xf bound_ctrl:1
	s_nop 0
	v_add_f32_dpp v112, v112, v112 row_ror:2 row_mask:0xf bank_mask:0xf bound_ctrl:1
	v_add_f32_dpp v114, v114, v114 row_ror:2 row_mask:0xf bank_mask:0xf bound_ctrl:1
	s_nop 0
	v_add_f32_dpp v112, v112, v112 row_ror:1 row_mask:0xf bank_mask:0xf bound_ctrl:1
	v_add_f32_dpp v114, v114, v114 row_ror:1 row_mask:0xf bank_mask:0xf bound_ctrl:1
	s_nop 0
	s_waitcnt lgkmcnt(2)
	v_pk_fma_f32 v[22:23], v[112:113], v[136:137], v[104:105] op_sel_hi:[0,1,1] neg_lo:[1,0,0] neg_hi:[1,0,0]
	v_pk_fma_f32 v[24:25], v[112:113], v[138:139], v[106:107] op_sel_hi:[0,1,1] neg_lo:[1,0,0] neg_hi:[1,0,0]
	ds_write_b32 v108, v114 offset:23424
	s_waitcnt lgkmcnt(2)
	v_pk_mul_f32 v[150:151], v[144:145], v[22:23]
	v_pk_fma_f32 v[150:151], v[146:147], v[24:25], v[150:151]
	v_add_f32_e32 v114, v150, v151
	s_nop 1
	v_add_f32_dpp v114, v114, v114 row_ror:8 row_mask:0xf bank_mask:0xf bound_ctrl:1
	s_nop 0
	s_nop 0
	v_add_f32_dpp v114, v114, v114 row_ror:4 row_mask:0xf bank_mask:0xf bound_ctrl:1
	s_nop 0
	s_nop 0
	v_add_f32_dpp v114, v114, v114 row_ror:2 row_mask:0xf bank_mask:0xf bound_ctrl:1
	s_nop 0
	s_nop 0
	v_add_f32_dpp v114, v114, v114 row_ror:1 row_mask:0xf bank_mask:0xf bound_ctrl:1
	s_nop 0
	ds_write_b32 v108, v114 offset:23488
	s_add_u32 s28, s28, 16
	s_cmp_lt_u32 s28, s25
	s_cbranch_scc1 .Lrw0_loop
	s_waitcnt lgkmcnt(0)
	s_barrier
	ds_read_b32 v89, v115 offset:22528
	s_sub_u32 s98, s28, 16
	v_add_u32_e32 v87, s98, v127
	v_mad_i64_i32 v[104:105], vcc, v87, v20, v[18:19]
	s_waitcnt lgkmcnt(0)
	v_cvt_pk_bf16_f32 v89, v89, v89
	global_store_short v[104:105], v89, off
	v_lshl_add_u32 v87, s17, 4, v127
	v_lshl_add_u32 v89, v87, 8, v95
	s_cmp_eq_u32 s18, 3
	s_cbranch_scc0 .Lrw0_f_not3
	s_load_dwordx2 s[36:37], s[14:15], 0x120
	s_waitcnt lgkmcnt(0)
	s_lshl_b32 s98, s42, 14
	s_add_u32 s36, s36, s98
	s_addc_u32 s37, s37, 0
	s_add_u32 s36, s36, 0x5e00000
	s_addc_u32 s37, s37, 0
	global_store_dwordx4 v89, v[22:25], s[36:37]
	s_branch .Lrw0_f_done
.Lrw0_f_not3:
	s_cmp_eq_u32 s18, 0
	s_cbranch_scc0 .Lrw0_f_done
	s_load_dwordx2 s[36:37], s[14:15], 0x148
	s_waitcnt lgkmcnt(0)
	s_lshl_b32 s98, s16, 14
	s_add_u32 s36, s36, s98
	s_addc_u32 s37, s37, 0
	global_store_dwordx4 v89, v[22:25], s[36:37]
.Lrw0_f_done:
	s_mov_b64 s[56:57], 0
	s_movk_i32 s58, 0x1600
	s_movk_i32 s59, 0x5800
	s_branch .LBB0_742

.LBB0_1291:
	s_and_b32 s0, s6, 0x7c0
	s_ashr_i32 s16, s2, 5
	s_and_b32 s14, s8, 0xfffff000
	v_add_u32_e32 v0, s0, v21
	s_and_b32 s15, s16, 1
	s_addk_i32 s14, 0x1000
	v_add_u32_e32 v33, 0x800, v0
	v_or_b32_e32 v0, v33, v20
	s_cmp_eq_u32 s15, 0
	s_cselect_b64 vcc, -1, 0
	v_sub_u32_e32 v1, 0xfff, v0
	v_cndmask_b32_e32 v0, v1, v0, vcc
	v_add_u32_e32 v0, s14, v0
	s_movk_i32 s0, 0x1520
	v_mad_i64_i32 v[0:1], s[0:1], v0, s0, v[26:27]
	s_and_b32 s0, s2, 0xc0
	s_lshl_b32 s4, s0, 1
	v_lshl_add_u64 v[0:1], v[0:1], 0, s[4:5]
	v_lshl_add_u64 v[0:1], v[0:1], 0, v[22:23]
	s_mov_b64 s[0:1], 0x1320
	v_lshl_add_u64 v[2:3], v[0:1], 0, s[0:1]
	v_add_co_u32_e64 v0, s[0:1], s10, v0
	s_ashr_i32 s17, s16, 31
	s_nop 0
	v_addc_co_u32_e64 v1, s[0:1], 0, v1, s[0:1]
	s_lshl_b64 s[0:1], s[16:17], 14
	s_nop 0
	v_lshl_add_u64 v[30:31], v[24:25], 0, s[0:1]
	global_load_dwordx4 v[16:19], v[0:1], off offset:800
	global_load_dwordx4 v[12:15], v[2:3], off offset:64
	s_nop 0
	global_load_dwordx4 v[0:3], v[30:31], off
	global_load_dwordx4 v[4:7], v[30:31], off offset:16
	s_mov_b64 s[0:1], 0x1000
	s_waitcnt vmcnt(1)
	s_waitcnt vmcnt(0)
	v_cvt_pk_bf16_f32 v36, v1, v1
	v_cvt_pk_bf16_f32 v1, v2, v2
	v_cvt_pk_bf16_f32 v34, v3, v3
	v_cvt_pk_bf16_f32 v2, v4, v4
	v_cvt_pk_bf16_f32 v4, v5, v5
	v_cvt_pk_bf16_f32 v3, v6, v7
	v_perm_b32 v2, v4, v2, s12
	global_load_dwordx4 v[4:7], v[30:31], off offset:128
	global_load_dwordx4 v[8:11], v[30:31], off offset:144
	v_cvt_pk_bf16_f32 v0, v0, v0
	v_perm_b32 v1, v34, v1, s12
	v_perm_b32 v0, v36, v0, s12
	s_waitcnt vmcnt(1)
	s_waitcnt vmcnt(0)
	v_cvt_pk_bf16_f32 v40, v5, v5
	v_cvt_pk_bf16_f32 v5, v6, v6
	v_cvt_pk_bf16_f32 v38, v7, v7
	v_cvt_pk_bf16_f32 v6, v8, v8
	v_cvt_pk_bf16_f32 v8, v9, v9
	v_cvt_pk_bf16_f32 v7, v10, v11
	v_perm_b32 v6, v8, v6, s12
	v_lshl_add_u64 v[8:9], v[30:31], 0, s[0:1]
	v_add_co_u32_e64 v34, s[0:1], s10, v30
	v_mfma_f32_16x16x32_bf16 v[0:3], v[16:19], v[0:3], 0
	s_nop 0
	v_addc_co_u32_e64 v35, s[0:1], 0, v31, s[0:1]
	s_movk_i32 s0, 0x2000
	v_cvt_pk_bf16_f32 v4, v4, v4
	v_perm_b32 v5, v38, v5, s12
	v_add_co_u32_e64 v38, s[0:1], s0, v30
	v_perm_b32 v4, v40, v4, s12
	s_nop 0
	v_addc_co_u32_e64 v39, s[0:1], 0, v31, s[0:1]
	v_mfma_f32_16x16x32_bf16 v[0:3], v[12:15], v[4:7], v[0:3]
	global_load_dwordx4 v[4:7], v[38:39], off offset:-4096
	s_nop 0
	global_load_dwordx4 v[8:11], v[8:9], off offset:16
	s_mov_b64 s[0:1], 0x1080
	s_waitcnt vmcnt(1)
	s_waitcnt vmcnt(0)
	v_cvt_pk_bf16_f32 v40, v5, v5
	v_cvt_pk_bf16_f32 v5, v6, v6
	v_cvt_pk_bf16_f32 v6, v7, v7
	v_cvt_pk_bf16_f32 v7, v10, v10
	v_cvt_pk_bf16_f32 v10, v11, v11
	v_lshl_add_u64 v[36:37], v[30:31], 0, s[0:1]
	v_perm_b32 v5, v6, v5, s12
	v_perm_b32 v7, v10, v7, s12
	v_cvt_pk_bf16_f32 v6, v8, v9
	global_load_dwordx4 v[8:11], v[34:35], off offset:128
	s_nop 0
	global_load_dwordx4 v[34:37], v[36:37], off offset:16
	v_cvt_pk_bf16_f32 v4, v4, v4
	v_perm_b32 v4, v40, v4, s12
	s_mov_b64 s[0:1], 0x2000
	s_waitcnt vmcnt(1)
	v_mfma_f32_16x16x32_bf16 v[4:7], v[16:19], v[4:7], 0
	s_waitcnt vmcnt(0)
	v_cvt_pk_bf16_f32 v8, v8, v8
	v_cvt_pk_bf16_f32 v42, v9, v9
	v_cvt_pk_bf16_f32 v9, v10, v10
	v_cvt_pk_bf16_f32 v10, v11, v11
	v_cvt_pk_bf16_f32 v11, v36, v36
	v_cvt_pk_bf16_f32 v36, v37, v37
	v_perm_b32 v9, v10, v9, s12
	v_perm_b32 v8, v42, v8, s12
	v_perm_b32 v11, v36, v11, s12
	v_cvt_pk_bf16_f32 v10, v34, v35
	v_lshl_add_u64 v[34:35], v[30:31], 0, s[0:1]
	s_mov_b64 s[0:1], 0x2080
	v_mfma_f32_16x16x32_bf16 v[4:7], v[12:15], v[8:11], v[4:7]
	global_load_dwordx4 v[8:11], v[38:39], off
	s_nop 0
	global_load_dwordx4 v[34:37], v[34:35], off offset:16
	s_waitcnt vmcnt(1)
	s_waitcnt vmcnt(0)
	v_cvt_pk_bf16_f32 v42, v9, v9
	v_cvt_pk_bf16_f32 v9, v10, v10
	v_cvt_pk_bf16_f32 v10, v11, v11
	v_cvt_pk_bf16_f32 v11, v36, v36
	v_cvt_pk_bf16_f32 v36, v37, v37
	v_lshl_add_u64 v[40:41], v[30:31], 0, s[0:1]
	v_perm_b32 v9, v10, v9, s12
	v_perm_b32 v11, v36, v11, s12
	v_cvt_pk_bf16_f32 v10, v34, v35
	global_load_dwordx4 v[34:37], v[38:39], off offset:128
	s_nop 0
	global_load_dwordx4 v[38:41], v[40:41], off offset:16
	v_cvt_pk_bf16_f32 v8, v8, v8
	v_perm_b32 v8, v42, v8, s12
	s_mov_b64 s[0:1], 0x3000
	s_waitcnt vmcnt(1)
	s_waitcnt vmcnt(0)
	v_mfma_f32_16x16x32_bf16 v[8:11], v[16:19], v[8:11], 0
	v_cvt_pk_bf16_f32 v44, v35, v35
	v_cvt_pk_bf16_f32 v35, v36, v36
	v_cvt_pk_bf16_f32 v36, v37, v37
	v_perm_b32 v35, v36, v35, s12
	v_cvt_pk_bf16_f32 v36, v38, v39
	v_lshl_add_u64 v[38:39], v[30:31], 0, s[0:1]
	s_movk_i32 s0, 0x3000
	v_cvt_pk_bf16_f32 v34, v34, v34
	v_cvt_pk_bf16_f32 v37, v40, v40
	v_cvt_pk_bf16_f32 v40, v41, v41
	v_add_co_u32_e64 v42, s[0:1], s0, v30
	v_perm_b32 v34, v44, v34, s12
	v_perm_b32 v37, v40, v37, s12
	v_addc_co_u32_e64 v43, s[0:1], 0, v31, s[0:1]
	s_nop 0
	v_mfma_f32_16x16x32_bf16 v[8:11], v[12:15], v[34:37], v[8:11]
	global_load_dwordx4 v[34:37], v[42:43], off
	s_nop 0
	global_load_dwordx4 v[38:41], v[38:39], off offset:16
	s_mov_b64 s[0:1], 0x3080
	v_lshl_add_u64 v[30:31], v[30:31], 0, s[0:1]
	s_lshl_b32 s0, s15, 9
	s_add_u32 s0, s22, s0
	s_addc_u32 s1, s23, 0
	s_add_u32 s0, s0, s4
	s_addc_u32 s1, s1, 0
	s_add_i32 s2, s2, s3
	s_add_i32 s6, s6, s7
	s_add_i32 s8, s8, s9
	s_cmpk_lt_i32 s2, 0x400
	s_waitcnt vmcnt(1)
	s_waitcnt vmcnt(0)
	v_cvt_pk_bf16_f32 v34, v34, v34
	v_cvt_pk_bf16_f32 v46, v35, v35
	v_cvt_pk_bf16_f32 v35, v36, v36
	v_cvt_pk_bf16_f32 v36, v37, v37
	v_cvt_pk_bf16_f32 v37, v40, v40
	v_cvt_pk_bf16_f32 v40, v41, v41
	v_perm_b32 v35, v36, v35, s12
	v_perm_b32 v34, v46, v34, s12
	v_perm_b32 v37, v40, v37, s12
	v_cvt_pk_bf16_f32 v36, v38, v39
	s_nop 1
	v_mfma_f32_16x16x32_bf16 v[16:19], v[16:19], v[34:37], 0
	global_load_dwordx4 v[34:37], v[42:43], off offset:128
	global_load_dwordx4 v[38:41], v[30:31], off offset:16
	s_waitcnt vmcnt(1)
	s_waitcnt vmcnt(0)
	v_cvt_pk_bf16_f32 v34, v34, v34
	v_cvt_pk_bf16_f32 v42, v35, v35
	v_cvt_pk_bf16_f32 v31, v36, v36
	v_cvt_pk_bf16_f32 v30, v37, v37
	v_cvt_pk_bf16_f32 v36, v38, v38
	v_cvt_pk_bf16_f32 v38, v39, v39
	v_perm_b32 v35, v30, v31, s12
	v_perm_b32 v34, v42, v34, s12
	v_cvt_pk_bf16_f32 v37, v40, v41
	v_perm_b32 v36, v38, v36, s12
	v_or_b32_e32 v30, v33, v32
	s_nop 0
	v_mfma_f32_16x16x32_bf16 v[12:15], v[12:15], v[34:37], v[16:19]
	s_nop 2
	v_sub_u32_e32 v18, 0xfff, v30
	v_cndmask_b32_e32 v18, v18, v30, vcc
	v_lshl_add_u64 v[16:17], s[0:1], 0, v[28:29]
	v_add_u32_e32 v18, s14, v18
	v_mad_i64_i32 v[18:19], s[0:1], v18, s13, v[16:17]
	global_load_ushort v31, v[18:19], off
	s_waitcnt vmcnt(0)
	v_lshlrev_b32_e32 v31, 16, v31
	v_add_f32_e32 v0, v0, v31
	v_cvt_pk_bf16_f32 v0, v0, v0
	global_store_short_d16_hi v[18:19], v0, off
	global_load_ushort v0, v[18:19], off offset:32
	s_waitcnt vmcnt(0)
	v_lshlrev_b32_e32 v0, 16, v0
	v_add_f32_e32 v0, v4, v0
	v_cvt_pk_bf16_f32 v0, v0, v0
	global_store_short_d16_hi v[18:19], v0, off offset:32
	global_load_ushort v0, v[18:19], off offset:64
	s_waitcnt vmcnt(0)
	v_lshlrev_b32_e32 v0, 16, v0
	v_add_f32_e32 v0, v8, v0
	v_cvt_pk_bf16_f32 v0, v0, v0
	global_store_short_d16_hi v[18:19], v0, off offset:64
	global_load_ushort v0, v[18:19], off offset:96
	s_waitcnt vmcnt(0)
	v_lshlrev_b32_e32 v0, 16, v0
	v_add_f32_e32 v0, v12, v0
	v_cvt_pk_bf16_f32 v0, v0, v0
	global_store_short_d16_hi v[18:19], v0, off offset:96
	v_or_b32_e32 v0, 1, v30
	v_sub_u32_e32 v4, 0xfff, v0
	v_cndmask_b32_e32 v0, v4, v0, vcc
	v_add_u32_e32 v0, s14, v0
	v_mad_i64_i32 v[18:19], s[0:1], v0, s13, v[16:17]
	global_load_ushort v0, v[18:19], off
	s_waitcnt vmcnt(0)
	v_lshlrev_b32_e32 v0, 16, v0
	v_add_f32_e32 v0, v1, v0
	v_cvt_pk_bf16_f32 v0, v0, v0
	global_store_short_d16_hi v[18:19], v0, off
	global_load_ushort v0, v[18:19], off offset:32
	s_waitcnt vmcnt(0)
	v_lshlrev_b32_e32 v0, 16, v0
	v_add_f32_e32 v0, v5, v0
	v_cvt_pk_bf16_f32 v0, v0, v0
	global_store_short_d16_hi v[18:19], v0, off offset:32
	global_load_ushort v0, v[18:19], off offset:64
	s_waitcnt vmcnt(0)
	v_lshlrev_b32_e32 v0, 16, v0
	v_add_f32_e32 v0, v9, v0
	v_cvt_pk_bf16_f32 v0, v0, v0
	global_store_short_d16_hi v[18:19], v0, off offset:64
	global_load_ushort v0, v[18:19], off offset:96
	s_waitcnt vmcnt(0)
	v_lshlrev_b32_e32 v0, 16, v0
	v_add_f32_e32 v0, v13, v0
	v_cvt_pk_bf16_f32 v0, v0, v0
	global_store_short_d16_hi v[18:19], v0, off offset:96
	v_or_b32_e32 v0, 2, v30
	v_sub_u32_e32 v1, 0xfff, v0
	v_cndmask_b32_e32 v0, v1, v0, vcc
	v_add_u32_e32 v0, s14, v0
	v_mad_i64_i32 v[0:1], s[0:1], v0, s13, v[16:17]
	global_load_ushort v4, v[0:1], off
	s_waitcnt vmcnt(0)
	v_lshlrev_b32_e32 v4, 16, v4
	v_add_f32_e32 v2, v2, v4
	v_cvt_pk_bf16_f32 v2, v2, v2
	global_store_short_d16_hi v[0:1], v2, off
	global_load_ushort v2, v[0:1], off offset:32
	s_waitcnt vmcnt(0)
	v_lshlrev_b32_e32 v2, 16, v2
	v_add_f32_e32 v2, v6, v2
	v_cvt_pk_bf16_f32 v2, v2, v2
	global_store_short_d16_hi v[0:1], v2, off offset:32
	global_load_ushort v2, v[0:1], off offset:64
	s_waitcnt vmcnt(0)
	v_lshlrev_b32_e32 v2, 16, v2
	v_add_f32_e32 v2, v10, v2
	v_cvt_pk_bf16_f32 v2, v2, v2
	global_store_short_d16_hi v[0:1], v2, off offset:64
	global_load_ushort v2, v[0:1], off offset:96
	s_waitcnt vmcnt(0)
	v_lshlrev_b32_e32 v2, 16, v2
	v_add_f32_e32 v2, v14, v2
	v_cvt_pk_bf16_f32 v2, v2, v2
	global_store_short_d16_hi v[0:1], v2, off offset:96
	v_or_b32_e32 v0, 3, v30
	v_sub_u32_e32 v1, 0xfff, v0
	v_cndmask_b32_e32 v0, v1, v0, vcc
	v_add_u32_e32 v0, s14, v0
	v_mad_i64_i32 v[0:1], s[0:1], v0, s13, v[16:17]
	global_load_ushort v2, v[0:1], off
	s_waitcnt vmcnt(0)
	v_lshlrev_b32_e32 v2, 16, v2
	v_add_f32_e32 v2, v3, v2
	v_cvt_pk_bf16_f32 v2, v2, v2
	global_store_short_d16_hi v[0:1], v2, off
	global_load_ushort v2, v[0:1], off offset:32
	s_waitcnt vmcnt(0)
	v_lshlrev_b32_e32 v2, 16, v2
	v_add_f32_e32 v2, v7, v2
	v_cvt_pk_bf16_f32 v2, v2, v2
	global_store_short_d16_hi v[0:1], v2, off offset:32
	global_load_ushort v2, v[0:1], off offset:64
	s_waitcnt vmcnt(0)
	v_lshlrev_b32_e32 v2, 16, v2
	v_add_f32_e32 v2, v11, v2
	v_cvt_pk_bf16_f32 v2, v2, v2
	global_store_short_d16_hi v[0:1], v2, off offset:64
	global_load_ushort v2, v[0:1], off offset:96
	s_waitcnt vmcnt(0)
	v_lshlrev_b32_e32 v2, 16, v2
	v_add_f32_e32 v2, v15, v2
	v_cvt_pk_bf16_f32 v2, v2, v2
	global_store_short_d16_hi v[0:1], v2, off offset:96
	s_cbranch_scc1 .LBB0_1291

.LBB0_1347:
	v_lshl_add_u64 v[116:117], v[166:167], 0, v[168:169]
	global_load_dwordx4 v[112:115], v[116:117], off offset:2048
	v_lshl_add_u64 v[174:175], v[172:173], 0, v[168:169]
	v_cmp_gt_i32_e64 s[6:7], s2, v197
	v_lshl_add_u64 v[180:181], v[166:167], 0, v[164:165]
	v_lshl_add_u64 v[178:179], v[170:171], 0, v[164:165]
	s_waitcnt vmcnt(0)
	v_lshlrev_b32_e32 v61, 16, v113
	v_and_b32_e32 v119, 0xffff0000, v113
	v_and_b32_e32 v118, 0xffff0000, v112
	v_lshlrev_b32_e32 v63, 16, v112
	v_and_b32_e32 v113, 0xffff0000, v115
	v_and_b32_e32 v112, 0xffff0000, v114
	v_mul_f32_e32 v69, v70, v61
	v_lshlrev_b32_e32 v61, 16, v114
	v_lshlrev_b32_e32 v65, 16, v115
	v_pk_mul_f32 v[128:129], v[146:147], v[112:113]
	global_load_dwordx4 v[112:115], v[174:175], off offset:1024
	v_pk_mul_f32 v[120:121], v[158:159], v[118:119]
	s_waitcnt lgkmcnt(0)
	v_mul_f32_e32 v71, v68, v63
	v_mul_f32_e32 v63, v44, v61
	v_mul_f32_e32 v61, v46, v65
	s_waitcnt vmcnt(0)
	v_lshlrev_b32_e32 v130, 16, v112
	v_lshlrev_b32_e32 v131, 16, v113
	v_and_b32_e32 v135, 0xffff0000, v113
	v_and_b32_e32 v134, 0xffff0000, v112
	v_lshlrev_b32_e32 v124, 16, v114
	v_lshlrev_b32_e32 v125, 16, v115
	v_and_b32_e32 v119, 0xffff0000, v115
	v_and_b32_e32 v118, 0xffff0000, v114
	global_load_dwordx4 v[112:115], v[174:175], off offset:1792
	s_waitcnt vmcnt(0)
	v_lshlrev_b32_e32 v132, 16, v112
	v_lshlrev_b32_e32 v133, 16, v113
	v_and_b32_e32 v177, 0xffff0000, v113
	v_and_b32_e32 v176, 0xffff0000, v112
	v_lshlrev_b32_e32 v126, 16, v114
	v_lshlrev_b32_e32 v127, 16, v115
	v_and_b32_e32 v123, 0xffff0000, v115
	v_and_b32_e32 v122, 0xffff0000, v114
	global_load_dwordx4 v[112:115], v[116:117], off offset:1280
	v_pk_add_f32 v[130:131], v[130:131], v[132:133]
	v_pk_add_f32 v[186:187], v[124:125], v[126:127]
	v_pk_add_f32 v[188:189], v[118:119], v[122:123]
	v_pk_add_f32 v[134:135], v[134:135], v[176:177]
	v_lshl_add_u64 v[176:177], v[172:173], 0, v[164:165]
	s_waitcnt vmcnt(0)
	v_lshlrev_b32_e32 v67, 16, v112
	v_lshlrev_b32_e32 v65, 16, v113
	v_mul_f32_e32 v77, 0xbfb8aa3b, v67
	v_and_b32_e32 v75, 0xffff0000, v112
	v_exp_f32_e32 v112, v77
	v_mul_f32_e32 v77, 0xbfb8aa3b, v65
	v_and_b32_e32 v73, 0xffff0000, v113
	v_exp_f32_e32 v113, v77
	s_nop 0
	v_pk_add_f32 v[112:113], v[112:113], 1.0 op_sel_hi:[1,0]
	s_nop 0
	v_rcp_f32_e32 v79, v113
	s_nop 0
	v_mul_f32_e32 v133, v65, v79
	v_rcp_f32_e32 v77, v112
	s_nop 0
	v_mul_f32_e32 v132, v67, v77
	v_mul_f32_e32 v65, 0xbfb8aa3b, v75
	v_exp_f32_e32 v112, v65
	v_mul_f32_e32 v65, 0xbfb8aa3b, v73
	v_exp_f32_e32 v113, v65
	s_nop 0
	v_pk_add_f32 v[112:113], v[112:113], 1.0 op_sel_hi:[1,0]
	s_nop 0
	v_rcp_f32_e32 v67, v113
	s_nop 0
	v_mul_f32_e32 v185, v73, v67
	v_rcp_f32_e32 v67, v112
	s_nop 0
	v_mul_f32_e32 v184, v75, v67
	v_lshlrev_b32_e32 v67, 16, v114
	v_lshlrev_b32_e32 v65, 16, v115
	v_mul_f32_e32 v77, 0xbfb8aa3b, v67
	v_exp_f32_e32 v112, v77
	v_mul_f32_e32 v77, 0xbfb8aa3b, v65
	v_exp_f32_e32 v113, v77
	v_and_b32_e32 v75, 0xffff0000, v114
	v_and_b32_e32 v73, 0xffff0000, v115
	v_pk_add_f32 v[112:113], v[112:113], 1.0 op_sel_hi:[1,0]
	s_nop 0
	v_rcp_f32_e32 v79, v113
	s_nop 0
	v_mul_f32_e32 v191, v65, v79
	v_rcp_f32_e32 v77, v112
	s_nop 0
	v_mul_f32_e32 v190, v67, v77
	v_mul_f32_e32 v65, 0xbfb8aa3b, v75
	v_exp_f32_e32 v112, v65
	v_mul_f32_e32 v65, 0xbfb8aa3b, v73
	v_exp_f32_e32 v113, v65
	s_nop 0
	v_pk_add_f32 v[112:113], v[112:113], 1.0 op_sel_hi:[1,0]
	s_nop 0
	v_rcp_f32_e32 v67, v113
	s_nop 0
	v_mul_f32_e32 v193, v73, v67
	v_rcp_f32_e32 v67, v112
	s_nop 0
	v_mul_f32_e32 v192, v75, v67
	v_cndmask_b32_e64 v67, v37, v39, s[6:7]
	v_cndmask_b32_e64 v73, v41, v43, s[6:7]
	v_or_b32_e32 v75, 2, v73
	v_and_b32_e32 v67, v67, v197
	v_cmp_lt_u32_e32 vcc, 1, v67
	v_cmp_lt_u32_e64 s[6:7], v67, v75
	v_add_u32_e32 v77, 1, v67
	s_and_b64 s[12:13], vcc, s[6:7]
	v_cmp_ne_u32_e32 vcc, 0, v67
	v_cmp_lt_u32_e64 s[6:7], v77, v75
	v_cndmask_b32_e64 v113, 0, -1, s[12:13]
	v_cndmask_b32_e64 v112, 0, v45, s[12:13]
	s_and_b64 s[10:11], vcc, s[6:7]
	v_lshl_add_u64 v[112:113], v[116:117], 0, v[112:113]
	v_cndmask_b32_e64 v115, 0, -1, s[10:11]
	v_cndmask_b32_e64 v114, 0, v47, s[10:11]
	v_lshl_add_u64 v[118:119], v[116:117], 0, v[114:115]
	global_load_dwordx4 v[112:115], v[112:113], off offset:2048
	v_add_u32_e32 v65, -1, v73
	v_cmp_lt_u32_e64 s[8:9], v67, v73
	v_add_u32_e32 v73, 3, v67
	v_cmp_lt_u32_e64 s[6:7], v73, v75
	v_add_u32_e32 v73, 4, v67
	v_cmp_lt_u32_e32 vcc, v73, v75
	v_cndmask_b32_e64 v136, 0, v49, s[6:7]
	v_lshl_add_u64 v[122:123], v[116:117], 0, v[136:137]
	v_cndmask_b32_e32 v136, 0, v51, vcc
	v_lshl_add_u64 v[124:125], v[116:117], 0, v[136:137]
	v_cndmask_b32_e64 v69, 0, v69, s[8:9]
	v_cndmask_b32_e64 v71, 0, v71, s[8:9]
	v_cndmask_b32_e64 v63, 0, v63, s[8:9]
	v_cndmask_b32_e64 v61, 0, v61, s[8:9]
	s_waitcnt vmcnt(0)
	v_and_b32_e32 v117, 0xffff0000, v113
	v_and_b32_e32 v116, 0xffff0000, v112
	v_lshlrev_b32_e32 v73, 16, v113
	v_lshlrev_b32_e32 v75, 16, v112
	v_pk_mul_f32 v[112:113], v[154:155], v[116:117]
	global_load_dwordx4 v[116:119], v[118:119], off offset:2048
	v_cndmask_b32_e64 v113, 0, v113, s[12:13]
	v_cndmask_b32_e64 v112, 0, v112, s[12:13]
	v_pk_add_f32 v[112:113], v[152:153], v[112:113]
	v_mul_f32_e32 v73, v62, v73
	v_cndmask_b32_e64 v73, 0, v73, s[12:13]
	v_mul_f32_e32 v75, v60, v75
	v_add_f32_e32 v73, v58, v73
	v_cndmask_b32_e64 v75, 0, v75, s[12:13]
	v_add_f32_e32 v75, v56, v75
	s_waitcnt vmcnt(0)
	v_and_b32_e32 v127, 0xffff0000, v117
	v_and_b32_e32 v126, 0xffff0000, v116
	v_lshlrev_b32_e32 v77, 16, v117
	v_lshlrev_b32_e32 v79, 16, v116
	v_pk_mul_f32 v[116:117], v[156:157], v[126:127]
	global_load_dwordx4 v[124:127], v[124:125], off offset:2048
	v_cndmask_b32_e64 v117, 0, v117, s[10:11]
	v_cndmask_b32_e64 v116, 0, v116, s[10:11]
	v_pk_add_f32 v[112:113], v[112:113], v[116:117]
	v_cndmask_b32_e64 v117, 0, v121, s[8:9]
	v_cndmask_b32_e64 v116, 0, v120, s[8:9]
	global_load_dwordx4 v[120:123], v[122:123], off offset:2048
	v_mul_f32_e32 v77, v66, v77
	v_cndmask_b32_e64 v77, 0, v77, s[10:11]
	v_mul_f32_e32 v79, v64, v79
	v_add_f32_e32 v73, v73, v77
	v_cndmask_b32_e64 v79, 0, v79, s[10:11]
	v_add_f32_e32 v69, v73, v69
	v_add_f32_e32 v75, v75, v79
	v_add_f32_e32 v71, v75, v71
	v_pk_add_f32 v[112:113], v[112:113], v[116:117]
	v_lshlrev_b32_e32 v77, 16, v118
	v_mul_f32_e32 v77, v32, v77
	v_lshlrev_b32_e32 v79, 16, v119
	v_cndmask_b32_e64 v77, 0, v77, s[10:11]
	s_waitcnt vmcnt(0)
	v_lshlrev_b32_e32 v73, 16, v121
	v_mul_f32_e32 v73, v74, v73
	v_lshlrev_b32_e32 v75, 16, v120
	v_cndmask_b32_e64 v73, 0, v73, s[6:7]
	v_mul_f32_e32 v75, v72, v75
	v_add_f32_e32 v69, v69, v73
	v_lshlrev_b32_e32 v73, 16, v125
	v_cndmask_b32_e64 v75, 0, v75, s[6:7]
	v_mul_f32_e32 v73, v78, v73
	v_and_b32_e32 v117, 0xffff0000, v121
	v_and_b32_e32 v116, 0xffff0000, v120
	v_add_f32_e32 v71, v71, v75
	v_lshlrev_b32_e32 v75, 16, v124
	v_cndmask_b32_e32 v73, 0, v73, vcc
	v_pk_mul_f32 v[116:117], v[160:161], v[116:117]
	v_mul_f32_e32 v75, v76, v75
	v_add_f32_e32 v69, v69, v73
	v_lshlrev_b32_e32 v73, 16, v114
	v_cndmask_b32_e64 v117, 0, v117, s[6:7]
	v_cndmask_b32_e64 v116, 0, v116, s[6:7]
	v_cndmask_b32_e32 v75, 0, v75, vcc
	v_mul_f32_e32 v73, v36, v73
	v_pk_add_f32 v[112:113], v[112:113], v[116:117]
	v_and_b32_e32 v117, 0xffff0000, v125
	v_and_b32_e32 v116, 0xffff0000, v124
	v_add_f32_e32 v71, v71, v75
	v_lshlrev_b32_e32 v75, 16, v115
	v_cndmask_b32_e64 v73, 0, v73, s[12:13]
	v_pk_mul_f32 v[116:117], v[162:163], v[116:117]
	v_add_f32_e32 v73, v40, v73
	v_mul_f32_e32 v75, v38, v75
	v_cndmask_b32_e32 v117, 0, v117, vcc
	v_cndmask_b32_e32 v116, 0, v116, vcc
	v_cndmask_b32_e64 v75, 0, v75, s[12:13]
	v_add_f32_e32 v73, v73, v77
	v_mul_f32_e32 v77, v34, v79
	v_pk_add_f32 v[116:117], v[112:113], v[116:117]
	v_and_b32_e32 v113, 0xffff0000, v115
	v_and_b32_e32 v112, 0xffff0000, v114
	v_add_f32_e32 v75, v42, v75
	v_cndmask_b32_e64 v77, 0, v77, s[10:11]
	v_add_f32_e32 v63, v73, v63
	v_lshlrev_b32_e32 v73, 16, v122
	v_pk_mul_f32 v[112:113], v[26:27], v[112:113]
	v_and_b32_e32 v115, 0xffff0000, v119
	v_and_b32_e32 v114, 0xffff0000, v118
	v_add_f32_e32 v75, v75, v77
	v_mul_f32_e32 v73, v48, v73
	v_cndmask_b32_e64 v113, 0, v113, s[12:13]
	v_cndmask_b32_e64 v112, 0, v112, s[12:13]
	v_pk_mul_f32 v[114:115], v[30:31], v[114:115]
	v_add_f32_e32 v61, v75, v61
	v_lshlrev_b32_e32 v75, 16, v123
	v_cndmask_b32_e64 v73, 0, v73, s[6:7]
	v_pk_add_f32 v[112:113], v[22:23], v[112:113]
	v_cndmask_b32_e64 v115, 0, v115, s[10:11]
	v_cndmask_b32_e64 v114, 0, v114, s[10:11]
	v_add_f32_e32 v63, v63, v73
	v_mul_f32_e32 v73, v50, v75
	v_pk_add_f32 v[112:113], v[112:113], v[114:115]
	v_cndmask_b32_e64 v115, 0, v129, s[8:9]
	v_cndmask_b32_e64 v114, 0, v128, s[8:9]
	v_cndmask_b32_e64 v73, 0, v73, s[6:7]
	v_pk_add_f32 v[112:113], v[112:113], v[114:115]
	v_and_b32_e32 v115, 0xffff0000, v123
	v_and_b32_e32 v114, 0xffff0000, v122
	v_add_f32_e32 v61, v61, v73
	v_lshlrev_b32_e32 v73, 16, v126
	v_pk_mul_f32 v[114:115], v[148:149], v[114:115]
	v_mul_f32_e32 v73, v52, v73
	v_cndmask_b32_e64 v115, 0, v115, s[6:7]
	v_cndmask_b32_e64 v114, 0, v114, s[6:7]
	v_lshlrev_b32_e32 v75, 16, v127
	v_cndmask_b32_e32 v73, 0, v73, vcc
	v_pk_add_f32 v[112:113], v[112:113], v[114:115]
	v_and_b32_e32 v115, 0xffff0000, v127
	v_and_b32_e32 v114, 0xffff0000, v126
	v_add_f32_e32 v63, v63, v73
	v_mul_f32_e32 v73, v54, v75
	v_cndmask_b32_e32 v73, 0, v73, vcc
	v_pk_mul_f32 v[114:115], v[150:151], v[114:115]
	v_add_f32_e32 v73, v61, v73
	v_cndmask_b32_e32 v115, 0, v115, vcc
	v_cndmask_b32_e32 v114, 0, v114, vcc
	v_mul_f32_e32 v61, 0xbfb8aa3b, v71
	v_pk_add_f32 v[112:113], v[112:113], v[114:115]
	v_exp_f32_e32 v114, v61
	v_mul_f32_e32 v61, 0xbfb8aa3b, v116
	v_exp_f32_e32 v118, v61
	v_mul_f32_e32 v61, 0xbfb8aa3b, v69
	v_exp_f32_e32 v115, v61
	v_mul_f32_e32 v61, 0xbfb8aa3b, v117
	v_exp_f32_e32 v119, v61
	v_pk_add_f32 v[114:115], v[114:115], 1.0 op_sel_hi:[1,0]
	s_nop 0
	v_rcp_f32_e32 v75, v115
	v_pk_add_f32 v[118:119], v[118:119], 1.0 op_sel_hi:[1,0]
	v_mul_f32_e32 v115, v69, v75
	v_rcp_f32_e32 v69, v114
	s_nop 0
	v_mul_f32_e32 v114, v71, v69
	v_rcp_f32_e32 v71, v119
	v_pk_fma_f32 v[114:115], v[138:139], v[114:115], v[130:131]
	v_mul_f32_e32 v61, v117, v71
	v_pk_mul_f32 v[182:183], v[114:115], v[132:133]
	v_mov_b32_e32 v115, v61
	v_rcp_f32_e32 v71, v118
	v_cndmask_b32_e64 v69, 0, v182, s[4:5]
	v_mul_f32_e32 v114, v116, v71
	v_pk_fma_f32 v[114:115], v[138:139], v[114:115], v[134:135]
	v_mul_f32_e32 v77, 0xbfb8aa3b, v63
	v_pk_mul_f32 v[184:185], v[114:115], v[184:185]
	v_exp_f32_e32 v114, v77
	v_mul_f32_e32 v77, 0xbfb8aa3b, v112
	v_exp_f32_e32 v116, v77
	v_mul_f32_e32 v77, 0xbfb8aa3b, v73
	v_exp_f32_e32 v115, v77
	v_mul_f32_e32 v77, 0xbfb8aa3b, v113
	v_exp_f32_e32 v117, v77
	v_cndmask_b32_e64 v61, 0, v184, s[4:5]
	v_pk_add_f32 v[114:115], v[114:115], 1.0 op_sel_hi:[1,0]
	v_mul_f32_e32 v61, v61, v61
	v_rcp_f32_e32 v79, v115
	v_pk_add_f32 v[116:117], v[116:117], 1.0 op_sel_hi:[1,0]
	v_fmac_f32_e32 v61, v69, v69
	v_cndmask_b32_e64 v71, 0, v183, s[4:5]
	v_mul_f32_e32 v115, v73, v79
	v_rcp_f32_e32 v77, v114
	v_cndmask_b32_e64 v75, 0, v185, s[4:5]
	v_fmac_f32_e32 v61, v71, v71
	v_fmac_f32_e32 v61, v75, v75
	v_mul_f32_e32 v114, v63, v77
	v_rcp_f32_e32 v77, v117
	v_pk_fma_f32 v[114:115], v[138:139], v[114:115], v[186:187]
	v_pk_mul_f32 v[186:187], v[114:115], v[190:191]
	v_mul_f32_e32 v113, v113, v77
	v_rcp_f32_e32 v77, v116
	v_cmp_eq_u32_e64 s[6:7], 0, v67
	v_cndmask_b32_e64 v73, 0, v186, s[4:5]
	v_fmac_f32_e32 v61, v73, v73
	v_mul_f32_e32 v112, v112, v77
	v_pk_fma_f32 v[112:113], v[138:139], v[112:113], v[188:189]
	global_load_dwordx4 v[116:119], v[176:177], off offset:512
	v_pk_mul_f32 v[188:189], v[112:113], v[192:193]
	global_load_dwordx4 v[112:115], v[176:177], off
	v_cmp_lt_u32_e32 vcc, v67, v65
	v_cndmask_b32_e64 v190, 0.5, 0, s[6:7]
	v_cndmask_b32_e64 v77, 0, v188, s[4:5]
	v_cndmask_b32_e32 v136, 0, v49, vcc
	v_cndmask_b32_e64 v191, 0, 0.5, vcc
	v_cndmask_b32_e64 v79, 0, v187, s[4:5]
	v_fmac_f32_e32 v61, v77, v77
	v_cndmask_b32_e64 v63, 0, v189, s[4:5]
	v_fmac_f32_e32 v61, v79, v79
	v_fmac_f32_e32 v61, v63, v63
	v_mov_b32_e32 v65, 0
	s_waitcnt vmcnt(1)
	v_and_b32_e32 v123, 0xffff0000, v117
	v_and_b32_e32 v122, 0xffff0000, v116
	s_waitcnt vmcnt(0)
	v_and_b32_e32 v121, 0xffff0000, v113
	v_and_b32_e32 v120, 0xffff0000, v112
	v_lshlrev_b32_e32 v113, 16, v113
	v_lshlrev_b32_e32 v112, 16, v112
	v_lshlrev_b32_e32 v117, 16, v117
	v_lshlrev_b32_e32 v116, 16, v116
	v_pk_add_f32 v[200:201], v[112:113], v[116:117]
	v_pk_add_f32 v[198:199], v[120:121], v[122:123]
	v_add_f32_e32 v112, 0, v200
	v_add_f32_e32 v112, v198, v112
	v_add_f32_e32 v112, v201, v112
	v_add_f32_e32 v120, v199, v112
	v_and_b32_e32 v113, 0xffff0000, v115
	v_and_b32_e32 v112, 0xffff0000, v114
	v_and_b32_e32 v117, 0xffff0000, v119
	v_and_b32_e32 v116, 0xffff0000, v118
	v_pk_add_f32 v[192:193], v[112:113], v[116:117]
	v_lshlrev_b32_e32 v113, 16, v115
	v_lshlrev_b32_e32 v112, 16, v114
	v_lshlrev_b32_e32 v115, 16, v119
	v_lshlrev_b32_e32 v114, 16, v118
	v_pk_add_f32 v[194:195], v[112:113], v[114:115]
	global_load_dwordx4 v[114:117], v[180:181], off offset:3360
	v_add_f32_e32 v112, v194, v120
	v_add_f32_e32 v112, v192, v112
	v_add_f32_e32 v112, v195, v112
	v_add_f32_e32 v112, v193, v112
	v_cndmask_b32_e64 v113, -1, 0, s[6:7]
	v_lshl_add_u64 v[118:119], v[180:181], 0, v[136:137]
	v_add_f32_dpp v69, v112, v112 quad_perm:[1,0,3,2] row_mask:0xf bank_mask:0xf bound_ctrl:1
	v_cndmask_b32_e64 v112, v47, 0, s[6:7]
	global_load_dwordx4 v[124:127], v[118:119], off offset:3360
	v_add_f32_dpp v69, v69, v69 quad_perm:[2,3,0,1] row_mask:0xf bank_mask:0xf bound_ctrl:1
	v_add_f32_dpp v61, v61, v61 row_ror:8 row_mask:0xf bank_mask:0xf bound_ctrl:1
	s_waitcnt vmcnt(1)
	v_lshlrev_b32_e32 v208, 16, v114
	v_and_b32_e32 v209, 0xffff0000, v114
	v_lshlrev_b32_e32 v206, 16, v115
	v_and_b32_e32 v207, 0xffff0000, v115
	v_lshlrev_b32_e32 v202, 16, v116
	v_and_b32_e32 v203, 0xffff0000, v116
	v_lshlrev_b32_e32 v114, 16, v117
	v_and_b32_e32 v115, 0xffff0000, v117
	v_lshl_add_u64 v[116:117], v[180:181], 0, v[112:113]
	global_load_dwordx4 v[120:123], v[116:117], off offset:3360
	s_waitcnt vmcnt(1)
	v_lshlrev_b32_e32 v113, 16, v127
	v_and_b32_e32 v129, 0xffff0000, v127
	v_lshlrev_b32_e32 v237, 16, v124
	v_and_b32_e32 v239, 0xffff0000, v124
	v_add_f32_dpp v69, v69, v69 row_half_mirror row_mask:0xf bank_mask:0xf bound_ctrl:1
	v_mul_f32_e32 v196, 0x3c800000, v69
	v_add_f32_dpp v61, v61, v61 row_ror:4 row_mask:0xf bank_mask:0xf bound_ctrl:1
	v_mov_b32_e32 v69, 0
	s_waitcnt vmcnt(0)
	v_and_b32_e32 v112, 0xffff0000, v123
	v_lshlrev_b32_e32 v128, 16, v123
	v_pk_mul_f32 v[112:113], v[190:191], v[112:113]
	v_and_b32_e32 v236, 0xffff0000, v120
	v_pk_fma_f32 v[112:113], v[190:191], v[128:129], v[112:113] op_sel:[0,0,1] op_sel_hi:[1,1,0]
	v_lshlrev_b32_e32 v238, 16, v120
	v_pk_add_f32 v[112:113], v[112:113], v[114:115] neg_lo:[0,1] neg_hi:[0,1]
	v_pk_mul_f32 v[236:237], v[190:191], v[236:237]
	v_pk_fma_f32 v[204:205], v[82:83], v[112:113], v[114:115]
	global_load_dwordx4 v[112:115], v[180:181], off offset:3872
	global_load_dwordx4 v[128:131], v[116:117], off offset:3872
	global_load_dwordx4 v[132:135], v[118:119], off offset:3872
	v_pk_fma_f32 v[236:237], v[190:191], v[238:239], v[236:237] op_sel:[0,0,1] op_sel_hi:[1,1,0]
	v_lshlrev_b32_e32 v124, 16, v121
	v_pk_add_f32 v[236:237], v[236:237], v[208:209] neg_lo:[0,1] neg_hi:[0,1]
	v_and_b32_e32 v123, 0xffff0000, v126
	v_pk_fma_f32 v[208:209], v[84:85], v[236:237], v[208:209]
	v_add_f32_dpp v61, v61, v61 row_ror:2 row_mask:0xf bank_mask:0xf bound_ctrl:1
	s_waitcnt vmcnt(2)
	v_lshlrev_b32_e32 v216, 16, v112
	v_and_b32_e32 v217, 0xffff0000, v112
	v_lshlrev_b32_e32 v212, 16, v113
	v_and_b32_e32 v213, 0xffff0000, v113
	v_lshlrev_b32_e32 v210, 16, v114
	v_and_b32_e32 v211, 0xffff0000, v114
	v_lshlrev_b32_e32 v112, 16, v115
	v_and_b32_e32 v113, 0xffff0000, v115
	s_waitcnt vmcnt(1)
	v_and_b32_e32 v114, 0xffff0000, v131
	s_waitcnt vmcnt(0)
	v_lshlrev_b32_e32 v115, 16, v135
	v_and_b32_e32 v215, 0xffff0000, v135
	v_lshlrev_b32_e32 v214, 16, v131
	v_pk_mul_f32 v[114:115], v[190:191], v[114:115]
	v_and_b32_e32 v236, 0xffff0000, v128
	v_pk_fma_f32 v[114:115], v[190:191], v[214:215], v[114:115] op_sel:[0,0,1] op_sel_hi:[1,1,0]
	v_lshlrev_b32_e32 v237, 16, v132
	v_pk_add_f32 v[114:115], v[114:115], v[112:113] neg_lo:[0,1] neg_hi:[0,1]
	v_and_b32_e32 v239, 0xffff0000, v132
	v_pk_fma_f32 v[214:215], v[90:91], v[114:115], v[112:113]
	v_add_co_u32_e32 v112, vcc, s2, v116
	v_lshlrev_b32_e32 v238, 16, v128
	s_nop 0
	v_addc_co_u32_e32 v113, vcc, 0, v117, vcc
	v_add_co_u32_e32 v116, vcc, s2, v118
	global_load_dwordx4 v[112:115], v[112:113], off offset:288
	s_nop 0
	v_addc_co_u32_e32 v117, vcc, 0, v119, vcc
	global_load_dwordx4 v[116:119], v[116:117], off offset:288
	s_nop 0
	global_load_dwordx4 v[228:231], v[178:179], off offset:1024
	v_pk_mul_f32 v[236:237], v[190:191], v[236:237]
	v_lshlrev_b32_e32 v132, 16, v129
	v_pk_fma_f32 v[236:237], v[190:191], v[238:239], v[236:237] op_sel:[0,0,1] op_sel_hi:[1,1,0]
	v_add_f32_dpp v61, v61, v61 row_ror:1 row_mask:0xf bank_mask:0xf bound_ctrl:1
	v_pk_add_f32 v[236:237], v[236:237], v[216:217] neg_lo:[0,1] neg_hi:[0,1]
	s_waitcnt vmcnt(0)
	v_lshlrev_b32_e32 v224, 16, v228
	v_and_b32_e32 v225, 0xffff0000, v228
	v_lshlrev_b32_e32 v222, 16, v229
	v_and_b32_e32 v223, 0xffff0000, v229
	v_lshlrev_b32_e32 v220, 16, v230
	v_and_b32_e32 v221, 0xffff0000, v230
	v_lshlrev_b32_e32 v218, 16, v231
	v_and_b32_e32 v219, 0xffff0000, v231
	global_load_dwordx4 v[228:231], v[178:179], off offset:1536
	v_pk_fma_f32 v[216:217], v[92:93], v[236:237], v[216:217]
	v_pk_add_f32 v[224:225], v[224:225], -1.0 op_sel_hi:[1,0]
	s_waitcnt vmcnt(0)
	v_lshlrev_b32_e32 v232, 16, v228
	v_and_b32_e32 v233, 0xffff0000, v228
	v_pk_add_f32 v[232:233], v[232:233], -1.0 op_sel_hi:[1,0]
	v_pk_fma_f32 v[224:225], v[104:105], v[224:225], 1.0 op_sel_hi:[1,1,0]
	v_pk_fma_f32 v[232:233], v[104:105], v[232:233], 1.0 op_sel_hi:[1,1,0]
	v_lshlrev_b32_e32 v228, 16, v229
	v_pk_mul_f32 v[232:233], v[216:217], v[232:233]
	v_and_b32_e32 v229, 0xffff0000, v229
	v_pk_fma_f32 v[216:217], v[216:217], v[224:225], v[232:233]
	v_lshlrev_b32_e32 v234, 16, v230
	v_pk_mul_f32 v[208:209], v[208:209], v[216:217]
	v_and_b32_e32 v235, 0xffff0000, v230
	v_pk_mul_f32 v[208:209], v[108:109], v[208:209]
	v_lshlrev_b32_e32 v230, 16, v231
	v_add_f32_e32 v63, 0, v208
	v_add_f32_e32 v63, v209, v63
	v_and_b32_e32 v208, 0xffff0000, v121
	v_lshlrev_b32_e32 v209, 16, v125
	v_and_b32_e32 v125, 0xffff0000, v125
	v_pk_mul_f32 v[120:121], v[190:191], v[208:209]
	v_and_b32_e32 v231, 0xffff0000, v231
	v_pk_fma_f32 v[120:121], v[190:191], v[124:125], v[120:121] op_sel:[0,0,1] op_sel_hi:[1,1,0]
	v_and_b32_e32 v124, 0xffff0000, v129
	v_lshlrev_b32_e32 v125, 16, v133
	v_and_b32_e32 v133, 0xffff0000, v133
	v_pk_mul_f32 v[124:125], v[190:191], v[124:125]
	v_pk_add_f32 v[128:129], v[222:223], -1.0 op_sel_hi:[1,0]
	v_pk_fma_f32 v[124:125], v[190:191], v[132:133], v[124:125] op_sel:[0,0,1] op_sel_hi:[1,1,0]
	v_pk_add_f32 v[132:133], v[228:229], -1.0 op_sel_hi:[1,0]
	v_pk_add_f32 v[124:125], v[124:125], v[212:213] neg_lo:[0,1] neg_hi:[0,1]
	v_pk_fma_f32 v[132:133], v[106:107], v[132:133], 1.0 op_sel_hi:[1,1,0]
	v_pk_fma_f32 v[124:125], v[94:95], v[124:125], v[212:213]
	v_pk_add_f32 v[120:121], v[120:121], v[206:207] neg_lo:[0,1] neg_hi:[0,1]
	v_pk_fma_f32 v[128:129], v[106:107], v[128:129], 1.0 op_sel_hi:[1,1,0]
	v_pk_mul_f32 v[132:133], v[124:125], v[132:133]
	v_pk_fma_f32 v[120:121], v[86:87], v[120:121], v[206:207]
	v_pk_fma_f32 v[124:125], v[124:125], v[128:129], v[132:133]
	v_pk_add_f32 v[128:129], v[198:199], v[196:197] op_sel_hi:[1,0] neg_lo:[0,1] neg_hi:[0,1]
	v_pk_mul_f32 v[120:121], v[120:121], v[124:125]
	v_and_b32_e32 v125, 0xffff0000, v134
	v_pk_mul_f32 v[120:121], v[110:111], v[120:121]
	v_lshlrev_b32_e32 v124, 16, v130
	v_add_f32_e32 v63, v120, v63
	v_add_f32_e32 v63, v121, v63
	v_and_b32_e32 v120, 0xffff0000, v122
	v_lshlrev_b32_e32 v121, 16, v126
	v_lshlrev_b32_e32 v122, 16, v122
	v_pk_mul_f32 v[120:121], v[190:191], v[120:121]
	v_pk_add_f32 v[126:127], v[234:235], -1.0 op_sel_hi:[1,0]
	v_pk_fma_f32 v[120:121], v[190:191], v[122:123], v[120:121] op_sel:[0,0,1] op_sel_hi:[1,1,0]
	v_and_b32_e32 v122, 0xffff0000, v130
	v_lshlrev_b32_e32 v123, 16, v134
	v_pk_mul_f32 v[122:123], v[190:191], v[122:123]
	v_pk_fma_f32 v[126:127], v[96:97], v[126:127], 1.0 op_sel_hi:[1,1,0]
	v_pk_fma_f32 v[122:123], v[190:191], v[124:125], v[122:123] op_sel:[0,0,1] op_sel_hi:[1,1,0]
	v_pk_add_f32 v[124:125], v[220:221], -1.0 op_sel_hi:[1,0]
	v_pk_add_f32 v[122:123], v[122:123], v[210:211] neg_lo:[0,1] neg_hi:[0,1]
	v_pk_add_f32 v[120:121], v[120:121], v[202:203] neg_lo:[0,1] neg_hi:[0,1]
	v_pk_fma_f32 v[122:123], v[88:89], v[122:123], v[210:211]
	v_pk_fma_f32 v[124:125], v[96:97], v[124:125], 1.0 op_sel_hi:[1,1,0]
	v_pk_mul_f32 v[126:127], v[122:123], v[126:127]
	v_pk_fma_f32 v[120:121], v[80:81], v[120:121], v[202:203]
	v_pk_fma_f32 v[122:123], v[122:123], v[124:125], v[126:127]
	v_pk_add_f32 v[130:131], v[200:201], v[196:197] op_sel_hi:[1,0] neg_lo:[0,1] neg_hi:[0,1]
	v_pk_mul_f32 v[120:121], v[120:121], v[122:123]
	v_pk_add_f32 v[122:123], v[230:231], -1.0 op_sel_hi:[1,0]
	v_pk_mul_f32 v[120:121], v[100:101], v[120:121]
	v_pk_fma_f32 v[122:123], v[98:99], v[122:123], 1.0 op_sel_hi:[1,1,0]
	v_add_f32_e32 v63, v120, v63
	v_add_f32_e32 v63, v121, v63
	v_pk_add_f32 v[120:121], v[218:219], -1.0 op_sel_hi:[1,0]
	v_pk_mul_f32 v[122:123], v[214:215], v[122:123]
	v_pk_fma_f32 v[120:121], v[98:99], v[120:121], 1.0 op_sel_hi:[1,1,0]
	s_nop 0
	v_pk_fma_f32 v[120:121], v[214:215], v[120:121], v[122:123]
	s_nop 0
	v_pk_mul_f32 v[120:121], v[204:205], v[120:121]
	s_nop 0
	v_pk_mul_f32 v[120:121], v[102:103], v[120:121]
	s_nop 0
	v_add_f32_e32 v63, v120, v63
	v_add_f32_e32 v63, v121, v63
	v_mov_b32_e32 v120, v130
	v_mov_b32_e32 v121, v128
	v_pk_mul_f32 v[132:133], v[120:121], v[120:121]
	v_mov_b32_e32 v120, v129
	v_mov_b32_e32 v121, v131
	v_pk_mul_f32 v[134:135], v[120:121], v[120:121]
	v_add_co_u32_e32 v120, vcc, s2, v180
	v_add_f32_e32 v67, v132, v133
	s_nop 0
	v_addc_co_u32_e32 v121, vcc, 0, v181, vcc
	global_load_dwordx4 v[124:127], v[120:121], off offset:288
	s_nop 0
	global_load_dwordx4 v[120:123], v[178:179], off offset:2048
	v_cmp_lt_i32_e32 vcc, v53, v55
	v_pk_add_f32 v[180:181], v[194:195], v[196:197] op_sel_hi:[1,0] neg_lo:[0,1] neg_hi:[0,1]
	v_pk_add_f32 v[178:179], v[192:193], v[196:197] op_sel_hi:[1,0] neg_lo:[0,1] neg_hi:[0,1]
	v_cndmask_b32_e32 v71, v227, v53, vcc
	v_lshlrev_b32_e32 v71, 2, v71
	ds_bpermute_b32 v71, v71, v61
	v_mov_b32_e32 v192, v178
	v_mov_b32_e32 v193, v180
	v_add_f32_e32 v67, v135, v67
	v_pk_mul_f32 v[192:193], v[192:193], v[192:193]
	v_add_f32_e32 v67, v134, v67
	v_cmp_lt_i32_e32 vcc, v57, v55
	v_mov_b32_e32 v194, v179
	v_mov_b32_e32 v195, v181
	v_add_f32_e32 v67, v193, v67
	s_waitcnt lgkmcnt(0)
	v_add_f32_e32 v61, v61, v71
	v_cndmask_b32_e32 v71, v227, v57, vcc
	v_pk_mul_f32 v[194:195], v[194:195], v[194:195]
	v_add_f32_e32 v67, v192, v67
	v_lshlrev_b32_e32 v71, 2, v71
	v_add_f32_e32 v67, v195, v67
	ds_bpermute_b32 v71, v71, v61
	v_add_f32_e32 v67, v194, v67
	v_add_f32_dpp v63, v63, v63 quad_perm:[1,0,3,2] row_mask:0xf bank_mask:0xf bound_ctrl:1
	s_nop 0
	v_add_f32_dpp v67, v67, v67 quad_perm:[1,0,3,2] row_mask:0xf bank_mask:0xf bound_ctrl:1
	v_add_f32_dpp v63, v63, v63 quad_perm:[2,3,0,1] row_mask:0xf bank_mask:0xf bound_ctrl:1
	s_nop 0
	v_add_f32_dpp v67, v67, v67 quad_perm:[2,3,0,1] row_mask:0xf bank_mask:0xf bound_ctrl:1
	v_mov_b32_dpp v65, v63 row_half_mirror row_mask:0xf bank_mask:0xf
	s_nop 0
	v_mov_b32_dpp v69, v67 row_half_mirror row_mask:0xf bank_mask:0xf
	s_and_saveexec_b64 s[6:7], s[4:5]
	s_cbranch_execz .LBB0_1349
	s_waitcnt lgkmcnt(0)
	v_add_f32_e32 v61, v61, v71
	v_fmamk_f32 v61, v61, 0x3b2aaaab, v33
	v_mul_f32_e32 v71, 0x4b800000, v61
	v_cmp_gt_f32_e32 vcc, s22, v61
	s_nop 1
	v_cndmask_b32_e32 v61, v61, v71, vcc
	v_rsq_f32_e32 v61, v61
	s_nop 0
	v_mul_f32_e32 v71, 0x45800000, v61
	v_cndmask_b32_e32 v134, v61, v71, vcc
	v_pk_mul_f32 v[132:133], v[182:183], v[134:135] op_sel_hi:[1,0]
	v_pk_mul_f32 v[182:183], v[184:185], v[134:135] op_sel_hi:[1,0]
	v_pk_mul_f32 v[132:133], v[28:29], v[132:133]
	v_pk_mul_f32 v[182:183], v[14:15], v[182:183]
	v_and_b32_sdwa v61, v133, v59 dst_sel:DWORD dst_unused:UNUSED_PAD src0_sel:WORD_1 src1_sel:DWORD
	v_and_b32_sdwa v71, v132, v59 dst_sel:DWORD dst_unused:UNUSED_PAD src0_sel:WORD_1 src1_sel:DWORD
	v_cvt_pk_bf16_f32 v73, v183, v183
	v_cvt_pk_bf16_f32 v75, v182, v182
	v_pk_mul_f32 v[182:183], v[186:187], v[134:135] op_sel_hi:[1,0]
	v_pk_mul_f32 v[134:135], v[188:189], v[134:135] op_sel_hi:[1,0]
	v_add3_u32 v71, v132, v71, s23
	v_add3_u32 v61, v133, v61, s23
	v_and_b32_e32 v73, 0xffff0000, v73
	v_and_b32_e32 v75, 0xffff0000, v75
	v_pk_mul_f32 v[134:135], v[18:19], v[134:135]
	v_or_b32_sdwa v133, v73, v61 dst_sel:DWORD dst_unused:UNUSED_PAD src0_sel:DWORD src1_sel:WORD_1
	v_or_b32_sdwa v132, v75, v71 dst_sel:DWORD dst_unused:UNUSED_PAD src0_sel:DWORD src1_sel:WORD_1
	v_pk_mul_f32 v[182:183], v[24:25], v[182:183]
	v_and_b32_sdwa v61, v183, v59 dst_sel:DWORD dst_unused:UNUSED_PAD src0_sel:WORD_1 src1_sel:DWORD
	v_and_b32_sdwa v71, v182, v59 dst_sel:DWORD dst_unused:UNUSED_PAD src0_sel:WORD_1 src1_sel:DWORD
	v_cvt_pk_bf16_f32 v73, v135, v135
	v_cvt_pk_bf16_f32 v75, v134, v134
	v_add3_u32 v71, v182, v71, s23
	v_add3_u32 v61, v183, v61, s23
	v_and_b32_e32 v73, 0xffff0000, v73
	v_and_b32_e32 v75, 0xffff0000, v75
	v_or_b32_sdwa v135, v73, v61 dst_sel:DWORD dst_unused:UNUSED_PAD src0_sel:DWORD src1_sel:WORD_1
	v_or_b32_sdwa v134, v75, v71 dst_sel:DWORD dst_unused:UNUSED_PAD src0_sel:DWORD src1_sel:WORD_1
	global_store_dwordx4 v[174:175], v[132:135], off
.LBB0_1349:
	s_or_b64 exec, exec, s[6:7]
	s_and_saveexec_b64 s[6:7], s[0:1]
	s_cbranch_execz .LBB0_1346
	v_lshlrev_b32_e32 v133, 16, v116
	v_and_b32_e32 v135, 0xffff0000, v116
	v_lshlrev_b32_e32 v175, 16, v117
	v_and_b32_e32 v117, 0xffff0000, v117
	v_and_b32_e32 v116, 0xffff0000, v113
	v_add_f32_e32 v61, v67, v69
	v_lshlrev_b32_e32 v132, 16, v112
	v_and_b32_e32 v134, 0xffff0000, v112
	v_lshlrev_b32_e32 v174, 16, v113
	v_pk_mul_f32 v[112:113], v[190:191], v[116:117]
	v_lshlrev_b32_e32 v117, 16, v118
	v_and_b32_e32 v183, 0xffff0000, v118
	v_lshlrev_b32_e32 v185, 16, v119
	v_and_b32_e32 v119, 0xffff0000, v119
	v_and_b32_e32 v118, 0xffff0000, v115
	v_fmamk_f32 v61, v61, 0x3c800000, v35
	v_pk_mul_f32 v[132:133], v[190:191], v[132:133]
	v_pk_mul_f32 v[174:175], v[190:191], v[174:175]
	v_lshlrev_b32_e32 v116, 16, v114
	v_and_b32_e32 v182, 0xffff0000, v114
	v_lshlrev_b32_e32 v184, 16, v115
	v_pk_mul_f32 v[114:115], v[190:191], v[118:119]
	v_add_f32_e32 v118, v63, v65
	v_mul_f32_e32 v63, 0x4b800000, v61
	v_cmp_gt_f32_e32 vcc, s22, v61
	v_pk_mul_f32 v[134:135], v[190:191], v[134:135]
	v_mov_b32_e32 v188, v132
	v_mov_b32_e32 v189, v174
	v_mov_b32_e32 v174, v133
	v_cndmask_b32_e32 v61, v61, v63, vcc
	v_pk_mul_f32 v[116:117], v[190:191], v[116:117]
	v_pk_mul_f32 v[184:185], v[190:191], v[184:185]
	v_pk_add_f32 v[132:133], v[188:189], v[174:175]
	v_mov_b32_e32 v174, v134
	v_mov_b32_e32 v175, v112
	v_mov_b32_e32 v112, v135
	v_rsq_f32_e32 v61, v61
	v_pk_add_f32 v[112:113], v[174:175], v[112:113]
	v_mov_b32_e32 v174, v116
	v_mov_b32_e32 v175, v184
	v_mov_b32_e32 v184, v117
	s_waitcnt vmcnt(1)
	v_lshlrev_b32_e32 v135, 16, v127
	v_lshlrev_b32_e32 v134, 16, v126
	v_pk_add_f32 v[116:117], v[174:175], v[184:185]
	v_pk_mul_f32 v[182:183], v[190:191], v[182:183]
	v_pk_add_f32 v[116:117], v[116:117], v[134:135] neg_lo:[0,1] neg_hi:[0,1]
	v_mul_f32_e32 v63, 0x45800000, v61
	v_pk_fma_f32 v[116:117], v[12:13], v[116:117], v[134:135]
	v_mov_b32_e32 v134, v182
	v_mov_b32_e32 v135, v114
	v_mov_b32_e32 v114, v183
	v_lshlrev_b32_e32 v187, 16, v125
	v_lshlrev_b32_e32 v186, 16, v124
	v_and_b32_e32 v125, 0xffff0000, v125
	v_and_b32_e32 v124, 0xffff0000, v124
	v_pk_add_f32 v[114:115], v[134:135], v[114:115]
	v_cndmask_b32_e32 v134, v61, v63, vcc
	v_pk_add_f32 v[112:113], v[112:113], v[124:125] neg_lo:[0,1] neg_hi:[0,1]
	v_pk_mul_f32 v[128:129], v[128:129], v[134:135] op_sel_hi:[1,0]
	v_pk_fma_f32 v[112:113], v[144:145], v[112:113], v[124:125]
	v_pk_fma_f32 v[128:129], v[142:143], v[128:129], v[140:141]
	s_waitcnt vmcnt(0)
	v_lshlrev_b32_e32 v125, 16, v121
	v_lshlrev_b32_e32 v124, 16, v120
	v_and_b32_e32 v121, 0xffff0000, v121
	v_and_b32_e32 v120, 0xffff0000, v120
	v_pk_fma_f32 v[112:113], v[112:113], v[118:119], v[128:129] op_sel_hi:[1,0,1]
	v_pk_add_f32 v[132:133], v[132:133], v[186:187] neg_lo:[0,1] neg_hi:[0,1]
	v_pk_mul_f32 v[130:131], v[130:131], v[134:135] op_sel_hi:[1,0]
	v_pk_mul_f32 v[112:113], v[112:113], v[120:121]
	v_pk_mul_f32 v[120:121], v[180:181], v[134:135] op_sel_hi:[1,0]
	v_pk_fma_f32 v[132:133], v[8:9], v[132:133], v[186:187]
	v_and_b32_e32 v127, 0xffff0000, v127
	v_and_b32_e32 v126, 0xffff0000, v126
	v_pk_fma_f32 v[130:131], v[4:5], v[130:131], v[0:1]
	v_pk_fma_f32 v[120:121], v[20:21], v[120:121], v[16:17]
	v_pk_add_f32 v[114:115], v[114:115], v[126:127] neg_lo:[0,1] neg_hi:[0,1]
	v_pk_fma_f32 v[130:131], v[132:133], v[118:119], v[130:131] op_sel_hi:[1,0,1]
	v_pk_fma_f32 v[116:117], v[116:117], v[118:119], v[120:121] op_sel_hi:[1,0,1]
	v_pk_mul_f32 v[120:121], v[178:179], v[134:135] op_sel_hi:[1,0]
	v_pk_fma_f32 v[114:115], v[10:11], v[114:115], v[126:127]
	v_pk_mul_f32 v[124:125], v[130:131], v[124:125]
	v_pk_fma_f32 v[120:121], v[6:7], v[120:121], v[2:3]
	v_lshlrev_b32_e32 v127, 16, v123
	v_lshlrev_b32_e32 v126, 16, v122
	v_and_b32_e32 v123, 0xffff0000, v123
	v_and_b32_e32 v122, 0xffff0000, v122
	v_pk_fma_f32 v[114:115], v[114:115], v[118:119], v[120:121] op_sel_hi:[1,0,1]
	v_and_b32_sdwa v61, v125, v59 dst_sel:DWORD dst_unused:UNUSED_PAD src0_sel:WORD_1 src1_sel:DWORD
	v_and_b32_sdwa v63, v124, v59 dst_sel:DWORD dst_unused:UNUSED_PAD src0_sel:WORD_1 src1_sel:DWORD
	v_cvt_pk_bf16_f32 v65, v113, v113
	v_cvt_pk_bf16_f32 v67, v112, v112
	v_pk_mul_f32 v[114:115], v[114:115], v[122:123]
	v_add3_u32 v63, v124, v63, s23
	v_add3_u32 v61, v125, v61, s23
	v_and_b32_e32 v65, 0xffff0000, v65
	v_and_b32_e32 v67, 0xffff0000, v67
	v_pk_mul_f32 v[116:117], v[116:117], v[126:127]
	v_or_b32_sdwa v113, v65, v61 dst_sel:DWORD dst_unused:UNUSED_PAD src0_sel:DWORD src1_sel:WORD_1
	v_or_b32_sdwa v112, v67, v63 dst_sel:DWORD dst_unused:UNUSED_PAD src0_sel:DWORD src1_sel:WORD_1
	v_and_b32_sdwa v61, v117, v59 dst_sel:DWORD dst_unused:UNUSED_PAD src0_sel:WORD_1 src1_sel:DWORD
	v_and_b32_sdwa v63, v116, v59 dst_sel:DWORD dst_unused:UNUSED_PAD src0_sel:WORD_1 src1_sel:DWORD
	v_cvt_pk_bf16_f32 v65, v115, v115
	v_cvt_pk_bf16_f32 v67, v114, v114
	v_add3_u32 v63, v116, v63, s23
	v_add3_u32 v61, v117, v61, s23
	v_and_b32_e32 v65, 0xffff0000, v65
	v_and_b32_e32 v67, 0xffff0000, v67
	v_or_b32_sdwa v115, v65, v61 dst_sel:DWORD dst_unused:UNUSED_PAD src0_sel:DWORD src1_sel:WORD_1
	v_or_b32_sdwa v114, v67, v63 dst_sel:DWORD dst_unused:UNUSED_PAD src0_sel:DWORD src1_sel:WORD_1
	global_store_dwordx4 v[176:177], v[112:115], off offset:768
	s_branch .LBB0_1346

.LBB0_1462:
	s_or_b64 exec, exec, s[14:15]
	s_and_b64 s[0:1], exec, vcc
	v_add_u32_e32 v65, 0xfffff000, v64
	s_or_b64 s[12:13], s[0:1], s[12:13]
	v_lshrrev_b32_e32 v65, 12, v65
	s_movk_i32 s0, 0xfff
	v_add_u32_e32 v65, 1, v65
	v_cmp_lt_i32_e32 vcc, s0, v64
	s_movk_i32 s0, 0x6000
	v_mov_b32_e32 v104, v56
	v_cndmask_b32_e32 v64, 0, v65, vcc
	v_mad_u64_u32 v[64:65], s[0:1], v64, s0, v[76:77]
	s_mov_b64 s[0:1], 0x3000
	s_nop 0
	v_lshl_add_u64 v[86:87], v[64:65], 0, s[0:1]
	s_mov_b64 s[0:1], 0x4000
	v_lshl_add_u64 v[88:89], v[64:65], 0, s[0:1]
	v_lshl_add_u64 v[102:103], v[86:87], 0, v[78:79]
	v_lshl_add_u64 v[96:97], v[86:87], 0, v[80:81]
	v_lshl_add_u64 v[92:93], v[86:87], 0, v[82:83]
	v_lshl_add_u64 v[64:65], v[86:87], 0, v[84:85]
	v_mov_b32_e32 v86, v57
	v_mov_b32_e32 v87, v61
	v_mov_b32_e32 v105, v60
	v_pk_add_f32 v[86:87], v[86:87], v[104:105]
	v_mov_b32_e32 v104, v58
	v_mov_b32_e32 v105, v62
	v_pk_add_f32 v[86:87], v[104:105], v[86:87]
	v_mov_b32_e32 v104, v59
	v_mov_b32_e32 v105, v63
	v_pk_add_f32 v[86:87], v[104:105], v[86:87]
	v_mov_b32_e32 v104, v48
	v_add_f32_e32 v87, 0, v87
	v_add_f32_e32 v106, v86, v87
	v_mov_b32_e32 v86, v49
	v_mov_b32_e32 v87, v53
	v_mov_b32_e32 v105, v52
	v_pk_add_f32 v[86:87], v[86:87], v[104:105]
	v_mov_b32_e32 v104, v50
	v_mov_b32_e32 v105, v54
	v_pk_add_f32 v[86:87], v[104:105], v[86:87]
	v_mov_b32_e32 v104, v51
	v_mov_b32_e32 v105, v55
	v_pk_add_f32 v[86:87], v[104:105], v[86:87]
	s_mov_b32 s0, 0x800000
	v_add_f32_e32 v87, v87, v106
	v_add_f32_e32 v86, v86, v87
	v_lshl_add_u64 v[90:91], v[88:89], 0, v[78:79]
	v_lshl_add_u64 v[94:95], v[88:89], 0, v[80:81]
	v_add_f32_dpp v86, v86, v86 row_ror:8 row_mask:0xf bank_mask:0xf bound_ctrl:1
	v_lshl_add_u64 v[66:67], v[88:89], 0, v[82:83]
	v_lshl_add_u64 v[88:89], v[88:89], 0, v[84:85]
	v_add_f32_dpp v86, v86, v86 row_ror:4 row_mask:0xf bank_mask:0xf bound_ctrl:1
	v_lshl_add_u64 v[74:75], v[74:75], 0, s[10:11]
	s_nop 0
	v_add_f32_dpp v86, v86, v86 row_ror:2 row_mask:0xf bank_mask:0xf bound_ctrl:1
	s_nop 1
	v_add_f32_dpp v86, v86, v86 row_ror:1 row_mask:0xf bank_mask:0xf bound_ctrl:1
	ds_bpermute_b32 v87, v98, v86
	s_waitcnt lgkmcnt(0)
	v_add_f32_e32 v86, v86, v87
	ds_bpermute_b32 v87, v99, v86
	s_waitcnt lgkmcnt(0)
	v_add_f32_e32 v86, v86, v87
	v_mul_f32_e32 v104, 0x3a800000, v86
	v_pk_add_f32 v[60:61], v[60:61], v[104:105] op_sel_hi:[1,0] neg_lo:[0,1] neg_hi:[0,1]
	v_pk_add_f32 v[56:57], v[56:57], v[104:105] op_sel_hi:[1,0] neg_lo:[0,1] neg_hi:[0,1]
	v_mov_b32_e32 v108, v61
	v_mov_b32_e32 v109, v57
	v_pk_add_f32 v[62:63], v[62:63], v[104:105] op_sel_hi:[1,0] neg_lo:[0,1] neg_hi:[0,1]
	v_pk_add_f32 v[58:59], v[58:59], v[104:105] op_sel_hi:[1,0] neg_lo:[0,1] neg_hi:[0,1]
	v_mov_b32_e32 v106, v60
	v_mov_b32_e32 v107, v56
	v_pk_mul_f32 v[108:109], v[108:109], v[108:109]
	v_pk_add_f32 v[52:53], v[52:53], v[104:105] op_sel_hi:[1,0] neg_lo:[0,1] neg_hi:[0,1]
	v_pk_fma_f32 v[106:107], v[106:107], v[106:107], v[108:109]
	v_mov_b32_e32 v108, v62
	v_mov_b32_e32 v109, v58
	v_pk_add_f32 v[48:49], v[48:49], v[104:105] op_sel_hi:[1,0] neg_lo:[0,1] neg_hi:[0,1]
	v_pk_fma_f32 v[106:107], v[108:109], v[108:109], v[106:107]
	v_mov_b32_e32 v108, v49
	v_mov_b32_e32 v109, v53
	v_pk_add_f32 v[54:55], v[54:55], v[104:105] op_sel_hi:[1,0] neg_lo:[0,1] neg_hi:[0,1]
	v_pk_add_f32 v[50:51], v[50:51], v[104:105] op_sel_hi:[1,0] neg_lo:[0,1] neg_hi:[0,1]
	v_mov_b32_e32 v104, v48
	v_mov_b32_e32 v105, v52
	v_pk_mul_f32 v[108:109], v[108:109], v[108:109]
	v_mov_b32_e32 v110, v63
	v_mov_b32_e32 v111, v59
	v_pk_fma_f32 v[104:105], v[104:105], v[104:105], v[108:109]
	v_mov_b32_e32 v108, v50
	v_mov_b32_e32 v109, v54
	v_pk_fma_f32 v[106:107], v[110:111], v[110:111], v[106:107]
	v_mov_b32_e32 v110, v51
	v_mov_b32_e32 v111, v55
	v_pk_fma_f32 v[104:105], v[108:109], v[108:109], v[104:105]
	v_add_f32_e32 v106, v106, v107
	v_pk_fma_f32 v[104:105], v[110:111], v[110:111], v[104:105]
	v_lshl_add_u64 v[86:87], v[70:71], 0, v[68:69]
	v_add_f32_e32 v105, v105, v106
	v_add_f32_e32 v104, v104, v105
	v_lshl_add_u64 v[70:71], v[70:71], 0, s[10:11]
	s_nop 0
	v_add_f32_dpp v104, v104, v104 row_ror:8 row_mask:0xf bank_mask:0xf bound_ctrl:1
	s_nop 1
	v_add_f32_dpp v104, v104, v104 row_ror:4 row_mask:0xf bank_mask:0xf bound_ctrl:1
	s_nop 1
	v_add_f32_dpp v104, v104, v104 row_ror:2 row_mask:0xf bank_mask:0xf bound_ctrl:1
	s_nop 1
	v_add_f32_dpp v104, v104, v104 row_ror:1 row_mask:0xf bank_mask:0xf bound_ctrl:1
	ds_bpermute_b32 v105, v98, v104
	s_waitcnt lgkmcnt(0)
	v_add_f32_e32 v104, v104, v105
	ds_bpermute_b32 v105, v99, v104
	s_waitcnt lgkmcnt(0)
	v_add_f32_e32 v104, v104, v105
	v_fmamk_f32 v104, v104, 0x3a800000, v100
	v_cmp_gt_f32_e32 vcc, s0, v104
	v_mul_f32_e32 v105, 0x4b800000, v104
	s_nop 0
	v_cndmask_b32_e32 v104, v104, v105, vcc
	v_rsq_f32_e32 v104, v104
	s_nop 0
	v_mul_f32_e32 v105, 0x45800000, v104
	v_cndmask_b32_e32 v104, v104, v105, vcc
	v_pk_mul_f32 v[60:61], v[60:61], v[104:105] op_sel_hi:[1,0]
	v_pk_mul_f32 v[62:63], v[62:63], v[104:105] op_sel_hi:[1,0]
	v_pk_mul_f32 v[56:57], v[56:57], v[104:105] op_sel_hi:[1,0]
	v_pk_mul_f32 v[58:59], v[58:59], v[104:105] op_sel_hi:[1,0]
	v_pk_mul_f32 v[52:53], v[52:53], v[104:105] op_sel_hi:[1,0]
	v_pk_mul_f32 v[54:55], v[54:55], v[104:105] op_sel_hi:[1,0]
	v_pk_mul_f32 v[48:49], v[48:49], v[104:105] op_sel_hi:[1,0]
	v_pk_mul_f32 v[50:51], v[50:51], v[104:105] op_sel_hi:[1,0]
	global_load_dwordx4 v[102:105], v[102:103], off
	s_nop 0
	global_load_dwordx4 v[106:109], v[90:91], off
	v_pk_fma_f32 v[60:61], v[0:1], v[60:61], v[4:5]
	v_pk_fma_f32 v[62:63], v[2:3], v[62:63], v[6:7]
	v_pk_fma_f32 v[56:57], v[8:9], v[56:57], v[12:13]
	v_pk_fma_f32 v[58:59], v[10:11], v[58:59], v[14:15]
	v_pk_fma_f32 v[52:53], v[16:17], v[52:53], v[20:21]
	v_pk_fma_f32 v[54:55], v[18:19], v[54:55], v[22:23]
	v_pk_fma_f32 v[48:49], v[24:25], v[48:49], v[28:29]
	v_pk_fma_f32 v[50:51], v[26:27], v[50:51], v[30:31]
	s_waitcnt vmcnt(0)
	v_pk_add_f32 v[90:91], v[108:109], 1.0 op_sel_hi:[1,0]
	v_pk_add_f32 v[106:107], v[106:107], 1.0 op_sel_hi:[1,0]
	v_pk_fma_f32 v[90:91], v[90:91], v[62:63], v[104:105]
	v_pk_fma_f32 v[102:103], v[106:107], v[60:61], v[102:103]
	v_cvt_pk_bf16_f32 v91, v90, v91
	v_cvt_pk_bf16_f32 v90, v102, v103
	global_load_dwordx4 v[102:105], v[96:97], off
	s_nop 0
	global_load_dwordx4 v[94:97], v[94:95], off
	s_waitcnt vmcnt(0)
	v_pk_add_f32 v[94:95], v[94:95], 1.0 op_sel_hi:[1,0]
	v_pk_add_f32 v[96:97], v[96:97], 1.0 op_sel_hi:[1,0]
	v_pk_fma_f32 v[94:95], v[94:95], v[56:57], v[102:103]
	v_pk_fma_f32 v[96:97], v[96:97], v[58:59], v[104:105]
	v_cvt_pk_bf16_f32 v94, v94, v94
	v_cvt_pk_bf16_f32 v104, v95, v95
	v_cvt_pk_bf16_f32 v95, v96, v96
	v_cvt_pk_bf16_f32 v96, v97, v97
	v_perm_b32 v94, v104, v94, s7
	global_load_dwordx4 v[102:105], v[92:93], off
	global_load_dwordx4 v[106:109], v[66:67], off
	v_perm_b32 v95, v96, v95, s7
	s_waitcnt vmcnt(0)
	v_pk_add_f32 v[66:67], v[108:109], 1.0 op_sel_hi:[1,0]
	v_pk_add_f32 v[92:93], v[106:107], 1.0 op_sel_hi:[1,0]
	v_pk_fma_f32 v[66:67], v[66:67], v[54:55], v[104:105]
	v_pk_fma_f32 v[92:93], v[92:93], v[52:53], v[102:103]
	v_cvt_pk_bf16_f32 v92, v92, v92
	v_cvt_pk_bf16_f32 v102, v93, v93
	v_cvt_pk_bf16_f32 v93, v66, v67
	v_perm_b32 v92, v102, v92, s7
	global_load_dwordx4 v[64:67], v[64:65], off
	s_nop 0
	global_load_dwordx4 v[102:105], v[88:89], off
	s_nop 0
	global_store_dwordx4 v[86:87], v[60:63], off
	global_store_dwordx4 v[86:87], v[56:59], off offset:1024
	global_store_dwordx4 v[86:87], v[52:55], off offset:2048
	global_store_dwordx4 v[86:87], v[48:51], off offset:3072
	global_store_dwordx2 v[72:73], v[90:91], off
	global_store_dwordx2 v[72:73], v[94:95], off offset:512
	global_store_dwordx2 v[72:73], v[92:93], off offset:1024
	v_mov_b64_e32 v[60:61], v[32:33]
	v_mov_b64_e32 v[62:63], v[34:35]
	v_mov_b64_e32 v[56:57], v[36:37]
	v_mov_b64_e32 v[58:59], v[38:39]
	s_waitcnt vmcnt(7)
	v_pk_add_f32 v[52:53], v[104:105], 1.0 op_sel_hi:[1,0]
	v_pk_add_f32 v[54:55], v[102:103], 1.0 op_sel_hi:[1,0]
	v_pk_fma_f32 v[50:51], v[52:53], v[50:51], v[66:67]
	v_pk_fma_f32 v[48:49], v[54:55], v[48:49], v[64:65]
	v_cvt_pk_bf16_f32 v48, v48, v48
	v_cvt_pk_bf16_f32 v54, v49, v49
	v_cvt_pk_bf16_f32 v49, v50, v50
	v_cvt_pk_bf16_f32 v50, v51, v51
	v_perm_b32 v49, v50, v49, s7
	v_perm_b32 v48, v54, v48, s7
	global_store_dwordx2 v[72:73], v[48:49], off offset:1536
	v_lshl_add_u64 v[72:73], v[72:73], 0, s[8:9]
	v_mov_b32_e32 v64, v101
	v_mov_b64_e32 v[52:53], v[40:41]
	v_mov_b64_e32 v[54:55], v[42:43]
	v_mov_b64_e32 v[48:49], v[44:45]
	v_mov_b64_e32 v[50:51], v[46:47]
	s_andn2_b64 exec, exec, s[12:13]
	s_cbranch_execz .LBB0_1465

.LBB0_1520:
	s_mul_i32 s39, s37, 0x6000
	s_waitcnt vmcnt(6)
	s_add_i32 s39, s17, s39
	s_mul_i32 s98, s38, 0x6000
	v_lshl_add_u64 v[196:197], v[136:137], 0, s[14:15]
	v_lshl_add_u64 v[198:199], v[134:135], 0, s[14:15]
	s_add_i32 s99, s39, s18
	s_waitcnt lgkmcnt(0)
	s_barrier
	v_add_u32_e32 v178, s98, v139
	v_add_u32_e32 v179, s98, v141
	ds_read_b128 v[162:165], v179
	ds_read_b128 v[146:149], v178
	ds_read_b128 v[166:169], v179 offset:1024
	ds_read_b128 v[170:173], v179 offset:2048
	ds_read_b128 v[174:177], v179 offset:3072
	ds_read_b128 v[150:153], v178 offset:1024
	ds_read_b128 v[154:157], v178 offset:2048
	ds_read_b128 v[158:161], v178 offset:3072
	ds_read_b128 v[180:183], v178 offset:4096
	ds_read_b128 v[184:187], v178 offset:5120
	ds_read_b128 v[188:191], v178 offset:6144
	ds_read_b128 v[192:195], v178 offset:7168
	v_lshl_add_u64 v[200:201], v[196:197], 0, s[10:11]
	s_mov_b32 m0, s39
	s_waitcnt lgkmcnt(10)
	v_mfma_f32_16x16x32_bf16 v[84:87], v[146:149], v[162:165], v[84:87]
	global_load_lds_dwordx4 v[200:201], off
	s_waitcnt lgkmcnt(9)
	v_mfma_f32_16x16x32_bf16 v[76:79], v[146:149], v[166:169], v[76:79]
	v_lshl_add_u64 v[200:201], v[196:197], 0, s[12:13]
	s_add_i32 m0, s39, 0x400
	s_waitcnt lgkmcnt(8)
	v_mfma_f32_16x16x32_bf16 v[68:71], v[146:149], v[170:173], v[68:71]
	global_load_lds_dwordx4 v[200:201], off
	s_waitcnt lgkmcnt(7)
	v_mfma_f32_16x16x32_bf16 v[60:63], v[146:149], v[174:177], v[60:63]
	s_mov_b64 s[100:101], 0x10080
	v_lshl_add_u64 v[200:201], v[196:197], 0, s[100:101]
	s_add_i32 m0, s39, 0x800
	s_waitcnt lgkmcnt(6)
	v_mfma_f32_16x16x32_bf16 v[52:55], v[150:153], v[162:165], v[52:55]
	global_load_lds_dwordx4 v[200:201], off
	v_mfma_f32_16x16x32_bf16 v[44:47], v[150:153], v[166:169], v[44:47]
	v_mfma_f32_16x16x32_bf16 v[36:39], v[150:153], v[170:173], v[36:39]
	s_mov_b64 s[100:101], 0x18080
	v_lshl_add_u64 v[200:201], v[196:197], 0, s[100:101]
	s_add_i32 m0, s39, 0xc00
	v_mfma_f32_16x16x32_bf16 v[32:35], v[150:153], v[174:177], v[32:35]
	global_load_lds_dwordx4 v[200:201], off
	s_waitcnt lgkmcnt(5)
	v_mfma_f32_16x16x32_bf16 v[28:31], v[154:157], v[162:165], v[28:31]
	v_lshl_add_u64 v[200:201], v[198:199], 0, s[10:11]
	s_add_i32 m0, s99, 0x4000
	v_mfma_f32_16x16x32_bf16 v[24:27], v[154:157], v[166:169], v[24:27]
	global_load_lds_dwordx4 v[200:201], off
	v_mfma_f32_16x16x32_bf16 v[20:23], v[154:157], v[170:173], v[20:23]
	v_lshl_add_u64 v[200:201], v[198:199], 0, s[12:13]
	s_add_i32 m0, s99, 0x4400
	v_mfma_f32_16x16x32_bf16 v[16:19], v[154:157], v[174:177], v[16:19]
	global_load_lds_dwordx4 v[200:201], off
	s_waitcnt lgkmcnt(4)
	v_mfma_f32_16x16x32_bf16 v[12:15], v[158:161], v[162:165], v[12:15]
	v_mfma_f32_16x16x32_bf16 v[8:11], v[158:161], v[166:169], v[8:11]
	v_mfma_f32_16x16x32_bf16 v[4:7], v[158:161], v[170:173], v[4:7]
	v_mfma_f32_16x16x32_bf16 v[0:3], v[158:161], v[174:177], v[0:3]
	s_waitcnt lgkmcnt(3)
	v_mfma_f32_16x16x32_bf16 v[124:127], v[180:183], v[162:165], v[124:127]
	v_mfma_f32_16x16x32_bf16 v[120:123], v[180:183], v[166:169], v[120:123]
	v_mfma_f32_16x16x32_bf16 v[116:119], v[180:183], v[170:173], v[116:119]
	v_mfma_f32_16x16x32_bf16 v[112:115], v[180:183], v[174:177], v[112:115]
	s_waitcnt lgkmcnt(2)
	v_mfma_f32_16x16x32_bf16 v[108:111], v[184:187], v[162:165], v[108:111]
	v_mfma_f32_16x16x32_bf16 v[104:107], v[184:187], v[166:169], v[104:107]
	v_mfma_f32_16x16x32_bf16 v[100:103], v[184:187], v[170:173], v[100:103]
	v_mfma_f32_16x16x32_bf16 v[96:99], v[184:187], v[174:177], v[96:99]
	s_waitcnt lgkmcnt(1)
	v_mfma_f32_16x16x32_bf16 v[92:95], v[188:191], v[162:165], v[92:95]
	v_mfma_f32_16x16x32_bf16 v[88:91], v[188:191], v[166:169], v[88:91]
	v_mfma_f32_16x16x32_bf16 v[80:83], v[188:191], v[170:173], v[80:83]
	v_mfma_f32_16x16x32_bf16 v[72:75], v[188:191], v[174:177], v[72:75]
	s_waitcnt lgkmcnt(0)
	v_mfma_f32_16x16x32_bf16 v[64:67], v[192:195], v[162:165], v[64:67]
	v_mfma_f32_16x16x32_bf16 v[56:59], v[192:195], v[166:169], v[56:59]
	v_mfma_f32_16x16x32_bf16 v[48:51], v[192:195], v[170:173], v[48:51]
	v_mfma_f32_16x16x32_bf16 v[40:43], v[192:195], v[174:177], v[40:43]
	s_add_i32 s39, s38, 1
	s_cmp_lg_u32 s38, 2
	s_cselect_b32 s38, s39, 0
	s_add_i32 s39, s37, 1
	s_cmp_lg_u32 s37, 2
	s_cselect_b32 s37, s39, 0
	s_add_u32 s14, s14, 64
	s_addc_u32 s15, s15, 0
	s_cmpk_eq_i32 s14, 0x780
	s_cbranch_scc0 .LBB0_1520
	s_waitcnt vmcnt(6)
	s_waitcnt lgkmcnt(0)
	s_barrier
	ds_read_b128 v[134:137], v139
	ds_read_b128 v[146:149], v139 offset:1024
	ds_read_b128 v[150:153], v139 offset:2048
	ds_read_b128 v[154:157], v139 offset:3072
	ds_read_b128 v[158:161], v141
	ds_read_b128 v[162:165], v141 offset:1024
	ds_read_b128 v[166:169], v141 offset:2048
	ds_read_b128 v[170:173], v141 offset:3072
	s_waitcnt lgkmcnt(0)
	s_nop 0
	v_mfma_f32_16x16x32_bf16 v[84:87], v[134:137], v[158:161], v[84:87]
	v_mfma_f32_16x16x32_bf16 v[76:79], v[134:137], v[162:165], v[76:79]
	v_mfma_f32_16x16x32_bf16 v[68:71], v[134:137], v[166:169], v[68:71]
	v_mfma_f32_16x16x32_bf16 v[60:63], v[134:137], v[170:173], v[60:63]
	v_mfma_f32_16x16x32_bf16 v[52:55], v[146:149], v[158:161], v[52:55]
	v_mfma_f32_16x16x32_bf16 v[44:47], v[146:149], v[162:165], v[44:47]
	v_mfma_f32_16x16x32_bf16 v[36:39], v[146:149], v[166:169], v[36:39]
	v_mfma_f32_16x16x32_bf16 v[32:35], v[146:149], v[170:173], v[32:35]
	v_mfma_f32_16x16x32_bf16 v[28:31], v[150:153], v[158:161], v[28:31]
	v_mfma_f32_16x16x32_bf16 v[24:27], v[150:153], v[162:165], v[24:27]
	v_mfma_f32_16x16x32_bf16 v[20:23], v[150:153], v[166:169], v[20:23]
	v_mfma_f32_16x16x32_bf16 v[16:19], v[150:153], v[170:173], v[16:19]
	v_mfma_f32_16x16x32_bf16 v[12:15], v[154:157], v[158:161], v[12:15]
	v_mfma_f32_16x16x32_bf16 v[8:11], v[154:157], v[162:165], v[8:11]
	v_mfma_f32_16x16x32_bf16 v[4:7], v[154:157], v[166:169], v[4:7]
	v_mfma_f32_16x16x32_bf16 v[0:3], v[154:157], v[170:173], v[0:3]
	ds_read_b128 v[134:137], v139 offset:4096
	ds_read_b128 v[146:149], v139 offset:5120
	ds_read_b128 v[150:153], v139 offset:6144
	ds_read_b128 v[154:157], v139 offset:7168
	s_waitcnt lgkmcnt(0)
	s_nop 0
	v_mfma_f32_16x16x32_bf16 v[124:127], v[134:137], v[158:161], v[124:127]
	v_mfma_f32_16x16x32_bf16 v[120:123], v[134:137], v[162:165], v[120:123]
	v_mfma_f32_16x16x32_bf16 v[174:177], v[134:137], v[166:169], v[116:119]
	v_mfma_f32_16x16x32_bf16 v[134:137], v[134:137], v[170:173], v[112:115]
	v_mfma_f32_16x16x32_bf16 v[178:181], v[146:149], v[158:161], v[108:111]
	v_mfma_f32_16x16x32_bf16 v[182:185], v[146:149], v[162:165], v[104:107]
	v_mfma_f32_16x16x32_bf16 v[186:189], v[146:149], v[166:169], v[100:103]
	v_mfma_f32_16x16x32_bf16 v[146:149], v[146:149], v[170:173], v[96:99]
	v_mfma_f32_16x16x32_bf16 v[190:193], v[150:153], v[158:161], v[92:95]
	v_mfma_f32_16x16x32_bf16 v[194:197], v[150:153], v[162:165], v[88:91]
	v_mfma_f32_16x16x32_bf16 v[198:201], v[150:153], v[166:169], v[80:83]
	v_mfma_f32_16x16x32_bf16 v[150:153], v[150:153], v[170:173], v[72:75]
	v_mfma_f32_16x16x32_bf16 v[158:161], v[154:157], v[158:161], v[64:67]
	v_mfma_f32_16x16x32_bf16 v[162:165], v[154:157], v[162:165], v[56:59]
	v_mfma_f32_16x16x32_bf16 v[166:169], v[154:157], v[166:169], v[48:51]
	v_mfma_f32_16x16x32_bf16 v[154:157], v[154:157], v[170:173], v[40:43]
	s_waitcnt vmcnt(0)
	s_waitcnt lgkmcnt(0)
	s_barrier
	ds_read_b128 v[40:43], v128
	ds_read_b128 v[48:51], v128 offset:1024
	ds_read_b128 v[56:59], v128 offset:2048
	ds_read_b128 v[170:173], v128 offset:3072
	ds_read_b128 v[202:205], v144
	ds_read_b128 v[206:209], v144 offset:1024
	ds_read_b128 v[210:213], v144 offset:2048
	ds_read_b128 v[214:217], v144 offset:3072
	s_waitcnt lgkmcnt(0)
	s_nop 0
	v_mfma_f32_16x16x32_bf16 v[222:225], v[40:43], v[206:209], v[76:79]
	v_mfma_f32_16x16x32_bf16 v[112:115], v[40:43], v[210:213], v[68:71]
	v_mfma_f32_16x16x32_bf16 v[72:75], v[170:173], v[202:205], v[12:15]
	v_mfma_f32_16x16x32_bf16 v[76:79], v[170:173], v[206:209], v[8:11]
	v_mfma_f32_16x16x32_bf16 v[64:67], v[170:173], v[210:213], v[4:7]
	v_mfma_f32_16x16x32_bf16 v[68:71], v[170:173], v[214:217], v[0:3]
	ds_read_b128 v[0:3], v128 offset:4096
	ds_read_b128 v[4:7], v128 offset:5120
	ds_read_b128 v[8:11], v128 offset:6144
	ds_read_b128 v[170:173], v128 offset:7168
	s_waitcnt lgkmcnt(0)
	v_mfma_f32_16x16x32_bf16 v[218:221], v[40:43], v[202:205], v[84:87]
	v_mfma_f32_16x16x32_bf16 v[116:119], v[40:43], v[214:217], v[60:63]
	v_mfma_f32_16x16x32_bf16 v[104:107], v[48:51], v[202:205], v[52:55]
	v_mfma_f32_16x16x32_bf16 v[108:111], v[48:51], v[206:209], v[44:47]
	v_mfma_f32_16x16x32_bf16 v[96:99], v[48:51], v[210:213], v[36:39]
	v_mfma_f32_16x16x32_bf16 v[100:103], v[48:51], v[214:217], v[32:35]
	v_mfma_f32_16x16x32_bf16 v[88:91], v[56:59], v[202:205], v[28:31]
	v_mfma_f32_16x16x32_bf16 v[92:95], v[56:59], v[206:209], v[24:27]
	v_mfma_f32_16x16x32_bf16 v[80:83], v[56:59], v[210:213], v[20:23]
	v_mfma_f32_16x16x32_bf16 v[84:87], v[56:59], v[214:217], v[16:19]
	v_mfma_f32_16x16x32_bf16 v[56:59], v[0:3], v[202:205], v[124:127]
	v_mfma_f32_16x16x32_bf16 v[60:63], v[0:3], v[206:209], v[120:123]
	v_mfma_f32_16x16x32_bf16 v[48:51], v[0:3], v[210:213], v[174:177]
	v_mfma_f32_16x16x32_bf16 v[52:55], v[0:3], v[214:217], v[134:137]
	v_mfma_f32_16x16x32_bf16 v[40:43], v[4:7], v[202:205], v[178:181]
	v_mfma_f32_16x16x32_bf16 v[44:47], v[4:7], v[206:209], v[182:185]
	v_mfma_f32_16x16x32_bf16 v[32:35], v[4:7], v[210:213], v[186:189]
	v_mfma_f32_16x16x32_bf16 v[36:39], v[4:7], v[214:217], v[146:149]
	v_mfma_f32_16x16x32_bf16 v[24:27], v[8:11], v[202:205], v[190:193]
	v_mfma_f32_16x16x32_bf16 v[28:31], v[8:11], v[206:209], v[194:197]
	v_mfma_f32_16x16x32_bf16 v[16:19], v[8:11], v[210:213], v[198:201]
	v_mfma_f32_16x16x32_bf16 v[20:23], v[8:11], v[214:217], v[150:153]
	v_mfma_f32_16x16x32_bf16 v[8:11], v[170:173], v[202:205], v[158:161]
	v_mfma_f32_16x16x32_bf16 v[12:15], v[170:173], v[206:209], v[162:165]
	v_mfma_f32_16x16x32_bf16 v[0:3], v[170:173], v[210:213], v[166:169]
	v_mfma_f32_16x16x32_bf16 v[4:7], v[170:173], v[214:217], v[154:157]
	v_mul_f32_e32 v121, 0xbfb8aa3b, v218
	v_exp_f32_e32 v121, v121
	v_or_b32_e32 v120, s36, v140
	v_ashrrev_i32_e32 v120, 1, v120
	v_or_b32_e32 v122, v120, v138
	v_add_f32_e32 v120, 1.0, v121
	v_rcp_f32_e32 v125, v120
	v_add_u32_e32 v124, s35, v145
	v_readlane_b32 s36, v241, 17
	v_mov_b32_e32 v126, v124
	v_mul_f32_e32 v120, v218, v125
	v_mul_f32_e32 v120, v222, v120
	v_mul_f32_e32 v134, 0xbfb8aa3b, v219
	v_readlane_b32 s37, v241, 18
	v_exp_f32_e32 v134, v134
	s_waitcnt lgkmcnt(0)
	s_barrier
	v_ashrrev_i32_e32 v123, 31, v122
	v_cvt_pk_bf16_f32 v125, v120, v120
	v_mov_b64_e32 v[120:121], s[36:37]
	v_mad_i64_i32 v[126:127], s[14:15], v126, s33, v[120:121]
	v_lshlrev_b64 v[122:123], 1, v[122:123]
	v_lshl_add_u64 v[126:127], v[126:127], 0, v[122:123]
	global_store_short_d16_hi v[126:127], v125, off
	v_add_f32_e32 v125, 1.0, v134
	v_rcp_f32_e32 v127, v125
	v_or_b32_e32 v134, 1, v124
	v_mov_b32_e32 v135, v134
	v_mul_f32_e32 v125, v219, v127
	v_mul_f32_e32 v125, v223, v125
	v_cvt_pk_bf16_f32 v125, v125, v125
	v_mul_f32_e32 v126, 0xbfb8aa3b, v220
	v_exp_f32_e32 v136, v126
	v_mad_i64_i32 v[126:127], s[14:15], v135, s33, v[120:121]
	v_lshl_add_u64 v[126:127], v[126:127], 0, v[122:123]
	global_store_short_d16_hi v[126:127], v125, off
	v_add_f32_e32 v125, 1.0, v136
	v_rcp_f32_e32 v127, v125
	v_or_b32_e32 v135, 2, v124
	v_mov_b32_e32 v136, v135
	v_mul_f32_e32 v125, v220, v127
	v_mul_f32_e32 v125, v224, v125
	v_cvt_pk_bf16_f32 v125, v125, v125
	v_mul_f32_e32 v126, 0xbfb8aa3b, v221
	v_exp_f32_e32 v137, v126
	v_mad_i64_i32 v[126:127], s[14:15], v136, s33, v[120:121]
	v_lshl_add_u64 v[126:127], v[126:127], 0, v[122:123]
	global_store_short_d16_hi v[126:127], v125, off
	v_add_f32_e32 v125, 1.0, v137
	v_rcp_f32_e32 v127, v125
	v_or_b32_e32 v136, 3, v124
	v_mov_b32_e32 v137, v136
	v_mul_f32_e32 v125, v221, v127
	v_mul_f32_e32 v125, v225, v125
	v_cvt_pk_bf16_f32 v125, v125, v125
	v_mul_f32_e32 v126, 0xbfb8aa3b, v112
	v_exp_f32_e32 v146, v126
	v_mad_i64_i32 v[126:127], s[14:15], v137, s33, v[120:121]
	v_lshl_add_u64 v[126:127], v[126:127], 0, v[122:123]
	v_add_f32_e32 v137, 1.0, v146
	v_rcp_f32_e32 v147, v137
	global_store_short_d16_hi v[126:127], v125, off
	v_mov_b32_e32 v125, v124
	v_mul_f32_e32 v112, v112, v147
	v_mul_f32_e32 v126, 0xbfb8aa3b, v113
	v_exp_f32_e32 v137, v126
	v_mul_f32_e32 v112, v116, v112
	v_cvt_pk_bf16_f32 v112, v112, v112
	v_add_f32_e32 v116, 1.0, v137
	v_mad_i64_i32 v[126:127], s[14:15], v125, s33, v[120:121]
	v_rcp_f32_e32 v137, v116
	v_lshl_add_u64 v[126:127], v[126:127], 0, v[122:123]
	global_store_short_d16_hi v[126:127], v112, off offset:32
	v_mul_f32_e32 v112, v113, v137
	v_mul_f32_e32 v116, 0xbfb8aa3b, v114
	v_exp_f32_e32 v116, v116
	v_mul_f32_e32 v112, v117, v112
	v_cvt_pk_bf16_f32 v117, v112, v112
	v_add_f32_e32 v116, 1.0, v116
	v_rcp_f32_e32 v126, v116
	v_mad_i64_i32 v[112:113], s[14:15], v134, s33, v[120:121]
	v_lshl_add_u64 v[112:113], v[112:113], 0, v[122:123]
	global_store_short_d16_hi v[112:113], v117, off offset:32
	v_mul_f32_e32 v112, v114, v126
	v_mul_f32_e32 v114, 0xbfb8aa3b, v115
	v_exp_f32_e32 v114, v114
	v_mul_f32_e32 v112, v118, v112
	v_add_f32_e32 v114, 1.0, v114
	v_rcp_f32_e32 v118, v114
	v_cvt_pk_bf16_f32 v116, v112, v112
	v_mad_i64_i32 v[112:113], s[14:15], v135, s33, v[120:121]
	v_lshl_add_u64 v[112:113], v[112:113], 0, v[122:123]
	global_store_short_d16_hi v[112:113], v116, off offset:32
	v_mul_f32_e32 v112, v115, v118
	v_mul_f32_e32 v112, v119, v112
	v_cvt_pk_bf16_f32 v114, v112, v112
	v_mul_f32_e32 v112, 0xbfb8aa3b, v104
	v_exp_f32_e32 v115, v112
	v_readlane_b32 s38, v241, 19
	v_mad_i64_i32 v[112:113], s[14:15], v136, s33, v[120:121]
	v_lshl_add_u64 v[112:113], v[112:113], 0, v[122:123]
	global_store_short_d16_hi v[112:113], v114, off offset:32
	v_add_f32_e32 v112, 1.0, v115
	v_rcp_f32_e32 v114, v112
	v_or_b32_e32 v115, 16, v124
	v_mov_b32_e32 v116, v115
	v_mul_f32_e32 v104, v104, v114
	v_mul_f32_e32 v104, v108, v104
	v_cvt_pk_bf16_f32 v104, v104, v104
	v_mul_f32_e32 v108, 0xbfb8aa3b, v105
	v_exp_f32_e32 v108, v108
	v_mad_i64_i32 v[112:113], s[14:15], v116, s33, v[120:121]
	v_lshl_add_u64 v[112:113], v[112:113], 0, v[122:123]
	global_store_short_d16_hi v[112:113], v104, off
	v_add_f32_e32 v104, 1.0, v108
	v_rcp_f32_e32 v112, v104
	v_or_b32_e32 v113, 17, v124
	v_mov_b32_e32 v114, v113
	v_mul_f32_e32 v104, v105, v112
	v_mul_f32_e32 v104, v109, v104
	v_cvt_pk_bf16_f32 v108, v104, v104
	v_mul_f32_e32 v104, 0xbfb8aa3b, v106
	v_exp_f32_e32 v109, v104
	v_mad_i64_i32 v[104:105], s[14:15], v114, s33, v[120:121]
	v_lshl_add_u64 v[104:105], v[104:105], 0, v[122:123]
	global_store_short_d16_hi v[104:105], v108, off
	v_add_f32_e32 v104, 1.0, v109
	v_rcp_f32_e32 v108, v104
	v_or_b32_e32 v109, 18, v124
	v_mov_b32_e32 v112, v109
	v_mul_f32_e32 v104, v106, v108
	v_mul_f32_e32 v104, v110, v104
	v_cvt_pk_bf16_f32 v106, v104, v104
	v_mul_f32_e32 v104, 0xbfb8aa3b, v107
	v_exp_f32_e32 v108, v104
	v_mad_i64_i32 v[104:105], s[14:15], v112, s33, v[120:121]
	v_lshl_add_u64 v[104:105], v[104:105], 0, v[122:123]
	global_store_short_d16_hi v[104:105], v106, off
	v_add_f32_e32 v104, 1.0, v108
	v_rcp_f32_e32 v106, v104
	v_or_b32_e32 v108, 19, v124
	v_mov_b32_e32 v110, v108
	v_mul_f32_e32 v104, v107, v106
	v_mul_f32_e32 v106, 0xbfb8aa3b, v96
	v_exp_f32_e32 v106, v106
	v_mul_f32_e32 v104, v111, v104
	v_add_f32_e32 v106, 1.0, v106
	v_cvt_pk_bf16_f32 v107, v104, v104
	v_mad_i64_i32 v[104:105], s[14:15], v110, s33, v[120:121]
	v_rcp_f32_e32 v111, v106
	v_lshl_add_u64 v[104:105], v[104:105], 0, v[122:123]
	global_store_short_d16_hi v[104:105], v107, off
	v_mul_f32_e32 v96, v96, v111
	v_mul_f32_e32 v104, 0xbfb8aa3b, v97
	v_exp_f32_e32 v106, v104
	v_mul_f32_e32 v96, v100, v96
	v_cvt_pk_bf16_f32 v96, v96, v96
	v_add_f32_e32 v100, 1.0, v106
	v_rcp_f32_e32 v107, v100
	v_mad_i64_i32 v[104:105], s[14:15], v115, s33, v[120:121]
	v_lshl_add_u64 v[104:105], v[104:105], 0, v[122:123]
	global_store_short_d16_hi v[104:105], v96, off offset:32
	v_mul_f32_e32 v96, v97, v107
	v_mul_f32_e32 v100, 0xbfb8aa3b, v98
	v_exp_f32_e32 v100, v100
	v_mul_f32_e32 v96, v101, v96
	v_add_f32_e32 v100, 1.0, v100
	v_rcp_f32_e32 v105, v100
	v_cvt_pk_bf16_f32 v101, v96, v96
	v_mad_i64_i32 v[96:97], s[14:15], v113, s33, v[120:121]
	v_lshl_add_u64 v[96:97], v[96:97], 0, v[122:123]
	global_store_short_d16_hi v[96:97], v101, off offset:32
	v_mul_f32_e32 v96, v98, v105
	v_mul_f32_e32 v98, 0xbfb8aa3b, v99
	v_exp_f32_e32 v98, v98
	v_mul_f32_e32 v96, v102, v96
	v_add_f32_e32 v98, 1.0, v98
	v_rcp_f32_e32 v102, v98
	v_cvt_pk_bf16_f32 v100, v96, v96
	v_mad_i64_i32 v[96:97], s[14:15], v109, s33, v[120:121]
	v_lshl_add_u64 v[96:97], v[96:97], 0, v[122:123]
	global_store_short_d16_hi v[96:97], v100, off offset:32
	v_mul_f32_e32 v96, v99, v102
	v_mul_f32_e32 v96, v103, v96
	v_cvt_pk_bf16_f32 v98, v96, v96
	v_mul_f32_e32 v96, 0xbfb8aa3b, v88
	v_exp_f32_e32 v99, v96
	v_readlane_b32 s39, v241, 20
	v_mad_i64_i32 v[96:97], s[14:15], v108, s33, v[120:121]
	v_lshl_add_u64 v[96:97], v[96:97], 0, v[122:123]
	global_store_short_d16_hi v[96:97], v98, off offset:32
	v_add_f32_e32 v96, 1.0, v99
	v_rcp_f32_e32 v98, v96
	v_or_b32_e32 v99, 32, v124
	v_mov_b32_e32 v100, v99
	v_mul_f32_e32 v88, v88, v98
	v_mul_f32_e32 v88, v92, v88
	v_cvt_pk_bf16_f32 v88, v88, v88
	v_mul_f32_e32 v92, 0xbfb8aa3b, v89
	v_exp_f32_e32 v92, v92
	v_mad_i64_i32 v[96:97], s[14:15], v100, s33, v[120:121]
	v_lshl_add_u64 v[96:97], v[96:97], 0, v[122:123]
	global_store_short_d16_hi v[96:97], v88, off
	v_add_f32_e32 v88, 1.0, v92
	v_rcp_f32_e32 v96, v88
	v_or_b32_e32 v97, 33, v124
	v_mov_b32_e32 v98, v97
	v_mul_f32_e32 v88, v89, v96
	v_mul_f32_e32 v88, v93, v88
	v_cvt_pk_bf16_f32 v92, v88, v88
	v_mul_f32_e32 v88, 0xbfb8aa3b, v90
	v_exp_f32_e32 v93, v88
	v_mad_i64_i32 v[88:89], s[14:15], v98, s33, v[120:121]
	v_lshl_add_u64 v[88:89], v[88:89], 0, v[122:123]
	global_store_short_d16_hi v[88:89], v92, off
	v_add_f32_e32 v88, 1.0, v93
	v_rcp_f32_e32 v92, v88
	v_or_b32_e32 v93, 34, v124
	v_mov_b32_e32 v96, v93
	v_mul_f32_e32 v88, v90, v92
	v_mul_f32_e32 v88, v94, v88
	v_cvt_pk_bf16_f32 v90, v88, v88
	v_mul_f32_e32 v88, 0xbfb8aa3b, v91
	v_exp_f32_e32 v92, v88
	v_mad_i64_i32 v[88:89], s[14:15], v96, s33, v[120:121]
	v_lshl_add_u64 v[88:89], v[88:89], 0, v[122:123]
	global_store_short_d16_hi v[88:89], v90, off
	v_add_f32_e32 v88, 1.0, v92
	v_rcp_f32_e32 v90, v88
	v_or_b32_e32 v92, 35, v124
	v_mov_b32_e32 v94, v92
	v_mul_f32_e32 v88, v91, v90
	v_mul_f32_e32 v90, 0xbfb8aa3b, v80
	v_exp_f32_e32 v90, v90
	v_mul_f32_e32 v88, v95, v88
	v_add_f32_e32 v90, 1.0, v90
	v_cvt_pk_bf16_f32 v91, v88, v88
	v_mad_i64_i32 v[88:89], s[14:15], v94, s33, v[120:121]
	v_rcp_f32_e32 v95, v90
	v_lshl_add_u64 v[88:89], v[88:89], 0, v[122:123]
	global_store_short_d16_hi v[88:89], v91, off
	v_mul_f32_e32 v80, v80, v95
	v_mul_f32_e32 v88, 0xbfb8aa3b, v81
	v_exp_f32_e32 v90, v88
	v_mul_f32_e32 v80, v84, v80
	v_cvt_pk_bf16_f32 v80, v80, v80
	v_add_f32_e32 v84, 1.0, v90
	v_rcp_f32_e32 v91, v84
	v_mad_i64_i32 v[88:89], s[14:15], v99, s33, v[120:121]
	v_lshl_add_u64 v[88:89], v[88:89], 0, v[122:123]
	global_store_short_d16_hi v[88:89], v80, off offset:32
	v_mul_f32_e32 v80, v81, v91
	v_mul_f32_e32 v84, 0xbfb8aa3b, v82
	v_exp_f32_e32 v84, v84
	v_mul_f32_e32 v80, v85, v80
	v_add_f32_e32 v84, 1.0, v84
	v_rcp_f32_e32 v89, v84
	v_cvt_pk_bf16_f32 v85, v80, v80
	v_mad_i64_i32 v[80:81], s[14:15], v97, s33, v[120:121]
	v_lshl_add_u64 v[80:81], v[80:81], 0, v[122:123]
	global_store_short_d16_hi v[80:81], v85, off offset:32
	v_mul_f32_e32 v80, v82, v89
	v_mul_f32_e32 v82, 0xbfb8aa3b, v83
	v_exp_f32_e32 v82, v82
	v_mul_f32_e32 v80, v86, v80
	v_add_f32_e32 v82, 1.0, v82
	v_rcp_f32_e32 v86, v82
	v_cvt_pk_bf16_f32 v84, v80, v80
	v_mad_i64_i32 v[80:81], s[14:15], v93, s33, v[120:121]
	v_lshl_add_u64 v[80:81], v[80:81], 0, v[122:123]
	global_store_short_d16_hi v[80:81], v84, off offset:32
	v_mul_f32_e32 v80, v83, v86
	v_mul_f32_e32 v80, v87, v80
	v_cvt_pk_bf16_f32 v82, v80, v80
	v_mul_f32_e32 v80, 0xbfb8aa3b, v72
	v_exp_f32_e32 v83, v80
	v_readlane_b32 s40, v241, 21
	v_mad_i64_i32 v[80:81], s[14:15], v92, s33, v[120:121]
	v_lshl_add_u64 v[80:81], v[80:81], 0, v[122:123]
	global_store_short_d16_hi v[80:81], v82, off offset:32
	v_add_f32_e32 v80, 1.0, v83
	v_rcp_f32_e32 v82, v80
	v_or_b32_e32 v83, 48, v124
	v_mov_b32_e32 v84, v83
	v_mul_f32_e32 v72, v72, v82
	v_mul_f32_e32 v72, v76, v72
	v_cvt_pk_bf16_f32 v72, v72, v72
	v_mul_f32_e32 v76, 0xbfb8aa3b, v73
	v_exp_f32_e32 v76, v76
	v_mad_i64_i32 v[80:81], s[14:15], v84, s33, v[120:121]
	v_lshl_add_u64 v[80:81], v[80:81], 0, v[122:123]
	global_store_short_d16_hi v[80:81], v72, off
	v_add_f32_e32 v72, 1.0, v76
	v_rcp_f32_e32 v80, v72
	v_or_b32_e32 v81, 49, v124
	v_mov_b32_e32 v82, v81
	v_mul_f32_e32 v72, v73, v80
	v_mul_f32_e32 v72, v77, v72
	v_cvt_pk_bf16_f32 v76, v72, v72
	v_mul_f32_e32 v72, 0xbfb8aa3b, v74
	v_exp_f32_e32 v77, v72
	v_mad_i64_i32 v[72:73], s[14:15], v82, s33, v[120:121]
	v_lshl_add_u64 v[72:73], v[72:73], 0, v[122:123]
	global_store_short_d16_hi v[72:73], v76, off
	v_add_f32_e32 v72, 1.0, v77
	v_rcp_f32_e32 v76, v72
	v_or_b32_e32 v77, 50, v124
	v_mov_b32_e32 v80, v77
	v_mul_f32_e32 v72, v74, v76
	v_mul_f32_e32 v72, v78, v72
	v_cvt_pk_bf16_f32 v74, v72, v72
	v_mul_f32_e32 v72, 0xbfb8aa3b, v75
	v_exp_f32_e32 v76, v72
	v_mad_i64_i32 v[72:73], s[14:15], v80, s33, v[120:121]
	v_lshl_add_u64 v[72:73], v[72:73], 0, v[122:123]
	global_store_short_d16_hi v[72:73], v74, off
	v_add_f32_e32 v72, 1.0, v76
	v_rcp_f32_e32 v74, v72
	v_or_b32_e32 v76, 51, v124
	v_mov_b32_e32 v78, v76
	v_mul_f32_e32 v72, v75, v74
	v_mul_f32_e32 v74, 0xbfb8aa3b, v64
	v_exp_f32_e32 v74, v74
	v_mul_f32_e32 v72, v79, v72
	v_add_f32_e32 v74, 1.0, v74
	v_cvt_pk_bf16_f32 v75, v72, v72
	v_mad_i64_i32 v[72:73], s[14:15], v78, s33, v[120:121]
	v_rcp_f32_e32 v79, v74
	v_lshl_add_u64 v[72:73], v[72:73], 0, v[122:123]
	global_store_short_d16_hi v[72:73], v75, off
	v_mul_f32_e32 v64, v64, v79
	v_mul_f32_e32 v72, 0xbfb8aa3b, v65
	v_exp_f32_e32 v74, v72
	v_mul_f32_e32 v64, v68, v64
	v_cvt_pk_bf16_f32 v64, v64, v64
	v_add_f32_e32 v68, 1.0, v74
	v_rcp_f32_e32 v75, v68
	v_mad_i64_i32 v[72:73], s[14:15], v83, s33, v[120:121]
	v_lshl_add_u64 v[72:73], v[72:73], 0, v[122:123]
	global_store_short_d16_hi v[72:73], v64, off offset:32
	v_mul_f32_e32 v64, v65, v75
	v_mul_f32_e32 v68, 0xbfb8aa3b, v66
	v_exp_f32_e32 v68, v68
	v_mul_f32_e32 v64, v69, v64
	v_add_f32_e32 v68, 1.0, v68
	v_rcp_f32_e32 v73, v68
	v_cvt_pk_bf16_f32 v69, v64, v64
	v_mad_i64_i32 v[64:65], s[14:15], v81, s33, v[120:121]
	v_lshl_add_u64 v[64:65], v[64:65], 0, v[122:123]
	global_store_short_d16_hi v[64:65], v69, off offset:32
	v_mul_f32_e32 v64, v66, v73
	v_mul_f32_e32 v66, 0xbfb8aa3b, v67
	v_exp_f32_e32 v66, v66
	v_mul_f32_e32 v64, v70, v64
	v_add_f32_e32 v66, 1.0, v66
	v_rcp_f32_e32 v70, v66
	v_cvt_pk_bf16_f32 v68, v64, v64
	v_mad_i64_i32 v[64:65], s[14:15], v77, s33, v[120:121]
	v_lshl_add_u64 v[64:65], v[64:65], 0, v[122:123]
	global_store_short_d16_hi v[64:65], v68, off offset:32
	v_mul_f32_e32 v64, v67, v70
	v_mul_f32_e32 v64, v71, v64
	v_cvt_pk_bf16_f32 v66, v64, v64
	v_mad_i64_i32 v[64:65], s[14:15], v76, s33, v[120:121]
	v_lshl_add_u64 v[64:65], v[64:65], 0, v[122:123]
	global_store_short_d16_hi v[64:65], v66, off offset:32
	v_readlane_b32 s41, v241, 22
	v_readlane_b32 s42, v241, 23
	v_readlane_b32 s43, v241, 24
	v_mul_f32_e32 v64, 0xbfb8aa3b, v56
	v_exp_f32_e32 v64, v64
	v_or_b32_e32 v66, 64, v124
	v_mov_b32_e32 v65, v66
	v_add_f32_e32 v64, 1.0, v64
	v_rcp_f32_e32 v68, v64
	s_add_i32 s2, s2, s3
	v_mul_f32_e32 v56, v56, v68
	v_mul_f32_e32 v56, v60, v56
	v_cvt_pk_bf16_f32 v56, v56, v56
	v_mul_f32_e32 v60, 0xbfb8aa3b, v57
	v_exp_f32_e32 v60, v60
	v_mad_i64_i32 v[64:65], s[14:15], v65, s33, v[120:121]
	v_lshl_add_u64 v[64:65], v[64:65], 0, v[122:123]
	global_store_short_d16_hi v[64:65], v56, off
	v_add_f32_e32 v56, 1.0, v60
	v_rcp_f32_e32 v64, v56
	v_or_b32_e32 v65, 0x41, v124
	v_mov_b32_e32 v67, v65
	v_mul_f32_e32 v56, v57, v64
	v_mul_f32_e32 v56, v61, v56
	v_cvt_pk_bf16_f32 v60, v56, v56
	v_mul_f32_e32 v56, 0xbfb8aa3b, v58
	v_exp_f32_e32 v61, v56
	v_mad_i64_i32 v[56:57], s[14:15], v67, s33, v[120:121]
	v_lshl_add_u64 v[56:57], v[56:57], 0, v[122:123]
	global_store_short_d16_hi v[56:57], v60, off
	v_add_f32_e32 v56, 1.0, v61
	v_rcp_f32_e32 v60, v56
	v_or_b32_e32 v61, 0x42, v124
	v_mov_b32_e32 v64, v61
	v_mul_f32_e32 v56, v58, v60
	v_mul_f32_e32 v56, v62, v56
	v_cvt_pk_bf16_f32 v58, v56, v56
	v_mul_f32_e32 v56, 0xbfb8aa3b, v59
	v_exp_f32_e32 v60, v56
	v_mad_i64_i32 v[56:57], s[14:15], v64, s33, v[120:121]
	v_lshl_add_u64 v[56:57], v[56:57], 0, v[122:123]
	global_store_short_d16_hi v[56:57], v58, off
	v_add_f32_e32 v56, 1.0, v60
	v_rcp_f32_e32 v58, v56
	v_or_b32_e32 v60, 0x43, v124
	v_mov_b32_e32 v62, v60
	v_mul_f32_e32 v56, v59, v58
	v_mul_f32_e32 v58, 0xbfb8aa3b, v48
	v_exp_f32_e32 v58, v58
	v_mul_f32_e32 v56, v63, v56
	v_add_f32_e32 v58, 1.0, v58
	v_cvt_pk_bf16_f32 v59, v56, v56
	v_mad_i64_i32 v[56:57], s[14:15], v62, s33, v[120:121]
	v_rcp_f32_e32 v63, v58
	v_lshl_add_u64 v[56:57], v[56:57], 0, v[122:123]
	global_store_short_d16_hi v[56:57], v59, off
	v_mul_f32_e32 v48, v48, v63
	v_mul_f32_e32 v56, 0xbfb8aa3b, v49
	v_exp_f32_e32 v58, v56
	v_mul_f32_e32 v48, v52, v48
	v_cvt_pk_bf16_f32 v48, v48, v48
	v_add_f32_e32 v52, 1.0, v58
	v_rcp_f32_e32 v59, v52
	v_mad_i64_i32 v[56:57], s[14:15], v66, s33, v[120:121]
	v_lshl_add_u64 v[56:57], v[56:57], 0, v[122:123]
	global_store_short_d16_hi v[56:57], v48, off offset:32
	v_mul_f32_e32 v48, v49, v59
	v_mul_f32_e32 v52, 0xbfb8aa3b, v50
	v_exp_f32_e32 v52, v52
	v_mul_f32_e32 v48, v53, v48
	v_add_f32_e32 v52, 1.0, v52
	v_rcp_f32_e32 v57, v52
	v_cvt_pk_bf16_f32 v53, v48, v48
	v_mad_i64_i32 v[48:49], s[14:15], v65, s33, v[120:121]
	v_lshl_add_u64 v[48:49], v[48:49], 0, v[122:123]
	global_store_short_d16_hi v[48:49], v53, off offset:32
	v_mul_f32_e32 v48, v50, v57
	v_mul_f32_e32 v50, 0xbfb8aa3b, v51
	v_exp_f32_e32 v50, v50
	v_mul_f32_e32 v48, v54, v48
	v_add_f32_e32 v50, 1.0, v50
	v_rcp_f32_e32 v54, v50
	v_cvt_pk_bf16_f32 v52, v48, v48
	v_mad_i64_i32 v[48:49], s[14:15], v61, s33, v[120:121]
	v_lshl_add_u64 v[48:49], v[48:49], 0, v[122:123]
	global_store_short_d16_hi v[48:49], v52, off offset:32
	v_mul_f32_e32 v48, v51, v54
	v_mul_f32_e32 v48, v55, v48
	v_cvt_pk_bf16_f32 v50, v48, v48
	v_mul_f32_e32 v48, 0xbfb8aa3b, v40
	v_exp_f32_e32 v51, v48
	s_add_i32 s19, s19, s20
	v_mad_i64_i32 v[48:49], s[14:15], v60, s33, v[120:121]
	v_lshl_add_u64 v[48:49], v[48:49], 0, v[122:123]
	global_store_short_d16_hi v[48:49], v50, off offset:32
	v_add_f32_e32 v48, 1.0, v51
	v_rcp_f32_e32 v50, v48
	v_or_b32_e32 v51, 0x50, v124
	v_mov_b32_e32 v52, v51
	v_mul_f32_e32 v40, v40, v50
	v_mul_f32_e32 v40, v44, v40
	v_cvt_pk_bf16_f32 v40, v40, v40
	v_mul_f32_e32 v44, 0xbfb8aa3b, v41
	v_exp_f32_e32 v44, v44
	v_mad_i64_i32 v[48:49], s[14:15], v52, s33, v[120:121]
	v_lshl_add_u64 v[48:49], v[48:49], 0, v[122:123]
	global_store_short_d16_hi v[48:49], v40, off
	v_add_f32_e32 v40, 1.0, v44
	v_rcp_f32_e32 v48, v40
	v_or_b32_e32 v49, 0x51, v124
	v_mov_b32_e32 v50, v49
	v_mul_f32_e32 v40, v41, v48
	v_mul_f32_e32 v40, v45, v40
	v_cvt_pk_bf16_f32 v44, v40, v40
	v_mul_f32_e32 v40, 0xbfb8aa3b, v42
	v_exp_f32_e32 v45, v40
	v_mad_i64_i32 v[40:41], s[14:15], v50, s33, v[120:121]
	v_lshl_add_u64 v[40:41], v[40:41], 0, v[122:123]
	global_store_short_d16_hi v[40:41], v44, off
	v_add_f32_e32 v40, 1.0, v45
	v_rcp_f32_e32 v44, v40
	v_or_b32_e32 v45, 0x52, v124
	v_mov_b32_e32 v48, v45
	v_mul_f32_e32 v40, v42, v44
	v_mul_f32_e32 v40, v46, v40
	v_cvt_pk_bf16_f32 v42, v40, v40
	v_mul_f32_e32 v40, 0xbfb8aa3b, v43
	v_exp_f32_e32 v44, v40
	v_mad_i64_i32 v[40:41], s[14:15], v48, s33, v[120:121]
	v_lshl_add_u64 v[40:41], v[40:41], 0, v[122:123]
	global_store_short_d16_hi v[40:41], v42, off
	v_add_f32_e32 v40, 1.0, v44
	v_rcp_f32_e32 v42, v40
	v_or_b32_e32 v44, 0x53, v124
	v_mov_b32_e32 v46, v44
	v_mul_f32_e32 v40, v43, v42
	v_mul_f32_e32 v42, 0xbfb8aa3b, v32
	v_exp_f32_e32 v42, v42
	v_mul_f32_e32 v40, v47, v40
	v_add_f32_e32 v42, 1.0, v42
	v_cvt_pk_bf16_f32 v43, v40, v40
	v_mad_i64_i32 v[40:41], s[14:15], v46, s33, v[120:121]
	v_rcp_f32_e32 v47, v42
	v_lshl_add_u64 v[40:41], v[40:41], 0, v[122:123]
	global_store_short_d16_hi v[40:41], v43, off
	v_mul_f32_e32 v32, v32, v47
	v_mul_f32_e32 v40, 0xbfb8aa3b, v33
	v_exp_f32_e32 v42, v40
	v_mul_f32_e32 v32, v36, v32
	v_cvt_pk_bf16_f32 v32, v32, v32
	v_add_f32_e32 v36, 1.0, v42
	v_rcp_f32_e32 v43, v36
	v_mad_i64_i32 v[40:41], s[14:15], v51, s33, v[120:121]
	v_lshl_add_u64 v[40:41], v[40:41], 0, v[122:123]
	global_store_short_d16_hi v[40:41], v32, off offset:32
	v_mul_f32_e32 v32, v33, v43
	v_mul_f32_e32 v36, 0xbfb8aa3b, v34
	v_exp_f32_e32 v36, v36
	v_mul_f32_e32 v32, v37, v32
	v_add_f32_e32 v36, 1.0, v36
	v_rcp_f32_e32 v41, v36
	v_cvt_pk_bf16_f32 v37, v32, v32
	v_mad_i64_i32 v[32:33], s[14:15], v49, s33, v[120:121]
	v_lshl_add_u64 v[32:33], v[32:33], 0, v[122:123]
	global_store_short_d16_hi v[32:33], v37, off offset:32
	v_mul_f32_e32 v32, v34, v41
	v_mul_f32_e32 v34, 0xbfb8aa3b, v35
	v_exp_f32_e32 v34, v34
	v_mul_f32_e32 v32, v38, v32
	v_add_f32_e32 v34, 1.0, v34
	v_rcp_f32_e32 v38, v34
	v_cvt_pk_bf16_f32 v36, v32, v32
	v_mad_i64_i32 v[32:33], s[14:15], v45, s33, v[120:121]
	v_lshl_add_u64 v[32:33], v[32:33], 0, v[122:123]
	global_store_short_d16_hi v[32:33], v36, off offset:32
	v_mul_f32_e32 v32, v35, v38
	v_mul_f32_e32 v32, v39, v32
	v_cvt_pk_bf16_f32 v34, v32, v32
	v_mul_f32_e32 v32, 0xbfb8aa3b, v24
	v_exp_f32_e32 v35, v32
	s_xor_b64 s[0:1], s[0:1], s[4:5]
	v_mad_i64_i32 v[32:33], s[14:15], v44, s33, v[120:121]
	v_lshl_add_u64 v[32:33], v[32:33], 0, v[122:123]
	global_store_short_d16_hi v[32:33], v34, off offset:32
	v_add_f32_e32 v32, 1.0, v35
	v_rcp_f32_e32 v34, v32
	v_or_b32_e32 v35, 0x60, v124
	v_mov_b32_e32 v36, v35
	v_mul_f32_e32 v24, v24, v34
	v_mul_f32_e32 v24, v28, v24
	v_cvt_pk_bf16_f32 v24, v24, v24
	v_mul_f32_e32 v28, 0xbfb8aa3b, v25
	v_exp_f32_e32 v28, v28
	v_mad_i64_i32 v[32:33], s[14:15], v36, s33, v[120:121]
	v_lshl_add_u64 v[32:33], v[32:33], 0, v[122:123]
	global_store_short_d16_hi v[32:33], v24, off
	v_add_f32_e32 v24, 1.0, v28
	v_rcp_f32_e32 v32, v24
	v_or_b32_e32 v33, 0x61, v124
	v_mov_b32_e32 v34, v33
	v_mul_f32_e32 v24, v25, v32
	v_mul_f32_e32 v24, v29, v24
	v_cvt_pk_bf16_f32 v28, v24, v24
	v_mul_f32_e32 v24, 0xbfb8aa3b, v26
	v_exp_f32_e32 v29, v24
	v_mad_i64_i32 v[24:25], s[14:15], v34, s33, v[120:121]
	v_lshl_add_u64 v[24:25], v[24:25], 0, v[122:123]
	global_store_short_d16_hi v[24:25], v28, off
	v_add_f32_e32 v24, 1.0, v29
	v_rcp_f32_e32 v28, v24
	v_or_b32_e32 v29, 0x62, v124
	v_mov_b32_e32 v32, v29
	v_mul_f32_e32 v24, v26, v28
	v_mul_f32_e32 v24, v30, v24
	v_cvt_pk_bf16_f32 v26, v24, v24
	v_mul_f32_e32 v24, 0xbfb8aa3b, v27
	v_exp_f32_e32 v28, v24
	v_mad_i64_i32 v[24:25], s[14:15], v32, s33, v[120:121]
	v_lshl_add_u64 v[24:25], v[24:25], 0, v[122:123]
	global_store_short_d16_hi v[24:25], v26, off
	v_add_f32_e32 v24, 1.0, v28
	v_rcp_f32_e32 v26, v24
	v_or_b32_e32 v28, 0x63, v124
	v_mov_b32_e32 v30, v28
	v_mul_f32_e32 v24, v27, v26
	v_mul_f32_e32 v26, 0xbfb8aa3b, v16
	v_exp_f32_e32 v26, v26
	v_mul_f32_e32 v24, v31, v24
	v_add_f32_e32 v26, 1.0, v26
	v_cvt_pk_bf16_f32 v27, v24, v24
	v_mad_i64_i32 v[24:25], s[14:15], v30, s33, v[120:121]
	v_rcp_f32_e32 v31, v26
	v_lshl_add_u64 v[24:25], v[24:25], 0, v[122:123]
	global_store_short_d16_hi v[24:25], v27, off
	v_mul_f32_e32 v16, v16, v31
	v_mul_f32_e32 v24, 0xbfb8aa3b, v17
	v_exp_f32_e32 v26, v24
	v_mul_f32_e32 v16, v20, v16
	v_cvt_pk_bf16_f32 v16, v16, v16
	v_add_f32_e32 v20, 1.0, v26
	v_rcp_f32_e32 v27, v20
	v_mad_i64_i32 v[24:25], s[14:15], v35, s33, v[120:121]
	v_lshl_add_u64 v[24:25], v[24:25], 0, v[122:123]
	global_store_short_d16_hi v[24:25], v16, off offset:32
	v_mul_f32_e32 v16, v17, v27
	v_mul_f32_e32 v20, 0xbfb8aa3b, v18
	v_exp_f32_e32 v20, v20
	v_mul_f32_e32 v16, v21, v16
	v_add_f32_e32 v20, 1.0, v20
	v_rcp_f32_e32 v25, v20
	v_cvt_pk_bf16_f32 v21, v16, v16
	v_mad_i64_i32 v[16:17], s[14:15], v33, s33, v[120:121]
	v_lshl_add_u64 v[16:17], v[16:17], 0, v[122:123]
	global_store_short_d16_hi v[16:17], v21, off offset:32
	v_mul_f32_e32 v16, v18, v25
	v_mul_f32_e32 v18, 0xbfb8aa3b, v19
	v_exp_f32_e32 v18, v18
	v_mul_f32_e32 v16, v22, v16
	v_add_f32_e32 v18, 1.0, v18
	v_rcp_f32_e32 v22, v18
	v_cvt_pk_bf16_f32 v20, v16, v16
	v_mad_i64_i32 v[16:17], s[14:15], v29, s33, v[120:121]
	v_lshl_add_u64 v[16:17], v[16:17], 0, v[122:123]
	global_store_short_d16_hi v[16:17], v20, off offset:32
	v_mul_f32_e32 v16, v19, v22
	v_mul_f32_e32 v16, v23, v16
	v_cvt_pk_bf16_f32 v18, v16, v16
	v_mul_f32_e32 v16, 0xbfb8aa3b, v8
	v_exp_f32_e32 v19, v16
	s_cmpk_gt_i32 s2, 0x1b7
	v_mad_i64_i32 v[16:17], s[14:15], v28, s33, v[120:121]
	v_lshl_add_u64 v[16:17], v[16:17], 0, v[122:123]
	global_store_short_d16_hi v[16:17], v18, off offset:32
	v_add_f32_e32 v16, 1.0, v19
	v_rcp_f32_e32 v18, v16
	v_or_b32_e32 v19, 0x70, v124
	v_mov_b32_e32 v20, v19
	v_mul_f32_e32 v8, v8, v18
	v_mul_f32_e32 v8, v12, v8
	v_cvt_pk_bf16_f32 v8, v8, v8
	v_mul_f32_e32 v12, 0xbfb8aa3b, v9
	v_exp_f32_e32 v12, v12
	v_mad_i64_i32 v[16:17], s[14:15], v20, s33, v[120:121]
	v_lshl_add_u64 v[16:17], v[16:17], 0, v[122:123]
	global_store_short_d16_hi v[16:17], v8, off
	v_add_f32_e32 v8, 1.0, v12
	v_rcp_f32_e32 v16, v8
	v_or_b32_e32 v17, 0x71, v124
	v_mov_b32_e32 v18, v17
	v_mul_f32_e32 v8, v9, v16
	v_mul_f32_e32 v8, v13, v8
	v_cvt_pk_bf16_f32 v12, v8, v8
	v_mul_f32_e32 v8, 0xbfb8aa3b, v10
	v_exp_f32_e32 v13, v8
	v_mad_i64_i32 v[8:9], s[14:15], v18, s33, v[120:121]
	v_lshl_add_u64 v[8:9], v[8:9], 0, v[122:123]
	global_store_short_d16_hi v[8:9], v12, off
	v_add_f32_e32 v8, 1.0, v13
	v_rcp_f32_e32 v12, v8
	v_or_b32_e32 v13, 0x72, v124
	v_mov_b32_e32 v16, v13
	v_mul_f32_e32 v8, v10, v12
	v_mul_f32_e32 v8, v14, v8
	v_cvt_pk_bf16_f32 v10, v8, v8
	v_mul_f32_e32 v8, 0xbfb8aa3b, v11
	v_exp_f32_e32 v12, v8
	v_mad_i64_i32 v[8:9], s[14:15], v16, s33, v[120:121]
	v_lshl_add_u64 v[8:9], v[8:9], 0, v[122:123]
	global_store_short_d16_hi v[8:9], v10, off
	v_add_f32_e32 v8, 1.0, v12
	v_rcp_f32_e32 v10, v8
	v_or_b32_e32 v12, 0x73, v124
	v_mov_b32_e32 v14, v12
	v_mul_f32_e32 v8, v11, v10
	v_mul_f32_e32 v10, 0xbfb8aa3b, v0
	v_exp_f32_e32 v10, v10
	v_mul_f32_e32 v8, v15, v8
	v_add_f32_e32 v10, 1.0, v10
	v_cvt_pk_bf16_f32 v11, v8, v8
	v_mad_i64_i32 v[8:9], s[14:15], v14, s33, v[120:121]
	v_rcp_f32_e32 v15, v10
	v_lshl_add_u64 v[8:9], v[8:9], 0, v[122:123]
	global_store_short_d16_hi v[8:9], v11, off
	v_mul_f32_e32 v0, v0, v15
	v_mul_f32_e32 v8, 0xbfb8aa3b, v1
	v_exp_f32_e32 v10, v8
	v_mul_f32_e32 v0, v4, v0
	v_cvt_pk_bf16_f32 v0, v0, v0
	v_add_f32_e32 v4, 1.0, v10
	v_rcp_f32_e32 v11, v4
	v_mad_i64_i32 v[8:9], s[14:15], v19, s33, v[120:121]
	v_lshl_add_u64 v[8:9], v[8:9], 0, v[122:123]
	global_store_short_d16_hi v[8:9], v0, off offset:32
	v_mul_f32_e32 v0, v1, v11
	v_mul_f32_e32 v4, 0xbfb8aa3b, v2
	v_exp_f32_e32 v4, v4
	v_mul_f32_e32 v0, v5, v0
	v_add_f32_e32 v4, 1.0, v4
	v_rcp_f32_e32 v9, v4
	v_cvt_pk_bf16_f32 v5, v0, v0
	v_mad_i64_i32 v[0:1], s[14:15], v17, s33, v[120:121]
	v_lshl_add_u64 v[0:1], v[0:1], 0, v[122:123]
	global_store_short_d16_hi v[0:1], v5, off offset:32
	v_mul_f32_e32 v0, v2, v9
	v_mul_f32_e32 v2, 0xbfb8aa3b, v3
	v_exp_f32_e32 v2, v2
	v_mul_f32_e32 v0, v6, v0
	v_add_f32_e32 v2, 1.0, v2
	v_rcp_f32_e32 v6, v2
	v_cvt_pk_bf16_f32 v4, v0, v0
	v_mad_i64_i32 v[0:1], s[14:15], v13, s33, v[120:121]
	v_lshl_add_u64 v[0:1], v[0:1], 0, v[122:123]
	global_store_short_d16_hi v[0:1], v4, off offset:32
	v_mul_f32_e32 v0, v3, v6
	v_mul_f32_e32 v0, v7, v0
	v_cvt_pk_bf16_f32 v2, v0, v0
	v_mad_i64_i32 v[0:1], s[14:15], v12, s33, v[120:121]
	v_lshl_add_u64 v[0:1], v[0:1], 0, v[122:123]
	global_store_short_d16_hi v[0:1], v2, off offset:32
	s_cbranch_scc0 .LBB0_1519

.LBB0_1633:
	s_or_b64 exec, exec, s[14:15]
	s_and_b64 s[0:1], exec, vcc
	v_add_u32_e32 v65, 0xfffff000, v64
	s_or_b64 s[12:13], s[0:1], s[12:13]
	v_lshrrev_b32_e32 v65, 12, v65
	s_movk_i32 s0, 0xfff
	v_add_u32_e32 v65, 6, v65
	v_cmp_lt_i32_e32 vcc, s0, v64
	s_movk_i32 s0, 0x6000
	v_mov_b32_e32 v94, v56
	v_cndmask_b32_e32 v64, 5, v65, vcc
	v_mad_u64_u32 v[64:65], s[0:1], v64, s0, v[76:77]
	s_mov_b64 s[0:1], 0x1000
	s_nop 0
	v_lshl_add_u64 v[86:87], v[64:65], 0, s[0:1]
	v_lshl_add_u64 v[90:91], v[86:87], 0, v[78:79]
	v_lshl_add_u64 v[92:93], v[86:87], 0, v[80:81]
	v_lshl_add_u64 v[66:67], v[86:87], 0, v[82:83]
	v_lshl_add_u64 v[88:89], v[86:87], 0, v[84:85]
	v_mov_b32_e32 v86, v57
	v_mov_b32_e32 v87, v61
	v_mov_b32_e32 v95, v60
	v_pk_add_f32 v[86:87], v[86:87], v[94:95]
	v_mov_b32_e32 v94, v58
	v_mov_b32_e32 v95, v62
	v_pk_add_f32 v[86:87], v[94:95], v[86:87]
	v_mov_b32_e32 v94, v59
	v_mov_b32_e32 v95, v63
	v_pk_add_f32 v[86:87], v[94:95], v[86:87]
	v_mov_b32_e32 v94, v48
	v_add_f32_e32 v87, 0, v87
	v_add_f32_e32 v100, v86, v87
	v_mov_b32_e32 v86, v49
	v_mov_b32_e32 v87, v53
	v_mov_b32_e32 v95, v52
	v_pk_add_f32 v[86:87], v[86:87], v[94:95]
	v_mov_b32_e32 v94, v50
	v_mov_b32_e32 v95, v54
	v_pk_add_f32 v[86:87], v[94:95], v[86:87]
	v_mov_b32_e32 v94, v51
	v_mov_b32_e32 v95, v55
	v_pk_add_f32 v[86:87], v[94:95], v[86:87]
	v_lshl_add_u64 v[64:65], v[64:65], 0, v[78:79]
	v_add_f32_e32 v87, v87, v100
	v_add_f32_e32 v86, v86, v87
	s_mov_b32 s0, 0x800000
	v_lshl_add_u64 v[74:75], v[74:75], 0, s[10:11]
	v_add_f32_dpp v86, v86, v86 row_ror:8 row_mask:0xf bank_mask:0xf bound_ctrl:1
	s_nop 1
	v_add_f32_dpp v86, v86, v86 row_ror:4 row_mask:0xf bank_mask:0xf bound_ctrl:1
	s_nop 1
	v_add_f32_dpp v86, v86, v86 row_ror:2 row_mask:0xf bank_mask:0xf bound_ctrl:1
	s_nop 1
	v_add_f32_dpp v86, v86, v86 row_ror:1 row_mask:0xf bank_mask:0xf bound_ctrl:1
	ds_bpermute_b32 v87, v96, v86
	s_waitcnt lgkmcnt(0)
	v_add_f32_e32 v86, v86, v87
	ds_bpermute_b32 v87, v97, v86
	s_waitcnt lgkmcnt(0)
	v_add_f32_e32 v86, v86, v87
	v_mul_f32_e32 v94, 0x3a800000, v86
	v_pk_add_f32 v[60:61], v[60:61], v[94:95] op_sel_hi:[1,0] neg_lo:[0,1] neg_hi:[0,1]
	v_pk_add_f32 v[56:57], v[56:57], v[94:95] op_sel_hi:[1,0] neg_lo:[0,1] neg_hi:[0,1]
	v_mov_b32_e32 v102, v61
	v_mov_b32_e32 v103, v57
	v_pk_add_f32 v[62:63], v[62:63], v[94:95] op_sel_hi:[1,0] neg_lo:[0,1] neg_hi:[0,1]
	v_pk_add_f32 v[58:59], v[58:59], v[94:95] op_sel_hi:[1,0] neg_lo:[0,1] neg_hi:[0,1]
	v_mov_b32_e32 v100, v60
	v_mov_b32_e32 v101, v56
	v_pk_mul_f32 v[102:103], v[102:103], v[102:103]
	v_pk_add_f32 v[52:53], v[52:53], v[94:95] op_sel_hi:[1,0] neg_lo:[0,1] neg_hi:[0,1]
	v_pk_fma_f32 v[100:101], v[100:101], v[100:101], v[102:103]
	v_mov_b32_e32 v102, v62
	v_mov_b32_e32 v103, v58
	v_pk_add_f32 v[48:49], v[48:49], v[94:95] op_sel_hi:[1,0] neg_lo:[0,1] neg_hi:[0,1]
	v_pk_fma_f32 v[100:101], v[102:103], v[102:103], v[100:101]
	v_mov_b32_e32 v102, v49
	v_mov_b32_e32 v103, v53
	v_pk_add_f32 v[54:55], v[54:55], v[94:95] op_sel_hi:[1,0] neg_lo:[0,1] neg_hi:[0,1]
	v_pk_add_f32 v[50:51], v[50:51], v[94:95] op_sel_hi:[1,0] neg_lo:[0,1] neg_hi:[0,1]
	v_mov_b32_e32 v94, v48
	v_mov_b32_e32 v95, v52
	v_pk_mul_f32 v[102:103], v[102:103], v[102:103]
	v_mov_b32_e32 v104, v63
	v_mov_b32_e32 v105, v59
	v_pk_fma_f32 v[94:95], v[94:95], v[94:95], v[102:103]
	v_mov_b32_e32 v102, v50
	v_mov_b32_e32 v103, v54
	v_pk_fma_f32 v[100:101], v[104:105], v[104:105], v[100:101]
	v_mov_b32_e32 v104, v51
	v_mov_b32_e32 v105, v55
	v_pk_fma_f32 v[94:95], v[102:103], v[102:103], v[94:95]
	v_add_f32_e32 v100, v100, v101
	v_pk_fma_f32 v[94:95], v[104:105], v[104:105], v[94:95]
	v_lshl_add_u64 v[86:87], v[70:71], 0, v[68:69]
	v_add_f32_e32 v95, v95, v100
	global_load_dwordx4 v[100:103], v[64:65], off
	global_load_dwordx4 v[104:107], v[90:91], off
	v_add_f32_e32 v94, v94, v95
	v_lshl_add_u64 v[70:71], v[70:71], 0, s[10:11]
	s_waitcnt vmcnt(0)
	v_pk_add_f32 v[90:91], v[106:107], 1.0 op_sel_hi:[1,0]
	v_add_f32_dpp v94, v94, v94 row_ror:8 row_mask:0xf bank_mask:0xf bound_ctrl:1
	s_nop 1
	v_add_f32_dpp v94, v94, v94 row_ror:4 row_mask:0xf bank_mask:0xf bound_ctrl:1
	s_nop 1
	v_add_f32_dpp v94, v94, v94 row_ror:2 row_mask:0xf bank_mask:0xf bound_ctrl:1
	s_nop 1
	v_add_f32_dpp v94, v94, v94 row_ror:1 row_mask:0xf bank_mask:0xf bound_ctrl:1
	ds_bpermute_b32 v95, v96, v94
	s_waitcnt lgkmcnt(0)
	v_add_f32_e32 v94, v94, v95
	ds_bpermute_b32 v95, v97, v94
	s_waitcnt lgkmcnt(0)
	v_add_f32_e32 v94, v94, v95
	v_fmamk_f32 v94, v94, 0x3a800000, v98
	v_cmp_gt_f32_e32 vcc, s0, v94
	v_mul_f32_e32 v95, 0x4b800000, v94
	s_nop 0
	v_cndmask_b32_e32 v94, v94, v95, vcc
	v_rsq_f32_e32 v94, v94
	s_nop 0
	v_mul_f32_e32 v95, 0x45800000, v94
	v_cndmask_b32_e32 v94, v94, v95, vcc
	v_pk_mul_f32 v[60:61], v[60:61], v[94:95] op_sel_hi:[1,0]
	v_pk_mul_f32 v[62:63], v[62:63], v[94:95] op_sel_hi:[1,0]
	v_pk_fma_f32 v[60:61], v[0:1], v[60:61], v[4:5]
	v_pk_fma_f32 v[62:63], v[2:3], v[62:63], v[6:7]
	v_pk_mul_f32 v[56:57], v[56:57], v[94:95] op_sel_hi:[1,0]
	v_pk_mul_f32 v[58:59], v[58:59], v[94:95] op_sel_hi:[1,0]
	v_pk_mul_f32 v[52:53], v[52:53], v[94:95] op_sel_hi:[1,0]
	v_pk_mul_f32 v[54:55], v[54:55], v[94:95] op_sel_hi:[1,0]
	v_pk_mul_f32 v[48:49], v[48:49], v[94:95] op_sel_hi:[1,0]
	v_pk_mul_f32 v[50:51], v[50:51], v[94:95] op_sel_hi:[1,0]
	v_pk_add_f32 v[94:95], v[104:105], 1.0 op_sel_hi:[1,0]
	v_pk_fma_f32 v[90:91], v[90:91], v[62:63], v[102:103]
	v_pk_fma_f32 v[94:95], v[94:95], v[60:61], v[100:101]
	v_cvt_pk_bf16_f32 v91, v90, v91
	v_cvt_pk_bf16_f32 v90, v94, v95
	global_load_dwordx4 v[100:103], v[64:65], off offset:1024
	s_nop 0
	global_load_dwordx4 v[92:95], v[92:93], off
	v_pk_fma_f32 v[56:57], v[8:9], v[56:57], v[12:13]
	v_pk_fma_f32 v[58:59], v[10:11], v[58:59], v[14:15]
	v_pk_fma_f32 v[52:53], v[16:17], v[52:53], v[20:21]
	v_pk_fma_f32 v[54:55], v[18:19], v[54:55], v[22:23]
	v_pk_fma_f32 v[48:49], v[24:25], v[48:49], v[28:29]
	v_pk_fma_f32 v[50:51], v[26:27], v[50:51], v[30:31]
	s_waitcnt vmcnt(0)
	v_pk_add_f32 v[92:93], v[92:93], 1.0 op_sel_hi:[1,0]
	v_pk_add_f32 v[94:95], v[94:95], 1.0 op_sel_hi:[1,0]
	v_pk_fma_f32 v[92:93], v[92:93], v[56:57], v[100:101]
	v_pk_fma_f32 v[94:95], v[94:95], v[58:59], v[102:103]
	v_cvt_pk_bf16_f32 v92, v92, v92
	v_cvt_pk_bf16_f32 v102, v93, v93
	v_cvt_pk_bf16_f32 v93, v94, v94
	v_cvt_pk_bf16_f32 v94, v95, v95
	v_perm_b32 v92, v102, v92, s7
	global_load_dwordx4 v[100:103], v[64:65], off offset:2048
	global_load_dwordx4 v[104:107], v[66:67], off
	v_perm_b32 v93, v94, v93, s7
	s_waitcnt vmcnt(0)
	v_pk_add_f32 v[66:67], v[106:107], 1.0 op_sel_hi:[1,0]
	v_pk_add_f32 v[94:95], v[104:105], 1.0 op_sel_hi:[1,0]
	v_pk_fma_f32 v[66:67], v[66:67], v[54:55], v[102:103]
	v_pk_fma_f32 v[94:95], v[94:95], v[52:53], v[100:101]
	v_cvt_pk_bf16_f32 v94, v94, v94
	v_cvt_pk_bf16_f32 v102, v95, v95
	v_cvt_pk_bf16_f32 v95, v66, v67
	v_perm_b32 v94, v102, v94, s7
	global_load_dwordx4 v[64:67], v[64:65], off offset:3072
	s_nop 0
	global_load_dwordx4 v[100:103], v[88:89], off
	s_nop 0
	global_store_dwordx4 v[86:87], v[60:63], off
	global_store_dwordx4 v[86:87], v[56:59], off offset:1024
	global_store_dwordx4 v[86:87], v[52:55], off offset:2048
	global_store_dwordx4 v[86:87], v[48:51], off offset:3072
	global_store_dwordx2 v[72:73], v[90:91], off
	global_store_dwordx2 v[72:73], v[92:93], off offset:512
	global_store_dwordx2 v[72:73], v[94:95], off offset:1024
	v_mov_b64_e32 v[60:61], v[32:33]
	v_mov_b64_e32 v[62:63], v[34:35]
	v_mov_b64_e32 v[56:57], v[36:37]
	v_mov_b64_e32 v[58:59], v[38:39]
	s_waitcnt vmcnt(7)
	v_pk_add_f32 v[52:53], v[102:103], 1.0 op_sel_hi:[1,0]
	v_pk_add_f32 v[54:55], v[100:101], 1.0 op_sel_hi:[1,0]
	v_pk_fma_f32 v[50:51], v[52:53], v[50:51], v[66:67]
	v_pk_fma_f32 v[48:49], v[54:55], v[48:49], v[64:65]
	v_cvt_pk_bf16_f32 v48, v48, v48
	v_cvt_pk_bf16_f32 v54, v49, v49
	v_cvt_pk_bf16_f32 v49, v50, v50
	v_cvt_pk_bf16_f32 v50, v51, v51
	v_perm_b32 v49, v50, v49, s7
	v_perm_b32 v48, v54, v48, s7
	global_store_dwordx2 v[72:73], v[48:49], off offset:1536
	v_lshl_add_u64 v[72:73], v[72:73], 0, s[8:9]
	v_mov_b32_e32 v64, v99
	v_mov_b64_e32 v[52:53], v[40:41]
	v_mov_b64_e32 v[54:55], v[42:43]
	v_mov_b64_e32 v[48:49], v[44:45]
	v_mov_b64_e32 v[50:51], v[46:47]
	s_andn2_b64 exec, exec, s[12:13]
	s_cbranch_execz .LBB0_1636

.LBB0_1692:
	s_mul_i32 s8, s6, 0x6000
	s_waitcnt vmcnt(6)
	s_add_i32 s10, s23, s8
	s_mul_i32 s98, s7, 0x6000
	v_lshl_add_u64 v[186:187], v[142:143], 0, s[0:1]
	v_lshl_add_u64 v[204:205], v[140:141], 0, s[0:1]
	s_add_i32 s99, s10, s24
	s_waitcnt lgkmcnt(0)
	s_barrier
	v_add_u32_e32 v184, s98, v144
	v_add_u32_e32 v185, s98, v146
	ds_read_b128 v[168:171], v185
	ds_read_b128 v[152:155], v184
	ds_read_b128 v[172:175], v185 offset:1024
	ds_read_b128 v[176:179], v185 offset:2048
	ds_read_b128 v[180:183], v185 offset:3072
	ds_read_b128 v[156:159], v184 offset:1024
	ds_read_b128 v[160:163], v184 offset:2048
	ds_read_b128 v[164:167], v184 offset:3072
	ds_read_b128 v[188:191], v184 offset:4096
	ds_read_b128 v[192:195], v184 offset:5120
	ds_read_b128 v[196:199], v184 offset:6144
	ds_read_b128 v[200:203], v184 offset:7168
	s_mov_b64 s[100:101], 0x80
	v_lshl_add_u64 v[206:207], v[186:187], 0, s[100:101]
	s_mov_b32 m0, s10
	s_waitcnt lgkmcnt(10)
	v_mfma_f32_16x16x32_bf16 v[84:87], v[152:155], v[168:171], v[84:87]
	global_load_lds_dwordx4 v[206:207], off
	s_waitcnt lgkmcnt(9)
	v_mfma_f32_16x16x32_bf16 v[76:79], v[152:155], v[172:175], v[76:79]
	s_mov_b64 s[100:101], 0x8080
	v_lshl_add_u64 v[206:207], v[186:187], 0, s[100:101]
	s_add_i32 m0, s10, 0x400
	s_waitcnt lgkmcnt(8)
	v_mfma_f32_16x16x32_bf16 v[68:71], v[152:155], v[176:179], v[68:71]
	global_load_lds_dwordx4 v[206:207], off
	s_waitcnt lgkmcnt(7)
	v_mfma_f32_16x16x32_bf16 v[60:63], v[152:155], v[180:183], v[60:63]
	s_mov_b64 s[100:101], 0x10080
	v_lshl_add_u64 v[206:207], v[186:187], 0, s[100:101]
	s_add_i32 m0, s10, 0x800
	s_waitcnt lgkmcnt(6)
	v_mfma_f32_16x16x32_bf16 v[52:55], v[156:159], v[168:171], v[52:55]
	global_load_lds_dwordx4 v[206:207], off
	v_mfma_f32_16x16x32_bf16 v[44:47], v[156:159], v[172:175], v[44:47]
	v_mfma_f32_16x16x32_bf16 v[36:39], v[156:159], v[176:179], v[36:39]
	s_mov_b64 s[100:101], 0x18080
	v_lshl_add_u64 v[206:207], v[186:187], 0, s[100:101]
	s_add_i32 m0, s10, 0xc00
	v_mfma_f32_16x16x32_bf16 v[32:35], v[156:159], v[180:183], v[32:35]
	global_load_lds_dwordx4 v[206:207], off
	s_waitcnt lgkmcnt(5)
	v_mfma_f32_16x16x32_bf16 v[28:31], v[160:163], v[168:171], v[28:31]
	s_mov_b64 s[100:101], 0x580080
	v_lshl_add_u64 v[206:207], v[204:205], 0, s[100:101]
	s_add_i32 m0, s99, 0x4000
	v_mfma_f32_16x16x32_bf16 v[24:27], v[160:163], v[172:175], v[24:27]
	global_load_lds_dwordx4 v[206:207], off
	v_mfma_f32_16x16x32_bf16 v[20:23], v[160:163], v[176:179], v[20:23]
	s_mov_b64 s[100:101], 0x588080
	v_lshl_add_u64 v[206:207], v[204:205], 0, s[100:101]
	s_add_i32 m0, s99, 0x4400
	v_mfma_f32_16x16x32_bf16 v[16:19], v[160:163], v[180:183], v[16:19]
	global_load_lds_dwordx4 v[206:207], off
	s_waitcnt lgkmcnt(4)
	v_mfma_f32_16x16x32_bf16 v[12:15], v[164:167], v[168:171], v[12:15]
	v_mfma_f32_16x16x32_bf16 v[8:11], v[164:167], v[172:175], v[8:11]
	v_mfma_f32_16x16x32_bf16 v[4:7], v[164:167], v[176:179], v[4:7]
	v_mfma_f32_16x16x32_bf16 v[0:3], v[164:167], v[180:183], v[0:3]
	s_waitcnt lgkmcnt(3)
	v_mfma_f32_16x16x32_bf16 v[124:127], v[188:191], v[168:171], v[124:127]
	v_mfma_f32_16x16x32_bf16 v[120:123], v[188:191], v[172:175], v[120:123]
	v_mfma_f32_16x16x32_bf16 v[116:119], v[188:191], v[176:179], v[116:119]
	v_mfma_f32_16x16x32_bf16 v[112:115], v[188:191], v[180:183], v[112:115]
	s_waitcnt lgkmcnt(2)
	v_mfma_f32_16x16x32_bf16 v[108:111], v[192:195], v[168:171], v[108:111]
	v_mfma_f32_16x16x32_bf16 v[104:107], v[192:195], v[172:175], v[104:107]
	v_mfma_f32_16x16x32_bf16 v[100:103], v[192:195], v[176:179], v[100:103]
	v_mfma_f32_16x16x32_bf16 v[96:99], v[192:195], v[180:183], v[96:99]
	s_waitcnt lgkmcnt(1)
	v_mfma_f32_16x16x32_bf16 v[92:95], v[196:199], v[168:171], v[92:95]
	v_mfma_f32_16x16x32_bf16 v[88:91], v[196:199], v[172:175], v[88:91]
	v_mfma_f32_16x16x32_bf16 v[80:83], v[196:199], v[176:179], v[80:83]
	v_mfma_f32_16x16x32_bf16 v[72:75], v[196:199], v[180:183], v[72:75]
	s_waitcnt lgkmcnt(0)
	v_mfma_f32_16x16x32_bf16 v[64:67], v[200:203], v[168:171], v[64:67]
	v_mfma_f32_16x16x32_bf16 v[56:59], v[200:203], v[172:175], v[56:59]
	v_mfma_f32_16x16x32_bf16 v[48:51], v[200:203], v[176:179], v[48:51]
	v_mfma_f32_16x16x32_bf16 v[40:43], v[200:203], v[180:183], v[40:43]
	s_add_i32 s8, s7, 1
	s_cmp_lg_u32 s7, 2
	s_cselect_b32 s7, s8, 0
	s_add_i32 s8, s6, 1
	s_cmp_lg_u32 s6, 2
	s_cselect_b32 s6, s8, 0
	s_add_u32 s0, s0, 64
	s_addc_u32 s1, s1, 0
	s_cmpk_eq_i32 s0, 0x780
	s_cbranch_scc0 .LBB0_1692
	s_waitcnt vmcnt(6)
	s_waitcnt lgkmcnt(0)
	s_barrier
	ds_read_b128 v[140:143], v144
	ds_read_b128 v[152:155], v144 offset:1024
	ds_read_b128 v[156:159], v144 offset:2048
	ds_read_b128 v[160:163], v144 offset:3072
	ds_read_b128 v[164:167], v146
	ds_read_b128 v[168:171], v146 offset:1024
	ds_read_b128 v[172:175], v146 offset:2048
	ds_read_b128 v[176:179], v146 offset:3072
	s_waitcnt lgkmcnt(0)
	s_nop 0
	v_mfma_f32_16x16x32_bf16 v[84:87], v[140:143], v[164:167], v[84:87]
	v_mfma_f32_16x16x32_bf16 v[76:79], v[140:143], v[168:171], v[76:79]
	v_mfma_f32_16x16x32_bf16 v[68:71], v[140:143], v[172:175], v[68:71]
	v_mfma_f32_16x16x32_bf16 v[60:63], v[140:143], v[176:179], v[60:63]
	v_mfma_f32_16x16x32_bf16 v[52:55], v[152:155], v[164:167], v[52:55]
	v_mfma_f32_16x16x32_bf16 v[44:47], v[152:155], v[168:171], v[44:47]
	v_mfma_f32_16x16x32_bf16 v[36:39], v[152:155], v[172:175], v[36:39]
	v_mfma_f32_16x16x32_bf16 v[32:35], v[152:155], v[176:179], v[32:35]
	v_mfma_f32_16x16x32_bf16 v[28:31], v[156:159], v[164:167], v[28:31]
	v_mfma_f32_16x16x32_bf16 v[24:27], v[156:159], v[168:171], v[24:27]
	v_mfma_f32_16x16x32_bf16 v[20:23], v[156:159], v[172:175], v[20:23]
	v_mfma_f32_16x16x32_bf16 v[16:19], v[156:159], v[176:179], v[16:19]
	v_mfma_f32_16x16x32_bf16 v[12:15], v[160:163], v[164:167], v[12:15]
	v_mfma_f32_16x16x32_bf16 v[8:11], v[160:163], v[168:171], v[8:11]
	v_mfma_f32_16x16x32_bf16 v[4:7], v[160:163], v[172:175], v[4:7]
	v_mfma_f32_16x16x32_bf16 v[0:3], v[160:163], v[176:179], v[0:3]
	ds_read_b128 v[140:143], v144 offset:4096
	ds_read_b128 v[152:155], v144 offset:5120
	ds_read_b128 v[156:159], v144 offset:6144
	ds_read_b128 v[160:163], v144 offset:7168
	s_waitcnt lgkmcnt(0)
	s_nop 0
	v_mfma_f32_16x16x32_bf16 v[180:183], v[140:143], v[164:167], v[124:127]
	v_mfma_f32_16x16x32_bf16 v[184:187], v[140:143], v[168:171], v[120:123]
	v_mfma_f32_16x16x32_bf16 v[188:191], v[140:143], v[172:175], v[116:119]
	v_mfma_f32_16x16x32_bf16 v[140:143], v[140:143], v[176:179], v[112:115]
	v_mfma_f32_16x16x32_bf16 v[192:195], v[152:155], v[164:167], v[108:111]
	v_mfma_f32_16x16x32_bf16 v[196:199], v[152:155], v[168:171], v[104:107]
	v_mfma_f32_16x16x32_bf16 v[200:203], v[152:155], v[172:175], v[100:103]
	v_mfma_f32_16x16x32_bf16 v[152:155], v[152:155], v[176:179], v[96:99]
	v_mfma_f32_16x16x32_bf16 v[204:207], v[156:159], v[164:167], v[92:95]
	v_mfma_f32_16x16x32_bf16 v[208:211], v[156:159], v[168:171], v[88:91]
	v_mfma_f32_16x16x32_bf16 v[212:215], v[156:159], v[172:175], v[80:83]
	v_mfma_f32_16x16x32_bf16 v[156:159], v[156:159], v[176:179], v[72:75]
	v_mfma_f32_16x16x32_bf16 v[164:167], v[160:163], v[164:167], v[64:67]
	v_mfma_f32_16x16x32_bf16 v[168:171], v[160:163], v[168:171], v[56:59]
	v_mfma_f32_16x16x32_bf16 v[172:175], v[160:163], v[172:175], v[48:51]
	v_mfma_f32_16x16x32_bf16 v[160:163], v[160:163], v[176:179], v[40:43]
	s_waitcnt vmcnt(0)
	s_waitcnt lgkmcnt(0)
	s_barrier
	ds_read_b128 v[40:43], v150
	ds_read_b128 v[48:51], v150 offset:1024
	ds_read_b128 v[56:59], v150 offset:2048
	ds_read_b128 v[176:179], v150 offset:3072
	ds_read_b128 v[216:219], v151
	ds_read_b128 v[220:223], v151 offset:1024
	ds_read_b128 v[228:231], v151 offset:2048
	ds_read_b128 v[232:235], v151 offset:3072
	s_waitcnt lgkmcnt(0)
	s_nop 0
	v_mfma_f32_16x16x32_bf16 v[116:119], v[40:43], v[220:223], v[76:79]
	v_mfma_f32_16x16x32_bf16 v[120:123], v[40:43], v[228:231], v[68:71]
	v_mfma_f32_16x16x32_bf16 v[64:67], v[176:179], v[216:219], v[12:15]
	v_mfma_f32_16x16x32_bf16 v[68:71], v[176:179], v[220:223], v[8:11]
	v_mfma_f32_16x16x32_bf16 v[72:75], v[176:179], v[228:231], v[4:7]
	v_mfma_f32_16x16x32_bf16 v[76:79], v[176:179], v[232:235], v[0:3]
	ds_read_b128 v[0:3], v150 offset:4096
	ds_read_b128 v[4:7], v150 offset:5120
	ds_read_b128 v[8:11], v150 offset:6144
	ds_read_b128 v[12:15], v150 offset:7168
	s_waitcnt lgkmcnt(0)
	v_mfma_f32_16x16x32_bf16 v[112:115], v[40:43], v[216:219], v[84:87]
	v_mfma_f32_16x16x32_bf16 v[124:127], v[40:43], v[232:235], v[60:63]
	v_mfma_f32_16x16x32_bf16 v[96:99], v[48:51], v[216:219], v[52:55]
	v_mfma_f32_16x16x32_bf16 v[100:103], v[48:51], v[220:223], v[44:47]
	v_mfma_f32_16x16x32_bf16 v[104:107], v[48:51], v[228:231], v[36:39]
	v_mfma_f32_16x16x32_bf16 v[108:111], v[48:51], v[232:235], v[32:35]
	v_mfma_f32_16x16x32_bf16 v[80:83], v[56:59], v[216:219], v[28:31]
	v_mfma_f32_16x16x32_bf16 v[84:87], v[56:59], v[220:223], v[24:27]
	v_mfma_f32_16x16x32_bf16 v[88:91], v[56:59], v[228:231], v[20:23]
	v_mfma_f32_16x16x32_bf16 v[92:95], v[56:59], v[232:235], v[16:19]
	v_mfma_f32_16x16x32_bf16 v[48:51], v[0:3], v[216:219], v[180:183]
	v_mfma_f32_16x16x32_bf16 v[52:55], v[0:3], v[220:223], v[184:187]
	v_mfma_f32_16x16x32_bf16 v[56:59], v[0:3], v[228:231], v[188:191]
	v_mfma_f32_16x16x32_bf16 v[60:63], v[0:3], v[232:235], v[140:143]
	v_mfma_f32_16x16x32_bf16 v[32:35], v[4:7], v[216:219], v[192:195]
	v_mfma_f32_16x16x32_bf16 v[36:39], v[4:7], v[220:223], v[196:199]
	v_mfma_f32_16x16x32_bf16 v[40:43], v[4:7], v[228:231], v[200:203]
	v_mfma_f32_16x16x32_bf16 v[44:47], v[4:7], v[232:235], v[152:155]
	v_mfma_f32_16x16x32_bf16 v[16:19], v[8:11], v[216:219], v[204:207]
	v_mfma_f32_16x16x32_bf16 v[20:23], v[8:11], v[220:223], v[208:211]
	v_mfma_f32_16x16x32_bf16 v[24:27], v[8:11], v[228:231], v[212:215]
	v_mfma_f32_16x16x32_bf16 v[28:31], v[8:11], v[232:235], v[156:159]
	v_mfma_f32_16x16x32_bf16 v[0:3], v[12:15], v[216:219], v[164:167]
	v_mfma_f32_16x16x32_bf16 v[4:7], v[12:15], v[220:223], v[168:171]
	v_mfma_f32_16x16x32_bf16 v[8:11], v[12:15], v[228:231], v[172:175]
	v_mfma_f32_16x16x32_bf16 v[12:15], v[12:15], v[232:235], v[160:163]
	v_add_u32_e32 v152, s4, v129
	v_or_b32_e32 v153, v152, v149
	v_or_b32_e32 v140, s5, v145
	v_mov_b32_e32 v155, v153
	v_mov_b64_e32 v[142:143], s[94:95]
	s_waitcnt lgkmcnt(0)
	s_barrier
	v_ashrrev_i32_e32 v141, 31, v140
	v_or_b32_e32 v154, v140, v128
	v_mad_i64_i32 v[142:143], s[0:1], v155, s39, v[142:143]
	v_lshl_add_u64 v[142:143], v[140:141], 1, v[142:143]
	v_lshl_add_u64 v[142:143], v[142:143], 0, v[130:131]
	v_cmp_gt_i32_e32 vcc, s40, v154
	s_and_saveexec_b64 s[0:1], vcc
	s_cbranch_execz .LBB0_1695
	v_cvt_pk_bf16_f32 v155, v112, v112
	global_store_short_d16_hi v[142:143], v155, off
.LBB0_1695:
	s_or_b64 exec, exec, s[0:1]
	v_or_b32_e32 v155, 16, v154
	v_cmp_gt_i32_e64 s[0:1], s40, v155
	s_and_saveexec_b64 s[4:5], s[0:1]
	s_cbranch_execz .LBB0_1697
	v_cvt_pk_bf16_f32 v155, v116, v116
	global_store_short_d16_hi v[142:143], v155, off offset:32
.LBB0_1697:
	s_or_b64 exec, exec, s[4:5]
	v_or_b32_e32 v155, 32, v154
	v_cmp_gt_i32_e64 s[4:5], s40, v155
	s_and_saveexec_b64 s[6:7], s[4:5]
	s_cbranch_execz .LBB0_1699
	v_cvt_pk_bf16_f32 v155, v120, v120
	global_store_short_d16_hi v[142:143], v155, off offset:64
.LBB0_1699:
	s_or_b64 exec, exec, s[6:7]
	v_or_b32_e32 v154, 48, v154
	v_cmp_gt_i32_e64 s[6:7], s40, v154
	s_and_saveexec_b64 s[8:9], s[6:7]
	s_cbranch_execz .LBB0_1701
	v_cvt_pk_bf16_f32 v154, v124, v124
	global_store_short_d16_hi v[142:143], v154, off offset:96

.LBB0_1705:
	v_cvt_pk_bf16_f32 v155, v125, v125
	global_store_short_d16_hi v[142:143], v155, off offset:96

.LBB0_1710:
	v_cvt_pk_bf16_f32 v156, v126, v126
	global_store_short_d16_hi v[142:143], v156, off offset:96

.LBB0_1715:
	v_cvt_pk_bf16_f32 v157, v127, v127
	global_store_short_d16_hi v[142:143], v157, off offset:96

.LBB0_1720:
	v_cvt_pk_bf16_f32 v158, v108, v108
	global_store_short_d16_hi v[142:143], v158, off offset:96

.LBB0_1725:
	v_cvt_pk_bf16_f32 v159, v109, v109
	global_store_short_d16_hi v[142:143], v159, off offset:96

.LBB0_1730:
	v_cvt_pk_bf16_f32 v160, v110, v110
	global_store_short_d16_hi v[142:143], v160, off offset:96

.LBB0_1735:
	v_cvt_pk_bf16_f32 v161, v111, v111
	global_store_short_d16_hi v[142:143], v161, off offset:96

.LBB0_1740:
	v_cvt_pk_bf16_f32 v162, v92, v92
	global_store_short_d16_hi v[142:143], v162, off offset:96

.LBB0_1745:
	v_cvt_pk_bf16_f32 v163, v93, v93
	global_store_short_d16_hi v[142:143], v163, off offset:96

.LBB0_1750:
	v_cvt_pk_bf16_f32 v164, v94, v94
	global_store_short_d16_hi v[142:143], v164, off offset:96

.LBB0_1755:
	v_cvt_pk_bf16_f32 v165, v95, v95
	global_store_short_d16_hi v[142:143], v165, off offset:96

.LBB0_1760:
	v_cvt_pk_bf16_f32 v166, v76, v76
	global_store_short_d16_hi v[142:143], v166, off offset:96

.LBB0_1765:
	v_cvt_pk_bf16_f32 v167, v77, v77
	global_store_short_d16_hi v[142:143], v167, off offset:96

.LBB0_1770:
	v_cvt_pk_bf16_f32 v168, v78, v78
	global_store_short_d16_hi v[142:143], v168, off offset:96

.LBB0_1775:
	v_cvt_pk_bf16_f32 v169, v79, v79
	global_store_short_d16_hi v[142:143], v169, off offset:96

.LBB0_1860:
	v_cvt_pk_bf16_f32 v155, v113, v113
	global_store_short_d16_hi v[142:143], v155, off
	s_or_b64 exec, exec, s[8:9]
	s_and_saveexec_b64 s[8:9], s[0:1]
	s_cbranch_execz .LBB0_1703
.LBB0_1861:
	v_cvt_pk_bf16_f32 v155, v117, v117
	global_store_short_d16_hi v[142:143], v155, off offset:32
	s_or_b64 exec, exec, s[8:9]
	s_and_saveexec_b64 s[8:9], s[4:5]
	s_cbranch_execz .LBB0_1704
.LBB0_1862:
	v_cvt_pk_bf16_f32 v155, v121, v121
	global_store_short_d16_hi v[142:143], v155, off offset:64
	s_or_b64 exec, exec, s[8:9]
	s_and_saveexec_b64 s[8:9], s[6:7]
	s_cbranch_execnz .LBB0_1705
	s_branch .LBB0_1706
.LBB0_1863:
	v_cvt_pk_bf16_f32 v156, v114, v114
	global_store_short_d16_hi v[142:143], v156, off
	s_or_b64 exec, exec, s[8:9]
	s_and_saveexec_b64 s[8:9], s[0:1]
	s_cbranch_execz .LBB0_1708
.LBB0_1864:
	v_cvt_pk_bf16_f32 v156, v118, v118
	global_store_short_d16_hi v[142:143], v156, off offset:32
	s_or_b64 exec, exec, s[8:9]
	s_and_saveexec_b64 s[8:9], s[4:5]
	s_cbranch_execz .LBB0_1709
.LBB0_1865:
	v_cvt_pk_bf16_f32 v156, v122, v122
	global_store_short_d16_hi v[142:143], v156, off offset:64
	s_or_b64 exec, exec, s[8:9]
	s_and_saveexec_b64 s[8:9], s[6:7]
	s_cbranch_execnz .LBB0_1710
	s_branch .LBB0_1711
.LBB0_1866:
	v_cvt_pk_bf16_f32 v157, v115, v115
	global_store_short_d16_hi v[142:143], v157, off
	s_or_b64 exec, exec, s[8:9]
	s_and_saveexec_b64 s[8:9], s[0:1]
	s_cbranch_execz .LBB0_1713
.LBB0_1867:
	v_cvt_pk_bf16_f32 v157, v119, v119
	global_store_short_d16_hi v[142:143], v157, off offset:32
	s_or_b64 exec, exec, s[8:9]
	s_and_saveexec_b64 s[8:9], s[4:5]
	s_cbranch_execz .LBB0_1714
.LBB0_1868:
	v_cvt_pk_bf16_f32 v157, v123, v123
	global_store_short_d16_hi v[142:143], v157, off offset:64
	s_or_b64 exec, exec, s[8:9]
	s_and_saveexec_b64 s[8:9], s[6:7]
	s_cbranch_execnz .LBB0_1715
	s_branch .LBB0_1716
.LBB0_1869:
	v_cvt_pk_bf16_f32 v158, v96, v96
	global_store_short_d16_hi v[142:143], v158, off
	s_or_b64 exec, exec, s[8:9]
	s_and_saveexec_b64 s[8:9], s[0:1]
	s_cbranch_execz .LBB0_1718
.LBB0_1870:
	v_cvt_pk_bf16_f32 v158, v100, v100
	global_store_short_d16_hi v[142:143], v158, off offset:32
	s_or_b64 exec, exec, s[8:9]
	s_and_saveexec_b64 s[8:9], s[4:5]
	s_cbranch_execz .LBB0_1719
.LBB0_1871:
	v_cvt_pk_bf16_f32 v158, v104, v104
	global_store_short_d16_hi v[142:143], v158, off offset:64
	s_or_b64 exec, exec, s[8:9]
	s_and_saveexec_b64 s[8:9], s[6:7]
	s_cbranch_execnz .LBB0_1720
	s_branch .LBB0_1721
.LBB0_1872:
	v_cvt_pk_bf16_f32 v159, v97, v97
	global_store_short_d16_hi v[142:143], v159, off
	s_or_b64 exec, exec, s[8:9]
	s_and_saveexec_b64 s[8:9], s[0:1]
	s_cbranch_execz .LBB0_1723
.LBB0_1873:
	v_cvt_pk_bf16_f32 v159, v101, v101
	global_store_short_d16_hi v[142:143], v159, off offset:32
	s_or_b64 exec, exec, s[8:9]
	s_and_saveexec_b64 s[8:9], s[4:5]
	s_cbranch_execz .LBB0_1724
.LBB0_1874:
	v_cvt_pk_bf16_f32 v159, v105, v105
	global_store_short_d16_hi v[142:143], v159, off offset:64
	s_or_b64 exec, exec, s[8:9]
	s_and_saveexec_b64 s[8:9], s[6:7]
	s_cbranch_execnz .LBB0_1725
	s_branch .LBB0_1726
.LBB0_1875:
	v_cvt_pk_bf16_f32 v160, v98, v98
	global_store_short_d16_hi v[142:143], v160, off
	s_or_b64 exec, exec, s[8:9]
	s_and_saveexec_b64 s[8:9], s[0:1]
	s_cbranch_execz .LBB0_1728
.LBB0_1876:
	v_cvt_pk_bf16_f32 v160, v102, v102
	global_store_short_d16_hi v[142:143], v160, off offset:32
	s_or_b64 exec, exec, s[8:9]
	s_and_saveexec_b64 s[8:9], s[4:5]
	s_cbranch_execz .LBB0_1729
.LBB0_1877:
	v_cvt_pk_bf16_f32 v160, v106, v106
	global_store_short_d16_hi v[142:143], v160, off offset:64
	s_or_b64 exec, exec, s[8:9]
	s_and_saveexec_b64 s[8:9], s[6:7]
	s_cbranch_execnz .LBB0_1730
	s_branch .LBB0_1731
.LBB0_1878:
	v_cvt_pk_bf16_f32 v161, v99, v99
	global_store_short_d16_hi v[142:143], v161, off
	s_or_b64 exec, exec, s[8:9]
	s_and_saveexec_b64 s[8:9], s[0:1]
	s_cbranch_execz .LBB0_1733
.LBB0_1879:
	v_cvt_pk_bf16_f32 v161, v103, v103
	global_store_short_d16_hi v[142:143], v161, off offset:32
	s_or_b64 exec, exec, s[8:9]
	s_and_saveexec_b64 s[8:9], s[4:5]
	s_cbranch_execz .LBB0_1734
.LBB0_1880:
	v_cvt_pk_bf16_f32 v161, v107, v107
	global_store_short_d16_hi v[142:143], v161, off offset:64
	s_or_b64 exec, exec, s[8:9]
	s_and_saveexec_b64 s[8:9], s[6:7]
	s_cbranch_execnz .LBB0_1735
	s_branch .LBB0_1736
.LBB0_1881:
	v_cvt_pk_bf16_f32 v162, v80, v80
	global_store_short_d16_hi v[142:143], v162, off
	s_or_b64 exec, exec, s[8:9]
	s_and_saveexec_b64 s[8:9], s[0:1]
	s_cbranch_execz .LBB0_1738
.LBB0_1882:
	v_cvt_pk_bf16_f32 v162, v84, v84
	global_store_short_d16_hi v[142:143], v162, off offset:32
	s_or_b64 exec, exec, s[8:9]
	s_and_saveexec_b64 s[8:9], s[4:5]
	s_cbranch_execz .LBB0_1739
.LBB0_1883:
	v_cvt_pk_bf16_f32 v162, v88, v88
	global_store_short_d16_hi v[142:143], v162, off offset:64
	s_or_b64 exec, exec, s[8:9]
	s_and_saveexec_b64 s[8:9], s[6:7]
	s_cbranch_execnz .LBB0_1740
	s_branch .LBB0_1741
.LBB0_1884:
	v_cvt_pk_bf16_f32 v163, v81, v81
	global_store_short_d16_hi v[142:143], v163, off
	s_or_b64 exec, exec, s[8:9]
	s_and_saveexec_b64 s[8:9], s[0:1]
	s_cbranch_execz .LBB0_1743
.LBB0_1885:
	v_cvt_pk_bf16_f32 v163, v85, v85
	global_store_short_d16_hi v[142:143], v163, off offset:32
	s_or_b64 exec, exec, s[8:9]
	s_and_saveexec_b64 s[8:9], s[4:5]
	s_cbranch_execz .LBB0_1744
.LBB0_1886:
	v_cvt_pk_bf16_f32 v163, v89, v89
	global_store_short_d16_hi v[142:143], v163, off offset:64
	s_or_b64 exec, exec, s[8:9]
	s_and_saveexec_b64 s[8:9], s[6:7]
	s_cbranch_execnz .LBB0_1745
	s_branch .LBB0_1746
.LBB0_1887:
	v_cvt_pk_bf16_f32 v164, v82, v82
	global_store_short_d16_hi v[142:143], v164, off
	s_or_b64 exec, exec, s[8:9]
	s_and_saveexec_b64 s[8:9], s[0:1]
	s_cbranch_execz .LBB0_1748
.LBB0_1888:
	v_cvt_pk_bf16_f32 v164, v86, v86
	global_store_short_d16_hi v[142:143], v164, off offset:32
	s_or_b64 exec, exec, s[8:9]
	s_and_saveexec_b64 s[8:9], s[4:5]
	s_cbranch_execz .LBB0_1749
.LBB0_1889:
	v_cvt_pk_bf16_f32 v164, v90, v90
	global_store_short_d16_hi v[142:143], v164, off offset:64
	s_or_b64 exec, exec, s[8:9]
	s_and_saveexec_b64 s[8:9], s[6:7]
	s_cbranch_execnz .LBB0_1750
	s_branch .LBB0_1751
.LBB0_1890:
	v_cvt_pk_bf16_f32 v165, v83, v83
	global_store_short_d16_hi v[142:143], v165, off
	s_or_b64 exec, exec, s[8:9]
	s_and_saveexec_b64 s[8:9], s[0:1]
	s_cbranch_execz .LBB0_1753
.LBB0_1891:
	v_cvt_pk_bf16_f32 v165, v87, v87
	global_store_short_d16_hi v[142:143], v165, off offset:32
	s_or_b64 exec, exec, s[8:9]
	s_and_saveexec_b64 s[8:9], s[4:5]
	s_cbranch_execz .LBB0_1754
.LBB0_1892:
	v_cvt_pk_bf16_f32 v165, v91, v91
	global_store_short_d16_hi v[142:143], v165, off offset:64
	s_or_b64 exec, exec, s[8:9]
	s_and_saveexec_b64 s[8:9], s[6:7]
	s_cbranch_execnz .LBB0_1755
	s_branch .LBB0_1756
.LBB0_1893:
	v_cvt_pk_bf16_f32 v166, v64, v64
	global_store_short_d16_hi v[142:143], v166, off
	s_or_b64 exec, exec, s[8:9]
	s_and_saveexec_b64 s[8:9], s[0:1]
	s_cbranch_execz .LBB0_1758
.LBB0_1894:
	v_cvt_pk_bf16_f32 v166, v68, v68
	global_store_short_d16_hi v[142:143], v166, off offset:32
	s_or_b64 exec, exec, s[8:9]
	s_and_saveexec_b64 s[8:9], s[4:5]
	s_cbranch_execz .LBB0_1759
.LBB0_1895:
	v_cvt_pk_bf16_f32 v166, v72, v72
	global_store_short_d16_hi v[142:143], v166, off offset:64
	s_or_b64 exec, exec, s[8:9]
	s_and_saveexec_b64 s[8:9], s[6:7]
	s_cbranch_execnz .LBB0_1760
	s_branch .LBB0_1761
.LBB0_1896:
	v_cvt_pk_bf16_f32 v167, v65, v65
	global_store_short_d16_hi v[142:143], v167, off
	s_or_b64 exec, exec, s[8:9]
	s_and_saveexec_b64 s[8:9], s[0:1]
	s_cbranch_execz .LBB0_1763
.LBB0_1897:
	v_cvt_pk_bf16_f32 v167, v69, v69
	global_store_short_d16_hi v[142:143], v167, off offset:32
	s_or_b64 exec, exec, s[8:9]
	s_and_saveexec_b64 s[8:9], s[4:5]
	s_cbranch_execz .LBB0_1764
.LBB0_1898:
	v_cvt_pk_bf16_f32 v167, v73, v73
	global_store_short_d16_hi v[142:143], v167, off offset:64
	s_or_b64 exec, exec, s[8:9]
	s_and_saveexec_b64 s[8:9], s[6:7]
	s_cbranch_execnz .LBB0_1765
	s_branch .LBB0_1766
.LBB0_1899:
	v_cvt_pk_bf16_f32 v168, v66, v66
	global_store_short_d16_hi v[142:143], v168, off
	s_or_b64 exec, exec, s[8:9]
	s_and_saveexec_b64 s[8:9], s[0:1]
	s_cbranch_execz .LBB0_1768
.LBB0_1900:
	v_cvt_pk_bf16_f32 v168, v70, v70
	global_store_short_d16_hi v[142:143], v168, off offset:32
	s_or_b64 exec, exec, s[8:9]
	s_and_saveexec_b64 s[8:9], s[4:5]
	s_cbranch_execz .LBB0_1769
.LBB0_1901:
	v_cvt_pk_bf16_f32 v168, v74, v74
	global_store_short_d16_hi v[142:143], v168, off offset:64
	s_or_b64 exec, exec, s[8:9]
	s_and_saveexec_b64 s[8:9], s[6:7]
	s_cbranch_execnz .LBB0_1770
	s_branch .LBB0_1771
.LBB0_1902:
	v_cvt_pk_bf16_f32 v169, v67, v67
	global_store_short_d16_hi v[142:143], v169, off
	s_or_b64 exec, exec, s[8:9]
	s_and_saveexec_b64 s[8:9], s[0:1]
	s_cbranch_execz .LBB0_1773
.LBB0_1903:
	v_cvt_pk_bf16_f32 v169, v71, v71
	global_store_short_d16_hi v[142:143], v169, off offset:32
	s_or_b64 exec, exec, s[8:9]
	s_and_saveexec_b64 s[8:9], s[4:5]
	s_cbranch_execz .LBB0_1774
.LBB0_1904:
	v_cvt_pk_bf16_f32 v169, v75, v75
	global_store_short_d16_hi v[142:143], v169, off offset:64
	s_or_b64 exec, exec, s[8:9]
	s_and_saveexec_b64 s[8:9], s[6:7]
	s_cbranch_execnz .LBB0_1775
	s_branch .LBB0_1776

.LBB0_2008:
	s_or_b64 exec, exec, s[6:7]
	v_cvt_pk_bf16_f32 v12, v12, v12
	v_lshrrev_b32_e32 v12, 16, v12
	v_cvt_pk_bf16_f32 v13, v13, v13
	v_and_or_b32 v14, v13, s2, v12
	v_cvt_pk_bf16_f32 v8, v8, v8
	v_lshrrev_b32_e32 v8, 16, v8
	v_cvt_pk_bf16_f32 v9, v9, v9
	v_and_or_b32 v13, v9, s2, v8
	v_cvt_pk_bf16_f32 v8, v28, v28
	v_lshrrev_b32_e32 v8, 16, v8
	v_cvt_pk_bf16_f32 v9, v29, v29
	v_and_or_b32 v12, v9, s2, v8
	v_cvt_pk_bf16_f32 v8, v10, v10
	v_add_u32_e32 v32, s10, v32
	s_movk_i32 s6, 0x4fff
	v_lshrrev_b32_e32 v8, 16, v8
	v_cvt_pk_bf16_f32 v9, v11, v11
	v_cmp_lt_i32_e32 vcc, s6, v32
	v_and_or_b32 v15, v9, s2, v8
	v_lshl_add_u64 v[8:9], v[26:27], 0, v[22:23]
	v_lshl_add_u64 v[24:25], v[24:25], 0, s[12:13]
	s_or_b64 s[16:17], vcc, s[16:17]
	v_lshl_add_u64 v[26:27], v[26:27], 0, s[14:15]
	global_store_dwordx4 v[8:9], v[12:15], off
	s_andn2_b64 exec, exec, s[16:17]
	s_cbranch_execz .LBB0_2064

.LBB0_2132:
	s_or_b64 exec, exec, s[34:35]
	v_readlane_b32 s56, v241, 17
	v_readlane_b32 s58, v241, 19
	v_readlane_b32 s59, v241, 20
	v_and_b32_sdwa v55, v52, v89 dst_sel:DWORD dst_unused:UNUSED_PAD src0_sel:WORD_1 src1_sel:DWORD
	v_add3_u32 v52, v52, v55, s52
	v_mov_b64_e32 v[50:51], s[58:59]
	v_mad_i64_i32 v[50:51], s[30:31], v54, s51, v[50:51]
	v_and_b32_sdwa v54, v53, v89 dst_sel:DWORD dst_unused:UNUSED_PAD src0_sel:WORD_1 src1_sel:DWORD
	v_add3_u32 v53, v53, v54, s52
	v_cvt_pk_bf16_f32 v49, v49, v49
	v_cvt_pk_bf16_f32 v48, v48, v48
	v_and_b32_e32 v49, 0xffff0000, v49
	v_and_b32_e32 v48, 0xffff0000, v48
	v_lshl_add_u64 v[50:51], v[78:79], 1, v[50:51]
	v_or_b32_sdwa v49, v49, v53 dst_sel:DWORD dst_unused:UNUSED_PAD src0_sel:DWORD src1_sel:WORD_1
	v_or_b32_sdwa v48, v48, v52 dst_sel:DWORD dst_unused:UNUSED_PAD src0_sel:DWORD src1_sel:WORD_1
	global_store_dwordx2 v[50:51], v[48:49], off
	v_or_b32_e32 v48, 16, v78
	v_cmp_lt_i32_e32 vcc, s50, v48
	v_readlane_b32 s57, v241, 18
	v_readlane_b32 s60, v241, 21
	v_readlane_b32 s61, v241, 22
	v_readlane_b32 s62, v241, 23
	v_readlane_b32 s63, v241, 24
	s_and_saveexec_b64 s[34:35], vcc
	s_xor_b64 s[34:35], exec, s[34:35]
	s_cbranch_execz .LBB0_2137
	s_cmpk_gt_u32 s53, 0x3ff
	s_cbranch_scc1 .LBB0_2136
	v_readlane_b32 s56, v241, 57
	v_mov_b32_e32 v70, v78
	v_readlane_b32 s68, v240, 5
	v_readlane_b32 s69, v240, 6
	v_readlane_b32 s57, v241, 58
	v_readlane_b32 s58, v241, 59
	v_lshl_add_u64 v[48:49], v[70:71], 2, s[68:69]
	global_load_dwordx4 v[50:53], v[48:49], off offset:64
	v_readlane_b32 s59, v241, 60
	v_readlane_b32 s60, v241, 61
	v_readlane_b32 s61, v241, 62
	v_readlane_b32 s62, v241, 63
	v_readlane_b32 s63, v240, 0
	v_readlane_b32 s64, v240, 1
	v_readlane_b32 s65, v240, 2
	v_readlane_b32 s66, v240, 3
	v_readlane_b32 s67, v240, 4
	v_readlane_b32 s70, v240, 7
	v_readlane_b32 s71, v240, 8
	s_mov_b64 s[30:31], -1
	s_waitcnt vmcnt(0)
	v_mov_b32_e32 v49, v52
	v_mov_b32_e32 v48, v50
	v_mov_b32_e32 v52, v51
	s_branch .LBB0_2137

.LBB0_2147:
	s_or_b64 exec, exec, s[34:35]
	v_readlane_b32 s56, v241, 17
	v_readlane_b32 s58, v241, 19
	v_readlane_b32 s59, v241, 20
	v_and_b32_sdwa v39, v36, v89 dst_sel:DWORD dst_unused:UNUSED_PAD src0_sel:WORD_1 src1_sel:DWORD
	v_add3_u32 v36, v36, v39, s52
	v_mov_b64_e32 v[34:35], s[58:59]
	v_mad_i64_i32 v[34:35], s[30:31], v38, s51, v[34:35]
	v_and_b32_sdwa v38, v37, v89 dst_sel:DWORD dst_unused:UNUSED_PAD src0_sel:WORD_1 src1_sel:DWORD
	v_add3_u32 v37, v37, v38, s52
	v_and_b32_sdwa v39, v32, v89 dst_sel:DWORD dst_unused:UNUSED_PAD src0_sel:WORD_1 src1_sel:DWORD
	v_cvt_pk_bf16_f32 v33, v33, v33
	v_add3_u32 v32, v32, v39, s52
	v_and_b32_e32 v33, 0xffff0000, v33
	v_and_b32_e32 v32, 0xffff0000, v32
	v_lshl_add_u64 v[34:35], v[78:79], 1, v[34:35]
	v_or_b32_sdwa v33, v33, v37 dst_sel:DWORD dst_unused:UNUSED_PAD src0_sel:DWORD src1_sel:WORD_1
	v_or_b32_sdwa v32, v32, v36 dst_sel:DWORD dst_unused:UNUSED_PAD src0_sel:DWORD src1_sel:WORD_1
	global_store_dwordx2 v[34:35], v[32:33], off offset:32
	v_or_b32_e32 v32, 32, v78
	v_cmp_lt_i32_e32 vcc, s50, v32
	v_readlane_b32 s57, v241, 18
	v_readlane_b32 s60, v241, 21
	v_readlane_b32 s61, v241, 22
	v_readlane_b32 s62, v241, 23
	v_readlane_b32 s63, v241, 24
	s_and_saveexec_b64 s[34:35], vcc
	s_xor_b64 s[34:35], exec, s[34:35]
	s_cbranch_execz .LBB0_2150
	s_cmpk_gt_u32 s53, 0x3ff
	s_cbranch_scc1 .LBB0_2173
	v_readlane_b32 s56, v241, 57
	v_mov_b32_e32 v70, v78
	v_readlane_b32 s68, v240, 5
	v_readlane_b32 s69, v240, 6
	v_readlane_b32 s57, v241, 58
	v_readlane_b32 s58, v241, 59
	v_lshl_add_u64 v[32:33], v[70:71], 2, s[68:69]
	global_load_dwordx4 v[34:37], v[32:33], off offset:128
	v_readlane_b32 s59, v241, 60
	v_readlane_b32 s60, v241, 61
	v_readlane_b32 s61, v241, 62
	v_readlane_b32 s62, v241, 63
	v_readlane_b32 s63, v240, 0
	v_readlane_b32 s64, v240, 1
	v_readlane_b32 s65, v240, 2
	v_readlane_b32 s66, v240, 3
	v_readlane_b32 s67, v240, 4
	v_readlane_b32 s70, v240, 7
	v_readlane_b32 s71, v240, 8
	s_mov_b64 s[30:31], -1
	s_waitcnt vmcnt(0)
	v_mov_b32_e32 v33, v36
	v_mov_b32_e32 v32, v34
	v_mov_b32_e32 v36, v35

.LBB0_2285:
	s_waitcnt vmcnt(0)
	ds_read2_b32 v[14:15], v13 offset1:4
	ds_read2_b32 v[16:17], v13 offset0:8 offset1:12
	v_add_u32_e32 v12, -2, v12
	s_add_i32 s15, s15, 4
	v_cmp_eq_u32_e32 vcc, 0, v12
	s_waitcnt lgkmcnt(1)
	v_and_b32_sdwa v3, v15, v116 dst_sel:DWORD dst_unused:UNUSED_PAD src0_sel:WORD_1 src1_sel:DWORD
	v_cvt_pk_bf16_f32 v20, v14, v14
	v_add_u32_e32 v14, s13, v10
	v_add3_u32 v3, v15, v3, s78
	v_add_u32_e32 v18, s13, v11
	v_mad_i64_i32 v[14:15], s[16:17], v14, s61, v[8:9]
	v_mad_i64_i32 v[18:19], s[16:17], v18, s61, v[8:9]
	global_store_short_d16_hi v[14:15], v20, off
	global_store_short_d16_hi v[18:19], v3, off
	s_waitcnt lgkmcnt(0)
	v_cvt_pk_bf16_f32 v18, v16, v16
	v_add_u32_e32 v14, s11, v10
	v_cvt_pk_bf16_f32 v3, v17, v17
	v_add_u32_e32 v16, s14, v11
	v_mad_i64_i32 v[14:15], s[16:17], v14, s61, v[8:9]
	v_mad_i64_i32 v[16:17], s[16:17], v16, s61, v[8:9]
	global_store_short_d16_hi v[14:15], v18, off
	global_store_short_d16_hi v[16:17], v3, off
	v_add_u32_e32 v11, 16, v11
	v_add_u32_e32 v10, 16, v10
	v_add_u32_e32 v13, 64, v13
	s_or_b64 s[8:9], vcc, s[8:9]
	v_mov_b32_e32 v3, s15
	s_andn2_b64 exec, exec, s[8:9]
	s_cbranch_execnz .LBB0_2285
	s_or_b64 exec, exec, s[8:9]
	v_lshlrev_b32_e32 v12, 2, v3
.LBB0_2287:
	s_or_b64 exec, exec, s[6:7]
	v_and_b32_e32 v3, 2, v7
	v_cmp_eq_u32_e32 vcc, 0, v3
	s_and_saveexec_b64 s[6:7], vcc
	s_cbranch_execz .LBB0_2289
	v_lshl_or_b32 v3, v1, 8, v4
	v_add_u32_e32 v4, v2, v12
	v_lshl_add_u32 v3, v4, 2, v3
	ds_read2_b32 v[12:13], v3 offset1:4
	v_add_u32_e32 v10, s13, v10
	v_add_u32_e32 v3, s13, v11
	v_mad_i64_i32 v[10:11], s[8:9], v10, s61, v[8:9]
	s_waitcnt lgkmcnt(0)
	v_cvt_pk_bf16_f32 v7, v12, v12
	v_cvt_pk_bf16_f32 v4, v13, v13
	v_mad_i64_i32 v[8:9], s[8:9], v3, s61, v[8:9]
	global_store_short_d16_hi v[10:11], v7, off
	global_store_short_d16_hi v[8:9], v4, off

.LBB0_2311:
	s_waitcnt vmcnt(0)
	ds_read2_b32 v[14:15], v12 offset1:4
	ds_read2_b32 v[16:17], v12 offset0:8 offset1:12
	v_add_u32_e32 v18, s13, v6
	v_ashrrev_i32_e32 v19, 31, v18
	v_lshlrev_b64 v[18:19], 11, v[18:19]
	s_waitcnt lgkmcnt(1)
	v_and_b32_sdwa v13, v14, v116 dst_sel:DWORD dst_unused:UNUSED_PAD src0_sel:WORD_1 src1_sel:DWORD
	v_and_b32_sdwa v3, v15, v116 dst_sel:DWORD dst_unused:UNUSED_PAD src0_sel:WORD_1 src1_sel:DWORD
	v_add3_u32 v13, v14, v13, s78
	v_add_u32_e32 v14, s13, v7
	v_add3_u32 v3, v15, v3, s78
	v_ashrrev_i32_e32 v15, 31, v14
	v_lshlrev_b64 v[14:15], 11, v[14:15]
	v_lshl_add_u64 v[18:19], v[4:5], 0, v[18:19]
	v_lshl_add_u64 v[14:15], v[4:5], 0, v[14:15]
	global_store_short_d16_hi v[18:19], v13, off
	global_store_short_d16_hi v[14:15], v3, off
	s_waitcnt lgkmcnt(0)
	v_and_b32_sdwa v13, v16, v116 dst_sel:DWORD dst_unused:UNUSED_PAD src0_sel:WORD_1 src1_sel:DWORD
	v_and_b32_sdwa v3, v17, v116 dst_sel:DWORD dst_unused:UNUSED_PAD src0_sel:WORD_1 src1_sel:DWORD
	v_add3_u32 v13, v16, v13, s78
	v_add_u32_e32 v16, s10, v6
	v_add3_u32 v3, v17, v3, s78
	v_add_u32_e32 v14, s11, v7
	v_ashrrev_i32_e32 v17, 31, v16
	v_ashrrev_i32_e32 v15, 31, v14
	v_lshlrev_b64 v[16:17], 11, v[16:17]
	v_lshlrev_b64 v[14:15], 11, v[14:15]
	v_lshl_add_u64 v[16:17], v[4:5], 0, v[16:17]
	v_lshl_add_u64 v[14:15], v[4:5], 0, v[14:15]
	global_store_short_d16_hi v[16:17], v13, off
	global_store_short_d16_hi v[14:15], v3, off
	ds_read2_b32 v[14:15], v12 offset0:16 offset1:20
	v_add_u32_e32 v16, s14, v6
	v_ashrrev_i32_e32 v17, 31, v16
	v_lshlrev_b64 v[16:17], 11, v[16:17]
	v_lshl_add_u64 v[16:17], v[4:5], 0, v[16:17]
	s_waitcnt lgkmcnt(0)
	v_and_b32_sdwa v13, v14, v116 dst_sel:DWORD dst_unused:UNUSED_PAD src0_sel:WORD_1 src1_sel:DWORD
	v_and_b32_sdwa v3, v15, v116 dst_sel:DWORD dst_unused:UNUSED_PAD src0_sel:WORD_1 src1_sel:DWORD
	v_add3_u32 v13, v14, v13, s78
	v_add_u32_e32 v14, s15, v7
	v_add3_u32 v3, v15, v3, s78
	v_ashrrev_i32_e32 v15, 31, v14
	v_lshlrev_b64 v[14:15], 11, v[14:15]
	v_lshl_add_u64 v[14:15], v[4:5], 0, v[14:15]
	global_store_short_d16_hi v[16:17], v13, off
	global_store_short_d16_hi v[14:15], v3, off
	ds_read2_b32 v[14:15], v12 offset0:24 offset1:28
	v_add_u32_e32 v16, s16, v6
	v_ashrrev_i32_e32 v17, 31, v16
	v_lshlrev_b64 v[16:17], 11, v[16:17]
	v_add_u32_e32 v11, -4, v11
	s_waitcnt lgkmcnt(0)
	v_cvt_pk_bf16_f32 v13, v14, v14
	v_add_u32_e32 v14, s17, v7
	v_cvt_pk_bf16_f32 v3, v15, v15
	v_ashrrev_i32_e32 v15, 31, v14
	v_lshlrev_b64 v[14:15], 11, v[14:15]
	v_lshl_add_u64 v[16:17], v[4:5], 0, v[16:17]
	s_add_i32 s18, s18, 8
	v_cmp_eq_u32_e32 vcc, 0, v11
	v_lshl_add_u64 v[14:15], v[4:5], 0, v[14:15]
	global_store_short_d16_hi v[16:17], v13, off
	global_store_short_d16_hi v[14:15], v3, off
	v_add_u32_e32 v7, 32, v7
	v_add_u32_e32 v6, 32, v6
	v_add_u32_e32 v12, 0x80, v12
	s_or_b64 s[8:9], vcc, s[8:9]
	v_mov_b32_e32 v13, s18
	s_andn2_b64 exec, exec, s[8:9]
	s_cbranch_execnz .LBB0_2311
	s_or_b64 exec, exec, s[8:9]

.LBB0_2331:
	ds_read2_b32 v[14:15], v13 offset1:4
	ds_read2_b32 v[16:17], v13 offset0:8 offset1:12
	v_add_u32_e32 v12, -4, v12
	s_add_i32 s19, s19, 8
	v_cmp_eq_u32_e32 vcc, 0, v12
	s_waitcnt lgkmcnt(1)
	v_and_b32_sdwa v3, v15, v116 dst_sel:DWORD dst_unused:UNUSED_PAD src0_sel:WORD_1 src1_sel:DWORD
	v_cvt_pk_bf16_f32 v20, v14, v14
	v_add_u32_e32 v14, s6, v9
	v_add_u32_e32 v18, s6, v8
	v_add3_u32 v3, v15, v3, s78
	v_ashrrev_i32_e32 v19, 31, v18
	v_ashrrev_i32_e32 v15, 31, v14
	v_lshlrev_b64 v[14:15], 11, v[14:15]
	v_lshlrev_b64 v[18:19], 11, v[18:19]
	v_lshl_add_u64 v[18:19], v[6:7], 0, v[18:19]
	v_lshl_add_u64 v[14:15], v[6:7], 0, v[14:15]
	global_store_short_d16_hi v[18:19], v20, off
	global_store_short_d16_hi v[14:15], v3, off
	s_waitcnt lgkmcnt(0)
	v_and_b32_sdwa v3, v17, v116 dst_sel:DWORD dst_unused:UNUSED_PAD src0_sel:WORD_1 src1_sel:DWORD
	v_cvt_pk_bf16_f32 v18, v16, v16
	v_add_u32_e32 v16, s7, v8
	v_add3_u32 v3, v17, v3, s78
	v_add_u32_e32 v14, s14, v9
	v_ashrrev_i32_e32 v17, 31, v16
	v_ashrrev_i32_e32 v15, 31, v14
	v_lshlrev_b64 v[16:17], 11, v[16:17]
	v_lshlrev_b64 v[14:15], 11, v[14:15]
	v_lshl_add_u64 v[16:17], v[6:7], 0, v[16:17]
	v_lshl_add_u64 v[14:15], v[6:7], 0, v[14:15]
	global_store_short_d16_hi v[16:17], v18, off
	global_store_short_d16_hi v[14:15], v3, off
	ds_read2_b32 v[14:15], v13 offset0:16 offset1:20
	s_or_b64 s[12:13], vcc, s[12:13]
	s_waitcnt lgkmcnt(0)
	v_cvt_pk_bf16_f32 v18, v14, v14
	v_add_u32_e32 v16, s15, v8
	v_and_b32_sdwa v3, v15, v116 dst_sel:DWORD dst_unused:UNUSED_PAD src0_sel:WORD_1 src1_sel:DWORD
	v_add_u32_e32 v14, s16, v9
	v_ashrrev_i32_e32 v17, 31, v16
	v_add3_u32 v3, v15, v3, s78
	v_ashrrev_i32_e32 v15, 31, v14
	v_lshlrev_b64 v[16:17], 11, v[16:17]
	v_lshlrev_b64 v[14:15], 11, v[14:15]
	v_lshl_add_u64 v[16:17], v[6:7], 0, v[16:17]
	v_lshl_add_u64 v[14:15], v[6:7], 0, v[14:15]
	global_store_short_d16_hi v[16:17], v18, off
	global_store_short_d16_hi v[14:15], v3, off
	ds_read2_b32 v[14:15], v13 offset0:24 offset1:28
	v_add_u32_e32 v13, 0x80, v13
	s_waitcnt lgkmcnt(0)
	v_cvt_pk_bf16_f32 v18, v14, v14
	v_add_u32_e32 v14, s18, v9
	v_add_u32_e32 v16, s17, v8
	v_cvt_pk_bf16_f32 v3, v15, v15
	v_ashrrev_i32_e32 v17, 31, v16
	v_ashrrev_i32_e32 v15, 31, v14
	v_lshlrev_b64 v[14:15], 11, v[14:15]
	v_lshlrev_b64 v[16:17], 11, v[16:17]
	v_lshl_add_u64 v[16:17], v[6:7], 0, v[16:17]
	v_lshl_add_u64 v[14:15], v[6:7], 0, v[14:15]
	global_store_short_d16_hi v[16:17], v18, off
	global_store_short_d16_hi v[14:15], v3, off
	v_add_u32_e32 v9, 32, v9
	v_add_u32_e32 v8, 32, v8
	v_mov_b32_e32 v14, s19
	s_andn2_b64 exec, exec, s[12:13]
	s_cbranch_execnz .LBB0_2331
	s_or_b64 exec, exec, s[12:13]

.LBB0_2347:
	s_waitcnt vmcnt(0)
	v_ashrrev_i32_e32 v64, 2, v1
	s_lshl_b32 s18, s6, 6
	v_and_b32_e32 v47, -16, v64
	v_and_b32_e32 v45, 15, v1
	v_add_u32_e32 v37, s18, v47
	v_or_b32_e32 v35, v37, v45
	v_add_u32_e32 v4, s16, v35
	v_mov_b64_e32 v[2:3], s[94:95]
	s_lshl_b32 s8, s10, 6
	v_bfe_u32 v36, v1, 4, 2
	v_mad_i64_i32 v[2:3], s[4:5], v4, s86, v[2:3]
	s_ashr_i32 s9, s8, 31
	v_lshl_add_u64 v[16:17], s[8:9], 1, v[2:3]
	v_lshlrev_b32_e32 v24, 4, v36
	v_mov_b32_e32 v25, v0
	v_lshl_add_u64 v[20:21], v[16:17], 0, v[24:25]
	global_load_dwordx4 v[2:5], v[20:21], off
	v_cndmask_b32_e64 v6, 0, 1, s[12:13]
	s_mov_b64 s[14:15], -1
	v_cmp_gt_u32_e64 s[4:5], 2, v36
	v_cmp_ne_u32_e64 s[6:7], 1, v6
	s_andn2_b64 vcc, exec, s[12:13]
	s_waitcnt vmcnt(0)
	v_and_b32_e32 v31, 0xffff0000, v2
	v_lshlrev_b32_e32 v30, 16, v2
	v_and_b32_e32 v29, 0xffff0000, v3
	v_lshlrev_b32_e32 v28, 16, v3
	v_and_b32_e32 v27, 0xffff0000, v4
	v_lshlrev_b32_e32 v26, 16, v4
	v_lshlrev_b32_e32 v22, 16, v5
	v_and_b32_e32 v2, 0xffff0000, v5
	s_cbranch_vccnz .LBB0_2349
	s_mov_b32 s12, 0x3e000000
	v_pk_mul_f32 v[4:5], v[30:31], s[12:13] op_sel_hi:[1,0]
	s_mov_b64 s[14:15], 0
	v_and_b32_sdwa v6, v4, v116 dst_sel:DWORD dst_unused:UNUSED_PAD src0_sel:WORD_1 src1_sel:DWORD
	v_add3_u32 v7, v4, v6, s78
	v_cvt_pk_bf16_f32 v3, v5, v5
	v_pk_mul_f32 v[4:5], v[28:29], s[12:13] op_sel_hi:[1,0]
	s_nop 0
	v_and_b32_sdwa v6, v5, v116 dst_sel:DWORD dst_unused:UNUSED_PAD src0_sel:WORD_1 src1_sel:DWORD
	v_cvt_pk_bf16_f32 v8, v4, v4
	v_add3_u32 v9, v5, v6, s78
	v_pk_mul_f32 v[4:5], v[26:27], s[12:13] op_sel_hi:[1,0]
	s_nop 0
	v_cvt_pk_bf16_f32 v6, v4, v5
	v_perm_b32 v4, v3, v7, s3
	v_mul_f32_e32 v3, 0x3e000000, v22
	v_bfe_u32 v7, v3, 16, 1
	v_add3_u32 v3, v3, v7, s78
	v_perm_b32 v5, v9, v8, s3
	v_alignbit_b32 v7, 0, v3, 16
.LBB0_2349:
	v_lshlrev_b32_e32 v3, 3, v36
	v_xor_b32_e32 v3, 16, v3
	v_and_b32_e32 v25, 16, v1
	s_andn2_b64 vcc, exec, s[14:15]
	v_lshlrev_b32_e32 v18, 1, v3
	s_cbranch_vccnz .LBB0_2351
	v_ashrrev_i32_e32 v3, 1, v37
	s_movk_i32 s11, 0xffe0
	v_and_or_b32 v4, v3, s11, v25
	v_readlane_b32 s36, v241, 1
	v_mov_b32_e32 v19, v0
	v_ashrrev_i32_e32 v5, 31, v4
	v_readlane_b32 s48, v241, 13
	v_readlane_b32 s49, v241, 14
	v_lshl_add_u64 v[12:13], v[16:17], 0, v[18:19]
	v_mov_b32_e32 v55, v31
	v_lshl_add_u64 v[8:9], v[4:5], 2, s[48:49]
	global_load_dwordx4 v[4:7], v[8:9], off offset:32
	global_load_dwordx4 v[38:41], v[8:9], off offset:16
	global_load_dwordx4 v[48:51], v[8:9], off
	s_nop 0
	global_load_dwordx4 v[8:11], v[8:9], off offset:48
	s_mov_b32 s12, 0x3e000000
	global_load_dwordx4 v[12:15], v[12:13], off
	v_readlane_b32 s37, v241, 2
	v_readlane_b32 s38, v241, 3
	v_readlane_b32 s39, v241, 4
	v_readlane_b32 s40, v241, 5
	v_readlane_b32 s41, v241, 6
	v_readlane_b32 s42, v241, 7
	v_readlane_b32 s43, v241, 8
	v_readlane_b32 s44, v241, 9
	v_readlane_b32 s45, v241, 10
	v_readlane_b32 s46, v241, 11
	v_readlane_b32 s47, v241, 12
	v_readlane_b32 s50, v241, 15
	v_readlane_b32 s51, v241, 16
	s_waitcnt vmcnt(4)
	v_mov_b32_e32 v52, v5
	s_waitcnt vmcnt(3)
	v_mov_b32_e32 v42, v39
	s_waitcnt vmcnt(2)
	v_mov_b32_e32 v32, v49
	v_mov_b32_e32 v49, v51
	v_mov_b32_e32 v33, v50
	s_waitcnt vmcnt(0)
	v_lshlrev_b32_e32 v3, 16, v12
	v_cndmask_b32_e64 v54, v3, -v3, s[4:5]
	v_and_b32_e32 v3, 0xffff0000, v12
	v_cndmask_b32_e64 v3, v3, -v3, s[4:5]
	v_mov_b32_e32 v31, v3
	v_pk_mul_f32 v[30:31], v[48:49], v[30:31]
	v_mov_b32_e32 v39, v41
	v_pk_fma_f32 v[30:31], v[32:33], v[54:55], v[30:31]
	v_mov_b32_e32 v43, v40
	v_pk_mul_f32 v[30:31], v[30:31], s[12:13] op_sel_hi:[1,0]
	v_mov_b32_e32 v53, v6
	v_lshlrev_b32_e32 v5, 16, v13
	v_cndmask_b32_e64 v12, v5, -v5, s[4:5]
	v_and_b32_e32 v5, 0xffff0000, v13
	v_cndmask_b32_e64 v5, v5, -v5, s[4:5]
	v_mov_b32_e32 v13, v29
	v_mov_b32_e32 v29, v5
	v_pk_mul_f32 v[28:29], v[38:39], v[28:29]
	v_pk_fma_f32 v[12:13], v[12:13], v[42:43], v[28:29]
	v_pk_mul_f32 v[12:13], v[12:13], s[12:13] op_sel_hi:[1,0]
	s_nop 0
	v_cvt_pk_bf16_f32 v28, v13, v13
	v_lshlrev_b32_e32 v5, 16, v14
	v_cvt_pk_bf16_f32 v23, v12, v12
	v_cndmask_b32_e64 v12, v5, -v5, s[4:5]
	v_and_b32_e32 v5, 0xffff0000, v14
	v_cndmask_b32_e64 v6, v5, -v5, s[4:5]
	v_mov_b32_e32 v13, v27
	v_mov_b32_e32 v5, v7
	v_mov_b32_e32 v27, v6
	v_pk_mul_f32 v[4:5], v[4:5], v[26:27]
	s_nop 0
	v_pk_fma_f32 v[4:5], v[12:13], v[52:53], v[4:5]
	s_nop 0
	v_pk_mul_f32 v[4:5], v[4:5], s[12:13] op_sel_hi:[1,0]
	s_nop 0
	v_cvt_pk_bf16_f32 v6, v4, v5
	v_cvt_pk_bf16_f32 v4, v30, v31
	v_lshlrev_b32_e32 v3, 16, v15
	v_perm_b32 v5, v28, v23, s3
	v_cndmask_b32_e64 v23, v3, -v3, s[4:5]
	v_pk_mul_f32 v[8:9], v[8:9], v[22:23]
	s_nop 0
	v_add_f32_e32 v3, v8, v9
	v_mul_f32_e32 v3, 0x3e000000, v3
	v_bfe_u32 v7, v3, 16, 1
	v_add3_u32 v3, v3, v7, s78
	v_alignbit_b32 v7, 0, v3, 16
	v_and_b32_e32 v3, 0xffff0000, v15
	v_cndmask_b32_e64 v3, v3, -v3, s[4:5]
	v_pk_mul_f32 v[2:3], v[10:11], v[2:3]
	s_nop 0
	v_add_f32_e32 v2, v2, v3
.LBB0_2351:
	global_load_dwordx4 v[8:11], v[20:21], off offset:64
	s_mov_b64 s[12:13], -1
	s_and_b64 vcc, exec, s[6:7]
	s_waitcnt vmcnt(0)
	v_and_b32_e32 v29, 0xffff0000, v8
	v_lshlrev_b32_e32 v28, 16, v8
	v_and_b32_e32 v31, 0xffff0000, v9
	v_lshlrev_b32_e32 v30, 16, v9
	v_and_b32_e32 v33, 0xffff0000, v10
	v_lshlrev_b32_e32 v32, 16, v10
	v_lshlrev_b32_e32 v34, 16, v11
	v_and_b32_e32 v26, 0xffff0000, v11
	s_cbranch_vccnz .LBB0_2353
	s_mov_b32 s6, 0x3e000000
	v_pk_mul_f32 v[8:9], v[28:29], s[6:7] op_sel_hi:[1,0]
	s_mov_b64 s[12:13], 0
	v_and_b32_sdwa v10, v8, v116 dst_sel:DWORD dst_unused:UNUSED_PAD src0_sel:WORD_1 src1_sel:DWORD
	v_add3_u32 v11, v8, v10, s78
	v_cvt_pk_bf16_f32 v3, v9, v9
	v_pk_mul_f32 v[8:9], v[30:31], s[6:7] op_sel_hi:[1,0]
	s_nop 0
	v_and_b32_sdwa v10, v9, v116 dst_sel:DWORD dst_unused:UNUSED_PAD src0_sel:WORD_1 src1_sel:DWORD
	v_cvt_pk_bf16_f32 v12, v8, v8
	v_add3_u32 v13, v9, v10, s78
	v_pk_mul_f32 v[8:9], v[32:33], s[6:7] op_sel_hi:[1,0]
	s_nop 0
	v_cvt_pk_bf16_f32 v10, v8, v9
	v_perm_b32 v8, v3, v11, s3
	v_mul_f32_e32 v3, 0x3e000000, v34
	v_bfe_u32 v11, v3, 16, 1
	v_add3_u32 v3, v3, v11, s78
	v_perm_b32 v9, v13, v12, s3
	v_alignbit_b32 v11, 0, v3, 16
.LBB0_2353:
	s_mov_b32 s20, 4
	s_andn2_b64 vcc, exec, s[12:13]
	s_mov_b32 s19, 4
	s_cbranch_vccnz .LBB0_2355
	v_mov_b32_e32 v19, v0
	v_lshl_add_u64 v[8:9], v[16:17], 0, v[18:19]
	v_lshlrev_b32_e32 v3, 5, v35
	s_movk_i32 s6, 0x7e0
	global_load_dwordx4 v[38:41], v[8:9], off offset:64
	v_and_or_b32 v3, v3, s6, v25
	v_readlane_b32 s36, v241, 1
	v_lshlrev_b32_e32 v3, 2, v3
	v_readlane_b32 s48, v241, 13
	v_readlane_b32 s49, v241, 14
	s_nop 4
	global_load_dwordx4 v[16:19], v3, s[48:49]
	global_load_dwordx4 v[12:15], v3, s[48:49] offset:16
	global_load_dwordx4 v[8:11], v3, s[48:49] offset:32
	global_load_dwordx4 v[20:23], v3, s[48:49] offset:48
	v_mov_b32_e32 v43, v29
	v_mov_b32_e32 v49, v31
	v_mov_b32_e32 v51, v33
	s_mov_b32 s19, 5
	s_mov_b32 s20, 9
	v_readlane_b32 s37, v241, 2
	v_readlane_b32 s38, v241, 3
	v_readlane_b32 s39, v241, 4
	v_readlane_b32 s40, v241, 5
	v_readlane_b32 s41, v241, 6
	v_readlane_b32 s42, v241, 7
	v_readlane_b32 s43, v241, 8
	v_readlane_b32 s44, v241, 9
	v_readlane_b32 s45, v241, 10
	v_readlane_b32 s46, v241, 11
	v_readlane_b32 s47, v241, 12
	v_readlane_b32 s50, v241, 15
	v_readlane_b32 s51, v241, 16
	s_waitcnt vmcnt(4)
	v_lshlrev_b32_e32 v3, 16, v38
	v_and_b32_e32 v25, 0xffff0000, v38
	v_and_b32_e32 v29, 0xffff0000, v39
	v_lshlrev_b32_e32 v31, 16, v40
	v_and_b32_e32 v33, 0xffff0000, v40
	v_lshlrev_b32_e32 v35, 16, v41
	s_waitcnt vmcnt(1)
	v_mov_b32_e32 v53, v10
	v_cndmask_b32_e64 v42, v3, -v3, s[4:5]
	v_cndmask_b32_e64 v3, v25, -v25, s[4:5]
	v_cndmask_b32_e64 v10, v29, -v29, s[4:5]
	v_lshlrev_b32_e32 v27, 16, v39
	v_mov_b32_e32 v38, v17
	v_mov_b32_e32 v40, v13
	v_mov_b32_e32 v52, v9
	v_mov_b32_e32 v17, v19
	v_mov_b32_e32 v13, v15
	v_cndmask_b32_e64 v50, v31, -v31, s[4:5]
	v_cndmask_b32_e64 v33, v33, -v33, s[4:5]
	v_mov_b32_e32 v9, v11
	v_cndmask_b32_e64 v35, v35, -v35, s[4:5]
	v_mov_b32_e32 v29, v3
	v_mov_b32_e32 v31, v10
	v_and_b32_e32 v44, 0xffff0000, v41
	v_mov_b32_e32 v39, v18
	v_mov_b32_e32 v41, v14
	v_cndmask_b32_e64 v48, v27, -v27, s[4:5]
	s_waitcnt vmcnt(0)
	v_pk_mul_f32 v[10:11], v[20:21], v[34:35]
	v_pk_mul_f32 v[16:17], v[16:17], v[28:29]
	v_pk_mul_f32 v[12:13], v[12:13], v[30:31]
	v_pk_mul_f32 v[8:9], v[8:9], v[32:33]
	v_cndmask_b32_e64 v27, v44, -v44, s[4:5]
	v_add_f32_e32 v3, v10, v11
	v_pk_fma_f32 v[10:11], v[38:39], v[42:43], v[16:17]
	v_pk_fma_f32 v[12:13], v[48:49], v[40:41], v[12:13]
	v_pk_fma_f32 v[8:9], v[50:51], v[52:53], v[8:9]
	s_mov_b32 s4, 0x3e000000
	v_pk_mul_f32 v[14:15], v[22:23], v[26:27]
	v_mul_f32_e32 v3, 0x3e000000, v3
	v_pk_mul_f32 v[10:11], v[10:11], s[4:5] op_sel_hi:[1,0]
	v_pk_mul_f32 v[12:13], v[12:13], s[4:5] op_sel_hi:[1,0]
	v_pk_mul_f32 v[8:9], v[8:9], s[4:5] op_sel_hi:[1,0]
	v_add_f32_e32 v26, v14, v15
	v_bfe_u32 v14, v3, 16, 1
	v_and_b32_sdwa v17, v13, v116 dst_sel:DWORD dst_unused:UNUSED_PAD src0_sel:WORD_1 src1_sel:DWORD
	v_add3_u32 v3, v3, v14, s78
	v_cvt_pk_bf16_f32 v14, v10, v10
	v_cvt_pk_bf16_f32 v15, v11, v11
	v_cvt_pk_bf16_f32 v12, v12, v12
	v_add3_u32 v13, v13, v17, s78
	v_alignbit_b32 v11, 0, v3, 16
	v_cvt_pk_bf16_f32 v10, v8, v9
	v_perm_b32 v9, v13, v12, s3
	v_perm_b32 v8, v15, v14, s3

.LBB0_2375:
	s_waitcnt vmcnt(0)
	v_cvt_pk_bf16_f32 v31, v30, v31
	v_cvt_pk_bf16_f32 v30, v28, v29
	v_cvt_pk_bf16_f32 v29, v38, v39
	v_cvt_pk_bf16_f32 v28, v36, v37
	ds_write_b128 v76, v[28:31] offset:16
	s_waitcnt lgkmcnt(0)
	s_barrier
	ds_read_b128 v[28:31], v77
	ds_read_b128 v[32:35], v77 offset:64
	s_waitcnt lgkmcnt(1)
	v_mfma_f32_16x16x32_bf16 v[28:31], v[4:7], v[28:31], 0
	s_and_b64 s[6:7], s[0:1], s[12:13]
	s_andn2_b64 vcc, exec, s[6:7]
	s_waitcnt lgkmcnt(0)
	v_mfma_f32_16x16x32_bf16 v[28:31], v[8:11], v[32:35], v[28:31]
	ds_read_b128 v[32:35], v77 offset:2304
	ds_read_b128 v[36:39], v77 offset:2368
	s_waitcnt lgkmcnt(1)
	v_mfma_f32_16x16x32_bf16 v[32:35], v[4:7], v[32:35], 0
	s_waitcnt lgkmcnt(0)
	v_mfma_f32_16x16x32_bf16 v[32:35], v[8:11], v[36:39], v[32:35]
	ds_read_b128 v[36:39], v77 offset:4608
	ds_read_b128 v[40:43], v77 offset:4672
	s_waitcnt lgkmcnt(1)
	v_mfma_f32_16x16x32_bf16 v[36:39], v[4:7], v[36:39], 0
	s_waitcnt lgkmcnt(0)
	v_mfma_f32_16x16x32_bf16 v[36:39], v[8:11], v[40:43], v[36:39]
	ds_read_b128 v[40:43], v77 offset:6912
	ds_read_b128 v[56:59], v77 offset:6976
	s_waitcnt lgkmcnt(1)
	v_mfma_f32_16x16x32_bf16 v[40:43], v[4:7], v[40:43], 0
	s_waitcnt lgkmcnt(0)
	v_mfma_f32_16x16x32_bf16 v[40:43], v[8:11], v[56:59], v[40:43]
	s_cbranch_vccnz .LBB0_2356
	v_add_u32_e32 v56, s25, v45
	v_sub_u32_e32 v57, v69, v56
	v_sub_u32_e32 v58, 0, v57
	v_max_i32_e32 v58, v57, v58
	s_movk_i32 s6, 0x80
	v_cmp_lt_u32_e32 vcc, s6, v58
	v_add_u32_e32 v58, 1, v57
	v_not_b32_e32 v59, v57
	v_max_i32_e32 v58, v58, v59
	v_cndmask_b32_e32 v28, v28, v118, vcc
	v_cmp_gt_u32_e32 vcc, s70, v58
	v_add_u32_e32 v58, 2, v57
	v_sub_u32_e32 v59, -2, v57
	v_max_i32_e32 v58, v58, v59
	v_cndmask_b32_e32 v29, v118, v29, vcc
	v_cmp_gt_u32_e32 vcc, s70, v58
	v_add_u32_e32 v58, 3, v57
	v_sub_u32_e32 v57, -3, v57
	v_max_i32_e32 v57, v58, v57
	v_cndmask_b32_e32 v30, v118, v30, vcc
	v_cmp_gt_u32_e32 vcc, s70, v57
	v_sub_u32_e32 v57, v70, v56
	v_sub_u32_e32 v58, 0, v57
	v_max_i32_e32 v58, v57, v58
	v_cndmask_b32_e32 v31, v118, v31, vcc
	v_cmp_gt_u32_e32 vcc, s70, v58
	v_add_u32_e32 v58, 1, v57
	v_not_b32_e32 v59, v57
	v_max_i32_e32 v58, v58, v59
	v_cndmask_b32_e32 v32, v118, v32, vcc
	v_cmp_gt_u32_e32 vcc, s70, v58
	v_add_u32_e32 v58, 2, v57
	v_sub_u32_e32 v59, -2, v57
	v_max_i32_e32 v58, v58, v59
	v_cndmask_b32_e32 v33, v118, v33, vcc
	v_cmp_gt_u32_e32 vcc, s70, v58
	v_add_u32_e32 v58, 3, v57
	v_sub_u32_e32 v57, -3, v57
	v_max_i32_e32 v57, v58, v57
	v_cndmask_b32_e32 v34, v118, v34, vcc
	v_cmp_gt_u32_e32 vcc, s70, v57
	v_sub_u32_e32 v57, v71, v56
	v_sub_u32_e32 v58, 0, v57
	v_max_i32_e32 v58, v57, v58
	v_cndmask_b32_e32 v35, v118, v35, vcc
	v_cmp_gt_u32_e32 vcc, s70, v58
	v_add_u32_e32 v58, 1, v57
	v_not_b32_e32 v59, v57
	v_max_i32_e32 v58, v58, v59
	v_cndmask_b32_e32 v36, v118, v36, vcc
	v_cmp_gt_u32_e32 vcc, s70, v58
	v_add_u32_e32 v58, 2, v57
	v_sub_u32_e32 v59, -2, v57
	v_max_i32_e32 v58, v58, v59
	v_cndmask_b32_e32 v37, v118, v37, vcc
	v_cmp_gt_u32_e32 vcc, s70, v58
	v_add_u32_e32 v58, 3, v57
	v_sub_u32_e32 v57, -3, v57
	v_max_i32_e32 v57, v58, v57
	v_sub_u32_e32 v56, v72, v56
	v_cndmask_b32_e32 v38, v118, v38, vcc
	v_cmp_gt_u32_e32 vcc, s70, v57
	v_sub_u32_e32 v57, 0, v56
	v_max_i32_e32 v57, v56, v57
	v_cndmask_b32_e32 v39, v118, v39, vcc
	v_cmp_gt_u32_e32 vcc, s70, v57
	v_add_u32_e32 v57, 1, v56
	v_not_b32_e32 v58, v56
	v_max_i32_e32 v57, v57, v58
	v_cndmask_b32_e32 v40, v118, v40, vcc
	v_cmp_gt_u32_e32 vcc, s70, v57
	v_add_u32_e32 v57, 2, v56
	v_sub_u32_e32 v58, -2, v56
	v_max_i32_e32 v57, v57, v58
	v_cndmask_b32_e32 v41, v118, v41, vcc
	v_cmp_gt_u32_e32 vcc, s70, v57
	v_add_u32_e32 v57, 3, v56
	v_sub_u32_e32 v56, -3, v56
	v_max_i32_e32 v56, v57, v56
	v_cndmask_b32_e32 v42, v118, v42, vcc
	v_cmp_gt_u32_e32 vcc, s70, v56
	s_nop 1
	v_cndmask_b32_e32 v43, v118, v43, vcc
	s_branch .LBB0_2356

.LBB0_2471:
	s_andn2_saveexec_b64 s[0:1], s[0:1]
	s_cbranch_execz .LBB0_2489
	v_add_u32_e32 v74, v130, v130
	v_add_u32_e32 v1, 0xb400, v74
	v_add_u32_e32 v143, 0xc000, v74
	ds_read2_b64 v[66:69], v1 offset0:96 offset1:192
	v_add_u32_e32 v89, 0xbc00, v74
	ds_read2_b64 v[74:77], v143 offset0:96 offset1:192
	ds_read2_b64 v[70:73], v89 offset0:32 offset1:128
	s_waitcnt vmcnt(16)
	v_lshlrev_b32_e32 v144, 16, v22
	v_lshlrev_b32_e32 v80, 16, v18
	v_lshlrev_b32_e32 v146, 16, v30
	v_mov_b32_e32 v81, v144
	v_lshlrev_b32_e32 v84, 16, v14
	s_waitcnt lgkmcnt(1)
	v_pk_fma_f32 v[80:81], v[66:67], v[80:81], v[76:77] op_sel_hi:[0,1,0]
	v_mov_b32_e32 v85, v146
	v_lshlrev_b32_e32 v145, 16, v34
	v_pk_fma_f32 v[80:81], v[68:69], v[84:85], v[80:81] op_sel_hi:[0,1,1]
	v_lshlrev_b32_e32 v147, 16, v38
	s_waitcnt lgkmcnt(0)
	v_pk_fma_f32 v[80:81], v[70:71], v[144:145], v[80:81] op_sel_hi:[0,1,1]
	v_pk_fma_f32 v[84:85], v[66:67], v[84:85], v[76:77] op_sel_hi:[0,1,0]
	v_lshlrev_b32_e32 v83, 16, v42
	v_mov_b32_e32 v82, v145
	v_pk_fma_f32 v[80:81], v[72:73], v[146:147], v[80:81] op_sel_hi:[0,1,1]
	v_pk_fma_f32 v[84:85], v[68:69], v[144:145], v[84:85] op_sel_hi:[0,1,1]
	v_pk_fma_f32 v[80:81], v[74:75], v[82:83], v[80:81] op_sel_hi:[0,1,1]
	v_pk_fma_f32 v[84:85], v[70:71], v[146:147], v[84:85] op_sel_hi:[0,1,1]
	v_lshlrev_b32_e32 v79, 16, v46
	v_mov_b32_e32 v78, v147
	v_mul_f32_e32 v107, 0xbfb8aa3b, v80
	v_pk_fma_f32 v[84:85], v[72:73], v[82:83], v[84:85] op_sel_hi:[0,1,1]
	v_exp_f32_e32 v154, v107
	v_mul_f32_e32 v107, 0xbfb8aa3b, v81
	v_pk_fma_f32 v[84:85], v[74:75], v[78:79], v[84:85] op_sel_hi:[0,1,1]
	v_exp_f32_e32 v155, v107
	v_mul_f32_e32 v107, 0xbfb8aa3b, v84
	v_exp_f32_e32 v144, v107
	v_mul_f32_e32 v107, 0xbfb8aa3b, v85
	v_exp_f32_e32 v145, v107
	v_pk_add_f32 v[154:155], v[154:155], 1.0 op_sel_hi:[1,0]
	v_and_b32_e32 v150, 0xffff0000, v22
	v_pk_add_f32 v[156:157], v[144:145], 1.0 op_sel_hi:[1,0]
	v_rcp_f32_e32 v144, v155
	v_and_b32_e32 v148, 0xffff0000, v18
	v_and_b32_e32 v152, 0xffff0000, v30
	v_mov_b32_e32 v149, v150
	v_mul_f32_e32 v144, v81, v144
	v_rcp_f32_e32 v107, v154
	v_and_b32_e32 v106, 0xffff0000, v14
	v_pk_fma_f32 v[148:149], v[66:67], v[148:149], v[76:77] op_sel:[1,0,1]
	v_mul_f32_e32 v145, v80, v107
	v_rcp_f32_e32 v81, v157
	s_nop 0
	v_mul_f32_e32 v146, v85, v81
	v_rcp_f32_e32 v81, v156
	s_nop 0
	v_mul_f32_e32 v147, v84, v81
	v_and_b32_e32 v84, 0xffff0000, v34
	v_mov_b32_e32 v107, v152
	v_mov_b32_e32 v151, v84
	v_and_b32_e32 v80, 0xffff0000, v38
	v_pk_fma_f32 v[148:149], v[68:69], v[106:107], v[148:149] op_sel:[1,0,0]
	v_pk_fma_f32 v[106:107], v[66:67], v[106:107], v[76:77] op_sel:[1,0,1]
	v_mov_b32_e32 v153, v80
	v_pk_fma_f32 v[148:149], v[70:71], v[150:151], v[148:149] op_sel:[1,0,0]
	v_pk_fma_f32 v[106:107], v[68:69], v[150:151], v[106:107] op_sel:[1,0,0]
	v_and_b32_e32 v85, 0xffff0000, v42
	v_pk_fma_f32 v[148:149], v[72:73], v[152:153], v[148:149] op_sel:[1,0,0]
	v_pk_fma_f32 v[106:107], v[70:71], v[152:153], v[106:107] op_sel:[1,0,0]
	v_and_b32_e32 v81, 0xffff0000, v46
	v_pk_fma_f32 v[148:149], v[74:75], v[84:85], v[148:149] op_sel:[1,0,0]
	v_pk_fma_f32 v[106:107], v[72:73], v[84:85], v[106:107] op_sel:[1,0,0]
	v_mul_f32_e32 v154, 0xbfb8aa3b, v148
	v_mul_f32_e32 v155, 0xbfb8aa3b, v149
	v_pk_fma_f32 v[150:151], v[74:75], v[80:81], v[106:107] op_sel:[1,0,0]
	v_exp_f32_e32 v154, v154
	v_exp_f32_e32 v155, v155
	v_mul_f32_e32 v106, 0xbfb8aa3b, v150
	v_mul_f32_e32 v107, 0xbfb8aa3b, v151
	v_exp_f32_e32 v106, v106
	v_exp_f32_e32 v107, v107
	v_pk_add_f32 v[154:155], v[154:155], 1.0 op_sel_hi:[1,0]
	v_pk_add_f32 v[152:153], v[106:107], 1.0 op_sel_hi:[1,0]
	v_rcp_f32_e32 v107, v155
	s_nop 0
	v_mul_f32_e32 v106, v149, v107
	v_rcp_f32_e32 v149, v154
	s_nop 0
	v_mul_f32_e32 v107, v148, v149
	v_rcp_f32_e32 v149, v153
	s_nop 0
	v_mul_f32_e32 v148, v151, v149
	v_rcp_f32_e32 v151, v152
	s_nop 0
	v_mul_f32_e32 v149, v150, v151
	v_lshlrev_b32_e32 v150, 16, v50
	v_lshlrev_b32_e32 v151, 16, v58
	v_lshlrev_b32_e32 v152, 16, v54
	v_lshlrev_b32_e32 v153, 16, v62
	v_pk_fma_f32 v[154:155], v[66:67], v[82:83], v[76:77] op_sel_hi:[0,1,0]
	v_pk_fma_f32 v[154:155], v[68:69], v[78:79], v[154:155] op_sel_hi:[0,1,1]
	v_pk_mov_b32 v[82:83], v[82:83], v[150:151] op_sel:[1,0]
	v_pk_mov_b32 v[156:157], v[78:79], v[152:153] op_sel:[1,0]
	v_pk_fma_f32 v[78:79], v[66:67], v[78:79], v[76:77] op_sel_hi:[0,1,0]
	v_pk_fma_f32 v[154:155], v[70:71], v[82:83], v[154:155] op_sel_hi:[0,1,1]
	v_pk_fma_f32 v[78:79], v[68:69], v[82:83], v[78:79] op_sel_hi:[0,1,1]
	v_pk_fma_f32 v[154:155], v[72:73], v[156:157], v[154:155] op_sel_hi:[0,1,1]
	v_pk_fma_f32 v[78:79], v[70:71], v[156:157], v[78:79] op_sel_hi:[0,1,1]
	v_pk_fma_f32 v[154:155], v[74:75], v[150:151], v[154:155] op_sel_hi:[0,1,1]
	v_pk_fma_f32 v[78:79], v[72:73], v[150:151], v[78:79] op_sel_hi:[0,1,1]
	v_mul_f32_e32 v158, 0xbfb8aa3b, v154
	v_mul_f32_e32 v159, 0xbfb8aa3b, v155
	v_pk_fma_f32 v[150:151], v[74:75], v[152:153], v[78:79] op_sel_hi:[0,1,1]
	v_exp_f32_e32 v158, v158
	v_exp_f32_e32 v159, v159
	v_mul_f32_e32 v78, 0xbfb8aa3b, v150
	v_mul_f32_e32 v79, 0xbfb8aa3b, v151
	v_exp_f32_e32 v78, v78
	v_exp_f32_e32 v79, v79
	v_pk_add_f32 v[158:159], v[158:159], 1.0 op_sel_hi:[1,0]
	v_pk_add_f32 v[152:153], v[78:79], 1.0 op_sel_hi:[1,0]
	v_rcp_f32_e32 v79, v159
	s_nop 0
	v_mul_f32_e32 v78, v155, v79
	v_rcp_f32_e32 v82, v158
	s_nop 0
	v_mul_f32_e32 v79, v154, v82
	v_rcp_f32_e32 v83, v153
	s_nop 0
	v_mul_f32_e32 v82, v151, v83
	v_rcp_f32_e32 v151, v152
	s_nop 0
	v_mul_f32_e32 v83, v150, v151
	v_and_b32_e32 v151, 0xffff0000, v58
	v_and_b32_e32 v150, 0xffff0000, v50
	v_pk_fma_f32 v[154:155], v[66:67], v[84:85], v[76:77] op_sel:[1,0,1]
	v_and_b32_e32 v153, 0xffff0000, v62
	v_and_b32_e32 v152, 0xffff0000, v54
	v_pk_fma_f32 v[154:155], v[68:69], v[80:81], v[154:155] op_sel:[1,0,0]
	v_pk_mov_b32 v[84:85], v[84:85], v[150:151] op_sel:[1,0]
	v_pk_fma_f32 v[66:67], v[66:67], v[80:81], v[76:77] op_sel:[1,0,1]
	v_pk_fma_f32 v[154:155], v[70:71], v[84:85], v[154:155] op_sel:[1,0,0]
	v_pk_mov_b32 v[156:157], v[80:81], v[152:153] op_sel:[1,0]
	v_pk_fma_f32 v[66:67], v[68:69], v[84:85], v[66:67] op_sel:[1,0,0]
	v_pk_fma_f32 v[154:155], v[72:73], v[156:157], v[154:155] op_sel:[1,0,0]
	v_pk_fma_f32 v[66:67], v[70:71], v[156:157], v[66:67] op_sel:[1,0,0]
	v_pk_fma_f32 v[154:155], v[74:75], v[150:151], v[154:155] op_sel:[1,0,0]
	v_pk_fma_f32 v[66:67], v[72:73], v[150:151], v[66:67] op_sel:[1,0,0]
	v_mul_f32_e32 v158, 0xbfb8aa3b, v154
	v_mul_f32_e32 v159, 0xbfb8aa3b, v155
	v_pk_fma_f32 v[70:71], v[74:75], v[152:153], v[66:67] op_sel:[1,0,0]
	v_exp_f32_e32 v158, v158
	v_exp_f32_e32 v159, v159
	v_mul_f32_e32 v66, 0xbfb8aa3b, v70
	v_mul_f32_e32 v67, 0xbfb8aa3b, v71
	v_exp_f32_e32 v66, v66
	v_exp_f32_e32 v67, v67
	v_pk_add_f32 v[158:159], v[158:159], 1.0 op_sel_hi:[1,0]
	v_pk_add_f32 v[72:73], v[66:67], 1.0 op_sel_hi:[1,0]
	v_rcp_f32_e32 v67, v159
	s_nop 0
	v_mul_f32_e32 v66, v155, v67
	v_rcp_f32_e32 v68, v158
	s_nop 0
	v_mul_f32_e32 v67, v154, v68
	v_rcp_f32_e32 v69, v73
	s_nop 0
	v_mul_f32_e32 v68, v71, v69
	v_rcp_f32_e32 v71, v72
	s_nop 0
	v_mul_f32_e32 v69, v70, v71
	s_and_saveexec_b64 s[58:59], s[8:9]
	s_cbranch_execz .LBB0_2474
	v_cvt_pk_bf16_f32 v70, v145, v107
	v_cvt_pk_bf16_f32 v71, v147, v149
	ds_write2_b32 v141, v70, v71 offset1:36
	v_cvt_pk_bf16_f32 v70, v144, v106
	v_cvt_pk_bf16_f32 v71, v146, v148
	ds_write2_b32 v141, v70, v71 offset0:72 offset1:108
	v_cvt_pk_bf16_f32 v70, v79, v67
	v_cvt_pk_bf16_f32 v71, v83, v69
	ds_write2_b32 v141, v70, v71 offset0:144 offset1:180
	v_cvt_pk_bf16_f32 v70, v78, v66
	v_cvt_pk_bf16_f32 v71, v82, v68
	ds_write2_b32 v141, v70, v71 offset0:216 offset1:252
.LBB0_2474:
	s_or_b64 exec, exec, s[58:59]
	s_and_saveexec_b64 s[58:59], s[10:11]
	s_cbranch_execz .LBB0_2476
	v_and_b32_sdwa v71, v145, v116 dst_sel:DWORD dst_unused:UNUSED_PAD src0_sel:WORD_1 src1_sel:DWORD
	v_add3_u32 v72, v145, v71, s78
	v_and_b32_sdwa v70, v144, v116 dst_sel:DWORD dst_unused:UNUSED_PAD src0_sel:WORD_1 src1_sel:DWORD
	v_cvt_pk_bf16_f32 v71, v146, v146
	v_cvt_pk_bf16_f32 v73, v147, v147
	v_add3_u32 v70, v144, v70, s78
	v_and_b32_e32 v71, 0xffff0000, v71
	v_and_b32_e32 v73, 0xffff0000, v73
	v_or_b32_sdwa v71, v71, v70 dst_sel:DWORD dst_unused:UNUSED_PAD src0_sel:DWORD src1_sel:WORD_1
	v_or_b32_sdwa v70, v73, v72 dst_sel:DWORD dst_unused:UNUSED_PAD src0_sel:DWORD src1_sel:WORD_1
	v_and_b32_sdwa v73, v79, v116 dst_sel:DWORD dst_unused:UNUSED_PAD src0_sel:WORD_1 src1_sel:DWORD
	v_add3_u32 v74, v79, v73, s78
	v_and_b32_sdwa v72, v78, v116 dst_sel:DWORD dst_unused:UNUSED_PAD src0_sel:WORD_1 src1_sel:DWORD
	v_cvt_pk_bf16_f32 v73, v82, v82
	v_cvt_pk_bf16_f32 v75, v83, v83
	v_add3_u32 v72, v78, v72, s78
	v_and_b32_e32 v73, 0xffff0000, v73
	v_and_b32_e32 v75, 0xffff0000, v75
	v_or_b32_sdwa v73, v73, v72 dst_sel:DWORD dst_unused:UNUSED_PAD src0_sel:DWORD src1_sel:WORD_1
	v_or_b32_sdwa v72, v75, v74 dst_sel:DWORD dst_unused:UNUSED_PAD src0_sel:DWORD src1_sel:WORD_1
	ds_write_b128 v131, v[70:73]
	v_and_b32_sdwa v71, v107, v116 dst_sel:DWORD dst_unused:UNUSED_PAD src0_sel:WORD_1 src1_sel:DWORD
	v_add3_u32 v72, v107, v71, s78
	v_and_b32_sdwa v70, v106, v116 dst_sel:DWORD dst_unused:UNUSED_PAD src0_sel:WORD_1 src1_sel:DWORD
	v_cvt_pk_bf16_f32 v71, v148, v148
	v_cvt_pk_bf16_f32 v73, v149, v149
	v_add3_u32 v70, v106, v70, s78
	v_and_b32_e32 v71, 0xffff0000, v71
	v_and_b32_e32 v73, 0xffff0000, v73
	v_or_b32_sdwa v71, v71, v70 dst_sel:DWORD dst_unused:UNUSED_PAD src0_sel:DWORD src1_sel:WORD_1
	v_or_b32_sdwa v70, v73, v72 dst_sel:DWORD dst_unused:UNUSED_PAD src0_sel:DWORD src1_sel:WORD_1
	v_and_b32_sdwa v72, v66, v116 dst_sel:DWORD dst_unused:UNUSED_PAD src0_sel:WORD_1 src1_sel:DWORD
	v_and_b32_sdwa v73, v67, v116 dst_sel:DWORD dst_unused:UNUSED_PAD src0_sel:WORD_1 src1_sel:DWORD
	v_add3_u32 v67, v67, v73, s78
	v_add3_u32 v66, v66, v72, s78
	v_and_b32_sdwa v72, v68, v116 dst_sel:DWORD dst_unused:UNUSED_PAD src0_sel:WORD_1 src1_sel:DWORD
	v_and_b32_sdwa v73, v69, v116 dst_sel:DWORD dst_unused:UNUSED_PAD src0_sel:WORD_1 src1_sel:DWORD
	v_add3_u32 v68, v68, v72, s78
	v_add3_u32 v69, v69, v73, s78
	v_and_b32_e32 v68, 0xffff0000, v68
	v_and_b32_e32 v69, 0xffff0000, v69
	v_or_b32_sdwa v73, v68, v66 dst_sel:DWORD dst_unused:UNUSED_PAD src0_sel:DWORD src1_sel:WORD_1
	v_or_b32_sdwa v72, v69, v67 dst_sel:DWORD dst_unused:UNUSED_PAD src0_sel:DWORD src1_sel:WORD_1
	ds_write_b128 v131, v[70:73] offset:144
.LBB0_2476:
	s_or_b64 exec, exec, s[58:59]
	ds_read2_b64 v[74:77], v1 offset0:97 offset1:193
	ds_read2_b64 v[66:69], v89 offset0:33 offset1:129
	ds_read2_b64 v[70:73], v143 offset0:97 offset1:193
	v_lshlrev_b32_e32 v106, 16, v23
	v_lshlrev_b32_e32 v80, 16, v19
	v_lshlrev_b32_e32 v144, 16, v31
	v_mov_b32_e32 v81, v106
	v_lshlrev_b32_e32 v84, 16, v15
	s_waitcnt lgkmcnt(0)
	v_pk_fma_f32 v[80:81], v[74:75], v[80:81], v[72:73] op_sel_hi:[0,1,0]
	v_mov_b32_e32 v85, v144
	v_lshlrev_b32_e32 v107, 16, v35
	v_pk_fma_f32 v[80:81], v[76:77], v[84:85], v[80:81] op_sel_hi:[0,1,1]
	v_lshlrev_b32_e32 v145, 16, v39
	v_pk_fma_f32 v[80:81], v[66:67], v[106:107], v[80:81] op_sel_hi:[0,1,1]
	v_pk_fma_f32 v[84:85], v[74:75], v[84:85], v[72:73] op_sel_hi:[0,1,0]
	v_lshlrev_b32_e32 v83, 16, v43
	v_mov_b32_e32 v82, v107
	v_pk_fma_f32 v[80:81], v[68:69], v[144:145], v[80:81] op_sel_hi:[0,1,1]
	v_pk_fma_f32 v[84:85], v[76:77], v[106:107], v[84:85] op_sel_hi:[0,1,1]
	v_pk_fma_f32 v[80:81], v[70:71], v[82:83], v[80:81] op_sel_hi:[0,1,1]
	v_pk_fma_f32 v[84:85], v[66:67], v[144:145], v[84:85] op_sel_hi:[0,1,1]
	v_lshlrev_b32_e32 v79, 16, v47
	v_mov_b32_e32 v78, v145
	v_mul_f32_e32 v147, 0xbfb8aa3b, v80
	v_pk_fma_f32 v[84:85], v[68:69], v[82:83], v[84:85] op_sel_hi:[0,1,1]
	v_exp_f32_e32 v154, v147
	v_mul_f32_e32 v147, 0xbfb8aa3b, v81
	v_pk_fma_f32 v[84:85], v[70:71], v[78:79], v[84:85] op_sel_hi:[0,1,1]
	v_exp_f32_e32 v155, v147
	v_mul_f32_e32 v106, 0xbfb8aa3b, v84
	v_mul_f32_e32 v107, 0xbfb8aa3b, v85
	v_exp_f32_e32 v106, v106
	v_exp_f32_e32 v107, v107
	v_pk_add_f32 v[154:155], v[154:155], 1.0 op_sel_hi:[1,0]
	v_and_b32_e32 v150, 0xffff0000, v23
	v_and_b32_e32 v146, 0xffff0000, v19
	v_pk_add_f32 v[156:157], v[106:107], 1.0 op_sel_hi:[1,0]
	v_rcp_f32_e32 v107, v155
	v_and_b32_e32 v152, 0xffff0000, v31
	v_and_b32_e32 v148, 0xffff0000, v15
	v_mov_b32_e32 v149, v152
	v_mul_f32_e32 v106, v81, v107
	v_rcp_f32_e32 v107, v154
	s_nop 0
	v_mul_f32_e32 v107, v80, v107
	v_rcp_f32_e32 v81, v157
	s_nop 0
	v_mul_f32_e32 v144, v85, v81
	v_rcp_f32_e32 v81, v156
	s_nop 0
	v_mul_f32_e32 v145, v84, v81
	v_mov_b32_e32 v147, v150
	v_and_b32_e32 v84, 0xffff0000, v35
	v_pk_fma_f32 v[146:147], v[74:75], v[146:147], v[72:73] op_sel:[1,0,1]
	v_mov_b32_e32 v151, v84
	v_and_b32_e32 v80, 0xffff0000, v39
	v_pk_fma_f32 v[146:147], v[76:77], v[148:149], v[146:147] op_sel:[1,0,0]
	v_mov_b32_e32 v153, v80
	v_pk_fma_f32 v[146:147], v[66:67], v[150:151], v[146:147] op_sel:[1,0,0]
	v_and_b32_e32 v85, 0xffff0000, v43
	v_pk_fma_f32 v[146:147], v[68:69], v[152:153], v[146:147] op_sel:[1,0,0]
	v_and_b32_e32 v81, 0xffff0000, v47
	v_pk_fma_f32 v[154:155], v[70:71], v[84:85], v[146:147] op_sel:[1,0,0]
	s_nop 0
	v_mul_f32_e32 v146, 0xbfb8aa3b, v154
	v_mul_f32_e32 v147, 0xbfb8aa3b, v155
	v_exp_f32_e32 v146, v146
	v_exp_f32_e32 v147, v147
	s_nop 0
	v_pk_add_f32 v[156:157], v[146:147], 1.0 op_sel_hi:[1,0]
	v_pk_fma_f32 v[146:147], v[74:75], v[148:149], v[72:73] op_sel:[1,0,1]
	s_nop 0
	v_pk_fma_f32 v[146:147], v[76:77], v[150:151], v[146:147] op_sel:[1,0,0]
	s_nop 0
	v_pk_fma_f32 v[146:147], v[66:67], v[152:153], v[146:147] op_sel:[1,0,0]
	s_nop 0
	v_pk_fma_f32 v[146:147], v[68:69], v[84:85], v[146:147] op_sel:[1,0,0]
	s_nop 0
	v_pk_fma_f32 v[150:151], v[70:71], v[80:81], v[146:147] op_sel:[1,0,0]
	s_nop 0
	v_mul_f32_e32 v146, 0xbfb8aa3b, v150
	v_mul_f32_e32 v147, 0xbfb8aa3b, v151
	v_exp_f32_e32 v146, v146
	v_exp_f32_e32 v147, v147
	s_nop 0
	v_pk_add_f32 v[152:153], v[146:147], 1.0 op_sel_hi:[1,0]
	v_rcp_f32_e32 v147, v157
	s_nop 0
	v_mul_f32_e32 v146, v155, v147
	v_rcp_f32_e32 v148, v156
	s_nop 0
	v_mul_f32_e32 v147, v154, v148
	v_rcp_f32_e32 v149, v153
	s_nop 0
	v_mul_f32_e32 v148, v151, v149
	v_rcp_f32_e32 v151, v152
	s_nop 0
	v_mul_f32_e32 v149, v150, v151
	v_lshlrev_b32_e32 v150, 16, v51
	v_lshlrev_b32_e32 v151, 16, v59
	v_lshlrev_b32_e32 v152, 16, v55
	v_lshlrev_b32_e32 v153, 16, v63
	v_pk_fma_f32 v[154:155], v[74:75], v[82:83], v[72:73] op_sel_hi:[0,1,0]
	v_pk_fma_f32 v[154:155], v[76:77], v[78:79], v[154:155] op_sel_hi:[0,1,1]
	v_pk_mov_b32 v[82:83], v[82:83], v[150:151] op_sel:[1,0]
	v_pk_mov_b32 v[156:157], v[78:79], v[152:153] op_sel:[1,0]
	v_pk_fma_f32 v[78:79], v[74:75], v[78:79], v[72:73] op_sel_hi:[0,1,0]
	v_pk_fma_f32 v[154:155], v[66:67], v[82:83], v[154:155] op_sel_hi:[0,1,1]
	v_pk_fma_f32 v[78:79], v[76:77], v[82:83], v[78:79] op_sel_hi:[0,1,1]
	v_pk_fma_f32 v[154:155], v[68:69], v[156:157], v[154:155] op_sel_hi:[0,1,1]
	v_pk_fma_f32 v[78:79], v[66:67], v[156:157], v[78:79] op_sel_hi:[0,1,1]
	v_pk_fma_f32 v[154:155], v[70:71], v[150:151], v[154:155] op_sel_hi:[0,1,1]
	v_pk_fma_f32 v[78:79], v[68:69], v[150:151], v[78:79] op_sel_hi:[0,1,1]
	v_mul_f32_e32 v158, 0xbfb8aa3b, v154
	v_mul_f32_e32 v159, 0xbfb8aa3b, v155
	v_pk_fma_f32 v[150:151], v[70:71], v[152:153], v[78:79] op_sel_hi:[0,1,1]
	v_exp_f32_e32 v158, v158
	v_exp_f32_e32 v159, v159
	v_mul_f32_e32 v78, 0xbfb8aa3b, v150
	v_mul_f32_e32 v79, 0xbfb8aa3b, v151
	v_exp_f32_e32 v78, v78
	v_exp_f32_e32 v79, v79
	v_pk_add_f32 v[158:159], v[158:159], 1.0 op_sel_hi:[1,0]
	v_pk_add_f32 v[152:153], v[78:79], 1.0 op_sel_hi:[1,0]
	v_rcp_f32_e32 v79, v159
	s_nop 0
	v_mul_f32_e32 v78, v155, v79
	v_rcp_f32_e32 v82, v158
	s_nop 0
	v_mul_f32_e32 v79, v154, v82
	v_rcp_f32_e32 v83, v153
	s_nop 0
	v_mul_f32_e32 v82, v151, v83
	v_rcp_f32_e32 v151, v152
	s_nop 0
	v_mul_f32_e32 v83, v150, v151
	v_and_b32_e32 v151, 0xffff0000, v59
	v_and_b32_e32 v150, 0xffff0000, v51
	v_pk_fma_f32 v[154:155], v[74:75], v[84:85], v[72:73] op_sel:[1,0,1]
	v_and_b32_e32 v153, 0xffff0000, v63
	v_and_b32_e32 v152, 0xffff0000, v55
	v_pk_fma_f32 v[154:155], v[76:77], v[80:81], v[154:155] op_sel:[1,0,0]
	v_pk_mov_b32 v[84:85], v[84:85], v[150:151] op_sel:[1,0]
	v_pk_fma_f32 v[72:73], v[74:75], v[80:81], v[72:73] op_sel:[1,0,1]
	v_pk_fma_f32 v[154:155], v[66:67], v[84:85], v[154:155] op_sel:[1,0,0]
	v_pk_mov_b32 v[156:157], v[80:81], v[152:153] op_sel:[1,0]
	v_pk_fma_f32 v[72:73], v[76:77], v[84:85], v[72:73] op_sel:[1,0,0]
	v_pk_fma_f32 v[154:155], v[68:69], v[156:157], v[154:155] op_sel:[1,0,0]
	v_pk_fma_f32 v[66:67], v[66:67], v[156:157], v[72:73] op_sel:[1,0,0]
	v_pk_fma_f32 v[154:155], v[70:71], v[150:151], v[154:155] op_sel:[1,0,0]
	v_pk_fma_f32 v[66:67], v[68:69], v[150:151], v[66:67] op_sel:[1,0,0]
	v_mul_f32_e32 v158, 0xbfb8aa3b, v154
	v_mul_f32_e32 v159, 0xbfb8aa3b, v155
	v_pk_fma_f32 v[70:71], v[70:71], v[152:153], v[66:67] op_sel:[1,0,0]
	v_exp_f32_e32 v158, v158
	v_exp_f32_e32 v159, v159
	v_mul_f32_e32 v66, 0xbfb8aa3b, v70
	v_mul_f32_e32 v67, 0xbfb8aa3b, v71
	v_exp_f32_e32 v66, v66
	v_exp_f32_e32 v67, v67
	v_pk_add_f32 v[158:159], v[158:159], 1.0 op_sel_hi:[1,0]
	v_pk_add_f32 v[72:73], v[66:67], 1.0 op_sel_hi:[1,0]
	v_rcp_f32_e32 v67, v159
	s_nop 0
	v_mul_f32_e32 v66, v155, v67
	v_rcp_f32_e32 v68, v158
	s_nop 0
	v_mul_f32_e32 v67, v154, v68
	v_rcp_f32_e32 v69, v73
	s_nop 0
	v_mul_f32_e32 v68, v71, v69
	v_rcp_f32_e32 v71, v72
	s_nop 0
	v_mul_f32_e32 v69, v70, v71
	s_and_saveexec_b64 s[58:59], s[8:9]
	s_cbranch_execz .LBB0_2478
	v_cvt_pk_bf16_f32 v70, v107, v147
	v_cvt_pk_bf16_f32 v71, v145, v149
	ds_write2_b32 v141, v70, v71 offset0:1 offset1:37
	v_cvt_pk_bf16_f32 v70, v106, v146
	v_cvt_pk_bf16_f32 v71, v144, v148
	ds_write2_b32 v141, v70, v71 offset0:73 offset1:109
	v_cvt_pk_bf16_f32 v70, v79, v67
	v_cvt_pk_bf16_f32 v71, v83, v69
	ds_write2_b32 v141, v70, v71 offset0:145 offset1:181
	v_cvt_pk_bf16_f32 v70, v78, v66
	v_cvt_pk_bf16_f32 v71, v82, v68
	ds_write2_b32 v141, v70, v71 offset0:217 offset1:253
.LBB0_2478:
	s_or_b64 exec, exec, s[58:59]
	s_and_saveexec_b64 s[58:59], s[10:11]
	s_cbranch_execz .LBB0_2480
	v_and_b32_sdwa v71, v107, v116 dst_sel:DWORD dst_unused:UNUSED_PAD src0_sel:WORD_1 src1_sel:DWORD
	v_add3_u32 v72, v107, v71, s78
	v_and_b32_sdwa v70, v106, v116 dst_sel:DWORD dst_unused:UNUSED_PAD src0_sel:WORD_1 src1_sel:DWORD
	v_cvt_pk_bf16_f32 v71, v144, v144
	v_cvt_pk_bf16_f32 v73, v145, v145
	v_add3_u32 v70, v106, v70, s78
	v_and_b32_e32 v71, 0xffff0000, v71
	v_and_b32_e32 v73, 0xffff0000, v73
	v_or_b32_sdwa v71, v71, v70 dst_sel:DWORD dst_unused:UNUSED_PAD src0_sel:DWORD src1_sel:WORD_1
	v_or_b32_sdwa v70, v73, v72 dst_sel:DWORD dst_unused:UNUSED_PAD src0_sel:DWORD src1_sel:WORD_1
	v_and_b32_sdwa v73, v79, v116 dst_sel:DWORD dst_unused:UNUSED_PAD src0_sel:WORD_1 src1_sel:DWORD
	v_add3_u32 v74, v79, v73, s78
	v_and_b32_sdwa v72, v78, v116 dst_sel:DWORD dst_unused:UNUSED_PAD src0_sel:WORD_1 src1_sel:DWORD
	v_cvt_pk_bf16_f32 v73, v82, v82
	v_cvt_pk_bf16_f32 v75, v83, v83
	v_add3_u32 v72, v78, v72, s78
	v_and_b32_e32 v73, 0xffff0000, v73
	v_and_b32_e32 v75, 0xffff0000, v75
	v_or_b32_sdwa v73, v73, v72 dst_sel:DWORD dst_unused:UNUSED_PAD src0_sel:DWORD src1_sel:WORD_1
	v_or_b32_sdwa v72, v75, v74 dst_sel:DWORD dst_unused:UNUSED_PAD src0_sel:DWORD src1_sel:WORD_1
	ds_write_b128 v132, v[70:73]
	v_and_b32_sdwa v71, v147, v116 dst_sel:DWORD dst_unused:UNUSED_PAD src0_sel:WORD_1 src1_sel:DWORD
	v_add3_u32 v72, v147, v71, s78
	v_and_b32_sdwa v70, v146, v116 dst_sel:DWORD dst_unused:UNUSED_PAD src0_sel:WORD_1 src1_sel:DWORD
	v_cvt_pk_bf16_f32 v71, v148, v148
	v_cvt_pk_bf16_f32 v73, v149, v149
	v_add3_u32 v70, v146, v70, s78
	v_and_b32_e32 v71, 0xffff0000, v71
	v_and_b32_e32 v73, 0xffff0000, v73
	v_or_b32_sdwa v71, v71, v70 dst_sel:DWORD dst_unused:UNUSED_PAD src0_sel:DWORD src1_sel:WORD_1
	v_or_b32_sdwa v70, v73, v72 dst_sel:DWORD dst_unused:UNUSED_PAD src0_sel:DWORD src1_sel:WORD_1
	v_and_b32_sdwa v72, v66, v116 dst_sel:DWORD dst_unused:UNUSED_PAD src0_sel:WORD_1 src1_sel:DWORD
	v_and_b32_sdwa v73, v67, v116 dst_sel:DWORD dst_unused:UNUSED_PAD src0_sel:WORD_1 src1_sel:DWORD
	v_add3_u32 v67, v67, v73, s78
	v_add3_u32 v66, v66, v72, s78
	v_and_b32_sdwa v72, v68, v116 dst_sel:DWORD dst_unused:UNUSED_PAD src0_sel:WORD_1 src1_sel:DWORD
	v_and_b32_sdwa v73, v69, v116 dst_sel:DWORD dst_unused:UNUSED_PAD src0_sel:WORD_1 src1_sel:DWORD
	v_add3_u32 v68, v68, v72, s78
	v_add3_u32 v69, v69, v73, s78
	v_and_b32_e32 v68, 0xffff0000, v68
	v_and_b32_e32 v69, 0xffff0000, v69
	v_or_b32_sdwa v73, v68, v66 dst_sel:DWORD dst_unused:UNUSED_PAD src0_sel:DWORD src1_sel:WORD_1
	v_or_b32_sdwa v72, v69, v67 dst_sel:DWORD dst_unused:UNUSED_PAD src0_sel:DWORD src1_sel:WORD_1
	ds_write_b128 v132, v[70:73] offset:144
.LBB0_2480:
	s_or_b64 exec, exec, s[58:59]
	ds_read2_b64 v[74:77], v1 offset0:98 offset1:194
	ds_read2_b64 v[66:69], v89 offset0:34 offset1:130
	ds_read2_b64 v[70:73], v143 offset0:98 offset1:194
	v_lshlrev_b32_e32 v106, 16, v24
	v_lshlrev_b32_e32 v80, 16, v20
	v_lshlrev_b32_e32 v144, 16, v32
	v_mov_b32_e32 v81, v106
	v_lshlrev_b32_e32 v84, 16, v16
	s_waitcnt lgkmcnt(0)
	v_pk_fma_f32 v[80:81], v[74:75], v[80:81], v[72:73] op_sel_hi:[0,1,0]
	v_mov_b32_e32 v85, v144
	v_lshlrev_b32_e32 v107, 16, v36
	v_pk_fma_f32 v[80:81], v[76:77], v[84:85], v[80:81] op_sel_hi:[0,1,1]
	v_lshlrev_b32_e32 v145, 16, v40
	v_pk_fma_f32 v[80:81], v[66:67], v[106:107], v[80:81] op_sel_hi:[0,1,1]
	v_pk_fma_f32 v[84:85], v[74:75], v[84:85], v[72:73] op_sel_hi:[0,1,0]
	v_lshlrev_b32_e32 v83, 16, v44
	v_mov_b32_e32 v82, v107
	v_pk_fma_f32 v[80:81], v[68:69], v[144:145], v[80:81] op_sel_hi:[0,1,1]
	v_pk_fma_f32 v[84:85], v[76:77], v[106:107], v[84:85] op_sel_hi:[0,1,1]
	v_pk_fma_f32 v[80:81], v[70:71], v[82:83], v[80:81] op_sel_hi:[0,1,1]
	v_pk_fma_f32 v[84:85], v[66:67], v[144:145], v[84:85] op_sel_hi:[0,1,1]
	v_lshlrev_b32_e32 v79, 16, v48
	v_mov_b32_e32 v78, v145
	v_mul_f32_e32 v147, 0xbfb8aa3b, v80
	v_pk_fma_f32 v[84:85], v[68:69], v[82:83], v[84:85] op_sel_hi:[0,1,1]
	v_exp_f32_e32 v154, v147
	v_mul_f32_e32 v147, 0xbfb8aa3b, v81
	v_pk_fma_f32 v[84:85], v[70:71], v[78:79], v[84:85] op_sel_hi:[0,1,1]
	v_exp_f32_e32 v155, v147
	v_mul_f32_e32 v106, 0xbfb8aa3b, v84
	v_mul_f32_e32 v107, 0xbfb8aa3b, v85
	v_exp_f32_e32 v106, v106
	v_exp_f32_e32 v107, v107
	v_pk_add_f32 v[154:155], v[154:155], 1.0 op_sel_hi:[1,0]
	v_and_b32_e32 v150, 0xffff0000, v24
	v_and_b32_e32 v146, 0xffff0000, v20
	v_pk_add_f32 v[156:157], v[106:107], 1.0 op_sel_hi:[1,0]
	v_rcp_f32_e32 v107, v155
	v_and_b32_e32 v152, 0xffff0000, v32
	v_and_b32_e32 v148, 0xffff0000, v16
	v_mov_b32_e32 v149, v152
	v_mul_f32_e32 v106, v81, v107
	v_rcp_f32_e32 v107, v154
	s_nop 0
	v_mul_f32_e32 v107, v80, v107
	v_rcp_f32_e32 v81, v157
	s_nop 0
	v_mul_f32_e32 v144, v85, v81
	v_rcp_f32_e32 v81, v156
	s_nop 0
	v_mul_f32_e32 v145, v84, v81
	v_mov_b32_e32 v147, v150
	v_and_b32_e32 v84, 0xffff0000, v36
	v_pk_fma_f32 v[146:147], v[74:75], v[146:147], v[72:73] op_sel:[1,0,1]
	v_mov_b32_e32 v151, v84
	v_and_b32_e32 v80, 0xffff0000, v40
	v_pk_fma_f32 v[146:147], v[76:77], v[148:149], v[146:147] op_sel:[1,0,0]
	v_mov_b32_e32 v153, v80
	v_pk_fma_f32 v[146:147], v[66:67], v[150:151], v[146:147] op_sel:[1,0,0]
	v_and_b32_e32 v85, 0xffff0000, v44
	v_pk_fma_f32 v[146:147], v[68:69], v[152:153], v[146:147] op_sel:[1,0,0]
	v_and_b32_e32 v81, 0xffff0000, v48
	v_pk_fma_f32 v[154:155], v[70:71], v[84:85], v[146:147] op_sel:[1,0,0]
	s_nop 0
	v_mul_f32_e32 v146, 0xbfb8aa3b, v154
	v_mul_f32_e32 v147, 0xbfb8aa3b, v155
	v_exp_f32_e32 v146, v146
	v_exp_f32_e32 v147, v147
	s_nop 0
	v_pk_add_f32 v[156:157], v[146:147], 1.0 op_sel_hi:[1,0]
	v_pk_fma_f32 v[146:147], v[74:75], v[148:149], v[72:73] op_sel:[1,0,1]
	s_nop 0
	v_pk_fma_f32 v[146:147], v[76:77], v[150:151], v[146:147] op_sel:[1,0,0]
	s_nop 0
	v_pk_fma_f32 v[146:147], v[66:67], v[152:153], v[146:147] op_sel:[1,0,0]
	s_nop 0
	v_pk_fma_f32 v[146:147], v[68:69], v[84:85], v[146:147] op_sel:[1,0,0]
	s_nop 0
	v_pk_fma_f32 v[150:151], v[70:71], v[80:81], v[146:147] op_sel:[1,0,0]
	s_nop 0
	v_mul_f32_e32 v146, 0xbfb8aa3b, v150
	v_mul_f32_e32 v147, 0xbfb8aa3b, v151
	v_exp_f32_e32 v146, v146
	v_exp_f32_e32 v147, v147
	s_nop 0
	v_pk_add_f32 v[152:153], v[146:147], 1.0 op_sel_hi:[1,0]
	v_rcp_f32_e32 v147, v157
	s_nop 0
	v_mul_f32_e32 v146, v155, v147
	v_rcp_f32_e32 v148, v156
	s_nop 0
	v_mul_f32_e32 v147, v154, v148
	v_rcp_f32_e32 v149, v153
	s_nop 0
	v_mul_f32_e32 v148, v151, v149
	v_rcp_f32_e32 v151, v152
	s_nop 0
	v_mul_f32_e32 v149, v150, v151
	v_lshlrev_b32_e32 v150, 16, v52
	v_lshlrev_b32_e32 v151, 16, v60
	v_lshlrev_b32_e32 v152, 16, v56
	v_lshlrev_b32_e32 v153, 16, v64
	v_pk_fma_f32 v[154:155], v[74:75], v[82:83], v[72:73] op_sel_hi:[0,1,0]
	v_pk_fma_f32 v[154:155], v[76:77], v[78:79], v[154:155] op_sel_hi:[0,1,1]
	v_pk_mov_b32 v[82:83], v[82:83], v[150:151] op_sel:[1,0]
	v_pk_mov_b32 v[156:157], v[78:79], v[152:153] op_sel:[1,0]
	v_pk_fma_f32 v[78:79], v[74:75], v[78:79], v[72:73] op_sel_hi:[0,1,0]
	v_pk_fma_f32 v[154:155], v[66:67], v[82:83], v[154:155] op_sel_hi:[0,1,1]
	v_pk_fma_f32 v[78:79], v[76:77], v[82:83], v[78:79] op_sel_hi:[0,1,1]
	v_pk_fma_f32 v[154:155], v[68:69], v[156:157], v[154:155] op_sel_hi:[0,1,1]
	v_pk_fma_f32 v[78:79], v[66:67], v[156:157], v[78:79] op_sel_hi:[0,1,1]
	v_pk_fma_f32 v[154:155], v[70:71], v[150:151], v[154:155] op_sel_hi:[0,1,1]
	v_pk_fma_f32 v[78:79], v[68:69], v[150:151], v[78:79] op_sel_hi:[0,1,1]
	v_mul_f32_e32 v158, 0xbfb8aa3b, v154
	v_mul_f32_e32 v159, 0xbfb8aa3b, v155
	v_pk_fma_f32 v[150:151], v[70:71], v[152:153], v[78:79] op_sel_hi:[0,1,1]
	v_exp_f32_e32 v158, v158
	v_exp_f32_e32 v159, v159
	v_mul_f32_e32 v78, 0xbfb8aa3b, v150
	v_mul_f32_e32 v79, 0xbfb8aa3b, v151
	v_exp_f32_e32 v78, v78
	v_exp_f32_e32 v79, v79
	v_pk_add_f32 v[158:159], v[158:159], 1.0 op_sel_hi:[1,0]
	v_pk_add_f32 v[152:153], v[78:79], 1.0 op_sel_hi:[1,0]
	v_rcp_f32_e32 v79, v159
	s_nop 0
	v_mul_f32_e32 v78, v155, v79
	v_rcp_f32_e32 v82, v158
	s_nop 0
	v_mul_f32_e32 v79, v154, v82
	v_rcp_f32_e32 v83, v153
	s_nop 0
	v_mul_f32_e32 v82, v151, v83
	v_rcp_f32_e32 v151, v152
	s_nop 0
	v_mul_f32_e32 v83, v150, v151
	v_and_b32_e32 v151, 0xffff0000, v60
	v_and_b32_e32 v150, 0xffff0000, v52
	v_pk_fma_f32 v[154:155], v[74:75], v[84:85], v[72:73] op_sel:[1,0,1]
	v_and_b32_e32 v153, 0xffff0000, v64
	v_and_b32_e32 v152, 0xffff0000, v56
	v_pk_fma_f32 v[154:155], v[76:77], v[80:81], v[154:155] op_sel:[1,0,0]
	v_pk_mov_b32 v[84:85], v[84:85], v[150:151] op_sel:[1,0]
	v_pk_fma_f32 v[72:73], v[74:75], v[80:81], v[72:73] op_sel:[1,0,1]
	v_pk_fma_f32 v[154:155], v[66:67], v[84:85], v[154:155] op_sel:[1,0,0]
	v_pk_mov_b32 v[156:157], v[80:81], v[152:153] op_sel:[1,0]
	v_pk_fma_f32 v[72:73], v[76:77], v[84:85], v[72:73] op_sel:[1,0,0]
	v_pk_fma_f32 v[154:155], v[68:69], v[156:157], v[154:155] op_sel:[1,0,0]
	v_pk_fma_f32 v[66:67], v[66:67], v[156:157], v[72:73] op_sel:[1,0,0]
	v_pk_fma_f32 v[154:155], v[70:71], v[150:151], v[154:155] op_sel:[1,0,0]
	v_pk_fma_f32 v[66:67], v[68:69], v[150:151], v[66:67] op_sel:[1,0,0]
	v_mul_f32_e32 v158, 0xbfb8aa3b, v154
	v_mul_f32_e32 v159, 0xbfb8aa3b, v155
	v_pk_fma_f32 v[70:71], v[70:71], v[152:153], v[66:67] op_sel:[1,0,0]
	v_exp_f32_e32 v158, v158
	v_exp_f32_e32 v159, v159
	v_mul_f32_e32 v66, 0xbfb8aa3b, v70
	v_mul_f32_e32 v67, 0xbfb8aa3b, v71
	v_exp_f32_e32 v66, v66
	v_exp_f32_e32 v67, v67
	v_pk_add_f32 v[158:159], v[158:159], 1.0 op_sel_hi:[1,0]
	v_pk_add_f32 v[72:73], v[66:67], 1.0 op_sel_hi:[1,0]
	v_rcp_f32_e32 v67, v159
	s_nop 0
	v_mul_f32_e32 v66, v155, v67
	v_rcp_f32_e32 v68, v158
	s_nop 0
	v_mul_f32_e32 v67, v154, v68
	v_rcp_f32_e32 v69, v73
	s_nop 0
	v_mul_f32_e32 v68, v71, v69
	v_rcp_f32_e32 v71, v72
	s_nop 0
	v_mul_f32_e32 v69, v70, v71
	s_and_saveexec_b64 s[58:59], s[8:9]
	s_cbranch_execz .LBB0_2482
	v_cvt_pk_bf16_f32 v70, v107, v147
	v_cvt_pk_bf16_f32 v71, v145, v149
	ds_write2_b32 v141, v70, v71 offset0:2 offset1:38
	v_cvt_pk_bf16_f32 v70, v106, v146
	v_cvt_pk_bf16_f32 v71, v144, v148
	ds_write2_b32 v141, v70, v71 offset0:74 offset1:110
	v_cvt_pk_bf16_f32 v70, v79, v67
	v_cvt_pk_bf16_f32 v71, v83, v69
	ds_write2_b32 v141, v70, v71 offset0:146 offset1:182
	v_cvt_pk_bf16_f32 v70, v78, v66
	v_cvt_pk_bf16_f32 v71, v82, v68
	ds_write2_b32 v141, v70, v71 offset0:218 offset1:254
.LBB0_2482:
	s_or_b64 exec, exec, s[58:59]
	s_and_saveexec_b64 s[58:59], s[10:11]
	s_cbranch_execz .LBB0_2484
	v_and_b32_sdwa v71, v107, v116 dst_sel:DWORD dst_unused:UNUSED_PAD src0_sel:WORD_1 src1_sel:DWORD
	v_add3_u32 v72, v107, v71, s78
	v_and_b32_sdwa v70, v106, v116 dst_sel:DWORD dst_unused:UNUSED_PAD src0_sel:WORD_1 src1_sel:DWORD
	v_cvt_pk_bf16_f32 v71, v144, v144
	v_cvt_pk_bf16_f32 v73, v145, v145
	v_add3_u32 v70, v106, v70, s78
	v_and_b32_e32 v71, 0xffff0000, v71
	v_and_b32_e32 v73, 0xffff0000, v73
	v_or_b32_sdwa v71, v71, v70 dst_sel:DWORD dst_unused:UNUSED_PAD src0_sel:DWORD src1_sel:WORD_1
	v_or_b32_sdwa v70, v73, v72 dst_sel:DWORD dst_unused:UNUSED_PAD src0_sel:DWORD src1_sel:WORD_1
	v_and_b32_sdwa v73, v79, v116 dst_sel:DWORD dst_unused:UNUSED_PAD src0_sel:WORD_1 src1_sel:DWORD
	v_add3_u32 v74, v79, v73, s78
	v_and_b32_sdwa v72, v78, v116 dst_sel:DWORD dst_unused:UNUSED_PAD src0_sel:WORD_1 src1_sel:DWORD
	v_cvt_pk_bf16_f32 v73, v82, v82
	v_cvt_pk_bf16_f32 v75, v83, v83
	v_add3_u32 v72, v78, v72, s78
	v_and_b32_e32 v73, 0xffff0000, v73
	v_and_b32_e32 v75, 0xffff0000, v75
	v_or_b32_sdwa v73, v73, v72 dst_sel:DWORD dst_unused:UNUSED_PAD src0_sel:DWORD src1_sel:WORD_1
	v_or_b32_sdwa v72, v75, v74 dst_sel:DWORD dst_unused:UNUSED_PAD src0_sel:DWORD src1_sel:WORD_1
	ds_write_b128 v133, v[70:73]
	v_and_b32_sdwa v71, v147, v116 dst_sel:DWORD dst_unused:UNUSED_PAD src0_sel:WORD_1 src1_sel:DWORD
	v_add3_u32 v72, v147, v71, s78
	v_and_b32_sdwa v70, v146, v116 dst_sel:DWORD dst_unused:UNUSED_PAD src0_sel:WORD_1 src1_sel:DWORD
	v_cvt_pk_bf16_f32 v71, v148, v148
	v_cvt_pk_bf16_f32 v73, v149, v149
	v_add3_u32 v70, v146, v70, s78
	v_and_b32_e32 v71, 0xffff0000, v71
	v_and_b32_e32 v73, 0xffff0000, v73
	v_or_b32_sdwa v71, v71, v70 dst_sel:DWORD dst_unused:UNUSED_PAD src0_sel:DWORD src1_sel:WORD_1
	v_or_b32_sdwa v70, v73, v72 dst_sel:DWORD dst_unused:UNUSED_PAD src0_sel:DWORD src1_sel:WORD_1
	v_and_b32_sdwa v72, v66, v116 dst_sel:DWORD dst_unused:UNUSED_PAD src0_sel:WORD_1 src1_sel:DWORD
	v_and_b32_sdwa v73, v67, v116 dst_sel:DWORD dst_unused:UNUSED_PAD src0_sel:WORD_1 src1_sel:DWORD
	v_add3_u32 v67, v67, v73, s78
	v_add3_u32 v66, v66, v72, s78
	v_and_b32_sdwa v72, v68, v116 dst_sel:DWORD dst_unused:UNUSED_PAD src0_sel:WORD_1 src1_sel:DWORD
	v_and_b32_sdwa v73, v69, v116 dst_sel:DWORD dst_unused:UNUSED_PAD src0_sel:WORD_1 src1_sel:DWORD
	v_add3_u32 v68, v68, v72, s78
	v_add3_u32 v69, v69, v73, s78
	v_and_b32_e32 v68, 0xffff0000, v68
	v_and_b32_e32 v69, 0xffff0000, v69
	v_or_b32_sdwa v73, v68, v66 dst_sel:DWORD dst_unused:UNUSED_PAD src0_sel:DWORD src1_sel:WORD_1
	v_or_b32_sdwa v72, v69, v67 dst_sel:DWORD dst_unused:UNUSED_PAD src0_sel:DWORD src1_sel:WORD_1
	ds_write_b128 v133, v[70:73] offset:144
.LBB0_2484:
	s_or_b64 exec, exec, s[58:59]
	ds_read2_b64 v[74:77], v1 offset0:99 offset1:195
	ds_read2_b64 v[66:69], v89 offset0:35 offset1:131
	ds_read2_b64 v[70:73], v143 offset0:99 offset1:195
	v_lshlrev_b32_e32 v106, 16, v25
	v_lshlrev_b32_e32 v80, 16, v21
	v_lshlrev_b32_e32 v150, 16, v33
	v_mov_b32_e32 v81, v106
	v_lshlrev_b32_e32 v84, 16, v17
	s_waitcnt lgkmcnt(0)
	v_pk_fma_f32 v[80:81], v[74:75], v[80:81], v[72:73] op_sel_hi:[0,1,0]
	v_mov_b32_e32 v85, v150
	v_lshlrev_b32_e32 v107, 16, v37
	v_pk_fma_f32 v[80:81], v[76:77], v[84:85], v[80:81] op_sel_hi:[0,1,1]
	v_lshlrev_b32_e32 v151, 16, v41
	v_pk_fma_f32 v[80:81], v[66:67], v[106:107], v[80:81] op_sel_hi:[0,1,1]
	v_lshlrev_b32_e32 v83, 16, v45
	v_mov_b32_e32 v82, v107
	v_pk_fma_f32 v[80:81], v[68:69], v[150:151], v[80:81] op_sel_hi:[0,1,1]
	v_pk_fma_f32 v[80:81], v[70:71], v[82:83], v[80:81] op_sel_hi:[0,1,1]
	v_mul_f32_e32 v1, 0xbfb8aa3b, v80
	v_pk_fma_f32 v[84:85], v[74:75], v[84:85], v[72:73] op_sel_hi:[0,1,0]
	v_exp_f32_e32 v154, v1
	v_mul_f32_e32 v1, 0xbfb8aa3b, v81
	v_pk_fma_f32 v[84:85], v[76:77], v[106:107], v[84:85] op_sel_hi:[0,1,1]
	v_exp_f32_e32 v155, v1
	v_pk_fma_f32 v[84:85], v[66:67], v[150:151], v[84:85] op_sel_hi:[0,1,1]
	v_lshlrev_b32_e32 v79, 16, v49
	v_mov_b32_e32 v78, v151
	v_pk_fma_f32 v[84:85], v[68:69], v[82:83], v[84:85] op_sel_hi:[0,1,1]
	v_pk_fma_f32 v[84:85], v[70:71], v[78:79], v[84:85] op_sel_hi:[0,1,1]
	v_mul_f32_e32 v1, 0xbfb8aa3b, v84
	v_pk_add_f32 v[154:155], v[154:155], 1.0 op_sel_hi:[1,0]
	v_exp_f32_e32 v106, v1
	v_mul_f32_e32 v1, 0xbfb8aa3b, v85
	v_exp_f32_e32 v107, v1
	v_rcp_f32_e32 v89, v155
	v_pk_add_f32 v[150:151], v[106:107], 1.0 op_sel_hi:[1,0]
	v_and_b32_e32 v148, 0xffff0000, v25
	v_and_b32_e32 v144, 0xffff0000, v21
	v_mul_f32_e32 v1, v81, v89
	v_rcp_f32_e32 v89, v154
	v_and_b32_e32 v152, 0xffff0000, v33
	v_mov_b32_e32 v145, v148
	v_and_b32_e32 v146, 0xffff0000, v17
	v_mul_f32_e32 v89, v80, v89
	v_rcp_f32_e32 v81, v151
	v_pk_fma_f32 v[144:145], v[74:75], v[144:145], v[72:73] op_sel:[1,0,1]
	v_mov_b32_e32 v147, v152
	v_pk_fma_f32 v[144:145], v[76:77], v[146:147], v[144:145] op_sel:[1,0,0]
	v_mul_f32_e32 v106, v85, v81
	v_rcp_f32_e32 v81, v150
	v_pk_fma_f32 v[146:147], v[74:75], v[146:147], v[72:73] op_sel:[1,0,1]
	v_mul_f32_e32 v107, v84, v81
	v_and_b32_e32 v84, 0xffff0000, v37
	v_mov_b32_e32 v149, v84
	v_and_b32_e32 v80, 0xffff0000, v41
	v_mov_b32_e32 v153, v80
	v_pk_fma_f32 v[144:145], v[66:67], v[148:149], v[144:145] op_sel:[1,0,0]
	v_and_b32_e32 v85, 0xffff0000, v45
	v_pk_fma_f32 v[144:145], v[68:69], v[152:153], v[144:145] op_sel:[1,0,0]
	v_pk_fma_f32 v[146:147], v[76:77], v[148:149], v[146:147] op_sel:[1,0,0]
	v_pk_fma_f32 v[144:145], v[70:71], v[84:85], v[144:145] op_sel:[1,0,0]
	v_pk_fma_f32 v[146:147], v[66:67], v[152:153], v[146:147] op_sel:[1,0,0]
	v_mul_f32_e32 v143, 0xbfb8aa3b, v144
	v_exp_f32_e32 v150, v143
	v_mul_f32_e32 v143, 0xbfb8aa3b, v145
	v_exp_f32_e32 v151, v143
	v_and_b32_e32 v81, 0xffff0000, v49
	v_pk_fma_f32 v[146:147], v[68:69], v[84:85], v[146:147] op_sel:[1,0,0]
	v_pk_add_f32 v[150:151], v[150:151], 1.0 op_sel_hi:[1,0]
	v_pk_fma_f32 v[146:147], v[70:71], v[80:81], v[146:147] op_sel:[1,0,0]
	s_nop 0
	v_mul_f32_e32 v143, 0xbfb8aa3b, v146
	v_exp_f32_e32 v148, v143
	v_mul_f32_e32 v143, 0xbfb8aa3b, v147
	v_exp_f32_e32 v149, v143
	v_rcp_f32_e32 v152, v151
	v_pk_add_f32 v[148:149], v[148:149], 1.0 op_sel_hi:[1,0]
	v_mul_f32_e32 v143, v145, v152
	v_rcp_f32_e32 v151, v150
	s_nop 0
	v_mul_f32_e32 v144, v144, v151
	v_rcp_f32_e32 v150, v149
	s_nop 0
	v_mul_f32_e32 v145, v147, v150
	v_rcp_f32_e32 v149, v148
	s_nop 0
	v_mul_f32_e32 v146, v146, v149
	v_lshlrev_b32_e32 v148, 16, v53
	v_lshlrev_b32_e32 v149, 16, v61
	v_pk_fma_f32 v[152:153], v[74:75], v[82:83], v[72:73] op_sel_hi:[0,1,0]
	v_lshlrev_b32_e32 v150, 16, v57
	v_lshlrev_b32_e32 v151, 16, v65
	v_pk_fma_f32 v[152:153], v[76:77], v[78:79], v[152:153] op_sel_hi:[0,1,1]
	v_pk_mov_b32 v[82:83], v[82:83], v[148:149] op_sel:[1,0]
	v_pk_mov_b32 v[154:155], v[78:79], v[150:151] op_sel:[1,0]
	v_pk_fma_f32 v[152:153], v[66:67], v[82:83], v[152:153] op_sel_hi:[0,1,1]
	v_pk_fma_f32 v[78:79], v[74:75], v[78:79], v[72:73] op_sel_hi:[0,1,0]
	v_pk_fma_f32 v[152:153], v[68:69], v[154:155], v[152:153] op_sel_hi:[0,1,1]
	v_pk_fma_f32 v[78:79], v[76:77], v[82:83], v[78:79] op_sel_hi:[0,1,1]
	v_pk_fma_f32 v[152:153], v[70:71], v[148:149], v[152:153] op_sel_hi:[0,1,1]
	v_pk_fma_f32 v[78:79], v[66:67], v[154:155], v[78:79] op_sel_hi:[0,1,1]
	v_mul_f32_e32 v147, 0xbfb8aa3b, v152
	v_pk_fma_f32 v[78:79], v[68:69], v[148:149], v[78:79] op_sel_hi:[0,1,1]
	v_exp_f32_e32 v156, v147
	v_mul_f32_e32 v147, 0xbfb8aa3b, v153
	v_pk_fma_f32 v[148:149], v[70:71], v[150:151], v[78:79] op_sel_hi:[0,1,1]
	v_exp_f32_e32 v157, v147
	v_mul_f32_e32 v78, 0xbfb8aa3b, v148
	v_mul_f32_e32 v79, 0xbfb8aa3b, v149
	v_exp_f32_e32 v78, v78
	v_exp_f32_e32 v79, v79
	v_pk_add_f32 v[156:157], v[156:157], 1.0 op_sel_hi:[1,0]
	v_pk_add_f32 v[150:151], v[78:79], 1.0 op_sel_hi:[1,0]
	v_rcp_f32_e32 v79, v157
	s_nop 0
	v_mul_f32_e32 v78, v153, v79
	v_rcp_f32_e32 v82, v156
	s_nop 0
	v_mul_f32_e32 v79, v152, v82
	v_rcp_f32_e32 v83, v151
	s_nop 0
	v_mul_f32_e32 v82, v149, v83
	v_rcp_f32_e32 v147, v150
	s_nop 0
	v_mul_f32_e32 v83, v148, v147
	v_and_b32_e32 v149, 0xffff0000, v61
	v_and_b32_e32 v148, 0xffff0000, v53
	v_pk_fma_f32 v[152:153], v[74:75], v[84:85], v[72:73] op_sel:[1,0,1]
	v_and_b32_e32 v151, 0xffff0000, v65
	v_and_b32_e32 v150, 0xffff0000, v57
	v_pk_fma_f32 v[152:153], v[76:77], v[80:81], v[152:153] op_sel:[1,0,0]
	v_pk_mov_b32 v[84:85], v[84:85], v[148:149] op_sel:[1,0]
	v_pk_mov_b32 v[154:155], v[80:81], v[150:151] op_sel:[1,0]
	v_pk_fma_f32 v[152:153], v[66:67], v[84:85], v[152:153] op_sel:[1,0,0]
	v_pk_fma_f32 v[72:73], v[74:75], v[80:81], v[72:73] op_sel:[1,0,1]
	v_pk_fma_f32 v[152:153], v[68:69], v[154:155], v[152:153] op_sel:[1,0,0]
	v_pk_fma_f32 v[72:73], v[76:77], v[84:85], v[72:73] op_sel:[1,0,0]
	v_pk_fma_f32 v[152:153], v[70:71], v[148:149], v[152:153] op_sel:[1,0,0]
	v_pk_fma_f32 v[66:67], v[66:67], v[154:155], v[72:73] op_sel:[1,0,0]
	v_mul_f32_e32 v147, 0xbfb8aa3b, v152
	v_pk_fma_f32 v[66:67], v[68:69], v[148:149], v[66:67] op_sel:[1,0,0]
	v_exp_f32_e32 v156, v147
	v_mul_f32_e32 v147, 0xbfb8aa3b, v153
	v_pk_fma_f32 v[70:71], v[70:71], v[150:151], v[66:67] op_sel:[1,0,0]
	v_exp_f32_e32 v157, v147
	v_mul_f32_e32 v66, 0xbfb8aa3b, v70
	v_mul_f32_e32 v67, 0xbfb8aa3b, v71
	v_exp_f32_e32 v66, v66
	v_exp_f32_e32 v67, v67
	v_pk_add_f32 v[156:157], v[156:157], 1.0 op_sel_hi:[1,0]
	v_pk_add_f32 v[72:73], v[66:67], 1.0 op_sel_hi:[1,0]
	v_rcp_f32_e32 v67, v157
	s_nop 0
	v_mul_f32_e32 v66, v153, v67
	v_rcp_f32_e32 v68, v156
	s_nop 0
	v_mul_f32_e32 v67, v152, v68
	v_rcp_f32_e32 v69, v73
	s_nop 0
	v_mul_f32_e32 v68, v71, v69
	v_rcp_f32_e32 v71, v72
	s_nop 0
	v_mul_f32_e32 v69, v70, v71
	s_and_saveexec_b64 s[58:59], s[8:9]
	s_cbranch_execz .LBB0_2486
	v_cvt_pk_bf16_f32 v70, v89, v144
	v_cvt_pk_bf16_f32 v71, v107, v146
	ds_write2_b32 v141, v70, v71 offset0:3 offset1:39
	v_cvt_pk_bf16_f32 v70, v1, v143
	v_cvt_pk_bf16_f32 v71, v106, v145
	ds_write2_b32 v141, v70, v71 offset0:75 offset1:111
	v_cvt_pk_bf16_f32 v70, v79, v67
	v_cvt_pk_bf16_f32 v71, v83, v69
	ds_write2_b32 v141, v70, v71 offset0:147 offset1:183
	v_cvt_pk_bf16_f32 v70, v78, v66
	v_cvt_pk_bf16_f32 v71, v82, v68
	ds_write2_b32 v141, v70, v71 offset0:219 offset1:255
.LBB0_2486:
	s_or_b64 exec, exec, s[58:59]
	s_and_saveexec_b64 s[58:59], s[10:11]
	s_cbranch_execz .LBB0_2488
	v_and_b32_sdwa v70, v1, v116 dst_sel:DWORD dst_unused:UNUSED_PAD src0_sel:WORD_1 src1_sel:DWORD
	v_and_b32_sdwa v71, v89, v116 dst_sel:DWORD dst_unused:UNUSED_PAD src0_sel:WORD_1 src1_sel:DWORD
	v_add3_u32 v72, v89, v71, s78
	v_add3_u32 v1, v1, v70, s78
	v_and_b32_sdwa v71, v107, v116 dst_sel:DWORD dst_unused:UNUSED_PAD src0_sel:WORD_1 src1_sel:DWORD
	v_cvt_pk_bf16_f32 v70, v106, v106
	v_add3_u32 v71, v107, v71, s78
	v_and_b32_e32 v70, 0xffff0000, v70
	v_and_b32_e32 v73, 0xffff0000, v71
	v_or_b32_sdwa v71, v70, v1 dst_sel:DWORD dst_unused:UNUSED_PAD src0_sel:DWORD src1_sel:WORD_1
	v_or_b32_sdwa v70, v73, v72 dst_sel:DWORD dst_unused:UNUSED_PAD src0_sel:DWORD src1_sel:WORD_1
	v_and_b32_sdwa v1, v78, v116 dst_sel:DWORD dst_unused:UNUSED_PAD src0_sel:WORD_1 src1_sel:DWORD
	v_and_b32_sdwa v72, v79, v116 dst_sel:DWORD dst_unused:UNUSED_PAD src0_sel:WORD_1 src1_sel:DWORD
	v_cvt_pk_bf16_f32 v73, v82, v82
	v_cvt_pk_bf16_f32 v74, v83, v83
	v_add3_u32 v72, v79, v72, s78
	v_add3_u32 v1, v78, v1, s78
	v_and_b32_e32 v73, 0xffff0000, v73
	v_and_b32_e32 v74, 0xffff0000, v74
	v_or_b32_sdwa v73, v73, v1 dst_sel:DWORD dst_unused:UNUSED_PAD src0_sel:DWORD src1_sel:WORD_1
	v_or_b32_sdwa v72, v74, v72 dst_sel:DWORD dst_unused:UNUSED_PAD src0_sel:DWORD src1_sel:WORD_1
	ds_write_b128 v134, v[70:73]
	v_and_b32_sdwa v1, v143, v116 dst_sel:DWORD dst_unused:UNUSED_PAD src0_sel:WORD_1 src1_sel:DWORD
	v_and_b32_sdwa v70, v144, v116 dst_sel:DWORD dst_unused:UNUSED_PAD src0_sel:WORD_1 src1_sel:DWORD
	v_cvt_pk_bf16_f32 v71, v145, v145
	v_cvt_pk_bf16_f32 v72, v146, v146
	v_add3_u32 v70, v144, v70, s78
	v_add3_u32 v1, v143, v1, s78
	v_and_b32_e32 v71, 0xffff0000, v71
	v_and_b32_e32 v72, 0xffff0000, v72
	v_or_b32_sdwa v71, v71, v1 dst_sel:DWORD dst_unused:UNUSED_PAD src0_sel:DWORD src1_sel:WORD_1
	v_or_b32_sdwa v70, v72, v70 dst_sel:DWORD dst_unused:UNUSED_PAD src0_sel:DWORD src1_sel:WORD_1
	v_and_b32_sdwa v1, v66, v116 dst_sel:DWORD dst_unused:UNUSED_PAD src0_sel:WORD_1 src1_sel:DWORD
	v_and_b32_sdwa v72, v67, v116 dst_sel:DWORD dst_unused:UNUSED_PAD src0_sel:WORD_1 src1_sel:DWORD
	v_add3_u32 v67, v67, v72, s78
	v_add3_u32 v1, v66, v1, s78
	v_and_b32_sdwa v72, v69, v116 dst_sel:DWORD dst_unused:UNUSED_PAD src0_sel:WORD_1 src1_sel:DWORD
	v_cvt_pk_bf16_f32 v66, v68, v68
	v_add3_u32 v68, v69, v72, s78
	v_and_b32_e32 v66, 0xffff0000, v66
	v_and_b32_e32 v68, 0xffff0000, v68
	v_or_b32_sdwa v73, v66, v1 dst_sel:DWORD dst_unused:UNUSED_PAD src0_sel:DWORD src1_sel:WORD_1
	v_or_b32_sdwa v72, v68, v67 dst_sel:DWORD dst_unused:UNUSED_PAD src0_sel:DWORD src1_sel:WORD_1
	ds_write_b128 v134, v[70:73] offset:144

.Lssd1_pf_done:
	ds_read_b128 v[70:73], v1
	ds_read_b128 v[66:69], v1 offset:64
	ds_read_b128 v[74:77], v142 offset:9216
	ds_read_b128 v[78:81], v142 offset:9280
	s_waitcnt lgkmcnt(1)
	v_mfma_f32_16x16x32_bf16 v[74:77], v[70:73], v[74:77], 0
	v_add_u32_e32 v89, 0xb400, v92
	s_add_i32 s73, s71, 64
	s_cmp_ge_u32 s73, s2
	s_waitcnt lgkmcnt(0)
	v_mfma_f32_16x16x32_bf16 v[144:147], v[66:69], v[78:81], v[74:77]
	ds_read_b128 v[78:81], v142 offset:11584
	s_nop 1
	ds_read_b128 v[74:77], v142 offset:11520
	s_waitcnt lgkmcnt(0)
	v_mfma_f32_16x16x32_bf16 v[74:77], v[70:73], v[74:77], 0
	v_mfma_f32_16x16x32_bf16 v[148:151], v[66:69], v[78:81], v[74:77]
	ds_read_b128 v[78:81], v142 offset:13888
	s_nop 5
	ds_read_b128 v[74:77], v142 offset:13824
	s_waitcnt lgkmcnt(0)
	v_mfma_f32_16x16x32_bf16 v[74:77], v[70:73], v[74:77], 0
	v_mfma_f32_16x16x32_bf16 v[82:85], v[66:69], v[78:81], v[74:77]
	ds_read_b128 v[78:81], v142 offset:16192
	s_nop 5
	ds_read_b128 v[74:77], v142 offset:16128
	s_waitcnt lgkmcnt(0)
	v_mfma_f32_16x16x32_bf16 v[74:77], v[70:73], v[74:77], 0
	v_mfma_f32_16x16x32_bf16 v[78:81], v[66:69], v[78:81], v[74:77]
	s_nop 6
	ds_read_b128 v[74:77], v140 offset:46080
	ds_read2_b32 v[106:107], v89 offset1:16
	ds_read2_b32 v[152:153], v89 offset0:64 offset1:80
	s_waitcnt lgkmcnt(1)
	v_sub_f32_e32 v143, v74, v106
	v_mul_f32_e32 v143, 0x3fb8aa3b, v143
	v_exp_f32_e32 v143, v143
	s_waitcnt lgkmcnt(0)
	v_mul_f32_e32 v143, v152, v143
	v_cndmask_b32_e64 v143, v143, 0, s[24:25]
	v_mul_f32_e32 v143, v144, v143
	v_cvt_pk_bf16_f32 v143, v143, v143
	ds_write_b16_d16_hi v93, v143
	v_sub_f32_e32 v143, v75, v106
	v_mul_f32_e32 v143, 0x3fb8aa3b, v143
	v_exp_f32_e32 v143, v143
	s_nop 0
	v_mul_f32_e32 v143, v152, v143
	v_cndmask_b32_e64 v143, v143, 0, s[26:27]
	v_mul_f32_e32 v143, v145, v143
	v_bfe_u32 v144, v143, 16, 1
	v_add3_u32 v143, v143, v144, s78
	ds_write_b16_d16_hi v93, v143 offset:144
	v_sub_f32_e32 v143, v76, v106
	v_mul_f32_e32 v143, 0x3fb8aa3b, v143
	v_exp_f32_e32 v143, v143
	v_sub_f32_e32 v106, v77, v106
	v_mul_f32_e32 v106, 0x3fb8aa3b, v106
	v_exp_f32_e32 v106, v106
	v_mul_f32_e32 v143, v152, v143
	v_cndmask_b32_e64 v143, v143, 0, s[28:29]
	v_mul_f32_e32 v143, v146, v143
	v_mul_f32_e32 v106, v152, v106
	v_bfe_u32 v144, v143, 16, 1
	v_cndmask_b32_e64 v106, v106, 0, s[30:31]
	v_add3_u32 v143, v143, v144, s78
	v_mul_f32_e32 v106, v147, v106
	ds_write_b16_d16_hi v93, v143 offset:288
	v_bfe_u32 v143, v106, 16, 1
	v_add3_u32 v106, v106, v143, s78
	ds_write_b16_d16_hi v93, v106 offset:432
	v_sub_f32_e32 v106, v74, v107
	v_mul_f32_e32 v106, 0x3fb8aa3b, v106
	v_exp_f32_e32 v106, v106
	s_nop 0
	v_mul_f32_e32 v106, v153, v106
	v_cndmask_b32_e64 v106, v106, 0, s[34:35]
	v_mul_f32_e32 v106, v148, v106
	v_bfe_u32 v143, v106, 16, 1
	v_add3_u32 v106, v106, v143, s78
	ds_write_b16_d16_hi v93, v106 offset:32
	v_sub_f32_e32 v106, v75, v107
	v_mul_f32_e32 v106, 0x3fb8aa3b, v106
	v_exp_f32_e32 v106, v106
	s_nop 0
	v_mul_f32_e32 v106, v153, v106
	v_cndmask_b32_e64 v106, v106, 0, s[36:37]
	v_mul_f32_e32 v106, v149, v106
	v_bfe_u32 v143, v106, 16, 1
	v_add3_u32 v106, v106, v143, s78
	ds_write_b16_d16_hi v93, v106 offset:176
	v_sub_f32_e32 v106, v76, v107
	v_mul_f32_e32 v106, 0x3fb8aa3b, v106
	v_exp_f32_e32 v106, v106
	s_nop 0
	v_mul_f32_e32 v106, v153, v106
	v_cndmask_b32_e64 v106, v106, 0, s[38:39]
	v_mul_f32_e32 v106, v150, v106
	v_bfe_u32 v143, v106, 16, 1
	v_add3_u32 v106, v106, v143, s78
	ds_write_b16_d16_hi v93, v106 offset:320
	v_sub_f32_e32 v106, v77, v107
	v_mul_f32_e32 v106, 0x3fb8aa3b, v106
	v_exp_f32_e32 v106, v106
	s_nop 0
	v_mul_f32_e32 v106, v153, v106
	v_cndmask_b32_e64 v106, v106, 0, s[40:41]
	v_mul_f32_e32 v106, v151, v106
	v_bfe_u32 v107, v106, 16, 1
	v_add3_u32 v106, v106, v107, s78
	ds_write_b16_d16_hi v93, v106 offset:464
	ds_read2_b32 v[106:107], v89 offset0:32 offset1:48
	ds_read2_b32 v[144:145], v89 offset0:96 offset1:112
	s_waitcnt lgkmcnt(1)
	v_sub_f32_e32 v89, v74, v106
	v_mul_f32_e32 v89, 0x3fb8aa3b, v89
	v_exp_f32_e32 v89, v89
	s_waitcnt lgkmcnt(0)
	v_mul_f32_e32 v89, v144, v89
	v_cndmask_b32_e64 v89, v89, 0, s[42:43]
	v_mul_f32_e32 v82, v82, v89
	v_bfe_u32 v89, v82, 16, 1
	v_add3_u32 v82, v82, v89, s78
	ds_write_b16_d16_hi v93, v82 offset:64
	v_sub_f32_e32 v82, v75, v106
	v_mul_f32_e32 v82, 0x3fb8aa3b, v82
	v_exp_f32_e32 v82, v82
	s_nop 0
	v_mul_f32_e32 v82, v144, v82
	v_cndmask_b32_e64 v82, v82, 0, s[44:45]
	v_mul_f32_e32 v82, v83, v82
	v_bfe_u32 v83, v82, 16, 1
	v_add3_u32 v82, v82, v83, s78
	ds_write_b16_d16_hi v93, v82 offset:208
	v_sub_f32_e32 v82, v76, v106
	v_mul_f32_e32 v82, 0x3fb8aa3b, v82
	v_exp_f32_e32 v82, v82
	s_nop 0
	v_mul_f32_e32 v82, v144, v82
	v_cndmask_b32_e64 v82, v82, 0, s[46:47]
	v_mul_f32_e32 v82, v84, v82
	v_bfe_u32 v83, v82, 16, 1
	v_add3_u32 v82, v82, v83, s78
	ds_write_b16_d16_hi v93, v82 offset:352
	v_sub_f32_e32 v82, v77, v106
	v_mul_f32_e32 v82, 0x3fb8aa3b, v82
	v_exp_f32_e32 v82, v82
	s_nop 0
	v_mul_f32_e32 v82, v144, v82
	v_cndmask_b32_e64 v82, v82, 0, s[48:49]
	v_mul_f32_e32 v82, v85, v82
	v_bfe_u32 v83, v82, 16, 1
	v_add3_u32 v82, v82, v83, s78
	ds_write_b16_d16_hi v93, v82 offset:496
	v_sub_f32_e32 v82, v74, v107
	v_mul_f32_e32 v82, 0x3fb8aa3b, v82
	v_exp_f32_e32 v82, v82
	s_nop 0
	v_mul_f32_e32 v82, v145, v82
	v_cndmask_b32_e64 v82, v82, 0, s[50:51]
	v_mul_f32_e32 v78, v78, v82
	v_bfe_u32 v82, v78, 16, 1
	v_add3_u32 v78, v78, v82, s78
	ds_write_b16_d16_hi v93, v78 offset:96
	v_sub_f32_e32 v78, v75, v107
	v_mul_f32_e32 v78, 0x3fb8aa3b, v78
	v_exp_f32_e32 v78, v78
	s_nop 0
	v_mul_f32_e32 v78, v145, v78
	v_cndmask_b32_e64 v78, v78, 0, s[52:53]
	v_mul_f32_e32 v78, v79, v78
	v_bfe_u32 v79, v78, 16, 1
	v_add3_u32 v78, v78, v79, s78
	ds_write_b16_d16_hi v93, v78 offset:240
	v_sub_f32_e32 v78, v76, v107
	v_mul_f32_e32 v78, 0x3fb8aa3b, v78
	v_exp_f32_e32 v78, v78
	s_nop 0
	v_mul_f32_e32 v78, v145, v78
	v_cndmask_b32_e64 v78, v78, 0, s[54:55]
	v_mul_f32_e32 v78, v80, v78
	v_bfe_u32 v79, v78, 16, 1
	v_add3_u32 v78, v78, v79, s78
	ds_write_b16_d16_hi v93, v78 offset:384
	v_sub_f32_e32 v78, v77, v107
	v_mul_f32_e32 v78, 0x3fb8aa3b, v78
	v_exp_f32_e32 v78, v78
	s_nop 0
	v_mul_f32_e32 v78, v145, v78
	v_cndmask_b32_e64 v78, v78, 0, s[56:57]
	v_mul_f32_e32 v78, v81, v78
	v_bfe_u32 v79, v78, 16, 1
	v_add3_u32 v78, v78, v79, s78
	ds_write_b16_d16_hi v93, v78 offset:528
	ds_read_b128 v[78:81], v1
	ds_read_b128 v[82:85], v1 offset:64
	ds_read_b128 v[144:147], v142 offset:36864
	ds_read_b128 v[148:151], v142 offset:36928
	ds_read_b128 v[152:155], v142 offset:41536
	s_waitcnt lgkmcnt(2)
	v_mfma_f32_16x16x32_bf16 v[144:147], v[70:73], v[144:147], 0
	v_mul_f32_e32 v1, 0x3fb8aa3b, v74
	v_exp_f32_e32 v106, v1
	v_mul_f32_e32 v1, 0x3fb8aa3b, v75
	v_exp_f32_e32 v107, v1
	v_mul_f32_e32 v1, 0x3fb8aa3b, v76
	v_exp_f32_e32 v156, v1
	v_mul_f32_e32 v1, 0x3fb8aa3b, v77
	s_waitcnt lgkmcnt(1)
	v_mfma_f32_16x16x32_bf16 v[144:147], v[66:69], v[148:151], v[144:147]
	v_exp_f32_e32 v157, v1
	ds_read_b128 v[74:77], v142 offset:18432
	ds_read_b128 v[148:151], v142 offset:39232
	v_add_u32_e32 v1, s71, v138
	s_nop 3
	v_pk_mul_f32 v[144:145], v[106:107], v[144:145]
	v_pk_mul_f32 v[146:147], v[156:157], v[146:147]
	s_waitcnt lgkmcnt(1)
	s_nop 0
	v_mfma_f32_16x16x32_bf16 v[74:77], v[78:81], v[74:77], v[144:147]
	s_nop 2
	ds_read_b128 v[144:147], v142 offset:18496
	s_waitcnt lgkmcnt(0)
	v_mfma_f32_16x16x32_bf16 v[74:77], v[82:85], v[144:147], v[74:77]
	ds_read_b128 v[144:147], v142 offset:39168
	s_waitcnt lgkmcnt(0)
	v_mfma_f32_16x16x32_bf16 v[144:147], v[70:73], v[144:147], 0
	v_mfma_f32_16x16x32_bf16 v[144:147], v[66:69], v[148:151], v[144:147]
	ds_read_b128 v[148:151], v142 offset:20736
	s_nop 6
	v_pk_mul_f32 v[144:145], v[106:107], v[144:145]
	v_pk_mul_f32 v[146:147], v[156:157], v[146:147]
	s_waitcnt lgkmcnt(0)
	s_nop 0
	v_mfma_f32_16x16x32_bf16 v[144:147], v[78:81], v[148:151], v[144:147]
	ds_read_b128 v[148:151], v142 offset:20800
	s_waitcnt lgkmcnt(0)
	v_mfma_f32_16x16x32_bf16 v[144:147], v[82:85], v[148:151], v[144:147]
	ds_read_b128 v[148:151], v142 offset:41472
	s_waitcnt lgkmcnt(0)
	v_mfma_f32_16x16x32_bf16 v[148:151], v[70:73], v[148:151], 0
	v_mfma_f32_16x16x32_bf16 v[148:151], v[66:69], v[152:155], v[148:151]
	ds_read_b128 v[152:155], v142 offset:23040
	s_nop 6
	v_pk_mul_f32 v[148:149], v[106:107], v[148:149]
	v_pk_mul_f32 v[150:151], v[156:157], v[150:151]
	s_waitcnt lgkmcnt(0)
	s_nop 0
	v_mfma_f32_16x16x32_bf16 v[148:151], v[78:81], v[152:155], v[148:151]
	ds_read_b128 v[152:155], v142 offset:23104
	s_waitcnt lgkmcnt(0)
	v_mfma_f32_16x16x32_bf16 v[148:151], v[82:85], v[152:155], v[148:151]
	ds_read_b128 v[152:155], v142 offset:43776
	s_waitcnt lgkmcnt(0)
	v_mfma_f32_16x16x32_bf16 v[70:73], v[70:73], v[152:155], 0
	ds_read_b128 v[152:155], v142 offset:43840
	s_waitcnt lgkmcnt(0)
	v_mfma_f32_16x16x32_bf16 v[66:69], v[66:69], v[152:155], v[70:73]
	s_nop 4
	ds_read_b128 v[70:73], v142 offset:25344
	s_nop 1
	v_pk_mul_f32 v[66:67], v[106:107], v[66:67]
	v_pk_mul_f32 v[68:69], v[156:157], v[68:69]
	s_waitcnt lgkmcnt(0)
	s_nop 0
	v_mfma_f32_16x16x32_bf16 v[66:69], v[78:81], v[70:73], v[66:69]
	ds_read_b128 v[70:73], v142 offset:25408
	s_waitcnt lgkmcnt(0)
	v_mfma_f32_16x16x32_bf16 v[66:69], v[82:85], v[70:73], v[66:69]
	v_add_u32_e32 v70, s84, v139
	v_cndmask_b32_e64 v70, v70, v1, s[6:7]
	v_add_u32_e32 v70, s33, v70
	v_mad_i64_i32 v[70:71], s[0:1], v70, s72, v[102:103]
	v_cvt_pk_bf16_f32 v72, v74, v74
	global_store_short_d16_hi v[70:71], v72, off offset:1024
	v_cvt_pk_bf16_f32 v72, v144, v144
	global_store_short_d16_hi v[70:71], v72, off offset:1056
	v_cvt_pk_bf16_f32 v72, v148, v148
	global_store_short_d16_hi v[70:71], v72, off offset:1088
	v_cvt_pk_bf16_f32 v66, v66, v66
	global_store_short_d16_hi v[70:71], v66, off offset:1120
	v_add_u32_e32 v66, 1, v1
	v_xad_u32 v70, v1, -2, s2
	v_cndmask_b32_e64 v66, v70, v66, s[6:7]
	v_add_u32_e32 v66, s33, v66
	v_mad_i64_i32 v[70:71], s[0:1], v66, s72, v[102:103]
	v_cvt_pk_bf16_f32 v66, v75, v75
	global_store_short_d16_hi v[70:71], v66, off offset:1024
	v_cvt_pk_bf16_f32 v66, v145, v145
	global_store_short_d16_hi v[70:71], v66, off offset:1056
	v_cvt_pk_bf16_f32 v66, v149, v149
	global_store_short_d16_hi v[70:71], v66, off offset:1088
	v_cvt_pk_bf16_f32 v66, v67, v67
	global_store_short_d16_hi v[70:71], v66, off offset:1120
	v_add_u32_e32 v66, 2, v1
	v_xad_u32 v67, v1, -3, s2
	v_cndmask_b32_e64 v66, v67, v66, s[6:7]
	v_add_u32_e32 v66, s33, v66
	v_mad_i64_i32 v[66:67], s[0:1], v66, s72, v[102:103]
	v_cvt_pk_bf16_f32 v70, v76, v76
	global_store_short_d16_hi v[66:67], v70, off offset:1024
	v_cvt_pk_bf16_f32 v70, v146, v146
	global_store_short_d16_hi v[66:67], v70, off offset:1056
	v_cvt_pk_bf16_f32 v70, v150, v150
	global_store_short_d16_hi v[66:67], v70, off offset:1088
	v_cvt_pk_bf16_f32 v68, v68, v68
	global_store_short_d16_hi v[66:67], v68, off offset:1120
	v_add_u32_e32 v66, 3, v1
	v_xad_u32 v1, v1, -4, s2
	v_cndmask_b32_e64 v1, v1, v66, s[6:7]
	v_add_u32_e32 v1, s33, v1
	v_mad_i64_i32 v[66:67], s[0:1], v1, s72, v[102:103]
	v_cvt_pk_bf16_f32 v1, v77, v77
	global_store_short_d16_hi v[66:67], v1, off offset:1024
	v_cvt_pk_bf16_f32 v1, v147, v147
	global_store_short_d16_hi v[66:67], v1, off offset:1056
	v_cvt_pk_bf16_f32 v1, v151, v151
	global_store_short_d16_hi v[66:67], v1, off offset:1088
	s_cselect_b64 s[0:1], -1, 0
	v_cvt_pk_bf16_f32 v1, v69, v69
	s_and_b64 vcc, exec, s[0:1]
	global_store_short_d16_hi v[66:67], v1, off offset:1120
.LBB0_2519:
	ds_read_b32 v1, v0 offset:46332
	ds_read_b128 v[66:69], v115 offset:18432
	ds_read_b128 v[70:73], v128 offset:46592
	ds_read_b128 v[74:77], v128 offset:46608
	s_sub_i32 s84, s84, 64
	s_and_b64 vcc, exec, s[0:1]
	s_waitcnt lgkmcnt(2)
	v_and_b32_e32 v79, 0xffff0000, v66
	v_lshlrev_b32_e32 v78, 16, v66
	s_waitcnt lgkmcnt(1)
	v_pk_mul_f32 v[70:71], v[70:71], v[78:79]
	v_and_b32_e32 v79, 0xffff0000, v67
	v_lshlrev_b32_e32 v78, 16, v67
	v_pk_mul_f32 v[66:67], v[72:73], v[78:79]
	v_and_b32_e32 v73, 0xffff0000, v68
	v_lshlrev_b32_e32 v72, 16, v68
	s_waitcnt lgkmcnt(0)
	v_pk_mul_f32 v[72:73], v[74:75], v[72:73]
	v_and_b32_e32 v75, 0xffff0000, v69
	v_lshlrev_b32_e32 v74, 16, v69
	v_pk_mul_f32 v[68:69], v[76:77], v[74:75]
	v_bfe_u32 v79, v72, 16, 1
	v_cvt_pk_bf16_f32 v82, v66, v66
	v_cvt_pk_bf16_f32 v83, v67, v67
	v_cvt_pk_bf16_f32 v84, v68, v68
	v_cvt_pk_bf16_f32 v85, v69, v69
	v_cvt_pk_bf16_f32 v81, v70, v70
	v_cvt_pk_bf16_f32 v80, v71, v71
	v_add3_u32 v79, v72, v79, s78
	v_cvt_pk_bf16_f32 v89, v73, v73
	ds_read_b128 v[66:69], v115 offset:18496
	ds_read_b128 v[70:73], v128 offset:46720
	v_mul_f32_e32 v1, 0x3fb8aa3b, v1
	s_waitcnt lgkmcnt(1)
	v_and_b32_e32 v75, 0xffff0000, v66
	v_lshlrev_b32_e32 v74, 16, v66
	s_waitcnt lgkmcnt(0)
	v_pk_mul_f32 v[74:75], v[70:71], v[74:75]
	v_and_b32_e32 v71, 0xffff0000, v67
	v_lshlrev_b32_e32 v70, 16, v67
	v_pk_mul_f32 v[66:67], v[72:73], v[70:71]
	ds_read_b128 v[70:73], v128 offset:46736
	v_and_b32_e32 v77, 0xffff0000, v68
	v_lshlrev_b32_e32 v76, 16, v68
	s_waitcnt lgkmcnt(0)
	v_pk_mul_f32 v[70:71], v[70:71], v[76:77]
	v_and_b32_e32 v77, 0xffff0000, v69
	v_lshlrev_b32_e32 v76, 16, v69
	v_pk_mul_f32 v[68:69], v[72:73], v[76:77]
	v_cvt_pk_bf16_f32 v144, v66, v66
	v_cvt_pk_bf16_f32 v145, v67, v67
	v_cvt_pk_bf16_f32 v146, v68, v68
	v_cvt_pk_bf16_f32 v147, v69, v69
	v_cvt_pk_bf16_f32 v106, v70, v70
	v_cvt_pk_bf16_f32 v148, v71, v71
	v_exp_f32_e32 v78, v1
	ds_read_b128 v[66:69], v142 offset:27648
	v_perm_b32 v73, v85, v84, s3
	v_perm_b32 v71, v83, v82, s3
	v_perm_b32 v72, v89, v79, s3
	v_perm_b32 v70, v80, v81, s3
	v_cvt_pk_bf16_f32 v143, v74, v74
	v_cvt_pk_bf16_f32 v107, v75, v75
	v_pk_mul_f32 v[4:5], v[4:5], v[78:79] op_sel_hi:[1,0]
	v_pk_mul_f32 v[2:3], v[2:3], v[78:79] op_sel_hi:[1,0]
	ds_read_b128 v[74:77], v142 offset:27712
	v_pk_mul_f32 v[8:9], v[8:9], v[78:79] op_sel_hi:[1,0]
	s_waitcnt lgkmcnt(1)
	v_mfma_f32_16x16x32_bf16 v[2:5], v[70:73], v[66:69], v[2:5]
	v_perm_b32 v69, v147, v146, s3
	v_perm_b32 v67, v145, v144, s3
	v_perm_b32 v68, v148, v106, s3
	v_perm_b32 v66, v107, v143, s3
	v_pk_mul_f32 v[6:7], v[6:7], v[78:79] op_sel_hi:[1,0]
	v_pk_mul_f32 v[12:13], v[12:13], v[78:79] op_sel_hi:[1,0]
	s_waitcnt lgkmcnt(0)
	v_mfma_f32_16x16x32_bf16 v[2:5], v[66:69], v[74:77], v[2:5]
	ds_read_b128 v[74:77], v142 offset:29952
	v_pk_mul_f32 v[10:11], v[10:11], v[78:79] op_sel_hi:[1,0]
	v_pk_mul_f32 v[28:29], v[28:29], v[78:79] op_sel_hi:[1,0]
	s_waitcnt lgkmcnt(0)
	v_mfma_f32_16x16x32_bf16 v[6:9], v[70:73], v[74:77], v[6:9]
	ds_read_b128 v[74:77], v142 offset:30016
	s_nop 1
	v_bfe_u32 v1, v2, 16, 1
	v_pk_mul_f32 v[26:27], v[26:27], v[78:79] op_sel_hi:[1,0]
	s_waitcnt lgkmcnt(0)
	v_mfma_f32_16x16x32_bf16 v[6:9], v[66:69], v[74:77], v[6:9]
	ds_read_b128 v[74:77], v142 offset:32256
	v_add3_u32 v1, v2, v1, s78
	s_waitcnt lgkmcnt(0)
	v_mfma_f32_16x16x32_bf16 v[10:13], v[70:73], v[74:77], v[10:13]
	ds_read_b128 v[74:77], v142 offset:32320
	s_waitcnt lgkmcnt(0)
	v_mfma_f32_16x16x32_bf16 v[10:13], v[66:69], v[74:77], v[10:13]
	ds_read_b128 v[74:77], v142 offset:34560
	s_waitcnt lgkmcnt(0)
	v_mfma_f32_16x16x32_bf16 v[26:29], v[70:73], v[74:77], v[26:29]
	ds_read_b128 v[70:73], v142 offset:34624
	s_waitcnt lgkmcnt(0)
	s_barrier
	ds_write_b16_d16_hi v93, v1 offset:36864
	v_bfe_u32 v1, v3, 16, 1
	v_add3_u32 v1, v3, v1, s78
	ds_write_b16_d16_hi v93, v1 offset:37008
	v_bfe_u32 v1, v4, 16, 1
	v_add3_u32 v1, v4, v1, s78
	ds_write_b16_d16_hi v93, v1 offset:37152
	v_bfe_u32 v1, v5, 16, 1
	v_add3_u32 v1, v5, v1, s78
	ds_write_b16_d16_hi v93, v1 offset:37296
	v_bfe_u32 v1, v6, 16, 1
	v_add3_u32 v1, v6, v1, s78
	ds_write_b16_d16_hi v93, v1 offset:36896
	v_bfe_u32 v1, v7, 16, 1
	v_add3_u32 v1, v7, v1, s78
	ds_write_b16_d16_hi v93, v1 offset:37040
	v_bfe_u32 v1, v8, 16, 1
	v_add3_u32 v1, v8, v1, s78
	ds_write_b16_d16_hi v93, v1 offset:37184
	v_bfe_u32 v1, v9, 16, 1
	v_add3_u32 v1, v9, v1, s78
	ds_write_b16_d16_hi v93, v1 offset:37328
	v_bfe_u32 v1, v10, 16, 1
	v_add3_u32 v1, v10, v1, s78
	ds_write_b16_d16_hi v93, v1 offset:36928
	v_bfe_u32 v1, v11, 16, 1
	v_add3_u32 v1, v11, v1, s78
	v_mfma_f32_16x16x32_bf16 v[26:29], v[66:69], v[70:73], v[26:29]
	ds_write_b16_d16_hi v93, v1 offset:37072
	v_bfe_u32 v1, v12, 16, 1
	v_add3_u32 v1, v12, v1, s78
	ds_write_b16_d16_hi v93, v1 offset:37216
	v_bfe_u32 v1, v13, 16, 1
	v_add3_u32 v1, v13, v1, s78
	ds_write_b16_d16_hi v93, v1 offset:37360
	s_nop 0
	v_bfe_u32 v1, v26, 16, 1
	v_add3_u32 v1, v26, v1, s78
	ds_write_b16_d16_hi v93, v1 offset:36960
	v_bfe_u32 v1, v27, 16, 1
	v_add3_u32 v1, v27, v1, s78
	ds_write_b16_d16_hi v93, v1 offset:37104
	v_bfe_u32 v1, v28, 16, 1
	v_add3_u32 v1, v28, v1, s78
	ds_write_b16_d16_hi v93, v1 offset:37248
	v_bfe_u32 v1, v29, 16, 1
	v_add3_u32 v1, v29, v1, s78
	ds_write_b16_d16_hi v93, v1 offset:37392
	s_cbranch_vccnz .LBB0_2521
	s_mov_b32 s71, s73
	s_and_saveexec_b64 s[0:1], s[4:5]
	s_xor_b64 s[0:1], exec, s[0:1]
	s_cbranch_execnz .Lssd1_w3back
	s_branch .LBB0_2471

.LBB0_2532:
	s_lshl_b64 s[0:1], s[8:9], 1
	v_readlane_b32 s4, v241, 17
	v_readlane_b32 s5, v241, 18
	v_rcp_f32_e32 v7, v55
	s_add_i32 s18, s18, s16
	v_readlane_b32 s8, v241, 21
	v_readlane_b32 s9, v241, 22
	v_mul_f32_e32 v8, 1.0, v7
	s_add_u32 s0, s8, s0
	v_or_b32_e32 v1, v68, v47
	s_addc_u32 s1, s9, s1
	v_lshlrev_b32_e32 v4, 1, v45
	v_mov_b32_e32 v5, v0
	v_mul_f32_e32 v9, v8, v12
	v_add_u32_e32 v1, s18, v1
	v_lshl_add_u64 v[4:5], s[0:1], 0, v[4:5]
	s_movk_i32 s4, 0x300
	v_mad_i64_i32 v[6:7], s[0:1], v1, s4, v[4:5]
	v_cvt_pk_bf16_f32 v9, v9, v9
	global_store_short_d16_hi v[6:7], v9, off
	v_mul_f32_e32 v9, v8, v16
	v_cvt_pk_bf16_f32 v9, v9, v9
	global_store_short_d16_hi v[6:7], v9, off offset:32
	v_mul_f32_e32 v9, v8, v20
	v_cvt_pk_bf16_f32 v9, v9, v9
	global_store_short_d16_hi v[6:7], v9, off offset:64
	v_rcp_f32_e32 v10, v54
	v_mul_f32_e32 v8, v8, v24
	v_cvt_pk_bf16_f32 v8, v8, v8
	global_store_short_d16_hi v[6:7], v8, off offset:96
	v_mul_f32_e32 v8, 1.0, v10
	v_mul_f32_e32 v9, v8, v13
	v_add_u32_e32 v6, 1, v1
	v_mad_i64_i32 v[6:7], s[0:1], v6, s4, v[4:5]
	v_cvt_pk_bf16_f32 v9, v9, v9
	global_store_short_d16_hi v[6:7], v9, off
	v_mul_f32_e32 v9, v8, v17
	v_cvt_pk_bf16_f32 v9, v9, v9
	global_store_short_d16_hi v[6:7], v9, off offset:32
	v_mul_f32_e32 v9, v8, v21
	v_cvt_pk_bf16_f32 v9, v9, v9
	global_store_short_d16_hi v[6:7], v9, off offset:64
	v_rcp_f32_e32 v10, v3
	v_mul_f32_e32 v8, v8, v25
	v_cvt_pk_bf16_f32 v8, v8, v8
	global_store_short_d16_hi v[6:7], v8, off offset:96
	v_mul_f32_e32 v3, 1.0, v10
	v_mul_f32_e32 v8, v3, v14
	v_add_u32_e32 v6, 2, v1
	v_mad_i64_i32 v[6:7], s[0:1], v6, s4, v[4:5]
	v_cvt_pk_bf16_f32 v8, v8, v8
	global_store_short_d16_hi v[6:7], v8, off
	v_mul_f32_e32 v8, v3, v18
	v_cvt_pk_bf16_f32 v8, v8, v8
	global_store_short_d16_hi v[6:7], v8, off offset:32
	v_mul_f32_e32 v8, v3, v22
	v_cvt_pk_bf16_f32 v8, v8, v8
	global_store_short_d16_hi v[6:7], v8, off offset:64
	v_rcp_f32_e32 v9, v2
	v_mul_f32_e32 v3, v3, v26
	v_cvt_pk_bf16_f32 v3, v3, v3
	global_store_short_d16_hi v[6:7], v3, off offset:96
	v_mul_f32_e32 v6, 1.0, v9
	v_add_u32_e32 v1, 3, v1
	v_mad_i64_i32 v[2:3], s[0:1], v1, s4, v[4:5]
	v_mul_f32_e32 v1, v6, v15
	v_cvt_pk_bf16_f32 v1, v1, v1
	global_store_short_d16_hi v[2:3], v1, off
	v_mul_f32_e32 v1, v6, v19
	v_cvt_pk_bf16_f32 v1, v1, v1
	global_store_short_d16_hi v[2:3], v1, off offset:32
	v_mul_f32_e32 v1, v6, v23
	v_cvt_pk_bf16_f32 v1, v1, v1
	global_store_short_d16_hi v[2:3], v1, off offset:64
	v_mul_f32_e32 v1, v6, v27
	v_cvt_pk_bf16_f32 v1, v1, v1
	v_readlane_b32 s6, v241, 19
	v_readlane_b32 s7, v241, 20
	v_readlane_b32 s10, v241, 23
	v_readlane_b32 s11, v241, 24
	global_store_short_d16_hi v[2:3], v1, off offset:96
	s_barrier
	s_cbranch_execz .LBB0_2379
	s_branch .LBB0_2524

.LBB0_2629:
	s_cmp_le_u32 s48, s43
	s_cbranch_scc1 .LBB0_2631
	s_not_b32 s30, s48
	s_lshl_b32 s30, s30, 6
	s_and_b32 s30, s30, 0x400
	v_add_u32_e32 v1, s30, v99
	ds_read_b32 v1, v1 offset:21504
	v_add_u32_e32 v50, s48, v93
	v_xad_u32 v51, v50, -1, s40
	v_cndmask_b32_e64 v50, v51, v50, s[16:17]
	v_add_u32_e32 v50, s33, v50
	s_waitcnt lgkmcnt(0)
	v_cvt_pk_bf16_f32 v1, v1, v1
	v_mad_i64_i32 v[50:51], s[30:31], s45, v50, 0
	v_lshl_add_u64 v[50:51], v[50:51], 1, v[100:101]
	global_store_short_d16_hi v[50:51], v1, off

.LBB0_2665:
	s_cmp_lt_u32 s48, s43
	s_cbranch_scc1 .LBB0_2667
	ds_read_b32 v1, v99 offset:21504
	v_add_u32_e32 v50, s48, v87
	v_xad_u32 v51, v50, -1, s40
	v_cndmask_b32_e64 v50, v51, v50, s[16:17]
	v_add_u32_e32 v50, s33, v50
	s_waitcnt lgkmcnt(0)
	v_cvt_pk_bf16_f32 v1, v1, v1
	v_mad_i64_i32 v[50:51], s[30:31], s45, v50, 0
	v_lshl_add_u64 v[50:51], v[50:51], 1, v[100:101]
	global_store_short_d16_hi v[50:51], v1, off

.LBB0_2714:
	s_waitcnt lgkmcnt(0)
	s_barrier
	ds_read_b32 v2, v99 offset:22528
	v_add_u32_e32 v1, s46, v93
	s_cmp_eq_u32 s42, 0
	v_xad_u32 v3, v1, -1, s40
	s_cselect_b64 vcc, -1, 0
	v_cndmask_b32_e32 v1, v3, v1, vcc
	s_waitcnt lgkmcnt(0)
	v_add_u32_e32 v1, s33, v1
	v_cvt_pk_bf16_f32 v4, v2, v2
	v_mad_i64_i32 v[2:3], s[4:5], s45, v1, 0
	v_lshl_add_u64 v[2:3], v[2:3], 1, s[26:27]
	v_lshl_add_u64 v[2:3], v[94:95], 1, v[2:3]
	s_cmp_lg_u32 s54, 3
	global_store_short_d16_hi v[2:3], v4, off
	s_cbranch_scc0 .LBB0_2718
	s_mov_b64 s[6:7], 0
	s_and_b64 vcc, exec, s[0:1]
	s_mov_b64 s[4:5], 0
	s_cbranch_vccnz .LBB0_2719
	s_and_b64 vcc, exec, s[6:7]
	s_cbranch_vccnz .LBB0_2720

.Lrw1_gdone:
	s_sub_u32 s29, s23, 1
	s_lshr_b32 s30, s23, 1
	s_cmp_eq_u32 s18, 0
	s_cselect_b32 s25, s30, s23
	s_sub_u32 s31, s18, 1
	s_cmp_lt_u32 s31, 2
	s_cselect_b32 s24, s30, 0
	s_cmp_eq_u32 s18, 2
	s_cselect_b32 s40, 0, 1.0
	s_mov_b32 s41, s40
	s_lshl_b32 s42, s21, 1
	s_add_u32 s42, s42, 1
	s_lshl_b32 s42, s42, 1
	s_add_u32 s42, s42, s20
	s_lshl_b32 s42, s42, 2
	s_add_u32 s42, s42, s19
	v_readlane_b32 s14, v246, 10
	v_readlane_b32 s15, v246, 11
	s_nop 4
	s_load_dwordx2 s[4:5], s[14:15], 0x178
	s_load_dwordx2 s[6:7], s[14:15], 0x188
	s_load_dwordx2 s[8:9], s[14:15], 0x198
	s_load_dwordx2 s[10:11], s[14:15], 0x98
	s_load_dwordx2 s[12:13], s[14:15], 0xc8
	s_load_dwordx2 s[26:27], s[14:15], 0xd0
	v_and_b32_e32 v87, 15, v226
	v_lshrrev_b32_e32 v127, 4, v226
	v_lshlrev_b32_e32 v95, 4, v87
	v_lshlrev_b32_e32 v108, 2, v127
	v_lshlrev_b32_e32 v110, 4, v226
	v_lshlrev_b32_e32 v115, 2, v226
	v_mul_u32_u24_e32 v1, 0x180, v127
	v_lshl_add_u32 v1, v87, 3, v1
	v_lshlrev_b32_e32 v2, 8, v127
	v_add_u32_e32 v3, v2, v95
	v_lshl_add_u32 v2, v87, 3, v2
	v_lshrrev_b32_e32 v89, 2, v87
	v_and_b32_e32 v90, 3, v87
	v_lshlrev_b32_e32 v91, 6, v127
	v_lshl_add_u32 v91, v90, 4, v91
	v_add_u32_e32 v91, 0x5000, v91
	v_add_u32_e32 v92, 0x9000, v110
	v_cmp_eq_u32_e32 vcc, s17, v89
	s_nop 1
	v_cndmask_b32_e32 v4, v92, v91, vcc
	s_mov_b32 s30, 0xaaaaaab
	s_lshl_b32 s31, s19, 7
	v_mul_hi_u32 v87, v226, s30
	v_mul_u32_u24_e32 v89, 24, v87
	v_sub_u32_e32 v89, v226, v89
	v_add_u32_e32 v15, -1, v87
	v_lshrrev_b32_e32 v90, 3, v89
	v_and_b32_e32 v89, 7, v89
	v_lshlrev_b32_e32 v90, 9, v90
	v_lshl_add_u32 v91, v89, 4, v90
	v_add_u32_e32 v91, s31, v91
	v_add_u32_e32 v91, 0xd20, v91
	s_add_u32 s34, s22, s29
	s_cmp_eq_u32 s20, 0
	s_cselect_b32 s34, s22, s34
	s_waitcnt lgkmcnt(0)
	s_mul_i32 s98, s34, 0x1520
	s_mul_hi_u32 s99, s34, 0x1520
	s_add_u32 s100, s4, s98
	s_addc_u32 s101, s5, s99
	s_mul_i32 s98, s34, 0xa00
	s_mul_hi_u32 s99, s34, 0xa00
	s_add_u32 s98, s6, s98
	s_addc_u32 s99, s7, s99
	v_mov_b32_e32 v92, 0
	v_mov_b32_e32 v6, s100
	v_mov_b32_e32 v7, s101
	v_add_co_u32_e32 v6, vcc, v6, v91
	s_nop 1
	v_addc_co_u32_e32 v7, vcc, 0, v7, vcc
	s_movk_i32 s36, 0x1520
	s_mul_i32 s37, s36, -1
	s_cmp_eq_u32 s20, 0
	s_cselect_b32 s34, s36, s37
	s_movk_i32 s36, 0xa00
	s_mul_i32 s37, s36, -1
	s_cselect_b32 s35, s36, s37
	v_mov_b32_e32 v12, s34
	v_add_u32_e32 v92, 0x100, v226
	v_mul_hi_u32 v87, v92, s30
	v_mul_u32_u24_e32 v89, 24, v87
	v_sub_u32_e32 v89, v92, v89
	v_add_u32_e32 v16, -1, v87
	v_lshrrev_b32_e32 v90, 3, v89
	v_and_b32_e32 v89, 7, v89
	v_lshlrev_b32_e32 v90, 9, v90
	v_lshl_add_u32 v91, v89, 4, v90
	v_add_u32_e32 v91, s31, v91
	v_add_u32_e32 v91, 0xd20, v91
	s_lshl_b32 s36, s20, 9
	s_add_u32 s36, s36, s31
	v_add_u32_e32 v92, 0xffffff50, v226
	v_lshrrev_b32_e32 v21, 4, v92
	v_and_b32_e32 v87, 15, v92
	v_lshrrev_b32_e32 v89, 3, v87
	v_and_b32_e32 v87, 7, v87
	v_lshlrev_b32_e32 v89, 10, v89
	v_lshl_add_u32 v90, v87, 4, v89
	v_add_u32_e32 v90, s36, v90
	v_cmp_gt_u32_e32 vcc, 0xb0, v226
	s_nop 1
	v_cndmask_b32_e32 v16, v21, v16, vcc
	v_cndmask_b32_e32 v91, v90, v91, vcc
	v_mov_b32_e32 v87, s35
	v_mov_b32_e32 v89, s34
	v_cndmask_b32_e32 v13, v87, v89, vcc
	v_mov_b32_e32 v87, s98
	v_mov_b32_e32 v89, s100
	v_cndmask_b32_e32 v8, v87, v89, vcc
	v_mov_b32_e32 v87, s99
	v_mov_b32_e32 v89, s101
	v_cndmask_b32_e32 v9, v87, v89, vcc
	v_add_co_u32_e32 v8, vcc, v8, v91
	s_nop 1
	v_addc_co_u32_e32 v9, vcc, 0, v9, vcc
	v_add_u32_e32 v92, 0x50, v226
	v_lshrrev_b32_e32 v17, 4, v92
	v_and_b32_e32 v87, 15, v92
	v_lshrrev_b32_e32 v89, 3, v87
	v_and_b32_e32 v87, 7, v87
	v_lshlrev_b32_e32 v89, 10, v89
	v_lshl_add_u32 v91, v87, 4, v89
	v_add_u32_e32 v91, s36, v91
	v_mov_b32_e32 v10, s98
	v_mov_b32_e32 v11, s99
	v_add_co_u32_e32 v10, vcc, v10, v91
	s_nop 1
	v_addc_co_u32_e32 v11, vcc, 0, v11, vcc
	v_mov_b32_e32 v14, s35
	s_add_u32 s30, s22, s29
	s_cmp_eq_u32 s20, 0
	s_cselect_b32 s30, s22, s30
	s_lshl_b32 s36, s19, 7
	s_lshl_b32 s37, s17, 5
	s_add_u32 s36, s36, s37
	s_cmp_eq_u32 s18, 2
	s_cbranch_scc1 .Lrw1_o_u2
	s_lshl_b32 s37, s20, 9
	s_add_u32 s36, s36, s37
	s_mul_i32 s98, s30, 0xa00
	s_mul_hi_u32 s99, s30, 0xa00
	s_add_u32 s98, s98, s36
	s_addc_u32 s99, s99, 0
	s_add_u32 s98, s8, s98
	s_addc_u32 s99, s9, s99
	s_movk_i32 s36, 0xa00
	s_mul_i32 s37, s36, -1
	s_cmp_eq_u32 s20, 0
	s_cselect_b32 s35, s36, s37
	s_branch .Lrw1_o_done

.Lrw1_o_done:
	v_and_b32_e32 v87, 15, v226
	v_lshlrev_b32_e32 v87, 1, v87
	v_mov_b32_e32 v18, s98
	v_mov_b32_e32 v19, s99
	v_add_co_u32_e32 v18, vcc, v18, v87
	s_nop 1
	v_addc_co_u32_e32 v19, vcc, 0, v19, vcc
	v_mov_b32_e32 v20, s35
	s_lshl_b32 s36, s19, 8
	s_add_u32 s98, s10, s36
	s_addc_u32 s99, s11, 0
	s_add_u32 s98, s98, 0x1000
	s_addc_u32 s99, s99, 0
	global_load_dwordx4 v[26:29], v95, s[98:99]
	global_load_dwordx4 v[30:33], v95, s[98:99] offset:1024
	global_load_dwordx4 v[34:37], v95, s[98:99] offset:2048
	s_add_u32 s98, s12, s36
	s_addc_u32 s99, s13, 0
	s_add_u32 s100, s26, s36
	s_addc_u32 s101, s27, 0
	global_load_dwordx4 v[38:41], v95, s[98:99] offset:1024
	global_load_dwordx4 v[42:45], v95, s[100:101] offset:1024
	v_lshl_add_u32 v87, s17, 4, v127
	v_lshl_add_u32 v89, v87, 8, v95
	v_mov_b32_e32 v22, 0
	v_mov_b32_e32 v23, 0
	v_mov_b32_e32 v24, 0
	v_mov_b32_e32 v25, 0
	s_cmp_eq_u32 s18, 0
	s_cbranch_scc0 .Lrw1_s_not0
	s_load_dwordx2 s[36:37], s[14:15], 0x28
	s_waitcnt lgkmcnt(0)
	s_lshl_b32 s98, s42, 14
	s_add_u32 s36, s36, s98
	s_addc_u32 s37, s37, 0
	global_load_dwordx4 v[22:25], v89, s[36:37]
	s_branch .Lrw1_s_done

.LBB0_2777:
	s_and_b32 s19, s20, 0x7c0
	s_ashr_i32 s18, s2, 5
	s_and_b32 s31, s22, 0xfffff000
	v_add_u32_e32 v10, s19, v1
	s_and_b32 s0, s18, 1
	s_addk_i32 s31, 0x1000
	v_add_u32_e32 v10, 0x800, v10
	s_cmp_eq_u32 s0, 0
	v_or_b32_e32 v11, v10, v0
	v_or_b32_e32 v10, v10, v18
	v_sub_u32_e32 v12, 0xfff, v11
	s_cselect_b64 vcc, -1, 0
	s_ashr_i32 s19, s18, 31
	v_sub_u32_e32 v13, 0xfff, v10
	v_or_b32_e32 v14, 1, v10
	v_or_b32_e32 v15, 2, v10
	v_or_b32_e32 v16, 3, v10
	v_cndmask_b32_e32 v11, v12, v11, vcc
	s_lshl_b64 s[18:19], s[18:19], 14
	v_cndmask_b32_e32 v12, v13, v10, vcc
	v_sub_u32_e32 v13, 0xfff, v14
	v_sub_u32_e32 v17, 0xfff, v15
	v_sub_u32_e32 v19, 0xfff, v16
	v_add_u32_e32 v28, s31, v11
	v_lshl_add_u64 v[10:11], v[4:5], 0, s[18:19]
	v_cndmask_b32_e32 v36, v13, v14, vcc
	v_cndmask_b32_e32 v37, v17, v15, vcc
	v_cndmask_b32_e32 v19, v19, v16, vcc
	v_add_co_u32_e32 v16, vcc, s24, v10
	s_and_b32 s33, s2, 0xc0
	s_nop 0
	v_addc_co_u32_e32 v17, vcc, 0, v11, vcc
	v_add_co_u32_e32 v60, vcc, s28, v10
	s_lshl_b32 s34, s0, 9
	s_nop 0
	v_addc_co_u32_e32 v61, vcc, 0, v11, vcc
	s_lshl_b32 s0, s33, 1
	v_add_u32_e32 v94, s31, v12
	v_mad_i64_i32 v[12:13], s[18:19], v28, s25, v[6:7]
	v_add_co_u32_e32 v76, vcc, s29, v10
	global_load_dwordx4 v[20:23], v[10:11], off offset:16
	global_load_dwordx4 v[24:27], v[10:11], off
	global_load_dwordx4 v[28:31], v[10:11], off offset:128
	global_load_dwordx4 v[32:35], v[10:11], off offset:144
	v_lshl_add_u64 v[14:15], v[10:11], 0, s[6:7]
	v_lshl_add_u64 v[52:53], v[10:11], 0, s[8:9]
	v_lshl_add_u64 v[56:57], v[10:11], 0, s[10:11]
	v_lshl_add_u64 v[64:65], v[10:11], 0, s[12:13]
	v_lshl_add_u64 v[68:69], v[10:11], 0, s[14:15]
	v_addc_co_u32_e32 v77, vcc, 0, v11, vcc
	v_lshl_add_u64 v[10:11], v[10:11], 0, s[16:17]
	v_lshl_add_u64 v[12:13], v[12:13], 0, s[0:1]
	v_add_u32_e32 v95, s31, v36
	v_add_u32_e32 v96, s31, v37
	global_load_dwordx4 v[36:39], v[14:15], off offset:16
	global_load_dwordx4 v[40:43], v[16:17], off offset:128
	global_load_dwordx4 v[44:47], v[60:61], off offset:-4096
	global_load_dwordx4 v[48:51], v[60:61], off
	s_nop 0
	global_load_dwordx4 v[52:55], v[52:53], off offset:16
	s_nop 0
	global_load_dwordx4 v[56:59], v[56:57], off offset:16
	s_nop 0
	global_load_dwordx4 v[60:63], v[60:61], off offset:128
	s_nop 0
	global_load_dwordx4 v[64:67], v[64:65], off offset:16
	s_nop 0
	global_load_dwordx4 v[68:71], v[68:69], off offset:16
	s_nop 0
	global_load_dwordx4 v[72:75], v[76:77], off
	s_nop 0
	global_load_dwordx4 v[76:79], v[76:77], off offset:128
	s_nop 0
	global_load_dwordx4 v[80:83], v[10:11], off offset:16
	v_lshl_add_u64 v[10:11], v[12:13], 0, v[2:3]
	v_lshl_add_u64 v[12:13], v[10:11], 0, s[4:5]
	v_add_co_u32_e32 v10, vcc, s24, v10
	s_add_u32 s33, s42, s34
	s_nop 0
	v_addc_co_u32_e32 v11, vcc, 0, v11, vcc
	global_load_dwordx4 v[84:87], v[10:11], off offset:800
	global_load_dwordx4 v[88:91], v[12:13], off offset:64
	s_addc_u32 s19, s43, 0
	s_add_u32 s18, s33, s0
	s_addc_u32 s19, s19, 0
	v_lshl_add_u64 v[92:93], s[18:19], 0, v[8:9]
	v_add_u32_e32 v19, s31, v19
	v_mad_i64_i32 v[16:17], s[18:19], v94, s30, v[92:93]
	v_mad_i64_i32 v[14:15], s[18:19], v95, s30, v[92:93]
	v_mad_i64_i32 v[12:13], s[18:19], v96, s30, v[92:93]
	v_mad_i64_i32 v[10:11], s[18:19], v19, s30, v[92:93]
	global_load_ushort v19, v[16:17], off
	global_load_ushort v92, v[16:17], off offset:32
	global_load_ushort v93, v[16:17], off offset:64
	global_load_ushort v94, v[16:17], off offset:96
	global_load_ushort v95, v[14:15], off
	global_load_ushort v96, v[14:15], off offset:32
	global_load_ushort v97, v[14:15], off offset:64
	global_load_ushort v98, v[14:15], off offset:96
	global_load_ushort v99, v[12:13], off
	global_load_ushort v100, v[12:13], off offset:32
	global_load_ushort v101, v[12:13], off offset:64
	global_load_ushort v102, v[12:13], off offset:96
	global_load_ushort v103, v[10:11], off
	global_load_ushort v104, v[10:11], off offset:32
	global_load_ushort v105, v[10:11], off offset:64
	global_load_ushort v106, v[10:11], off offset:96
	s_add_i32 s2, s2, s3
	s_add_i32 s20, s20, s21
	s_add_i32 s22, s22, s23
	s_cmpk_lt_i32 s2, 0x400
	s_waitcnt vmcnt(33)
	s_waitcnt vmcnt(32)
	s_waitcnt vmcnt(30)
	s_waitcnt vmcnt(27)
	s_waitcnt vmcnt(25)
	s_waitcnt vmcnt(24)
	s_waitcnt vmcnt(23)
	s_waitcnt vmcnt(22)
	s_waitcnt vmcnt(20)
	v_cvt_pk_bf16_f32 v23, v22, v23
	v_cvt_pk_bf16_f32 v22, v20, v21
	v_cvt_pk_bf16_f32 v21, v26, v27
	v_cvt_pk_bf16_f32 v20, v24, v25
	v_cvt_pk_bf16_f32 v27, v34, v35
	v_cvt_pk_bf16_f32 v26, v32, v33
	v_cvt_pk_bf16_f32 v25, v30, v31
	v_cvt_pk_bf16_f32 v24, v28, v29
	v_cvt_pk_bf16_f32 v28, v44, v44
	v_cvt_pk_bf16_f32 v30, v45, v45
	v_cvt_pk_bf16_f32 v29, v46, v46
	v_cvt_pk_bf16_f32 v31, v47, v47
	v_cvt_pk_bf16_f32 v32, v36, v36
	v_cvt_pk_bf16_f32 v33, v37, v37
	v_cvt_pk_bf16_f32 v34, v38, v38
	v_cvt_pk_bf16_f32 v35, v39, v39
	v_cvt_pk_bf16_f32 v36, v40, v40
	v_cvt_pk_bf16_f32 v37, v41, v41
	v_cvt_pk_bf16_f32 v38, v42, v42
	v_cvt_pk_bf16_f32 v39, v43, v43
	v_cvt_pk_bf16_f32 v40, v52, v52
	v_cvt_pk_bf16_f32 v41, v53, v53
	v_cvt_pk_bf16_f32 v42, v54, v54
	v_cvt_pk_bf16_f32 v43, v55, v55
	v_cvt_pk_bf16_f32 v44, v48, v48
	v_cvt_pk_bf16_f32 v45, v49, v49
	v_cvt_pk_bf16_f32 v46, v50, v50
	v_cvt_pk_bf16_f32 v47, v51, v51
	v_cvt_pk_bf16_f32 v48, v56, v56
	v_cvt_pk_bf16_f32 v49, v57, v57
	v_cvt_pk_bf16_f32 v50, v58, v58
	v_cvt_pk_bf16_f32 v51, v59, v59
	v_perm_b32 v29, v31, v29, s27
	v_perm_b32 v28, v30, v28, s27
	v_perm_b32 v31, v35, v34, s27
	v_perm_b32 v30, v33, v32, s27
	v_perm_b32 v33, v39, v38, s27
	v_perm_b32 v32, v37, v36, s27
	v_perm_b32 v37, v47, v46, s27
	v_perm_b32 v36, v45, v44, s27
	v_perm_b32 v39, v51, v50, s27
	v_perm_b32 v38, v49, v48, s27
	v_cvt_pk_bf16_f32 v45, v74, v75
	v_cvt_pk_bf16_f32 v44, v72, v73
	v_cvt_pk_bf16_f32 v47, v70, v71
	s_waitcnt vmcnt(17)
	v_mfma_f32_16x16x32_bf16 v[20:23], v[84:87], v[20:23], 0
	v_cvt_pk_bf16_f32 v46, v68, v69
	v_mfma_f32_16x16x32_bf16 v[28:31], v[84:87], v[28:31], 0
	v_mfma_f32_16x16x32_bf16 v[36:39], v[84:87], v[36:39], 0
	v_mfma_f32_16x16x32_bf16 v[44:47], v[84:87], v[44:47], 0
	v_perm_b32 v35, v43, v42, s27
	v_perm_b32 v34, v41, v40, s27
	v_cvt_pk_bf16_f32 v41, v62, v63
	v_cvt_pk_bf16_f32 v40, v60, v61
	v_cvt_pk_bf16_f32 v43, v66, v67
	v_cvt_pk_bf16_f32 v42, v64, v65
	v_cvt_pk_bf16_f32 v49, v78, v79
	v_cvt_pk_bf16_f32 v48, v76, v77
	v_cvt_pk_bf16_f32 v51, v82, v83
	v_cvt_pk_bf16_f32 v50, v80, v81
	s_waitcnt vmcnt(16)
	v_mfma_f32_16x16x32_bf16 v[20:23], v[88:91], v[24:27], v[20:23]
	s_waitcnt vmcnt(15)
	v_lshlrev_b32_e32 v19, 16, v19
	s_waitcnt vmcnt(14)
	v_lshlrev_b32_e32 v52, 16, v92
	s_waitcnt vmcnt(13)
	v_lshlrev_b32_e32 v53, 16, v93
	v_mfma_f32_16x16x32_bf16 v[24:27], v[88:91], v[32:35], v[28:31]
	s_waitcnt vmcnt(12)
	v_lshlrev_b32_e32 v54, 16, v94
	s_waitcnt vmcnt(11)
	v_lshlrev_b32_e32 v55, 16, v95
	s_waitcnt vmcnt(10)
	v_lshlrev_b32_e32 v56, 16, v96
	v_mfma_f32_16x16x32_bf16 v[28:31], v[88:91], v[40:43], v[36:39]
	s_waitcnt vmcnt(9)
	v_lshlrev_b32_e32 v57, 16, v97
	s_waitcnt vmcnt(8)
	v_lshlrev_b32_e32 v58, 16, v98
	s_waitcnt vmcnt(7)
	v_lshlrev_b32_e32 v59, 16, v99
	v_mfma_f32_16x16x32_bf16 v[32:35], v[88:91], v[48:51], v[44:47]
	s_waitcnt vmcnt(6)
	v_lshlrev_b32_e32 v60, 16, v100
	s_waitcnt vmcnt(5)
	v_lshlrev_b32_e32 v61, 16, v101
	s_waitcnt vmcnt(4)
	v_lshlrev_b32_e32 v62, 16, v102
	s_waitcnt vmcnt(3)
	v_lshlrev_b32_e32 v63, 16, v103
	s_waitcnt vmcnt(2)
	v_lshlrev_b32_e32 v36, 16, v104
	s_waitcnt vmcnt(1)
	v_lshlrev_b32_e32 v37, 16, v105
	s_waitcnt vmcnt(0)
	v_lshlrev_b32_e32 v38, 16, v106
	v_add_f32_e32 v19, v20, v19
	v_add_f32_e32 v20, v24, v52
	v_add_f32_e32 v24, v28, v53
	v_add_f32_e32 v28, v32, v54
	v_add_f32_e32 v21, v21, v55
	v_add_f32_e32 v25, v25, v56
	v_add_f32_e32 v29, v29, v57
	v_add_f32_e32 v32, v33, v58
	v_add_f32_e32 v22, v22, v59
	v_add_f32_e32 v26, v26, v60
	v_add_f32_e32 v30, v30, v61
	v_add_f32_e32 v33, v34, v62
	v_add_f32_e32 v23, v23, v63
	v_add_f32_e32 v27, v27, v36
	v_add_f32_e32 v31, v31, v37
	v_add_f32_e32 v34, v35, v38
	v_cvt_pk_bf16_f32 v19, v19, v19
	v_cvt_pk_bf16_f32 v20, v20, v20
	v_cvt_pk_bf16_f32 v24, v24, v24
	v_cvt_pk_bf16_f32 v28, v28, v28
	v_cvt_pk_bf16_f32 v21, v21, v21
	v_cvt_pk_bf16_f32 v25, v25, v25
	v_cvt_pk_bf16_f32 v29, v29, v29
	v_cvt_pk_bf16_f32 v32, v32, v32
	v_cvt_pk_bf16_f32 v22, v22, v22
	v_cvt_pk_bf16_f32 v26, v26, v26
	v_cvt_pk_bf16_f32 v30, v30, v30
	v_cvt_pk_bf16_f32 v33, v33, v33
	v_cvt_pk_bf16_f32 v23, v23, v23
	v_cvt_pk_bf16_f32 v27, v27, v27
	v_cvt_pk_bf16_f32 v31, v31, v31
	v_cvt_pk_bf16_f32 v34, v34, v34
	global_store_short_d16_hi v[16:17], v19, off
	global_store_short_d16_hi v[16:17], v20, off offset:32
	global_store_short_d16_hi v[16:17], v24, off offset:64
	global_store_short_d16_hi v[16:17], v28, off offset:96
	global_store_short_d16_hi v[14:15], v21, off
	global_store_short_d16_hi v[14:15], v25, off offset:32
	global_store_short_d16_hi v[14:15], v29, off offset:64
	global_store_short_d16_hi v[14:15], v32, off offset:96
	global_store_short_d16_hi v[12:13], v22, off
	global_store_short_d16_hi v[12:13], v26, off offset:32
	global_store_short_d16_hi v[12:13], v30, off offset:64
	global_store_short_d16_hi v[12:13], v33, off offset:96
	global_store_short_d16_hi v[10:11], v23, off
	global_store_short_d16_hi v[10:11], v27, off offset:32
	global_store_short_d16_hi v[10:11], v31, off offset:64
	global_store_short_d16_hi v[10:11], v34, off offset:96
	s_cbranch_scc1 .LBB0_2777

.LBB0_2833:
	v_lshl_add_u64 v[128:129], v[174:175], 0, v[176:177]
	v_lshl_add_u64 v[182:183], v[180:181], 0, v[176:177]
	global_load_dwordx4 v[112:115], v[128:129], off offset:2048
	global_load_dwordx4 v[116:119], v[182:183], off offset:1024
	global_load_dwordx4 v[120:123], v[182:183], off offset:1792
	global_load_dwordx4 v[124:127], v[128:129], off offset:1280
	s_waitcnt vmcnt(2)
	v_and_b32_e32 v135, 0xffff0000, v117
	v_lshlrev_b32_e32 v63, 16, v112
	s_waitcnt vmcnt(0)
	v_lshlrev_b32_e32 v69, 16, v125
	s_waitcnt lgkmcnt(0)
	v_lshlrev_b32_e32 v71, 16, v124
	v_lshlrev_b32_e32 v61, 16, v113
	v_and_b32_e32 v131, 0xffff0000, v113
	v_and_b32_e32 v130, 0xffff0000, v112
	v_and_b32_e32 v113, 0xffff0000, v115
	v_and_b32_e32 v112, 0xffff0000, v114
	v_mul_f32_e32 v77, v68, v63
	v_mul_f32_e32 v63, 0xbfb8aa3b, v71
	v_mul_f32_e32 v79, 0xbfb8aa3b, v69
	v_lshlrev_b32_e32 v138, 16, v122
	v_lshlrev_b32_e32 v139, 16, v123
	v_and_b32_e32 v133, 0xffff0000, v123
	v_and_b32_e32 v132, 0xffff0000, v122
	v_and_b32_e32 v73, 0xffff0000, v125
	v_and_b32_e32 v75, 0xffff0000, v124
	v_pk_mul_f32 v[122:123], v[154:155], v[112:113]
	v_exp_f32_e32 v112, v63
	v_exp_f32_e32 v113, v79
	v_mul_f32_e32 v124, 0xbfb8aa3b, v75
	v_mul_f32_e32 v125, 0xbfb8aa3b, v73
	v_exp_f32_e32 v124, v124
	v_exp_f32_e32 v125, v125
	v_pk_add_f32 v[112:113], v[112:113], 1.0 op_sel_hi:[1,0]
	v_lshlrev_b32_e32 v65, 16, v114
	v_lshlrev_b32_e32 v67, 16, v115
	v_lshlrev_b32_e32 v114, 16, v116
	v_lshlrev_b32_e32 v115, 16, v117
	v_and_b32_e32 v134, 0xffff0000, v116
	v_lshlrev_b32_e32 v136, 16, v118
	v_lshlrev_b32_e32 v137, 16, v119
	v_and_b32_e32 v117, 0xffff0000, v119
	v_and_b32_e32 v116, 0xffff0000, v118
	v_lshlrev_b32_e32 v118, 16, v120
	v_lshlrev_b32_e32 v119, 16, v121
	v_and_b32_e32 v121, 0xffff0000, v121
	v_and_b32_e32 v120, 0xffff0000, v120
	v_pk_add_f32 v[118:119], v[114:115], v[118:119]
	v_pk_add_f32 v[114:115], v[134:135], v[120:121]
	v_pk_add_f32 v[120:121], v[124:125], 1.0 op_sel_hi:[1,0]
	v_div_scale_f32 v124, s[6:7], v112, v112, v71
	v_rcp_f32_e32 v142, v113
	v_div_scale_f32 v134, s[8:9], v121, v121, v73
	v_rcp_f32_e32 v143, v124
	v_rcp_f32_e32 v144, v134
	v_fma_f32 v186, -v124, v143, 1.0
	v_div_scale_f32 v125, s[6:7], v71, v112, v71
	v_fma_f32 v187, -v134, v144, 1.0
	v_fmac_f32_e32 v143, v186, v143
	v_div_scale_f32 v135, s[8:9], v73, v121, v73
	v_fmac_f32_e32 v144, v187, v144
	v_mul_f32_e32 v186, v125, v143
	v_mul_f32_e32 v187, v135, v144
	v_fma_f32 v190, -v124, v186, v125
	v_div_scale_f32 v140, s[10:11], v120, v120, v75
	v_fma_f32 v191, -v134, v187, v135
	v_fmac_f32_e32 v186, v190, v143
	v_rcp_f32_e32 v184, v140
	v_fmac_f32_e32 v187, v191, v144
	v_fma_f32 v79, -v124, v186, v125
	v_mul_f32_e32 v125, v69, v142
	s_mov_b64 vcc, s[6:7]
	v_fma_f32 v134, -v134, v187, v135
	v_div_fmas_f32 v63, v79, v143, v186
	s_mov_b64 vcc, s[8:9]
	v_div_fixup_f32 v124, v63, v112, v71
	v_div_fmas_f32 v63, v134, v144, v187
	v_lshlrev_b32_e32 v71, 16, v126
	v_div_fixup_f32 v121, v63, v121, v73
	v_lshlrev_b32_e32 v69, 16, v127
	v_mul_f32_e32 v73, 0xbfb8aa3b, v71
	v_fma_f32 v188, -v140, v184, 1.0
	v_exp_f32_e32 v112, v73
	v_mul_f32_e32 v73, 0xbfb8aa3b, v69
	v_div_scale_f32 v141, s[10:11], v75, v120, v75
	v_fmac_f32_e32 v184, v188, v184
	v_exp_f32_e32 v113, v73
	v_mul_f32_e32 v188, v141, v184
	v_fma_f32 v192, -v140, v188, v141
	v_fmac_f32_e32 v188, v192, v184
	v_fma_f32 v63, -v140, v188, v141
	s_mov_b64 vcc, s[10:11]
	v_pk_add_f32 v[134:135], v[112:113], 1.0 op_sel_hi:[1,0]
	v_div_fmas_f32 v63, v63, v184, v188
	v_div_fixup_f32 v120, v63, v120, v75
	v_rcp_f32_e32 v75, v135
	v_cmp_gt_i32_e32 vcc, s2, v204
	v_and_b32_e32 v79, 0xffff0000, v127
	v_and_b32_e32 v140, 0xffff0000, v126
	v_cndmask_b32_e32 v63, v29, v31, vcc
	v_cndmask_b32_e32 v198, v41, v43, vcc
	v_or_b32_e32 v141, 2, v198
	v_and_b32_e32 v63, v63, v204
	v_cmp_lt_u32_e32 vcc, 1, v63
	v_cmp_lt_u32_e64 s[6:7], v63, v141
	s_and_b64 s[6:7], vcc, s[6:7]
	v_pk_add_f32 v[112:113], v[136:137], v[138:139]
	v_cndmask_b32_e64 v127, 0, -1, s[6:7]
	v_cndmask_b32_e64 v126, 0, v45, s[6:7]
	v_lshl_add_u64 v[126:127], v[128:129], 0, v[126:127]
	global_load_dwordx4 v[186:189], v[126:127], off offset:2048
	v_add_u32_e32 v126, 1, v63
	v_cmp_ne_u32_e64 s[8:9], 0, v63
	v_cmp_lt_u32_e64 s[10:11], v126, v141
	s_and_b64 s[8:9], s[8:9], s[10:11]
	v_cndmask_b32_e64 v127, 0, -1, s[8:9]
	v_cndmask_b32_e64 v126, 0, v47, s[8:9]
	v_lshl_add_u64 v[126:127], v[128:129], 0, v[126:127]
	global_load_dwordx4 v[190:193], v[126:127], off offset:2048
	v_rcp_f32_e32 v142, v134
	v_mul_f32_e32 v127, v69, v75
	v_pk_add_f32 v[116:117], v[116:117], v[132:133]
	v_mul_f32_e32 v75, 0xbfb8aa3b, v140
	v_exp_f32_e32 v136, v75
	v_mul_f32_e32 v75, 0xbfb8aa3b, v79
	v_exp_f32_e32 v137, v75
	v_add_u32_e32 v126, 3, v63
	v_cmp_lt_u32_e64 s[12:13], v126, v141
	v_mul_f32_e32 v126, v71, v142
	v_pk_add_f32 v[136:137], v[136:137], 1.0 op_sel_hi:[1,0]
	v_cndmask_b32_e64 v144, 0, v49, s[12:13]
	v_lshl_add_u64 v[138:139], v[128:129], 0, v[144:145]
	v_add_u32_e32 v73, 4, v63
	global_load_dwordx4 v[194:197], v[138:139], off offset:2048
	v_cmp_lt_u32_e64 s[10:11], v73, v141
	v_rcp_f32_e32 v71, v137
	v_mul_f32_e32 v61, v70, v61
	v_cndmask_b32_e64 v144, 0, v51, s[10:11]
	v_lshl_add_u64 v[128:129], v[128:129], 0, v[144:145]
	global_load_dwordx4 v[132:135], v[128:129], off offset:2048
	v_rcp_f32_e32 v128, v136
	v_mul_f32_e32 v141, v79, v71
	v_mul_f32_e32 v65, v44, v65
	v_mul_f32_e32 v140, v140, v128
	v_cmp_lt_u32_e32 vcc, v63, v198
	v_pk_mul_f32 v[130:131], v[166:167], v[130:131]
	v_mul_f32_e32 v67, v46, v67
	v_cndmask_b32_e32 v61, 0, v61, vcc
	v_cndmask_b32_e32 v65, 0, v65, vcc
	v_cndmask_b32_e32 v131, 0, v131, vcc
	v_cndmask_b32_e32 v130, 0, v130, vcc
	s_waitcnt vmcnt(3)
	v_lshlrev_b32_e32 v71, 16, v187
	v_mul_f32_e32 v71, v62, v71
	v_lshlrev_b32_e32 v73, 16, v186
	v_cndmask_b32_e64 v71, 0, v71, s[6:7]
	v_mul_f32_e32 v73, v60, v73
	v_add_f32_e32 v71, v58, v71
	v_cndmask_b32_e64 v73, 0, v73, s[6:7]
	v_add_f32_e32 v73, v56, v73
	v_and_b32_e32 v129, 0xffff0000, v187
	v_and_b32_e32 v128, 0xffff0000, v186
	v_pk_mul_f32 v[128:129], v[162:163], v[128:129]
	v_cndmask_b32_e32 v67, 0, v67, vcc
	v_cndmask_b32_e64 v129, 0, v129, s[6:7]
	v_cndmask_b32_e64 v128, 0, v128, s[6:7]
	s_waitcnt vmcnt(2)
	v_lshlrev_b32_e32 v75, 16, v191
	v_mul_f32_e32 v75, v66, v75
	v_lshlrev_b32_e32 v79, 16, v190
	v_cndmask_b32_e64 v75, 0, v75, s[8:9]
	v_mul_f32_e32 v79, v64, v79
	v_add_f32_e32 v71, v71, v75
	v_cndmask_b32_e64 v79, 0, v79, s[8:9]
	v_add_f32_e32 v61, v71, v61
	v_add_f32_e32 v73, v73, v79
	v_cndmask_b32_e32 v75, 0, v77, vcc
	v_add_f32_e32 v73, v73, v75
	v_lshlrev_b32_e32 v77, 16, v192
	v_and_b32_e32 v143, 0xffff0000, v191
	v_and_b32_e32 v142, 0xffff0000, v190
	v_mul_f32_e32 v77, v28, v77
	v_pk_mul_f32 v[142:143], v[164:165], v[142:143]
	v_lshlrev_b32_e32 v79, 16, v193
	v_cndmask_b32_e64 v77, 0, v77, s[8:9]
	v_pk_add_f32 v[128:129], v[160:161], v[128:129]
	v_cndmask_b32_e64 v143, 0, v143, s[8:9]
	v_cndmask_b32_e64 v142, 0, v142, s[8:9]
	v_pk_add_f32 v[128:129], v[128:129], v[142:143]
	v_cndmask_b32_e32 v123, 0, v123, vcc
	v_pk_add_f32 v[128:129], v[128:129], v[130:131]
	v_cndmask_b32_e32 v122, 0, v122, vcc
	v_add_u32_e32 v69, -1, v198
	v_lshl_add_u64 v[184:185], v[180:181], 0, v[172:173]
	s_waitcnt vmcnt(1)
	v_lshlrev_b32_e32 v71, 16, v195
	v_mul_f32_e32 v71, v74, v71
	v_lshlrev_b32_e32 v75, 16, v194
	v_cndmask_b32_e64 v71, 0, v71, s[12:13]
	v_mul_f32_e32 v75, v72, v75
	v_add_f32_e32 v61, v61, v71
	s_waitcnt vmcnt(0)
	v_lshlrev_b32_e32 v71, 16, v133
	v_cndmask_b32_e64 v75, 0, v75, s[12:13]
	v_mul_f32_e32 v71, v78, v71
	v_add_f32_e32 v73, v73, v75
	v_lshlrev_b32_e32 v75, 16, v132
	v_cndmask_b32_e64 v71, 0, v71, s[10:11]
	v_mul_f32_e32 v75, v76, v75
	v_add_f32_e32 v61, v61, v71
	v_lshlrev_b32_e32 v71, 16, v188
	v_cndmask_b32_e64 v75, 0, v75, s[10:11]
	v_mul_f32_e32 v71, v24, v71
	v_add_f32_e32 v73, v73, v75
	v_lshlrev_b32_e32 v75, 16, v189
	v_cndmask_b32_e64 v71, 0, v71, s[6:7]
	v_add_f32_e32 v71, v40, v71
	v_mul_f32_e32 v75, v26, v75
	v_cndmask_b32_e64 v75, 0, v75, s[6:7]
	v_add_f32_e32 v71, v71, v77
	v_mul_f32_e32 v77, v30, v79
	v_add_f32_e32 v75, v42, v75
	v_cndmask_b32_e64 v77, 0, v77, s[8:9]
	v_add_f32_e32 v65, v71, v65
	v_lshlrev_b32_e32 v71, 16, v196
	v_and_b32_e32 v131, 0xffff0000, v195
	v_and_b32_e32 v130, 0xffff0000, v194
	v_add_f32_e32 v75, v75, v77
	v_mul_f32_e32 v71, v48, v71
	v_pk_mul_f32 v[130:131], v[168:169], v[130:131]
	v_add_f32_e32 v67, v75, v67
	v_lshlrev_b32_e32 v75, 16, v197
	v_cndmask_b32_e64 v71, 0, v71, s[12:13]
	v_cndmask_b32_e64 v131, 0, v131, s[12:13]
	v_cndmask_b32_e64 v130, 0, v130, s[12:13]
	v_add_f32_e32 v65, v65, v71
	v_mul_f32_e32 v71, v50, v75
	v_pk_add_f32 v[128:129], v[128:129], v[130:131]
	v_and_b32_e32 v131, 0xffff0000, v133
	v_and_b32_e32 v130, 0xffff0000, v132
	v_cndmask_b32_e64 v71, 0, v71, s[12:13]
	v_pk_mul_f32 v[130:131], v[170:171], v[130:131]
	v_add_f32_e32 v67, v67, v71
	v_lshlrev_b32_e32 v71, 16, v134
	v_cndmask_b32_e64 v131, 0, v131, s[10:11]
	v_cndmask_b32_e64 v130, 0, v130, s[10:11]
	v_mul_f32_e32 v71, v52, v71
	v_pk_add_f32 v[128:129], v[128:129], v[130:131]
	v_and_b32_e32 v131, 0xffff0000, v189
	v_and_b32_e32 v130, 0xffff0000, v188
	v_lshlrev_b32_e32 v75, 16, v135
	v_cndmask_b32_e64 v71, 0, v71, s[10:11]
	v_pk_mul_f32 v[130:131], v[34:35], v[130:131]
	v_and_b32_e32 v133, 0xffff0000, v193
	v_and_b32_e32 v132, 0xffff0000, v192
	v_add_f32_e32 v65, v65, v71
	v_mul_f32_e32 v71, v54, v75
	v_cndmask_b32_e64 v131, 0, v131, s[6:7]
	v_cndmask_b32_e64 v130, 0, v130, s[6:7]
	v_pk_mul_f32 v[132:133], v[38:39], v[132:133]
	v_cndmask_b32_e64 v71, 0, v71, s[10:11]
	v_pk_add_f32 v[130:131], v[22:23], v[130:131]
	v_cndmask_b32_e64 v133, 0, v133, s[8:9]
	v_cndmask_b32_e64 v132, 0, v132, s[8:9]
	v_add_f32_e32 v67, v67, v71
	v_mul_f32_e32 v71, 0xbfb8aa3b, v73
	v_pk_add_f32 v[130:131], v[130:131], v[132:133]
	v_exp_f32_e32 v132, v71
	v_mul_f32_e32 v71, 0xbfb8aa3b, v61
	v_exp_f32_e32 v133, v71
	v_pk_add_f32 v[122:123], v[130:131], v[122:123]
	v_and_b32_e32 v131, 0xffff0000, v197
	v_and_b32_e32 v130, 0xffff0000, v196
	v_pk_mul_f32 v[130:131], v[156:157], v[130:131]
	v_mul_f32_e32 v71, 0xbfb8aa3b, v128
	v_cndmask_b32_e64 v131, 0, v131, s[12:13]
	v_cndmask_b32_e64 v130, 0, v130, s[12:13]
	v_pk_add_f32 v[122:123], v[122:123], v[130:131]
	v_and_b32_e32 v130, 0xffff0000, v134
	v_exp_f32_e32 v134, v71
	v_pk_add_f32 v[132:133], v[132:133], 1.0 op_sel_hi:[1,0]
	v_mul_f32_e32 v71, 0xbfb8aa3b, v129
	v_and_b32_e32 v131, 0xffff0000, v135
	v_exp_f32_e32 v135, v71
	v_rcp_f32_e32 v75, v133
	v_pk_mul_f32 v[130:131], v[158:159], v[130:131]
	v_cmp_lt_u32_e64 s[8:9], v63, v69
	v_cndmask_b32_e64 v131, 0, v131, s[10:11]
	v_cndmask_b32_e64 v130, 0, v130, s[10:11]
	v_pk_add_f32 v[142:143], v[122:123], v[130:131]
	v_rcp_f32_e32 v130, v132
	v_mul_f32_e32 v131, v61, v75
	v_pk_add_f32 v[122:123], v[134:135], 1.0 op_sel_hi:[1,0]
	v_mul_f32_e32 v130, v73, v130
	v_rcp_f32_e32 v71, v123
	v_pk_fma_f32 v[118:119], v[146:147], v[130:131], v[118:119]
	global_load_dwordx4 v[200:203], v[184:185], off
	global_load_dwordx4 v[206:209], v[184:185], off offset:512
	v_rcp_f32_e32 v79, v122
	v_mul_f32_e32 v61, v129, v71
	v_pk_mul_f32 v[186:187], v[118:119], v[124:125]
	v_mov_b32_e32 v119, v61
	v_mul_f32_e32 v118, v128, v79
	v_pk_fma_f32 v[114:115], v[146:147], v[118:119], v[114:115]
	v_mul_f32_e32 v71, 0xbfb8aa3b, v65
	v_pk_mul_f32 v[188:189], v[114:115], v[120:121]
	v_exp_f32_e32 v114, v71
	v_mul_f32_e32 v71, 0xbfb8aa3b, v67
	v_exp_f32_e32 v115, v71
	v_mul_f32_e32 v71, 0xbfb8aa3b, v142
	v_exp_f32_e32 v118, v71
	v_mul_f32_e32 v71, 0xbfb8aa3b, v143
	v_pk_add_f32 v[114:115], v[114:115], 1.0 op_sel_hi:[1,0]
	v_exp_f32_e32 v119, v71
	v_rcp_f32_e32 v75, v115
	v_pk_add_f32 v[118:119], v[118:119], 1.0 op_sel_hi:[1,0]
	v_lshl_add_u64 v[138:139], v[174:175], 0, v[172:173]
	v_cndmask_b32_e64 v144, 0, v49, s[8:9]
	v_rcp_f32_e32 v122, v114
	v_mul_f32_e32 v115, v67, v75
	v_lshl_add_u64 v[220:221], v[138:139], 0, v[144:145]
	v_mul_f32_e32 v114, v65, v122
	v_rcp_f32_e32 v67, v119
	v_cmp_eq_u32_e64 s[6:7], 0, v63
	v_pk_fma_f32 v[112:113], v[146:147], v[114:115], v[112:113]
	global_load_dwordx4 v[210:213], v[138:139], off offset:3872
	v_div_scale_f32 v65, s[10:11], v118, v118, v142
	v_cndmask_b32_e64 v121, -1, 0, s[6:7]
	v_cndmask_b32_e64 v120, v47, 0, s[6:7]
	v_rcp_f32_e32 v69, v65
	v_lshl_add_u64 v[218:219], v[138:139], 0, v[120:121]
	v_pk_mul_f32 v[190:191], v[112:113], v[126:127]
	global_load_dwordx4 v[112:115], v[138:139], off offset:3360
	global_load_dwordx4 v[120:123], v[218:219], off offset:3360
	global_load_dwordx4 v[124:127], v[220:221], off offset:3360
	v_mul_f32_e32 v119, v143, v67
	v_fma_f32 v63, -v65, v69, 1.0
	v_fmac_f32_e32 v69, v63, v69
	v_div_scale_f32 v63, vcc, v142, v118, v142
	v_mul_f32_e32 v67, v63, v69
	global_load_dwordx4 v[128:131], v[218:219], off offset:3872
	global_load_dwordx4 v[132:135], v[220:221], off offset:3872
	v_fma_f32 v75, -v65, v67, v63
	v_fmac_f32_e32 v67, v75, v69
	v_fma_f32 v63, -v65, v67, v63
	v_div_fmas_f32 v63, v63, v69, v67
	v_div_fixup_f32 v118, v63, v118, v142
	v_lshl_add_u64 v[136:137], v[178:179], 0, v[172:173]
	v_pk_fma_f32 v[116:117], v[146:147], v[118:119], v[116:117]
	global_load_dwordx4 v[214:217], v[136:137], off offset:1536
	v_pk_mul_f32 v[192:193], v[116:117], v[140:141]
	global_load_dwordx4 v[140:143], v[136:137], off offset:1024
	s_waitcnt vmcnt(9)
	v_and_b32_e32 v117, 0xffff0000, v201
	v_and_b32_e32 v116, 0xffff0000, v200
	s_waitcnt vmcnt(8)
	v_and_b32_e32 v119, 0xffff0000, v207
	v_and_b32_e32 v118, 0xffff0000, v206
	v_pk_add_f32 v[196:197], v[116:117], v[118:119]
	v_lshlrev_b32_e32 v117, 16, v201
	v_lshlrev_b32_e32 v116, 16, v200
	v_lshlrev_b32_e32 v119, 16, v207
	v_lshlrev_b32_e32 v118, 16, v206
	v_pk_add_f32 v[198:199], v[116:117], v[118:119]
	v_and_b32_e32 v117, 0xffff0000, v203
	v_and_b32_e32 v116, 0xffff0000, v202
	v_and_b32_e32 v119, 0xffff0000, v209
	v_and_b32_e32 v118, 0xffff0000, v208
	v_pk_add_f32 v[200:201], v[116:117], v[118:119]
	v_lshlrev_b32_e32 v117, 16, v203
	v_lshlrev_b32_e32 v116, 16, v202
	v_lshlrev_b32_e32 v119, 16, v209
	v_lshlrev_b32_e32 v118, 16, v208
	v_cndmask_b32_e64 v195, 0, 0.5, s[8:9]
	v_cndmask_b32_e64 v194, 0.5, 0, s[6:7]
	v_pk_add_f32 v[202:203], v[116:117], v[118:119]
	v_add_f32_e32 v69, 0, v198
	v_add_f32_e32 v69, v196, v69
	v_cndmask_b32_e64 v61, 0, v188, s[0:1]
	v_add_f32_e32 v69, v199, v69
	v_cndmask_b32_e64 v73, 0, v186, s[0:1]
	v_mul_f32_e32 v61, v61, v61
	v_add_f32_e32 v69, v197, v69
	v_cndmask_b32_e64 v77, 0, v187, s[0:1]
	v_add_f32_e32 v69, v202, v69
	v_fmac_f32_e32 v61, v73, v73
	v_cndmask_b32_e64 v79, 0, v189, s[0:1]
	v_add_f32_e32 v69, v200, v69
	v_fmac_f32_e32 v61, v77, v77
	v_cndmask_b32_e64 v71, 0, v190, s[0:1]
	v_add_f32_e32 v69, v203, v69
	v_fmac_f32_e32 v61, v79, v79
	v_cndmask_b32_e64 v63, 0, v192, s[0:1]
	v_add_f32_e32 v69, v201, v69
	v_fmac_f32_e32 v61, v71, v71
	v_fmac_f32_e32 v61, v63, v63
	v_add_f32_dpp v63, v69, v69 quad_perm:[1,0,3,2] row_mask:0xf bank_mask:0xf bound_ctrl:1
	s_waitcnt vmcnt(7)
	v_lshlrev_b32_e32 v230, 16, v212
	v_and_b32_e32 v231, 0xffff0000, v212
	v_lshlrev_b32_e32 v228, 16, v210
	v_and_b32_e32 v229, 0xffff0000, v210
	v_add_f32_dpp v63, v63, v63 quad_perm:[2,3,0,1] row_mask:0xf bank_mask:0xf bound_ctrl:1
	v_lshlrev_b32_e32 v210, 16, v211
	v_and_b32_e32 v211, 0xffff0000, v211
	v_add_f32_dpp v63, v63, v63 row_half_mirror row_mask:0xf bank_mask:0xf bound_ctrl:1
	v_mul_f32_e32 v144, 0x3c800000, v63
	v_cndmask_b32_e64 v65, 0, v191, s[0:1]
	v_cndmask_b32_e64 v67, 0, v193, s[0:1]
	v_fmac_f32_e32 v61, v65, v65
	v_fmac_f32_e32 v61, v67, v67
	v_mov_b32_e32 v67, 0
	s_waitcnt vmcnt(6)
	v_lshlrev_b32_e32 v206, 16, v112
	v_and_b32_e32 v207, 0xffff0000, v112
	v_lshlrev_b32_e32 v208, 16, v113
	v_and_b32_e32 v209, 0xffff0000, v113
	v_lshlrev_b32_e32 v222, 16, v114
	v_and_b32_e32 v223, 0xffff0000, v114
	v_lshlrev_b32_e32 v112, 16, v115
	v_and_b32_e32 v113, 0xffff0000, v115
	s_waitcnt vmcnt(5)
	v_and_b32_e32 v114, 0xffff0000, v123
	s_waitcnt vmcnt(4)
	v_lshlrev_b32_e32 v115, 16, v127
	v_and_b32_e32 v117, 0xffff0000, v127
	v_lshlrev_b32_e32 v116, 16, v123
	v_pk_mul_f32 v[114:115], v[194:195], v[114:115]
	v_and_b32_e32 v236, 0xffff0000, v120
	v_pk_fma_f32 v[114:115], v[194:195], v[116:117], v[114:115] op_sel:[0,0,1] op_sel_hi:[1,1,0]
	s_waitcnt vmcnt(2)
	v_and_b32_e32 v117, 0xffff0000, v135
	v_pk_add_f32 v[114:115], v[114:115], v[112:113] neg_lo:[0,1] neg_hi:[0,1]
	v_lshlrev_b32_e32 v116, 16, v131
	v_pk_fma_f32 v[224:225], v[106:107], v[114:115], v[112:113]
	v_and_b32_e32 v114, 0xffff0000, v131
	v_lshlrev_b32_e32 v115, 16, v135
	v_pk_mul_f32 v[114:115], v[194:195], v[114:115]
	v_lshlrev_b32_e32 v237, 16, v124
	v_lshlrev_b32_e32 v112, 16, v213
	v_and_b32_e32 v113, 0xffff0000, v213
	v_pk_fma_f32 v[114:115], v[194:195], v[116:117], v[114:115] op_sel:[0,0,1] op_sel_hi:[1,1,0]
	v_and_b32_e32 v239, 0xffff0000, v124
	v_lshlrev_b32_e32 v238, 16, v120
	v_pk_mul_f32 v[236:237], v[194:195], v[236:237]
	v_pk_add_f32 v[114:115], v[114:115], v[112:113] neg_lo:[0,1] neg_hi:[0,1]
	v_pk_fma_f32 v[236:237], v[194:195], v[238:239], v[236:237] op_sel:[0,0,1] op_sel_hi:[1,1,0]
	v_pk_fma_f32 v[212:213], v[110:111], v[114:115], v[112:113]
	v_add_co_u32_e32 v112, vcc, s2, v218
	v_pk_add_f32 v[236:237], v[236:237], v[206:207] neg_lo:[0,1] neg_hi:[0,1]
	s_nop 0
	v_addc_co_u32_e32 v113, vcc, 0, v219, vcc
	v_pk_fma_f32 v[206:207], v[96:97], v[236:237], v[206:207]
	v_and_b32_e32 v236, 0xffff0000, v128
	v_lshlrev_b32_e32 v237, 16, v132
	v_add_co_u32_e32 v116, vcc, s2, v220
	v_and_b32_e32 v239, 0xffff0000, v132
	v_lshlrev_b32_e32 v238, 16, v128
	v_pk_mul_f32 v[236:237], v[194:195], v[236:237]
	v_addc_co_u32_e32 v117, vcc, 0, v221, vcc
	s_waitcnt vmcnt(0)
	v_lshlrev_b32_e32 v220, 16, v142
	v_and_b32_e32 v221, 0xffff0000, v142
	v_lshlrev_b32_e32 v232, 16, v143
	v_and_b32_e32 v233, 0xffff0000, v143
	v_lshlrev_b32_e32 v142, 16, v214
	v_and_b32_e32 v143, 0xffff0000, v214
	v_pk_fma_f32 v[236:237], v[194:195], v[238:239], v[236:237] op_sel:[0,0,1] op_sel_hi:[1,1,0]
	v_lshlrev_b32_e32 v218, 16, v140
	v_and_b32_e32 v219, 0xffff0000, v140
	v_pk_add_f32 v[236:237], v[236:237], v[228:229] neg_lo:[0,1] neg_hi:[0,1]
	v_pk_add_f32 v[142:143], v[142:143], -1.0 op_sel_hi:[1,0]
	v_pk_fma_f32 v[228:229], v[100:101], v[236:237], v[228:229]
	v_pk_add_f32 v[218:219], v[218:219], -1.0 op_sel_hi:[1,0]
	v_pk_fma_f32 v[142:143], v[88:89], v[142:143], 1.0 op_sel_hi:[1,1,0]
	v_pk_fma_f32 v[218:219], v[88:89], v[218:219], 1.0 op_sel_hi:[1,1,0]
	v_pk_mul_f32 v[142:143], v[228:229], v[142:143]
	v_lshlrev_b32_e32 v124, 16, v121
	v_pk_fma_f32 v[142:143], v[228:229], v[218:219], v[142:143]
	v_lshlrev_b32_e32 v132, 16, v129
	v_pk_mul_f32 v[142:143], v[206:207], v[142:143]
	v_lshlrev_b32_e32 v214, 16, v215
	v_pk_mul_f32 v[142:143], v[92:93], v[142:143]
	v_and_b32_e32 v215, 0xffff0000, v215
	v_add_f32_e32 v63, 0, v142
	v_add_f32_e32 v63, v143, v63
	v_and_b32_e32 v142, 0xffff0000, v121
	v_lshlrev_b32_e32 v143, 16, v125
	v_and_b32_e32 v125, 0xffff0000, v125
	v_pk_mul_f32 v[120:121], v[194:195], v[142:143]
	v_lshlrev_b32_e32 v140, 16, v141
	v_pk_fma_f32 v[120:121], v[194:195], v[124:125], v[120:121] op_sel:[0,0,1] op_sel_hi:[1,1,0]
	v_and_b32_e32 v124, 0xffff0000, v129
	v_lshlrev_b32_e32 v125, 16, v133
	v_and_b32_e32 v133, 0xffff0000, v133
	v_pk_mul_f32 v[124:125], v[194:195], v[124:125]
	v_and_b32_e32 v141, 0xffff0000, v141
	v_pk_fma_f32 v[124:125], v[194:195], v[132:133], v[124:125] op_sel:[0,0,1] op_sel_hi:[1,1,0]
	v_pk_add_f32 v[132:133], v[214:215], -1.0 op_sel_hi:[1,0]
	v_pk_add_f32 v[124:125], v[124:125], v[210:211] neg_lo:[0,1] neg_hi:[0,1]
	v_pk_add_f32 v[128:129], v[140:141], -1.0 op_sel_hi:[1,0]
	v_pk_fma_f32 v[124:125], v[102:103], v[124:125], v[210:211]
	v_pk_fma_f32 v[132:133], v[90:91], v[132:133], 1.0 op_sel_hi:[1,1,0]
	v_pk_add_f32 v[120:121], v[120:121], v[208:209] neg_lo:[0,1] neg_hi:[0,1]
	v_pk_fma_f32 v[128:129], v[90:91], v[128:129], 1.0 op_sel_hi:[1,1,0]
	v_pk_mul_f32 v[132:133], v[124:125], v[132:133]
	v_pk_fma_f32 v[120:121], v[98:99], v[120:121], v[208:209]
	v_pk_fma_f32 v[124:125], v[124:125], v[128:129], v[132:133]
	global_load_dwordx4 v[112:115], v[112:113], off offset:288
	s_nop 0
	global_load_dwordx4 v[116:119], v[116:117], off offset:288
	v_pk_mul_f32 v[120:121], v[120:121], v[124:125]
	v_add_co_u32_e32 v124, vcc, s2, v138
	v_pk_mul_f32 v[120:121], v[94:95], v[120:121]
	s_nop 0
	v_addc_co_u32_e32 v125, vcc, 0, v139, vcc
	global_load_dwordx4 v[140:143], v[124:125], off offset:288
	s_nop 0
	global_load_dwordx4 v[136:139], v[136:137], off offset:2048
	v_add_f32_e32 v63, v120, v63
	v_add_f32_e32 v63, v121, v63
	v_and_b32_e32 v120, 0xffff0000, v122
	v_lshlrev_b32_e32 v121, 16, v126
	v_and_b32_e32 v123, 0xffff0000, v126
	v_lshlrev_b32_e32 v122, 16, v122
	v_pk_mul_f32 v[120:121], v[194:195], v[120:121]
	v_and_b32_e32 v125, 0xffff0000, v134
	v_pk_fma_f32 v[120:121], v[194:195], v[122:123], v[120:121] op_sel:[0,0,1] op_sel_hi:[1,1,0]
	v_and_b32_e32 v122, 0xffff0000, v130
	v_lshlrev_b32_e32 v123, 16, v134
	v_lshlrev_b32_e32 v124, 16, v130
	v_pk_mul_f32 v[122:123], v[194:195], v[122:123]
	v_lshlrev_b32_e32 v234, 16, v216
	v_and_b32_e32 v235, 0xffff0000, v216
	v_pk_fma_f32 v[122:123], v[194:195], v[124:125], v[122:123] op_sel:[0,0,1] op_sel_hi:[1,1,0]
	v_pk_add_f32 v[126:127], v[234:235], -1.0 op_sel_hi:[1,0]
	v_pk_add_f32 v[122:123], v[122:123], v[230:231] neg_lo:[0,1] neg_hi:[0,1]
	v_pk_add_f32 v[124:125], v[220:221], -1.0 op_sel_hi:[1,0]
	v_pk_fma_f32 v[122:123], v[108:109], v[122:123], v[230:231]
	v_pk_fma_f32 v[126:127], v[80:81], v[126:127], 1.0 op_sel_hi:[1,1,0]
	v_pk_add_f32 v[120:121], v[120:121], v[222:223] neg_lo:[0,1] neg_hi:[0,1]
	v_pk_fma_f32 v[124:125], v[80:81], v[124:125], 1.0 op_sel_hi:[1,1,0]
	v_pk_mul_f32 v[126:127], v[122:123], v[126:127]
	v_pk_fma_f32 v[120:121], v[104:105], v[120:121], v[222:223]
	v_pk_fma_f32 v[122:123], v[122:123], v[124:125], v[126:127]
	v_lshlrev_b32_e32 v216, 16, v217
	v_pk_mul_f32 v[120:121], v[120:121], v[122:123]
	v_and_b32_e32 v217, 0xffff0000, v217
	v_pk_mul_f32 v[120:121], v[84:85], v[120:121]
	v_pk_add_f32 v[122:123], v[216:217], -1.0 op_sel_hi:[1,0]
	v_add_f32_e32 v63, v120, v63
	v_add_f32_e32 v63, v121, v63
	v_pk_add_f32 v[120:121], v[232:233], -1.0 op_sel_hi:[1,0]
	v_pk_fma_f32 v[122:123], v[82:83], v[122:123], 1.0 op_sel_hi:[1,1,0]
	v_pk_fma_f32 v[120:121], v[82:83], v[120:121], 1.0 op_sel_hi:[1,1,0]
	v_pk_mul_f32 v[122:123], v[212:213], v[122:123]
	v_add_f32_dpp v61, v61, v61 row_ror:8 row_mask:0xf bank_mask:0xf bound_ctrl:1
	v_pk_fma_f32 v[120:121], v[212:213], v[120:121], v[122:123]
	v_cmp_lt_i32_e32 vcc, v53, v55
	v_pk_mul_f32 v[120:121], v[224:225], v[120:121]
	v_add_f32_dpp v61, v61, v61 row_ror:4 row_mask:0xf bank_mask:0xf bound_ctrl:1
	v_pk_mul_f32 v[120:121], v[86:87], v[120:121]
	v_cndmask_b32_e32 v69, v227, v53, vcc
	v_add_f32_e32 v63, v120, v63
	v_add_f32_dpp v61, v61, v61 row_ror:2 row_mask:0xf bank_mask:0xf bound_ctrl:1
	v_add_f32_e32 v63, v121, v63
	v_pk_add_f32 v[124:125], v[198:199], v[144:145] op_sel_hi:[1,0] neg_lo:[0,1] neg_hi:[0,1]
	v_pk_add_f32 v[120:121], v[196:197], v[144:145] op_sel_hi:[1,0] neg_lo:[0,1] neg_hi:[0,1]
	v_add_f32_dpp v61, v61, v61 row_ror:1 row_mask:0xf bank_mask:0xf bound_ctrl:1
	v_lshlrev_b32_e32 v69, 2, v69
	v_mov_b32_e32 v122, v124
	v_mov_b32_e32 v123, v120
	ds_bpermute_b32 v69, v69, v61
	v_add_f32_dpp v63, v63, v63 quad_perm:[1,0,3,2] row_mask:0xf bank_mask:0xf bound_ctrl:1
	v_pk_mul_f32 v[128:129], v[122:123], v[122:123]
	v_mov_b32_e32 v122, v121
	v_mov_b32_e32 v123, v125
	v_add_f32_dpp v65, v63, v63 quad_perm:[2,3,0,1] row_mask:0xf bank_mask:0xf bound_ctrl:1
	v_pk_mul_f32 v[130:131], v[122:123], v[122:123]
	v_pk_add_f32 v[126:127], v[202:203], v[144:145] op_sel_hi:[1,0] neg_lo:[0,1] neg_hi:[0,1]
	v_pk_add_f32 v[122:123], v[200:201], v[144:145] op_sel_hi:[1,0] neg_lo:[0,1] neg_hi:[0,1]
	v_add_f32_e32 v63, v128, v129
	v_mov_b32_e32 v132, v122
	v_mov_b32_e32 v133, v126
	v_add_f32_e32 v63, v131, v63
	v_pk_mul_f32 v[132:133], v[132:133], v[132:133]
	v_add_f32_e32 v63, v130, v63
	v_cmp_lt_i32_e32 vcc, v57, v55
	v_mov_b32_e32 v134, v123
	v_mov_b32_e32 v135, v127
	v_add_f32_e32 v63, v133, v63
	s_waitcnt lgkmcnt(0)
	v_add_f32_e32 v69, v61, v69
	v_cndmask_b32_e32 v61, v227, v57, vcc
	v_pk_mul_f32 v[134:135], v[134:135], v[134:135]
	v_add_f32_e32 v63, v132, v63
	v_lshlrev_b32_e32 v61, 2, v61
	v_add_f32_e32 v63, v135, v63
	ds_bpermute_b32 v71, v61, v69
	v_add_f32_e32 v63, v134, v63
	v_mov_b32_dpp v67, v65 row_half_mirror row_mask:0xf bank_mask:0xf
	s_nop 0
	v_add_f32_dpp v61, v63, v63 quad_perm:[1,0,3,2] row_mask:0xf bank_mask:0xf bound_ctrl:1
	v_mov_b32_e32 v63, 0
	s_nop 0
	v_add_f32_dpp v61, v61, v61 quad_perm:[2,3,0,1] row_mask:0xf bank_mask:0xf bound_ctrl:1
	s_nop 1
	v_mov_b32_dpp v63, v61 row_half_mirror row_mask:0xf bank_mask:0xf
	s_and_saveexec_b64 s[6:7], s[0:1]
	s_cbranch_execz .LBB0_2835
	s_waitcnt lgkmcnt(0)
	v_add_f32_e32 v69, v69, v71
	v_fmamk_f32 v69, v69, 0x3b2aaaab, v25
	v_mul_f32_e32 v71, 0x4b800000, v69
	v_cmp_gt_f32_e32 vcc, s22, v69
	s_nop 1
	v_cndmask_b32_e32 v69, v69, v71, vcc
	v_rsq_f32_e32 v69, v69
	s_nop 0
	v_mul_f32_e32 v71, 0x45800000, v69
	v_cndmask_b32_e32 v130, v69, v71, vcc
	v_pk_mul_f32 v[132:133], v[188:189], v[130:131] op_sel_hi:[1,0]
	v_pk_mul_f32 v[128:129], v[186:187], v[130:131] op_sel_hi:[1,0]
	v_pk_mul_f32 v[132:133], v[10:11], v[132:133]
	v_pk_mul_f32 v[128:129], v[36:37], v[128:129]
	v_and_b32_sdwa v69, v129, v59 dst_sel:DWORD dst_unused:UNUSED_PAD src0_sel:WORD_1 src1_sel:DWORD
	v_and_b32_sdwa v71, v128, v59 dst_sel:DWORD dst_unused:UNUSED_PAD src0_sel:WORD_1 src1_sel:DWORD
	v_cvt_pk_bf16_f32 v73, v133, v133
	v_cvt_pk_bf16_f32 v75, v132, v132
	v_pk_mul_f32 v[132:133], v[190:191], v[130:131] op_sel_hi:[1,0]
	v_pk_mul_f32 v[130:131], v[192:193], v[130:131] op_sel_hi:[1,0]
	v_add3_u32 v71, v128, v71, s23
	v_add3_u32 v69, v129, v69, s23
	v_and_b32_e32 v73, 0xffff0000, v73
	v_and_b32_e32 v75, 0xffff0000, v75
	v_pk_mul_f32 v[130:131], v[14:15], v[130:131]
	v_or_b32_sdwa v129, v73, v69 dst_sel:DWORD dst_unused:UNUSED_PAD src0_sel:DWORD src1_sel:WORD_1
	v_or_b32_sdwa v128, v75, v71 dst_sel:DWORD dst_unused:UNUSED_PAD src0_sel:DWORD src1_sel:WORD_1
	v_pk_mul_f32 v[132:133], v[32:33], v[132:133]
	v_and_b32_sdwa v69, v133, v59 dst_sel:DWORD dst_unused:UNUSED_PAD src0_sel:WORD_1 src1_sel:DWORD
	v_and_b32_sdwa v71, v132, v59 dst_sel:DWORD dst_unused:UNUSED_PAD src0_sel:WORD_1 src1_sel:DWORD
	v_cvt_pk_bf16_f32 v73, v131, v131
	v_cvt_pk_bf16_f32 v75, v130, v130
	v_add3_u32 v71, v132, v71, s23
	v_add3_u32 v69, v133, v69, s23
	v_and_b32_e32 v73, 0xffff0000, v73
	v_and_b32_e32 v75, 0xffff0000, v75
	v_or_b32_sdwa v131, v73, v69 dst_sel:DWORD dst_unused:UNUSED_PAD src0_sel:DWORD src1_sel:WORD_1
	v_or_b32_sdwa v130, v75, v71 dst_sel:DWORD dst_unused:UNUSED_PAD src0_sel:DWORD src1_sel:WORD_1
	global_store_dwordx4 v[182:183], v[128:131], off
.LBB0_2835:
	s_or_b64 exec, exec, s[6:7]
	s_and_saveexec_b64 s[6:7], s[4:5]
	s_cbranch_execz .LBB0_2832
	s_waitcnt vmcnt(2)
	v_lshlrev_b32_e32 v129, 16, v116
	v_lshlrev_b32_e32 v128, 16, v112
	v_lshlrev_b32_e32 v133, 16, v117
	v_lshlrev_b32_e32 v132, 16, v113
	v_pk_mul_f32 v[128:129], v[194:195], v[128:129]
	v_and_b32_e32 v131, 0xffff0000, v116
	v_and_b32_e32 v130, 0xffff0000, v112
	v_pk_mul_f32 v[132:133], v[194:195], v[132:133]
	v_and_b32_e32 v117, 0xffff0000, v117
	v_and_b32_e32 v116, 0xffff0000, v113
	v_add_f32_e32 v61, v61, v63
	v_pk_mul_f32 v[130:131], v[194:195], v[130:131]
	v_pk_mul_f32 v[112:113], v[194:195], v[116:117]
	v_mov_b32_e32 v188, v128
	v_mov_b32_e32 v189, v132
	v_mov_b32_e32 v132, v129
	v_fmamk_f32 v61, v61, 0x3c800000, v27
	v_pk_add_f32 v[128:129], v[188:189], v[132:133]
	v_mov_b32_e32 v132, v130
	v_mov_b32_e32 v133, v112
	v_mov_b32_e32 v112, v131
	v_mul_f32_e32 v63, 0x4b800000, v61
	v_cmp_gt_f32_e32 vcc, s22, v61
	v_lshlrev_b32_e32 v117, 16, v118
	v_lshlrev_b32_e32 v116, 16, v114
	v_lshlrev_b32_e32 v183, 16, v119
	v_lshlrev_b32_e32 v182, 16, v115
	s_waitcnt vmcnt(1)
	v_lshlrev_b32_e32 v187, 16, v141
	v_lshlrev_b32_e32 v186, 16, v140
	v_and_b32_e32 v141, 0xffff0000, v141
	v_and_b32_e32 v140, 0xffff0000, v140
	v_pk_add_f32 v[112:113], v[132:133], v[112:113]
	v_cndmask_b32_e32 v61, v61, v63, vcc
	v_pk_mul_f32 v[116:117], v[194:195], v[116:117]
	v_pk_mul_f32 v[182:183], v[194:195], v[182:183]
	v_pk_add_f32 v[112:113], v[112:113], v[140:141] neg_lo:[0,1] neg_hi:[0,1]
	v_rsq_f32_e32 v61, v61
	v_pk_fma_f32 v[112:113], v[152:153], v[112:113], v[140:141]
	s_waitcnt vmcnt(0)
	v_lshlrev_b32_e32 v131, 16, v137
	v_lshlrev_b32_e32 v130, 16, v136
	v_and_b32_e32 v133, 0xffff0000, v137
	v_and_b32_e32 v132, 0xffff0000, v136
	v_lshlrev_b32_e32 v137, 16, v143
	v_lshlrev_b32_e32 v136, 16, v142
	v_and_b32_e32 v141, 0xffff0000, v143
	v_and_b32_e32 v140, 0xffff0000, v142
	v_mov_b32_e32 v142, v116
	v_mov_b32_e32 v143, v182
	v_mov_b32_e32 v182, v117
	v_and_b32_e32 v135, 0xffff0000, v118
	v_and_b32_e32 v134, 0xffff0000, v114
	v_and_b32_e32 v119, 0xffff0000, v119
	v_and_b32_e32 v118, 0xffff0000, v115
	v_pk_add_f32 v[116:117], v[142:143], v[182:183]
	v_pk_mul_f32 v[134:135], v[194:195], v[134:135]
	v_pk_mul_f32 v[114:115], v[194:195], v[118:119]
	v_pk_add_f32 v[116:117], v[116:117], v[136:137] neg_lo:[0,1] neg_hi:[0,1]
	v_mul_f32_e32 v63, 0x45800000, v61
	v_pk_fma_f32 v[116:117], v[20:21], v[116:117], v[136:137]
	v_mov_b32_e32 v136, v134
	v_mov_b32_e32 v137, v114
	v_mov_b32_e32 v114, v135
	v_pk_add_f32 v[114:115], v[136:137], v[114:115]
	v_lshlrev_b32_e32 v134, 16, v138
	v_and_b32_e32 v136, 0xffff0000, v138
	v_cndmask_b32_e32 v138, v61, v63, vcc
	v_pk_mul_f32 v[120:121], v[120:121], v[138:139] op_sel_hi:[1,0]
	v_add_f32_e32 v118, v65, v67
	v_pk_add_f32 v[128:129], v[128:129], v[186:187] neg_lo:[0,1] neg_hi:[0,1]
	v_pk_mul_f32 v[124:125], v[124:125], v[138:139] op_sel_hi:[1,0]
	v_pk_fma_f32 v[120:121], v[150:151], v[120:121], v[148:149]
	v_pk_fma_f32 v[128:129], v[16:17], v[128:129], v[186:187]
	v_pk_fma_f32 v[124:125], v[4:5], v[124:125], v[0:1]
	v_pk_fma_f32 v[112:113], v[112:113], v[118:119], v[120:121] op_sel_hi:[1,0,1]
	v_pk_add_f32 v[114:115], v[114:115], v[140:141] neg_lo:[0,1] neg_hi:[0,1]
	v_pk_fma_f32 v[124:125], v[128:129], v[118:119], v[124:125] op_sel_hi:[1,0,1]
	v_pk_mul_f32 v[112:113], v[112:113], v[132:133]
	v_pk_mul_f32 v[122:123], v[122:123], v[138:139] op_sel_hi:[1,0]
	v_pk_fma_f32 v[114:115], v[18:19], v[114:115], v[140:141]
	v_pk_mul_f32 v[120:121], v[124:125], v[130:131]
	v_pk_mul_f32 v[124:125], v[126:127], v[138:139] op_sel_hi:[1,0]
	v_pk_fma_f32 v[122:123], v[6:7], v[122:123], v[2:3]
	v_and_b32_e32 v137, 0xffff0000, v139
	v_pk_fma_f32 v[124:125], v[12:13], v[124:125], v[8:9]
	v_pk_fma_f32 v[114:115], v[114:115], v[118:119], v[122:123] op_sel_hi:[1,0,1]
	v_and_b32_sdwa v61, v121, v59 dst_sel:DWORD dst_unused:UNUSED_PAD src0_sel:WORD_1 src1_sel:DWORD
	v_and_b32_sdwa v63, v120, v59 dst_sel:DWORD dst_unused:UNUSED_PAD src0_sel:WORD_1 src1_sel:DWORD
	v_cvt_pk_bf16_f32 v65, v113, v113
	v_cvt_pk_bf16_f32 v67, v112, v112
	v_lshlrev_b32_e32 v135, 16, v139
	v_pk_fma_f32 v[116:117], v[116:117], v[118:119], v[124:125] op_sel_hi:[1,0,1]
	v_pk_mul_f32 v[114:115], v[114:115], v[136:137]
	v_add3_u32 v63, v120, v63, s23
	v_add3_u32 v61, v121, v61, s23
	v_and_b32_e32 v65, 0xffff0000, v65
	v_and_b32_e32 v67, 0xffff0000, v67
	v_pk_mul_f32 v[116:117], v[116:117], v[134:135]
	v_or_b32_sdwa v113, v65, v61 dst_sel:DWORD dst_unused:UNUSED_PAD src0_sel:DWORD src1_sel:WORD_1
	v_or_b32_sdwa v112, v67, v63 dst_sel:DWORD dst_unused:UNUSED_PAD src0_sel:DWORD src1_sel:WORD_1
	v_and_b32_sdwa v61, v117, v59 dst_sel:DWORD dst_unused:UNUSED_PAD src0_sel:WORD_1 src1_sel:DWORD
	v_and_b32_sdwa v63, v116, v59 dst_sel:DWORD dst_unused:UNUSED_PAD src0_sel:WORD_1 src1_sel:DWORD
	v_cvt_pk_bf16_f32 v65, v115, v115
	v_cvt_pk_bf16_f32 v67, v114, v114
	v_add3_u32 v63, v116, v63, s23
	v_add3_u32 v61, v117, v61, s23
	v_and_b32_e32 v65, 0xffff0000, v65
	v_and_b32_e32 v67, 0xffff0000, v67
	v_or_b32_sdwa v115, v65, v61 dst_sel:DWORD dst_unused:UNUSED_PAD src0_sel:DWORD src1_sel:WORD_1
	v_or_b32_sdwa v114, v67, v63 dst_sel:DWORD dst_unused:UNUSED_PAD src0_sel:DWORD src1_sel:WORD_1
	global_store_dwordx4 v[184:185], v[112:115], off offset:768
	s_branch .LBB0_2832

.LBB0_2948:
	s_or_b64 exec, exec, s[18:19]
	v_add_u32_e32 v87, 0xfffff000, v82
	v_mov_b32_e32 v90, v57
	v_mov_b32_e32 v91, v61
	v_mov_b32_e32 v92, v56
	v_mov_b32_e32 v93, v60
	v_lshrrev_b32_e32 v87, 12, v87
	v_pk_add_f32 v[90:91], v[90:91], v[92:93]
	v_mov_b32_e32 v92, v58
	v_mov_b32_e32 v93, v62
	v_add_u32_e32 v87, 6, v87
	v_cmp_lt_i32_e64 s[0:1], s7, v82
	v_pk_add_f32 v[90:91], v[92:93], v[90:91]
	v_mov_b32_e32 v92, v59
	v_mov_b32_e32 v93, v63
	v_cndmask_b32_e64 v82, 5, v87, s[0:1]
	v_pk_add_f32 v[90:91], v[92:93], v[90:91]
	v_mad_u64_u32 v[88:89], s[0:1], v82, s20, v[72:73]
	v_add_f32_e32 v82, 0, v91
	v_add_f32_e32 v82, v90, v82
	v_mov_b32_e32 v90, v49
	v_mov_b32_e32 v91, v53
	v_mov_b32_e32 v92, v48
	v_mov_b32_e32 v93, v52
	v_pk_add_f32 v[90:91], v[90:91], v[92:93]
	v_mov_b32_e32 v92, v50
	v_mov_b32_e32 v93, v54
	v_pk_add_f32 v[90:91], v[92:93], v[90:91]
	v_mov_b32_e32 v92, v51
	v_mov_b32_e32 v93, v55
	v_pk_add_f32 v[90:91], v[92:93], v[90:91]
	v_lshl_add_u64 v[100:101], v[88:89], 0, s[14:15]
	v_add_f32_e32 v82, v91, v82
	v_add_f32_e32 v82, v90, v82
	v_lshl_add_u64 v[96:97], v[88:89], 0, s[16:17]
	v_lshl_add_u64 v[92:93], v[100:101], 0, v[74:75]
	v_add_f32_dpp v82, v82, v82 row_ror:8 row_mask:0xf bank_mask:0xf bound_ctrl:1
	v_lshl_add_u64 v[94:95], v[96:97], 0, v[74:75]
	v_lshl_add_u64 v[98:99], v[100:101], 0, v[76:77]
	v_add_f32_dpp v82, v82, v82 row_ror:4 row_mask:0xf bank_mask:0xf bound_ctrl:1
	v_lshl_add_u64 v[102:103], v[96:97], 0, v[76:77]
	v_lshl_add_u64 v[104:105], v[100:101], 0, v[78:79]
	v_add_f32_dpp v82, v82, v82 row_ror:2 row_mask:0xf bank_mask:0xf bound_ctrl:1
	v_lshl_add_u64 v[106:107], v[96:97], 0, v[78:79]
	v_lshl_add_u64 v[96:97], v[96:97], 0, v[80:81]
	v_add_f32_dpp v82, v82, v82 row_ror:1 row_mask:0xf bank_mask:0xf bound_ctrl:1
	ds_bpermute_b32 v87, v84, v82
	v_lshl_add_u64 v[100:101], v[100:101], 0, v[80:81]
	v_lshl_add_u64 v[124:125], v[66:67], 0, v[64:65]
	s_and_b64 s[18:19], exec, vcc
	s_or_b64 s[12:13], s[18:19], s[12:13]
	s_waitcnt lgkmcnt(0)
	v_add_f32_e32 v82, v82, v87
	ds_bpermute_b32 v87, v85, v82
	v_lshl_add_u64 v[70:71], v[70:71], 0, s[10:11]
	v_lshl_add_u64 v[66:67], v[66:67], 0, s[10:11]
	s_waitcnt lgkmcnt(0)
	v_add_f32_e32 v82, v82, v87
	v_mul_f32_e32 v82, 0x3a800000, v82
	v_pk_add_f32 v[108:109], v[60:61], v[82:83] op_sel_hi:[1,0] neg_lo:[0,1] neg_hi:[0,1]
	v_pk_add_f32 v[112:113], v[56:57], v[82:83] op_sel_hi:[1,0] neg_lo:[0,1] neg_hi:[0,1]
	v_pk_add_f32 v[114:115], v[58:59], v[82:83] op_sel_hi:[1,0] neg_lo:[0,1] neg_hi:[0,1]
	v_mov_b32_e32 v58, v109
	v_mov_b32_e32 v59, v113
	v_pk_add_f32 v[110:111], v[62:63], v[82:83] op_sel_hi:[1,0] neg_lo:[0,1] neg_hi:[0,1]
	v_mov_b32_e32 v56, v108
	v_mov_b32_e32 v57, v112
	v_pk_mul_f32 v[58:59], v[58:59], v[58:59]
	v_mov_b32_e32 v118, v110
	v_pk_fma_f32 v[116:117], v[56:57], v[56:57], v[58:59]
	v_mov_b32_e32 v119, v114
	global_load_dwordx4 v[60:63], v[92:93], off
	global_load_dwordx4 v[88:91], v[94:95], off
	v_mov_b32_e32 v120, v111
	v_mov_b32_e32 v121, v115
	global_load_dwordx4 v[56:59], v[98:99], off
	global_load_dwordx4 v[92:95], v[102:103], off
	v_pk_fma_f32 v[98:99], v[118:119], v[118:119], v[116:117]
	v_pk_add_f32 v[116:117], v[52:53], v[82:83] op_sel_hi:[1,0] neg_lo:[0,1] neg_hi:[0,1]
	v_pk_fma_f32 v[98:99], v[120:121], v[120:121], v[98:99]
	v_pk_add_f32 v[120:121], v[48:49], v[82:83] op_sel_hi:[1,0] neg_lo:[0,1] neg_hi:[0,1]
	v_pk_add_f32 v[122:123], v[50:51], v[82:83] op_sel_hi:[1,0] neg_lo:[0,1] neg_hi:[0,1]
	v_mov_b32_e32 v50, v121
	v_mov_b32_e32 v51, v117
	v_mov_b32_e32 v48, v120
	v_mov_b32_e32 v49, v116
	v_pk_mul_f32 v[50:51], v[50:51], v[50:51]
	v_pk_add_f32 v[118:119], v[54:55], v[82:83] op_sel_hi:[1,0] neg_lo:[0,1] neg_hi:[0,1]
	v_pk_fma_f32 v[102:103], v[48:49], v[48:49], v[50:51]
	global_load_dwordx4 v[48:51], v[104:105], off
	global_load_dwordx4 v[52:55], v[106:107], off
	v_mov_b32_e32 v104, v122
	v_mov_b32_e32 v105, v118
	v_mov_b32_e32 v106, v123
	v_mov_b32_e32 v107, v119
	v_pk_fma_f32 v[102:103], v[104:105], v[104:105], v[102:103]
	v_add_f32_e32 v82, v98, v99
	v_pk_fma_f32 v[102:103], v[106:107], v[106:107], v[102:103]
	global_load_dwordx4 v[96:99], v[96:97], off
	v_add_f32_e32 v82, v103, v82
	v_add_f32_e32 v82, v102, v82
	global_load_dwordx4 v[100:103], v[100:101], off
	s_waitcnt vmcnt(6)
	v_pk_add_f32 v[90:91], v[90:91], 1.0 op_sel_hi:[1,0]
	v_add_f32_dpp v82, v82, v82 row_ror:8 row_mask:0xf bank_mask:0xf bound_ctrl:1
	v_pk_add_f32 v[88:89], v[88:89], 1.0 op_sel_hi:[1,0]
	s_waitcnt vmcnt(2)
	v_pk_add_f32 v[54:55], v[54:55], 1.0 op_sel_hi:[1,0]
	v_add_f32_dpp v82, v82, v82 row_ror:4 row_mask:0xf bank_mask:0xf bound_ctrl:1
	v_pk_add_f32 v[52:53], v[52:53], 1.0 op_sel_hi:[1,0]
	s_nop 0
	v_add_f32_dpp v82, v82, v82 row_ror:2 row_mask:0xf bank_mask:0xf bound_ctrl:1
	s_nop 1
	v_add_f32_dpp v82, v82, v82 row_ror:1 row_mask:0xf bank_mask:0xf bound_ctrl:1
	ds_bpermute_b32 v87, v84, v82
	s_waitcnt lgkmcnt(0)
	v_add_f32_e32 v82, v82, v87
	ds_bpermute_b32 v87, v85, v82
	s_waitcnt lgkmcnt(0)
	v_add_f32_e32 v82, v82, v87
	v_fmamk_f32 v82, v82, 0x3a800000, v83
	v_mul_f32_e32 v87, 0x4b800000, v82
	v_cmp_gt_f32_e64 s[0:1], s21, v82
	s_nop 1
	v_cndmask_b32_e64 v82, v82, v87, s[0:1]
	v_rsq_f32_e32 v82, v82
	s_nop 0
	v_mul_f32_e32 v87, 0x45800000, v82
	v_cndmask_b32_e64 v82, v82, v87, s[0:1]
	v_pk_mul_f32 v[104:105], v[108:109], v[82:83] op_sel_hi:[1,0]
	v_pk_mul_f32 v[106:107], v[110:111], v[82:83] op_sel_hi:[1,0]
	v_pk_fma_f32 v[104:105], v[0:1], v[104:105], v[4:5]
	v_pk_fma_f32 v[106:107], v[2:3], v[106:107], v[6:7]
	v_pk_fma_f32 v[60:61], v[88:89], v[104:105], v[60:61]
	v_pk_fma_f32 v[62:63], v[90:91], v[106:107], v[62:63]
	v_pk_mul_f32 v[108:109], v[112:113], v[82:83] op_sel_hi:[1,0]
	v_pk_mul_f32 v[110:111], v[114:115], v[82:83] op_sel_hi:[1,0]
	v_pk_mul_f32 v[112:113], v[116:117], v[82:83] op_sel_hi:[1,0]
	v_pk_mul_f32 v[114:115], v[118:119], v[82:83] op_sel_hi:[1,0]
	v_pk_mul_f32 v[116:117], v[120:121], v[82:83] op_sel_hi:[1,0]
	v_pk_mul_f32 v[118:119], v[122:123], v[82:83] op_sel_hi:[1,0]
	v_pk_fma_f32 v[112:113], v[16:17], v[112:113], v[20:21]
	v_pk_fma_f32 v[114:115], v[18:19], v[114:115], v[22:23]
	v_cvt_pk_bf16_f32 v60, v60, v60
	v_cvt_pk_bf16_f32 v88, v61, v61
	v_cvt_pk_bf16_f32 v61, v62, v62
	v_cvt_pk_bf16_f32 v62, v63, v63
	v_pk_fma_f32 v[108:109], v[8:9], v[108:109], v[12:13]
	v_pk_fma_f32 v[110:111], v[10:11], v[110:111], v[14:15]
	v_perm_b32 v61, v62, v61, s23
	v_perm_b32 v60, v88, v60, s23
	v_pk_add_f32 v[62:63], v[94:95], 1.0 op_sel_hi:[1,0]
	v_pk_add_f32 v[88:89], v[92:93], 1.0 op_sel_hi:[1,0]
	v_pk_fma_f32 v[48:49], v[52:53], v[112:113], v[48:49]
	v_pk_fma_f32 v[50:51], v[54:55], v[114:115], v[50:51]
	v_pk_fma_f32 v[56:57], v[88:89], v[108:109], v[56:57]
	v_pk_fma_f32 v[58:59], v[62:63], v[110:111], v[58:59]
	v_cvt_pk_bf16_f32 v48, v48, v48
	v_cvt_pk_bf16_f32 v54, v49, v49
	v_cvt_pk_bf16_f32 v49, v50, v50
	v_cvt_pk_bf16_f32 v50, v51, v51
	v_cvt_pk_bf16_f32 v56, v56, v56
	v_cvt_pk_bf16_f32 v82, v57, v57
	v_cvt_pk_bf16_f32 v57, v58, v58
	v_cvt_pk_bf16_f32 v58, v59, v59
	v_perm_b32 v49, v50, v49, s23
	v_perm_b32 v48, v54, v48, s23
	v_pk_fma_f32 v[116:117], v[24:25], v[116:117], v[28:29]
	v_pk_fma_f32 v[118:119], v[26:27], v[118:119], v[30:31]
	v_perm_b32 v57, v58, v57, s23
	v_perm_b32 v56, v82, v56, s23
	global_store_dwordx4 v[124:125], v[104:107], off
	global_store_dwordx4 v[124:125], v[108:111], off offset:1024
	global_store_dwordx4 v[124:125], v[112:115], off offset:2048
	global_store_dwordx4 v[124:125], v[116:119], off offset:3072
	global_store_dwordx2 v[68:69], v[60:61], off
	global_store_dwordx2 v[68:69], v[56:57], off offset:512
	global_store_dwordx2 v[68:69], v[48:49], off offset:1024
	s_waitcnt vmcnt(8)
	v_pk_add_f32 v[48:49], v[98:99], 1.0 op_sel_hi:[1,0]
	v_pk_add_f32 v[50:51], v[96:97], 1.0 op_sel_hi:[1,0]
	s_waitcnt vmcnt(7)
	v_pk_fma_f32 v[48:49], v[48:49], v[118:119], v[102:103]
	v_pk_fma_f32 v[50:51], v[50:51], v[116:117], v[100:101]
	v_cvt_pk_bf16_f32 v49, v48, v49
	v_cvt_pk_bf16_f32 v48, v50, v51
	global_store_dwordx2 v[68:69], v[48:49], off offset:1536
	v_lshl_add_u64 v[68:69], v[68:69], 0, s[8:9]
	v_mov_b32_e32 v82, v86
	v_mov_b64_e32 v[60:61], v[32:33]
	v_mov_b64_e32 v[62:63], v[34:35]
	v_mov_b64_e32 v[56:57], v[36:37]
	v_mov_b64_e32 v[58:59], v[38:39]
	v_mov_b64_e32 v[52:53], v[40:41]
	v_mov_b64_e32 v[54:55], v[42:43]
	v_mov_b64_e32 v[48:49], v[44:45]
	v_mov_b64_e32 v[50:51], v[46:47]
	s_andn2_b64 exec, exec, s[12:13]
	s_cbranch_execz .LBB0_2951

.LBB0_3006:
	s_mul_i32 s51, s49, 0x6000
	s_waitcnt vmcnt(6)
	s_add_i32 s51, s29, s51
	s_mul_i32 s98, s50, 0x6000
	v_lshl_add_u64 v[196:197], v[136:137], 0, s[26:27]
	v_lshl_add_u64 v[198:199], v[134:135], 0, s[26:27]
	s_add_i32 s99, s51, s30
	s_waitcnt lgkmcnt(0)
	s_barrier
	v_add_u32_e32 v178, s98, v139
	v_add_u32_e32 v179, s98, v141
	ds_read_b128 v[162:165], v179
	ds_read_b128 v[146:149], v178
	ds_read_b128 v[166:169], v179 offset:1024
	ds_read_b128 v[170:173], v179 offset:2048
	ds_read_b128 v[174:177], v179 offset:3072
	ds_read_b128 v[150:153], v178 offset:1024
	ds_read_b128 v[154:157], v178 offset:2048
	ds_read_b128 v[158:161], v178 offset:3072
	ds_read_b128 v[180:183], v178 offset:4096
	ds_read_b128 v[184:187], v178 offset:5120
	ds_read_b128 v[188:191], v178 offset:6144
	ds_read_b128 v[192:195], v178 offset:7168
	v_lshl_add_u64 v[200:201], v[196:197], 0, s[18:19]
	s_mov_b32 m0, s51
	s_waitcnt lgkmcnt(10)
	v_mfma_f32_16x16x32_bf16 v[84:87], v[146:149], v[162:165], v[84:87]
	global_load_lds_dwordx4 v[200:201], off
	s_waitcnt lgkmcnt(9)
	v_mfma_f32_16x16x32_bf16 v[76:79], v[146:149], v[166:169], v[76:79]
	v_lshl_add_u64 v[200:201], v[196:197], 0, s[20:21]
	s_add_i32 m0, s51, 0x400
	s_waitcnt lgkmcnt(8)
	v_mfma_f32_16x16x32_bf16 v[68:71], v[146:149], v[170:173], v[68:71]
	global_load_lds_dwordx4 v[200:201], off
	s_waitcnt lgkmcnt(7)
	v_mfma_f32_16x16x32_bf16 v[60:63], v[146:149], v[174:177], v[60:63]
	v_lshl_add_u64 v[200:201], v[196:197], 0, s[22:23]
	s_add_i32 m0, s51, 0x800
	s_waitcnt lgkmcnt(6)
	v_mfma_f32_16x16x32_bf16 v[52:55], v[150:153], v[162:165], v[52:55]
	global_load_lds_dwordx4 v[200:201], off
	v_mfma_f32_16x16x32_bf16 v[44:47], v[150:153], v[166:169], v[44:47]
	v_mfma_f32_16x16x32_bf16 v[36:39], v[150:153], v[170:173], v[36:39]
	v_lshl_add_u64 v[200:201], v[196:197], 0, s[24:25]
	s_add_i32 m0, s51, 0xc00
	v_mfma_f32_16x16x32_bf16 v[32:35], v[150:153], v[174:177], v[32:35]
	global_load_lds_dwordx4 v[200:201], off
	s_waitcnt lgkmcnt(5)
	v_mfma_f32_16x16x32_bf16 v[28:31], v[154:157], v[162:165], v[28:31]
	v_lshl_add_u64 v[200:201], v[198:199], 0, s[18:19]
	s_add_i32 m0, s99, 0x4000
	v_mfma_f32_16x16x32_bf16 v[24:27], v[154:157], v[166:169], v[24:27]
	global_load_lds_dwordx4 v[200:201], off
	v_mfma_f32_16x16x32_bf16 v[20:23], v[154:157], v[170:173], v[20:23]
	v_lshl_add_u64 v[200:201], v[198:199], 0, s[20:21]
	s_add_i32 m0, s99, 0x4400
	v_mfma_f32_16x16x32_bf16 v[16:19], v[154:157], v[174:177], v[16:19]
	global_load_lds_dwordx4 v[200:201], off
	s_waitcnt lgkmcnt(4)
	v_mfma_f32_16x16x32_bf16 v[12:15], v[158:161], v[162:165], v[12:15]
	v_mfma_f32_16x16x32_bf16 v[8:11], v[158:161], v[166:169], v[8:11]
	v_mfma_f32_16x16x32_bf16 v[4:7], v[158:161], v[170:173], v[4:7]
	v_mfma_f32_16x16x32_bf16 v[0:3], v[158:161], v[174:177], v[0:3]
	s_waitcnt lgkmcnt(3)
	v_mfma_f32_16x16x32_bf16 v[124:127], v[180:183], v[162:165], v[124:127]
	v_mfma_f32_16x16x32_bf16 v[120:123], v[180:183], v[166:169], v[120:123]
	v_mfma_f32_16x16x32_bf16 v[116:119], v[180:183], v[170:173], v[116:119]
	v_mfma_f32_16x16x32_bf16 v[112:115], v[180:183], v[174:177], v[112:115]
	s_waitcnt lgkmcnt(2)
	v_mfma_f32_16x16x32_bf16 v[108:111], v[184:187], v[162:165], v[108:111]
	v_mfma_f32_16x16x32_bf16 v[104:107], v[184:187], v[166:169], v[104:107]
	v_mfma_f32_16x16x32_bf16 v[100:103], v[184:187], v[170:173], v[100:103]
	v_mfma_f32_16x16x32_bf16 v[96:99], v[184:187], v[174:177], v[96:99]
	s_waitcnt lgkmcnt(1)
	v_mfma_f32_16x16x32_bf16 v[92:95], v[188:191], v[162:165], v[92:95]
	v_mfma_f32_16x16x32_bf16 v[88:91], v[188:191], v[166:169], v[88:91]
	v_mfma_f32_16x16x32_bf16 v[80:83], v[188:191], v[170:173], v[80:83]
	v_mfma_f32_16x16x32_bf16 v[72:75], v[188:191], v[174:177], v[72:75]
	s_waitcnt lgkmcnt(0)
	v_mfma_f32_16x16x32_bf16 v[64:67], v[192:195], v[162:165], v[64:67]
	v_mfma_f32_16x16x32_bf16 v[56:59], v[192:195], v[166:169], v[56:59]
	v_mfma_f32_16x16x32_bf16 v[48:51], v[192:195], v[170:173], v[48:51]
	v_mfma_f32_16x16x32_bf16 v[40:43], v[192:195], v[174:177], v[40:43]
	s_add_i32 s51, s50, 1
	s_cmp_lg_u32 s50, 2
	s_cselect_b32 s50, s51, 0
	s_add_i32 s51, s49, 1
	s_cmp_lg_u32 s49, 2
	s_cselect_b32 s49, s51, 0
	s_add_u32 s26, s26, 64
	s_addc_u32 s27, s27, 0
	s_cmpk_eq_i32 s26, 0x780
	s_cbranch_scc0 .LBB0_3006
	s_waitcnt vmcnt(6)
	s_waitcnt lgkmcnt(0)
	s_barrier
	ds_read_b128 v[134:137], v139
	ds_read_b128 v[146:149], v139 offset:1024
	ds_read_b128 v[150:153], v139 offset:2048
	ds_read_b128 v[154:157], v139 offset:3072
	ds_read_b128 v[158:161], v141
	ds_read_b128 v[162:165], v141 offset:1024
	ds_read_b128 v[166:169], v141 offset:2048
	ds_read_b128 v[170:173], v141 offset:3072
	s_waitcnt lgkmcnt(0)
	s_nop 0
	v_mfma_f32_16x16x32_bf16 v[84:87], v[134:137], v[158:161], v[84:87]
	v_mfma_f32_16x16x32_bf16 v[76:79], v[134:137], v[162:165], v[76:79]
	v_mfma_f32_16x16x32_bf16 v[68:71], v[134:137], v[166:169], v[68:71]
	v_mfma_f32_16x16x32_bf16 v[60:63], v[134:137], v[170:173], v[60:63]
	v_mfma_f32_16x16x32_bf16 v[52:55], v[146:149], v[158:161], v[52:55]
	v_mfma_f32_16x16x32_bf16 v[44:47], v[146:149], v[162:165], v[44:47]
	v_mfma_f32_16x16x32_bf16 v[36:39], v[146:149], v[166:169], v[36:39]
	v_mfma_f32_16x16x32_bf16 v[32:35], v[146:149], v[170:173], v[32:35]
	v_mfma_f32_16x16x32_bf16 v[28:31], v[150:153], v[158:161], v[28:31]
	v_mfma_f32_16x16x32_bf16 v[24:27], v[150:153], v[162:165], v[24:27]
	v_mfma_f32_16x16x32_bf16 v[20:23], v[150:153], v[166:169], v[20:23]
	v_mfma_f32_16x16x32_bf16 v[16:19], v[150:153], v[170:173], v[16:19]
	v_mfma_f32_16x16x32_bf16 v[12:15], v[154:157], v[158:161], v[12:15]
	v_mfma_f32_16x16x32_bf16 v[8:11], v[154:157], v[162:165], v[8:11]
	v_mfma_f32_16x16x32_bf16 v[4:7], v[154:157], v[166:169], v[4:7]
	v_mfma_f32_16x16x32_bf16 v[0:3], v[154:157], v[170:173], v[0:3]
	ds_read_b128 v[134:137], v139 offset:4096
	ds_read_b128 v[146:149], v139 offset:5120
	ds_read_b128 v[150:153], v139 offset:6144
	ds_read_b128 v[154:157], v139 offset:7168
	s_waitcnt lgkmcnt(0)
	s_nop 0
	v_mfma_f32_16x16x32_bf16 v[124:127], v[134:137], v[158:161], v[124:127]
	v_mfma_f32_16x16x32_bf16 v[120:123], v[134:137], v[162:165], v[120:123]
	v_mfma_f32_16x16x32_bf16 v[174:177], v[134:137], v[166:169], v[116:119]
	v_mfma_f32_16x16x32_bf16 v[134:137], v[134:137], v[170:173], v[112:115]
	v_mfma_f32_16x16x32_bf16 v[178:181], v[146:149], v[158:161], v[108:111]
	v_mfma_f32_16x16x32_bf16 v[182:185], v[146:149], v[162:165], v[104:107]
	v_mfma_f32_16x16x32_bf16 v[186:189], v[146:149], v[166:169], v[100:103]
	v_mfma_f32_16x16x32_bf16 v[146:149], v[146:149], v[170:173], v[96:99]
	v_mfma_f32_16x16x32_bf16 v[190:193], v[150:153], v[158:161], v[92:95]
	v_mfma_f32_16x16x32_bf16 v[194:197], v[150:153], v[162:165], v[88:91]
	v_mfma_f32_16x16x32_bf16 v[198:201], v[150:153], v[166:169], v[80:83]
	v_mfma_f32_16x16x32_bf16 v[150:153], v[150:153], v[170:173], v[72:75]
	v_mfma_f32_16x16x32_bf16 v[158:161], v[154:157], v[158:161], v[64:67]
	v_mfma_f32_16x16x32_bf16 v[162:165], v[154:157], v[162:165], v[56:59]
	v_mfma_f32_16x16x32_bf16 v[166:169], v[154:157], v[166:169], v[48:51]
	v_mfma_f32_16x16x32_bf16 v[154:157], v[154:157], v[170:173], v[40:43]
	s_waitcnt vmcnt(0)
	s_waitcnt lgkmcnt(0)
	s_barrier
	ds_read_b128 v[40:43], v128
	ds_read_b128 v[48:51], v128 offset:1024
	ds_read_b128 v[56:59], v128 offset:2048
	ds_read_b128 v[170:173], v128 offset:3072
	ds_read_b128 v[202:205], v144
	ds_read_b128 v[206:209], v144 offset:1024
	ds_read_b128 v[210:213], v144 offset:2048
	ds_read_b128 v[214:217], v144 offset:3072
	s_waitcnt lgkmcnt(0)
	s_nop 0
	v_mfma_f32_16x16x32_bf16 v[222:225], v[40:43], v[206:209], v[76:79]
	v_mfma_f32_16x16x32_bf16 v[112:115], v[40:43], v[210:213], v[68:71]
	v_mfma_f32_16x16x32_bf16 v[72:75], v[170:173], v[202:205], v[12:15]
	v_mfma_f32_16x16x32_bf16 v[76:79], v[170:173], v[206:209], v[8:11]
	v_mfma_f32_16x16x32_bf16 v[64:67], v[170:173], v[210:213], v[4:7]
	v_mfma_f32_16x16x32_bf16 v[68:71], v[170:173], v[214:217], v[0:3]
	ds_read_b128 v[0:3], v128 offset:4096
	ds_read_b128 v[4:7], v128 offset:5120
	ds_read_b128 v[8:11], v128 offset:6144
	ds_read_b128 v[170:173], v128 offset:7168
	s_waitcnt lgkmcnt(0)
	v_mfma_f32_16x16x32_bf16 v[218:221], v[40:43], v[202:205], v[84:87]
	v_mfma_f32_16x16x32_bf16 v[116:119], v[40:43], v[214:217], v[60:63]
	v_mfma_f32_16x16x32_bf16 v[104:107], v[48:51], v[202:205], v[52:55]
	v_mfma_f32_16x16x32_bf16 v[108:111], v[48:51], v[206:209], v[44:47]
	v_mfma_f32_16x16x32_bf16 v[96:99], v[48:51], v[210:213], v[36:39]
	v_mfma_f32_16x16x32_bf16 v[100:103], v[48:51], v[214:217], v[32:35]
	v_mfma_f32_16x16x32_bf16 v[88:91], v[56:59], v[202:205], v[28:31]
	v_mfma_f32_16x16x32_bf16 v[92:95], v[56:59], v[206:209], v[24:27]
	v_mfma_f32_16x16x32_bf16 v[80:83], v[56:59], v[210:213], v[20:23]
	v_mfma_f32_16x16x32_bf16 v[84:87], v[56:59], v[214:217], v[16:19]
	v_mfma_f32_16x16x32_bf16 v[56:59], v[0:3], v[202:205], v[124:127]
	v_mfma_f32_16x16x32_bf16 v[60:63], v[0:3], v[206:209], v[120:123]
	v_mfma_f32_16x16x32_bf16 v[48:51], v[0:3], v[210:213], v[174:177]
	v_mfma_f32_16x16x32_bf16 v[52:55], v[0:3], v[214:217], v[134:137]
	v_mfma_f32_16x16x32_bf16 v[40:43], v[4:7], v[202:205], v[178:181]
	v_mfma_f32_16x16x32_bf16 v[44:47], v[4:7], v[206:209], v[182:185]
	v_mfma_f32_16x16x32_bf16 v[32:35], v[4:7], v[210:213], v[186:189]
	v_mfma_f32_16x16x32_bf16 v[36:39], v[4:7], v[214:217], v[146:149]
	v_mfma_f32_16x16x32_bf16 v[24:27], v[8:11], v[202:205], v[190:193]
	v_mfma_f32_16x16x32_bf16 v[28:31], v[8:11], v[206:209], v[194:197]
	v_mfma_f32_16x16x32_bf16 v[16:19], v[8:11], v[210:213], v[198:201]
	v_mfma_f32_16x16x32_bf16 v[20:23], v[8:11], v[214:217], v[150:153]
	v_mfma_f32_16x16x32_bf16 v[8:11], v[170:173], v[202:205], v[158:161]
	v_mfma_f32_16x16x32_bf16 v[12:15], v[170:173], v[206:209], v[162:165]
	v_mfma_f32_16x16x32_bf16 v[0:3], v[170:173], v[210:213], v[166:169]
	v_mfma_f32_16x16x32_bf16 v[4:7], v[170:173], v[214:217], v[154:157]
	v_mul_f32_e32 v121, 0xbfb8aa3b, v218
	v_exp_f32_e32 v121, v121
	v_or_b32_e32 v120, s48, v140
	v_ashrrev_i32_e32 v120, 1, v120
	v_or_b32_e32 v122, v120, v138
	v_add_f32_e32 v120, 1.0, v121
	v_rcp_f32_e32 v125, v120
	v_add_u32_e32 v124, s47, v145
	v_mov_b32_e32 v126, v124
	s_waitcnt lgkmcnt(0)
	v_mul_f32_e32 v120, v218, v125
	v_mul_f32_e32 v120, v222, v120
	v_mul_f32_e32 v134, 0xbfb8aa3b, v219
	v_exp_f32_e32 v134, v134
	s_barrier
	v_ashrrev_i32_e32 v123, 31, v122
	v_cvt_pk_bf16_f32 v125, v120, v120
	v_mov_b64_e32 v[120:121], s[52:53]
	v_mad_i64_i32 v[126:127], s[26:27], v126, s45, v[120:121]
	v_lshlrev_b64 v[122:123], 1, v[122:123]
	v_lshl_add_u64 v[126:127], v[126:127], 0, v[122:123]
	global_store_short_d16_hi v[126:127], v125, off
	v_add_f32_e32 v125, 1.0, v134
	v_rcp_f32_e32 v127, v125
	v_or_b32_e32 v134, 1, v124
	v_mov_b32_e32 v135, v134
	v_mul_f32_e32 v125, v219, v127
	v_mul_f32_e32 v125, v223, v125
	v_cvt_pk_bf16_f32 v125, v125, v125
	v_mul_f32_e32 v126, 0xbfb8aa3b, v220
	v_exp_f32_e32 v136, v126
	v_mad_i64_i32 v[126:127], s[26:27], v135, s45, v[120:121]
	v_lshl_add_u64 v[126:127], v[126:127], 0, v[122:123]
	global_store_short_d16_hi v[126:127], v125, off
	v_add_f32_e32 v125, 1.0, v136
	v_rcp_f32_e32 v127, v125
	v_or_b32_e32 v135, 2, v124
	v_mov_b32_e32 v136, v135
	v_mul_f32_e32 v125, v220, v127
	v_mul_f32_e32 v125, v224, v125
	v_cvt_pk_bf16_f32 v125, v125, v125
	v_mul_f32_e32 v126, 0xbfb8aa3b, v221
	v_exp_f32_e32 v137, v126
	v_mad_i64_i32 v[126:127], s[26:27], v136, s45, v[120:121]
	v_lshl_add_u64 v[126:127], v[126:127], 0, v[122:123]
	global_store_short_d16_hi v[126:127], v125, off
	v_add_f32_e32 v125, 1.0, v137
	v_rcp_f32_e32 v127, v125
	v_or_b32_e32 v136, 3, v124
	v_mov_b32_e32 v137, v136
	v_mul_f32_e32 v125, v221, v127
	v_mul_f32_e32 v125, v225, v125
	v_cvt_pk_bf16_f32 v125, v125, v125
	v_mul_f32_e32 v126, 0xbfb8aa3b, v112
	v_exp_f32_e32 v146, v126
	v_mad_i64_i32 v[126:127], s[26:27], v137, s45, v[120:121]
	v_lshl_add_u64 v[126:127], v[126:127], 0, v[122:123]
	v_add_f32_e32 v137, 1.0, v146
	v_rcp_f32_e32 v147, v137
	global_store_short_d16_hi v[126:127], v125, off
	v_mov_b32_e32 v125, v124
	v_mul_f32_e32 v112, v112, v147
	v_mul_f32_e32 v126, 0xbfb8aa3b, v113
	v_exp_f32_e32 v137, v126
	v_mul_f32_e32 v112, v116, v112
	v_cvt_pk_bf16_f32 v112, v112, v112
	v_add_f32_e32 v116, 1.0, v137
	v_mad_i64_i32 v[126:127], s[26:27], v125, s45, v[120:121]
	v_rcp_f32_e32 v137, v116
	v_lshl_add_u64 v[126:127], v[126:127], 0, v[122:123]
	global_store_short_d16_hi v[126:127], v112, off offset:32
	v_mul_f32_e32 v112, v113, v137
	v_mul_f32_e32 v116, 0xbfb8aa3b, v114
	v_exp_f32_e32 v116, v116
	v_mul_f32_e32 v112, v117, v112
	v_cvt_pk_bf16_f32 v117, v112, v112
	v_add_f32_e32 v116, 1.0, v116
	v_rcp_f32_e32 v126, v116
	v_mad_i64_i32 v[112:113], s[26:27], v134, s45, v[120:121]
	v_lshl_add_u64 v[112:113], v[112:113], 0, v[122:123]
	global_store_short_d16_hi v[112:113], v117, off offset:32
	v_mul_f32_e32 v112, v114, v126
	v_mul_f32_e32 v114, 0xbfb8aa3b, v115
	v_exp_f32_e32 v114, v114
	v_mul_f32_e32 v112, v118, v112
	v_add_f32_e32 v114, 1.0, v114
	v_rcp_f32_e32 v118, v114
	v_cvt_pk_bf16_f32 v116, v112, v112
	v_mad_i64_i32 v[112:113], s[26:27], v135, s45, v[120:121]
	v_lshl_add_u64 v[112:113], v[112:113], 0, v[122:123]
	global_store_short_d16_hi v[112:113], v116, off offset:32
	v_mul_f32_e32 v112, v115, v118
	v_mul_f32_e32 v112, v119, v112
	v_cvt_pk_bf16_f32 v114, v112, v112
	v_mul_f32_e32 v112, 0xbfb8aa3b, v104
	v_exp_f32_e32 v115, v112
	s_nop 0
	v_mad_i64_i32 v[112:113], s[26:27], v136, s45, v[120:121]
	v_lshl_add_u64 v[112:113], v[112:113], 0, v[122:123]
	global_store_short_d16_hi v[112:113], v114, off offset:32
	v_add_f32_e32 v112, 1.0, v115
	v_rcp_f32_e32 v114, v112
	v_or_b32_e32 v115, 16, v124
	v_mov_b32_e32 v116, v115
	v_mul_f32_e32 v104, v104, v114
	v_mul_f32_e32 v104, v108, v104
	v_cvt_pk_bf16_f32 v104, v104, v104
	v_mul_f32_e32 v108, 0xbfb8aa3b, v105
	v_exp_f32_e32 v108, v108
	v_mad_i64_i32 v[112:113], s[26:27], v116, s45, v[120:121]
	v_lshl_add_u64 v[112:113], v[112:113], 0, v[122:123]
	global_store_short_d16_hi v[112:113], v104, off
	v_add_f32_e32 v104, 1.0, v108
	v_rcp_f32_e32 v112, v104
	v_or_b32_e32 v113, 17, v124
	v_mov_b32_e32 v114, v113
	v_mul_f32_e32 v104, v105, v112
	v_mul_f32_e32 v104, v109, v104
	v_cvt_pk_bf16_f32 v108, v104, v104
	v_mul_f32_e32 v104, 0xbfb8aa3b, v106
	v_exp_f32_e32 v109, v104
	v_mad_i64_i32 v[104:105], s[26:27], v114, s45, v[120:121]
	v_lshl_add_u64 v[104:105], v[104:105], 0, v[122:123]
	global_store_short_d16_hi v[104:105], v108, off
	v_add_f32_e32 v104, 1.0, v109
	v_rcp_f32_e32 v108, v104
	v_or_b32_e32 v109, 18, v124
	v_mov_b32_e32 v112, v109
	v_mul_f32_e32 v104, v106, v108
	v_mul_f32_e32 v104, v110, v104
	v_cvt_pk_bf16_f32 v106, v104, v104
	v_mul_f32_e32 v104, 0xbfb8aa3b, v107
	v_exp_f32_e32 v108, v104
	v_mad_i64_i32 v[104:105], s[26:27], v112, s45, v[120:121]
	v_lshl_add_u64 v[104:105], v[104:105], 0, v[122:123]
	global_store_short_d16_hi v[104:105], v106, off
	v_add_f32_e32 v104, 1.0, v108
	v_rcp_f32_e32 v106, v104
	v_or_b32_e32 v108, 19, v124
	v_mov_b32_e32 v110, v108
	v_mul_f32_e32 v104, v107, v106
	v_mul_f32_e32 v106, 0xbfb8aa3b, v96
	v_exp_f32_e32 v106, v106
	v_mul_f32_e32 v104, v111, v104
	v_add_f32_e32 v106, 1.0, v106
	v_cvt_pk_bf16_f32 v107, v104, v104
	v_mad_i64_i32 v[104:105], s[26:27], v110, s45, v[120:121]
	v_rcp_f32_e32 v111, v106
	v_lshl_add_u64 v[104:105], v[104:105], 0, v[122:123]
	global_store_short_d16_hi v[104:105], v107, off
	v_mul_f32_e32 v96, v96, v111
	v_mul_f32_e32 v104, 0xbfb8aa3b, v97
	v_exp_f32_e32 v106, v104
	v_mul_f32_e32 v96, v100, v96
	v_cvt_pk_bf16_f32 v96, v96, v96
	v_add_f32_e32 v100, 1.0, v106
	v_rcp_f32_e32 v107, v100
	v_mad_i64_i32 v[104:105], s[26:27], v115, s45, v[120:121]
	v_lshl_add_u64 v[104:105], v[104:105], 0, v[122:123]
	global_store_short_d16_hi v[104:105], v96, off offset:32
	v_mul_f32_e32 v96, v97, v107
	v_mul_f32_e32 v100, 0xbfb8aa3b, v98
	v_exp_f32_e32 v100, v100
	v_mul_f32_e32 v96, v101, v96
	v_add_f32_e32 v100, 1.0, v100
	v_rcp_f32_e32 v105, v100
	v_cvt_pk_bf16_f32 v101, v96, v96
	v_mad_i64_i32 v[96:97], s[26:27], v113, s45, v[120:121]
	v_lshl_add_u64 v[96:97], v[96:97], 0, v[122:123]
	global_store_short_d16_hi v[96:97], v101, off offset:32
	v_mul_f32_e32 v96, v98, v105
	v_mul_f32_e32 v98, 0xbfb8aa3b, v99
	v_exp_f32_e32 v98, v98
	v_mul_f32_e32 v96, v102, v96
	v_add_f32_e32 v98, 1.0, v98
	v_rcp_f32_e32 v102, v98
	v_cvt_pk_bf16_f32 v100, v96, v96
	v_mad_i64_i32 v[96:97], s[26:27], v109, s45, v[120:121]
	v_lshl_add_u64 v[96:97], v[96:97], 0, v[122:123]
	global_store_short_d16_hi v[96:97], v100, off offset:32
	v_mul_f32_e32 v96, v99, v102
	v_mul_f32_e32 v96, v103, v96
	v_cvt_pk_bf16_f32 v98, v96, v96
	v_mul_f32_e32 v96, 0xbfb8aa3b, v88
	v_exp_f32_e32 v99, v96
	s_nop 0
	v_mad_i64_i32 v[96:97], s[26:27], v108, s45, v[120:121]
	v_lshl_add_u64 v[96:97], v[96:97], 0, v[122:123]
	global_store_short_d16_hi v[96:97], v98, off offset:32
	v_add_f32_e32 v96, 1.0, v99
	v_rcp_f32_e32 v98, v96
	v_or_b32_e32 v99, 32, v124
	v_mov_b32_e32 v100, v99
	v_mul_f32_e32 v88, v88, v98
	v_mul_f32_e32 v88, v92, v88
	v_cvt_pk_bf16_f32 v88, v88, v88
	v_mul_f32_e32 v92, 0xbfb8aa3b, v89
	v_exp_f32_e32 v92, v92
	v_mad_i64_i32 v[96:97], s[26:27], v100, s45, v[120:121]
	v_lshl_add_u64 v[96:97], v[96:97], 0, v[122:123]
	global_store_short_d16_hi v[96:97], v88, off
	v_add_f32_e32 v88, 1.0, v92
	v_rcp_f32_e32 v96, v88
	v_or_b32_e32 v97, 33, v124
	v_mov_b32_e32 v98, v97
	v_mul_f32_e32 v88, v89, v96
	v_mul_f32_e32 v88, v93, v88
	v_cvt_pk_bf16_f32 v92, v88, v88
	v_mul_f32_e32 v88, 0xbfb8aa3b, v90
	v_exp_f32_e32 v93, v88
	v_mad_i64_i32 v[88:89], s[26:27], v98, s45, v[120:121]
	v_lshl_add_u64 v[88:89], v[88:89], 0, v[122:123]
	global_store_short_d16_hi v[88:89], v92, off
	v_add_f32_e32 v88, 1.0, v93
	v_rcp_f32_e32 v92, v88
	v_or_b32_e32 v93, 34, v124
	v_mov_b32_e32 v96, v93
	v_mul_f32_e32 v88, v90, v92
	v_mul_f32_e32 v88, v94, v88
	v_cvt_pk_bf16_f32 v90, v88, v88
	v_mul_f32_e32 v88, 0xbfb8aa3b, v91
	v_exp_f32_e32 v92, v88
	v_mad_i64_i32 v[88:89], s[26:27], v96, s45, v[120:121]
	v_lshl_add_u64 v[88:89], v[88:89], 0, v[122:123]
	global_store_short_d16_hi v[88:89], v90, off
	v_add_f32_e32 v88, 1.0, v92
	v_rcp_f32_e32 v90, v88
	v_or_b32_e32 v92, 35, v124
	v_mov_b32_e32 v94, v92
	v_mul_f32_e32 v88, v91, v90
	v_mul_f32_e32 v90, 0xbfb8aa3b, v80
	v_exp_f32_e32 v90, v90
	v_mul_f32_e32 v88, v95, v88
	v_add_f32_e32 v90, 1.0, v90
	v_cvt_pk_bf16_f32 v91, v88, v88
	v_mad_i64_i32 v[88:89], s[26:27], v94, s45, v[120:121]
	v_rcp_f32_e32 v95, v90
	v_lshl_add_u64 v[88:89], v[88:89], 0, v[122:123]
	global_store_short_d16_hi v[88:89], v91, off
	v_mul_f32_e32 v80, v80, v95
	v_mul_f32_e32 v88, 0xbfb8aa3b, v81
	v_exp_f32_e32 v90, v88
	v_mul_f32_e32 v80, v84, v80
	v_cvt_pk_bf16_f32 v80, v80, v80
	v_add_f32_e32 v84, 1.0, v90
	v_rcp_f32_e32 v91, v84
	v_mad_i64_i32 v[88:89], s[26:27], v99, s45, v[120:121]
	v_lshl_add_u64 v[88:89], v[88:89], 0, v[122:123]
	global_store_short_d16_hi v[88:89], v80, off offset:32
	v_mul_f32_e32 v80, v81, v91
	v_mul_f32_e32 v84, 0xbfb8aa3b, v82
	v_exp_f32_e32 v84, v84
	v_mul_f32_e32 v80, v85, v80
	v_add_f32_e32 v84, 1.0, v84
	v_rcp_f32_e32 v89, v84
	v_cvt_pk_bf16_f32 v85, v80, v80
	v_mad_i64_i32 v[80:81], s[26:27], v97, s45, v[120:121]
	v_lshl_add_u64 v[80:81], v[80:81], 0, v[122:123]
	global_store_short_d16_hi v[80:81], v85, off offset:32
	v_mul_f32_e32 v80, v82, v89
	v_mul_f32_e32 v82, 0xbfb8aa3b, v83
	v_exp_f32_e32 v82, v82
	v_mul_f32_e32 v80, v86, v80
	v_add_f32_e32 v82, 1.0, v82
	v_rcp_f32_e32 v86, v82
	v_cvt_pk_bf16_f32 v84, v80, v80
	v_mad_i64_i32 v[80:81], s[26:27], v93, s45, v[120:121]
	v_lshl_add_u64 v[80:81], v[80:81], 0, v[122:123]
	global_store_short_d16_hi v[80:81], v84, off offset:32
	v_mul_f32_e32 v80, v83, v86
	v_mul_f32_e32 v80, v87, v80
	v_cvt_pk_bf16_f32 v82, v80, v80
	v_mul_f32_e32 v80, 0xbfb8aa3b, v72
	v_exp_f32_e32 v83, v80
	s_nop 0
	v_mad_i64_i32 v[80:81], s[26:27], v92, s45, v[120:121]
	v_lshl_add_u64 v[80:81], v[80:81], 0, v[122:123]
	global_store_short_d16_hi v[80:81], v82, off offset:32
	v_add_f32_e32 v80, 1.0, v83
	v_rcp_f32_e32 v82, v80
	v_or_b32_e32 v83, 48, v124
	v_mov_b32_e32 v84, v83
	v_mul_f32_e32 v72, v72, v82
	v_mul_f32_e32 v72, v76, v72
	v_cvt_pk_bf16_f32 v72, v72, v72
	v_mul_f32_e32 v76, 0xbfb8aa3b, v73
	v_exp_f32_e32 v76, v76
	v_mad_i64_i32 v[80:81], s[26:27], v84, s45, v[120:121]
	v_lshl_add_u64 v[80:81], v[80:81], 0, v[122:123]
	global_store_short_d16_hi v[80:81], v72, off
	v_add_f32_e32 v72, 1.0, v76
	v_rcp_f32_e32 v80, v72
	v_or_b32_e32 v81, 49, v124
	v_mov_b32_e32 v82, v81
	v_mul_f32_e32 v72, v73, v80
	v_mul_f32_e32 v72, v77, v72
	v_cvt_pk_bf16_f32 v76, v72, v72
	v_mul_f32_e32 v72, 0xbfb8aa3b, v74
	v_exp_f32_e32 v77, v72
	v_mad_i64_i32 v[72:73], s[26:27], v82, s45, v[120:121]
	v_lshl_add_u64 v[72:73], v[72:73], 0, v[122:123]
	global_store_short_d16_hi v[72:73], v76, off
	v_add_f32_e32 v72, 1.0, v77
	v_rcp_f32_e32 v76, v72
	v_or_b32_e32 v77, 50, v124
	v_mov_b32_e32 v80, v77
	v_mul_f32_e32 v72, v74, v76
	v_mul_f32_e32 v72, v78, v72
	v_cvt_pk_bf16_f32 v74, v72, v72
	v_mul_f32_e32 v72, 0xbfb8aa3b, v75
	v_exp_f32_e32 v76, v72
	v_mad_i64_i32 v[72:73], s[26:27], v80, s45, v[120:121]
	v_lshl_add_u64 v[72:73], v[72:73], 0, v[122:123]
	global_store_short_d16_hi v[72:73], v74, off
	v_add_f32_e32 v72, 1.0, v76
	v_rcp_f32_e32 v74, v72
	v_or_b32_e32 v76, 51, v124
	v_mov_b32_e32 v78, v76
	v_mul_f32_e32 v72, v75, v74
	v_mul_f32_e32 v74, 0xbfb8aa3b, v64
	v_exp_f32_e32 v74, v74
	v_mul_f32_e32 v72, v79, v72
	v_add_f32_e32 v74, 1.0, v74
	v_cvt_pk_bf16_f32 v75, v72, v72
	v_mad_i64_i32 v[72:73], s[26:27], v78, s45, v[120:121]
	v_rcp_f32_e32 v79, v74
	v_lshl_add_u64 v[72:73], v[72:73], 0, v[122:123]
	global_store_short_d16_hi v[72:73], v75, off
	v_mul_f32_e32 v64, v64, v79
	v_mul_f32_e32 v72, 0xbfb8aa3b, v65
	v_exp_f32_e32 v74, v72
	v_mul_f32_e32 v64, v68, v64
	v_cvt_pk_bf16_f32 v64, v64, v64
	v_add_f32_e32 v68, 1.0, v74
	v_rcp_f32_e32 v75, v68
	v_mad_i64_i32 v[72:73], s[26:27], v83, s45, v[120:121]
	v_lshl_add_u64 v[72:73], v[72:73], 0, v[122:123]
	global_store_short_d16_hi v[72:73], v64, off offset:32
	v_mul_f32_e32 v64, v65, v75
	v_mul_f32_e32 v68, 0xbfb8aa3b, v66
	v_exp_f32_e32 v68, v68
	v_mul_f32_e32 v64, v69, v64
	v_add_f32_e32 v68, 1.0, v68
	v_rcp_f32_e32 v73, v68
	v_cvt_pk_bf16_f32 v69, v64, v64
	v_mad_i64_i32 v[64:65], s[26:27], v81, s45, v[120:121]
	v_lshl_add_u64 v[64:65], v[64:65], 0, v[122:123]
	global_store_short_d16_hi v[64:65], v69, off offset:32
	v_mul_f32_e32 v64, v66, v73
	v_mul_f32_e32 v66, 0xbfb8aa3b, v67
	v_exp_f32_e32 v66, v66
	v_mul_f32_e32 v64, v70, v64
	v_add_f32_e32 v66, 1.0, v66
	v_rcp_f32_e32 v70, v66
	v_cvt_pk_bf16_f32 v68, v64, v64
	v_mad_i64_i32 v[64:65], s[26:27], v77, s45, v[120:121]
	v_lshl_add_u64 v[64:65], v[64:65], 0, v[122:123]
	global_store_short_d16_hi v[64:65], v68, off offset:32
	v_mul_f32_e32 v64, v67, v70
	v_mul_f32_e32 v64, v71, v64
	v_cvt_pk_bf16_f32 v66, v64, v64
	v_mad_i64_i32 v[64:65], s[26:27], v76, s45, v[120:121]
	v_lshl_add_u64 v[64:65], v[64:65], 0, v[122:123]
	global_store_short_d16_hi v[64:65], v66, off offset:32
	v_mul_f32_e32 v64, 0xbfb8aa3b, v56
	v_exp_f32_e32 v64, v64
	v_or_b32_e32 v66, 64, v124
	v_mov_b32_e32 v65, v66
	v_add_f32_e32 v64, 1.0, v64
	v_rcp_f32_e32 v68, v64
	s_add_i32 s2, s2, s3
	v_mul_f32_e32 v56, v56, v68
	v_mul_f32_e32 v56, v60, v56
	v_cvt_pk_bf16_f32 v56, v56, v56
	v_mul_f32_e32 v60, 0xbfb8aa3b, v57
	v_exp_f32_e32 v60, v60
	v_mad_i64_i32 v[64:65], s[26:27], v65, s45, v[120:121]
	v_lshl_add_u64 v[64:65], v[64:65], 0, v[122:123]
	global_store_short_d16_hi v[64:65], v56, off
	v_add_f32_e32 v56, 1.0, v60
	v_rcp_f32_e32 v64, v56
	v_or_b32_e32 v65, 0x41, v124
	v_mov_b32_e32 v67, v65
	v_mul_f32_e32 v56, v57, v64
	v_mul_f32_e32 v56, v61, v56
	v_cvt_pk_bf16_f32 v60, v56, v56
	v_mul_f32_e32 v56, 0xbfb8aa3b, v58
	v_exp_f32_e32 v61, v56
	v_mad_i64_i32 v[56:57], s[26:27], v67, s45, v[120:121]
	v_lshl_add_u64 v[56:57], v[56:57], 0, v[122:123]
	global_store_short_d16_hi v[56:57], v60, off
	v_add_f32_e32 v56, 1.0, v61
	v_rcp_f32_e32 v60, v56
	v_or_b32_e32 v61, 0x42, v124
	v_mov_b32_e32 v64, v61
	v_mul_f32_e32 v56, v58, v60
	v_mul_f32_e32 v56, v62, v56
	v_cvt_pk_bf16_f32 v58, v56, v56
	v_mul_f32_e32 v56, 0xbfb8aa3b, v59
	v_exp_f32_e32 v60, v56
	v_mad_i64_i32 v[56:57], s[26:27], v64, s45, v[120:121]
	v_lshl_add_u64 v[56:57], v[56:57], 0, v[122:123]
	global_store_short_d16_hi v[56:57], v58, off
	v_add_f32_e32 v56, 1.0, v60
	v_rcp_f32_e32 v58, v56
	v_or_b32_e32 v60, 0x43, v124
	v_mov_b32_e32 v62, v60
	v_mul_f32_e32 v56, v59, v58
	v_mul_f32_e32 v58, 0xbfb8aa3b, v48
	v_exp_f32_e32 v58, v58
	v_mul_f32_e32 v56, v63, v56
	v_add_f32_e32 v58, 1.0, v58
	v_cvt_pk_bf16_f32 v59, v56, v56
	v_mad_i64_i32 v[56:57], s[26:27], v62, s45, v[120:121]
	v_rcp_f32_e32 v63, v58
	v_lshl_add_u64 v[56:57], v[56:57], 0, v[122:123]
	global_store_short_d16_hi v[56:57], v59, off
	v_mul_f32_e32 v48, v48, v63
	v_mul_f32_e32 v56, 0xbfb8aa3b, v49
	v_exp_f32_e32 v58, v56
	v_mul_f32_e32 v48, v52, v48
	v_cvt_pk_bf16_f32 v48, v48, v48
	v_add_f32_e32 v52, 1.0, v58
	v_rcp_f32_e32 v59, v52
	v_mad_i64_i32 v[56:57], s[26:27], v66, s45, v[120:121]
	v_lshl_add_u64 v[56:57], v[56:57], 0, v[122:123]
	global_store_short_d16_hi v[56:57], v48, off offset:32
	v_mul_f32_e32 v48, v49, v59
	v_mul_f32_e32 v52, 0xbfb8aa3b, v50
	v_exp_f32_e32 v52, v52
	v_mul_f32_e32 v48, v53, v48
	v_add_f32_e32 v52, 1.0, v52
	v_rcp_f32_e32 v57, v52
	v_cvt_pk_bf16_f32 v53, v48, v48
	v_mad_i64_i32 v[48:49], s[26:27], v65, s45, v[120:121]
	v_lshl_add_u64 v[48:49], v[48:49], 0, v[122:123]
	global_store_short_d16_hi v[48:49], v53, off offset:32
	v_mul_f32_e32 v48, v50, v57
	v_mul_f32_e32 v50, 0xbfb8aa3b, v51
	v_exp_f32_e32 v50, v50
	v_mul_f32_e32 v48, v54, v48
	v_add_f32_e32 v50, 1.0, v50
	v_rcp_f32_e32 v54, v50
	v_cvt_pk_bf16_f32 v52, v48, v48
	v_mad_i64_i32 v[48:49], s[26:27], v61, s45, v[120:121]
	v_lshl_add_u64 v[48:49], v[48:49], 0, v[122:123]
	global_store_short_d16_hi v[48:49], v52, off offset:32
	v_mul_f32_e32 v48, v51, v54
	v_mul_f32_e32 v48, v55, v48
	v_cvt_pk_bf16_f32 v50, v48, v48
	v_mul_f32_e32 v48, 0xbfb8aa3b, v40
	v_exp_f32_e32 v51, v48
	s_add_i32 s31, s31, s33
	v_mad_i64_i32 v[48:49], s[26:27], v60, s45, v[120:121]
	v_lshl_add_u64 v[48:49], v[48:49], 0, v[122:123]
	global_store_short_d16_hi v[48:49], v50, off offset:32
	v_add_f32_e32 v48, 1.0, v51
	v_rcp_f32_e32 v50, v48
	v_or_b32_e32 v51, 0x50, v124
	v_mov_b32_e32 v52, v51
	v_mul_f32_e32 v40, v40, v50
	v_mul_f32_e32 v40, v44, v40
	v_cvt_pk_bf16_f32 v40, v40, v40
	v_mul_f32_e32 v44, 0xbfb8aa3b, v41
	v_exp_f32_e32 v44, v44
	v_mad_i64_i32 v[48:49], s[26:27], v52, s45, v[120:121]
	v_lshl_add_u64 v[48:49], v[48:49], 0, v[122:123]
	global_store_short_d16_hi v[48:49], v40, off
	v_add_f32_e32 v40, 1.0, v44
	v_rcp_f32_e32 v48, v40
	v_or_b32_e32 v49, 0x51, v124
	v_mov_b32_e32 v50, v49
	v_mul_f32_e32 v40, v41, v48
	v_mul_f32_e32 v40, v45, v40
	v_cvt_pk_bf16_f32 v44, v40, v40
	v_mul_f32_e32 v40, 0xbfb8aa3b, v42
	v_exp_f32_e32 v45, v40
	v_mad_i64_i32 v[40:41], s[26:27], v50, s45, v[120:121]
	v_lshl_add_u64 v[40:41], v[40:41], 0, v[122:123]
	global_store_short_d16_hi v[40:41], v44, off
	v_add_f32_e32 v40, 1.0, v45
	v_rcp_f32_e32 v44, v40
	v_or_b32_e32 v45, 0x52, v124
	v_mov_b32_e32 v48, v45
	v_mul_f32_e32 v40, v42, v44
	v_mul_f32_e32 v40, v46, v40
	v_cvt_pk_bf16_f32 v42, v40, v40
	v_mul_f32_e32 v40, 0xbfb8aa3b, v43
	v_exp_f32_e32 v44, v40
	v_mad_i64_i32 v[40:41], s[26:27], v48, s45, v[120:121]
	v_lshl_add_u64 v[40:41], v[40:41], 0, v[122:123]
	global_store_short_d16_hi v[40:41], v42, off
	v_add_f32_e32 v40, 1.0, v44
	v_rcp_f32_e32 v42, v40
	v_or_b32_e32 v44, 0x53, v124
	v_mov_b32_e32 v46, v44
	v_mul_f32_e32 v40, v43, v42
	v_mul_f32_e32 v42, 0xbfb8aa3b, v32
	v_exp_f32_e32 v42, v42
	v_mul_f32_e32 v40, v47, v40
	v_add_f32_e32 v42, 1.0, v42
	v_cvt_pk_bf16_f32 v43, v40, v40
	v_mad_i64_i32 v[40:41], s[26:27], v46, s45, v[120:121]
	v_rcp_f32_e32 v47, v42
	v_lshl_add_u64 v[40:41], v[40:41], 0, v[122:123]
	global_store_short_d16_hi v[40:41], v43, off
	v_mul_f32_e32 v32, v32, v47
	v_mul_f32_e32 v40, 0xbfb8aa3b, v33
	v_exp_f32_e32 v42, v40
	v_mul_f32_e32 v32, v36, v32
	v_cvt_pk_bf16_f32 v32, v32, v32
	v_add_f32_e32 v36, 1.0, v42
	v_rcp_f32_e32 v43, v36
	v_mad_i64_i32 v[40:41], s[26:27], v51, s45, v[120:121]
	v_lshl_add_u64 v[40:41], v[40:41], 0, v[122:123]
	global_store_short_d16_hi v[40:41], v32, off offset:32
	v_mul_f32_e32 v32, v33, v43
	v_mul_f32_e32 v36, 0xbfb8aa3b, v34
	v_exp_f32_e32 v36, v36
	v_mul_f32_e32 v32, v37, v32
	v_add_f32_e32 v36, 1.0, v36
	v_rcp_f32_e32 v41, v36
	v_cvt_pk_bf16_f32 v37, v32, v32
	v_mad_i64_i32 v[32:33], s[26:27], v49, s45, v[120:121]
	v_lshl_add_u64 v[32:33], v[32:33], 0, v[122:123]
	global_store_short_d16_hi v[32:33], v37, off offset:32
	v_mul_f32_e32 v32, v34, v41
	v_mul_f32_e32 v34, 0xbfb8aa3b, v35
	v_exp_f32_e32 v34, v34
	v_mul_f32_e32 v32, v38, v32
	v_add_f32_e32 v34, 1.0, v34
	v_rcp_f32_e32 v38, v34
	v_cvt_pk_bf16_f32 v36, v32, v32
	v_mad_i64_i32 v[32:33], s[26:27], v45, s45, v[120:121]
	v_lshl_add_u64 v[32:33], v[32:33], 0, v[122:123]
	global_store_short_d16_hi v[32:33], v36, off offset:32
	v_mul_f32_e32 v32, v35, v38
	v_mul_f32_e32 v32, v39, v32
	v_cvt_pk_bf16_f32 v34, v32, v32
	v_mul_f32_e32 v32, 0xbfb8aa3b, v24
	v_exp_f32_e32 v35, v32
	s_xor_b64 s[0:1], s[0:1], s[4:5]
	v_mad_i64_i32 v[32:33], s[26:27], v44, s45, v[120:121]
	v_lshl_add_u64 v[32:33], v[32:33], 0, v[122:123]
	global_store_short_d16_hi v[32:33], v34, off offset:32
	v_add_f32_e32 v32, 1.0, v35
	v_rcp_f32_e32 v34, v32
	v_or_b32_e32 v35, 0x60, v124
	v_mov_b32_e32 v36, v35
	v_mul_f32_e32 v24, v24, v34
	v_mul_f32_e32 v24, v28, v24
	v_cvt_pk_bf16_f32 v24, v24, v24
	v_mul_f32_e32 v28, 0xbfb8aa3b, v25
	v_exp_f32_e32 v28, v28
	v_mad_i64_i32 v[32:33], s[26:27], v36, s45, v[120:121]
	v_lshl_add_u64 v[32:33], v[32:33], 0, v[122:123]
	global_store_short_d16_hi v[32:33], v24, off
	v_add_f32_e32 v24, 1.0, v28
	v_rcp_f32_e32 v32, v24
	v_or_b32_e32 v33, 0x61, v124
	v_mov_b32_e32 v34, v33
	v_mul_f32_e32 v24, v25, v32
	v_mul_f32_e32 v24, v29, v24
	v_cvt_pk_bf16_f32 v28, v24, v24
	v_mul_f32_e32 v24, 0xbfb8aa3b, v26
	v_exp_f32_e32 v29, v24
	v_mad_i64_i32 v[24:25], s[26:27], v34, s45, v[120:121]
	v_lshl_add_u64 v[24:25], v[24:25], 0, v[122:123]
	global_store_short_d16_hi v[24:25], v28, off
	v_add_f32_e32 v24, 1.0, v29
	v_rcp_f32_e32 v28, v24
	v_or_b32_e32 v29, 0x62, v124
	v_mov_b32_e32 v32, v29
	v_mul_f32_e32 v24, v26, v28
	v_mul_f32_e32 v24, v30, v24
	v_cvt_pk_bf16_f32 v26, v24, v24
	v_mul_f32_e32 v24, 0xbfb8aa3b, v27
	v_exp_f32_e32 v28, v24
	v_mad_i64_i32 v[24:25], s[26:27], v32, s45, v[120:121]
	v_lshl_add_u64 v[24:25], v[24:25], 0, v[122:123]
	global_store_short_d16_hi v[24:25], v26, off
	v_add_f32_e32 v24, 1.0, v28
	v_rcp_f32_e32 v26, v24
	v_or_b32_e32 v28, 0x63, v124
	v_mov_b32_e32 v30, v28
	v_mul_f32_e32 v24, v27, v26
	v_mul_f32_e32 v26, 0xbfb8aa3b, v16
	v_exp_f32_e32 v26, v26
	v_mul_f32_e32 v24, v31, v24
	v_add_f32_e32 v26, 1.0, v26
	v_cvt_pk_bf16_f32 v27, v24, v24
	v_mad_i64_i32 v[24:25], s[26:27], v30, s45, v[120:121]
	v_rcp_f32_e32 v31, v26
	v_lshl_add_u64 v[24:25], v[24:25], 0, v[122:123]
	global_store_short_d16_hi v[24:25], v27, off
	v_mul_f32_e32 v16, v16, v31
	v_mul_f32_e32 v24, 0xbfb8aa3b, v17
	v_exp_f32_e32 v26, v24
	v_mul_f32_e32 v16, v20, v16
	v_cvt_pk_bf16_f32 v16, v16, v16
	v_add_f32_e32 v20, 1.0, v26
	v_rcp_f32_e32 v27, v20
	v_mad_i64_i32 v[24:25], s[26:27], v35, s45, v[120:121]
	v_lshl_add_u64 v[24:25], v[24:25], 0, v[122:123]
	global_store_short_d16_hi v[24:25], v16, off offset:32
	v_mul_f32_e32 v16, v17, v27
	v_mul_f32_e32 v20, 0xbfb8aa3b, v18
	v_exp_f32_e32 v20, v20
	v_mul_f32_e32 v16, v21, v16
	v_add_f32_e32 v20, 1.0, v20
	v_rcp_f32_e32 v25, v20
	v_cvt_pk_bf16_f32 v21, v16, v16
	v_mad_i64_i32 v[16:17], s[26:27], v33, s45, v[120:121]
	v_lshl_add_u64 v[16:17], v[16:17], 0, v[122:123]
	global_store_short_d16_hi v[16:17], v21, off offset:32
	v_mul_f32_e32 v16, v18, v25
	v_mul_f32_e32 v18, 0xbfb8aa3b, v19
	v_exp_f32_e32 v18, v18
	v_mul_f32_e32 v16, v22, v16
	v_add_f32_e32 v18, 1.0, v18
	v_rcp_f32_e32 v22, v18
	v_cvt_pk_bf16_f32 v20, v16, v16
	v_mad_i64_i32 v[16:17], s[26:27], v29, s45, v[120:121]
	v_lshl_add_u64 v[16:17], v[16:17], 0, v[122:123]
	global_store_short_d16_hi v[16:17], v20, off offset:32
	v_mul_f32_e32 v16, v19, v22
	v_mul_f32_e32 v16, v23, v16
	v_cvt_pk_bf16_f32 v18, v16, v16
	v_mul_f32_e32 v16, 0xbfb8aa3b, v8
	v_exp_f32_e32 v19, v16
	s_cmpk_gt_i32 s2, 0x1b7
	v_mad_i64_i32 v[16:17], s[26:27], v28, s45, v[120:121]
	v_lshl_add_u64 v[16:17], v[16:17], 0, v[122:123]
	global_store_short_d16_hi v[16:17], v18, off offset:32
	v_add_f32_e32 v16, 1.0, v19
	v_rcp_f32_e32 v18, v16
	v_or_b32_e32 v19, 0x70, v124
	v_mov_b32_e32 v20, v19
	v_mul_f32_e32 v8, v8, v18
	v_mul_f32_e32 v8, v12, v8
	v_cvt_pk_bf16_f32 v8, v8, v8
	v_mul_f32_e32 v12, 0xbfb8aa3b, v9
	v_exp_f32_e32 v12, v12
	v_mad_i64_i32 v[16:17], s[26:27], v20, s45, v[120:121]
	v_lshl_add_u64 v[16:17], v[16:17], 0, v[122:123]
	global_store_short_d16_hi v[16:17], v8, off
	v_add_f32_e32 v8, 1.0, v12
	v_rcp_f32_e32 v16, v8
	v_or_b32_e32 v17, 0x71, v124
	v_mov_b32_e32 v18, v17
	v_mul_f32_e32 v8, v9, v16
	v_mul_f32_e32 v8, v13, v8
	v_cvt_pk_bf16_f32 v12, v8, v8
	v_mul_f32_e32 v8, 0xbfb8aa3b, v10
	v_exp_f32_e32 v13, v8
	v_mad_i64_i32 v[8:9], s[26:27], v18, s45, v[120:121]
	v_lshl_add_u64 v[8:9], v[8:9], 0, v[122:123]
	global_store_short_d16_hi v[8:9], v12, off
	v_add_f32_e32 v8, 1.0, v13
	v_rcp_f32_e32 v12, v8
	v_or_b32_e32 v13, 0x72, v124
	v_mov_b32_e32 v16, v13
	v_mul_f32_e32 v8, v10, v12
	v_mul_f32_e32 v8, v14, v8
	v_cvt_pk_bf16_f32 v10, v8, v8
	v_mul_f32_e32 v8, 0xbfb8aa3b, v11
	v_exp_f32_e32 v12, v8
	v_mad_i64_i32 v[8:9], s[26:27], v16, s45, v[120:121]
	v_lshl_add_u64 v[8:9], v[8:9], 0, v[122:123]
	global_store_short_d16_hi v[8:9], v10, off
	v_add_f32_e32 v8, 1.0, v12
	v_rcp_f32_e32 v10, v8
	v_or_b32_e32 v12, 0x73, v124
	v_mov_b32_e32 v14, v12
	v_mul_f32_e32 v8, v11, v10
	v_mul_f32_e32 v10, 0xbfb8aa3b, v0
	v_exp_f32_e32 v10, v10
	v_mul_f32_e32 v8, v15, v8
	v_add_f32_e32 v10, 1.0, v10
	v_cvt_pk_bf16_f32 v11, v8, v8
	v_mad_i64_i32 v[8:9], s[26:27], v14, s45, v[120:121]
	v_rcp_f32_e32 v15, v10
	v_lshl_add_u64 v[8:9], v[8:9], 0, v[122:123]
	global_store_short_d16_hi v[8:9], v11, off
	v_mul_f32_e32 v0, v0, v15
	v_mul_f32_e32 v8, 0xbfb8aa3b, v1
	v_exp_f32_e32 v10, v8
	v_mul_f32_e32 v0, v4, v0
	v_cvt_pk_bf16_f32 v0, v0, v0
	v_add_f32_e32 v4, 1.0, v10
	v_rcp_f32_e32 v11, v4
	v_mad_i64_i32 v[8:9], s[26:27], v19, s45, v[120:121]
	v_lshl_add_u64 v[8:9], v[8:9], 0, v[122:123]
	global_store_short_d16_hi v[8:9], v0, off offset:32
	v_mul_f32_e32 v0, v1, v11
	v_mul_f32_e32 v4, 0xbfb8aa3b, v2
	v_exp_f32_e32 v4, v4
	v_mul_f32_e32 v0, v5, v0
	v_add_f32_e32 v4, 1.0, v4
	v_rcp_f32_e32 v9, v4
	v_cvt_pk_bf16_f32 v5, v0, v0
	v_mad_i64_i32 v[0:1], s[26:27], v17, s45, v[120:121]
	v_lshl_add_u64 v[0:1], v[0:1], 0, v[122:123]
	global_store_short_d16_hi v[0:1], v5, off offset:32
	v_mul_f32_e32 v0, v2, v9
	v_mul_f32_e32 v2, 0xbfb8aa3b, v3
	v_exp_f32_e32 v2, v2
	v_mul_f32_e32 v0, v6, v0
	v_add_f32_e32 v2, 1.0, v2
	v_rcp_f32_e32 v6, v2
	v_cvt_pk_bf16_f32 v4, v0, v0
	v_mad_i64_i32 v[0:1], s[26:27], v13, s45, v[120:121]
	v_lshl_add_u64 v[0:1], v[0:1], 0, v[122:123]
	global_store_short_d16_hi v[0:1], v4, off offset:32
	v_mul_f32_e32 v0, v3, v6
	v_mul_f32_e32 v0, v7, v0
	v_cvt_pk_bf16_f32 v2, v0, v0
	v_mad_i64_i32 v[0:1], s[26:27], v12, s45, v[120:121]
	v_lshl_add_u64 v[0:1], v[0:1], 0, v[122:123]
	global_store_short_d16_hi v[0:1], v2, off offset:32
	s_cbranch_scc0 .LBB0_3005
